# dead-code sweep on top of copy-forwarding: 70 dead VALU results + 109 dead scalar reloads removed via hazard-checked filler removal (306 slots total vs v34)
# speedup vs baseline: 1.0029x; 1.0029x over previous
.LBB0_147:
	v_writelane_b32 v251, s72, 38
	s_nop 1
	v_writelane_b32 v251, s73, 39
	v_writelane_b32 v251, s74, 40
	v_writelane_b32 v251, s75, 41
	v_writelane_b32 v251, s76, 42
	v_writelane_b32 v251, s77, 43
	v_writelane_b32 v251, s78, 44
	v_writelane_b32 v251, s79, 45
	v_writelane_b32 v251, s80, 46
	v_writelane_b32 v251, s81, 47
	v_writelane_b32 v251, s82, 48
	v_writelane_b32 v251, s83, 49
	v_writelane_b32 v251, s84, 50
	v_writelane_b32 v251, s85, 51
	v_writelane_b32 v251, s86, 52
	v_writelane_b32 v251, s87, 53
	s_or_b64 exec, exec, s[0:1]
	v_readlane_b32 s2, v251, 36
	s_cmpk_lt_i32 s2, 0x19e0
	s_cselect_b64 s[4:5], -1, 0
	s_add_u32 s62, s92, 0x1f4e0000
	s_addc_u32 s63, s93, 0
	s_add_u32 s33, s92, 0x1f1e0000
	v_writelane_b32 v251, s4, 54
	s_addc_u32 s35, s93, 0
	s_mul_i32 s0, s95, s94
	v_writelane_b32 v251, s5, 55
	s_add_u32 s4, s92, 0x1e420000
	s_addc_u32 s5, s93, 0
	s_add_u32 s34, s92, 0x1d920000
	v_writelane_b32 v251, s4, 56
	s_addc_u32 s27, s93, 0
	s_add_u32 s1, s92, 0x1c320000
	v_writelane_b32 v251, s5, 57
	v_writelane_b32 v251, s1, 58
	s_addc_u32 s1, s93, 0
	v_writelane_b32 v251, s1, 59
	s_lshl_b32 s1, s2, 2
	s_lshl_b32 s8, s94, 2
	v_writelane_b32 v251, s1, 60
	s_add_u32 s1, s92, 0x250e0000
	v_writelane_b32 v251, s1, 61
	s_addc_u32 s1, s93, 0
	s_add_u32 s82, s92, 0x4800000
	s_addc_u32 s83, s93, 0
	s_mul_i32 s24, s0, s61
	s_add_u32 s0, s92, 0x25467800
	v_writelane_b32 v251, s1, 62
	s_addc_u32 s1, s93, 0
	v_writelane_b32 v251, s0, 63
	s_mov_b64 s[6:7], src_shared_base
	s_mov_b64 s[96:97], 0x1400
	v_writelane_b32 v250, s1, 0
	s_add_u32 s0, s92, 0x25467a00
	s_addc_u32 s1, s93, 0
	v_writelane_b32 v250, s0, 1
	v_mov_b32_e32 v97, 0
	v_mbcnt_lo_u32_b32 v195, -1, 0
	v_writelane_b32 v250, s1, 2
	s_add_u32 s0, s92, 0x25467b00
	s_addc_u32 s1, s93, 0
	v_writelane_b32 v250, s0, 3
	v_mov_b32_e32 v163, 0x358637bd
	v_mov_b32_e32 v190, 1
	v_writelane_b32 v250, s1, 4
	s_add_u32 s0, s92, 0x25467c00
	s_addc_u32 s1, s93, 0
	v_writelane_b32 v250, s0, 5
	v_mov_b32_e32 v191, 0x3ecc95a3
	v_mov_b32_e32 v192, 0x3ab69700
	v_writelane_b32 v250, s1, 6
	s_add_u32 s0, s92, 0x25467d00
	s_addc_u32 s1, s93, 0
	v_writelane_b32 v250, s0, 7
	v_mov_b32_e32 v193, 0x260
	v_mov_b32_e32 v194, 0xb00000
	v_writelane_b32 v250, s1, 8
	s_add_u32 s0, s92, 0x25467e00
	s_addc_u32 s1, s93, 0
	v_writelane_b32 v250, s0, 9
	v_mbcnt_hi_u32_b32 v196, -1, v195
	v_mov_b32_e32 v197, 0x42800000
	v_writelane_b32 v250, s1, 10
	s_add_u32 s0, s92, 0x25467f00
	s_addc_u32 s1, s93, 0
	v_writelane_b32 v250, s0, 11
	v_not_b32_e32 v198, 63
	v_mov_b32_e32 v168, 0x3f317218
	v_writelane_b32 v250, s1, 12
	s_add_u32 s0, s92, 0x25468000
	s_addc_u32 s1, s93, 0
	v_writelane_b32 v250, s0, 13
	v_mov_b32_e32 v199, 0x7f800000
	v_mov_b32_e32 v200, 0x7fc00000
	v_writelane_b32 v250, s1, 14
	s_add_u32 s0, s92, 0x25468100
	s_addc_u32 s1, s93, 0
	v_writelane_b32 v250, s0, 15
	v_mov_b32_e32 v201, 0xff800000
	v_mov_b32_e32 v202, 0x7f000000
	v_writelane_b32 v250, s1, 16
	s_add_u32 s0, s92, 0x25468200
	s_addc_u32 s1, s93, 0
	v_writelane_b32 v250, s0, 17
	v_bfrev_b32_e32 v203, 0.5
	v_mov_b32_e32 v204, 0xf149f2ca
	v_writelane_b32 v250, s1, 18
	s_add_u32 s0, s92, 0x25468300
	s_addc_u32 s1, s93, 0
	v_writelane_b32 v250, s0, 19
	v_mov_b32_e32 v240, v97
	v_mov_b32_e32 v241, v97
	v_writelane_b32 v250, s1, 20
	s_add_u32 s0, s92, 0x25468400
	s_addc_u32 s1, s93, 0
	v_writelane_b32 v250, s0, 21
	v_mov_b32_e32 v205, 0xff61b1e6
	s_mov_b32 s86, 0x800000
	v_writelane_b32 v250, s1, 22
	s_add_u32 s0, s92, 0x25468500
	s_addc_u32 s1, s93, 0
	v_writelane_b32 v250, s0, 23
	s_mov_b32 s28, 0x4800000
	s_movk_i32 s29, 0x47ff
	v_writelane_b32 v250, s1, 24
	s_add_u32 s0, s92, 0x25468600
	s_addc_u32 s1, s93, 0
	v_writelane_b32 v250, s0, 25
	s_movk_i32 s84, 0x48
	s_mov_b32 s81, 0x1fffffc0
	v_writelane_b32 v250, s1, 26
	s_add_u32 s0, s92, 0x25468700
	s_addc_u32 s1, s93, 0
	v_writelane_b32 v250, s0, 27
	s_movk_i32 s18, 0x1600
	s_mov_b32 s19, 0x2c000
	v_writelane_b32 v250, s1, 28
	s_add_u32 s0, s92, 0x25468800
	s_addc_u32 s1, s93, 0
	v_writelane_b32 v250, s0, 29
	s_mov_b32 s20, 0x58000
	s_mov_b32 s21, 0x84000
	v_writelane_b32 v250, s1, 30
	s_add_u32 s0, s92, 0x25468900
	s_addc_u32 s1, s93, 0
	v_writelane_b32 v250, s0, 31
	s_cmp_eq_u32 s60, 15
	s_mov_b32 s22, 0x2d000
	v_writelane_b32 v250, s1, 32
	s_cselect_b64 s[0:1], -1, 0
	v_writelane_b32 v250, s0, 33
	s_cmp_eq_u32 s60, 14
	s_mov_b32 s23, 0x59000
	v_writelane_b32 v250, s1, 34
	s_cselect_b64 s[0:1], -1, 0
	v_writelane_b32 v250, s0, 35
	s_cmp_eq_u32 s60, 13
	s_mov_b32 s25, 0x85000
	v_writelane_b32 v250, s1, 36
	s_cselect_b64 s[0:1], -1, 0
	v_writelane_b32 v250, s0, 37
	s_cmp_eq_u32 s60, 12
	s_movk_i32 s74, 0x3600
	v_writelane_b32 v250, s1, 38
	s_cselect_b64 s[0:1], -1, 0
	v_writelane_b32 v250, s0, 39
	s_cmp_eq_u32 s60, 11
	s_mov_b32 s79, 0xffff0000
	v_writelane_b32 v250, s1, 40
	s_cselect_b64 s[0:1], -1, 0
	v_writelane_b32 v250, s0, 41
	s_cmp_eq_u32 s60, 10
	s_movk_i32 s87, 0x110
	v_writelane_b32 v250, s1, 42
	s_cselect_b64 s[0:1], -1, 0
	v_writelane_b32 v250, s0, 43
	s_cmp_eq_u32 s60, 9
	s_movk_i32 s80, 0x2ff
	v_writelane_b32 v250, s1, 44
	s_cselect_b64 s[0:1], -1, 0
	v_writelane_b32 v250, s0, 45
	s_cmp_eq_u32 s60, 8
	s_mov_b32 s85, 0x6c000
	v_writelane_b32 v250, s1, 46
	s_cselect_b64 s[0:1], -1, 0
	v_writelane_b32 v250, s0, 47
	s_cmp_eq_u32 s60, 7
	s_movk_i32 s58, 0x101
	v_writelane_b32 v250, s1, 48
	v_readlane_b32 s0, v251, 2
	v_readlane_b32 s1, v251, 3
	s_mov_b32 s59, 0xff61b1e6
	s_movk_i32 s77, 0x6ff
	v_lshl_add_u64 v[0:1], v[0:1], 2, s[0:1]
	s_mov_b64 s[0:1], 0x2400
	v_lshl_add_u64 v[164:165], v[0:1], 0, s[0:1]
	s_cselect_b64 s[0:1], -1, 0
	v_writelane_b32 v250, s0, 49
	s_cmp_eq_u32 s60, 6
	v_lshl_add_u64 v[166:167], v[0:1], 0, s[96:97]
	v_writelane_b32 v250, s1, 50
	s_cselect_b64 s[0:1], -1, 0
	v_writelane_b32 v250, s0, 51
	s_cmp_eq_u32 s60, 5
	s_mov_b64 s[36:37], 0x800
	v_writelane_b32 v250, s1, 52
	s_cselect_b64 s[0:1], -1, 0
	v_writelane_b32 v250, s0, 53
	s_cmp_eq_u32 s60, 4
	v_writelane_b32 v250, s1, 54
	s_cselect_b64 s[0:1], -1, 0
	v_writelane_b32 v250, s0, 55
	s_cmp_eq_u32 s60, 3
	s_barrier
	v_writelane_b32 v250, s1, 56
	s_cselect_b64 s[0:1], -1, 0
	v_writelane_b32 v250, s0, 57
	s_cmp_eq_u32 s60, 2
	s_nop 0
	v_writelane_b32 v250, s1, 58
	s_cselect_b64 s[0:1], -1, 0
	v_writelane_b32 v250, s0, 59
	s_cmp_eq_u32 s60, 1
	v_writelane_b32 v250, s1, 60
	s_cselect_b64 s[0:1], -1, 0
	v_writelane_b32 v250, s0, 61
	s_cmp_eq_u32 s60, 0
	v_writelane_b32 v250, s1, 62
	s_cselect_b64 s[0:1], -1, 0
	v_writelane_b32 v250, s0, 63
	v_writelane_b32 v249, s1, 0
	s_add_u32 s0, s92, 0x2546aa00
	s_addc_u32 s1, s93, 0
	v_writelane_b32 v249, s0, 1
	v_writelane_b32 v249, s1, 2
	s_add_u32 s0, s92, 0x2546ab00
	s_addc_u32 s1, s93, 0
	s_add_u32 s56, s92, 0x6c00000
	s_addc_u32 s57, s93, 0
	v_writelane_b32 v249, s0, 3
	s_cmpk_lt_i32 s2, 0x18c0
	v_writelane_b32 v249, s1, 4
	s_cselect_b64 s[0:1], -1, 0
	v_writelane_b32 v249, s0, 5
	v_writelane_b32 v249, s1, 6
	s_add_u32 s0, s92, 0xcf00000
	s_addc_u32 s1, s93, 0
	v_writelane_b32 v249, s0, 7
	s_cmpk_lt_i32 s2, 0xfc0
	v_writelane_b32 v249, s1, 8
	s_cselect_b64 s[0:1], -1, 0
	v_writelane_b32 v249, s0, 9
	v_writelane_b32 v249, s1, 10
	s_add_u32 s0, s92, 0xb400000
	s_addc_u32 s1, s93, 0
	v_writelane_b32 v249, s0, 11
	v_writelane_b32 v249, s1, 12
	s_add_u32 s0, s92, 0xcf01800
	s_addc_u32 s1, s93, 0
	v_writelane_b32 v249, s0, 13
	v_writelane_b32 v249, s1, 14
	s_add_u32 s0, s92, 0x25347600
	s_addc_u32 s1, s93, 0
	v_writelane_b32 v249, s0, 15
	v_writelane_b32 v249, s1, 16
	s_add_u32 s0, s92, 0x1c200000
	s_addc_u32 s1, s93, 0
	s_add_u32 s95, s92, 0x252b4000
	s_addc_u32 s76, s93, 0
	v_writelane_b32 v249, s0, 17
	s_cmp_lg_u32 0, -1
	v_writelane_b32 v249, s1, 18
	s_cselect_b64 s[0:1], -1, 0
	v_writelane_b32 v249, s0, 19
	v_writelane_b32 v249, s1, 20
	s_add_u32 s0, s92, 0x25224000
	s_addc_u32 s1, s93, 0
	v_writelane_b32 v249, s0, 21
	v_writelane_b32 v249, s1, 22
	s_add_u32 s0, s92, 0xc600000
	v_writelane_b32 v249, s0, 23
	s_addc_u32 s0, s93, 0
	v_writelane_b32 v249, s0, 24
	s_add_u32 s0, s92, 0x21ae0000
	v_writelane_b32 v249, s0, 25
	s_addc_u32 s0, s93, 0
	v_writelane_b32 v249, s0, 26
	s_add_u32 s0, s92, 0x22ce0000
	s_addc_u32 s1, s93, 0
	v_writelane_b32 v249, s0, 27
	v_writelane_b32 v249, s1, 28
	s_add_u32 s0, s92, 0x252b6400
	s_addc_u32 s1, s93, 0
	s_add_u32 s78, s92, 0x25346400
	s_addc_u32 s72, s93, 0
	s_add_u32 s64, s92, 0x1f6e0000
	v_writelane_b32 v249, s0, 29
	s_addc_u32 s65, s93, 0
	v_writelane_b32 v249, s1, 30
	s_add_u32 s0, s92, 0xcf00400
	s_addc_u32 s1, s93, 0
	s_add_u32 s66, s92, 0x208e0000
	v_writelane_b32 v249, s0, 31
	s_addc_u32 s67, s93, 0
	v_writelane_b32 v249, s1, 32
	s_add_u32 s0, s92, 0x1ce20000
	v_writelane_b32 v249, s0, 33
	s_addc_u32 s0, s93, 0
	v_writelane_b32 v249, s0, 34
	s_add_u32 s0, s92, 0x1dea0000
	v_writelane_b32 v249, s0, 35
	s_addc_u32 s0, s93, 0
	s_abs_i32 s3, s94
	v_cvt_f32_u32_e32 v2, s3
	v_writelane_b32 v249, s0, 36
	s_sub_i32 s0, 0, s3
	v_rcp_iflag_f32_e32 v2, v2
	s_nop 0
	v_mul_f32_e32 v2, 0x4f7ffffe, v2
	v_cvt_u32_f32_e32 v2, v2
	s_nop 0
	v_readfirstlane_b32 s1, v2
	s_mul_i32 s0, s0, s1
	s_mul_hi_u32 s0, s1, s0
	s_add_i32 s0, s1, s0
	v_writelane_b32 v249, s0, 37
	s_mul_hi_u32 s0, s0, 0x480
	s_mul_i32 s0, s0, s3
	s_sub_i32 s0, 0x480, s0
	s_sub_i32 s1, s0, s3
	s_cmp_ge_u32 s0, s3
	s_cselect_b32 s0, s1, s0
	s_sub_i32 s1, s0, s3
	s_cmp_ge_u32 s0, s3
	s_cselect_b32 s0, s1, s0
	v_writelane_b32 v249, s3, 38
	s_sub_i32 s3, 0x480, s0
	s_cmp_lt_i32 s2, s3
	s_cselect_b64 s[4:5], -1, 0
	v_writelane_b32 v249, s4, 39
	v_writelane_b32 v248, s3, 0
	v_writelane_b32 v249, s5, 40
	s_lshl_b32 s4, s0, 1
	s_cmp_lt_i32 s2, s4
	s_cselect_b64 s[0:1], -1, 0
	v_writelane_b32 v249, s0, 41
	s_ashr_i32 s9, s8, 31
	s_lshl_b64 s[30:31], s[8:9], 11
	v_writelane_b32 v249, s1, 42
	s_lshl_b32 s0, s2, 5
	s_add_i32 s0, s0, 0xfffe5000
	v_writelane_b32 v249, s0, 43
	s_lshl_b32 s0, s94, 5
	s_lshl_b64 s[14:15], s[8:9], 12
	v_writelane_b32 v249, s0, 44
	s_add_u32 s0, s92, 0x25349600
	v_writelane_b32 v249, s0, 45
	s_addc_u32 s0, s93, 0
	v_writelane_b32 v249, s0, 46
	s_add_u32 s0, s92, 0x25346600
	v_writelane_b32 v249, s0, 47
	s_addc_u32 s0, s93, 0
	v_writelane_b32 v249, s0, 48
	s_add_i32 s0, 0, 0x13ff0
	v_writelane_b32 v249, s0, 49
	s_add_i32 s0, 0, 0x13ff4
	v_writelane_b32 v249, s0, 50
	s_add_i32 s0, 0, 0x11800
	v_writelane_b32 v249, s0, 51
	s_add_i32 s0, 0, 0x8c00
	v_writelane_b32 v249, s0, 52
	s_add_i32 s0, 0, 0x8800
	v_writelane_b32 v249, s0, 53
	s_add_i32 s0, 0, 0x11c00
	v_writelane_b32 v249, s0, 54
	s_add_i32 s0, 0, 0x11a00
	v_writelane_b32 v248, s4, 1
	v_writelane_b32 v249, s0, 55
	s_mov_b32 s1, s7
	v_writelane_b32 v248, s30, 2
	v_writelane_b32 v249, s0, 56
	s_mov_b32 s2, 0
	v_writelane_b32 v248, s31, 3
	v_writelane_b32 v249, s1, 57
	v_writelane_b32 v248, s14, 4
	v_writelane_b32 v249, s62, 58
	s_mov_b32 s0, s8
	v_writelane_b32 v248, s15, 5
	v_writelane_b32 v249, s63, 59
	v_writelane_b32 v248, s34, 6
	v_writelane_b32 v249, s0, 60
	v_writelane_b32 v248, s24, 7
	v_writelane_b32 v248, s82, 8
	v_writelane_b32 v249, s1, 61
	s_mov_b32 s5, 0
	v_writelane_b32 v249, s56, 62
	v_writelane_b32 v248, s83, 9
	v_writelane_b32 v248, s27, 10
	v_writelane_b32 v249, s57, 63
	s_branch .LBB0_151

.LBB0_151:
	s_cmp_eq_u32 s2, 0
	s_mov_b32 s68, s27
	s_mov_b32 s69, s24
	v_writelane_b32 v248, s2, 11
	s_cbranch_scc1 .LBB0_209
	v_readlane_b32 s0, v251, 54
	v_readlane_b32 s1, v251, 55
	s_andn2_b64 vcc, exec, s[0:1]
	s_cbranch_vccnz .LBB0_209
	v_readlane_b32 s6, v248, 11
	s_lshl_b32 s4, s6, 20
	s_lshl_b64 s[0:1], s[4:5], 2
	s_add_u32 s0, s88, s0
	s_mul_i32 s4, s6, 0x6c4000
	v_readlane_b32 s8, v251, 4
	s_addc_u32 s1, s89, s1
	s_lshl_b64 s[2:3], s[4:5], 2
	v_readlane_b32 s12, v251, 8
	v_readlane_b32 s13, v251, 9
	s_add_u32 s2, s12, s2
	s_addc_u32 s3, s13, s3
	s_lshl_b32 s10, s6, 1
	v_readlane_b32 s6, v251, 36
	s_mov_b32 s11, s6
	v_readlane_b32 s9, v251, 5
	v_readlane_b32 s14, v251, 10
	v_readlane_b32 s15, v251, 11
	v_readlane_b32 s16, v251, 12
	v_readlane_b32 s17, v251, 13
	v_readlane_b32 s18, v251, 14
	v_readlane_b32 s19, v251, 15
	v_readlane_b32 s20, v251, 16
	v_readlane_b32 s21, v251, 17
	v_readlane_b32 s22, v251, 18
	v_readlane_b32 s23, v251, 19
	v_readlane_b32 s7, v251, 37
	s_branch .LBB0_155

.LBB0_173:
	s_andn2_b64 vcc, exec, s[12:13]
	s_cbranch_vccnz .LBB0_175
	s_mul_i32 s12, s8, 3
	s_add_i32 s12, s4, s12
	s_ashr_i32 s13, s12, 31
	v_readlane_b32 s16, v251, 20
	s_lshl_b64 s[12:13], s[12:13], 21
	v_readlane_b32 s30, v251, 34
	v_readlane_b32 s31, v251, 35
	s_add_u32 s12, s30, s12
	s_addc_u32 s13, s31, s13
	v_readlane_b32 s30, v248, 2
	v_ashrrev_i32_e32 v3, 31, v2
	s_mov_b32 s24, s69
	s_mov_b32 s27, s68
	s_mov_b32 s25, 0x85000
	s_movk_i32 s29, 0x47ff
	s_mov_b32 s28, 0x4800000
	v_readlane_b32 s31, v248, 3
	v_lshl_add_u64 v[0:1], v[2:3], 2, s[12:13]
	v_readlane_b32 s17, v251, 21
	v_readlane_b32 s18, v251, 22
	v_readlane_b32 s19, v251, 23
	v_readlane_b32 s20, v251, 24
	v_readlane_b32 s21, v251, 25
	v_readlane_b32 s22, v251, 26
	v_readlane_b32 s23, v251, 27
	v_readlane_b32 s26, v251, 30
	v_readlane_b32 s14, v248, 1
	v_readlane_b32 s9, v248, 0

.LBB0_184:
	s_andn2_b64 vcc, exec, s[42:43]
	s_cbranch_vccnz .LBB0_186
	s_add_i32 s12, s4, s10
	v_readlane_b32 s16, v251, 4
	s_mul_hi_i32 s13, s12, 0xb00000
	s_mul_i32 s12, s12, 0xb00000
	v_readlane_b32 s18, v251, 6
	v_readlane_b32 s19, v251, 7
	s_nop 0
	s_add_u32 s12, s18, s12
	v_readlane_b32 s30, v248, 2
	s_addc_u32 s13, s19, s13
	v_ashrrev_i32_e32 v3, 31, v2
	s_mov_b32 s24, s69
	s_mov_b32 s27, s68
	s_mov_b32 s25, 0x85000
	s_movk_i32 s29, 0x47ff
	s_mov_b32 s28, 0x4800000
	v_readlane_b32 s31, v248, 3
	v_lshl_add_u64 v[0:1], v[2:3], 2, s[12:13]
	s_mov_b64 s[12:13], 0x400
	v_readlane_b32 s17, v251, 5
	v_readlane_b32 s20, v251, 8
	v_readlane_b32 s21, v251, 9
	v_readlane_b32 s22, v251, 10
	v_readlane_b32 s23, v251, 11
	v_readlane_b32 s26, v251, 14
	v_readlane_b32 s14, v248, 1
	v_readlane_b32 s9, v248, 0

.LBB0_187:
	s_andn2_b64 vcc, exec, s[44:45]
	s_cbranch_vccnz .LBB0_189
	v_readlane_b32 s12, v251, 4
	v_readlane_b32 s40, v251, 38
	v_and_b32_e32 v0, 32, v4
	v_readlane_b32 s13, v251, 5
	v_readlane_b32 s55, v251, 53
	v_readlane_b32 s54, v251, 52
	v_mov_b32_e32 v1, s13
	v_mov_b32_e32 v3, s55
	v_cmp_eq_u32_e32 vcc, 0, v0
	v_mov_b32_e32 v0, s12
	s_add_i32 s4, s4, s10
	v_cndmask_b32_e32 v1, v1, v3, vcc
	v_mov_b32_e32 v3, s54
	v_cndmask_b32_e32 v0, v0, v3, vcc
	v_mad_i64_i32 v[0:1], s[12:13], s4, v194, v[0:1]
	s_lshl_b32 s12, s62, 5
	v_and_b32_e32 v2, 31, v4
	s_ashr_i32 s13, s12, 31
	v_lshl_add_u64 v[0:1], s[12:13], 2, v[0:1]
	v_lshlrev_b32_e32 v96, 2, v2
	s_mov_b32 s24, s69
	s_mov_b32 s27, s68
	s_mov_b32 s25, 0x85000
	s_movk_i32 s29, 0x47ff
	s_mov_b32 s28, 0x4800000
	v_lshl_add_u64 v[0:1], v[0:1], 0, v[96:97]
	s_mov_b64 s[12:13], 0xb00
	v_readlane_b32 s14, v251, 6
	v_readlane_b32 s15, v251, 7
	v_readlane_b32 s16, v251, 8
	v_readlane_b32 s17, v251, 9
	v_readlane_b32 s18, v251, 10
	v_readlane_b32 s19, v251, 11
	v_readlane_b32 s20, v251, 12
	v_readlane_b32 s21, v251, 13
	v_readlane_b32 s22, v251, 14
	v_readlane_b32 s23, v251, 15
	v_readlane_b32 s26, v251, 18
	v_readlane_b32 s41, v251, 39
	v_readlane_b32 s42, v251, 40
	v_readlane_b32 s43, v251, 41
	v_readlane_b32 s44, v251, 42
	v_readlane_b32 s45, v251, 43
	v_readlane_b32 s46, v251, 44
	v_readlane_b32 s47, v251, 45
	v_readlane_b32 s48, v251, 46
	v_readlane_b32 s49, v251, 47
	v_readlane_b32 s50, v251, 48
	v_readlane_b32 s51, v251, 49
	v_readlane_b32 s52, v251, 50
	v_readlane_b32 s53, v251, 51

.Lnrm_done0:
	s_movk_i32 s0, 0x4800
	v_cmp_gt_i32_e32 vcc, s0, v0
	s_mul_hi_u32 s0, s3, 0x3000
	v_writelane_b32 v248, s0, 12
	s_mul_i32 s0, s3, 0x3000
	v_writelane_b32 v248, s0, 13
	s_and_saveexec_b64 s[0:1], vcc
	s_mov_b64 s[6:7], 0x1000
	s_cbranch_execz .LBB0_212
	v_and_b32_e32 v6, 63, v1
	v_and_b32_e32 v1, 64, v196
	v_add_u32_e32 v1, 64, v1
	v_xor_b32_e32 v2, 32, v196
	v_cmp_lt_i32_e32 vcc, v2, v1
	v_readlane_b32 s40, v251, 38
	s_nop 0
	v_cndmask_b32_e32 v2, v196, v2, vcc
	v_lshlrev_b32_e32 v10, 2, v2
	v_xor_b32_e32 v2, 16, v196
	v_cmp_lt_i32_e32 vcc, v2, v1
	s_nop 0
	s_nop 0
	v_cndmask_b32_e32 v2, v196, v2, vcc
	v_lshlrev_b32_e32 v11, 2, v2
	v_xor_b32_e32 v2, 8, v196
	v_cmp_lt_i32_e32 vcc, v2, v1
	s_nop 0
	v_readlane_b32 s52, v251, 50
	v_cndmask_b32_e32 v2, v196, v2, vcc
	v_lshlrev_b32_e32 v12, 2, v2
	v_xor_b32_e32 v2, 4, v196
	v_cmp_lt_i32_e32 vcc, v2, v1
	v_readlane_b32 s53, v251, 51
	v_readlane_b32 s54, v251, 52
	v_cndmask_b32_e32 v2, v196, v2, vcc
	v_lshlrev_b32_e32 v13, 2, v2
	v_xor_b32_e32 v2, 2, v196
	v_cmp_lt_i32_e32 vcc, v2, v1
	v_readlane_b32 s55, v251, 53
	s_mov_b64 s[48:49], s[52:53]
	v_cndmask_b32_e32 v2, v196, v2, vcc
	v_lshlrev_b32_e32 v14, 2, v2
	v_xor_b32_e32 v2, 1, v196
	v_cmp_lt_i32_e32 vcc, v2, v1
	v_readlane_b32 s2, v248, 13
	s_add_u32 s2, s48, s2
	v_cndmask_b32_e32 v1, v196, v2, vcc
	v_lshlrev_b32_e32 v15, 2, v1
	v_ashrrev_i32_e32 v1, 31, v0
	v_readlane_b32 s3, v248, 12
	v_lshlrev_b32_e32 v8, 3, v6
	v_lshlrev_b64 v[4:5], 11, v[0:1]
	s_addc_u32 s3, s49, s3
	v_or_b32_e32 v16, 0x200, v8
	v_lshlrev_b32_e32 v96, 5, v6
	v_lshl_or_b32 v4, v6, 4, v4
	v_lshlrev_b64 v[6:7], 12, v[0:1]
	v_lshl_add_u64 v[2:3], s[2:3], 0, v[96:97]
	v_or_b32_e32 v6, v6, v96
	s_mov_b64 s[2:3], 0
	v_lshlrev_b32_e32 v96, 2, v8
	v_lshlrev_b32_e32 v8, 2, v16
	v_readlane_b32 s41, v251, 39
	v_readlane_b32 s42, v251, 40
	v_readlane_b32 s43, v251, 41
	v_readlane_b32 s44, v251, 42
	v_readlane_b32 s45, v251, 43
	v_readlane_b32 s46, v251, 44
	v_readlane_b32 s47, v251, 45
	s_mov_b64 s[50:51], s[54:55]

.Lnrm_done1:
	s_movk_i32 s0, 0x4800
	v_cmp_gt_i32_e32 vcc, s0, v12
	s_and_saveexec_b64 s[0:1], vcc
	s_mov_b64 s[10:11], 0x1000
	s_cbranch_execz .LBB0_391
	v_and_b32_e32 v1, 63, v0
	v_mbcnt_hi_u32_b32 v0, -1, v195
	v_and_b32_e32 v2, 64, v0
	v_add_u32_e32 v2, 64, v2
	v_xor_b32_e32 v3, 32, v0
	v_cmp_lt_i32_e32 vcc, v3, v2
	v_readlane_b32 s40, v251, 38
	s_add_u32 s2, s16, 0x3000
	v_cndmask_b32_e32 v3, v0, v3, vcc
	v_lshlrev_b32_e32 v29, 2, v3
	v_xor_b32_e32 v3, 16, v0
	v_cmp_lt_i32_e32 vcc, v3, v2
	s_nop 0
	s_nop 0
	v_cndmask_b32_e32 v3, v0, v3, vcc
	v_lshlrev_b32_e32 v32, 2, v3
	v_xor_b32_e32 v3, 8, v0
	v_cmp_lt_i32_e32 vcc, v3, v2
	s_nop 0
	s_nop 0
	v_cndmask_b32_e32 v3, v0, v3, vcc
	v_lshlrev_b32_e32 v33, 2, v3
	v_xor_b32_e32 v3, 4, v0
	v_cmp_lt_i32_e32 vcc, v3, v2
	v_readlane_b32 s52, v251, 50
	v_readlane_b32 s53, v251, 51
	v_cndmask_b32_e32 v3, v0, v3, vcc
	v_lshlrev_b32_e32 v34, 2, v3
	v_xor_b32_e32 v3, 2, v0
	v_cmp_lt_i32_e32 vcc, v3, v2
	s_addc_u32 s3, s17, 0
	v_readlane_b32 s54, v251, 52
	v_cndmask_b32_e32 v3, v0, v3, vcc
	v_lshlrev_b32_e32 v35, 2, v3
	v_xor_b32_e32 v3, 1, v0
	v_readlane_b32 s55, v251, 53
	s_mov_b64 s[48:49], s[52:53]
	v_readlane_b32 s4, v248, 13
	v_cmp_lt_i32_e32 vcc, v3, v2
	s_add_u32 s4, s48, s4
	v_readlane_b32 s6, v248, 12
	v_cndmask_b32_e32 v0, v0, v3, vcc
	s_addc_u32 s7, s49, s6
	v_lshlrev_b32_e32 v36, 2, v0
	v_lshlrev_b32_e32 v0, 3, v1
	s_add_u32 s6, s4, 0x1000
	v_or_b32_e32 v2, 0x200, v0
	s_addc_u32 s7, s7, 0
	v_lshlrev_b32_e32 v96, 2, v2
	v_ashrrev_i32_e32 v13, 31, v12
	v_lshl_add_u64 v[14:15], s[6:7], 0, v[96:97]
	v_lshlrev_b32_e32 v96, 5, v1
	v_lshlrev_b64 v[18:19], 11, v[12:13]
	v_lshlrev_b64 v[20:21], 12, v[12:13]
	v_lshl_add_u64 v[16:17], s[6:7], 0, v[96:97]
	v_lshl_or_b32 v18, v1, 4, v18
	v_or_b32_e32 v20, v20, v96
	s_mov_b64 s[6:7], 0
	v_lshlrev_b32_e32 v96, 2, v0
	v_lshlrev_b32_e32 v22, 2, v2
	v_readlane_b32 s41, v251, 39
	v_readlane_b32 s42, v251, 40
	v_readlane_b32 s43, v251, 41
	v_readlane_b32 s44, v251, 42
	v_readlane_b32 s45, v251, 43
	v_readlane_b32 s46, v251, 44
	v_readlane_b32 s47, v251, 45
	s_mov_b64 s[50:51], s[54:55]

.LBB0_483:
	v_mbcnt_hi_u32_b32 v98, -1, v195
	v_and_b32_e32 v132, 64, v98
	v_xor_b32_e32 v99, 32, v98
	v_add_u32_e32 v132, 64, v132
	v_cmp_lt_i32_e32 vcc, v99, v132
	v_cvt_pk_bf16_f32 v48, v48, v49
	v_cvt_pk_bf16_f32 v49, v50, v51
	v_cvt_pk_bf16_f32 v51, v54, v55
	v_cvt_pk_bf16_f32 v32, v32, v33
	v_cvt_pk_bf16_f32 v33, v34, v35
	v_cvt_pk_bf16_f32 v34, v36, v37
	v_cvt_pk_bf16_f32 v50, v52, v53
	v_cndmask_b32_e64 v53, v49, v51, s[38:39]
	v_cndmask_b32_e64 v36, v32, v34, s[38:39]
	v_mov_b32_e32 v133, v53
	v_mov_b32_e32 v255, v53
	s_nop 1
	v_permlane32_swap_b32_e32 v133, v255
	s_nop 1
	v_mov_b32_dpp v133, v255 quad_perm:[0,1,2,3] row_mask:0x3 bank_mask:0xf
	v_cvt_pk_bf16_f32 v35, v38, v39
	v_mov_b32_e32 v38, v36
	v_mov_b32_e32 v255, v36
	s_nop 1
	v_permlane32_swap_b32_e32 v38, v255
	s_nop 1
	v_mov_b32_dpp v38, v255 quad_perm:[0,1,2,3] row_mask:0x3 bank_mask:0xf
	v_cndmask_b32_e64 v52, v48, v50, s[38:39]
	v_mov_b32_e32 v99, v52
	v_mov_b32_e32 v255, v52
	s_nop 1
	v_permlane32_swap_b32_e32 v99, v255
	s_nop 1
	v_mov_b32_dpp v99, v255 quad_perm:[0,1,2,3] row_mask:0x3 bank_mask:0xf
	v_cvt_pk_bf16_f32 v16, v16, v17
	v_cvt_pk_bf16_f32 v17, v18, v19
	v_cvt_pk_bf16_f32 v18, v20, v21
	v_cvt_pk_bf16_f32 v19, v22, v23
	v_cvt_pk_bf16_f32 v0, v0, v1
	v_cvt_pk_bf16_f32 v1, v2, v3
	v_cvt_pk_bf16_f32 v2, v4, v5
	v_cvt_pk_bf16_f32 v3, v6, v7
	s_waitcnt lgkmcnt(0)
	v_cndmask_b32_e64 v49, v133, v49, s[38:39]
	v_cndmask_b32_e64 v51, v51, v133, s[38:39]
	v_cvt_pk_bf16_f32 v133, v56, v57
	v_cvt_pk_bf16_f32 v58, v58, v59
	v_cvt_pk_bf16_f32 v59, v60, v61
	v_cvt_pk_bf16_f32 v60, v62, v63
	v_cndmask_b32_e64 v37, v33, v35, s[38:39]
	v_cndmask_b32_e64 v32, v38, v32, s[38:39]
	v_cndmask_b32_e64 v34, v34, v38, s[38:39]
	v_cvt_pk_bf16_f32 v38, v40, v41
	v_cvt_pk_bf16_f32 v40, v42, v43
	v_cvt_pk_bf16_f32 v41, v44, v45
	v_cvt_pk_bf16_f32 v42, v46, v47
	v_cndmask_b32_e64 v20, v16, v18, s[38:39]
	v_cndmask_b32_e64 v21, v17, v19, s[38:39]
	v_cvt_pk_bf16_f32 v22, v24, v25
	v_cvt_pk_bf16_f32 v23, v26, v27
	v_cvt_pk_bf16_f32 v24, v28, v29
	v_cvt_pk_bf16_f32 v25, v30, v31
	v_cndmask_b32_e64 v4, v0, v2, s[38:39]
	v_cndmask_b32_e64 v5, v1, v3, s[38:39]
	v_cvt_pk_bf16_f32 v6, v8, v9
	v_cvt_pk_bf16_f32 v7, v10, v11
	v_cvt_pk_bf16_f32 v8, v12, v13
	v_cvt_pk_bf16_f32 v9, v14, v15
	v_cndmask_b32_e64 v56, v133, v59, s[38:39]
	v_cndmask_b32_e64 v57, v58, v60, s[38:39]
	v_mov_b32_e32 v39, v37
	v_mov_b32_e32 v255, v37
	s_nop 1
	v_permlane32_swap_b32_e32 v39, v255
	s_nop 1
	v_mov_b32_dpp v39, v255 quad_perm:[0,1,2,3] row_mask:0x3 bank_mask:0xf
	v_cndmask_b32_e64 v43, v38, v41, s[38:39]
	v_cndmask_b32_e64 v44, v40, v42, s[38:39]
	v_mov_b32_e32 v255, v20
	s_nop 1
	v_permlane32_swap_b32_e32 v20, v255
	s_nop 1
	v_mov_b32_dpp v20, v255 quad_perm:[0,1,2,3] row_mask:0x3 bank_mask:0xf
	v_mov_b32_e32 v255, v21
	s_nop 1
	v_permlane32_swap_b32_e32 v21, v255
	s_nop 1
	v_mov_b32_dpp v21, v255 quad_perm:[0,1,2,3] row_mask:0x3 bank_mask:0xf
	v_cndmask_b32_e64 v26, v22, v24, s[38:39]
	v_cndmask_b32_e64 v27, v23, v25, s[38:39]
	v_mov_b32_e32 v255, v4
	s_nop 1
	v_permlane32_swap_b32_e32 v4, v255
	s_nop 1
	v_mov_b32_dpp v4, v255 quad_perm:[0,1,2,3] row_mask:0x3 bank_mask:0xf
	v_mov_b32_e32 v255, v5
	s_nop 1
	v_permlane32_swap_b32_e32 v5, v255
	s_nop 1
	v_mov_b32_dpp v5, v255 quad_perm:[0,1,2,3] row_mask:0x3 bank_mask:0xf
	v_cndmask_b32_e64 v10, v6, v8, s[38:39]
	v_cndmask_b32_e64 v11, v7, v9, s[38:39]
	v_lshl_or_b32 v98, s2, 7, v176
	v_readlane_b32 s2, v249, 7
	v_mov_b32_e32 v61, v56
	v_mov_b32_e32 v255, v56
	s_nop 1
	v_permlane32_swap_b32_e32 v61, v255
	s_nop 1
	v_mov_b32_dpp v61, v255 quad_perm:[0,1,2,3] row_mask:0x3 bank_mask:0xf
	v_mov_b32_e32 v62, v57
	v_mov_b32_e32 v255, v57
	s_nop 1
	v_permlane32_swap_b32_e32 v62, v255
	s_nop 1
	v_mov_b32_dpp v62, v255 quad_perm:[0,1,2,3] row_mask:0x3 bank_mask:0xf
	v_mov_b32_e32 v255, v43
	s_nop 1
	v_permlane32_swap_b32_e32 v43, v255
	s_nop 1
	v_mov_b32_dpp v43, v255 quad_perm:[0,1,2,3] row_mask:0x3 bank_mask:0xf
	v_mov_b32_e32 v255, v44
	s_nop 1
	v_permlane32_swap_b32_e32 v44, v255
	s_nop 1
	v_mov_b32_dpp v44, v255 quad_perm:[0,1,2,3] row_mask:0x3 bank_mask:0xf
	v_mov_b32_e32 v255, v26
	s_nop 1
	v_permlane32_swap_b32_e32 v26, v255
	s_nop 1
	v_mov_b32_dpp v26, v255 quad_perm:[0,1,2,3] row_mask:0x3 bank_mask:0xf
	v_mov_b32_e32 v255, v27
	s_nop 1
	v_permlane32_swap_b32_e32 v27, v255
	s_nop 1
	v_mov_b32_dpp v27, v255 quad_perm:[0,1,2,3] row_mask:0x3 bank_mask:0xf
	v_mov_b32_e32 v255, v10
	s_nop 1
	v_permlane32_swap_b32_e32 v10, v255
	s_nop 1
	v_mov_b32_dpp v10, v255 quad_perm:[0,1,2,3] row_mask:0x3 bank_mask:0xf
	v_mov_b32_e32 v255, v11
	s_nop 1
	v_permlane32_swap_b32_e32 v11, v255
	s_nop 1
	v_mov_b32_dpp v11, v255 quad_perm:[0,1,2,3] row_mask:0x3 bank_mask:0xf
	v_lshl_add_u32 v96, s6, 7, v175
	v_readlane_b32 s3, v249, 8
	v_cndmask_b32_e64 v48, v99, v48, s[38:39]
	v_cndmask_b32_e64 v50, v50, v99, s[38:39]
	v_mov_b64_e32 v[52:53], s[2:3]
	v_ashrrev_i32_e32 v99, 31, v98
	v_or_b32_e32 v36, 32, v96
	v_mad_i64_i32 v[54:55], s[2:3], v96, s74, v[52:53]
	v_lshlrev_b64 v[56:57], 1, v[98:99]
	v_mad_i64_i32 v[36:37], s[2:3], v36, s74, v[52:53]
	v_lshl_add_u64 v[54:55], v[54:55], 0, v[56:57]
	v_cndmask_b32_e64 v33, v39, v33, s[38:39]
	v_cndmask_b32_e64 v35, v35, v39, s[38:39]
	v_lshl_add_u64 v[36:37], v[36:37], 0, v[56:57]
	v_cndmask_b32_e64 v16, v20, v16, s[38:39]
	v_cndmask_b32_e64 v17, v21, v17, s[38:39]
	v_cndmask_b32_e64 v18, v18, v20, s[38:39]
	v_cndmask_b32_e64 v19, v19, v21, s[38:39]
	v_cndmask_b32_e64 v0, v4, v0, s[38:39]
	v_cndmask_b32_e64 v1, v5, v1, s[38:39]
	v_cndmask_b32_e64 v2, v2, v4, s[38:39]
	v_cndmask_b32_e64 v3, v3, v5, s[38:39]
	global_store_dwordx4 v[54:55], v[48:51], off
	global_store_dwordx4 v[36:37], v[32:35], off
	global_store_dwordx4 v[54:55], v[16:19], off offset:64
	v_cndmask_b32_e64 v48, v61, v133, s[38:39]
	v_cndmask_b32_e64 v49, v62, v58, s[38:39]
	v_cndmask_b32_e64 v50, v59, v61, s[38:39]
	v_cndmask_b32_e64 v51, v60, v62, s[38:39]
	v_cndmask_b32_e64 v32, v43, v38, s[38:39]
	v_cndmask_b32_e64 v33, v44, v40, s[38:39]
	v_cndmask_b32_e64 v34, v41, v43, s[38:39]
	v_cndmask_b32_e64 v35, v42, v44, s[38:39]
	v_cndmask_b32_e64 v16, v26, v22, s[38:39]
	v_cndmask_b32_e64 v17, v27, v23, s[38:39]
	v_cndmask_b32_e64 v18, v24, v26, s[38:39]
	v_cndmask_b32_e64 v19, v25, v27, s[38:39]
	global_store_dwordx4 v[36:37], v[0:3], off offset:64
	global_store_dwordx4 v[54:55], v[48:51], off offset:32
	global_store_dwordx4 v[36:37], v[32:35], off offset:32
	v_cndmask_b32_e64 v0, v10, v6, s[38:39]
	v_cndmask_b32_e64 v1, v11, v7, s[38:39]
	v_cndmask_b32_e64 v2, v8, v10, s[38:39]
	v_cndmask_b32_e64 v3, v9, v11, s[38:39]
	global_store_dwordx4 v[54:55], v[16:19], off offset:96
	global_store_dwordx4 v[36:37], v[0:3], off offset:96
	s_branch .LBB0_442

.LBB0_537:
	s_cmpk_gt_i32 s2, 0x47f
	s_mov_b64 s[0:1], -1
	s_cbranch_scc0 .LBB0_586
	s_cmpk_gt_u32 s2, 0xd7f
	s_cbranch_scc0 .LBB0_544
	s_nop 0
	s_nop 0
	v_and_b32_e32 v4, 63, v162
	v_or_b32_e32 v96, s44, v4
	s_waitcnt lgkmcnt(0)
	v_lshlrev_b64 v[0:1], 2, v[96:97]
	v_readlane_b32 s16, v251, 28
	v_readlane_b32 s17, v251, 29
	v_readlane_b32 s18, v251, 30
	v_readlane_b32 s19, v251, 31
	v_mov_b32_e32 v6, v162
	v_lshl_add_u64 v[2:3], s[16:17], 0, v[0:1]
	v_lshl_add_u64 v[0:1], s[18:19], 0, v[0:1]
	global_load_dword v12, v[2:3], off
	global_load_dword v13, v[0:1], off
	v_and_b32_e32 v0, 15, v162
	v_cvt_f32_ubyte0_e32 v0, v0
	v_mul_f32_e32 v1, 0xbf549a78, v0
	s_mov_b32 s0, 0xc2fc0000
	v_cmp_gt_f32_e32 vcc, s0, v1
	s_lshl_b32 s0, s2, 5
	s_add_i32 s0, s0, 0xfffe5000
	v_cndmask_b32_e32 v1, 0, v197, vcc
	v_fmac_f32_e32 v1, 0xbf549a78, v0
	v_exp_f32_e32 v0, v1
	v_cndmask_b32_e32 v1, 0, v198, vcc
	v_mbcnt_hi_u32_b32 v2, -1, v195
	v_and_b32_e32 v3, 64, v2
	v_ldexp_f32 v14, v0, v1
	v_ashrrev_i32_e32 v0, 3, v6
	v_and_b32_e32 v6, -8, v0
	v_add_u32_e32 v7, s0, v6
	v_readlane_b32 s0, v249, 13
	v_and_b32_e32 v0, 16, v162
	v_lshlrev_b32_e32 v96, 1, v4
	v_readlane_b32 s1, v249, 14
	v_add_u32_e32 v3, 64, v3
	v_xor_b32_e32 v5, 32, v2
	v_cmp_eq_u32_e32 vcc, 0, v0
	v_lshl_add_u64 v[0:1], s[0:1], 0, v[96:97]
	v_cmp_lt_i32_e64 s[0:1], v5, v3
	s_nop 0
	s_mov_b32 s3, 0
	v_cndmask_b32_e64 v5, v2, v5, s[0:1]
	v_lshlrev_b32_e32 v15, 2, v5
	v_xor_b32_e32 v5, 16, v2
	v_cmp_lt_i32_e64 s[0:1], v5, v3
	v_cmp_gt_u32_e64 s[38:39], 32, v4
	v_bfe_u32 v21, v7, 6, 5
	v_cndmask_b32_e64 v5, v2, v5, s[0:1]
	v_lshlrev_b32_e32 v16, 2, v5
	v_xor_b32_e32 v5, 8, v2
	v_cmp_lt_i32_e64 s[0:1], v5, v3
	v_add_u32_e32 v22, s42, v6
	s_movk_i32 s8, 0x4000
	v_cndmask_b32_e64 v5, v2, v5, s[0:1]
	v_lshlrev_b32_e32 v17, 2, v5
	v_xor_b32_e32 v5, 4, v2
	v_cmp_lt_i32_e64 s[0:1], v5, v3
	s_mov_b32 s10, 0x3c800000
	v_readlane_b32 s9, v251, 21
	v_cndmask_b32_e64 v5, v2, v5, s[0:1]
	v_lshlrev_b32_e32 v18, 2, v5
	v_xor_b32_e32 v5, 2, v2
	v_cmp_lt_i32_e64 s[0:1], v5, v3
	v_readlane_b32 s11, v251, 23
	v_readlane_b32 s12, v251, 24
	v_cndmask_b32_e64 v5, v2, v5, s[0:1]
	v_lshlrev_b32_e32 v19, 2, v5
	v_xor_b32_e32 v5, 1, v2
	v_cmp_lt_i32_e64 s[0:1], v5, v3
	v_readlane_b32 s13, v251, 25
	v_readlane_b32 s14, v251, 26
	v_cndmask_b32_e64 v2, v2, v5, s[0:1]
	v_readlane_b32 s0, v249, 11
	v_readlane_b32 s1, v249, 12
	v_lshlrev_b32_e32 v20, 2, v2
	v_readlane_b32 s15, v251, 27
	v_lshl_add_u64 v[2:3], s[0:1], 0, v[96:97]
	v_lshlrev_b32_e32 v96, 1, v4
	v_readlane_b32 s20, v251, 32
	v_readlane_b32 s21, v251, 33
	v_readlane_b32 s22, v251, 34
	v_readlane_b32 s23, v251, 35
	s_branch .LBB0_541

.LBB0_544:
	s_and_b64 vcc, exec, s[0:1]
	s_cbranch_vccz .LBB0_639
	v_mov_b32_e32 v51, v162
	s_bfe_u32 s4, s2, 0x30001
	s_lshl_b32 s3, s4, 6
	s_waitcnt vmcnt(7)
	v_lshlrev_b32_e32 v66, 3, v51
	v_and_b32_e32 v50, 56, v66
	v_or_b32_e32 v14, s3, v50
	v_readlane_b32 s0, v248, 18
	v_readlane_b32 s8, v251, 4
	v_readlane_b32 s14, v251, 10
	s_waitcnt lgkmcnt(0)
	v_or_b32_e32 v0, s0, v14
	v_readlane_b32 s15, v251, 11
	v_mov_b32_e32 v1, v97
	s_mov_b64 s[0:1], 0x1000
	v_lshl_add_u64 v[8:9], v[0:1], 2, s[14:15]
	v_or_b32_e32 v96, s34, v14
	v_readlane_b32 s16, v251, 12
	v_readlane_b32 s17, v251, 13
	v_lshl_add_u64 v[10:11], v[8:9], 0, s[0:1]
	s_mov_b64 s[0:1], 0x1800
	v_lshl_add_u64 v[2:3], v[96:97], 2, s[16:17]
	v_lshl_add_u64 v[12:13], v[8:9], 0, s[0:1]
	s_movk_i32 s0, 0x1000
	s_barrier
	global_load_dwordx4 v[4:7], v[2:3], off offset:16
	s_nop 0
	global_load_dwordx4 v[0:3], v[2:3], off
	s_nop 0
	global_load_dwordx4 v[44:47], v[8:9], off offset:16
	global_load_dwordx4 v[40:43], v[8:9], off
	global_load_dwordx4 v[36:39], v[8:9], off offset:2064
	global_load_dwordx4 v[32:35], v[8:9], off offset:2048
	v_add_co_u32_e32 v8, vcc, s0, v8
	s_add_i32 s0, s2, 0xfffffb80
	s_nop 0
	v_addc_co_u32_e32 v9, vcc, 0, v9, vcc
	global_load_dwordx4 v[24:27], v[8:9], off
	global_load_dwordx4 v[16:19], v[8:9], off offset:2048
	global_load_dwordx4 v[28:31], v[10:11], off offset:16
	global_load_dwordx4 v[20:23], v[12:13], off offset:16
	s_lshr_b32 s1, s0, 4
	s_mul_i32 s6, s1, 57
	s_bfe_u32 s6, s6, 0x6000a
	s_mul_i32 s6, s6, 18
	s_sub_i32 s1, s1, s6
	s_mul_i32 s0, s0, 0xe38f
	s_and_b32 s43, s1, 0xff
	s_lshr_b32 s45, s0, 24
	s_lshl_b32 s0, s45, 8
	s_lshl_b32 s38, s43, 7
	s_lshl_b32 s1, s45, 11
	s_addk_i32 s0, 0x4000
	s_add_i32 s39, s38, 0xffffff00
	s_cmp_lt_u32 s43, 2
	s_movk_i32 s6, 0x800
	s_cselect_b32 s38, s38, s39
	v_ashrrev_i32_e32 v52, 3, v51
	s_cselect_b32 s7, 0x100, s6
	s_cselect_b32 s6, s0, s1
	v_readlane_b32 s0, v249, 7
	v_add_u32_e32 v53, s38, v52
	v_lshlrev_b32_e32 v96, 1, v14
	v_readlane_b32 s1, v249, 8
	v_add_u32_e32 v54, -2, v53
	v_cmp_lt_i32_e32 vcc, 1, v53
	v_lshl_add_u64 v[48:49], s[0:1], 0, v[96:97]
	v_cmp_gt_u32_e64 s[0:1], s7, v54
	s_and_b64 s[40:41], vcc, s[0:1]
	v_readlane_b32 s9, v251, 5
	v_readlane_b32 s10, v251, 6
	v_readlane_b32 s11, v251, 7
	v_readlane_b32 s12, v251, 8
	v_readlane_b32 s13, v251, 9
	v_readlane_b32 s18, v251, 14
	v_readlane_b32 s19, v251, 15
	v_readlane_b32 s20, v251, 16
	v_readlane_b32 s21, v251, 17
	v_readlane_b32 s22, v251, 18
	v_readlane_b32 s23, v251, 19
	s_waitcnt vmcnt(8)
	v_mov_b64_e32 v[8:9], v[0:1]
	v_mov_b32_e32 v206, 0
	v_mov_b32_e32 v207, 0
	v_mov_b32_e32 v208, 0
	v_mov_b32_e32 v209, 0
	s_and_saveexec_b64 s[0:1], s[40:41]
	s_cbranch_execz .Lrg1_i
	v_add_u32_e32 v8, s6, v54
	v_mad_u64_u32 v[8:9], s[40:41], v8, s74, v[48:49]
	global_load_dwordx4 v[206:209], v[8:9], off

.Lrg4_i:
	s_or_b64 exec, exec, s[0:1]
	s_waitcnt vmcnt(0)
	s_nop 0
	v_mov_b32_e32 v9, v207
	v_mov_b32_e32 v10, v208
	v_mov_b32_e32 v11, v209
	v_lshlrev_b32_e32 v54, 16, v206
	v_and_b32_e32 v55, 0xffff0000, v206
	v_lshlrev_b32_e32 v8, 16, v9
	v_and_b32_e32 v9, 0xffff0000, v9
	v_lshlrev_b32_e32 v12, 16, v10
	v_and_b32_e32 v13, 0xffff0000, v10
	v_lshlrev_b32_e32 v10, 16, v11
	v_and_b32_e32 v11, 0xffff0000, v11
	v_pk_fma_f32 v[14:15], v[46:47], v[10:11], v[6:7]
	v_pk_fma_f32 v[12:13], v[44:45], v[12:13], v[4:5]
	v_pk_fma_f32 v[10:11], v[42:43], v[8:9], v[2:3]
	v_pk_fma_f32 v[8:9], v[40:41], v[54:55], v[0:1]
	v_mov_b32_e32 v55, v211
	v_mov_b32_e32 v56, v212
	v_mov_b32_e32 v57, v213
	v_lshlrev_b32_e32 v58, 16, v210
	v_and_b32_e32 v59, 0xffff0000, v210
	v_lshlrev_b32_e32 v54, 16, v55
	v_and_b32_e32 v55, 0xffff0000, v55
	v_lshlrev_b32_e32 v60, 16, v56
	v_and_b32_e32 v61, 0xffff0000, v56
	v_lshlrev_b32_e32 v56, 16, v57
	v_and_b32_e32 v57, 0xffff0000, v57
	v_pk_fma_f32 v[14:15], v[38:39], v[56:57], v[14:15]
	v_pk_fma_f32 v[12:13], v[36:37], v[60:61], v[12:13]
	v_pk_fma_f32 v[10:11], v[34:35], v[54:55], v[10:11]
	v_pk_fma_f32 v[8:9], v[32:33], v[58:59], v[8:9]
	v_mov_b32_e32 v55, v215
	v_mov_b32_e32 v56, v216
	v_mov_b32_e32 v57, v217
	v_lshlrev_b32_e32 v58, 16, v214
	v_and_b32_e32 v59, 0xffff0000, v214
	v_lshlrev_b32_e32 v54, 16, v55
	v_and_b32_e32 v55, 0xffff0000, v55
	v_lshlrev_b32_e32 v60, 16, v56
	v_and_b32_e32 v61, 0xffff0000, v56
	v_lshlrev_b32_e32 v56, 16, v57
	v_and_b32_e32 v57, 0xffff0000, v57
	v_pk_fma_f32 v[14:15], v[30:31], v[56:57], v[14:15]
	v_pk_fma_f32 v[12:13], v[28:29], v[60:61], v[12:13]
	v_pk_fma_f32 v[10:11], v[26:27], v[54:55], v[10:11]
	v_pk_fma_f32 v[8:9], v[24:25], v[58:59], v[8:9]
	v_mov_b32_e32 v55, v219
	v_mov_b32_e32 v56, v220
	v_mov_b32_e32 v57, v221
	v_lshlrev_b32_e32 v58, 16, v218
	v_and_b32_e32 v59, 0xffff0000, v218
	v_lshlrev_b32_e32 v54, 16, v55
	v_and_b32_e32 v55, 0xffff0000, v55
	v_lshlrev_b32_e32 v60, 16, v56
	v_and_b32_e32 v61, 0xffff0000, v56
	v_lshlrev_b32_e32 v56, 16, v57
	v_and_b32_e32 v57, 0xffff0000, v57
	v_pk_fma_f32 v[14:15], v[22:23], v[56:57], v[14:15]
	v_pk_fma_f32 v[12:13], v[20:21], v[60:61], v[12:13]
	v_pk_fma_f32 v[10:11], v[18:19], v[54:55], v[10:11]
	v_pk_fma_f32 v[8:9], v[16:17], v[58:59], v[8:9]
	v_lshl_add_u32 v53, v50, 2, 0
	v_lshl_add_u32 v54, v52, 8, v53
	v_lshlrev_b32_e32 v50, 1, v50
	ds_write_b128 v54, v[8:11] offset:36864
	ds_write_b128 v54, v[12:15] offset:36880
	v_add_u32_e32 v54, 32, v52
	v_sub_u32_e32 v50, v53, v50
	s_movk_i32 s0, 0x90
	v_add_u32_e32 v55, s38, v54
	v_cvt_pk_bf16_f32 v8, v8, v9
	v_cvt_pk_bf16_f32 v9, v10, v11
	v_cvt_pk_bf16_f32 v10, v12, v13
	v_cvt_pk_bf16_f32 v11, v14, v15
	v_mad_u64_u32 v[12:13], s[0:1], v52, s0, v[50:51]
	v_add_u32_e32 v56, -2, v55
	ds_write_b128 v12, v[8:11]
	v_cmp_lt_i32_e32 vcc, 1, v55
	v_cmp_gt_u32_e64 s[0:1], s7, v56
	s_and_b64 s[40:41], vcc, s[0:1]
	v_mov_b64_e32 v[8:9], v[0:1]
	v_mov_b32_e32 v206, 0
	v_mov_b32_e32 v207, 0
	v_mov_b32_e32 v208, 0
	v_mov_b32_e32 v209, 0
	s_and_saveexec_b64 s[0:1], s[40:41]
	s_cbranch_execz .Lrg5_i
	v_add_u32_e32 v8, s6, v56
	v_mad_u64_u32 v[8:9], s[40:41], v8, s74, v[48:49]
	global_load_dwordx4 v[206:209], v[8:9], off

.Lrg8_i:
	s_or_b64 exec, exec, s[0:1]
	s_waitcnt vmcnt(0)
	s_nop 0
	v_mov_b32_e32 v9, v207
	v_mov_b32_e32 v10, v208
	v_mov_b32_e32 v11, v209
	v_lshlrev_b32_e32 v56, 16, v206
	v_and_b32_e32 v57, 0xffff0000, v206
	v_lshlrev_b32_e32 v8, 16, v9
	v_and_b32_e32 v9, 0xffff0000, v9
	v_lshlrev_b32_e32 v12, 16, v10
	v_and_b32_e32 v13, 0xffff0000, v10
	v_lshlrev_b32_e32 v10, 16, v11
	v_and_b32_e32 v11, 0xffff0000, v11
	v_pk_fma_f32 v[14:15], v[46:47], v[10:11], v[6:7]
	v_pk_fma_f32 v[12:13], v[44:45], v[12:13], v[4:5]
	v_pk_fma_f32 v[10:11], v[42:43], v[8:9], v[2:3]
	v_pk_fma_f32 v[8:9], v[40:41], v[56:57], v[0:1]
	v_mov_b32_e32 v57, v211
	v_mov_b32_e32 v58, v212
	v_mov_b32_e32 v59, v213
	v_lshlrev_b32_e32 v60, 16, v210
	v_and_b32_e32 v61, 0xffff0000, v210
	v_lshlrev_b32_e32 v56, 16, v57
	v_and_b32_e32 v57, 0xffff0000, v57
	v_lshlrev_b32_e32 v62, 16, v58
	v_and_b32_e32 v63, 0xffff0000, v58
	v_lshlrev_b32_e32 v58, 16, v59
	v_and_b32_e32 v59, 0xffff0000, v59
	v_pk_fma_f32 v[14:15], v[38:39], v[58:59], v[14:15]
	v_pk_fma_f32 v[12:13], v[36:37], v[62:63], v[12:13]
	v_pk_fma_f32 v[10:11], v[34:35], v[56:57], v[10:11]
	v_pk_fma_f32 v[8:9], v[32:33], v[60:61], v[8:9]
	v_mov_b32_e32 v57, v215
	v_mov_b32_e32 v58, v216
	v_mov_b32_e32 v59, v217
	v_lshlrev_b32_e32 v60, 16, v214
	v_and_b32_e32 v61, 0xffff0000, v214
	v_lshlrev_b32_e32 v56, 16, v57
	v_and_b32_e32 v57, 0xffff0000, v57
	v_lshlrev_b32_e32 v62, 16, v58
	v_and_b32_e32 v63, 0xffff0000, v58
	v_lshlrev_b32_e32 v58, 16, v59
	v_and_b32_e32 v59, 0xffff0000, v59
	v_pk_fma_f32 v[14:15], v[30:31], v[58:59], v[14:15]
	v_pk_fma_f32 v[12:13], v[28:29], v[62:63], v[12:13]
	v_pk_fma_f32 v[10:11], v[26:27], v[56:57], v[10:11]
	v_pk_fma_f32 v[8:9], v[24:25], v[60:61], v[8:9]
	v_mov_b32_e32 v57, v219
	v_mov_b32_e32 v58, v220
	v_mov_b32_e32 v59, v221
	v_lshlrev_b32_e32 v60, 16, v218
	v_and_b32_e32 v61, 0xffff0000, v218
	v_lshlrev_b32_e32 v56, 16, v57
	v_and_b32_e32 v57, 0xffff0000, v57
	v_lshlrev_b32_e32 v62, 16, v58
	v_and_b32_e32 v63, 0xffff0000, v58
	v_lshlrev_b32_e32 v58, 16, v59
	v_and_b32_e32 v59, 0xffff0000, v59
	v_pk_fma_f32 v[14:15], v[22:23], v[58:59], v[14:15]
	v_pk_fma_f32 v[12:13], v[20:21], v[62:63], v[12:13]
	v_pk_fma_f32 v[10:11], v[18:19], v[56:57], v[10:11]
	v_pk_fma_f32 v[8:9], v[16:17], v[60:61], v[8:9]
	v_lshl_add_u32 v55, v54, 8, v53
	s_movk_i32 s0, 0x90
	ds_write_b128 v55, v[8:11] offset:36864
	ds_write_b128 v55, v[12:15] offset:36880
	v_cvt_pk_bf16_f32 v8, v8, v9
	v_cvt_pk_bf16_f32 v9, v10, v11
	v_cvt_pk_bf16_f32 v10, v12, v13
	v_mad_u64_u32 v[12:13], s[0:1], v54, s0, v[50:51]
	v_add_u32_e32 v54, 64, v52
	v_add_u32_e32 v55, s38, v54
	v_cvt_pk_bf16_f32 v11, v14, v15
	v_add_u32_e32 v56, -2, v55
	ds_write_b128 v12, v[8:11]
	v_cmp_lt_i32_e32 vcc, 1, v55
	v_cmp_gt_u32_e64 s[0:1], s7, v56
	s_and_b64 s[40:41], vcc, s[0:1]
	v_mov_b64_e32 v[8:9], v[0:1]
	v_mov_b32_e32 v206, 0
	v_mov_b32_e32 v207, 0
	v_mov_b32_e32 v208, 0
	v_mov_b32_e32 v209, 0
	s_and_saveexec_b64 s[0:1], s[40:41]
	s_cbranch_execz .Lrg9_i
	v_add_u32_e32 v8, s6, v56
	v_mad_u64_u32 v[8:9], s[40:41], v8, s74, v[48:49]
	global_load_dwordx4 v[206:209], v[8:9], off

.LBB0_578:
	v_add_u32_e32 v2, s4, v0
	s_addk_i32 s4, 0x800
	v_mov_b32_e32 v222, v2
	v_ashrrev_i32_e32 v223, 31, v222
	v_lshlrev_b64 v[222:223], 2, v[222:223]
	v_lshl_add_u64 v[224:225], s[0:1], 0, v[222:223]
	global_load_dword v206, v[224:225], off
	global_load_dword v207, v[224:225], off offset:256
	v_lshl_add_u64 v[224:225], s[6:7], 0, v[222:223]
	global_load_dword v208, v[224:225], off
	global_load_dword v209, v[224:225], off offset:256
	v_add_u32_e32 v222, 0x200, v2
	v_ashrrev_i32_e32 v223, 31, v222
	v_lshlrev_b64 v[222:223], 2, v[222:223]
	v_lshl_add_u64 v[224:225], s[0:1], 0, v[222:223]
	global_load_dword v210, v[224:225], off
	global_load_dword v211, v[224:225], off offset:256
	v_lshl_add_u64 v[224:225], s[6:7], 0, v[222:223]
	global_load_dword v212, v[224:225], off
	global_load_dword v213, v[224:225], off offset:256
	v_add_u32_e32 v222, 0x400, v2
	v_ashrrev_i32_e32 v223, 31, v222
	v_lshlrev_b64 v[222:223], 2, v[222:223]
	v_lshl_add_u64 v[224:225], s[0:1], 0, v[222:223]
	global_load_dword v214, v[224:225], off
	global_load_dword v215, v[224:225], off offset:256
	v_lshl_add_u64 v[224:225], s[6:7], 0, v[222:223]
	global_load_dword v216, v[224:225], off
	global_load_dword v217, v[224:225], off offset:256
	v_add_u32_e32 v222, 0x600, v2
	v_ashrrev_i32_e32 v223, 31, v222
	v_lshlrev_b64 v[222:223], 2, v[222:223]
	v_lshl_add_u64 v[224:225], s[0:1], 0, v[222:223]
	global_load_dword v218, v[224:225], off
	global_load_dword v219, v[224:225], off offset:256
	v_lshl_add_u64 v[224:225], s[6:7], 0, v[222:223]
	global_load_dword v220, v[224:225], off
	global_load_dword v221, v[224:225], off offset:256
	v_add_u32_e32 v2, s4, v0
	s_addk_i32 s4, 0x800
	v_mov_b32_e32 v222, v2
	v_ashrrev_i32_e32 v223, 31, v222
	v_lshlrev_b64 v[222:223], 2, v[222:223]
	v_lshl_add_u64 v[224:225], s[0:1], 0, v[222:223]
	global_load_dword v10, v[224:225], off
	global_load_dword v11, v[224:225], off offset:256
	v_lshl_add_u64 v[224:225], s[6:7], 0, v[222:223]
	global_load_dword v12, v[224:225], off
	global_load_dword v13, v[224:225], off offset:256
	v_add_u32_e32 v222, 0x200, v2
	v_ashrrev_i32_e32 v223, 31, v222
	v_lshlrev_b64 v[222:223], 2, v[222:223]
	v_lshl_add_u64 v[224:225], s[0:1], 0, v[222:223]
	global_load_dword v14, v[224:225], off
	global_load_dword v15, v[224:225], off offset:256
	v_lshl_add_u64 v[224:225], s[6:7], 0, v[222:223]
	global_load_dword v16, v[224:225], off
	global_load_dword v17, v[224:225], off offset:256
	v_add_u32_e32 v222, 0x400, v2
	v_ashrrev_i32_e32 v223, 31, v222
	v_lshlrev_b64 v[222:223], 2, v[222:223]
	v_lshl_add_u64 v[224:225], s[0:1], 0, v[222:223]
	global_load_dword v18, v[224:225], off
	global_load_dword v19, v[224:225], off offset:256
	v_lshl_add_u64 v[224:225], s[6:7], 0, v[222:223]
	global_load_dword v20, v[224:225], off
	global_load_dword v21, v[224:225], off offset:256
	v_add_u32_e32 v222, 0x600, v2
	v_ashrrev_i32_e32 v223, 31, v222
	v_lshlrev_b64 v[222:223], 2, v[222:223]
	v_lshl_add_u64 v[224:225], s[0:1], 0, v[222:223]
	global_load_dword v22, v[224:225], off
	global_load_dword v23, v[224:225], off offset:256
	v_lshl_add_u64 v[224:225], s[6:7], 0, v[222:223]
	global_load_dword v24, v[224:225], off
	global_load_dword v25, v[224:225], off offset:256
	v_add_u32_e32 v9, 0x2400, v1
	s_waitcnt vmcnt(16)
	v_cvt_pk_bf16_f32 v226, v206, v207
	v_cvt_pk_bf16_f32 v230, v208, v209
	v_cvt_pk_bf16_f32 v227, v210, v211
	v_cvt_pk_bf16_f32 v231, v212, v213
	v_cvt_pk_bf16_f32 v228, v214, v215
	v_cvt_pk_bf16_f32 v232, v216, v217
	v_cvt_pk_bf16_f32 v229, v218, v219
	v_cvt_pk_bf16_f32 v233, v220, v221
	ds_write2_b32 v1, v226, v227 offset1:4
	ds_write2_b32 v9, v230, v231 offset1:4
	ds_write2_b32 v1, v228, v229 offset0:8 offset1:12
	ds_write2_b32 v9, v232, v233 offset0:8 offset1:12
	v_add_u32_e32 v1, 64, v1
	v_add_u32_e32 v9, 0x2400, v1
	s_waitcnt vmcnt(0)
	v_cvt_pk_bf16_f32 v226, v10, v11
	v_cvt_pk_bf16_f32 v230, v12, v13
	v_cvt_pk_bf16_f32 v227, v14, v15
	v_cvt_pk_bf16_f32 v231, v16, v17
	v_cvt_pk_bf16_f32 v228, v18, v19
	v_cvt_pk_bf16_f32 v232, v20, v21
	v_cvt_pk_bf16_f32 v229, v22, v23
	v_cvt_pk_bf16_f32 v233, v24, v25
	ds_write2_b32 v1, v226, v227 offset1:4
	ds_write2_b32 v9, v230, v231 offset1:4
	ds_write2_b32 v1, v228, v229 offset0:8 offset1:12
	ds_write2_b32 v9, v232, v233 offset0:8 offset1:12
	s_cmpk_eq_i32 s4, 0x1000
	v_and_b32_e32 v71, 31, v51
	v_mul_u32_u24_e32 v0, 0x48, v71
	v_lshrrev_b32_e32 v1, 1, v51
	v_lshlrev_b32_e32 v0, 1, v0
	v_and_b32_e32 v1, 16, v1
	s_movk_i32 s0, 0x1200
	v_add3_u32 v67, 0, v0, v1
	v_mov_b32_e32 v0, 0
	v_mul_lo_u32 v65, v64, s0
	s_mov_b32 s0, -16
	v_mov_b32_e32 v1, v0
	v_mov_b32_e32 v2, v0
	v_mov_b32_e32 v3, v0
	v_mov_b32_e32 v4, v0
	v_mov_b32_e32 v5, v0
	v_mov_b32_e32 v6, v0
	v_mov_b32_e32 v7, v0
	v_mov_b32_e32 v8, v0
	v_mov_b32_e32 v9, v0
	v_mov_b32_e32 v10, v0
	v_mov_b32_e32 v11, v0
	v_mov_b32_e32 v12, v0
	v_mov_b32_e32 v13, v0
	v_mov_b32_e32 v14, v0
	v_mov_b32_e32 v15, v0
	v_mov_b32_e32 v32, v0
	v_mov_b32_e32 v33, v0
	v_mov_b32_e32 v34, v0
	v_mov_b32_e32 v35, v0
	v_mov_b32_e32 v36, v0
	v_mov_b32_e32 v37, v0
	v_mov_b32_e32 v38, v0
	v_mov_b32_e32 v39, v0
	v_mov_b32_e32 v40, v0
	v_mov_b32_e32 v41, v0
	v_mov_b32_e32 v42, v0
	v_mov_b32_e32 v43, v0
	v_mov_b32_e32 v44, v0
	v_mov_b32_e32 v45, v0
	v_mov_b32_e32 v46, v0
	v_mov_b32_e32 v47, v0
	v_mov_b32_e32 v16, v0
	v_mov_b32_e32 v17, v0
	v_mov_b32_e32 v18, v0
	v_mov_b32_e32 v19, v0
	v_mov_b32_e32 v20, v0
	v_mov_b32_e32 v21, v0
	v_mov_b32_e32 v22, v0
	v_mov_b32_e32 v23, v0
	v_mov_b32_e32 v24, v0
	v_mov_b32_e32 v25, v0
	v_mov_b32_e32 v26, v0
	v_mov_b32_e32 v27, v0
	v_mov_b32_e32 v28, v0
	v_mov_b32_e32 v29, v0
	v_mov_b32_e32 v30, v0
	v_mov_b32_e32 v31, v0
	v_mov_b32_e32 v48, v0
	v_mov_b32_e32 v49, v0
	v_mov_b32_e32 v50, v0
	v_mov_b32_e32 v51, v0
	v_mov_b32_e32 v52, v0
	v_mov_b32_e32 v53, v0
	v_mov_b32_e32 v54, v0
	v_mov_b32_e32 v55, v0
	v_mov_b32_e32 v56, v0
	v_mov_b32_e32 v57, v0
	v_mov_b32_e32 v58, v0
	v_mov_b32_e32 v59, v0
	v_mov_b32_e32 v60, v0
	v_mov_b32_e32 v61, v0
	v_mov_b32_e32 v62, v0
	v_mov_b32_e32 v63, v0
	s_waitcnt lgkmcnt(0)
	s_barrier
.LBB0_580:
	v_add_u32_e32 v68, v67, v65
	ds_read_b128 v[72:75], v67 offset:18432
	ds_read_b128 v[76:79], v68
	s_add_i32 s0, s0, 32
	s_cmp_lt_u32 s0, 48
	s_waitcnt lgkmcnt(0)
	v_mfma_f32_32x32x16_bf16 v[48:63], v[76:79], v[72:75], v[48:63]
	ds_read_b128 v[72:75], v67 offset:23040
	s_waitcnt lgkmcnt(0)
	v_mfma_f32_32x32x16_bf16 v[16:31], v[76:79], v[72:75], v[16:31]
	ds_read_b128 v[72:75], v67 offset:27648
	s_waitcnt lgkmcnt(0)
	v_mfma_f32_32x32x16_bf16 v[32:47], v[76:79], v[72:75], v[32:47]
	ds_read_b128 v[72:75], v67 offset:32256
	ds_read_b128 v[80:83], v67 offset:18464
	s_waitcnt lgkmcnt(1)
	v_mfma_f32_32x32x16_bf16 v[0:15], v[76:79], v[72:75], v[0:15]
	ds_read_b128 v[72:75], v68 offset:32
	ds_read_b128 v[76:79], v67 offset:23072
	s_waitcnt lgkmcnt(0)
	v_mfma_f32_32x32x16_bf16 v[16:31], v[72:75], v[76:79], v[16:31]
	ds_read_b128 v[76:79], v67 offset:27680
	s_waitcnt lgkmcnt(0)
	v_mfma_f32_32x32x16_bf16 v[32:47], v[72:75], v[76:79], v[32:47]
	ds_read_b128 v[76:79], v67 offset:32288
	v_add_u32_e32 v67, 64, v67
	v_mfma_f32_32x32x16_bf16 v[48:63], v[72:75], v[80:83], v[48:63]
	s_waitcnt lgkmcnt(0)
	v_mfma_f32_32x32x16_bf16 v[0:15], v[72:75], v[76:79], v[0:15]
	s_cbranch_scc1 .LBB0_580
	s_lshl_b32 s0, s39, 9
	s_or_b32 s6, s0, s3
	v_or_b32_e32 v96, s6, v71
	v_readlane_b32 s8, v251, 20
	v_lshlrev_b32_e32 v67, 11, v64
	v_lshlrev_b64 v[64:65], 2, v[96:97]
	v_readlane_b32 s10, v251, 22
	v_readlane_b32 s11, v251, 23
	s_barrier
	s_nop 0
	v_lshl_add_u64 v[68:69], s[10:11], 0, v[64:65]
	v_readlane_b32 s100, v251, 16
	v_readlane_b32 s101, v251, 17
	s_nop 1
	v_lshl_add_u64 v[220:221], s[100:101], 0, v[64:65]
	v_readlane_b32 s100, v251, 20
	v_readlane_b32 s101, v251, 21
	s_nop 1
	v_lshl_add_u64 v[222:223], s[100:101], 0, v[64:65]
	global_load_dword v224, v[220:221], off
	global_load_dword v225, v[222:223], off
	global_load_dword v226, v[68:69], off offset:128
	global_load_dword v227, v[222:223], off offset:128
	global_load_dword v228, v[220:221], off offset:128
	global_load_dword v68, v[68:69], off
	s_mov_b32 s7, 0x3f2aaaab
	s_mov_b32 s39, 0x3f317218
	v_readlane_b32 s12, v251, 4
	v_readlane_b32 s24, v251, 16
	v_readlane_b32 s25, v251, 17
	v_readlane_b32 s9, v251, 21
	s_mov_b32 s40, 0x7f800000
	s_mov_b32 s41, 0x33800000
	s_mov_b32 s15, 0x43000000
	s_mov_b32 s16, 0x42b17217
	s_mov_b32 s17, 0xf800000
	s_mov_b32 s18, 0xc1880000
	v_add_u32_e32 v96, s6, v71
	s_cmp_eq_u32 s38, 0
	s_mov_b32 s4, 0
	v_readlane_b32 s13, v251, 5
	v_readlane_b32 s14, v251, 6
	v_readlane_b32 s19, v251, 11
	v_readlane_b32 s20, v251, 12
	v_readlane_b32 s21, v251, 13
	v_readlane_b32 s22, v251, 14
	v_readlane_b32 s23, v251, 15
	v_readlane_b32 s26, v251, 18
	v_readlane_b32 s27, v251, 19
	s_waitcnt vmcnt(0)
	v_mul_f32_e32 v68, 0xbfb8aa3b, v68
	v_exp_f32_e32 v70, v68
	s_nop 0
	v_add_f32_e32 v72, 1.0, v70
	v_add_f32_e32 v68, -1.0, v72
	v_sub_f32_e32 v69, v68, v72
	v_add_f32_e32 v69, 1.0, v69
	v_sub_f32_e32 v68, v70, v68
	v_add_f32_e32 v73, v68, v69
	v_frexp_mant_f32_e32 v68, v72
	v_cmp_gt_f32_e32 vcc, s7, v68
	v_cvt_f64_f32_e32 v[68:69], v72
	v_frexp_exp_i32_f64_e32 v68, v[68:69]
	v_subbrev_co_u32_e32 v78, vcc, 0, v68, vcc
	v_sub_u32_e32 v68, 0, v78
	v_ldexp_f32 v69, v72, v68
	v_add_f32_e32 v72, -1.0, v69
	v_add_f32_e32 v74, 1.0, v69
	v_ldexp_f32 v68, v73, v68
	v_add_f32_e32 v73, 1.0, v72
	v_add_f32_e32 v75, -1.0, v74
	v_sub_f32_e32 v73, v69, v73
	v_sub_f32_e32 v69, v69, v75
	v_add_f32_e32 v73, v68, v73
	v_add_f32_e32 v68, v68, v69
	v_add_f32_e32 v79, v74, v68
	v_rcp_f32_e32 v81, v79
	v_sub_f32_e32 v69, v79, v74
	v_sub_f32_e32 v80, v68, v69
	v_add_f32_e32 v69, v72, v73
	v_mul_f32_e32 v83, v69, v81
	v_sub_f32_e32 v68, v69, v72
	v_mul_f32_e32 v72, v79, v83
	v_fma_f32 v74, v83, v79, -v72
	v_fmac_f32_e32 v74, v83, v80
	v_sub_f32_e32 v82, v73, v68
	v_add_f32_e32 v68, v72, v74
	v_sub_f32_e32 v73, v69, v68
	v_pk_add_f32 v[76:77], v[68:69], v[72:73] neg_lo:[0,1] neg_hi:[0,1]
	v_mov_b32_e32 v75, v68
	v_pk_add_f32 v[68:69], v[76:77], v[74:75] neg_lo:[0,1] neg_hi:[0,1]
	v_cmp_neq_f32_e32 vcc, s40, v70
	v_add_f32_e32 v69, v82, v69
	v_add_f32_e32 v68, v68, v69
	v_add_f32_e32 v69, v73, v68
	v_mul_f32_e32 v82, v81, v69
	v_mul_f32_e32 v72, v79, v82
	v_fma_f32 v74, v82, v79, -v72
	v_fmac_f32_e32 v74, v82, v80
	v_sub_f32_e32 v73, v73, v69
	v_add_f32_e32 v79, v68, v73
	v_add_f32_e32 v68, v72, v74
	v_sub_f32_e32 v73, v69, v68
	v_pk_add_f32 v[76:77], v[68:69], v[72:73] neg_lo:[0,1] neg_hi:[0,1]
	v_mov_b32_e32 v75, v68
	v_pk_add_f32 v[68:69], v[76:77], v[74:75] neg_lo:[0,1] neg_hi:[0,1]
	v_add_f32_e32 v69, v79, v69
	v_add_f32_e32 v68, v68, v69
	v_add_f32_e32 v69, v83, v82
	v_add_f32_e32 v68, v73, v68
	v_sub_f32_e32 v72, v69, v83
	v_mul_f32_e32 v68, v81, v68
	v_sub_f32_e32 v72, v82, v72
	v_add_f32_e32 v72, v72, v68
	v_add_f32_e32 v74, v69, v72
	v_mul_f32_e32 v75, v74, v74
	v_fmamk_f32 v68, v75, 0x3e9b6dac, v191
	v_fmaak_f32 v169, v75, v68, 0x3f2aaada
	v_cvt_f32_i32_e32 v68, v78
	v_sub_f32_e32 v69, v74, v69
	v_sub_f32_e32 v69, v72, v69
	v_ldexp_f32 v76, v69, 1
	v_mul_f32_e32 v69, v74, v75
	v_ldexp_f32 v73, v74, 1
	v_pk_mul_f32 v[74:75], v[68:69], v[168:169]
	v_fma_f32 v72, v68, s39, -v74
	v_fmac_f32_e32 v72, 0xb102e308, v68
	v_pk_add_f32 v[68:69], v[74:75], v[72:73]
	v_sub_f32_e32 v73, v69, v73
	v_sub_f32_e32 v73, v75, v73
	v_add_f32_e32 v77, v76, v73
	v_mov_b32_e32 v76, v74
	v_pk_add_f32 v[74:75], v[68:69], v[74:75] neg_lo:[0,1] neg_hi:[0,1]
	v_pk_add_f32 v[78:79], v[68:69], v[76:77]
	v_mov_b32_e32 v73, v68
	v_mov_b32_e32 v75, v79
	v_pk_add_f32 v[80:81], v[72:73], v[74:75] neg_lo:[0,1] neg_hi:[0,1]
	v_pk_add_f32 v[72:73], v[72:73], v[74:75]
	v_mov_b32_e32 v76, v77
	v_pk_add_f32 v[74:75], v[72:73], v[68:69] op_sel:[1,0] op_sel_hi:[0,1] neg_lo:[0,1] neg_hi:[0,1]
	v_pk_add_f32 v[82:83], v[78:79], v[74:75] op_sel_hi:[1,0] neg_lo:[0,1] neg_hi:[0,1]
	v_mov_b32_e32 v78, v79
	v_mov_b32_e32 v79, v73
	v_pk_mov_b32 v[74:75], v[68:69], v[74:75] op_sel:[1,0]
	v_mov_b32_e32 v77, v68
	v_pk_add_f32 v[74:75], v[78:79], v[74:75] neg_lo:[0,1] neg_hi:[0,1]
	v_mov_b32_e32 v82, v80
	v_pk_add_f32 v[68:69], v[76:77], v[74:75] neg_lo:[0,1] neg_hi:[0,1]
	v_mov_b32_e32 v81, v73
	v_pk_add_f32 v[74:75], v[82:83], v[68:69]
	v_pk_add_f32 v[76:77], v[74:75], v[74:75] op_sel:[0,1] op_sel_hi:[1,0]
	v_pk_add_f32 v[72:73], v[72:73], v[76:77] op_sel:[1,0] op_sel_hi:[0,1]
	v_mov_b32_e32 v75, v72
	v_pk_add_f32 v[78:79], v[74:75], v[80:81] neg_lo:[0,1] neg_hi:[0,1]
	v_mov_b32_e32 v69, v76
	v_sub_f32_e32 v73, v74, v78
	v_pk_add_f32 v[68:69], v[68:69], v[78:79] neg_lo:[0,1] neg_hi:[0,1]
	v_sub_f32_e32 v73, v80, v73
	v_add_f32_e32 v68, v68, v73
	v_add_f32_e32 v68, v68, v69
	v_add_f32_e32 v68, v72, v68
	v_mov_b32_e32 v74, v224
	v_mov_b32_e32 v73, v225
	v_cndmask_b32_e32 v68, v199, v68, vcc
	v_cmp_ngt_f32_e32 vcc, -1.0, v70
	s_waitcnt vmcnt(1)
	v_add_f32_e32 v48, v48, v74
	v_mul_f32_e32 v48, 0xbfb8aa3b, v48
	v_exp_f32_e32 v48, v48
	v_cndmask_b32_e32 v68, v200, v68, vcc
	v_cmp_neq_f32_e32 vcc, -1.0, v70
	s_waitcnt vmcnt(0)
	v_add_f32_e32 v32, v32, v73
	v_add_f32_e32 v48, 1.0, v48
	v_rcp_f32_e32 v48, v48
	v_cndmask_b32_e32 v68, v201, v68, vcc
	v_cmp_lt_f32_e64 vcc, |v70|, s41
	v_mul_f32_e32 v32, 0xbfb8aa3b, v32
	v_exp_f32_e32 v32, v32
	v_cndmask_b32_e32 v68, v68, v70, vcc
	v_mul_f32_e32 v72, 0xc1000000, v68
	v_mul_f32_e32 v48, v48, v72
	v_mul_f32_e32 v64, 0x3fb8aa3b, v48
	v_add_f32_e32 v48, v48, v48
	v_exp_f32_e32 v68, v64
	v_mul_f32_e32 v64, 0x3fb8aa3b, v48
	v_rndne_f32_e32 v64, v64
	v_fmamk_f32 v65, v64, 0xbf317218, v48
	v_fmac_f32_e32 v65, 0x3102e308, v64
	v_fmamk_f32 v69, v65, 0x395133b1, v192
	v_cmp_eq_f32_e32 vcc, s15, v64
	v_cvt_i32_f32_e32 v64, v64
	v_fmaak_f32 v69, v65, v69, 0x3c0887f9
	v_fmaak_f32 v69, v65, v69, 0x3d2aaa81
	v_fmaak_f32 v69, v65, v69, 0x3e2aaaab
	v_fma_f32 v69, v65, v69, 0.5
	v_ldexp_f32 v64, 1.0, v64
	v_mul_f32_e32 v69, v65, v69
	v_cndmask_b32_e32 v64, v64, v202, vcc
	v_fmac_f32_e32 v65, v65, v69
	v_add_f32_e32 v69, -1.0, v64
	v_fmac_f32_e32 v69, v64, v65
	v_add_f32_e32 v64, v69, v69
	v_cndmask_b32_e32 v64, v69, v64, vcc
	v_cmp_nlt_f32_e32 vcc, s16, v48
	v_add_f32_e32 v32, 1.0, v32
	v_rcp_f32_e32 v32, v32
	v_cndmask_b32_e64 v64, v201, -v64, vcc
	v_cmp_gt_f32_e32 vcc, s17, v64
	v_mul_f32_e32 v65, 0x4f800000, v64
	v_add_f32_e32 v33, v33, v73
	v_cndmask_b32_e32 v64, v64, v65, vcc
	v_sqrt_f32_e32 v65, v64
	v_mul_f32_e32 v33, 0xbfb8aa3b, v33
	v_exp_f32_e32 v33, v33
	v_add_f32_e32 v34, v34, v73
	v_add_u32_e32 v69, -1, v65
	v_fma_f32 v70, -v69, v65, v64
	v_cmp_ge_f32_e64 s[0:1], 0, v70
	v_add_u32_e32 v70, 1, v65
	v_add_f32_e32 v33, 1.0, v33
	v_cndmask_b32_e64 v69, v65, v69, s[0:1]
	v_fma_f32 v65, -v70, v65, v64
	v_cmp_lt_f32_e64 s[0:1], 0, v65
	v_rcp_f32_e32 v33, v33
	v_mul_f32_e32 v34, 0xbfb8aa3b, v34
	v_cndmask_b32_e64 v65, v69, v70, s[0:1]
	v_mul_f32_e32 v69, 0x37800000, v65
	v_cndmask_b32_e32 v65, v65, v69, vcc
	v_cmp_class_f32_e32 vcc, v64, v193
	v_exp_f32_e32 v34, v34
	s_nop 0
	v_cndmask_b32_e32 v64, v65, v64, vcc
	v_cmp_ngt_f32_e32 vcc, s18, v48
	v_add_f32_e32 v34, 1.0, v34
	v_rcp_f32_e32 v34, v34
	v_cndmask_b32_e32 v48, 1.0, v64, vcc
	v_mul_f32_e32 v48, v32, v48
	v_and_b32_e32 v32, 0x100, v66
	v_or3_b32 v32, v67, v71, v32
	v_lshl_add_u32 v70, v32, 2, 0
	v_add_u32_e32 v32, 0x9000, v70
	ds_read2_b32 v[64:65], v32 offset1:32
	s_waitcnt lgkmcnt(0)
	v_mul_f32_e32 v48, v64, v48
	ds_write_b32 v70, v68
	ds_write_b32 v70, v48 offset:36864
	v_add_f32_e32 v48, v49, v74
	v_mul_f32_e32 v48, 0xbfb8aa3b, v48
	v_exp_f32_e32 v48, v48
	s_nop 0
	v_add_f32_e32 v48, 1.0, v48
	v_rcp_f32_e32 v48, v48
	s_nop 0
	v_mul_f32_e32 v48, v48, v72
	v_mul_f32_e32 v49, 0x3fb8aa3b, v48
	v_add_f32_e32 v48, v48, v48
	v_exp_f32_e32 v64, v49
	v_mul_f32_e32 v49, 0x3fb8aa3b, v48
	v_rndne_f32_e32 v49, v49
	v_fmamk_f32 v66, v49, 0xbf317218, v48
	v_fmac_f32_e32 v66, 0x3102e308, v49
	v_fmamk_f32 v67, v66, 0x395133b1, v192
	v_cmp_eq_f32_e32 vcc, s15, v49
	v_cvt_i32_f32_e32 v49, v49
	v_fmaak_f32 v67, v66, v67, 0x3c0887f9
	v_fmaak_f32 v67, v66, v67, 0x3d2aaa81
	v_fmaak_f32 v67, v66, v67, 0x3e2aaaab
	v_fma_f32 v67, v66, v67, 0.5
	v_ldexp_f32 v49, 1.0, v49
	v_mul_f32_e32 v67, v66, v67
	v_cndmask_b32_e32 v49, v49, v202, vcc
	v_fmac_f32_e32 v66, v66, v67
	v_add_f32_e32 v67, -1.0, v49
	v_fmac_f32_e32 v67, v49, v66
	v_add_f32_e32 v49, v67, v67
	v_cndmask_b32_e32 v49, v67, v49, vcc
	v_cmp_nlt_f32_e32 vcc, s16, v48
	s_nop 1
	v_cndmask_b32_e64 v49, v201, -v49, vcc
	v_cmp_gt_f32_e32 vcc, s17, v49
	v_mul_f32_e32 v66, 0x4f800000, v49
	s_nop 0
	v_cndmask_b32_e32 v49, v49, v66, vcc
	v_sqrt_f32_e32 v66, v49
	s_nop 0
	v_add_u32_e32 v67, -1, v66
	v_fma_f32 v68, -v67, v66, v49
	v_cmp_ge_f32_e64 s[0:1], 0, v68
	v_add_u32_e32 v68, 1, v66
	s_nop 0
	v_cndmask_b32_e64 v67, v66, v67, s[0:1]
	v_fma_f32 v66, -v68, v66, v49
	v_cmp_lt_f32_e64 s[0:1], 0, v66
	s_nop 1
	v_cndmask_b32_e64 v66, v67, v68, s[0:1]
	v_mul_f32_e32 v67, 0x37800000, v66
	v_cndmask_b32_e32 v66, v66, v67, vcc
	v_cmp_class_f32_e32 vcc, v49, v193
	s_nop 1
	v_cndmask_b32_e32 v49, v66, v49, vcc
	v_cmp_ngt_f32_e32 vcc, s18, v48
	s_nop 1
	v_cndmask_b32_e32 v48, 1.0, v49, vcc
	v_mul_f32_e32 v33, v33, v48
	ds_read2_b32 v[48:49], v32 offset0:64 offset1:96
	s_waitcnt lgkmcnt(0)
	v_mul_f32_e32 v33, v48, v33
	ds_write_b32 v70, v64 offset:256
	ds_write_b32 v70, v33 offset:37120
	v_add_f32_e32 v33, v50, v74
	v_mul_f32_e32 v33, 0xbfb8aa3b, v33
	v_exp_f32_e32 v33, v33
	s_nop 0
	v_add_f32_e32 v33, 1.0, v33
	v_rcp_f32_e32 v33, v33
	s_nop 0
	v_mul_f32_e32 v33, v33, v72
	v_mul_f32_e32 v48, 0x3fb8aa3b, v33
	v_add_f32_e32 v33, v33, v33
	v_mul_f32_e32 v50, 0x3fb8aa3b, v33
	v_rndne_f32_e32 v50, v50
	v_fmamk_f32 v64, v50, 0xbf317218, v33
	v_fmac_f32_e32 v64, 0x3102e308, v50
	v_fmamk_f32 v66, v64, 0x395133b1, v192
	v_cmp_eq_f32_e32 vcc, s15, v50
	v_cvt_i32_f32_e32 v50, v50
	v_fmaak_f32 v66, v64, v66, 0x3c0887f9
	v_fmaak_f32 v66, v64, v66, 0x3d2aaa81
	v_fmaak_f32 v66, v64, v66, 0x3e2aaaab
	v_fma_f32 v66, v64, v66, 0.5
	v_ldexp_f32 v50, 1.0, v50
	v_mul_f32_e32 v66, v64, v66
	v_cndmask_b32_e32 v50, v50, v202, vcc
	v_fmac_f32_e32 v64, v64, v66
	v_add_f32_e32 v66, -1.0, v50
	v_fmac_f32_e32 v66, v50, v64
	v_add_f32_e32 v50, v66, v66
	v_cndmask_b32_e32 v50, v66, v50, vcc
	v_cmp_nlt_f32_e32 vcc, s16, v33
	v_exp_f32_e32 v48, v48
	s_nop 0
	v_cndmask_b32_e64 v50, v201, -v50, vcc
	v_cmp_gt_f32_e32 vcc, s17, v50
	v_mul_f32_e32 v64, 0x4f800000, v50
	s_nop 0
	v_cndmask_b32_e32 v50, v50, v64, vcc
	v_sqrt_f32_e32 v64, v50
	s_nop 0
	v_add_u32_e32 v66, -1, v64
	v_fma_f32 v67, -v66, v64, v50
	v_cmp_ge_f32_e64 s[0:1], 0, v67
	v_add_u32_e32 v67, 1, v64
	s_nop 0
	v_cndmask_b32_e64 v66, v64, v66, s[0:1]
	v_fma_f32 v64, -v67, v64, v50
	v_cmp_lt_f32_e64 s[0:1], 0, v64
	s_nop 1
	v_cndmask_b32_e64 v64, v66, v67, s[0:1]
	v_mul_f32_e32 v66, 0x37800000, v64
	v_cndmask_b32_e32 v64, v64, v66, vcc
	ds_read2_b32 v[66:67], v32 offset0:128 offset1:160
	v_cmp_class_f32_e32 vcc, v50, v193
	s_nop 1
	v_cndmask_b32_e32 v50, v64, v50, vcc
	v_cmp_ngt_f32_e32 vcc, s18, v33
	s_nop 1
	v_cndmask_b32_e32 v33, 1.0, v50, vcc
	v_mul_f32_e32 v33, v34, v33
	s_waitcnt lgkmcnt(0)
	v_mul_f32_e32 v33, v66, v33
	ds_write_b32 v70, v48 offset:512
	ds_write_b32 v70, v33 offset:37376
	v_add_f32_e32 v33, v51, v74
	v_mul_f32_e32 v33, 0xbfb8aa3b, v33
	v_exp_f32_e32 v33, v33
	v_add_f32_e32 v34, v35, v73
	v_mul_f32_e32 v34, 0xbfb8aa3b, v34
	v_exp_f32_e32 v34, v34
	v_add_f32_e32 v33, 1.0, v33
	v_rcp_f32_e32 v33, v33
	v_add_f32_e32 v34, 1.0, v34
	v_rcp_f32_e32 v34, v34
	v_mul_f32_e32 v33, v33, v72
	v_mul_f32_e32 v35, 0x3fb8aa3b, v33
	v_add_f32_e32 v33, v33, v33
	v_mul_f32_e32 v48, 0x3fb8aa3b, v33
	v_rndne_f32_e32 v48, v48
	v_fmamk_f32 v50, v48, 0xbf317218, v33
	v_fmac_f32_e32 v50, 0x3102e308, v48
	v_fmamk_f32 v51, v50, 0x395133b1, v192
	v_cmp_eq_f32_e32 vcc, s15, v48
	v_cvt_i32_f32_e32 v48, v48
	v_fmaak_f32 v51, v50, v51, 0x3c0887f9
	v_fmaak_f32 v51, v50, v51, 0x3d2aaa81
	v_fmaak_f32 v51, v50, v51, 0x3e2aaaab
	v_fma_f32 v51, v50, v51, 0.5
	v_ldexp_f32 v48, 1.0, v48
	v_mul_f32_e32 v51, v50, v51
	v_cndmask_b32_e32 v48, v48, v202, vcc
	v_fmac_f32_e32 v50, v50, v51
	v_add_f32_e32 v51, -1.0, v48
	v_fmac_f32_e32 v51, v48, v50
	v_add_f32_e32 v48, v51, v51
	v_cndmask_b32_e32 v48, v51, v48, vcc
	v_cmp_nlt_f32_e32 vcc, s16, v33
	v_exp_f32_e32 v35, v35
	s_nop 0
	v_cndmask_b32_e64 v48, v201, -v48, vcc
	v_cmp_gt_f32_e32 vcc, s17, v48
	v_mul_f32_e32 v50, 0x4f800000, v48
	s_nop 0
	v_cndmask_b32_e32 v48, v48, v50, vcc
	v_sqrt_f32_e32 v50, v48
	s_nop 0
	v_add_u32_e32 v51, -1, v50
	v_fma_f32 v64, -v51, v50, v48
	v_cmp_ge_f32_e64 s[0:1], 0, v64
	v_add_u32_e32 v64, 1, v50
	s_nop 0
	v_cndmask_b32_e64 v51, v50, v51, s[0:1]
	v_fma_f32 v50, -v64, v50, v48
	v_cmp_lt_f32_e64 s[0:1], 0, v50
	s_nop 1
	v_cndmask_b32_e64 v50, v51, v64, s[0:1]
	v_mul_f32_e32 v51, 0x37800000, v50
	v_cndmask_b32_e32 v50, v50, v51, vcc
	v_cmp_class_f32_e32 vcc, v48, v193
	s_nop 1
	v_cndmask_b32_e32 v48, v50, v48, vcc
	ds_read2_b32 v[50:51], v32 offset0:192 offset1:224
	v_cmp_ngt_f32_e32 vcc, s18, v33
	s_nop 1
	v_cndmask_b32_e32 v33, 1.0, v48, vcc
	v_mul_f32_e32 v33, v34, v33
	s_waitcnt lgkmcnt(0)
	v_mul_f32_e32 v32, v50, v33
	ds_write_b32 v70, v35 offset:768
	ds_write_b32 v70, v32 offset:37632
	v_add_f32_e32 v32, v52, v74
	v_mul_f32_e32 v32, 0xbfb8aa3b, v32
	v_exp_f32_e32 v32, v32
	v_add_f32_e32 v33, v36, v73
	v_mul_f32_e32 v33, 0xbfb8aa3b, v33
	v_exp_f32_e32 v33, v33
	v_add_f32_e32 v32, 1.0, v32
	v_rcp_f32_e32 v32, v32
	v_add_f32_e32 v33, 1.0, v33
	v_rcp_f32_e32 v33, v33
	v_mul_f32_e32 v32, v32, v72
	v_mul_f32_e32 v34, 0x3fb8aa3b, v32
	v_add_f32_e32 v32, v32, v32
	v_mul_f32_e32 v35, 0x3fb8aa3b, v32
	v_rndne_f32_e32 v35, v35
	v_fmamk_f32 v36, v35, 0xbf317218, v32
	v_fmac_f32_e32 v36, 0x3102e308, v35
	v_fmamk_f32 v48, v36, 0x395133b1, v192
	v_cmp_eq_f32_e32 vcc, s15, v35
	v_cvt_i32_f32_e32 v35, v35
	v_fmaak_f32 v48, v36, v48, 0x3c0887f9
	v_fmaak_f32 v48, v36, v48, 0x3d2aaa81
	v_fmaak_f32 v48, v36, v48, 0x3e2aaaab
	v_fma_f32 v48, v36, v48, 0.5
	v_ldexp_f32 v35, 1.0, v35
	v_mul_f32_e32 v48, v36, v48
	v_cndmask_b32_e32 v35, v35, v202, vcc
	v_fmac_f32_e32 v36, v36, v48
	v_add_f32_e32 v48, -1.0, v35
	v_fmac_f32_e32 v48, v35, v36
	v_add_f32_e32 v35, v48, v48
	v_cndmask_b32_e32 v35, v48, v35, vcc
	v_cmp_nlt_f32_e32 vcc, s16, v32
	v_exp_f32_e32 v34, v34
	s_nop 0
	v_cndmask_b32_e64 v35, v201, -v35, vcc
	v_cmp_gt_f32_e32 vcc, s17, v35
	v_mul_f32_e32 v36, 0x4f800000, v35
	s_nop 0
	v_cndmask_b32_e32 v35, v35, v36, vcc
	v_sqrt_f32_e32 v36, v35
	s_nop 0
	v_add_u32_e32 v48, -1, v36
	v_fma_f32 v50, -v48, v36, v35
	v_cmp_ge_f32_e64 s[0:1], 0, v50
	v_add_u32_e32 v50, 1, v36
	s_nop 0
	v_cndmask_b32_e64 v48, v36, v48, s[0:1]
	v_fma_f32 v36, -v50, v36, v35
	v_cmp_lt_f32_e64 s[0:1], 0, v36
	s_nop 1
	v_cndmask_b32_e64 v36, v48, v50, s[0:1]
	v_mul_f32_e32 v48, 0x37800000, v36
	v_cndmask_b32_e32 v36, v36, v48, vcc
	v_cmp_class_f32_e32 vcc, v35, v193
	s_nop 1
	v_cndmask_b32_e32 v35, v36, v35, vcc
	v_cmp_ngt_f32_e32 vcc, s18, v32
	s_nop 1
	v_cndmask_b32_e32 v32, 1.0, v35, vcc
	v_mul_f32_e32 v33, v33, v32
	v_add_u32_e32 v32, 0x9800, v70
	ds_read2_b32 v[68:69], v32 offset1:32
	s_waitcnt lgkmcnt(0)
	v_mul_f32_e32 v33, v68, v33
	ds_write_b32 v70, v34 offset:2048
	ds_write_b32 v70, v33 offset:38912
	v_add_f32_e32 v33, v53, v74
	v_mul_f32_e32 v33, 0xbfb8aa3b, v33
	v_exp_f32_e32 v33, v33
	v_add_f32_e32 v34, v37, v73
	v_mul_f32_e32 v34, 0xbfb8aa3b, v34
	v_exp_f32_e32 v34, v34
	v_add_f32_e32 v33, 1.0, v33
	v_rcp_f32_e32 v33, v33
	v_add_f32_e32 v34, 1.0, v34
	v_rcp_f32_e32 v34, v34
	v_mul_f32_e32 v33, v33, v72
	v_mul_f32_e32 v35, 0x3fb8aa3b, v33
	v_add_f32_e32 v33, v33, v33
	v_mul_f32_e32 v36, 0x3fb8aa3b, v33
	v_rndne_f32_e32 v36, v36
	v_fmamk_f32 v37, v36, 0xbf317218, v33
	v_fmac_f32_e32 v37, 0x3102e308, v36
	v_fmamk_f32 v48, v37, 0x395133b1, v192
	v_cmp_eq_f32_e32 vcc, s15, v36
	v_cvt_i32_f32_e32 v36, v36
	v_fmaak_f32 v48, v37, v48, 0x3c0887f9
	v_fmaak_f32 v48, v37, v48, 0x3d2aaa81
	v_fmaak_f32 v48, v37, v48, 0x3e2aaaab
	v_fma_f32 v48, v37, v48, 0.5
	v_ldexp_f32 v36, 1.0, v36
	v_mul_f32_e32 v48, v37, v48
	v_cndmask_b32_e32 v36, v36, v202, vcc
	v_fmac_f32_e32 v37, v37, v48
	v_add_f32_e32 v48, -1.0, v36
	v_fmac_f32_e32 v48, v36, v37
	v_add_f32_e32 v36, v48, v48
	v_cndmask_b32_e32 v36, v48, v36, vcc
	v_cmp_nlt_f32_e32 vcc, s16, v33
	v_exp_f32_e32 v35, v35
	s_nop 0
	v_cndmask_b32_e64 v36, v201, -v36, vcc
	v_cmp_gt_f32_e32 vcc, s17, v36
	v_mul_f32_e32 v37, 0x4f800000, v36
	s_nop 0
	v_cndmask_b32_e32 v36, v36, v37, vcc
	v_sqrt_f32_e32 v37, v36
	s_nop 0
	v_add_u32_e32 v48, -1, v37
	v_fma_f32 v50, -v48, v37, v36
	v_cmp_ge_f32_e64 s[0:1], 0, v50
	v_add_u32_e32 v50, 1, v37
	s_nop 0
	v_cndmask_b32_e64 v48, v37, v48, s[0:1]
	v_fma_f32 v37, -v50, v37, v36
	v_cmp_lt_f32_e64 s[0:1], 0, v37
	s_nop 1
	v_cndmask_b32_e64 v37, v48, v50, s[0:1]
	v_mul_f32_e32 v48, 0x37800000, v37
	v_cndmask_b32_e32 v37, v37, v48, vcc
	v_cmp_class_f32_e32 vcc, v36, v193
	s_nop 1
	v_cndmask_b32_e32 v36, v37, v36, vcc
	v_cmp_ngt_f32_e32 vcc, s18, v33
	s_nop 1
	v_cndmask_b32_e32 v33, 1.0, v36, vcc
	ds_read2_b32 v[36:37], v32 offset0:64 offset1:96
	v_mul_f32_e32 v33, v34, v33
	v_add_f32_e32 v34, v38, v73
	v_mul_f32_e32 v34, 0xbfb8aa3b, v34
	v_exp_f32_e32 v34, v34
	s_waitcnt lgkmcnt(0)
	v_mul_f32_e32 v33, v36, v33
	ds_write_b32 v70, v35 offset:2304
	ds_write_b32 v70, v33 offset:39168
	v_add_f32_e32 v33, v54, v74
	v_mul_f32_e32 v33, 0xbfb8aa3b, v33
	v_exp_f32_e32 v33, v33
	v_add_f32_e32 v34, 1.0, v34
	v_rcp_f32_e32 v34, v34
	ds_read2_b32 v[52:53], v32 offset0:128 offset1:160
	v_add_f32_e32 v33, 1.0, v33
	v_rcp_f32_e32 v33, v33
	s_nop 0
	v_mul_f32_e32 v33, v33, v72
	v_mul_f32_e32 v35, 0x3fb8aa3b, v33
	v_add_f32_e32 v33, v33, v33
	v_mul_f32_e32 v36, 0x3fb8aa3b, v33
	v_rndne_f32_e32 v36, v36
	v_fmamk_f32 v38, v36, 0xbf317218, v33
	v_fmac_f32_e32 v38, 0x3102e308, v36
	v_fmamk_f32 v48, v38, 0x395133b1, v192
	v_cmp_eq_f32_e32 vcc, s15, v36
	v_cvt_i32_f32_e32 v36, v36
	v_fmaak_f32 v48, v38, v48, 0x3c0887f9
	v_fmaak_f32 v48, v38, v48, 0x3d2aaa81
	v_fmaak_f32 v48, v38, v48, 0x3e2aaaab
	v_fma_f32 v48, v38, v48, 0.5
	v_ldexp_f32 v36, 1.0, v36
	v_mul_f32_e32 v48, v38, v48
	v_cndmask_b32_e32 v36, v36, v202, vcc
	v_fmac_f32_e32 v38, v38, v48
	v_add_f32_e32 v48, -1.0, v36
	v_fmac_f32_e32 v48, v36, v38
	v_add_f32_e32 v36, v48, v48
	v_cndmask_b32_e32 v36, v48, v36, vcc
	v_cmp_nlt_f32_e32 vcc, s16, v33
	v_exp_f32_e32 v35, v35
	s_nop 0
	v_cndmask_b32_e64 v36, v201, -v36, vcc
	v_cmp_gt_f32_e32 vcc, s17, v36
	v_mul_f32_e32 v38, 0x4f800000, v36
	s_nop 0
	v_cndmask_b32_e32 v36, v36, v38, vcc
	v_sqrt_f32_e32 v38, v36
	s_nop 0
	v_add_u32_e32 v48, -1, v38
	v_fma_f32 v50, -v48, v38, v36
	v_cmp_ge_f32_e64 s[0:1], 0, v50
	v_add_u32_e32 v50, 1, v38
	s_nop 0
	v_cndmask_b32_e64 v48, v38, v48, s[0:1]
	v_fma_f32 v38, -v50, v38, v36
	v_cmp_lt_f32_e64 s[0:1], 0, v38
	s_nop 1
	v_cndmask_b32_e64 v38, v48, v50, s[0:1]
	v_mul_f32_e32 v48, 0x37800000, v38
	v_cndmask_b32_e32 v38, v38, v48, vcc
	v_cmp_class_f32_e32 vcc, v36, v193
	s_nop 1
	v_cndmask_b32_e32 v36, v38, v36, vcc
	v_cmp_ngt_f32_e32 vcc, s18, v33
	s_nop 1
	v_cndmask_b32_e32 v33, 1.0, v36, vcc
	v_mul_f32_e32 v33, v34, v33
	s_waitcnt lgkmcnt(0)
	v_mul_f32_e32 v33, v52, v33
	ds_write_b32 v70, v35 offset:2560
	ds_write_b32 v70, v33 offset:39424
	v_add_f32_e32 v33, v55, v74
	v_mul_f32_e32 v33, 0xbfb8aa3b, v33
	v_exp_f32_e32 v33, v33
	v_add_f32_e32 v34, v39, v73
	v_mul_f32_e32 v34, 0xbfb8aa3b, v34
	v_exp_f32_e32 v34, v34
	v_add_f32_e32 v33, 1.0, v33
	v_rcp_f32_e32 v33, v33
	v_add_f32_e32 v34, 1.0, v34
	v_rcp_f32_e32 v34, v34
	v_mul_f32_e32 v33, v33, v72
	v_mul_f32_e32 v35, 0x3fb8aa3b, v33
	v_add_f32_e32 v33, v33, v33
	v_mul_f32_e32 v36, 0x3fb8aa3b, v33
	v_rndne_f32_e32 v36, v36
	v_fmamk_f32 v38, v36, 0xbf317218, v33
	v_fmac_f32_e32 v38, 0x3102e308, v36
	v_fmamk_f32 v39, v38, 0x395133b1, v192
	v_cmp_eq_f32_e32 vcc, s15, v36
	v_cvt_i32_f32_e32 v36, v36
	v_fmaak_f32 v39, v38, v39, 0x3c0887f9
	v_fmaak_f32 v39, v38, v39, 0x3d2aaa81
	v_fmaak_f32 v39, v38, v39, 0x3e2aaaab
	v_fma_f32 v39, v38, v39, 0.5
	v_ldexp_f32 v36, 1.0, v36
	v_mul_f32_e32 v39, v38, v39
	v_cndmask_b32_e32 v36, v36, v202, vcc
	v_fmac_f32_e32 v38, v38, v39
	v_add_f32_e32 v39, -1.0, v36
	v_fmac_f32_e32 v39, v36, v38
	v_add_f32_e32 v36, v39, v39
	v_cndmask_b32_e32 v36, v39, v36, vcc
	v_cmp_nlt_f32_e32 vcc, s16, v33
	v_exp_f32_e32 v35, v35
	s_nop 0
	v_cndmask_b32_e64 v36, v201, -v36, vcc
	v_cmp_gt_f32_e32 vcc, s17, v36
	v_mul_f32_e32 v38, 0x4f800000, v36
	s_nop 0
	v_cndmask_b32_e32 v36, v36, v38, vcc
	v_sqrt_f32_e32 v38, v36
	s_nop 0
	v_add_u32_e32 v39, -1, v38
	v_fma_f32 v48, -v39, v38, v36
	v_cmp_ge_f32_e64 s[0:1], 0, v48
	v_add_u32_e32 v48, 1, v38
	s_nop 0
	v_cndmask_b32_e64 v39, v38, v39, s[0:1]
	v_fma_f32 v38, -v48, v38, v36
	v_cmp_lt_f32_e64 s[0:1], 0, v38
	s_nop 1
	v_cndmask_b32_e64 v38, v39, v48, s[0:1]
	v_mul_f32_e32 v39, 0x37800000, v38
	v_cndmask_b32_e32 v38, v38, v39, vcc
	v_cmp_class_f32_e32 vcc, v36, v193
	s_nop 1
	v_cndmask_b32_e32 v36, v38, v36, vcc
	ds_read2_b32 v[38:39], v32 offset0:192 offset1:224
	v_cmp_ngt_f32_e32 vcc, s18, v33
	s_nop 1
	v_cndmask_b32_e32 v33, 1.0, v36, vcc
	v_mul_f32_e32 v33, v34, v33
	s_waitcnt lgkmcnt(0)
	v_mul_f32_e32 v32, v38, v33
	ds_write_b32 v70, v35 offset:2816
	ds_write_b32 v70, v32 offset:39680
	v_add_f32_e32 v32, v56, v74
	v_mul_f32_e32 v32, 0xbfb8aa3b, v32
	v_exp_f32_e32 v32, v32
	v_add_f32_e32 v33, v40, v73
	v_mul_f32_e32 v33, 0xbfb8aa3b, v33
	v_exp_f32_e32 v33, v33
	v_add_f32_e32 v32, 1.0, v32
	v_rcp_f32_e32 v32, v32
	v_add_f32_e32 v33, 1.0, v33
	v_rcp_f32_e32 v33, v33
	v_mul_f32_e32 v32, v32, v72
	v_mul_f32_e32 v34, 0x3fb8aa3b, v32
	v_add_f32_e32 v32, v32, v32
	v_mul_f32_e32 v35, 0x3fb8aa3b, v32
	v_rndne_f32_e32 v35, v35
	v_fmamk_f32 v36, v35, 0xbf317218, v32
	v_fmac_f32_e32 v36, 0x3102e308, v35
	v_fmamk_f32 v38, v36, 0x395133b1, v192
	v_cmp_eq_f32_e32 vcc, s15, v35
	v_cvt_i32_f32_e32 v35, v35
	v_fmaak_f32 v38, v36, v38, 0x3c0887f9
	v_fmaak_f32 v38, v36, v38, 0x3d2aaa81
	v_fmaak_f32 v38, v36, v38, 0x3e2aaaab
	v_fma_f32 v38, v36, v38, 0.5
	v_ldexp_f32 v35, 1.0, v35
	v_mul_f32_e32 v38, v36, v38
	v_cndmask_b32_e32 v35, v35, v202, vcc
	v_fmac_f32_e32 v36, v36, v38
	v_add_f32_e32 v38, -1.0, v35
	v_fmac_f32_e32 v38, v35, v36
	v_add_f32_e32 v35, v38, v38
	v_cndmask_b32_e32 v35, v38, v35, vcc
	v_cmp_nlt_f32_e32 vcc, s16, v32
	v_exp_f32_e32 v34, v34
	s_nop 0
	v_cndmask_b32_e64 v35, v201, -v35, vcc
	v_cmp_gt_f32_e32 vcc, s17, v35
	v_mul_f32_e32 v36, 0x4f800000, v35
	s_nop 0
	v_cndmask_b32_e32 v35, v35, v36, vcc
	v_sqrt_f32_e32 v36, v35
	s_nop 0
	v_add_u32_e32 v38, -1, v36
	v_fma_f32 v40, -v38, v36, v35
	v_cmp_ge_f32_e64 s[0:1], 0, v40
	v_add_u32_e32 v40, 1, v36
	s_nop 0
	v_cndmask_b32_e64 v38, v36, v38, s[0:1]
	v_fma_f32 v36, -v40, v36, v35
	v_cmp_lt_f32_e64 s[0:1], 0, v36
	s_nop 1
	v_cndmask_b32_e64 v36, v38, v40, s[0:1]
	v_mul_f32_e32 v38, 0x37800000, v36
	v_cndmask_b32_e32 v36, v36, v38, vcc
	v_cmp_class_f32_e32 vcc, v35, v193
	s_nop 1
	v_cndmask_b32_e32 v35, v36, v35, vcc
	v_cmp_ngt_f32_e32 vcc, s18, v32
	s_nop 1
	v_cndmask_b32_e32 v32, 1.0, v35, vcc
	v_mul_f32_e32 v33, v33, v32
	v_add_u32_e32 v32, 0xa000, v70
	ds_read2_b32 v[54:55], v32 offset1:32
	s_waitcnt lgkmcnt(0)
	v_mul_f32_e32 v33, v54, v33
	ds_write_b32 v70, v34 offset:4096
	ds_write_b32 v70, v33 offset:40960
	v_add_f32_e32 v33, v57, v74
	v_mul_f32_e32 v33, 0xbfb8aa3b, v33
	v_exp_f32_e32 v33, v33
	v_add_f32_e32 v34, v41, v73
	v_mul_f32_e32 v34, 0xbfb8aa3b, v34
	v_exp_f32_e32 v34, v34
	v_add_f32_e32 v33, 1.0, v33
	v_rcp_f32_e32 v33, v33
	v_add_f32_e32 v34, 1.0, v34
	v_rcp_f32_e32 v34, v34
	v_mul_f32_e32 v33, v33, v72
	v_mul_f32_e32 v35, 0x3fb8aa3b, v33
	v_add_f32_e32 v33, v33, v33
	v_mul_f32_e32 v36, 0x3fb8aa3b, v33
	v_rndne_f32_e32 v36, v36
	v_fmamk_f32 v38, v36, 0xbf317218, v33
	v_fmac_f32_e32 v38, 0x3102e308, v36
	v_fmamk_f32 v40, v38, 0x395133b1, v192
	v_cmp_eq_f32_e32 vcc, s15, v36
	v_cvt_i32_f32_e32 v36, v36
	v_fmaak_f32 v40, v38, v40, 0x3c0887f9
	v_fmaak_f32 v40, v38, v40, 0x3d2aaa81
	v_fmaak_f32 v40, v38, v40, 0x3e2aaaab
	v_fma_f32 v40, v38, v40, 0.5
	v_ldexp_f32 v36, 1.0, v36
	v_mul_f32_e32 v40, v38, v40
	v_cndmask_b32_e32 v36, v36, v202, vcc
	v_fmac_f32_e32 v38, v38, v40
	v_add_f32_e32 v40, -1.0, v36
	v_fmac_f32_e32 v40, v36, v38
	v_add_f32_e32 v36, v40, v40
	v_cndmask_b32_e32 v36, v40, v36, vcc
	v_cmp_nlt_f32_e32 vcc, s16, v33
	v_exp_f32_e32 v35, v35
	s_nop 0
	v_cndmask_b32_e64 v36, v201, -v36, vcc
	v_cmp_gt_f32_e32 vcc, s17, v36
	v_mul_f32_e32 v38, 0x4f800000, v36
	s_nop 0
	v_cndmask_b32_e32 v36, v36, v38, vcc
	v_sqrt_f32_e32 v38, v36
	s_nop 0
	v_add_u32_e32 v40, -1, v38
	v_fma_f32 v41, -v40, v38, v36
	v_cmp_ge_f32_e64 s[0:1], 0, v41
	v_add_u32_e32 v41, 1, v38
	s_nop 0
	v_cndmask_b32_e64 v40, v38, v40, s[0:1]
	v_fma_f32 v38, -v41, v38, v36
	v_cmp_lt_f32_e64 s[0:1], 0, v38
	s_nop 1
	v_cndmask_b32_e64 v38, v40, v41, s[0:1]
	v_mul_f32_e32 v40, 0x37800000, v38
	v_cndmask_b32_e32 v38, v38, v40, vcc
	ds_read2_b32 v[40:41], v32 offset0:64 offset1:96
	v_cmp_class_f32_e32 vcc, v36, v193
	s_nop 1
	v_cndmask_b32_e32 v36, v38, v36, vcc
	v_cmp_ngt_f32_e32 vcc, s18, v33
	s_nop 1
	v_cndmask_b32_e32 v33, 1.0, v36, vcc
	v_mul_f32_e32 v33, v34, v33
	s_waitcnt lgkmcnt(0)
	v_mul_f32_e32 v33, v40, v33
	ds_write_b32 v70, v35 offset:4352
	ds_write_b32 v70, v33 offset:41216
	v_add_f32_e32 v33, v58, v74
	v_mul_f32_e32 v33, 0xbfb8aa3b, v33
	v_exp_f32_e32 v33, v33
	v_add_f32_e32 v34, v42, v73
	v_mul_f32_e32 v34, 0xbfb8aa3b, v34
	v_exp_f32_e32 v34, v34
	v_add_f32_e32 v33, 1.0, v33
	v_rcp_f32_e32 v33, v33
	ds_read2_b32 v[56:57], v32 offset0:128 offset1:160
	v_add_f32_e32 v34, 1.0, v34
	v_rcp_f32_e32 v34, v34
	v_mul_f32_e32 v33, v33, v72
	v_mul_f32_e32 v35, 0x3fb8aa3b, v33
	v_add_f32_e32 v33, v33, v33
	v_mul_f32_e32 v36, 0x3fb8aa3b, v33
	v_rndne_f32_e32 v36, v36
	v_fmamk_f32 v38, v36, 0xbf317218, v33
	v_fmac_f32_e32 v38, 0x3102e308, v36
	v_fmamk_f32 v40, v38, 0x395133b1, v192
	v_cmp_eq_f32_e32 vcc, s15, v36
	v_cvt_i32_f32_e32 v36, v36
	v_fmaak_f32 v40, v38, v40, 0x3c0887f9
	v_fmaak_f32 v40, v38, v40, 0x3d2aaa81
	v_fmaak_f32 v40, v38, v40, 0x3e2aaaab
	v_fma_f32 v40, v38, v40, 0.5
	v_ldexp_f32 v36, 1.0, v36
	v_mul_f32_e32 v40, v38, v40
	v_cndmask_b32_e32 v36, v36, v202, vcc
	v_fmac_f32_e32 v38, v38, v40
	v_add_f32_e32 v40, -1.0, v36
	v_fmac_f32_e32 v40, v36, v38
	v_add_f32_e32 v36, v40, v40
	v_cndmask_b32_e32 v36, v40, v36, vcc
	v_cmp_nlt_f32_e32 vcc, s16, v33
	v_exp_f32_e32 v35, v35
	s_nop 0
	v_cndmask_b32_e64 v36, v201, -v36, vcc
	v_cmp_gt_f32_e32 vcc, s17, v36
	v_mul_f32_e32 v38, 0x4f800000, v36
	s_nop 0
	v_cndmask_b32_e32 v36, v36, v38, vcc
	v_sqrt_f32_e32 v38, v36
	s_nop 0
	v_add_u32_e32 v40, -1, v38
	v_fma_f32 v42, -v40, v38, v36
	v_cmp_ge_f32_e64 s[0:1], 0, v42
	v_add_u32_e32 v42, 1, v38
	s_nop 0
	v_cndmask_b32_e64 v40, v38, v40, s[0:1]
	v_fma_f32 v38, -v42, v38, v36
	v_cmp_lt_f32_e64 s[0:1], 0, v38
	s_nop 1
	v_cndmask_b32_e64 v38, v40, v42, s[0:1]
	v_mul_f32_e32 v40, 0x37800000, v38
	v_cndmask_b32_e32 v38, v38, v40, vcc
	v_cmp_class_f32_e32 vcc, v36, v193
	s_nop 1
	v_cndmask_b32_e32 v36, v38, v36, vcc
	v_cmp_ngt_f32_e32 vcc, s18, v33
	s_nop 1
	v_cndmask_b32_e32 v33, 1.0, v36, vcc
	v_mul_f32_e32 v33, v34, v33
	s_waitcnt lgkmcnt(0)
	v_mul_f32_e32 v33, v56, v33
	ds_write_b32 v70, v35 offset:4608
	ds_write_b32 v70, v33 offset:41472
	v_add_f32_e32 v33, v59, v74
	v_mul_f32_e32 v33, 0xbfb8aa3b, v33
	v_exp_f32_e32 v33, v33
	v_add_f32_e32 v34, v43, v73
	v_mul_f32_e32 v34, 0xbfb8aa3b, v34
	v_exp_f32_e32 v34, v34
	v_add_f32_e32 v33, 1.0, v33
	v_rcp_f32_e32 v33, v33
	v_add_f32_e32 v34, 1.0, v34
	v_rcp_f32_e32 v34, v34
	v_mul_f32_e32 v33, v33, v72
	v_mul_f32_e32 v35, 0x3fb8aa3b, v33
	v_add_f32_e32 v33, v33, v33
	v_mul_f32_e32 v36, 0x3fb8aa3b, v33
	v_rndne_f32_e32 v36, v36
	v_fmamk_f32 v38, v36, 0xbf317218, v33
	v_fmac_f32_e32 v38, 0x3102e308, v36
	v_fmamk_f32 v40, v38, 0x395133b1, v192
	v_cmp_eq_f32_e32 vcc, s15, v36
	v_cvt_i32_f32_e32 v36, v36
	v_fmaak_f32 v40, v38, v40, 0x3c0887f9
	v_fmaak_f32 v40, v38, v40, 0x3d2aaa81
	v_fmaak_f32 v40, v38, v40, 0x3e2aaaab
	v_fma_f32 v40, v38, v40, 0.5
	v_ldexp_f32 v36, 1.0, v36
	v_mul_f32_e32 v40, v38, v40
	v_cndmask_b32_e32 v36, v36, v202, vcc
	v_fmac_f32_e32 v38, v38, v40
	v_add_f32_e32 v40, -1.0, v36
	v_fmac_f32_e32 v40, v36, v38
	v_add_f32_e32 v36, v40, v40
	v_cndmask_b32_e32 v36, v40, v36, vcc
	v_cmp_nlt_f32_e32 vcc, s16, v33
	v_exp_f32_e32 v35, v35
	s_nop 0
	v_cndmask_b32_e64 v36, v201, -v36, vcc
	v_cmp_gt_f32_e32 vcc, s17, v36
	v_mul_f32_e32 v38, 0x4f800000, v36
	s_nop 0
	v_cndmask_b32_e32 v36, v36, v38, vcc
	v_sqrt_f32_e32 v38, v36
	s_nop 0
	v_add_u32_e32 v40, -1, v38
	v_fma_f32 v42, -v40, v38, v36
	v_cmp_ge_f32_e64 s[0:1], 0, v42
	v_add_u32_e32 v42, 1, v38
	s_nop 0
	v_cndmask_b32_e64 v40, v38, v40, s[0:1]
	v_fma_f32 v38, -v42, v38, v36
	v_cmp_lt_f32_e64 s[0:1], 0, v38
	s_nop 1
	v_cndmask_b32_e64 v38, v40, v42, s[0:1]
	v_mul_f32_e32 v40, 0x37800000, v38
	ds_read2_b32 v[42:43], v32 offset0:192 offset1:224
	v_cndmask_b32_e32 v38, v38, v40, vcc
	v_cmp_class_f32_e32 vcc, v36, v193
	s_nop 1
	v_cndmask_b32_e32 v36, v38, v36, vcc
	v_cmp_ngt_f32_e32 vcc, s18, v33
	s_nop 1
	v_cndmask_b32_e32 v33, 1.0, v36, vcc
	v_mul_f32_e32 v33, v34, v33
	s_waitcnt lgkmcnt(0)
	v_mul_f32_e32 v32, v42, v33
	ds_write_b32 v70, v35 offset:4864
	ds_write_b32 v70, v32 offset:41728
	v_add_f32_e32 v32, v60, v74
	v_mul_f32_e32 v32, 0xbfb8aa3b, v32
	v_exp_f32_e32 v32, v32
	v_add_f32_e32 v33, v44, v73
	v_mul_f32_e32 v33, 0xbfb8aa3b, v33
	v_exp_f32_e32 v33, v33
	v_add_f32_e32 v32, 1.0, v32
	v_rcp_f32_e32 v32, v32
	v_add_f32_e32 v33, 1.0, v33
	v_rcp_f32_e32 v33, v33
	v_mul_f32_e32 v32, v32, v72
	v_mul_f32_e32 v34, 0x3fb8aa3b, v32
	v_add_f32_e32 v32, v32, v32
	v_mul_f32_e32 v35, 0x3fb8aa3b, v32
	v_rndne_f32_e32 v35, v35
	v_fmamk_f32 v36, v35, 0xbf317218, v32
	v_fmac_f32_e32 v36, 0x3102e308, v35
	v_fmamk_f32 v38, v36, 0x395133b1, v192
	v_cmp_eq_f32_e32 vcc, s15, v35
	v_cvt_i32_f32_e32 v35, v35
	v_fmaak_f32 v38, v36, v38, 0x3c0887f9
	v_fmaak_f32 v38, v36, v38, 0x3d2aaa81
	v_fmaak_f32 v38, v36, v38, 0x3e2aaaab
	v_fma_f32 v38, v36, v38, 0.5
	v_ldexp_f32 v35, 1.0, v35
	v_mul_f32_e32 v38, v36, v38
	v_cndmask_b32_e32 v35, v35, v202, vcc
	v_fmac_f32_e32 v36, v36, v38
	v_add_f32_e32 v38, -1.0, v35
	v_fmac_f32_e32 v38, v35, v36
	v_add_f32_e32 v35, v38, v38
	v_cndmask_b32_e32 v35, v38, v35, vcc
	v_cmp_nlt_f32_e32 vcc, s16, v32
	v_exp_f32_e32 v34, v34
	s_nop 0
	v_cndmask_b32_e64 v35, v201, -v35, vcc
	v_cmp_gt_f32_e32 vcc, s17, v35
	v_mul_f32_e32 v36, 0x4f800000, v35
	s_nop 0
	v_cndmask_b32_e32 v35, v35, v36, vcc
	v_sqrt_f32_e32 v36, v35
	s_nop 0
	v_add_u32_e32 v38, -1, v36
	v_fma_f32 v40, -v38, v36, v35
	v_cmp_ge_f32_e64 s[0:1], 0, v40
	v_add_u32_e32 v40, 1, v36
	s_nop 0
	v_cndmask_b32_e64 v38, v36, v38, s[0:1]
	v_fma_f32 v36, -v40, v36, v35
	v_cmp_lt_f32_e64 s[0:1], 0, v36
	s_nop 1
	v_cndmask_b32_e64 v36, v38, v40, s[0:1]
	v_mul_f32_e32 v38, 0x37800000, v36
	v_cndmask_b32_e32 v36, v36, v38, vcc
	v_cmp_class_f32_e32 vcc, v35, v193
	s_nop 1
	v_cndmask_b32_e32 v35, v36, v35, vcc
	v_cmp_ngt_f32_e32 vcc, s18, v32
	s_nop 1
	v_cndmask_b32_e32 v32, 1.0, v35, vcc
	v_mul_f32_e32 v32, v33, v32
	v_add_u32_e32 v33, 0xa800, v70
	ds_read2_b32 v[58:59], v33 offset1:32
	s_waitcnt lgkmcnt(0)
	v_mul_f32_e32 v32, v58, v32
	ds_write_b32 v70, v34 offset:6144
	ds_write_b32 v70, v32 offset:43008
	v_add_f32_e32 v32, v61, v74
	v_mul_f32_e32 v32, 0xbfb8aa3b, v32
	v_exp_f32_e32 v32, v32
	v_add_f32_e32 v34, v45, v73
	v_mul_f32_e32 v34, 0xbfb8aa3b, v34
	v_exp_f32_e32 v34, v34
	v_add_f32_e32 v32, 1.0, v32
	v_rcp_f32_e32 v32, v32
	ds_read2_b32 v[44:45], v33 offset0:64 offset1:96
	v_add_f32_e32 v34, 1.0, v34
	v_rcp_f32_e32 v34, v34
	v_mul_f32_e32 v32, v32, v72
	v_mul_f32_e32 v35, 0x3fb8aa3b, v32
	v_add_f32_e32 v32, v32, v32
	v_mul_f32_e32 v36, 0x3fb8aa3b, v32
	v_rndne_f32_e32 v36, v36
	v_fmamk_f32 v38, v36, 0xbf317218, v32
	v_fmac_f32_e32 v38, 0x3102e308, v36
	v_fmamk_f32 v40, v38, 0x395133b1, v192
	v_cmp_eq_f32_e32 vcc, s15, v36
	v_cvt_i32_f32_e32 v36, v36
	v_fmaak_f32 v40, v38, v40, 0x3c0887f9
	v_fmaak_f32 v40, v38, v40, 0x3d2aaa81
	v_fmaak_f32 v40, v38, v40, 0x3e2aaaab
	v_fma_f32 v40, v38, v40, 0.5
	v_ldexp_f32 v36, 1.0, v36
	v_mul_f32_e32 v40, v38, v40
	v_cndmask_b32_e32 v36, v36, v202, vcc
	v_fmac_f32_e32 v38, v38, v40
	v_add_f32_e32 v40, -1.0, v36
	v_fmac_f32_e32 v40, v36, v38
	v_add_f32_e32 v36, v40, v40
	v_cndmask_b32_e32 v36, v40, v36, vcc
	v_cmp_nlt_f32_e32 vcc, s16, v32
	v_exp_f32_e32 v35, v35
	s_nop 0
	v_cndmask_b32_e64 v36, v201, -v36, vcc
	v_cmp_gt_f32_e32 vcc, s17, v36
	v_mul_f32_e32 v38, 0x4f800000, v36
	s_nop 0
	v_cndmask_b32_e32 v36, v36, v38, vcc
	v_sqrt_f32_e32 v38, v36
	s_nop 0
	v_add_u32_e32 v40, -1, v38
	v_fma_f32 v42, -v40, v38, v36
	v_cmp_ge_f32_e64 s[0:1], 0, v42
	v_add_u32_e32 v42, 1, v38
	s_nop 0
	v_cndmask_b32_e64 v40, v38, v40, s[0:1]
	v_fma_f32 v38, -v42, v38, v36
	v_cmp_lt_f32_e64 s[0:1], 0, v38
	s_nop 1
	v_cndmask_b32_e64 v38, v40, v42, s[0:1]
	v_mul_f32_e32 v40, 0x37800000, v38
	v_cndmask_b32_e32 v38, v38, v40, vcc
	v_cmp_class_f32_e32 vcc, v36, v193
	s_nop 1
	v_cndmask_b32_e32 v36, v38, v36, vcc
	v_cmp_ngt_f32_e32 vcc, s18, v32
	s_nop 1
	v_cndmask_b32_e32 v32, 1.0, v36, vcc
	v_mul_f32_e32 v32, v34, v32
	s_waitcnt lgkmcnt(0)
	v_mul_f32_e32 v32, v44, v32
	ds_write_b32 v70, v35 offset:6400
	ds_write_b32 v70, v32 offset:43264
	v_add_f32_e32 v32, v62, v74
	v_mul_f32_e32 v32, 0xbfb8aa3b, v32
	v_exp_f32_e32 v32, v32
	v_add_f32_e32 v34, v46, v73
	v_mul_f32_e32 v34, 0xbfb8aa3b, v34
	v_exp_f32_e32 v34, v34
	v_add_f32_e32 v32, 1.0, v32
	v_rcp_f32_e32 v32, v32
	v_add_f32_e32 v34, 1.0, v34
	v_rcp_f32_e32 v34, v34
	v_mul_f32_e32 v32, v32, v72
	v_mul_f32_e32 v35, 0x3fb8aa3b, v32
	v_add_f32_e32 v32, v32, v32
	v_exp_f32_e32 v36, v35
	v_mul_f32_e32 v35, 0x3fb8aa3b, v32
	v_rndne_f32_e32 v35, v35
	v_fmamk_f32 v38, v35, 0xbf317218, v32
	v_fmac_f32_e32 v38, 0x3102e308, v35
	v_fmamk_f32 v40, v38, 0x395133b1, v192
	v_cmp_eq_f32_e32 vcc, s15, v35
	v_cvt_i32_f32_e32 v35, v35
	v_fmaak_f32 v40, v38, v40, 0x3c0887f9
	v_fmaak_f32 v40, v38, v40, 0x3d2aaa81
	v_fmaak_f32 v40, v38, v40, 0x3e2aaaab
	v_fma_f32 v40, v38, v40, 0.5
	v_ldexp_f32 v35, 1.0, v35
	v_mul_f32_e32 v40, v38, v40
	v_cndmask_b32_e32 v35, v35, v202, vcc
	v_fmac_f32_e32 v38, v38, v40
	v_add_f32_e32 v40, -1.0, v35
	v_fmac_f32_e32 v40, v35, v38
	v_add_f32_e32 v35, v40, v40
	v_cndmask_b32_e32 v35, v40, v35, vcc
	v_cmp_nlt_f32_e32 vcc, s16, v32
	s_nop 1
	v_cndmask_b32_e64 v35, v201, -v35, vcc
	v_cmp_gt_f32_e32 vcc, s17, v35
	v_mul_f32_e32 v38, 0x4f800000, v35
	s_nop 0
	v_cndmask_b32_e32 v35, v35, v38, vcc
	v_sqrt_f32_e32 v38, v35
	s_nop 0
	v_add_u32_e32 v40, -1, v38
	v_fma_f32 v42, -v40, v38, v35
	v_cmp_ge_f32_e64 s[0:1], 0, v42
	v_add_u32_e32 v42, 1, v38
	s_nop 0
	v_cndmask_b32_e64 v40, v38, v40, s[0:1]
	v_fma_f32 v38, -v42, v38, v35
	v_cmp_lt_f32_e64 s[0:1], 0, v38
	s_nop 1
	v_cndmask_b32_e64 v38, v40, v42, s[0:1]
	v_mul_f32_e32 v40, 0x37800000, v38
	v_cndmask_b32_e32 v38, v38, v40, vcc
	v_cmp_class_f32_e32 vcc, v35, v193
	s_nop 1
	v_cndmask_b32_e32 v35, v38, v35, vcc
	v_cmp_ngt_f32_e32 vcc, s18, v32
	s_nop 1
	v_cndmask_b32_e32 v32, 1.0, v35, vcc
	v_mul_f32_e32 v32, v34, v32
	ds_read2_b32 v[34:35], v33 offset0:128 offset1:160
	s_waitcnt lgkmcnt(0)
	v_mul_f32_e32 v32, v34, v32
	ds_write_b32 v70, v36 offset:6656
	ds_write_b32 v70, v32 offset:43520
	v_add_f32_e32 v32, v63, v74
	v_mul_f32_e32 v32, 0xbfb8aa3b, v32
	v_exp_f32_e32 v32, v32
	v_add_f32_e32 v34, v47, v73
	v_mul_f32_e32 v34, 0xbfb8aa3b, v34
	v_exp_f32_e32 v34, v34
	v_add_f32_e32 v32, 1.0, v32
	v_rcp_f32_e32 v32, v32
	v_lshlrev_b64 v[46:47], 2, v[96:97]
	v_add_f32_e32 v34, 1.0, v34
	v_rcp_f32_e32 v36, v34
	v_mul_f32_e32 v32, v32, v72
	v_mul_f32_e32 v34, 0x3fb8aa3b, v32
	v_add_f32_e32 v32, v32, v32
	v_mul_f32_e32 v38, 0x3fb8aa3b, v32
	v_rndne_f32_e32 v38, v38
	v_fmamk_f32 v40, v38, 0xbf317218, v32
	v_fmac_f32_e32 v40, 0x3102e308, v38
	v_fmamk_f32 v42, v40, 0x395133b1, v192
	v_cmp_eq_f32_e32 vcc, s15, v38
	v_cvt_i32_f32_e32 v38, v38
	v_fmaak_f32 v42, v40, v42, 0x3c0887f9
	v_fmaak_f32 v42, v40, v42, 0x3d2aaa81
	v_fmaak_f32 v42, v40, v42, 0x3e2aaaab
	v_fma_f32 v42, v40, v42, 0.5
	v_ldexp_f32 v38, 1.0, v38
	v_mul_f32_e32 v42, v40, v42
	v_cndmask_b32_e32 v38, v38, v202, vcc
	v_fmac_f32_e32 v40, v40, v42
	v_add_f32_e32 v42, -1.0, v38
	v_fmac_f32_e32 v42, v38, v40
	v_add_f32_e32 v38, v42, v42
	v_cndmask_b32_e32 v38, v42, v38, vcc
	v_cmp_nlt_f32_e32 vcc, s16, v32
	s_nop 0
	v_exp_f32_e32 v34, v34
	v_cndmask_b32_e64 v38, v201, -v38, vcc
	v_cmp_gt_f32_e32 vcc, s17, v38
	v_mul_f32_e32 v40, 0x4f800000, v38
	s_nop 0
	v_cndmask_b32_e32 v38, v38, v40, vcc
	v_sqrt_f32_e32 v40, v38
	s_nop 0
	v_add_u32_e32 v42, -1, v40
	v_fma_f32 v44, -v42, v40, v38
	v_cmp_ge_f32_e64 s[0:1], 0, v44
	v_add_u32_e32 v44, 1, v40
	s_nop 0
	v_cndmask_b32_e64 v42, v40, v42, s[0:1]
	v_fma_f32 v40, -v44, v40, v38
	v_cmp_lt_f32_e64 s[0:1], 0, v40
	s_nop 1
	v_cndmask_b32_e64 v40, v42, v44, s[0:1]
	v_mul_f32_e32 v42, 0x37800000, v40
	v_cndmask_b32_e32 v40, v40, v42, vcc
	v_cmp_class_f32_e32 vcc, v38, v193
	s_nop 1
	v_cndmask_b32_e32 v38, v40, v38, vcc
	v_cmp_ngt_f32_e32 vcc, s18, v32
	s_nop 1
	v_cndmask_b32_e32 v32, 1.0, v38, vcc
	v_mul_f32_e32 v36, v36, v32
	ds_read2_b32 v[32:33], v33 offset0:192 offset1:224
	s_waitcnt lgkmcnt(0)
	v_mul_f32_e32 v32, v32, v36
	ds_write_b32 v70, v32 offset:43776
	s_waitcnt vmcnt(0)
	v_mul_f32_e32 v32, 0xbfb8aa3b, v226
	v_exp_f32_e32 v32, v32
	s_nop 0
	v_add_f32_e32 v36, 1.0, v32
	v_add_f32_e32 v38, -1.0, v36
	v_sub_f32_e32 v40, v38, v36
	v_add_f32_e32 v40, 1.0, v40
	v_sub_f32_e32 v38, v32, v38
	v_add_f32_e32 v38, v38, v40
	v_frexp_mant_f32_e32 v40, v36
	v_cvt_f64_f32_e32 v[60:61], v36
	v_cmp_gt_f32_e32 vcc, s7, v40
	v_frexp_exp_i32_f64_e32 v40, v[60:61]
	s_nop 0
	v_subbrev_co_u32_e32 v40, vcc, 0, v40, vcc
	v_sub_u32_e32 v42, 0, v40
	v_ldexp_f32 v36, v36, v42
	v_ldexp_f32 v38, v38, v42
	v_add_f32_e32 v42, -1.0, v36
	v_add_f32_e32 v48, 1.0, v36
	v_add_f32_e32 v44, 1.0, v42
	v_add_f32_e32 v50, -1.0, v48
	v_sub_f32_e32 v44, v36, v44
	v_sub_f32_e32 v36, v36, v50
	v_add_f32_e32 v36, v38, v36
	v_add_f32_e32 v44, v38, v44
	v_add_f32_e32 v38, v48, v36
	v_sub_f32_e32 v48, v38, v48
	v_sub_f32_e32 v36, v36, v48
	v_rcp_f32_e32 v48, v38
	v_add_f32_e32 v61, v42, v44
	v_sub_f32_e32 v42, v61, v42
	v_sub_f32_e32 v42, v44, v42
	v_mul_f32_e32 v44, v61, v48
	v_mul_f32_e32 v62, v38, v44
	v_fma_f32 v72, v44, v38, -v62
	v_fmac_f32_e32 v72, v44, v36
	v_add_f32_e32 v60, v62, v72
	v_sub_f32_e32 v63, v61, v60
	v_pk_add_f32 v[74:75], v[60:61], v[62:63] neg_lo:[0,1] neg_hi:[0,1]
	v_mov_b32_e32 v73, v60
	v_pk_add_f32 v[60:61], v[74:75], v[72:73] neg_lo:[0,1] neg_hi:[0,1]
	v_cmp_neq_f32_e32 vcc, s40, v32
	v_add_f32_e32 v42, v42, v61
	v_add_f32_e32 v42, v60, v42
	v_add_f32_e32 v61, v63, v42
	v_mul_f32_e32 v50, v48, v61
	v_mul_f32_e32 v62, v38, v50
	v_fma_f32 v72, v50, v38, -v62
	v_fmac_f32_e32 v72, v50, v36
	v_add_f32_e32 v60, v62, v72
	v_sub_f32_e32 v36, v63, v61
	v_sub_f32_e32 v63, v61, v60
	v_pk_add_f32 v[74:75], v[60:61], v[62:63] neg_lo:[0,1] neg_hi:[0,1]
	v_mov_b32_e32 v73, v60
	v_add_f32_e32 v36, v42, v36
	v_pk_add_f32 v[60:61], v[74:75], v[72:73] neg_lo:[0,1] neg_hi:[0,1]
	v_add_f32_e32 v38, v44, v50
	v_add_f32_e32 v36, v36, v61
	v_add_f32_e32 v36, v60, v36
	v_add_f32_e32 v36, v63, v36
	v_sub_f32_e32 v42, v38, v44
	v_mul_f32_e32 v36, v48, v36
	v_sub_f32_e32 v42, v50, v42
	v_add_f32_e32 v36, v42, v36
	v_add_f32_e32 v42, v38, v36
	v_cvt_f32_i32_e32 v60, v40
	v_mul_f32_e32 v44, v42, v42
	v_fmamk_f32 v48, v44, 0x3e9b6dac, v191
	v_fmaak_f32 v169, v44, v48, 0x3f2aaada
	v_mul_f32_e32 v61, v42, v44
	v_pk_mul_f32 v[72:73], v[60:61], v[168:169]
	v_ldexp_f32 v63, v42, 1
	v_fma_f32 v62, v60, s39, -v72
	v_fmac_f32_e32 v62, 0xb102e308, v60
	v_sub_f32_e32 v38, v42, v38
	v_pk_add_f32 v[60:61], v[72:73], v[62:63]
	v_sub_f32_e32 v36, v36, v38
	v_sub_f32_e32 v38, v61, v63
	v_ldexp_f32 v36, v36, 1
	v_sub_f32_e32 v38, v73, v38
	v_add_f32_e32 v75, v36, v38
	v_mov_b32_e32 v74, v72
	v_pk_add_f32 v[72:73], v[60:61], v[72:73] neg_lo:[0,1] neg_hi:[0,1]
	v_pk_add_f32 v[76:77], v[60:61], v[74:75]
	v_mov_b32_e32 v63, v60
	v_mov_b32_e32 v73, v77
	v_pk_add_f32 v[78:79], v[62:63], v[72:73] neg_lo:[0,1] neg_hi:[0,1]
	v_pk_add_f32 v[62:63], v[62:63], v[72:73]
	v_mov_b32_e32 v74, v75
	v_pk_add_f32 v[72:73], v[62:63], v[60:61] op_sel:[1,0] op_sel_hi:[0,1] neg_lo:[0,1] neg_hi:[0,1]
	v_pk_add_f32 v[80:81], v[76:77], v[72:73] op_sel_hi:[1,0] neg_lo:[0,1] neg_hi:[0,1]
	v_mov_b32_e32 v76, v77
	v_mov_b32_e32 v77, v63
	v_pk_mov_b32 v[72:73], v[60:61], v[72:73] op_sel:[1,0]
	v_mov_b32_e32 v75, v60
	v_pk_add_f32 v[72:73], v[76:77], v[72:73] neg_lo:[0,1] neg_hi:[0,1]
	v_mov_b32_e32 v80, v78
	v_pk_add_f32 v[60:61], v[74:75], v[72:73] neg_lo:[0,1] neg_hi:[0,1]
	v_mov_b32_e32 v79, v63
	v_pk_add_f32 v[72:73], v[80:81], v[60:61]
	v_pk_add_f32 v[74:75], v[72:73], v[72:73] op_sel:[0,1] op_sel_hi:[1,0]
	v_pk_add_f32 v[62:63], v[62:63], v[74:75] op_sel:[1,0] op_sel_hi:[0,1]
	v_mov_b32_e32 v73, v62
	v_pk_add_f32 v[76:77], v[72:73], v[78:79] neg_lo:[0,1] neg_hi:[0,1]
	v_mov_b32_e32 v61, v74
	v_sub_f32_e32 v36, v72, v76
	v_pk_add_f32 v[60:61], v[60:61], v[76:77] neg_lo:[0,1] neg_hi:[0,1]
	v_sub_f32_e32 v36, v78, v36
	v_add_f32_e32 v36, v60, v36
	v_add_f32_e32 v36, v36, v61
	v_add_f32_e32 v36, v62, v36
	v_cndmask_b32_e32 v36, v199, v36, vcc
	v_cmp_ngt_f32_e32 vcc, -1.0, v32
	v_lshl_add_u64 v[60:61], s[24:25], 0, v[46:47]
	s_nop 0
	v_cndmask_b32_e32 v36, v200, v36, vcc
	v_cmp_neq_f32_e32 vcc, -1.0, v32
	v_mov_b32_e32 v38, v227
	s_waitcnt vmcnt(0)
	v_add_f32_e32 v0, v0, v38
	v_cndmask_b32_e32 v36, v201, v36, vcc
	v_cmp_lt_f32_e64 vcc, |v32|, s41
	v_mul_f32_e32 v0, 0xbfb8aa3b, v0
	v_exp_f32_e32 v0, v0
	v_cndmask_b32_e32 v32, v36, v32, vcc
	v_mov_b32_e32 v36, v228
	v_mul_f32_e32 v32, 0xc1000000, v32
	v_add_f32_e32 v0, 1.0, v0
	v_rcp_f32_e32 v0, v0
	v_add_f32_e32 v1, v1, v38
	v_mul_f32_e32 v1, 0xbfb8aa3b, v1
	v_exp_f32_e32 v1, v1
	s_waitcnt vmcnt(0)
	v_add_f32_e32 v16, v16, v36
	v_mul_f32_e32 v16, 0xbfb8aa3b, v16
	v_exp_f32_e32 v16, v16
	v_add_f32_e32 v1, 1.0, v1
	v_rcp_f32_e32 v1, v1
	v_add_f32_e32 v16, 1.0, v16
	v_rcp_f32_e32 v16, v16
	s_nop 0
	v_mul_f32_e32 v16, v16, v32
	v_mul_f32_e32 v40, 0x3fb8aa3b, v16
	v_add_f32_e32 v16, v16, v16
	v_mul_f32_e32 v42, 0x3fb8aa3b, v16
	v_rndne_f32_e32 v42, v42
	v_fmamk_f32 v44, v42, 0xbf317218, v16
	v_fmac_f32_e32 v44, 0x3102e308, v42
	v_fmamk_f32 v46, v44, 0x395133b1, v192
	v_cmp_eq_f32_e32 vcc, s15, v42
	v_cvt_i32_f32_e32 v42, v42
	v_fmaak_f32 v46, v44, v46, 0x3c0887f9
	v_fmaak_f32 v46, v44, v46, 0x3d2aaa81
	v_fmaak_f32 v46, v44, v46, 0x3e2aaaab
	v_fma_f32 v46, v44, v46, 0.5
	v_ldexp_f32 v42, 1.0, v42
	v_mul_f32_e32 v46, v44, v46
	v_cndmask_b32_e32 v42, v42, v202, vcc
	v_fmac_f32_e32 v44, v44, v46
	v_add_f32_e32 v46, -1.0, v42
	v_fmac_f32_e32 v46, v42, v44
	v_add_f32_e32 v42, v46, v46
	v_cndmask_b32_e32 v42, v46, v42, vcc
	v_cmp_nlt_f32_e32 vcc, s16, v16
	v_exp_f32_e32 v40, v40
	s_nop 0
	v_cndmask_b32_e64 v42, v201, -v42, vcc
	v_cmp_gt_f32_e32 vcc, s17, v42
	v_mul_f32_e32 v44, 0x4f800000, v42
	s_nop 0
	v_cndmask_b32_e32 v42, v42, v44, vcc
	v_sqrt_f32_e32 v44, v42
	s_nop 0
	v_add_u32_e32 v46, -1, v44
	v_fma_f32 v47, -v46, v44, v42
	v_cmp_ge_f32_e64 s[0:1], 0, v47
	v_add_u32_e32 v47, 1, v44
	s_nop 0
	v_cndmask_b32_e64 v46, v44, v46, s[0:1]
	v_fma_f32 v44, -v47, v44, v42
	v_cmp_lt_f32_e64 s[0:1], 0, v44
	s_nop 1
	v_cndmask_b32_e64 v44, v46, v47, s[0:1]
	v_mul_f32_e32 v46, 0x37800000, v44
	v_cndmask_b32_e32 v44, v44, v46, vcc
	v_cmp_class_f32_e32 vcc, v42, v193
	s_nop 1
	v_cndmask_b32_e32 v42, v44, v42, vcc
	v_cmp_ngt_f32_e32 vcc, s18, v16
	s_nop 1
	v_cndmask_b32_e32 v16, 1.0, v42, vcc
	v_mul_f32_e32 v0, v0, v16
	v_mul_f32_e32 v0, v65, v0
	ds_write_b32 v70, v40 offset:128
	ds_write_b32 v70, v0 offset:36992
	v_add_f32_e32 v0, v17, v36
	v_mul_f32_e32 v0, 0xbfb8aa3b, v0
	v_exp_f32_e32 v0, v0
	s_nop 0
	v_add_f32_e32 v0, 1.0, v0
	v_rcp_f32_e32 v0, v0
	s_nop 0
	v_mul_f32_e32 v0, v0, v32
	v_mul_f32_e32 v16, 0x3fb8aa3b, v0
	v_add_f32_e32 v0, v0, v0
	v_mul_f32_e32 v17, 0x3fb8aa3b, v0
	v_rndne_f32_e32 v17, v17
	v_fmamk_f32 v40, v17, 0xbf317218, v0
	v_fmac_f32_e32 v40, 0x3102e308, v17
	v_fmamk_f32 v42, v40, 0x395133b1, v192
	v_cmp_eq_f32_e32 vcc, s15, v17
	v_cvt_i32_f32_e32 v17, v17
	v_fmaak_f32 v42, v40, v42, 0x3c0887f9
	v_fmaak_f32 v42, v40, v42, 0x3d2aaa81
	v_fmaak_f32 v42, v40, v42, 0x3e2aaaab
	v_fma_f32 v42, v40, v42, 0.5
	v_ldexp_f32 v17, 1.0, v17
	v_mul_f32_e32 v42, v40, v42
	v_cndmask_b32_e32 v17, v17, v202, vcc
	v_fmac_f32_e32 v40, v40, v42
	v_add_f32_e32 v42, -1.0, v17
	v_fmac_f32_e32 v42, v17, v40
	v_add_f32_e32 v17, v42, v42
	v_cndmask_b32_e32 v17, v42, v17, vcc
	v_cmp_nlt_f32_e32 vcc, s16, v0
	v_exp_f32_e32 v16, v16
	s_nop 0
	v_cndmask_b32_e64 v17, v201, -v17, vcc
	v_cmp_gt_f32_e32 vcc, s17, v17
	v_mul_f32_e32 v40, 0x4f800000, v17
	s_nop 0
	v_cndmask_b32_e32 v17, v17, v40, vcc
	v_sqrt_f32_e32 v40, v17
	s_nop 0
	v_add_u32_e32 v42, -1, v40
	v_fma_f32 v44, -v42, v40, v17
	v_cmp_ge_f32_e64 s[0:1], 0, v44
	v_add_u32_e32 v44, 1, v40
	s_nop 0
	v_cndmask_b32_e64 v42, v40, v42, s[0:1]
	v_fma_f32 v40, -v44, v40, v17
	v_cmp_lt_f32_e64 s[0:1], 0, v40
	s_nop 1
	v_cndmask_b32_e64 v40, v42, v44, s[0:1]
	v_mul_f32_e32 v42, 0x37800000, v40
	v_cndmask_b32_e32 v40, v40, v42, vcc
	v_cmp_class_f32_e32 vcc, v17, v193
	s_nop 1
	v_cndmask_b32_e32 v17, v40, v17, vcc
	v_cmp_ngt_f32_e32 vcc, s18, v0
	s_nop 1
	v_cndmask_b32_e32 v0, 1.0, v17, vcc
	v_mul_f32_e32 v0, v1, v0
	v_mul_f32_e32 v0, v49, v0
	ds_write_b32 v70, v16 offset:384
	ds_write_b32 v70, v0 offset:37248
	v_add_f32_e32 v0, v18, v36
	v_mul_f32_e32 v0, 0xbfb8aa3b, v0
	v_exp_f32_e32 v0, v0
	v_add_f32_e32 v1, v2, v38
	v_mul_f32_e32 v1, 0xbfb8aa3b, v1
	v_exp_f32_e32 v1, v1
	v_add_f32_e32 v0, 1.0, v0
	v_rcp_f32_e32 v0, v0
	v_add_f32_e32 v1, 1.0, v1
	v_rcp_f32_e32 v1, v1
	v_mul_f32_e32 v0, v0, v32
	v_mul_f32_e32 v2, 0x3fb8aa3b, v0
	v_add_f32_e32 v0, v0, v0
	v_mul_f32_e32 v16, 0x3fb8aa3b, v0
	v_rndne_f32_e32 v16, v16
	v_fmamk_f32 v17, v16, 0xbf317218, v0
	v_fmac_f32_e32 v17, 0x3102e308, v16
	v_fmamk_f32 v18, v17, 0x395133b1, v192
	v_cmp_eq_f32_e32 vcc, s15, v16
	v_cvt_i32_f32_e32 v16, v16
	v_fmaak_f32 v18, v17, v18, 0x3c0887f9
	v_fmaak_f32 v18, v17, v18, 0x3d2aaa81
	v_fmaak_f32 v18, v17, v18, 0x3e2aaaab
	v_fma_f32 v18, v17, v18, 0.5
	v_ldexp_f32 v16, 1.0, v16
	v_mul_f32_e32 v18, v17, v18
	v_cndmask_b32_e32 v16, v16, v202, vcc
	v_fmac_f32_e32 v17, v17, v18
	v_add_f32_e32 v18, -1.0, v16
	v_fmac_f32_e32 v18, v16, v17
	v_add_f32_e32 v16, v18, v18
	v_cndmask_b32_e32 v16, v18, v16, vcc
	v_cmp_nlt_f32_e32 vcc, s16, v0
	v_exp_f32_e32 v2, v2
	s_nop 0
	v_cndmask_b32_e64 v16, v201, -v16, vcc
	v_cmp_gt_f32_e32 vcc, s17, v16
	v_mul_f32_e32 v17, 0x4f800000, v16
	s_nop 0
	v_cndmask_b32_e32 v16, v16, v17, vcc
	v_sqrt_f32_e32 v17, v16
	s_nop 0
	v_add_u32_e32 v18, -1, v17
	v_fma_f32 v40, -v18, v17, v16
	v_cmp_ge_f32_e64 s[0:1], 0, v40
	v_add_u32_e32 v40, 1, v17
	s_nop 0
	v_cndmask_b32_e64 v18, v17, v18, s[0:1]
	v_fma_f32 v17, -v40, v17, v16
	v_cmp_lt_f32_e64 s[0:1], 0, v17
	s_nop 1
	v_cndmask_b32_e64 v17, v18, v40, s[0:1]
	v_mul_f32_e32 v18, 0x37800000, v17
	v_cndmask_b32_e32 v17, v17, v18, vcc
	v_cmp_class_f32_e32 vcc, v16, v193
	s_nop 1
	v_cndmask_b32_e32 v16, v17, v16, vcc
	v_cmp_ngt_f32_e32 vcc, s18, v0
	s_nop 1
	v_cndmask_b32_e32 v0, 1.0, v16, vcc
	v_mul_f32_e32 v0, v1, v0
	v_mul_f32_e32 v0, v67, v0
	ds_write_b32 v70, v2 offset:640
	ds_write_b32 v70, v0 offset:37504
	v_add_f32_e32 v0, v19, v36
	v_mul_f32_e32 v0, 0xbfb8aa3b, v0
	v_exp_f32_e32 v0, v0
	v_add_f32_e32 v1, v3, v38
	v_mul_f32_e32 v1, 0xbfb8aa3b, v1
	v_exp_f32_e32 v1, v1
	v_add_f32_e32 v0, 1.0, v0
	v_rcp_f32_e32 v0, v0
	v_add_f32_e32 v1, 1.0, v1
	v_rcp_f32_e32 v1, v1
	v_mul_f32_e32 v0, v0, v32
	v_mul_f32_e32 v2, 0x3fb8aa3b, v0
	v_add_f32_e32 v0, v0, v0
	v_mul_f32_e32 v3, 0x3fb8aa3b, v0
	v_rndne_f32_e32 v3, v3
	v_fmamk_f32 v16, v3, 0xbf317218, v0
	v_fmac_f32_e32 v16, 0x3102e308, v3
	v_fmamk_f32 v17, v16, 0x395133b1, v192
	v_cmp_eq_f32_e32 vcc, s15, v3
	v_cvt_i32_f32_e32 v3, v3
	v_fmaak_f32 v17, v16, v17, 0x3c0887f9
	v_fmaak_f32 v17, v16, v17, 0x3d2aaa81
	v_fmaak_f32 v17, v16, v17, 0x3e2aaaab
	v_fma_f32 v17, v16, v17, 0.5
	v_ldexp_f32 v3, 1.0, v3
	v_mul_f32_e32 v17, v16, v17
	v_cndmask_b32_e32 v3, v3, v202, vcc
	v_fmac_f32_e32 v16, v16, v17
	v_add_f32_e32 v17, -1.0, v3
	v_fmac_f32_e32 v17, v3, v16
	v_add_f32_e32 v3, v17, v17
	v_cndmask_b32_e32 v3, v17, v3, vcc
	v_cmp_nlt_f32_e32 vcc, s16, v0
	v_exp_f32_e32 v2, v2
	s_nop 0
	v_cndmask_b32_e64 v3, v201, -v3, vcc
	v_cmp_gt_f32_e32 vcc, s17, v3
	v_mul_f32_e32 v16, 0x4f800000, v3
	s_nop 0
	v_cndmask_b32_e32 v3, v3, v16, vcc
	v_sqrt_f32_e32 v16, v3
	s_nop 0
	v_add_u32_e32 v17, -1, v16
	v_fma_f32 v18, -v17, v16, v3
	v_cmp_ge_f32_e64 s[0:1], 0, v18
	v_add_u32_e32 v18, 1, v16
	s_nop 0
	v_cndmask_b32_e64 v17, v16, v17, s[0:1]
	v_fma_f32 v16, -v18, v16, v3
	v_cmp_lt_f32_e64 s[0:1], 0, v16
	s_nop 1
	v_cndmask_b32_e64 v16, v17, v18, s[0:1]
	v_mul_f32_e32 v17, 0x37800000, v16
	v_cndmask_b32_e32 v16, v16, v17, vcc
	v_cmp_class_f32_e32 vcc, v3, v193
	s_nop 1
	v_cndmask_b32_e32 v3, v16, v3, vcc
	v_cmp_ngt_f32_e32 vcc, s18, v0
	s_nop 1
	v_cndmask_b32_e32 v0, 1.0, v3, vcc
	v_mul_f32_e32 v0, v1, v0
	v_mul_f32_e32 v0, v51, v0
	ds_write_b32 v70, v2 offset:896
	ds_write_b32 v70, v0 offset:37760
	v_add_f32_e32 v0, v20, v36
	v_mul_f32_e32 v0, 0xbfb8aa3b, v0
	v_exp_f32_e32 v0, v0
	v_add_f32_e32 v1, v4, v38
	v_mul_f32_e32 v1, 0xbfb8aa3b, v1
	v_exp_f32_e32 v1, v1
	v_add_f32_e32 v0, 1.0, v0
	v_rcp_f32_e32 v0, v0
	v_add_f32_e32 v1, 1.0, v1
	v_rcp_f32_e32 v1, v1
	v_mul_f32_e32 v0, v0, v32
	v_mul_f32_e32 v2, 0x3fb8aa3b, v0
	v_add_f32_e32 v0, v0, v0
	v_mul_f32_e32 v3, 0x3fb8aa3b, v0
	v_rndne_f32_e32 v3, v3
	v_fmamk_f32 v4, v3, 0xbf317218, v0
	v_fmac_f32_e32 v4, 0x3102e308, v3
	v_fmamk_f32 v16, v4, 0x395133b1, v192
	v_cmp_eq_f32_e32 vcc, s15, v3
	v_cvt_i32_f32_e32 v3, v3
	v_fmaak_f32 v16, v4, v16, 0x3c0887f9
	v_fmaak_f32 v16, v4, v16, 0x3d2aaa81
	v_fmaak_f32 v16, v4, v16, 0x3e2aaaab
	v_fma_f32 v16, v4, v16, 0.5
	v_ldexp_f32 v3, 1.0, v3
	v_mul_f32_e32 v16, v4, v16
	v_cndmask_b32_e32 v3, v3, v202, vcc
	v_fmac_f32_e32 v4, v4, v16
	v_add_f32_e32 v16, -1.0, v3
	v_fmac_f32_e32 v16, v3, v4
	v_add_f32_e32 v3, v16, v16
	v_cndmask_b32_e32 v3, v16, v3, vcc
	v_cmp_nlt_f32_e32 vcc, s16, v0
	v_exp_f32_e32 v2, v2
	s_nop 0
	v_cndmask_b32_e64 v3, v201, -v3, vcc
	v_cmp_gt_f32_e32 vcc, s17, v3
	v_mul_f32_e32 v4, 0x4f800000, v3
	s_nop 0
	v_cndmask_b32_e32 v3, v3, v4, vcc
	v_sqrt_f32_e32 v4, v3
	s_nop 0
	v_add_u32_e32 v16, -1, v4
	v_fma_f32 v17, -v16, v4, v3
	v_cmp_ge_f32_e64 s[0:1], 0, v17
	v_add_u32_e32 v17, 1, v4
	s_nop 0
	v_cndmask_b32_e64 v16, v4, v16, s[0:1]
	v_fma_f32 v4, -v17, v4, v3
	v_cmp_lt_f32_e64 s[0:1], 0, v4
	s_nop 1
	v_cndmask_b32_e64 v4, v16, v17, s[0:1]
	v_mul_f32_e32 v16, 0x37800000, v4
	v_cndmask_b32_e32 v4, v4, v16, vcc
	v_cmp_class_f32_e32 vcc, v3, v193
	s_nop 1
	v_cndmask_b32_e32 v3, v4, v3, vcc
	v_cmp_ngt_f32_e32 vcc, s18, v0
	s_nop 1
	v_cndmask_b32_e32 v0, 1.0, v3, vcc
	v_mul_f32_e32 v0, v1, v0
	v_mul_f32_e32 v0, v69, v0
	ds_write_b32 v70, v2 offset:2176
	ds_write_b32 v70, v0 offset:39040
	v_add_f32_e32 v0, v21, v36
	v_mul_f32_e32 v0, 0xbfb8aa3b, v0
	v_exp_f32_e32 v0, v0
	v_add_f32_e32 v1, v5, v38
	v_mul_f32_e32 v1, 0xbfb8aa3b, v1
	v_exp_f32_e32 v1, v1
	v_add_f32_e32 v0, 1.0, v0
	v_rcp_f32_e32 v0, v0
	v_add_f32_e32 v1, 1.0, v1
	v_rcp_f32_e32 v1, v1
	v_mul_f32_e32 v0, v0, v32
	v_mul_f32_e32 v2, 0x3fb8aa3b, v0
	v_add_f32_e32 v0, v0, v0
	v_mul_f32_e32 v3, 0x3fb8aa3b, v0
	v_rndne_f32_e32 v3, v3
	v_fmamk_f32 v4, v3, 0xbf317218, v0
	v_fmac_f32_e32 v4, 0x3102e308, v3
	v_fmamk_f32 v5, v4, 0x395133b1, v192
	v_cmp_eq_f32_e32 vcc, s15, v3
	v_cvt_i32_f32_e32 v3, v3
	v_fmaak_f32 v5, v4, v5, 0x3c0887f9
	v_fmaak_f32 v5, v4, v5, 0x3d2aaa81
	v_fmaak_f32 v5, v4, v5, 0x3e2aaaab
	v_fma_f32 v5, v4, v5, 0.5
	v_ldexp_f32 v3, 1.0, v3
	v_mul_f32_e32 v5, v4, v5
	v_cndmask_b32_e32 v3, v3, v202, vcc
	v_fmac_f32_e32 v4, v4, v5
	v_add_f32_e32 v5, -1.0, v3
	v_fmac_f32_e32 v5, v3, v4
	v_add_f32_e32 v3, v5, v5
	v_cndmask_b32_e32 v3, v5, v3, vcc
	v_cmp_nlt_f32_e32 vcc, s16, v0
	v_exp_f32_e32 v2, v2
	s_nop 0
	v_cndmask_b32_e64 v3, v201, -v3, vcc
	v_cmp_gt_f32_e32 vcc, s17, v3
	v_mul_f32_e32 v4, 0x4f800000, v3
	s_nop 0
	v_cndmask_b32_e32 v3, v3, v4, vcc
	v_sqrt_f32_e32 v4, v3
	s_nop 0
	v_add_u32_e32 v5, -1, v4
	v_fma_f32 v16, -v5, v4, v3
	v_cmp_ge_f32_e64 s[0:1], 0, v16
	v_add_u32_e32 v16, 1, v4
	s_nop 0
	v_cndmask_b32_e64 v5, v4, v5, s[0:1]
	v_fma_f32 v4, -v16, v4, v3
	v_cmp_lt_f32_e64 s[0:1], 0, v4
	s_nop 1
	v_cndmask_b32_e64 v4, v5, v16, s[0:1]
	v_mul_f32_e32 v5, 0x37800000, v4
	v_cndmask_b32_e32 v4, v4, v5, vcc
	v_cmp_class_f32_e32 vcc, v3, v193
	s_nop 1
	v_cndmask_b32_e32 v3, v4, v3, vcc
	v_cmp_ngt_f32_e32 vcc, s18, v0
	s_nop 1
	v_cndmask_b32_e32 v0, 1.0, v3, vcc
	v_mul_f32_e32 v0, v1, v0
	v_mul_f32_e32 v0, v37, v0
	ds_write_b32 v70, v2 offset:2432
	ds_write_b32 v70, v0 offset:39296
	v_add_f32_e32 v0, v22, v36
	v_mul_f32_e32 v0, 0xbfb8aa3b, v0
	v_exp_f32_e32 v0, v0
	v_add_f32_e32 v1, v6, v38
	v_mul_f32_e32 v1, 0xbfb8aa3b, v1
	v_exp_f32_e32 v1, v1
	v_add_f32_e32 v0, 1.0, v0
	v_rcp_f32_e32 v0, v0
	v_add_f32_e32 v1, 1.0, v1
	v_rcp_f32_e32 v1, v1
	v_mul_f32_e32 v0, v0, v32
	v_mul_f32_e32 v2, 0x3fb8aa3b, v0
	v_add_f32_e32 v0, v0, v0
	v_mul_f32_e32 v3, 0x3fb8aa3b, v0
	v_rndne_f32_e32 v3, v3
	v_fmamk_f32 v4, v3, 0xbf317218, v0
	v_fmac_f32_e32 v4, 0x3102e308, v3
	v_fmamk_f32 v5, v4, 0x395133b1, v192
	v_cmp_eq_f32_e32 vcc, s15, v3
	v_cvt_i32_f32_e32 v3, v3
	v_fmaak_f32 v5, v4, v5, 0x3c0887f9
	v_fmaak_f32 v5, v4, v5, 0x3d2aaa81
	v_fmaak_f32 v5, v4, v5, 0x3e2aaaab
	v_fma_f32 v5, v4, v5, 0.5
	v_ldexp_f32 v3, 1.0, v3
	v_mul_f32_e32 v5, v4, v5
	v_cndmask_b32_e32 v3, v3, v202, vcc
	v_fmac_f32_e32 v4, v4, v5
	v_add_f32_e32 v5, -1.0, v3
	v_fmac_f32_e32 v5, v3, v4
	v_add_f32_e32 v3, v5, v5
	v_cndmask_b32_e32 v3, v5, v3, vcc
	v_cmp_nlt_f32_e32 vcc, s16, v0
	v_exp_f32_e32 v2, v2
	s_nop 0
	v_cndmask_b32_e64 v3, v201, -v3, vcc
	v_cmp_gt_f32_e32 vcc, s17, v3
	v_mul_f32_e32 v4, 0x4f800000, v3
	s_nop 0
	v_cndmask_b32_e32 v3, v3, v4, vcc
	v_sqrt_f32_e32 v4, v3
	s_nop 0
	v_add_u32_e32 v5, -1, v4
	v_fma_f32 v6, -v5, v4, v3
	v_cmp_ge_f32_e64 s[0:1], 0, v6
	v_add_u32_e32 v6, 1, v4
	s_nop 0
	v_cndmask_b32_e64 v5, v4, v5, s[0:1]
	v_fma_f32 v4, -v6, v4, v3
	v_cmp_lt_f32_e64 s[0:1], 0, v4
	s_nop 1
	v_cndmask_b32_e64 v4, v5, v6, s[0:1]
	v_mul_f32_e32 v5, 0x37800000, v4
	v_cndmask_b32_e32 v4, v4, v5, vcc
	v_cmp_class_f32_e32 vcc, v3, v193
	s_nop 1
	v_cndmask_b32_e32 v3, v4, v3, vcc
	v_cmp_ngt_f32_e32 vcc, s18, v0
	s_nop 1
	v_cndmask_b32_e32 v0, 1.0, v3, vcc
	v_mul_f32_e32 v0, v1, v0
	v_mul_f32_e32 v0, v53, v0
	ds_write_b32 v70, v2 offset:2688
	ds_write_b32 v70, v0 offset:39552
	v_add_f32_e32 v0, v23, v36
	v_mul_f32_e32 v0, 0xbfb8aa3b, v0
	v_exp_f32_e32 v0, v0
	v_add_f32_e32 v1, v7, v38
	v_mul_f32_e32 v1, 0xbfb8aa3b, v1
	v_exp_f32_e32 v1, v1
	v_add_f32_e32 v0, 1.0, v0
	v_rcp_f32_e32 v0, v0
	v_add_f32_e32 v1, 1.0, v1
	v_rcp_f32_e32 v1, v1
	v_mul_f32_e32 v0, v0, v32
	v_mul_f32_e32 v2, 0x3fb8aa3b, v0
	v_add_f32_e32 v0, v0, v0
	v_mul_f32_e32 v3, 0x3fb8aa3b, v0
	v_rndne_f32_e32 v3, v3
	v_fmamk_f32 v4, v3, 0xbf317218, v0
	v_fmac_f32_e32 v4, 0x3102e308, v3
	v_fmamk_f32 v5, v4, 0x395133b1, v192
	v_cmp_eq_f32_e32 vcc, s15, v3
	v_cvt_i32_f32_e32 v3, v3
	v_fmaak_f32 v5, v4, v5, 0x3c0887f9
	v_fmaak_f32 v5, v4, v5, 0x3d2aaa81
	v_fmaak_f32 v5, v4, v5, 0x3e2aaaab
	v_fma_f32 v5, v4, v5, 0.5
	v_ldexp_f32 v3, 1.0, v3
	v_mul_f32_e32 v5, v4, v5
	v_cndmask_b32_e32 v3, v3, v202, vcc
	v_fmac_f32_e32 v4, v4, v5
	v_add_f32_e32 v5, -1.0, v3
	v_fmac_f32_e32 v5, v3, v4
	v_add_f32_e32 v3, v5, v5
	v_cndmask_b32_e32 v3, v5, v3, vcc
	v_cmp_nlt_f32_e32 vcc, s16, v0
	v_exp_f32_e32 v2, v2
	s_nop 0
	v_cndmask_b32_e64 v3, v201, -v3, vcc
	v_cmp_gt_f32_e32 vcc, s17, v3
	v_mul_f32_e32 v4, 0x4f800000, v3
	s_nop 0
	v_cndmask_b32_e32 v3, v3, v4, vcc
	v_sqrt_f32_e32 v4, v3
	s_nop 0
	v_add_u32_e32 v5, -1, v4
	v_fma_f32 v6, -v5, v4, v3
	v_cmp_ge_f32_e64 s[0:1], 0, v6
	v_add_u32_e32 v6, 1, v4
	s_nop 0
	v_cndmask_b32_e64 v5, v4, v5, s[0:1]
	v_fma_f32 v4, -v6, v4, v3
	v_cmp_lt_f32_e64 s[0:1], 0, v4
	s_nop 1
	v_cndmask_b32_e64 v4, v5, v6, s[0:1]
	v_mul_f32_e32 v5, 0x37800000, v4
	v_cndmask_b32_e32 v4, v4, v5, vcc
	v_cmp_class_f32_e32 vcc, v3, v193
	s_nop 1
	v_cndmask_b32_e32 v3, v4, v3, vcc
	v_cmp_ngt_f32_e32 vcc, s18, v0
	s_nop 1
	v_cndmask_b32_e32 v0, 1.0, v3, vcc
	v_mul_f32_e32 v0, v1, v0
	v_mul_f32_e32 v0, v39, v0
	ds_write_b32 v70, v2 offset:2944
	ds_write_b32 v70, v0 offset:39808
	v_add_f32_e32 v0, v24, v36
	v_mul_f32_e32 v0, 0xbfb8aa3b, v0
	v_exp_f32_e32 v0, v0
	v_add_f32_e32 v1, v8, v38
	v_mul_f32_e32 v1, 0xbfb8aa3b, v1
	v_exp_f32_e32 v1, v1
	v_add_f32_e32 v0, 1.0, v0
	v_rcp_f32_e32 v0, v0
	v_add_f32_e32 v1, 1.0, v1
	v_rcp_f32_e32 v1, v1
	v_mul_f32_e32 v0, v0, v32
	v_mul_f32_e32 v2, 0x3fb8aa3b, v0
	v_add_f32_e32 v0, v0, v0
	v_mul_f32_e32 v3, 0x3fb8aa3b, v0
	v_rndne_f32_e32 v3, v3
	v_fmamk_f32 v4, v3, 0xbf317218, v0
	v_fmac_f32_e32 v4, 0x3102e308, v3
	v_fmamk_f32 v5, v4, 0x395133b1, v192
	v_cmp_eq_f32_e32 vcc, s15, v3
	v_cvt_i32_f32_e32 v3, v3
	v_fmaak_f32 v5, v4, v5, 0x3c0887f9
	v_fmaak_f32 v5, v4, v5, 0x3d2aaa81
	v_fmaak_f32 v5, v4, v5, 0x3e2aaaab
	v_fma_f32 v5, v4, v5, 0.5
	v_ldexp_f32 v3, 1.0, v3
	v_mul_f32_e32 v5, v4, v5
	v_cndmask_b32_e32 v3, v3, v202, vcc
	v_fmac_f32_e32 v4, v4, v5
	v_add_f32_e32 v5, -1.0, v3
	v_fmac_f32_e32 v5, v3, v4
	v_add_f32_e32 v3, v5, v5
	v_cndmask_b32_e32 v3, v5, v3, vcc
	v_cmp_nlt_f32_e32 vcc, s16, v0
	v_exp_f32_e32 v2, v2
	s_nop 0
	v_cndmask_b32_e64 v3, v201, -v3, vcc
	v_cmp_gt_f32_e32 vcc, s17, v3
	v_mul_f32_e32 v4, 0x4f800000, v3
	s_nop 0
	v_cndmask_b32_e32 v3, v3, v4, vcc
	v_sqrt_f32_e32 v4, v3
	s_nop 0
	v_add_u32_e32 v5, -1, v4
	v_fma_f32 v6, -v5, v4, v3
	v_cmp_ge_f32_e64 s[0:1], 0, v6
	v_add_u32_e32 v6, 1, v4
	s_nop 0
	v_cndmask_b32_e64 v5, v4, v5, s[0:1]
	v_fma_f32 v4, -v6, v4, v3
	v_cmp_lt_f32_e64 s[0:1], 0, v4
	s_nop 1
	v_cndmask_b32_e64 v4, v5, v6, s[0:1]
	v_mul_f32_e32 v5, 0x37800000, v4
	v_cndmask_b32_e32 v4, v4, v5, vcc
	v_cmp_class_f32_e32 vcc, v3, v193
	s_nop 1
	v_cndmask_b32_e32 v3, v4, v3, vcc
	v_cmp_ngt_f32_e32 vcc, s18, v0
	s_nop 1
	v_cndmask_b32_e32 v0, 1.0, v3, vcc
	v_mul_f32_e32 v0, v1, v0
	v_mul_f32_e32 v0, v55, v0
	ds_write_b32 v70, v2 offset:4224
	ds_write_b32 v70, v0 offset:41088
	v_add_f32_e32 v0, v25, v36
	v_mul_f32_e32 v0, 0xbfb8aa3b, v0
	v_exp_f32_e32 v0, v0
	v_add_f32_e32 v1, v9, v38
	v_mul_f32_e32 v1, 0xbfb8aa3b, v1
	v_exp_f32_e32 v1, v1
	v_add_f32_e32 v0, 1.0, v0
	v_rcp_f32_e32 v0, v0
	v_add_f32_e32 v1, 1.0, v1
	v_rcp_f32_e32 v1, v1
	v_mul_f32_e32 v0, v0, v32
	v_mul_f32_e32 v2, 0x3fb8aa3b, v0
	v_add_f32_e32 v0, v0, v0
	v_mul_f32_e32 v3, 0x3fb8aa3b, v0
	v_rndne_f32_e32 v3, v3
	v_fmamk_f32 v4, v3, 0xbf317218, v0
	v_fmac_f32_e32 v4, 0x3102e308, v3
	v_fmamk_f32 v5, v4, 0x395133b1, v192
	v_cmp_eq_f32_e32 vcc, s15, v3
	v_cvt_i32_f32_e32 v3, v3
	v_fmaak_f32 v5, v4, v5, 0x3c0887f9
	v_fmaak_f32 v5, v4, v5, 0x3d2aaa81
	v_fmaak_f32 v5, v4, v5, 0x3e2aaaab
	v_fma_f32 v5, v4, v5, 0.5
	v_ldexp_f32 v3, 1.0, v3
	v_mul_f32_e32 v5, v4, v5
	v_cndmask_b32_e32 v3, v3, v202, vcc
	v_fmac_f32_e32 v4, v4, v5
	v_add_f32_e32 v5, -1.0, v3
	v_fmac_f32_e32 v5, v3, v4
	v_add_f32_e32 v3, v5, v5
	v_cndmask_b32_e32 v3, v5, v3, vcc
	v_cmp_nlt_f32_e32 vcc, s16, v0
	v_exp_f32_e32 v2, v2
	s_nop 0
	v_cndmask_b32_e64 v3, v201, -v3, vcc
	v_cmp_gt_f32_e32 vcc, s17, v3
	v_mul_f32_e32 v4, 0x4f800000, v3
	s_nop 0
	v_cndmask_b32_e32 v3, v3, v4, vcc
	v_sqrt_f32_e32 v4, v3
	s_nop 0
	v_add_u32_e32 v5, -1, v4
	v_fma_f32 v6, -v5, v4, v3
	v_cmp_ge_f32_e64 s[0:1], 0, v6
	v_add_u32_e32 v6, 1, v4
	s_nop 0
	v_cndmask_b32_e64 v5, v4, v5, s[0:1]
	v_fma_f32 v4, -v6, v4, v3
	v_cmp_lt_f32_e64 s[0:1], 0, v4
	s_nop 1
	v_cndmask_b32_e64 v4, v5, v6, s[0:1]
	v_mul_f32_e32 v5, 0x37800000, v4
	v_cndmask_b32_e32 v4, v4, v5, vcc
	v_cmp_class_f32_e32 vcc, v3, v193
	s_nop 1
	v_cndmask_b32_e32 v3, v4, v3, vcc
	v_cmp_ngt_f32_e32 vcc, s18, v0
	s_nop 1
	v_cndmask_b32_e32 v0, 1.0, v3, vcc
	v_mul_f32_e32 v0, v1, v0
	v_mul_f32_e32 v0, v41, v0
	ds_write_b32 v70, v2 offset:4480
	ds_write_b32 v70, v0 offset:41344
	v_add_f32_e32 v0, v26, v36
	v_mul_f32_e32 v0, 0xbfb8aa3b, v0
	v_exp_f32_e32 v0, v0
	v_add_f32_e32 v1, v10, v38
	v_mul_f32_e32 v1, 0xbfb8aa3b, v1
	v_exp_f32_e32 v1, v1
	v_add_f32_e32 v0, 1.0, v0
	v_rcp_f32_e32 v0, v0
	v_add_f32_e32 v1, 1.0, v1
	v_rcp_f32_e32 v1, v1
	v_mul_f32_e32 v0, v0, v32
	v_mul_f32_e32 v2, 0x3fb8aa3b, v0
	v_add_f32_e32 v0, v0, v0
	v_mul_f32_e32 v3, 0x3fb8aa3b, v0
	v_rndne_f32_e32 v3, v3
	v_fmamk_f32 v4, v3, 0xbf317218, v0
	v_fmac_f32_e32 v4, 0x3102e308, v3
	v_fmamk_f32 v5, v4, 0x395133b1, v192
	v_cmp_eq_f32_e32 vcc, s15, v3
	v_cvt_i32_f32_e32 v3, v3
	v_fmaak_f32 v5, v4, v5, 0x3c0887f9
	v_fmaak_f32 v5, v4, v5, 0x3d2aaa81
	v_fmaak_f32 v5, v4, v5, 0x3e2aaaab
	v_fma_f32 v5, v4, v5, 0.5
	v_ldexp_f32 v3, 1.0, v3
	v_mul_f32_e32 v5, v4, v5
	v_cndmask_b32_e32 v3, v3, v202, vcc
	v_fmac_f32_e32 v4, v4, v5
	v_add_f32_e32 v5, -1.0, v3
	v_fmac_f32_e32 v5, v3, v4
	v_add_f32_e32 v3, v5, v5
	v_cndmask_b32_e32 v3, v5, v3, vcc
	v_cmp_nlt_f32_e32 vcc, s16, v0
	v_exp_f32_e32 v2, v2
	s_nop 0
	v_cndmask_b32_e64 v3, v201, -v3, vcc
	v_cmp_gt_f32_e32 vcc, s17, v3
	v_mul_f32_e32 v4, 0x4f800000, v3
	s_nop 0
	v_cndmask_b32_e32 v3, v3, v4, vcc
	v_sqrt_f32_e32 v4, v3
	s_nop 0
	v_add_u32_e32 v5, -1, v4
	v_fma_f32 v6, -v5, v4, v3
	v_cmp_ge_f32_e64 s[0:1], 0, v6
	v_add_u32_e32 v6, 1, v4
	s_nop 0
	v_cndmask_b32_e64 v5, v4, v5, s[0:1]
	v_fma_f32 v4, -v6, v4, v3
	v_cmp_lt_f32_e64 s[0:1], 0, v4
	s_nop 1
	v_cndmask_b32_e64 v4, v5, v6, s[0:1]
	v_mul_f32_e32 v5, 0x37800000, v4
	v_cndmask_b32_e32 v4, v4, v5, vcc
	v_cmp_class_f32_e32 vcc, v3, v193
	s_nop 1
	v_cndmask_b32_e32 v3, v4, v3, vcc
	v_cmp_ngt_f32_e32 vcc, s18, v0
	s_nop 1
	v_cndmask_b32_e32 v0, 1.0, v3, vcc
	v_mul_f32_e32 v0, v1, v0
	v_mul_f32_e32 v0, v57, v0
	ds_write_b32 v70, v2 offset:4736
	ds_write_b32 v70, v0 offset:41600
	v_add_f32_e32 v0, v27, v36
	v_mul_f32_e32 v0, 0xbfb8aa3b, v0
	v_exp_f32_e32 v0, v0
	v_add_f32_e32 v1, v11, v38
	v_mul_f32_e32 v1, 0xbfb8aa3b, v1
	v_exp_f32_e32 v1, v1
	v_add_f32_e32 v0, 1.0, v0
	v_rcp_f32_e32 v0, v0
	v_add_f32_e32 v1, 1.0, v1
	v_rcp_f32_e32 v1, v1
	v_mul_f32_e32 v0, v0, v32
	v_mul_f32_e32 v2, 0x3fb8aa3b, v0
	v_add_f32_e32 v0, v0, v0
	v_mul_f32_e32 v3, 0x3fb8aa3b, v0
	v_rndne_f32_e32 v3, v3
	v_fmamk_f32 v4, v3, 0xbf317218, v0
	v_fmac_f32_e32 v4, 0x3102e308, v3
	v_fmamk_f32 v5, v4, 0x395133b1, v192
	v_cmp_eq_f32_e32 vcc, s15, v3
	v_cvt_i32_f32_e32 v3, v3
	v_fmaak_f32 v5, v4, v5, 0x3c0887f9
	v_fmaak_f32 v5, v4, v5, 0x3d2aaa81
	v_fmaak_f32 v5, v4, v5, 0x3e2aaaab
	v_fma_f32 v5, v4, v5, 0.5
	v_ldexp_f32 v3, 1.0, v3
	v_mul_f32_e32 v5, v4, v5
	v_cndmask_b32_e32 v3, v3, v202, vcc
	v_fmac_f32_e32 v4, v4, v5
	v_add_f32_e32 v5, -1.0, v3
	v_fmac_f32_e32 v5, v3, v4
	v_add_f32_e32 v3, v5, v5
	v_cndmask_b32_e32 v3, v5, v3, vcc
	v_cmp_nlt_f32_e32 vcc, s16, v0
	v_exp_f32_e32 v2, v2
	s_nop 0
	v_cndmask_b32_e64 v3, v201, -v3, vcc
	v_cmp_gt_f32_e32 vcc, s17, v3
	v_mul_f32_e32 v4, 0x4f800000, v3
	s_nop 0
	v_cndmask_b32_e32 v3, v3, v4, vcc
	v_sqrt_f32_e32 v4, v3
	s_nop 0
	v_add_u32_e32 v5, -1, v4
	v_fma_f32 v6, -v5, v4, v3
	v_cmp_ge_f32_e64 s[0:1], 0, v6
	v_add_u32_e32 v6, 1, v4
	s_nop 0
	v_cndmask_b32_e64 v5, v4, v5, s[0:1]
	v_fma_f32 v4, -v6, v4, v3
	v_cmp_lt_f32_e64 s[0:1], 0, v4
	s_nop 1
	v_cndmask_b32_e64 v4, v5, v6, s[0:1]
	v_mul_f32_e32 v5, 0x37800000, v4
	v_cndmask_b32_e32 v4, v4, v5, vcc
	v_cmp_class_f32_e32 vcc, v3, v193
	s_nop 1
	v_cndmask_b32_e32 v3, v4, v3, vcc
	v_cmp_ngt_f32_e32 vcc, s18, v0
	s_nop 1
	v_cndmask_b32_e32 v0, 1.0, v3, vcc
	v_mul_f32_e32 v0, v1, v0
	v_mul_f32_e32 v0, v43, v0
	ds_write_b32 v70, v2 offset:4992
	ds_write_b32 v70, v0 offset:41856
	v_add_f32_e32 v0, v28, v36
	v_mul_f32_e32 v0, 0xbfb8aa3b, v0
	v_exp_f32_e32 v0, v0
	v_add_f32_e32 v1, v12, v38
	v_mul_f32_e32 v1, 0xbfb8aa3b, v1
	v_exp_f32_e32 v1, v1
	v_add_f32_e32 v0, 1.0, v0
	v_rcp_f32_e32 v0, v0
	v_add_f32_e32 v1, 1.0, v1
	v_rcp_f32_e32 v1, v1
	v_mul_f32_e32 v0, v0, v32
	v_mul_f32_e32 v2, 0x3fb8aa3b, v0
	v_add_f32_e32 v0, v0, v0
	v_mul_f32_e32 v3, 0x3fb8aa3b, v0
	v_rndne_f32_e32 v3, v3
	v_fmamk_f32 v4, v3, 0xbf317218, v0
	v_fmac_f32_e32 v4, 0x3102e308, v3
	v_fmamk_f32 v5, v4, 0x395133b1, v192
	v_cmp_eq_f32_e32 vcc, s15, v3
	v_cvt_i32_f32_e32 v3, v3
	v_fmaak_f32 v5, v4, v5, 0x3c0887f9
	v_fmaak_f32 v5, v4, v5, 0x3d2aaa81
	v_fmaak_f32 v5, v4, v5, 0x3e2aaaab
	v_fma_f32 v5, v4, v5, 0.5
	v_ldexp_f32 v3, 1.0, v3
	v_mul_f32_e32 v5, v4, v5
	v_cndmask_b32_e32 v3, v3, v202, vcc
	v_fmac_f32_e32 v4, v4, v5
	v_add_f32_e32 v5, -1.0, v3
	v_fmac_f32_e32 v5, v3, v4
	v_add_f32_e32 v3, v5, v5
	v_cndmask_b32_e32 v3, v5, v3, vcc
	v_cmp_nlt_f32_e32 vcc, s16, v0
	v_exp_f32_e32 v2, v2
	s_nop 0
	v_cndmask_b32_e64 v3, v201, -v3, vcc
	v_cmp_gt_f32_e32 vcc, s17, v3
	v_mul_f32_e32 v4, 0x4f800000, v3
	s_nop 0
	v_cndmask_b32_e32 v3, v3, v4, vcc
	v_sqrt_f32_e32 v4, v3
	s_nop 0
	v_add_u32_e32 v5, -1, v4
	v_fma_f32 v6, -v5, v4, v3
	v_cmp_ge_f32_e64 s[0:1], 0, v6
	v_add_u32_e32 v6, 1, v4
	s_nop 0
	v_cndmask_b32_e64 v5, v4, v5, s[0:1]
	v_fma_f32 v4, -v6, v4, v3
	v_cmp_lt_f32_e64 s[0:1], 0, v4
	s_nop 1
	v_cndmask_b32_e64 v4, v5, v6, s[0:1]
	v_mul_f32_e32 v5, 0x37800000, v4
	v_cndmask_b32_e32 v4, v4, v5, vcc
	v_cmp_class_f32_e32 vcc, v3, v193
	s_nop 1
	v_cndmask_b32_e32 v3, v4, v3, vcc
	v_cmp_ngt_f32_e32 vcc, s18, v0
	s_nop 1
	v_cndmask_b32_e32 v0, 1.0, v3, vcc
	v_mul_f32_e32 v0, v1, v0
	v_mul_f32_e32 v0, v59, v0
	ds_write_b32 v70, v2 offset:6272
	ds_write_b32 v70, v0 offset:43136
	v_add_f32_e32 v0, v29, v36
	v_mul_f32_e32 v0, 0xbfb8aa3b, v0
	v_exp_f32_e32 v0, v0
	v_add_f32_e32 v1, v13, v38
	v_mul_f32_e32 v1, 0xbfb8aa3b, v1
	v_exp_f32_e32 v1, v1
	v_add_f32_e32 v0, 1.0, v0
	v_rcp_f32_e32 v0, v0
	v_add_f32_e32 v1, 1.0, v1
	v_rcp_f32_e32 v1, v1
	v_mul_f32_e32 v0, v0, v32
	v_mul_f32_e32 v2, 0x3fb8aa3b, v0
	v_add_f32_e32 v0, v0, v0
	v_mul_f32_e32 v3, 0x3fb8aa3b, v0
	v_rndne_f32_e32 v3, v3
	v_fmamk_f32 v4, v3, 0xbf317218, v0
	v_fmac_f32_e32 v4, 0x3102e308, v3
	v_fmamk_f32 v5, v4, 0x395133b1, v192
	v_cmp_eq_f32_e32 vcc, s15, v3
	v_cvt_i32_f32_e32 v3, v3
	v_fmaak_f32 v5, v4, v5, 0x3c0887f9
	v_fmaak_f32 v5, v4, v5, 0x3d2aaa81
	v_fmaak_f32 v5, v4, v5, 0x3e2aaaab
	v_fma_f32 v5, v4, v5, 0.5
	v_ldexp_f32 v3, 1.0, v3
	v_mul_f32_e32 v5, v4, v5
	v_cndmask_b32_e32 v3, v3, v202, vcc
	v_fmac_f32_e32 v4, v4, v5
	v_add_f32_e32 v5, -1.0, v3
	v_fmac_f32_e32 v5, v3, v4
	v_add_f32_e32 v3, v5, v5
	v_cndmask_b32_e32 v3, v5, v3, vcc
	v_cmp_nlt_f32_e32 vcc, s16, v0
	v_exp_f32_e32 v2, v2
	s_nop 0
	v_cndmask_b32_e64 v3, v201, -v3, vcc
	v_cmp_gt_f32_e32 vcc, s17, v3
	v_mul_f32_e32 v4, 0x4f800000, v3
	s_nop 0
	v_cndmask_b32_e32 v3, v3, v4, vcc
	v_sqrt_f32_e32 v4, v3
	s_nop 0
	v_add_u32_e32 v5, -1, v4
	v_fma_f32 v6, -v5, v4, v3
	v_cmp_ge_f32_e64 s[0:1], 0, v6
	v_add_u32_e32 v6, 1, v4
	s_nop 0
	v_cndmask_b32_e64 v5, v4, v5, s[0:1]
	v_fma_f32 v4, -v6, v4, v3
	v_cmp_lt_f32_e64 s[0:1], 0, v4
	s_nop 1
	v_cndmask_b32_e64 v4, v5, v6, s[0:1]
	v_mul_f32_e32 v5, 0x37800000, v4
	v_cndmask_b32_e32 v4, v4, v5, vcc
	v_cmp_class_f32_e32 vcc, v3, v193
	s_nop 1
	v_cndmask_b32_e32 v3, v4, v3, vcc
	v_cmp_ngt_f32_e32 vcc, s18, v0
	s_nop 1
	v_cndmask_b32_e32 v0, 1.0, v3, vcc
	v_mul_f32_e32 v0, v1, v0
	v_mul_f32_e32 v0, v45, v0
	ds_write_b32 v70, v2 offset:6528
	ds_write_b32 v70, v0 offset:43392
	v_add_f32_e32 v0, v30, v36
	v_mul_f32_e32 v0, 0xbfb8aa3b, v0
	v_exp_f32_e32 v0, v0
	v_add_f32_e32 v1, v14, v38
	v_mul_f32_e32 v1, 0xbfb8aa3b, v1
	v_exp_f32_e32 v1, v1
	v_add_f32_e32 v0, 1.0, v0
	v_rcp_f32_e32 v0, v0
	v_add_f32_e32 v1, 1.0, v1
	v_rcp_f32_e32 v1, v1
	v_mul_f32_e32 v0, v0, v32
	v_mul_f32_e32 v2, 0x3fb8aa3b, v0
	v_add_f32_e32 v0, v0, v0
	v_mul_f32_e32 v3, 0x3fb8aa3b, v0
	v_rndne_f32_e32 v3, v3
	v_fmamk_f32 v4, v3, 0xbf317218, v0
	v_fmac_f32_e32 v4, 0x3102e308, v3
	v_fmamk_f32 v5, v4, 0x395133b1, v192
	v_cmp_eq_f32_e32 vcc, s15, v3
	v_cvt_i32_f32_e32 v3, v3
	v_fmaak_f32 v5, v4, v5, 0x3c0887f9
	v_fmaak_f32 v5, v4, v5, 0x3d2aaa81
	v_fmaak_f32 v5, v4, v5, 0x3e2aaaab
	v_fma_f32 v5, v4, v5, 0.5
	v_ldexp_f32 v3, 1.0, v3
	v_mul_f32_e32 v5, v4, v5
	v_cndmask_b32_e32 v3, v3, v202, vcc
	v_fmac_f32_e32 v4, v4, v5
	v_add_f32_e32 v5, -1.0, v3
	v_fmac_f32_e32 v5, v3, v4
	v_add_f32_e32 v3, v5, v5
	v_cndmask_b32_e32 v3, v5, v3, vcc
	v_cmp_nlt_f32_e32 vcc, s16, v0
	v_exp_f32_e32 v2, v2
	s_nop 0
	v_cndmask_b32_e64 v3, v201, -v3, vcc
	v_cmp_gt_f32_e32 vcc, s17, v3
	v_mul_f32_e32 v4, 0x4f800000, v3
	s_nop 0
	v_cndmask_b32_e32 v3, v3, v4, vcc
	v_sqrt_f32_e32 v4, v3
	s_nop 0
	v_add_u32_e32 v5, -1, v4
	v_fma_f32 v6, -v5, v4, v3
	v_cmp_ge_f32_e64 s[0:1], 0, v6
	v_add_u32_e32 v6, 1, v4
	s_nop 0
	v_cndmask_b32_e64 v5, v4, v5, s[0:1]
	v_fma_f32 v4, -v6, v4, v3
	v_cmp_lt_f32_e64 s[0:1], 0, v4
	s_nop 1
	v_cndmask_b32_e64 v4, v5, v6, s[0:1]
	v_mul_f32_e32 v5, 0x37800000, v4
	v_cndmask_b32_e32 v4, v4, v5, vcc
	v_cmp_class_f32_e32 vcc, v3, v193
	s_nop 1
	v_cndmask_b32_e32 v3, v4, v3, vcc
	v_cmp_ngt_f32_e32 vcc, s18, v0
	s_nop 1
	v_cndmask_b32_e32 v0, 1.0, v3, vcc
	v_mul_f32_e32 v0, v1, v0
	v_mul_f32_e32 v0, v35, v0
	v_add_u32_e32 v1, 0x1800, v70
	ds_write2_b32 v1, v2, v34 offset0:160 offset1:192
	ds_write_b32 v70, v0 offset:43648
	v_add_f32_e32 v0, v31, v36
	v_mul_f32_e32 v0, 0xbfb8aa3b, v0
	v_exp_f32_e32 v0, v0
	v_add_f32_e32 v1, v15, v38
	v_mul_f32_e32 v1, 0xbfb8aa3b, v1
	v_exp_f32_e32 v1, v1
	v_add_f32_e32 v0, 1.0, v0
	v_rcp_f32_e32 v0, v0
	v_add_f32_e32 v1, 1.0, v1
	v_rcp_f32_e32 v1, v1
	v_mul_f32_e32 v0, v0, v32
	v_mul_f32_e32 v2, 0x3fb8aa3b, v0
	v_add_f32_e32 v0, v0, v0
	v_mul_f32_e32 v3, 0x3fb8aa3b, v0
	v_rndne_f32_e32 v3, v3
	v_fmamk_f32 v4, v3, 0xbf317218, v0
	v_fmac_f32_e32 v4, 0x3102e308, v3
	v_fmamk_f32 v5, v4, 0x395133b1, v192
	v_cmp_eq_f32_e32 vcc, s15, v3
	v_cvt_i32_f32_e32 v3, v3
	v_fmaak_f32 v5, v4, v5, 0x3c0887f9
	v_fmaak_f32 v5, v4, v5, 0x3d2aaa81
	v_fmaak_f32 v5, v4, v5, 0x3e2aaaab
	v_fma_f32 v5, v4, v5, 0.5
	v_ldexp_f32 v3, 1.0, v3
	v_mul_f32_e32 v5, v4, v5
	v_cndmask_b32_e32 v3, v3, v202, vcc
	v_fmac_f32_e32 v4, v4, v5
	v_add_f32_e32 v5, -1.0, v3
	v_fmac_f32_e32 v5, v3, v4
	v_add_f32_e32 v3, v5, v5
	v_cndmask_b32_e32 v3, v5, v3, vcc
	v_cmp_nlt_f32_e32 vcc, s16, v0
	v_exp_f32_e32 v2, v2
	s_nop 0
	v_cndmask_b32_e64 v3, v201, -v3, vcc
	v_cmp_gt_f32_e32 vcc, s17, v3
	v_mul_f32_e32 v4, 0x4f800000, v3
	s_nop 0
	v_cndmask_b32_e32 v3, v3, v4, vcc
	v_sqrt_f32_e32 v4, v3
	s_nop 0
	v_add_u32_e32 v5, -1, v4
	v_fma_f32 v6, -v5, v4, v3
	v_cmp_ge_f32_e64 s[0:1], 0, v6
	v_add_u32_e32 v6, 1, v4
	s_nop 0
	v_cndmask_b32_e64 v5, v4, v5, s[0:1]
	v_fma_f32 v4, -v6, v4, v3
	v_cmp_lt_f32_e64 s[0:1], 0, v4
	s_nop 1
	v_cndmask_b32_e64 v4, v5, v6, s[0:1]
	v_mul_f32_e32 v5, 0x37800000, v4
	v_cndmask_b32_e32 v4, v4, v5, vcc
	v_cmp_class_f32_e32 vcc, v3, v193
	v_mov_b32_e32 v6, 1.0
	s_mov_b32 s0, 24
	v_cndmask_b32_e32 v3, v4, v3, vcc
	v_cmp_ngt_f32_e32 vcc, s18, v0
	s_nop 1
	v_cndmask_b32_e32 v0, 1.0, v3, vcc
	v_mul_f32_e32 v0, v1, v0
	v_mul_f32_e32 v0, v33, v0
	ds_write_b32 v70, v2 offset:7040
	ds_write_b32 v70, v0 offset:43904
	v_mov_b32_e32 v2, v162
	s_waitcnt lgkmcnt(0)
	s_barrier
	s_cselect_b64 vcc, -1, 0
	v_and_b32_e32 v3, 63, v2
	v_ashrrev_i32_e32 v4, 6, v2
	v_lshl_or_b32 v5, v4, 11, v3
	v_mov_b32_e32 v1, 0

.LBB0_587:
	s_mul_hi_i32 s0, s2, 0x38e38e39
	s_lshr_b32 s1, s0, 31
	s_ashr_i32 s0, s0, 2
	s_add_i32 s0, s0, s1
	s_mul_i32 s1, s0, 18
	s_sub_i32 s1, s2, s1
	s_and_b32 s13, s0, 1
	s_bfe_u32 s3, s0, 0x20001
	s_ashr_i32 s0, s0, 3
	s_lshl_b32 s4, s1, 7
	s_cmp_lt_i32 s1, 2
	s_movk_i32 s6, 0xff00
	s_cselect_b32 s1, 8, 11
	s_cselect_b32 s6, 0x4000, s6
	s_lshl_b32 s0, s0, s1
	s_add_i32 s12, s6, s4
	s_waitcnt vmcnt(7)
	v_mov_b32_e32 v65, v162
	s_add_i32 s12, s12, s0
	s_movk_i32 s0, 0x80
	v_cmp_gt_i32_e32 vcc, s0, v65
	v_lshl_add_u32 v2, v65, 2, 0
	s_barrier
	s_and_saveexec_b64 s[6:7], vcc
	s_cbranch_execz .LBB0_589
	s_waitcnt lgkmcnt(0)
	v_add_u32_e32 v0, s12, v65
	v_ashrrev_i32_e32 v1, 31, v0
	v_readlane_b32 s0, v249, 17
	v_lshlrev_b64 v[0:1], 6, v[0:1]
	v_readlane_b32 s1, v249, 18
	s_lshl_b32 s38, s13, 3
	s_lshl_b32 s4, s13, 5
	v_lshl_add_u64 v[0:1], s[0:1], 0, v[0:1]
	v_readlane_b32 s8, v248, 19
	v_lshl_add_u64 v[0:1], v[0:1], 0, s[4:5]
	s_lshl_b32 s4, s3, 2
	s_or_b32 s0, s38, s8
	v_lshl_add_u64 v[0:1], v[0:1], 0, s[4:5]
	s_or_b32 s4, s0, s3
	s_lshl_b64 s[0:1], s[4:5], 2
	v_readlane_b32 s20, v251, 24
	v_readlane_b32 s21, v251, 25
	s_add_u32 s0, s20, s0
	s_addc_u32 s1, s21, s1
	global_load_dword v4, v97, s[0:1]
	s_or_b32 s0, s3, s8
	s_add_i32 s4, s0, s38
	s_lshl_b64 s[0:1], s[4:5], 2
	s_add_u32 s0, s20, s0
	s_addc_u32 s1, s21, s1
	global_load_dword v3, v[0:1], off
	global_load_dword v0, v[0:1], off offset:16
	global_load_dword v1, v97, s[0:1] offset:16
	s_mov_b32 s0, 0xbfb8aa3b
	v_readlane_b32 s30, v248, 2
	s_mov_b32 s24, s69
	s_mov_b32 s27, s68
	s_mov_b64 s[16:17], s[82:83]
	s_mov_b32 s25, 0x85000
	s_mov_b32 s23, 0x59000
	s_mov_b32 s22, 0x2d000
	s_mov_b32 s19, 0x2c000
	s_movk_i32 s18, 0x1600
	s_movk_i32 s29, 0x47ff
	s_mov_b32 s28, 0x4800000
	v_readlane_b32 s31, v248, 3
	s_mov_b32 s20, 0x58000
	s_mov_b32 s21, 0x84000
	v_readlane_b32 s26, v251, 30
	s_waitcnt vmcnt(2)
	v_add_f32_e32 v3, v3, v4
	v_add_u32_e32 v4, 0x11000, v2
	ds_write_b32 v4, v3
	s_waitcnt vmcnt(0)
	v_add_f32_e32 v1, v0, v1
	v_min_f32_e32 v0, 0, v1
	v_mul_f32_e64 v1, |v1|, s0
	v_exp_f32_e32 v1, v1
	s_mov_b32 s0, 0x3f2aaaab
	v_add_f32_e32 v3, 1.0, v1
	v_add_f32_e32 v4, -1.0, v3
	v_sub_f32_e32 v5, v4, v3
	v_add_f32_e32 v5, 1.0, v5
	v_sub_f32_e32 v4, v1, v4
	v_add_f32_e32 v6, v4, v5
	v_frexp_mant_f32_e32 v4, v3
	v_cmp_gt_f32_e64 s[0:1], s0, v4
	v_cvt_f64_f32_e32 v[4:5], v3
	v_frexp_exp_i32_f64_e32 v4, v[4:5]
	v_subbrev_co_u32_e64 v4, s[0:1], 0, v4, s[0:1]
	v_sub_u32_e32 v5, 0, v4
	v_ldexp_f32 v3, v3, v5
	v_ldexp_f32 v5, v6, v5
	v_add_f32_e32 v6, -1.0, v3
	v_add_f32_e32 v7, 1.0, v6
	v_sub_f32_e32 v7, v3, v7
	v_add_f32_e32 v7, v5, v7
	v_add_f32_e32 v8, v6, v7
	v_sub_f32_e32 v6, v8, v6
	v_sub_f32_e32 v6, v7, v6
	v_add_f32_e32 v7, 1.0, v3
	v_add_f32_e32 v9, -1.0, v7
	v_sub_f32_e32 v3, v3, v9
	v_add_f32_e32 v3, v5, v3
	v_add_f32_e32 v5, v7, v3
	v_sub_f32_e32 v7, v5, v7
	v_sub_f32_e32 v3, v3, v7
	v_rcp_f32_e32 v7, v5
	v_cvt_f32_i32_e32 v4, v4
	s_mov_b32 s0, 0x3f317218
	v_mul_f32_e32 v9, v8, v7
	v_mul_f32_e32 v10, v5, v9
	v_fma_f32 v11, v9, v5, -v10
	v_fmac_f32_e32 v11, v9, v3
	v_add_f32_e32 v12, v10, v11
	v_sub_f32_e32 v13, v8, v12
	v_sub_f32_e32 v8, v8, v13
	v_sub_f32_e32 v10, v12, v10
	v_sub_f32_e32 v8, v8, v12
	v_add_f32_e32 v6, v6, v8
	v_sub_f32_e32 v8, v10, v11
	v_add_f32_e32 v6, v8, v6
	v_add_f32_e32 v8, v13, v6
	v_mul_f32_e32 v10, v7, v8
	v_mul_f32_e32 v11, v5, v10
	v_fma_f32 v5, v10, v5, -v11
	v_fmac_f32_e32 v5, v10, v3
	v_sub_f32_e32 v3, v13, v8
	v_add_f32_e32 v3, v6, v3
	v_add_f32_e32 v6, v11, v5
	v_sub_f32_e32 v12, v8, v6
	v_sub_f32_e32 v8, v8, v12
	v_sub_f32_e32 v11, v6, v11
	v_sub_f32_e32 v6, v8, v6
	v_add_f32_e32 v3, v3, v6
	v_sub_f32_e32 v5, v11, v5
	v_add_f32_e32 v3, v5, v3
	v_add_f32_e32 v5, v9, v10
	v_add_f32_e32 v3, v12, v3
	v_sub_f32_e32 v6, v5, v9
	v_mul_f32_e32 v3, v7, v3
	v_sub_f32_e32 v6, v10, v6
	v_add_f32_e32 v3, v6, v3
	v_mul_f32_e32 v9, 0x3f317218, v4
	v_add_f32_e32 v6, v5, v3
	v_fma_f32 v10, v4, s0, -v9
	v_mul_f32_e32 v7, v6, v6
	v_fmac_f32_e32 v10, 0xb102e308, v4
	v_sub_f32_e32 v4, v6, v5
	v_fmamk_f32 v8, v7, 0x3e9b6dac, v191
	v_sub_f32_e32 v3, v3, v4
	v_add_f32_e32 v4, v9, v10
	v_fmaak_f32 v8, v7, v8, 0x3f2aaada
	v_sub_f32_e32 v5, v4, v9
	v_ldexp_f32 v9, v6, 1
	v_mul_f32_e32 v6, v6, v7
	v_mul_f32_e32 v6, v6, v8
	v_add_f32_e32 v7, v9, v6
	v_sub_f32_e32 v8, v7, v9
	v_ldexp_f32 v3, v3, 1
	v_sub_f32_e32 v6, v6, v8
	v_add_f32_e32 v3, v3, v6
	v_add_f32_e32 v6, v7, v3
	v_sub_f32_e32 v7, v6, v7
	v_sub_f32_e32 v3, v3, v7
	v_add_f32_e32 v7, v4, v6
	v_sub_f32_e32 v8, v7, v4
	v_sub_f32_e32 v9, v7, v8
	v_sub_f32_e32 v5, v10, v5
	v_sub_f32_e32 v4, v4, v9
	v_sub_f32_e32 v6, v6, v8
	v_add_f32_e32 v4, v6, v4
	v_add_f32_e32 v6, v5, v3
	v_sub_f32_e32 v8, v6, v5
	v_sub_f32_e32 v9, v6, v8
	v_sub_f32_e32 v5, v5, v9
	v_sub_f32_e32 v3, v3, v8
	v_add_f32_e32 v4, v6, v4
	v_add_f32_e32 v3, v3, v5
	v_add_f32_e32 v5, v7, v4
	v_sub_f32_e32 v6, v5, v7
	v_sub_f32_e32 v4, v4, v6
	v_add_f32_e32 v3, v3, v4
	s_mov_b32 s0, 0x7f800000
	v_add_f32_e32 v3, v5, v3
	v_cmp_neq_f32_e64 s[0:1], s0, v1
	s_nop 1
	v_cndmask_b32_e64 v3, v199, v3, s[0:1]
	v_cmp_ngt_f32_e64 s[0:1], -1.0, v1
	s_nop 1
	v_cndmask_b32_e64 v3, v200, v3, s[0:1]
	v_cmp_neq_f32_e64 s[0:1], -1.0, v1
	s_nop 1
	v_cndmask_b32_e64 v3, v201, v3, s[0:1]
	s_mov_b32 s0, 0x33800000
	v_cmp_lt_f32_e64 s[38:39], |v1|, s0
	s_nop 1
	v_cndmask_b32_e64 v1, v3, v1, s[38:39]
	v_sub_f32_e32 v0, v0, v1
	v_add_u32_e32 v1, 0x11200, v2
	ds_write_b32 v1, v0

.LBB0_703:
	v_ashrrev_i32_e32 v4, 31, v1
	v_lshrrev_b32_e32 v4, 29, v4
	v_add_u32_e32 v4, v1, v4
	v_ashrrev_i32_e32 v8, 3, v4
	v_ashrrev_i32_e32 v9, 31, v8
	v_lshlrev_b32_e32 v6, 6, v8
	v_lshlrev_b64 v[4:5], 10, v[8:9]
	v_sub_u32_e32 v6, v3, v6
	v_lshl_add_u64 v[4:5], s[2:3], 0, v[4:5]
	v_ashrrev_i32_e32 v7, 31, v6
	v_lshl_add_u64 v[4:5], v[6:7], 1, v[4:5]
	global_load_dwordx4 v[10:13], v[4:5], off
	v_add_u32_e32 v9, 0x100, v1
	v_cmp_lt_i32_e32 vcc, s80, v1
	s_or_b64 s[6:7], vcc, s[6:7]
	v_mov_b32_e32 v1, v9
	v_lshl_add_u32 v8, v8, 4, v2
	v_add_u32_e32 v2, 0x1000, v2
	v_add_u32_e32 v3, 0x800, v3
	v_mov_b32_e32 v22, v8
	v_ashrrev_i32_e32 v4, 31, v1
	v_lshrrev_b32_e32 v4, 29, v4
	v_add_u32_e32 v4, v1, v4
	v_ashrrev_i32_e32 v8, 3, v4
	v_ashrrev_i32_e32 v9, 31, v8
	v_lshlrev_b32_e32 v6, 6, v8
	v_lshlrev_b64 v[4:5], 10, v[8:9]
	v_sub_u32_e32 v6, v3, v6
	v_lshl_add_u64 v[4:5], s[2:3], 0, v[4:5]
	v_ashrrev_i32_e32 v7, 31, v6
	v_lshl_add_u64 v[4:5], v[6:7], 1, v[4:5]
	global_load_dwordx4 v[14:17], v[4:5], off
	v_add_u32_e32 v9, 0x100, v1
	v_cmp_lt_i32_e32 vcc, s80, v1
	s_or_b64 s[6:7], vcc, s[6:7]
	v_mov_b32_e32 v1, v9
	v_lshl_add_u32 v8, v8, 4, v2
	v_add_u32_e32 v2, 0x1000, v2
	v_add_u32_e32 v3, 0x800, v3
	v_mov_b32_e32 v23, v8
	v_ashrrev_i32_e32 v4, 31, v1
	v_lshrrev_b32_e32 v4, 29, v4
	v_add_u32_e32 v4, v1, v4
	v_ashrrev_i32_e32 v8, 3, v4
	v_ashrrev_i32_e32 v9, 31, v8
	v_lshlrev_b32_e32 v6, 6, v8
	v_lshlrev_b64 v[4:5], 10, v[8:9]
	v_sub_u32_e32 v6, v3, v6
	v_lshl_add_u64 v[4:5], s[2:3], 0, v[4:5]
	v_ashrrev_i32_e32 v7, 31, v6
	v_lshl_add_u64 v[4:5], v[6:7], 1, v[4:5]
	global_load_dwordx4 v[18:21], v[4:5], off
	v_add_u32_e32 v9, 0x100, v1
	v_cmp_lt_i32_e32 vcc, s80, v1
	s_or_b64 s[6:7], vcc, s[6:7]
	v_mov_b32_e32 v1, v9
	v_lshl_add_u32 v8, v8, 4, v2
	v_add_u32_e32 v2, 0x1000, v2
	v_add_u32_e32 v3, 0x800, v3
	v_mov_b32_e32 v24, v8
	v_ashrrev_i32_e32 v4, 31, v1
	v_lshrrev_b32_e32 v4, 29, v4
	v_add_u32_e32 v4, v1, v4
	v_ashrrev_i32_e32 v8, 3, v4
	v_ashrrev_i32_e32 v9, 31, v8
	v_lshlrev_b32_e32 v6, 6, v8
	v_lshlrev_b64 v[4:5], 10, v[8:9]
	v_sub_u32_e32 v6, v3, v6
	v_lshl_add_u64 v[4:5], s[2:3], 0, v[4:5]
	v_ashrrev_i32_e32 v7, 31, v6
	v_lshl_add_u64 v[4:5], v[6:7], 1, v[4:5]
	global_load_dwordx4 v[4:7], v[4:5], off
	v_cmp_lt_i32_e32 vcc, s80, v1
	s_or_b64 s[6:7], vcc, s[6:7]
	v_lshl_add_u32 v8, v8, 4, v2
	s_waitcnt vmcnt(3)
	ds_write_b128 v22, v[10:13]
	s_waitcnt vmcnt(2)
	ds_write_b128 v23, v[14:17]
	s_waitcnt vmcnt(1)
	ds_write_b128 v24, v[18:21]
	s_waitcnt vmcnt(0)
	ds_write_b128 v8, v[4:7]
.LBB0_704:
	s_or_b64 exec, exec, s[0:1]
	s_or_b32 s0, s38, s45
	s_mov_b32 s1, s5
	s_nop 0
	s_lshl_b64 s[0:1], s[0:1], 2
	v_readlane_b32 s28, v251, 32
	v_readlane_b32 s29, v251, 33
	s_add_u32 s0, s28, s0
	s_addc_u32 s1, s29, s1
	s_waitcnt lgkmcnt(0)
	s_barrier
	global_load_dword v146, v97, s[0:1]
	v_ashrrev_i32_e32 v1, 6, v0
	s_lshl_b32 s43, s13, 8
	v_lshlrev_b32_e32 v2, 5, v1
	v_and_b32_e32 v157, 31, v0
	s_addk_i32 s43, 0x3e80
	v_or_b32_e32 v3, v2, v157
	s_movk_i32 s7, 0x90
	v_lshrrev_b32_e32 v4, 1, v0
	s_cmp_lt_u32 s49, 16
	v_mul_lo_u32 v3, v3, s7
	v_and_b32_e32 v4, 16, v4
	s_cselect_b64 s[0:1], -1, 0
	s_lshl_b32 s2, s38, 4
	v_add3_u32 v3, 0, v3, v4
	s_and_b32 s2, s2, 64
	ds_read_b128 v[98:101], v3 offset:35840
	ds_read_b128 v[102:105], v3 offset:35872
	ds_read_b128 v[106:109], v3 offset:35904
	ds_read_b128 v[110:113], v3 offset:35936
	s_add_i32 s49, s49, -1
	s_lshl_b32 s50, s13, 11
	s_lshl_b32 s3, s2, 1
	v_readlane_b32 s6, v249, 23
	v_mul_u32_u24_e32 v3, 0x90, v157
	s_add_u32 s51, s6, s3
	v_readlane_b32 s3, v249, 24
	v_add3_u32 v158, 0, v3, v4
	v_lshrrev_b32_e32 v3, 3, v0
	v_lshlrev_b32_e32 v0, 3, v0
	s_addc_u32 s52, s3, 0
	v_and_b32_e32 v0, 0xf8, v0
	s_movk_i32 s3, 0x2200
	v_lshlrev_b32_e32 v5, 7, v157
	v_and_or_b32 v159, v3, 4, v2
	v_subrev_u32_e32 v2, s12, v157
	v_add_u32_e32 v16, 0, v0
	v_mul_lo_u32 v0, v1, s3
	v_mul_u32_u24_e32 v1, 0x88, v157
	v_add_u32_e32 v183, 0x80, v2
	v_mad_u32_u24 v2, v157, s7, v5
	s_add_i32 s3, 0, 0x4800
	v_mul_lo_u32 v17, v159, s87
	v_add3_u32 v184, v2, v4, s3
	v_or_b32_e32 v0, v0, v4
	v_lshlrev_b32_e32 v1, 1, v1
	v_readlane_b32 s3, v249, 52
	v_mov_b32_e32 v14, v97
	v_mov_b32_e32 v15, v97
	v_add3_u32 v185, v0, v1, s3
	v_mov_b32_e32 v96, v97
	v_mov_b32_e32 v0, v97
	v_mov_b32_e32 v1, v97
	v_mov_b32_e32 v2, v97
	v_mov_b32_e32 v3, v97
	v_mov_b32_e32 v4, v97
	v_mov_b32_e32 v5, v97
	v_mov_b32_e32 v6, v97
	v_mov_b32_e32 v7, v97
	v_mov_b32_e32 v8, v97
	v_mov_b32_e32 v9, v97
	v_mov_b32_e32 v10, v97
	v_mov_b32_e32 v11, v97
	v_mov_b32_e32 v12, v97
	v_mov_b32_e32 v13, v97
	v_add_u32_e32 v186, v16, v17
	v_mov_b64_e32 v[30:31], v[14:15]
	v_readlane_b32 s30, v248, 2
	v_or_b32_e32 v161, 1, v159
	v_or_b32_e32 v169, 2, v159
	v_or_b32_e32 v170, 3, v159
	v_or_b32_e32 v171, 8, v159
	v_or_b32_e32 v172, 9, v159
	v_or_b32_e32 v173, 10, v159
	v_or_b32_e32 v174, 11, v159
	v_or_b32_e32 v175, 16, v159
	v_or_b32_e32 v176, 17, v159
	v_or_b32_e32 v177, 18, v159
	v_or_b32_e32 v178, 19, v159
	v_or_b32_e32 v179, 24, v159
	v_or_b32_e32 v180, 25, v159
	v_or_b32_e32 v181, 26, v159
	v_or_b32_e32 v182, 27, v159
	s_mov_b32 s53, 0
	s_lshl_b32 s54, s2, 1
	s_waitcnt vmcnt(0)
	v_mov_b32_e32 v145, v146
	v_mov_b32_e32 v144, v146
	v_mov_b32_e32 v143, v146
	v_mov_b32_e32 v142, v146
	v_mov_b32_e32 v141, v146
	v_mov_b32_e32 v140, v146
	v_mov_b32_e32 v139, v146
	v_mov_b32_e32 v138, v146
	v_mov_b32_e32 v137, v146
	v_mov_b32_e32 v136, v146
	v_mov_b32_e32 v135, v146
	v_mov_b32_e32 v134, v146
	v_mov_b32_e32 v133, v146
	v_mov_b32_e32 v132, v146
	v_mov_b32_e32 v131, v146
	v_mov_b32_e32 v130, v146
	v_mov_b64_e32 v[28:29], v[12:13]
	v_mov_b64_e32 v[26:27], v[10:11]
	v_mov_b64_e32 v[24:25], v[8:9]
	v_mov_b64_e32 v[22:23], v[6:7]
	v_mov_b64_e32 v[20:21], v[4:5]
	v_mov_b64_e32 v[18:19], v[2:3]
	v_mov_b64_e32 v[16:17], v[0:1]
	v_mov_b64_e32 v[114:115], v[96:97]
	v_mov_b64_e32 v[116:117], v[96:97]
	v_mov_b64_e32 v[118:119], v[96:97]
	v_mov_b64_e32 v[120:121], v[96:97]
	v_mov_b64_e32 v[122:123], v[96:97]
	v_mov_b64_e32 v[124:125], v[96:97]
	v_mov_b64_e32 v[126:127], v[96:97]
	v_mov_b64_e32 v[128:129], v[96:97]
	v_readlane_b32 s31, v248, 3
	s_mov_b32 s28, 0x4800000
	s_movk_i32 s29, 0x47ff
	s_movk_i32 s18, 0x1600
	s_mov_b32 s19, 0x2c000
	s_mov_b32 s20, 0x58000
	s_mov_b32 s21, 0x84000
	s_mov_b32 s22, 0x2d000
	s_mov_b32 s23, 0x59000
	s_mov_b32 s25, 0x85000
	s_mov_b64 s[16:17], s[82:83]
	s_mov_b32 s27, s68
	s_mov_b32 s24, s69
	v_readlane_b32 s26, v251, 30
	s_cmp_gt_u32 s53, 2
	s_cselect_b64 s[2:3], -1, 0
	s_and_b64 vcc, exec, s[2:3]
	s_cbranch_vccz .LBB0_706

.LBB0_717:
	s_or_b64 exec, exec, s[6:7]
	ds_write_b128 v70, v[52:55]
	ds_write_b128 v70, v[56:59] offset:4608
	ds_write_b128 v70, v[60:63] offset:9216
	ds_write_b128 v70, v[64:67] offset:13824
	s_waitcnt lgkmcnt(0)
	s_barrier
	ds_read_b128 v[32:35], v158
	ds_read_b128 v[36:39], v158 offset:4608
	s_waitcnt lgkmcnt(1)
	v_mfma_f32_32x32x16_bf16 v[80:95], v[98:101], v[32:35], 0
	s_waitcnt lgkmcnt(0)
	v_mfma_f32_32x32x16_bf16 v[48:63], v[98:101], v[36:39], 0
	ds_read_b128 v[32:35], v158 offset:9216
	ds_read_b128 v[36:39], v158 offset:13824
	s_waitcnt lgkmcnt(1)
	v_mfma_f32_32x32x16_bf16 v[64:79], v[98:101], v[32:35], 0
	s_waitcnt lgkmcnt(0)
	v_mfma_f32_32x32x16_bf16 v[32:47], v[98:101], v[36:39], 0
	ds_read_b128 v[148:151], v158 offset:32
	s_waitcnt lgkmcnt(0)
	v_mfma_f32_32x32x16_bf16 v[80:95], v[102:105], v[148:151], v[80:95]
	ds_read_b128 v[148:151], v158 offset:4640
	s_waitcnt lgkmcnt(0)
	v_mfma_f32_32x32x16_bf16 v[48:63], v[102:105], v[148:151], v[48:63]
	ds_read_b128 v[148:151], v158 offset:9248
	s_waitcnt lgkmcnt(0)
	v_mfma_f32_32x32x16_bf16 v[64:79], v[102:105], v[148:151], v[64:79]
	ds_read_b128 v[148:151], v158 offset:13856
	s_waitcnt lgkmcnt(0)
	v_mfma_f32_32x32x16_bf16 v[32:47], v[102:105], v[148:151], v[32:47]
	ds_read_b128 v[148:151], v158 offset:64
	s_waitcnt lgkmcnt(0)
	v_mfma_f32_32x32x16_bf16 v[80:95], v[106:109], v[148:151], v[80:95]
	ds_read_b128 v[148:151], v158 offset:4672
	s_waitcnt lgkmcnt(0)
	v_mfma_f32_32x32x16_bf16 v[48:63], v[106:109], v[148:151], v[48:63]
	ds_read_b128 v[148:151], v158 offset:9280
	s_waitcnt lgkmcnt(0)
	v_mfma_f32_32x32x16_bf16 v[64:79], v[106:109], v[148:151], v[64:79]
	ds_read_b128 v[148:151], v158 offset:13888
	s_waitcnt lgkmcnt(0)
	v_mfma_f32_32x32x16_bf16 v[32:47], v[106:109], v[148:151], v[32:47]
	ds_read_b128 v[148:151], v158 offset:96
	s_waitcnt lgkmcnt(0)
	v_mfma_f32_32x32x16_bf16 v[80:95], v[110:113], v[148:151], v[80:95]
	ds_read_b128 v[148:151], v158 offset:4704
	s_waitcnt lgkmcnt(0)
	v_mfma_f32_32x32x16_bf16 v[48:63], v[110:113], v[148:151], v[48:63]
	ds_read_b128 v[148:151], v158 offset:9312
	s_waitcnt lgkmcnt(0)
	v_mfma_f32_32x32x16_bf16 v[64:79], v[110:113], v[148:151], v[64:79]
	ds_read_b128 v[148:151], v158 offset:13920
	s_waitcnt lgkmcnt(0)
	v_mfma_f32_32x32x16_bf16 v[32:47], v[110:113], v[148:151], v[32:47]
	s_cmp_eq_u32 s53, 1
	s_cbranch_scc1 .Latt_nm
	s_cmp_gt_u32 s53, 2
	s_cbranch_scc1 .Latt_nm
	s_add_i32 s6, s53, s49
	v_mbcnt_hi_u32_b32 v148, -1, v195
	v_lshl_add_u32 v96, s6, 7, v183
	v_and_b32_e32 v147, 64, v148
	v_add_u32_e32 v149, 64, v147
	v_sub_u32_e32 v147, v96, v159
	v_cmp_gt_u32_e32 vcc, s58, v147
	s_or_b64 vcc, s[2:3], vcc
	v_add_u32_e32 v150, 32, v147
	v_cndmask_b32_e32 v80, v204, v80, vcc
	v_cmp_gt_u32_e32 vcc, s58, v150
	s_or_b64 vcc, s[2:3], vcc
	v_add_u32_e32 v151, 64, v147
	v_cndmask_b32_e32 v48, v204, v48, vcc
	v_cmp_gt_u32_e32 vcc, s58, v151
	s_or_b64 vcc, s[2:3], vcc
	v_add_u32_e32 v147, 0x60, v147
	v_cndmask_b32_e32 v64, v204, v64, vcc
	v_cmp_gt_u32_e32 vcc, s58, v147
	s_or_b64 vcc, s[2:3], vcc
	v_xor_b32_e32 v147, 16, v148
	v_cndmask_b32_e32 v32, v204, v32, vcc
	v_cmp_lt_i32_e32 vcc, v147, v149
	v_max3_f32 v150, v80, s59, v48
	v_max3_f32 v150, v150, v64, v32
	v_mov_b32_e32 v151, v150
	v_mov_b32_e32 v255, v150
	s_nop 1
	v_permlane16_swap_b32_e32 v151, v255
	v_add_u32_e32 v187, 0x8800, v186
	v_add_u32_e32 v215, 0x9000, v186
	v_max_f32_e32 v150, v151, v255
	v_xor_b32_e32 v151, 8, v148
	v_cmp_lt_i32_e32 vcc, v151, v149
	v_max_f32_dpp v150, v150, v150 row_ror:8 row_mask:0xf bank_mask:0xf
	v_xor_b32_e32 v151, 4, v148
	v_cmp_lt_i32_e32 vcc, v151, v149
	s_nop 1
	v_cndmask_b32_e32 v151, v148, v151, vcc
	s_nop 0
	v_mov_b32_dpp v151, v150 row_shl:4 row_mask:0xf bank_mask:0x5
	v_mov_b32_dpp v151, v150 row_shr:4 row_mask:0xf bank_mask:0xa
	v_max_f32_e32 v150, v150, v151
	v_xor_b32_e32 v151, 2, v148
	v_cmp_lt_i32_e32 vcc, v151, v149
	v_max_f32_dpp v150, v150, v150 quad_perm:[2,3,0,1] row_mask:0xf bank_mask:0xf
	v_xor_b32_e32 v151, 1, v148
	v_cmp_lt_i32_e32 vcc, v151, v149
	v_sub_u32_e32 v149, v96, v161
	s_nop 0
	v_cndmask_b32_e32 v148, v148, v151, vcc
	v_cmp_gt_u32_e32 vcc, s58, v149
	s_or_b64 vcc, s[2:3], vcc
	s_nop 0
	v_cndmask_b32_e32 v151, v204, v81, vcc
	v_add_u32_e32 v81, 32, v149
	v_cmp_gt_u32_e32 vcc, s58, v81
	s_or_b64 vcc, s[2:3], vcc
	v_add_u32_e32 v81, 64, v149
	v_cndmask_b32_e32 v152, v204, v49, vcc
	v_cmp_gt_u32_e32 vcc, s58, v81
	s_or_b64 vcc, s[2:3], vcc
	v_max3_f32 v49, v151, s59, v152
	v_cndmask_b32_e32 v153, v204, v65, vcc
	v_add_u32_e32 v65, 0x60, v149
	v_cmp_gt_u32_e32 vcc, s58, v65
	s_or_b64 vcc, s[2:3], vcc
	v_mov_b32_dpp v148, v150 quad_perm:[1,0,3,2] row_mask:0xf bank_mask:0xf
	v_cndmask_b32_e32 v154, v204, v33, vcc
	v_max3_f32 v33, v49, v153, v154
	v_mov_b32_e32 v49, v33
	v_mov_b32_e32 v255, v33
	s_nop 1
	v_permlane16_swap_b32_e32 v49, v255
	v_max3_f32 v207, v130, v150, v148
	v_sub_f32_e32 v48, v48, v207
	v_mul_f32_e32 v48, 0x3fb8aa3b, v48
	v_max_f32_e32 v49, v49, v255
	v_sub_f32_e32 v33, v80, v207
	v_sub_f32_e32 v32, v32, v207
	v_mul_f32_e32 v32, 0x3fb8aa3b, v32
	v_sub_f32_e32 v130, v130, v207
	v_max_f32_dpp v65, v49, v49 row_ror:8 row_mask:0xf bank_mask:0xf
	s_nop 1
	v_mov_b32_dpp v80, v65 row_shl:4 row_mask:0xf bank_mask:0x5
	v_mov_b32_dpp v80, v65 row_shr:4 row_mask:0xf bank_mask:0xa
	v_exp_f32_e32 v49, v48
	v_sub_f32_e32 v48, v64, v207
	v_mul_f32_e32 v48, 0x3fb8aa3b, v48
	v_exp_f32_e32 v81, v48
	v_max_f32_e32 v64, v80, v80
	v_max_f32_e32 v64, v65, v64
	s_nop 1
	v_mov_b32_dpp v80, v64 quad_perm:[2,3,0,1] row_mask:0xf bank_mask:0xf
	v_exp_f32_e32 v65, v32
	v_mul_f32_e32 v33, 0x3fb8aa3b, v33
	v_exp_f32_e32 v33, v33
	v_max_f32_e32 v32, v80, v80
	v_max_f32_e32 v32, v64, v32
	s_nop 1
	v_mov_b32_dpp v48, v32 quad_perm:[1,0,3,2] row_mask:0xf bank_mask:0xf
	v_mul_f32_e32 v64, 0x3fb8aa3b, v130
	v_exp_f32_e32 v130, v64
	v_cvt_pk_bf16_f32 v148, v33, v49
	v_cvt_pk_bf16_f32 v149, v81, v65
	v_max3_f32 v206, v131, v32, v48
	v_sub_u32_e32 v32, v96, v169
	v_cmp_gt_u32_e32 vcc, s58, v32
	s_or_b64 vcc, s[2:3], vcc
	v_add_u32_e32 v48, 32, v32
	v_cndmask_b32_e32 v82, v204, v82, vcc
	v_cmp_gt_u32_e32 vcc, s58, v48
	s_or_b64 vcc, s[2:3], vcc
	v_add_u32_e32 v64, 64, v32
	v_cndmask_b32_e32 v50, v204, v50, vcc
	v_cmp_gt_u32_e32 vcc, s58, v64
	s_or_b64 vcc, s[2:3], vcc
	v_add_u32_e32 v32, 0x60, v32
	v_cndmask_b32_e32 v66, v204, v66, vcc
	v_cmp_gt_u32_e32 vcc, s58, v32
	s_or_b64 vcc, s[2:3], vcc
	v_max3_f32 v48, v82, s59, v50
	v_cndmask_b32_e32 v34, v204, v34, vcc
	v_max3_f32 v48, v48, v66, v34
	v_mov_b32_e32 v64, v48
	v_mov_b32_e32 v255, v48
	s_nop 1
	v_permlane16_swap_b32_e32 v64, v255
	v_sub_f32_e32 v32, v151, v206
	v_sub_f32_e32 v80, v152, v206
	v_mul_f32_e32 v32, 0x3fb8aa3b, v32
	v_exp_f32_e32 v32, v32
	v_max_f32_e32 v64, v64, v255
	v_mul_f32_e32 v48, 0x3fb8aa3b, v80
	v_sub_f32_e32 v80, v153, v206
	v_mul_f32_e32 v80, 0x3fb8aa3b, v80
	v_exp_f32_e32 v48, v48
	v_max_f32_dpp v150, v64, v64 row_ror:8 row_mask:0xf bank_mask:0xf
	v_sub_f32_e32 v64, v154, v206
	v_sub_u32_e32 v154, v96, v170
	v_cmp_gt_u32_e32 vcc, s58, v154
	s_or_b64 vcc, s[2:3], vcc
	v_mov_b32_dpp v151, v150 row_shl:4 row_mask:0xf bank_mask:0x5
	v_mov_b32_dpp v151, v150 row_shr:4 row_mask:0xf bank_mask:0xa
	v_cndmask_b32_e32 v155, v204, v83, vcc
	v_add_u32_e32 v83, 32, v154
	v_cmp_gt_u32_e32 vcc, s58, v83
	s_or_b64 vcc, s[2:3], vcc
	v_add_u32_e32 v83, 64, v154
	v_cndmask_b32_e32 v156, v204, v51, vcc
	v_cmp_gt_u32_e32 vcc, s58, v83
	s_or_b64 vcc, s[2:3], vcc
	v_max3_f32 v51, v155, s59, v156
	v_cndmask_b32_e32 v160, v204, v67, vcc
	v_add_u32_e32 v67, 0x60, v154
	v_cmp_gt_u32_e32 vcc, s58, v67
	s_or_b64 vcc, s[2:3], vcc
	s_nop 0
	v_cndmask_b32_e32 v154, v204, v35, vcc
	v_max3_f32 v35, v51, v160, v154
	v_max_f32_e32 v152, v150, v151
	v_mov_b32_e32 v51, v35
	v_mov_b32_e32 v255, v35
	s_nop 1
	v_permlane16_swap_b32_e32 v51, v255
	v_mov_b32_dpp v153, v152 quad_perm:[2,3,0,1] row_mask:0xf bank_mask:0xf
	v_mul_f32_e32 v64, 0x3fb8aa3b, v64
	v_exp_f32_e32 v80, v80
	v_exp_f32_e32 v64, v64
	v_max_f32_e32 v51, v51, v255
	v_max_f32_e32 v152, v152, v153
	s_nop 1
	v_mov_b32_dpp v153, v152 quad_perm:[1,0,3,2] row_mask:0xf bank_mask:0xf
	v_cvt_pk_bf16_f32 v150, v32, v48
	v_cvt_pk_bf16_f32 v151, v80, v64
	ds_write2_b64 v187, v[148:149], v[150:151] offset0:128 offset1:162
	v_max3_f32 v189, v132, v152, v153
	v_max_f32_dpp v67, v51, v51 row_ror:8 row_mask:0xf bank_mask:0xf
	v_sub_f32_e32 v35, v82, v189
	s_nop 1
	v_mov_b32_dpp v82, v67 row_shl:4 row_mask:0xf bank_mask:0x5
	v_mov_b32_dpp v82, v67 row_shr:4 row_mask:0xf bank_mask:0xa
	v_sub_f32_e32 v50, v50, v189
	v_mul_f32_e32 v50, 0x3fb8aa3b, v50
	v_exp_f32_e32 v51, v50
	v_sub_f32_e32 v50, v66, v189
	s_waitcnt lgkmcnt(0)
	v_max_f32_e32 v66, v82, v82
	v_max_f32_e32 v66, v67, v66
	s_nop 1
	v_mov_b32_dpp v82, v66 quad_perm:[2,3,0,1] row_mask:0xf bank_mask:0xf
	v_sub_f32_e32 v34, v34, v189
	v_mul_f32_e32 v34, 0x3fb8aa3b, v34
	v_exp_f32_e32 v67, v34
	v_mul_f32_e32 v50, 0x3fb8aa3b, v50
	v_max_f32_e32 v34, v82, v82
	v_max_f32_e32 v34, v66, v34
	v_exp_f32_e32 v83, v50
	s_nop 1
	v_mov_b32_dpp v50, v34 quad_perm:[1,0,3,2] row_mask:0xf bank_mask:0xf
	v_sub_f32_e32 v132, v132, v189
	v_mul_f32_e32 v66, 0x3fb8aa3b, v132
	v_exp_f32_e32 v132, v66
	v_mul_f32_e32 v35, 0x3fb8aa3b, v35
	v_max3_f32 v188, v133, v34, v50
	v_sub_u32_e32 v34, v96, v171
	v_cmp_gt_u32_e32 vcc, s58, v34
	s_or_b64 vcc, s[2:3], vcc
	v_add_u32_e32 v50, 32, v34
	v_cndmask_b32_e32 v84, v204, v84, vcc
	v_cmp_gt_u32_e32 vcc, s58, v50
	s_or_b64 vcc, s[2:3], vcc
	v_add_u32_e32 v66, 64, v34
	v_cndmask_b32_e32 v52, v204, v52, vcc
	v_cmp_gt_u32_e32 vcc, s58, v66
	s_or_b64 vcc, s[2:3], vcc
	v_add_u32_e32 v34, 0x60, v34
	v_cndmask_b32_e32 v68, v204, v68, vcc
	v_cmp_gt_u32_e32 vcc, s58, v34
	s_or_b64 vcc, s[2:3], vcc
	v_max3_f32 v50, v84, s59, v52
	v_cndmask_b32_e32 v150, v204, v36, vcc
	v_max3_f32 v34, v50, v68, v150
	v_mov_b32_e32 v36, v34
	v_mov_b32_e32 v255, v34
	s_nop 1
	v_permlane16_swap_b32_e32 v36, v255
	v_sub_f32_e32 v151, v154, v188
	v_sub_f32_e32 v50, v133, v188
	v_mul_f32_e32 v133, 0x3fb8aa3b, v50
	v_sub_f32_e32 v50, v155, v188
	v_max_f32_e32 v36, v36, v255
	s_nop 1
	v_mov_b32_dpp v66, v36 row_ror:8 row_mask:0xf bank_mask:0xf
	v_mul_f32_e32 v50, 0x3fb8aa3b, v50
	v_exp_f32_e32 v34, v50
	v_sub_f32_e32 v50, v156, v188
	v_sub_f32_e32 v82, v160, v188
	v_max_f32_e32 v36, v36, v66
	s_nop 1
	v_mov_b32_dpp v66, v36 row_shl:4 row_mask:0xf bank_mask:0x5
	v_mov_b32_dpp v66, v36 row_shr:4 row_mask:0xf bank_mask:0xa
	v_mul_f32_e32 v50, 0x3fb8aa3b, v50
	v_mul_f32_e32 v82, 0x3fb8aa3b, v82
	v_exp_f32_e32 v35, v35
	v_exp_f32_e32 v50, v50
	v_max_f32_e32 v152, v36, v66
	s_nop 1
	v_mov_b32_dpp v153, v152 quad_perm:[2,3,0,1] row_mask:0xf bank_mask:0xf
	v_mul_f32_e32 v36, 0x3fb8aa3b, v151
	v_exp_f32_e32 v82, v82
	v_exp_f32_e32 v66, v36
	v_cvt_pk_bf16_f32 v148, v35, v51
	v_max_f32_e32 v151, v153, v153
	v_sub_u32_e32 v153, v96, v172
	v_cmp_gt_u32_e32 vcc, s58, v153
	s_or_b64 vcc, s[2:3], vcc
	v_cvt_pk_bf16_f32 v149, v83, v67
	v_cndmask_b32_e32 v154, v204, v85, vcc
	v_add_u32_e32 v85, 32, v153
	v_cmp_gt_u32_e32 vcc, s58, v85
	s_or_b64 vcc, s[2:3], vcc
	v_add_u32_e32 v85, 64, v153
	v_cndmask_b32_e32 v155, v204, v53, vcc
	v_cmp_gt_u32_e32 vcc, s58, v85
	s_or_b64 vcc, s[2:3], vcc
	v_max3_f32 v53, v154, s59, v155
	v_cndmask_b32_e32 v156, v204, v69, vcc
	v_add_u32_e32 v69, 0x60, v153
	v_cmp_gt_u32_e32 vcc, s58, v69
	s_or_b64 vcc, s[2:3], vcc
	v_cvt_pk_bf16_f32 v36, v34, v50
	v_cndmask_b32_e32 v153, v204, v37, vcc
	v_max3_f32 v53, v53, v156, v153
	v_mov_b32_e32 v69, v53
	v_mov_b32_e32 v255, v53
	s_nop 1
	v_permlane16_swap_b32_e32 v69, v255
	s_nop 1
	v_mov_b32_dpp v69, v255 quad_perm:[0,1,2,3] row_mask:0x5 bank_mask:0xf
	v_cvt_pk_bf16_f32 v37, v82, v66
	ds_write2_b64 v187, v[148:149], v[36:37] offset0:196 offset1:230
	v_max_f32_e32 v151, v152, v151
	s_nop 1
	v_mov_b32_dpp v152, v151 quad_perm:[1,0,3,2] row_mask:0xf bank_mask:0xf
	v_max_f32_e32 v37, v69, v69
	v_max_f32_e32 v53, v53, v37
	v_sub_f32_e32 v131, v131, v206
	s_waitcnt lgkmcnt(0)
	v_max3_f32 v187, v134, v151, v152
	v_sub_f32_e32 v37, v84, v187
	v_sub_f32_e32 v52, v52, v187
	v_max_f32_dpp v69, v53, v53 row_ror:8 row_mask:0xf bank_mask:0xf
	s_nop 1
	v_mov_b32_dpp v84, v69 row_shl:4 row_mask:0xf bank_mask:0x5
	v_mov_b32_dpp v84, v69 row_shr:4 row_mask:0xf bank_mask:0xa
	v_mul_f32_e32 v52, 0x3fb8aa3b, v52
	v_exp_f32_e32 v53, v52
	v_sub_f32_e32 v52, v68, v187
	v_mul_f32_e32 v52, 0x3fb8aa3b, v52
	v_max_f32_e32 v68, v84, v84
	v_max_f32_e32 v68, v69, v68
	s_nop 1
	v_mov_b32_dpp v84, v68 quad_perm:[2,3,0,1] row_mask:0xf bank_mask:0xf
	v_exp_f32_e32 v85, v52
	v_sub_f32_e32 v52, v150, v187
	v_mul_f32_e32 v52, 0x3fb8aa3b, v52
	v_exp_f32_e32 v69, v52
	v_max_f32_e32 v52, v84, v84
	v_max_f32_e32 v52, v68, v52
	s_nop 1
	v_mov_b32_dpp v68, v52 quad_perm:[1,0,3,2] row_mask:0xf bank_mask:0xf
	v_sub_f32_e32 v36, v134, v187
	v_mul_f32_e32 v36, 0x3fb8aa3b, v36
	v_exp_f32_e32 v134, v36
	v_sub_u32_e32 v36, v96, v173
	v_cmp_gt_u32_e32 vcc, s58, v36
	v_max3_f32 v160, v135, v52, v68
	s_or_b64 vcc, s[2:3], vcc
	v_add_u32_e32 v52, 32, v36
	v_cndmask_b32_e32 v86, v204, v86, vcc
	v_cmp_gt_u32_e32 vcc, s58, v52
	s_or_b64 vcc, s[2:3], vcc
	v_add_u32_e32 v68, 64, v36
	v_cndmask_b32_e32 v54, v204, v54, vcc
	v_cmp_gt_u32_e32 vcc, s58, v68
	s_or_b64 vcc, s[2:3], vcc
	v_add_u32_e32 v36, 0x60, v36
	v_cndmask_b32_e32 v70, v204, v70, vcc
	v_cmp_gt_u32_e32 vcc, s58, v36
	s_or_b64 vcc, s[2:3], vcc
	v_max3_f32 v52, v86, s59, v54
	v_cndmask_b32_e32 v38, v204, v38, vcc
	v_max3_f32 v52, v52, v70, v38
	v_mov_b32_e32 v68, v52
	v_mov_b32_e32 v255, v52
	s_nop 1
	v_permlane16_swap_b32_e32 v68, v255
	v_sub_f32_e32 v36, v154, v160
	v_sub_u32_e32 v154, v96, v174
	v_cmp_gt_u32_e32 vcc, s58, v154
	s_or_b64 vcc, s[2:3], vcc
	v_max_f32_e32 v68, v68, v255
	v_cndmask_b32_e32 v212, v204, v87, vcc
	v_add_u32_e32 v87, 32, v154
	v_cmp_gt_u32_e32 vcc, s58, v87
	s_or_b64 vcc, s[2:3], vcc
	v_add_u32_e32 v87, 64, v154
	v_max_f32_dpp v150, v68, v68 row_ror:8 row_mask:0xf bank_mask:0xf
	v_cndmask_b32_e32 v213, v204, v55, vcc
	v_cmp_gt_u32_e32 vcc, s58, v87
	v_mov_b32_dpp v151, v150 row_shl:4 row_mask:0xf bank_mask:0x5
	v_mov_b32_dpp v151, v150 row_shr:4 row_mask:0xf bank_mask:0xa
	s_or_b64 vcc, s[2:3], vcc
	v_cndmask_b32_e32 v214, v204, v71, vcc
	v_add_u32_e32 v71, 0x60, v154
	v_cmp_gt_u32_e32 vcc, s58, v71
	s_or_b64 vcc, s[2:3], vcc
	v_max3_f32 v55, v212, s59, v213
	v_cndmask_b32_e32 v154, v204, v39, vcc
	v_max3_f32 v39, v55, v214, v154
	v_max_f32_e32 v152, v150, v151
	v_mov_b32_e32 v55, v39
	v_mov_b32_e32 v255, v39
	s_nop 1
	v_permlane16_swap_b32_e32 v55, v255
	v_sub_f32_e32 v68, v153, v160
	v_mov_b32_dpp v153, v152 quad_perm:[2,3,0,1] row_mask:0xf bank_mask:0xf
	v_sub_f32_e32 v84, v155, v160
	v_mul_f32_e32 v52, 0x3fb8aa3b, v84
	v_max_f32_e32 v55, v55, v255
	v_max_f32_e32 v152, v152, v153
	s_nop 0
	s_nop 1
	v_mov_b32_dpp v153, v152 quad_perm:[1,0,3,2] row_mask:0xf bank_mask:0xf
	v_sub_f32_e32 v84, v156, v160
	v_mul_f32_e32 v37, 0x3fb8aa3b, v37
	v_mul_f32_e32 v36, 0x3fb8aa3b, v36
	v_max3_f32 v156, v136, v152, v153
	v_max_f32_dpp v71, v55, v55 row_ror:8 row_mask:0xf bank_mask:0xf
	v_sub_f32_e32 v39, v86, v156
	s_nop 1
	v_mov_b32_dpp v86, v71 row_shl:4 row_mask:0xf bank_mask:0x5
	v_mov_b32_dpp v86, v71 row_shr:4 row_mask:0xf bank_mask:0xa
	v_sub_f32_e32 v54, v54, v156
	v_mul_f32_e32 v54, 0x3fb8aa3b, v54
	v_exp_f32_e32 v55, v54
	v_sub_f32_e32 v54, v70, v156
	v_max_f32_e32 v70, v86, v86
	v_max_f32_e32 v70, v71, v70
	s_nop 1
	v_mov_b32_dpp v86, v70 quad_perm:[2,3,0,1] row_mask:0xf bank_mask:0xf
	v_sub_f32_e32 v38, v38, v156
	v_mul_f32_e32 v38, 0x3fb8aa3b, v38
	v_exp_f32_e32 v71, v38
	v_mul_f32_e32 v54, 0x3fb8aa3b, v54
	v_max_f32_e32 v38, v86, v86
	v_max_f32_e32 v38, v70, v38
	v_exp_f32_e32 v87, v54
	s_nop 1
	v_mov_b32_dpp v54, v38 quad_perm:[1,0,3,2] row_mask:0xf bank_mask:0xf
	v_sub_f32_e32 v136, v136, v156
	v_mul_f32_e32 v84, 0x3fb8aa3b, v84
	v_mul_f32_e32 v68, 0x3fb8aa3b, v68
	v_mul_f32_e32 v70, 0x3fb8aa3b, v136
	v_max3_f32 v155, v137, v38, v54
	v_sub_u32_e32 v38, v96, v175
	v_cmp_gt_u32_e32 vcc, s58, v38
	s_or_b64 vcc, s[2:3], vcc
	v_add_u32_e32 v54, 32, v38
	v_cndmask_b32_e32 v88, v204, v88, vcc
	v_cmp_gt_u32_e32 vcc, s58, v54
	v_exp_f32_e32 v37, v37
	v_exp_f32_e32 v36, v36
	v_exp_f32_e32 v52, v52
	v_exp_f32_e32 v84, v84
	v_exp_f32_e32 v68, v68
	v_exp_f32_e32 v136, v70
	s_or_b64 vcc, s[2:3], vcc
	v_add_u32_e32 v70, 64, v38
	v_cndmask_b32_e32 v56, v204, v56, vcc
	v_cmp_gt_u32_e32 vcc, s58, v70
	s_or_b64 vcc, s[2:3], vcc
	v_add_u32_e32 v38, 0x60, v38
	v_cndmask_b32_e32 v72, v204, v72, vcc
	v_cmp_gt_u32_e32 vcc, s58, v38
	v_cvt_pk_bf16_f32 v148, v37, v53
	v_cvt_pk_bf16_f32 v149, v85, v69
	v_cvt_pk_bf16_f32 v150, v36, v52
	v_cvt_pk_bf16_f32 v151, v84, v68
	s_or_b64 vcc, s[2:3], vcc
	ds_write2_b64 v215, v[148:149], v[150:151] offset0:144 offset1:178
	v_max3_f32 v54, v88, s59, v56
	v_cndmask_b32_e32 v150, v204, v40, vcc
	v_max3_f32 v38, v54, v72, v150
	v_mov_b32_e32 v40, v38
	v_mov_b32_e32 v255, v38
	s_nop 1
	v_permlane16_swap_b32_e32 v40, v255
	v_sub_f32_e32 v151, v154, v155
	v_sub_f32_e32 v54, v137, v155
	v_mul_f32_e32 v137, 0x3fb8aa3b, v54
	v_sub_f32_e32 v54, v212, v155
	s_waitcnt lgkmcnt(0)
	v_max_f32_e32 v40, v40, v255
	s_nop 1
	v_mov_b32_dpp v70, v40 row_ror:8 row_mask:0xf bank_mask:0xf
	v_mul_f32_e32 v54, 0x3fb8aa3b, v54
	v_exp_f32_e32 v38, v54
	v_sub_f32_e32 v54, v213, v155
	v_sub_f32_e32 v86, v214, v155
	v_max_f32_e32 v40, v40, v70
	s_nop 1
	v_mov_b32_dpp v70, v40 row_shl:4 row_mask:0xf bank_mask:0x5
	v_mov_b32_dpp v70, v40 row_shr:4 row_mask:0xf bank_mask:0xa
	v_mul_f32_e32 v39, 0x3fb8aa3b, v39
	v_mul_f32_e32 v54, 0x3fb8aa3b, v54
	v_mul_f32_e32 v86, 0x3fb8aa3b, v86
	v_exp_f32_e32 v39, v39
	v_max_f32_e32 v152, v40, v70
	s_nop 1
	v_mov_b32_dpp v153, v152 quad_perm:[2,3,0,1] row_mask:0xf bank_mask:0xf
	v_mul_f32_e32 v40, 0x3fb8aa3b, v151
	v_exp_f32_e32 v54, v54
	v_exp_f32_e32 v86, v86
	v_exp_f32_e32 v70, v40
	v_max_f32_e32 v151, v153, v153
	v_sub_u32_e32 v153, v96, v176
	v_cmp_gt_u32_e32 vcc, s58, v153
	s_or_b64 vcc, s[2:3], vcc
	v_cvt_pk_bf16_f32 v148, v39, v55
	v_cndmask_b32_e32 v212, v204, v89, vcc
	v_add_u32_e32 v89, 32, v153
	v_cmp_gt_u32_e32 vcc, s58, v89
	s_or_b64 vcc, s[2:3], vcc
	v_add_u32_e32 v89, 64, v153
	v_cndmask_b32_e32 v213, v204, v57, vcc
	v_cmp_gt_u32_e32 vcc, s58, v89
	s_or_b64 vcc, s[2:3], vcc
	v_max3_f32 v57, v212, s59, v213
	v_cndmask_b32_e32 v214, v204, v73, vcc
	v_add_u32_e32 v73, 0x60, v153
	v_cmp_gt_u32_e32 vcc, s58, v73
	s_or_b64 vcc, s[2:3], vcc
	v_cvt_pk_bf16_f32 v149, v87, v71
	v_cndmask_b32_e32 v216, v204, v41, vcc
	v_max3_f32 v57, v57, v214, v216
	v_mov_b32_e32 v73, v57
	v_mov_b32_e32 v255, v57
	s_nop 1
	v_permlane16_swap_b32_e32 v73, v255
	s_nop 1
	v_mov_b32_dpp v73, v255 quad_perm:[0,1,2,3] row_mask:0x5 bank_mask:0xf
	v_cvt_pk_bf16_f32 v40, v38, v54
	v_cvt_pk_bf16_f32 v41, v86, v70
	ds_write2_b64 v215, v[148:149], v[40:41] offset0:212 offset1:246
	v_max_f32_e32 v151, v152, v151
	v_max_f32_e32 v41, v73, v73
	v_max_f32_e32 v57, v57, v41
	v_mov_b32_dpp v152, v151 quad_perm:[1,0,3,2] row_mask:0xf bank_mask:0xf
	v_sub_f32_e32 v135, v135, v160
	v_mul_f32_e32 v131, 0x3fb8aa3b, v131
	v_mul_f32_e32 v135, 0x3fb8aa3b, v135
	s_waitcnt lgkmcnt(0)
	v_max3_f32 v154, v138, v151, v152
	v_max_f32_dpp v73, v57, v57 row_ror:8 row_mask:0xf bank_mask:0xf
	v_sub_f32_e32 v41, v88, v154
	s_nop 1
	v_mov_b32_dpp v88, v73 row_shl:4 row_mask:0xf bank_mask:0x5
	v_mov_b32_dpp v88, v73 row_shr:4 row_mask:0xf bank_mask:0xa
	v_sub_f32_e32 v56, v56, v154
	v_mul_f32_e32 v56, 0x3fb8aa3b, v56
	v_exp_f32_e32 v57, v56
	v_sub_f32_e32 v56, v72, v154
	v_max_f32_e32 v72, v88, v88
	v_max_f32_e32 v72, v73, v72
	s_nop 1
	v_mov_b32_dpp v88, v72 quad_perm:[2,3,0,1] row_mask:0xf bank_mask:0xf
	v_mul_f32_e32 v56, 0x3fb8aa3b, v56
	v_exp_f32_e32 v89, v56
	v_sub_f32_e32 v56, v150, v154
	v_mul_f32_e32 v56, 0x3fb8aa3b, v56
	v_exp_f32_e32 v73, v56
	v_max_f32_e32 v56, v88, v88
	v_max_f32_e32 v56, v72, v56
	s_nop 1
	v_mov_b32_dpp v72, v56 quad_perm:[1,0,3,2] row_mask:0xf bank_mask:0xf
	v_sub_f32_e32 v40, v138, v154
	v_mul_f32_e32 v40, 0x3fb8aa3b, v40
	v_exp_f32_e32 v138, v40
	v_sub_u32_e32 v40, v96, v177
	v_cmp_gt_u32_e32 vcc, s58, v40
	v_max3_f32 v153, v139, v56, v72
	s_or_b64 vcc, s[2:3], vcc
	v_add_u32_e32 v56, 32, v40
	v_cndmask_b32_e32 v90, v204, v90, vcc
	v_cmp_gt_u32_e32 vcc, s58, v56
	s_or_b64 vcc, s[2:3], vcc
	v_add_u32_e32 v72, 64, v40
	v_cndmask_b32_e32 v58, v204, v58, vcc
	v_cmp_gt_u32_e32 vcc, s58, v72
	s_or_b64 vcc, s[2:3], vcc
	v_add_u32_e32 v40, 0x60, v40
	v_cndmask_b32_e32 v74, v204, v74, vcc
	v_cmp_gt_u32_e32 vcc, s58, v40
	s_or_b64 vcc, s[2:3], vcc
	v_max3_f32 v56, v90, s59, v58
	v_cndmask_b32_e32 v42, v204, v42, vcc
	v_max3_f32 v56, v56, v74, v42
	v_mov_b32_e32 v72, v56
	v_mov_b32_e32 v255, v56
	s_nop 1
	v_permlane16_swap_b32_e32 v72, v255
	v_sub_f32_e32 v88, v213, v153
	v_sub_u32_e32 v213, v96, v178
	v_cmp_gt_u32_e32 vcc, s58, v213
	s_or_b64 vcc, s[2:3], vcc
	v_max_f32_e32 v72, v72, v255
	v_mul_f32_e32 v56, 0x3fb8aa3b, v88
	v_sub_f32_e32 v88, v214, v153
	v_cndmask_b32_e32 v214, v204, v91, vcc
	v_add_u32_e32 v91, 32, v213
	v_cmp_gt_u32_e32 vcc, s58, v91
	s_or_b64 vcc, s[2:3], vcc
	v_add_u32_e32 v91, 64, v213
	v_max_f32_dpp v150, v72, v72 row_ror:8 row_mask:0xf bank_mask:0xf
	v_cndmask_b32_e32 v215, v204, v59, vcc
	v_cmp_gt_u32_e32 vcc, s58, v91
	v_mov_b32_dpp v151, v150 row_shl:4 row_mask:0xf bank_mask:0x5
	v_mov_b32_dpp v151, v150 row_shr:4 row_mask:0xf bank_mask:0xa
	s_or_b64 vcc, s[2:3], vcc
	v_sub_f32_e32 v72, v216, v153
	v_cndmask_b32_e32 v216, v204, v75, vcc
	v_add_u32_e32 v75, 0x60, v213
	v_cmp_gt_u32_e32 vcc, s58, v75
	s_or_b64 vcc, s[2:3], vcc
	v_max3_f32 v59, v214, s59, v215
	v_cndmask_b32_e32 v213, v204, v43, vcc
	v_max3_f32 v43, v59, v216, v213
	v_sub_f32_e32 v40, v212, v153
	v_max_f32_e32 v152, v150, v151
	v_mov_b32_e32 v59, v43
	v_mov_b32_e32 v255, v43
	s_nop 1
	v_permlane16_swap_b32_e32 v59, v255
	v_mul_f32_e32 v41, 0x3fb8aa3b, v41
	v_mul_f32_e32 v40, 0x3fb8aa3b, v40
	v_mul_f32_e32 v88, 0x3fb8aa3b, v88
	v_mul_f32_e32 v72, 0x3fb8aa3b, v72
	v_mov_b32_dpp v212, v152 quad_perm:[2,3,0,1] row_mask:0xf bank_mask:0xf
	v_exp_f32_e32 v41, v41
	v_exp_f32_e32 v40, v40
	v_exp_f32_e32 v56, v56
	v_exp_f32_e32 v88, v88
	v_exp_f32_e32 v72, v72
	v_cvt_pk_bf16_f32 v148, v41, v57
	v_cvt_pk_bf16_f32 v149, v89, v73
	v_cvt_pk_bf16_f32 v150, v40, v56
	v_cvt_pk_bf16_f32 v151, v88, v72
	v_add_u32_e32 v75, 0x9800, v186
	v_max_f32_e32 v59, v59, v255
	v_max_f32_e32 v152, v152, v212
	ds_write2_b64 v75, v[148:149], v[150:151] offset0:160 offset1:194
	s_nop 0
	v_mov_b32_dpp v212, v152 quad_perm:[1,0,3,2] row_mask:0xf bank_mask:0xf
	v_sub_f32_e32 v139, v139, v153
	v_mul_f32_e32 v139, 0x3fb8aa3b, v139
	v_exp_f32_e32 v131, v131
	s_waitcnt lgkmcnt(0)
	v_max3_f32 v152, v140, v152, v212
	v_max_f32_dpp v75, v59, v59 row_ror:8 row_mask:0xf bank_mask:0xf
	v_sub_f32_e32 v43, v90, v152
	s_nop 1
	v_mov_b32_dpp v90, v75 row_shl:4 row_mask:0xf bank_mask:0x5
	v_mov_b32_dpp v90, v75 row_shr:4 row_mask:0xf bank_mask:0xa
	v_sub_f32_e32 v58, v58, v152
	v_mul_f32_e32 v58, 0x3fb8aa3b, v58
	v_exp_f32_e32 v59, v58
	v_sub_f32_e32 v58, v74, v152
	v_max_f32_e32 v74, v90, v90
	v_max_f32_e32 v74, v75, v74
	s_nop 1
	v_mov_b32_dpp v90, v74 quad_perm:[2,3,0,1] row_mask:0xf bank_mask:0xf
	v_sub_f32_e32 v42, v42, v152
	v_mul_f32_e32 v42, 0x3fb8aa3b, v42
	v_exp_f32_e32 v75, v42
	v_mul_f32_e32 v58, 0x3fb8aa3b, v58
	v_max_f32_e32 v42, v90, v90
	v_max_f32_e32 v42, v74, v42
	v_exp_f32_e32 v91, v58
	s_nop 1
	v_mov_b32_dpp v58, v42 quad_perm:[1,0,3,2] row_mask:0xf bank_mask:0xf
	v_sub_f32_e32 v140, v140, v152
	v_mul_f32_e32 v74, 0x3fb8aa3b, v140
	v_exp_f32_e32 v140, v74
	v_mul_f32_e32 v43, 0x3fb8aa3b, v43
	v_max3_f32 v151, v141, v42, v58
	v_sub_u32_e32 v42, v96, v179
	v_cmp_gt_u32_e32 vcc, s58, v42
	s_or_b64 vcc, s[2:3], vcc
	v_add_u32_e32 v58, 32, v42
	v_cndmask_b32_e32 v92, v204, v92, vcc
	v_cmp_gt_u32_e32 vcc, s58, v58
	s_or_b64 vcc, s[2:3], vcc
	v_add_u32_e32 v74, 64, v42
	v_cndmask_b32_e32 v60, v204, v60, vcc
	v_cmp_gt_u32_e32 vcc, s58, v74
	s_or_b64 vcc, s[2:3], vcc
	v_add_u32_e32 v42, 0x60, v42
	v_cndmask_b32_e32 v76, v204, v76, vcc
	v_cmp_gt_u32_e32 vcc, s58, v42
	s_or_b64 vcc, s[2:3], vcc
	v_max3_f32 v58, v92, s59, v60
	v_cndmask_b32_e32 v44, v204, v44, vcc
	v_max3_f32 v58, v58, v76, v44
	v_mov_b32_e32 v74, v58
	v_mov_b32_e32 v255, v58
	s_nop 1
	v_permlane16_swap_b32_e32 v74, v255
	v_sub_f32_e32 v90, v215, v151
	v_sub_u32_e32 v215, v96, v180
	v_cmp_gt_u32_e32 vcc, s58, v215
	s_or_b64 vcc, s[2:3], vcc
	v_max_f32_e32 v74, v74, v255
	v_mul_f32_e32 v58, 0x3fb8aa3b, v90
	v_sub_f32_e32 v90, v216, v151
	v_cndmask_b32_e32 v216, v204, v93, vcc
	v_add_u32_e32 v93, 32, v215
	v_cmp_gt_u32_e32 vcc, s58, v93
	s_or_b64 vcc, s[2:3], vcc
	v_add_u32_e32 v93, 64, v215
	v_max_f32_dpp v150, v74, v74 row_ror:8 row_mask:0xf bank_mask:0xf
	v_cndmask_b32_e32 v217, v204, v61, vcc
	v_cmp_gt_u32_e32 vcc, s58, v93
	v_mov_b32_dpp v212, v150 row_shl:4 row_mask:0xf bank_mask:0x5
	v_mov_b32_dpp v212, v150 row_shr:4 row_mask:0xf bank_mask:0xa
	s_or_b64 vcc, s[2:3], vcc
	v_cndmask_b32_e32 v218, v204, v77, vcc
	v_add_u32_e32 v77, 0x60, v215
	v_cmp_gt_u32_e32 vcc, s58, v77
	s_or_b64 vcc, s[2:3], vcc
	v_max3_f32 v61, v216, s59, v217
	v_cndmask_b32_e32 v215, v204, v45, vcc
	v_max3_f32 v45, v61, v218, v215
	v_sub_f32_e32 v42, v214, v151
	v_sub_f32_e32 v74, v213, v151
	v_max_f32_e32 v150, v150, v212
	v_mov_b32_e32 v61, v45
	v_mov_b32_e32 v255, v45
	s_nop 1
	v_permlane16_swap_b32_e32 v61, v255
	v_mul_f32_e32 v42, 0x3fb8aa3b, v42
	v_mul_f32_e32 v90, 0x3fb8aa3b, v90
	v_mul_f32_e32 v74, 0x3fb8aa3b, v74
	v_mov_b32_dpp v214, v150 quad_perm:[2,3,0,1] row_mask:0xf bank_mask:0xf
	v_exp_f32_e32 v43, v43
	v_exp_f32_e32 v42, v42
	v_exp_f32_e32 v58, v58
	v_exp_f32_e32 v90, v90
	v_exp_f32_e32 v74, v74
	v_cvt_pk_bf16_f32 v148, v43, v59
	v_cvt_pk_bf16_f32 v149, v91, v75
	v_cvt_pk_bf16_f32 v212, v42, v58
	v_cvt_pk_bf16_f32 v213, v90, v74
	v_add_u32_e32 v77, 0x9c00, v186
	v_max_f32_e32 v61, v61, v255
	v_max_f32_e32 v150, v150, v214
	ds_write2_b64 v77, v[148:149], v[212:213] offset0:100 offset1:134
	s_nop 0
	v_mov_b32_dpp v214, v150 quad_perm:[1,0,3,2] row_mask:0xf bank_mask:0xf
	v_sub_f32_e32 v141, v141, v151
	v_mul_f32_e32 v141, 0x3fb8aa3b, v141
	v_exp_f32_e32 v133, v133
	s_waitcnt lgkmcnt(0)
	v_max3_f32 v150, v142, v150, v214
	v_max_f32_dpp v77, v61, v61 row_ror:8 row_mask:0xf bank_mask:0xf
	v_sub_f32_e32 v45, v92, v150
	s_nop 1
	v_mov_b32_dpp v92, v77 row_shl:4 row_mask:0xf bank_mask:0x5
	v_mov_b32_dpp v92, v77 row_shr:4 row_mask:0xf bank_mask:0xa
	v_sub_f32_e32 v60, v60, v150
	v_mul_f32_e32 v60, 0x3fb8aa3b, v60
	v_exp_f32_e32 v61, v60
	v_sub_f32_e32 v60, v76, v150
	v_max_f32_e32 v76, v92, v92
	v_max_f32_e32 v76, v77, v76
	s_nop 1
	v_mov_b32_dpp v92, v76 quad_perm:[2,3,0,1] row_mask:0xf bank_mask:0xf
	v_sub_f32_e32 v44, v44, v150
	v_mul_f32_e32 v44, 0x3fb8aa3b, v44
	v_exp_f32_e32 v77, v44
	v_mul_f32_e32 v60, 0x3fb8aa3b, v60
	v_max_f32_e32 v44, v92, v92
	v_max_f32_e32 v44, v76, v44
	v_exp_f32_e32 v93, v60
	s_nop 1
	v_mov_b32_dpp v60, v44 quad_perm:[1,0,3,2] row_mask:0xf bank_mask:0xf
	v_sub_f32_e32 v142, v142, v150
	v_mul_f32_e32 v76, 0x3fb8aa3b, v142
	v_exp_f32_e32 v142, v76
	v_mul_f32_e32 v45, 0x3fb8aa3b, v45
	v_max3_f32 v149, v143, v44, v60
	v_sub_u32_e32 v44, v96, v181
	v_cmp_gt_u32_e32 vcc, s58, v44
	s_or_b64 vcc, s[2:3], vcc
	v_add_u32_e32 v60, 32, v44
	v_cndmask_b32_e32 v94, v204, v94, vcc
	v_cmp_gt_u32_e32 vcc, s58, v60
	s_or_b64 vcc, s[2:3], vcc
	v_add_u32_e32 v76, 64, v44
	v_cndmask_b32_e32 v62, v204, v62, vcc
	v_cmp_gt_u32_e32 vcc, s58, v76
	s_or_b64 vcc, s[2:3], vcc
	v_add_u32_e32 v44, 0x60, v44
	v_cndmask_b32_e32 v78, v204, v78, vcc
	v_cmp_gt_u32_e32 vcc, s58, v44
	s_or_b64 vcc, s[2:3], vcc
	v_max3_f32 v60, v94, s59, v62
	v_cndmask_b32_e32 v46, v204, v46, vcc
	v_max3_f32 v60, v60, v78, v46
	v_mov_b32_e32 v76, v60
	v_mov_b32_e32 v255, v60
	s_nop 1
	v_permlane16_swap_b32_e32 v76, v255
	v_sub_u32_e32 v96, v96, v182
	v_cmp_gt_u32_e32 vcc, s58, v96
	s_or_b64 vcc, s[2:3], vcc
	v_sub_f32_e32 v92, v217, v149
	v_max_f32_e32 v76, v76, v255
	v_cndmask_b32_e32 v217, v204, v95, vcc
	v_add_u32_e32 v95, 32, v96
	v_cmp_gt_u32_e32 vcc, s58, v95
	s_or_b64 vcc, s[2:3], vcc
	v_add_u32_e32 v95, 64, v96
	v_mul_f32_e32 v60, 0x3fb8aa3b, v92
	v_sub_f32_e32 v92, v218, v149
	v_max_f32_dpp v148, v76, v76 row_ror:8 row_mask:0xf bank_mask:0xf
	v_cndmask_b32_e32 v218, v204, v63, vcc
	v_cmp_gt_u32_e32 vcc, s58, v95
	v_mov_b32_dpp v214, v148 row_shl:4 row_mask:0xf bank_mask:0x5
	v_mov_b32_dpp v214, v148 row_shr:4 row_mask:0xf bank_mask:0xa
	s_or_b64 vcc, s[2:3], vcc
	v_cndmask_b32_e32 v219, v204, v79, vcc
	v_add_u32_e32 v79, 0x60, v96
	v_cmp_gt_u32_e32 vcc, s58, v79
	s_or_b64 vcc, s[2:3], vcc
	v_max3_f32 v63, v217, s59, v218
	v_cndmask_b32_e32 v96, v204, v47, vcc
	v_max3_f32 v47, v63, v219, v96
	v_sub_f32_e32 v44, v216, v149
	v_sub_f32_e32 v76, v215, v149
	v_max_f32_e32 v148, v148, v214
	v_mov_b32_e32 v63, v47
	v_mov_b32_e32 v255, v47
	s_nop 1
	v_permlane16_swap_b32_e32 v63, v255
	v_mul_f32_e32 v44, 0x3fb8aa3b, v44
	v_mul_f32_e32 v92, 0x3fb8aa3b, v92
	v_mul_f32_e32 v76, 0x3fb8aa3b, v76
	v_mov_b32_dpp v216, v148 quad_perm:[2,3,0,1] row_mask:0xf bank_mask:0xf
	v_exp_f32_e32 v45, v45
	v_exp_f32_e32 v44, v44
	v_exp_f32_e32 v60, v60
	v_exp_f32_e32 v92, v92
	v_exp_f32_e32 v76, v76
	v_cvt_pk_bf16_f32 v212, v45, v61
	v_cvt_pk_bf16_f32 v213, v93, v77
	v_cvt_pk_bf16_f32 v214, v44, v60
	v_cvt_pk_bf16_f32 v215, v92, v76
	v_add_u32_e32 v79, 0xa000, v186
	v_max_f32_e32 v63, v63, v255
	v_max_f32_e32 v148, v148, v216
	ds_write2_b64 v79, v[212:213], v[214:215] offset0:176 offset1:210
	s_nop 0
	v_mov_b32_dpp v216, v148 quad_perm:[1,0,3,2] row_mask:0xf bank_mask:0xf
	v_sub_f32_e32 v143, v143, v149
	v_mul_f32_e32 v143, 0x3fb8aa3b, v143
	v_exp_f32_e32 v135, v135
	s_waitcnt lgkmcnt(0)
	v_max3_f32 v148, v144, v148, v216
	v_max_f32_dpp v79, v63, v63 row_ror:8 row_mask:0xf bank_mask:0xf
	v_sub_f32_e32 v47, v94, v148
	s_nop 1
	v_mov_b32_dpp v94, v79 row_shl:4 row_mask:0xf bank_mask:0x5
	v_mov_b32_dpp v94, v79 row_shr:4 row_mask:0xf bank_mask:0xa
	v_sub_f32_e32 v62, v62, v148
	v_mul_f32_e32 v62, 0x3fb8aa3b, v62
	v_exp_f32_e32 v63, v62
	v_sub_f32_e32 v62, v78, v148
	v_max_f32_e32 v78, v94, v94
	v_max_f32_e32 v78, v79, v78
	s_nop 1
	v_mov_b32_dpp v94, v78 quad_perm:[2,3,0,1] row_mask:0xf bank_mask:0xf
	v_sub_f32_e32 v46, v46, v148
	v_mul_f32_e32 v46, 0x3fb8aa3b, v46
	v_exp_f32_e32 v79, v46
	v_mul_f32_e32 v62, 0x3fb8aa3b, v62
	v_max_f32_e32 v46, v94, v94
	v_max_f32_e32 v46, v78, v46
	v_exp_f32_e32 v95, v62
	s_nop 1
	v_mov_b32_dpp v62, v46 quad_perm:[1,0,3,2] row_mask:0xf bank_mask:0xf
	v_sub_f32_e32 v144, v144, v148
	v_mul_f32_e32 v78, 0x3fb8aa3b, v144
	v_exp_f32_e32 v144, v78
	v_mul_f32_e32 v47, 0x3fb8aa3b, v47
	v_max3_f32 v147, v145, v46, v62
	v_sub_f32_e32 v78, v219, v147
	v_mul_f32_e32 v78, 0x3fb8aa3b, v78
	v_sub_f32_e32 v46, v217, v147
	v_sub_f32_e32 v62, v218, v147
	v_exp_f32_e32 v94, v78
	v_sub_f32_e32 v78, v96, v147
	v_sub_f32_e32 v145, v145, v147
	v_mul_f32_e32 v46, 0x3fb8aa3b, v46
	v_mul_f32_e32 v62, 0x3fb8aa3b, v62
	v_mul_f32_e32 v78, 0x3fb8aa3b, v78
	v_exp_f32_e32 v47, v47
	v_exp_f32_e32 v46, v46
	v_exp_f32_e32 v62, v62
	v_exp_f32_e32 v78, v78
	v_mul_f32_e32 v96, 0x3fb8aa3b, v145
	v_exp_f32_e32 v137, v137
	v_exp_f32_e32 v139, v139
	v_exp_f32_e32 v141, v141
	v_exp_f32_e32 v143, v143
	v_exp_f32_e32 v145, v96
	v_cvt_pk_bf16_f32 v208, v47, v63
	v_cvt_pk_bf16_f32 v209, v95, v79
	v_cvt_pk_bf16_f32 v210, v46, v62
	v_cvt_pk_bf16_f32 v211, v94, v78
	v_add_u32_e32 v96, 0xa400, v186
	ds_write2_b64 v96, v[208:209], v[210:211] offset0:116 offset1:150
	v_pk_mul_f32 v[14:15], v[14:15], v[144:145]
	v_pk_mul_f32 v[12:13], v[12:13], v[142:143]
	v_pk_mul_f32 v[10:11], v[10:11], v[140:141]
	v_pk_mul_f32 v[8:9], v[8:9], v[138:139]
	v_pk_mul_f32 v[6:7], v[6:7], v[136:137]
	v_pk_mul_f32 v[4:5], v[4:5], v[134:135]
	v_pk_mul_f32 v[2:3], v[2:3], v[132:133]
	v_pk_mul_f32 v[0:1], v[0:1], v[130:131]
	v_pk_mul_f32 v[30:31], v[30:31], v[144:145]
	v_pk_mul_f32 v[28:29], v[28:29], v[142:143]
	v_pk_mul_f32 v[26:27], v[26:27], v[140:141]
	v_pk_mul_f32 v[24:25], v[24:25], v[138:139]
	v_pk_mul_f32 v[22:23], v[22:23], v[136:137]
	v_pk_mul_f32 v[20:21], v[20:21], v[134:135]
	v_pk_mul_f32 v[18:19], v[18:19], v[132:133]
	v_pk_mul_f32 v[16:17], v[16:17], v[130:131]
	s_mov_b32 s2, -16
	v_mov_b32_e32 v96, v185
	v_mov_b32_e32 v208, v184

.Latt_nm:
	s_nop 7
	s_nop 7
	s_nop 7
	s_add_i32 s6, s53, s49
	v_mbcnt_hi_u32_b32 v148, -1, v195
	v_lshl_add_u32 v96, s6, 7, v183
	v_and_b32_e32 v147, 64, v148
	v_add_u32_e32 v149, 64, v147
	v_xor_b32_e32 v147, 16, v148
	v_cmp_lt_i32_e32 vcc, v147, v149
	v_max3_f32 v150, v80, s59, v48
	v_max3_f32 v150, v150, v64, v32
	v_mov_b32_e32 v151, v150
	v_mov_b32_e32 v255, v150
	s_nop 1
	v_permlane16_swap_b32_e32 v151, v255
	v_add_u32_e32 v187, 0x8800, v186
	v_add_u32_e32 v215, 0x9000, v186
	v_max_f32_e32 v150, v151, v255
	v_xor_b32_e32 v151, 8, v148
	v_cmp_lt_i32_e32 vcc, v151, v149
	v_max_f32_dpp v150, v150, v150 row_ror:8 row_mask:0xf bank_mask:0xf
	v_xor_b32_e32 v151, 4, v148
	v_cmp_lt_i32_e32 vcc, v151, v149
	s_nop 1
	v_cndmask_b32_e32 v151, v148, v151, vcc
	s_nop 1
	v_mov_b32_dpp v151, v150 row_shl:4 row_mask:0xf bank_mask:0x5
	s_nop 1
	v_mov_b32_dpp v151, v150 row_shr:4 row_mask:0xf bank_mask:0xa
	v_max_f32_e32 v150, v150, v151
	v_xor_b32_e32 v151, 2, v148
	v_cmp_lt_i32_e32 vcc, v151, v149
	v_max_f32_dpp v150, v150, v150 quad_perm:[2,3,0,1] row_mask:0xf bank_mask:0xf
	v_xor_b32_e32 v151, 1, v148
	v_cmp_lt_i32_e32 vcc, v151, v149
	v_sub_u32_e32 v149, v96, v161
	s_nop 0
	v_cndmask_b32_e32 v148, v148, v151, vcc
	v_mov_b32_e32 v151, v81
	v_mov_b32_e32 v152, v49
	v_max3_f32 v49, v151, s59, v152
	v_mov_b32_e32 v153, v65
	v_add_u32_e32 v65, 0x60, v149
	v_mov_b32_dpp v148, v150 quad_perm:[1,0,3,2] row_mask:0xf bank_mask:0xf
	v_mov_b32_e32 v154, v33
	v_max3_f32 v33, v49, v153, v154
	v_mov_b32_e32 v49, v33
	v_mov_b32_e32 v255, v33
	s_nop 1
	v_permlane16_swap_b32_e32 v49, v255
	v_max3_f32 v207, v130, v150, v148
	v_sub_f32_e32 v48, v48, v207
	v_mul_f32_e32 v48, 0x3fb8aa3b, v48
	v_max_f32_e32 v49, v49, v255
	v_sub_f32_e32 v33, v80, v207
	v_sub_f32_e32 v32, v32, v207
	v_mul_f32_e32 v32, 0x3fb8aa3b, v32
	v_sub_f32_e32 v130, v130, v207
	v_max_f32_dpp v65, v49, v49 row_ror:8 row_mask:0xf bank_mask:0xf
	s_nop 1
	v_mov_b32_dpp v80, v65 row_shl:4 row_mask:0xf bank_mask:0x5
	s_nop 1
	v_mov_b32_dpp v80, v65 row_shr:4 row_mask:0xf bank_mask:0xa
	v_exp_f32_e32 v49, v48
	v_sub_f32_e32 v48, v64, v207
	v_mul_f32_e32 v48, 0x3fb8aa3b, v48
	v_exp_f32_e32 v81, v48
	v_max_f32_e32 v64, v80, v80
	v_max_f32_e32 v64, v65, v64
	s_nop 1
	v_mov_b32_dpp v80, v64 quad_perm:[2,3,0,1] row_mask:0xf bank_mask:0xf
	v_exp_f32_e32 v65, v32
	v_mul_f32_e32 v33, 0x3fb8aa3b, v33
	v_exp_f32_e32 v33, v33
	v_max_f32_e32 v32, v80, v80
	v_max_f32_e32 v32, v64, v32
	s_nop 1
	v_mov_b32_dpp v48, v32 quad_perm:[1,0,3,2] row_mask:0xf bank_mask:0xf
	v_mul_f32_e32 v64, 0x3fb8aa3b, v130
	v_exp_f32_e32 v130, v64
	v_cvt_pk_bf16_f32 v148, v33, v49
	v_cvt_pk_bf16_f32 v149, v81, v65
	v_max3_f32 v206, v131, v32, v48
	v_max3_f32 v48, v82, s59, v50
	v_max3_f32 v48, v48, v66, v34
	v_mov_b32_e32 v64, v48
	v_mov_b32_e32 v255, v48
	s_nop 1
	v_permlane16_swap_b32_e32 v64, v255
	v_sub_f32_e32 v32, v151, v206
	v_sub_f32_e32 v80, v152, v206
	v_mul_f32_e32 v32, 0x3fb8aa3b, v32
	v_exp_f32_e32 v32, v32
	v_max_f32_e32 v64, v64, v255
	v_mul_f32_e32 v48, 0x3fb8aa3b, v80
	v_sub_f32_e32 v80, v153, v206
	v_mul_f32_e32 v80, 0x3fb8aa3b, v80
	v_exp_f32_e32 v48, v48
	v_max_f32_dpp v150, v64, v64 row_ror:8 row_mask:0xf bank_mask:0xf
	v_sub_f32_e32 v64, v154, v206
	v_sub_u32_e32 v154, v96, v170
	v_mov_b32_dpp v151, v150 row_shl:4 row_mask:0xf bank_mask:0x5
	s_nop 1
	v_mov_b32_dpp v151, v150 row_shr:4 row_mask:0xf bank_mask:0xa
	v_mov_b32_e32 v155, v83
	v_mov_b32_e32 v156, v51
	v_max3_f32 v51, v155, s59, v156
	v_mov_b32_e32 v160, v67
	v_add_u32_e32 v67, 0x60, v154
	v_mov_b32_e32 v154, v35
	v_max3_f32 v35, v51, v160, v154
	v_max_f32_e32 v152, v150, v151
	v_mov_b32_e32 v51, v35
	v_mov_b32_e32 v255, v35
	s_nop 1
	v_permlane16_swap_b32_e32 v51, v255
	v_mov_b32_dpp v153, v152 quad_perm:[2,3,0,1] row_mask:0xf bank_mask:0xf
	v_mul_f32_e32 v64, 0x3fb8aa3b, v64
	v_exp_f32_e32 v80, v80
	v_exp_f32_e32 v64, v64
	v_max_f32_e32 v51, v51, v255
	v_max_f32_e32 v152, v152, v153
	s_nop 1
	v_mov_b32_dpp v153, v152 quad_perm:[1,0,3,2] row_mask:0xf bank_mask:0xf
	v_cvt_pk_bf16_f32 v150, v32, v48
	v_cvt_pk_bf16_f32 v151, v80, v64
	ds_write2_b64 v187, v[148:149], v[150:151] offset0:128 offset1:162
	v_max3_f32 v189, v132, v152, v153
	v_max_f32_dpp v67, v51, v51 row_ror:8 row_mask:0xf bank_mask:0xf
	v_sub_f32_e32 v35, v82, v189
	s_nop 1
	v_mov_b32_dpp v82, v67 row_shl:4 row_mask:0xf bank_mask:0x5
	s_nop 1
	v_mov_b32_dpp v82, v67 row_shr:4 row_mask:0xf bank_mask:0xa
	v_sub_f32_e32 v50, v50, v189
	v_mul_f32_e32 v50, 0x3fb8aa3b, v50
	v_exp_f32_e32 v51, v50
	v_sub_f32_e32 v50, v66, v189
	s_waitcnt lgkmcnt(0)
	v_max_f32_e32 v66, v82, v82
	v_max_f32_e32 v66, v67, v66
	s_nop 1
	v_mov_b32_dpp v82, v66 quad_perm:[2,3,0,1] row_mask:0xf bank_mask:0xf
	v_sub_f32_e32 v34, v34, v189
	v_mul_f32_e32 v34, 0x3fb8aa3b, v34
	v_exp_f32_e32 v67, v34
	v_mul_f32_e32 v50, 0x3fb8aa3b, v50
	v_max_f32_e32 v34, v82, v82
	v_max_f32_e32 v34, v66, v34
	v_exp_f32_e32 v83, v50
	s_nop 1
	v_mov_b32_dpp v50, v34 quad_perm:[1,0,3,2] row_mask:0xf bank_mask:0xf
	v_sub_f32_e32 v132, v132, v189
	v_mul_f32_e32 v66, 0x3fb8aa3b, v132
	v_exp_f32_e32 v132, v66
	v_mul_f32_e32 v35, 0x3fb8aa3b, v35
	v_max3_f32 v188, v133, v34, v50
	v_sub_u32_e32 v34, v96, v171
	v_add_u32_e32 v66, 64, v34
	v_max3_f32 v50, v84, s59, v52
	v_mov_b32_e32 v150, v36
	v_max3_f32 v34, v50, v68, v150
	v_mov_b32_e32 v36, v34
	v_mov_b32_e32 v255, v34
	s_nop 1
	v_permlane16_swap_b32_e32 v36, v255
	v_sub_f32_e32 v151, v154, v188
	v_sub_f32_e32 v50, v133, v188
	v_mul_f32_e32 v133, 0x3fb8aa3b, v50
	v_sub_f32_e32 v50, v155, v188
	v_max_f32_e32 v36, v36, v255
	s_nop 1
	v_mov_b32_dpp v66, v36 row_ror:8 row_mask:0xf bank_mask:0xf
	v_mul_f32_e32 v50, 0x3fb8aa3b, v50
	v_exp_f32_e32 v34, v50
	v_sub_f32_e32 v50, v156, v188
	v_sub_f32_e32 v82, v160, v188
	v_max_f32_e32 v36, v36, v66
	s_nop 1
	v_mov_b32_dpp v66, v36 row_shl:4 row_mask:0xf bank_mask:0x5
	s_nop 1
	v_mov_b32_dpp v66, v36 row_shr:4 row_mask:0xf bank_mask:0xa
	v_mul_f32_e32 v50, 0x3fb8aa3b, v50
	v_mul_f32_e32 v82, 0x3fb8aa3b, v82
	v_exp_f32_e32 v35, v35
	v_exp_f32_e32 v50, v50
	v_max_f32_e32 v152, v36, v66
	s_nop 1
	v_mov_b32_dpp v153, v152 quad_perm:[2,3,0,1] row_mask:0xf bank_mask:0xf
	v_mul_f32_e32 v36, 0x3fb8aa3b, v151
	v_exp_f32_e32 v82, v82
	v_exp_f32_e32 v66, v36
	v_cvt_pk_bf16_f32 v148, v35, v51
	v_max_f32_e32 v151, v153, v153
	v_cvt_pk_bf16_f32 v149, v83, v67
	v_mov_b32_e32 v154, v85
	v_mov_b32_e32 v155, v53
	v_max3_f32 v53, v154, s59, v155
	v_mov_b32_e32 v156, v69
	v_cvt_pk_bf16_f32 v36, v34, v50
	v_mov_b32_e32 v153, v37
	v_max3_f32 v53, v53, v156, v153
	v_mov_b32_e32 v69, v53
	v_mov_b32_e32 v255, v53
	s_nop 1
	v_permlane16_swap_b32_e32 v69, v255
	s_nop 1
	v_mov_b32_dpp v69, v255 quad_perm:[0,1,2,3] row_mask:0x5 bank_mask:0xf
	v_cvt_pk_bf16_f32 v37, v82, v66
	ds_write2_b64 v187, v[148:149], v[36:37] offset0:196 offset1:230
	v_max_f32_e32 v151, v152, v151
	s_nop 1
	v_mov_b32_dpp v152, v151 quad_perm:[1,0,3,2] row_mask:0xf bank_mask:0xf
	v_max_f32_e32 v37, v69, v69
	v_max_f32_e32 v53, v53, v37
	v_sub_f32_e32 v131, v131, v206
	s_waitcnt lgkmcnt(0)
	v_max3_f32 v187, v134, v151, v152
	v_sub_f32_e32 v37, v84, v187
	v_sub_f32_e32 v52, v52, v187
	v_max_f32_dpp v69, v53, v53 row_ror:8 row_mask:0xf bank_mask:0xf
	s_nop 1
	v_mov_b32_dpp v84, v69 row_shl:4 row_mask:0xf bank_mask:0x5
	s_nop 1
	v_mov_b32_dpp v84, v69 row_shr:4 row_mask:0xf bank_mask:0xa
	v_mul_f32_e32 v52, 0x3fb8aa3b, v52
	v_exp_f32_e32 v53, v52
	v_sub_f32_e32 v52, v68, v187
	v_mul_f32_e32 v52, 0x3fb8aa3b, v52
	v_max_f32_e32 v68, v84, v84
	v_max_f32_e32 v68, v69, v68
	s_nop 1
	v_mov_b32_dpp v84, v68 quad_perm:[2,3,0,1] row_mask:0xf bank_mask:0xf
	v_exp_f32_e32 v85, v52
	v_sub_f32_e32 v52, v150, v187
	v_mul_f32_e32 v52, 0x3fb8aa3b, v52
	v_exp_f32_e32 v69, v52
	v_max_f32_e32 v52, v84, v84
	v_max_f32_e32 v52, v68, v52
	s_nop 1
	v_mov_b32_dpp v68, v52 quad_perm:[1,0,3,2] row_mask:0xf bank_mask:0xf
	v_sub_f32_e32 v36, v134, v187
	v_mul_f32_e32 v36, 0x3fb8aa3b, v36
	v_exp_f32_e32 v134, v36
	v_max3_f32 v160, v135, v52, v68
	v_max3_f32 v52, v86, s59, v54
	v_max3_f32 v52, v52, v70, v38
	v_mov_b32_e32 v68, v52
	v_mov_b32_e32 v255, v52
	s_nop 1
	v_permlane16_swap_b32_e32 v68, v255
	v_sub_f32_e32 v36, v154, v160
	v_sub_u32_e32 v154, v96, v174
	v_max_f32_e32 v68, v68, v255
	s_nop 1
	v_mov_b32_e32 v212, v87
	v_max_f32_dpp v150, v68, v68 row_ror:8 row_mask:0xf bank_mask:0xf
	v_mov_b32_e32 v213, v55
	s_nop 0
	v_mov_b32_dpp v151, v150 row_shl:4 row_mask:0xf bank_mask:0x5
	s_nop 1
	v_mov_b32_dpp v151, v150 row_shr:4 row_mask:0xf bank_mask:0xa
	v_mov_b32_e32 v214, v71
	v_add_u32_e32 v71, 0x60, v154
	v_max3_f32 v55, v212, s59, v213
	v_mov_b32_e32 v154, v39
	v_max3_f32 v39, v55, v214, v154
	v_max_f32_e32 v152, v150, v151
	v_mov_b32_e32 v55, v39
	v_mov_b32_e32 v255, v39
	s_nop 1
	v_permlane16_swap_b32_e32 v55, v255
	v_sub_f32_e32 v68, v153, v160
	v_mov_b32_dpp v153, v152 quad_perm:[2,3,0,1] row_mask:0xf bank_mask:0xf
	v_sub_f32_e32 v84, v155, v160
	v_mul_f32_e32 v52, 0x3fb8aa3b, v84
	v_max_f32_e32 v55, v55, v255
	v_max_f32_e32 v152, v152, v153
	s_nop 0
	s_nop 1
	v_mov_b32_dpp v153, v152 quad_perm:[1,0,3,2] row_mask:0xf bank_mask:0xf
	v_sub_f32_e32 v84, v156, v160
	v_mul_f32_e32 v37, 0x3fb8aa3b, v37
	v_mul_f32_e32 v36, 0x3fb8aa3b, v36
	v_max3_f32 v156, v136, v152, v153
	v_max_f32_dpp v71, v55, v55 row_ror:8 row_mask:0xf bank_mask:0xf
	v_sub_f32_e32 v39, v86, v156
	s_nop 1
	v_mov_b32_dpp v86, v71 row_shl:4 row_mask:0xf bank_mask:0x5
	s_nop 1
	v_mov_b32_dpp v86, v71 row_shr:4 row_mask:0xf bank_mask:0xa
	v_sub_f32_e32 v54, v54, v156
	v_mul_f32_e32 v54, 0x3fb8aa3b, v54
	v_exp_f32_e32 v55, v54
	v_sub_f32_e32 v54, v70, v156
	v_max_f32_e32 v70, v86, v86
	v_max_f32_e32 v70, v71, v70
	s_nop 1
	v_mov_b32_dpp v86, v70 quad_perm:[2,3,0,1] row_mask:0xf bank_mask:0xf
	v_sub_f32_e32 v38, v38, v156
	v_mul_f32_e32 v38, 0x3fb8aa3b, v38
	v_exp_f32_e32 v71, v38
	v_mul_f32_e32 v54, 0x3fb8aa3b, v54
	v_max_f32_e32 v38, v86, v86
	v_max_f32_e32 v38, v70, v38
	v_exp_f32_e32 v87, v54
	s_nop 1
	v_mov_b32_dpp v54, v38 quad_perm:[1,0,3,2] row_mask:0xf bank_mask:0xf
	v_sub_f32_e32 v136, v136, v156
	v_mul_f32_e32 v84, 0x3fb8aa3b, v84
	v_mul_f32_e32 v68, 0x3fb8aa3b, v68
	v_mul_f32_e32 v70, 0x3fb8aa3b, v136
	v_max3_f32 v155, v137, v38, v54
	v_sub_u32_e32 v38, v96, v175
	v_exp_f32_e32 v37, v37
	v_exp_f32_e32 v36, v36
	v_exp_f32_e32 v52, v52
	v_exp_f32_e32 v84, v84
	v_exp_f32_e32 v68, v68
	v_exp_f32_e32 v136, v70
	v_add_u32_e32 v70, 64, v38
	v_cvt_pk_bf16_f32 v148, v37, v53
	v_cvt_pk_bf16_f32 v149, v85, v69
	v_cvt_pk_bf16_f32 v150, v36, v52
	v_cvt_pk_bf16_f32 v151, v84, v68
	ds_write2_b64 v215, v[148:149], v[150:151] offset0:144 offset1:178
	v_max3_f32 v54, v88, s59, v56
	v_mov_b32_e32 v150, v40
	v_max3_f32 v38, v54, v72, v150
	v_mov_b32_e32 v40, v38
	v_mov_b32_e32 v255, v38
	s_nop 1
	v_permlane16_swap_b32_e32 v40, v255
	v_sub_f32_e32 v151, v154, v155
	v_sub_f32_e32 v54, v137, v155
	v_mul_f32_e32 v137, 0x3fb8aa3b, v54
	v_sub_f32_e32 v54, v212, v155
	s_waitcnt lgkmcnt(0)
	v_max_f32_e32 v40, v40, v255
	s_nop 1
	v_mov_b32_dpp v70, v40 row_ror:8 row_mask:0xf bank_mask:0xf
	v_mul_f32_e32 v54, 0x3fb8aa3b, v54
	v_exp_f32_e32 v38, v54
	v_sub_f32_e32 v54, v213, v155
	v_sub_f32_e32 v86, v214, v155
	v_max_f32_e32 v40, v40, v70
	s_nop 1
	v_mov_b32_dpp v70, v40 row_shl:4 row_mask:0xf bank_mask:0x5
	s_nop 1
	v_mov_b32_dpp v70, v40 row_shr:4 row_mask:0xf bank_mask:0xa
	v_mul_f32_e32 v39, 0x3fb8aa3b, v39
	v_mul_f32_e32 v54, 0x3fb8aa3b, v54
	v_mul_f32_e32 v86, 0x3fb8aa3b, v86
	v_exp_f32_e32 v39, v39
	v_max_f32_e32 v152, v40, v70
	s_nop 1
	v_mov_b32_dpp v153, v152 quad_perm:[2,3,0,1] row_mask:0xf bank_mask:0xf
	v_mul_f32_e32 v40, 0x3fb8aa3b, v151
	v_exp_f32_e32 v54, v54
	v_exp_f32_e32 v86, v86
	v_exp_f32_e32 v70, v40
	v_max_f32_e32 v151, v153, v153
	v_cvt_pk_bf16_f32 v148, v39, v55
	v_mov_b32_e32 v212, v89
	v_mov_b32_e32 v213, v57
	v_max3_f32 v57, v212, s59, v213
	v_mov_b32_e32 v214, v73
	v_cvt_pk_bf16_f32 v149, v87, v71
	v_mov_b32_e32 v216, v41
	v_max3_f32 v57, v57, v214, v216
	v_mov_b32_e32 v73, v57
	v_mov_b32_e32 v255, v57
	s_nop 1
	v_permlane16_swap_b32_e32 v73, v255
	s_nop 1
	v_mov_b32_dpp v73, v255 quad_perm:[0,1,2,3] row_mask:0x5 bank_mask:0xf
	v_cvt_pk_bf16_f32 v40, v38, v54
	v_cvt_pk_bf16_f32 v41, v86, v70
	ds_write2_b64 v215, v[148:149], v[40:41] offset0:212 offset1:246
	v_max_f32_e32 v151, v152, v151
	v_max_f32_e32 v41, v73, v73
	v_max_f32_e32 v57, v57, v41
	v_mov_b32_dpp v152, v151 quad_perm:[1,0,3,2] row_mask:0xf bank_mask:0xf
	v_sub_f32_e32 v135, v135, v160
	v_mul_f32_e32 v131, 0x3fb8aa3b, v131
	v_mul_f32_e32 v135, 0x3fb8aa3b, v135
	s_waitcnt lgkmcnt(0)
	v_max3_f32 v154, v138, v151, v152
	v_max_f32_dpp v73, v57, v57 row_ror:8 row_mask:0xf bank_mask:0xf
	v_sub_f32_e32 v41, v88, v154
	s_nop 1
	v_mov_b32_dpp v88, v73 row_shl:4 row_mask:0xf bank_mask:0x5
	s_nop 1
	v_mov_b32_dpp v88, v73 row_shr:4 row_mask:0xf bank_mask:0xa
	v_sub_f32_e32 v56, v56, v154
	v_mul_f32_e32 v56, 0x3fb8aa3b, v56
	v_exp_f32_e32 v57, v56
	v_sub_f32_e32 v56, v72, v154
	v_max_f32_e32 v72, v88, v88
	v_max_f32_e32 v72, v73, v72
	s_nop 1
	v_mov_b32_dpp v88, v72 quad_perm:[2,3,0,1] row_mask:0xf bank_mask:0xf
	v_mul_f32_e32 v56, 0x3fb8aa3b, v56
	v_exp_f32_e32 v89, v56
	v_sub_f32_e32 v56, v150, v154
	v_mul_f32_e32 v56, 0x3fb8aa3b, v56
	v_exp_f32_e32 v73, v56
	v_max_f32_e32 v56, v88, v88
	v_max_f32_e32 v56, v72, v56
	s_nop 1
	v_mov_b32_dpp v72, v56 quad_perm:[1,0,3,2] row_mask:0xf bank_mask:0xf
	v_sub_f32_e32 v40, v138, v154
	v_mul_f32_e32 v40, 0x3fb8aa3b, v40
	v_exp_f32_e32 v138, v40
	v_max3_f32 v153, v139, v56, v72
	v_max3_f32 v56, v90, s59, v58
	v_max3_f32 v56, v56, v74, v42
	v_mov_b32_e32 v72, v56
	v_mov_b32_e32 v255, v56
	s_nop 1
	v_permlane16_swap_b32_e32 v72, v255
	v_sub_f32_e32 v88, v213, v153
	v_max_f32_e32 v72, v72, v255
	v_mul_f32_e32 v56, 0x3fb8aa3b, v88
	v_sub_f32_e32 v88, v214, v153
	v_mov_b32_e32 v214, v91
	v_max_f32_dpp v150, v72, v72 row_ror:8 row_mask:0xf bank_mask:0xf
	v_mov_b32_e32 v215, v59
	s_nop 0
	v_mov_b32_dpp v151, v150 row_shl:4 row_mask:0xf bank_mask:0x5
	s_nop 1
	v_mov_b32_dpp v151, v150 row_shr:4 row_mask:0xf bank_mask:0xa
	v_sub_f32_e32 v72, v216, v153
	v_mov_b32_e32 v216, v75
	v_max3_f32 v59, v214, s59, v215
	v_mov_b32_e32 v213, v43
	v_max3_f32 v43, v59, v216, v213
	v_sub_f32_e32 v40, v212, v153
	v_max_f32_e32 v152, v150, v151
	v_mov_b32_e32 v59, v43
	v_mov_b32_e32 v255, v43
	s_nop 1
	v_permlane16_swap_b32_e32 v59, v255
	v_mul_f32_e32 v41, 0x3fb8aa3b, v41
	v_mul_f32_e32 v40, 0x3fb8aa3b, v40
	v_mul_f32_e32 v88, 0x3fb8aa3b, v88
	v_mul_f32_e32 v72, 0x3fb8aa3b, v72
	v_mov_b32_dpp v212, v152 quad_perm:[2,3,0,1] row_mask:0xf bank_mask:0xf
	v_exp_f32_e32 v41, v41
	v_exp_f32_e32 v40, v40
	v_exp_f32_e32 v56, v56
	v_exp_f32_e32 v88, v88
	v_exp_f32_e32 v72, v72
	v_cvt_pk_bf16_f32 v148, v41, v57
	v_cvt_pk_bf16_f32 v149, v89, v73
	v_cvt_pk_bf16_f32 v150, v40, v56
	v_cvt_pk_bf16_f32 v151, v88, v72
	v_add_u32_e32 v75, 0x9800, v186
	v_max_f32_e32 v59, v59, v255
	v_max_f32_e32 v152, v152, v212
	ds_write2_b64 v75, v[148:149], v[150:151] offset0:160 offset1:194
	s_nop 0
	v_mov_b32_dpp v212, v152 quad_perm:[1,0,3,2] row_mask:0xf bank_mask:0xf
	v_sub_f32_e32 v139, v139, v153
	v_mul_f32_e32 v139, 0x3fb8aa3b, v139
	v_exp_f32_e32 v131, v131
	s_waitcnt lgkmcnt(0)
	v_max3_f32 v152, v140, v152, v212
	v_max_f32_dpp v75, v59, v59 row_ror:8 row_mask:0xf bank_mask:0xf
	v_sub_f32_e32 v43, v90, v152
	s_nop 1
	v_mov_b32_dpp v90, v75 row_shl:4 row_mask:0xf bank_mask:0x5
	s_nop 1
	v_mov_b32_dpp v90, v75 row_shr:4 row_mask:0xf bank_mask:0xa
	v_sub_f32_e32 v58, v58, v152
	v_mul_f32_e32 v58, 0x3fb8aa3b, v58
	v_exp_f32_e32 v59, v58
	v_sub_f32_e32 v58, v74, v152
	v_max_f32_e32 v74, v90, v90
	v_max_f32_e32 v74, v75, v74
	s_nop 1
	v_mov_b32_dpp v90, v74 quad_perm:[2,3,0,1] row_mask:0xf bank_mask:0xf
	v_sub_f32_e32 v42, v42, v152
	v_mul_f32_e32 v42, 0x3fb8aa3b, v42
	v_exp_f32_e32 v75, v42
	v_mul_f32_e32 v58, 0x3fb8aa3b, v58
	v_max_f32_e32 v42, v90, v90
	v_max_f32_e32 v42, v74, v42
	v_exp_f32_e32 v91, v58
	s_nop 1
	v_mov_b32_dpp v58, v42 quad_perm:[1,0,3,2] row_mask:0xf bank_mask:0xf
	v_sub_f32_e32 v140, v140, v152
	v_mul_f32_e32 v74, 0x3fb8aa3b, v140
	v_exp_f32_e32 v140, v74
	v_mul_f32_e32 v43, 0x3fb8aa3b, v43
	v_max3_f32 v151, v141, v42, v58
	v_max3_f32 v58, v92, s59, v60
	v_max3_f32 v58, v58, v76, v44
	v_mov_b32_e32 v74, v58
	v_mov_b32_e32 v255, v58
	s_nop 1
	v_permlane16_swap_b32_e32 v74, v255
	v_sub_f32_e32 v90, v215, v151
	v_max_f32_e32 v74, v74, v255
	v_mul_f32_e32 v58, 0x3fb8aa3b, v90
	v_sub_f32_e32 v90, v216, v151
	v_mov_b32_e32 v216, v93
	v_max_f32_dpp v150, v74, v74 row_ror:8 row_mask:0xf bank_mask:0xf
	v_mov_b32_e32 v217, v61
	s_nop 0
	v_mov_b32_dpp v212, v150 row_shl:4 row_mask:0xf bank_mask:0x5
	s_nop 1
	v_mov_b32_dpp v212, v150 row_shr:4 row_mask:0xf bank_mask:0xa
	v_mov_b32_e32 v218, v77
	v_max3_f32 v61, v216, s59, v217
	v_mov_b32_e32 v215, v45
	v_max3_f32 v45, v61, v218, v215
	v_sub_f32_e32 v42, v214, v151
	v_sub_f32_e32 v74, v213, v151
	v_max_f32_e32 v150, v150, v212
	v_mov_b32_e32 v61, v45
	v_mov_b32_e32 v255, v45
	s_nop 1
	v_permlane16_swap_b32_e32 v61, v255
	v_mul_f32_e32 v42, 0x3fb8aa3b, v42
	v_mul_f32_e32 v90, 0x3fb8aa3b, v90
	v_mul_f32_e32 v74, 0x3fb8aa3b, v74
	v_mov_b32_dpp v214, v150 quad_perm:[2,3,0,1] row_mask:0xf bank_mask:0xf
	v_exp_f32_e32 v43, v43
	v_exp_f32_e32 v42, v42
	v_exp_f32_e32 v58, v58
	v_exp_f32_e32 v90, v90
	v_exp_f32_e32 v74, v74
	v_cvt_pk_bf16_f32 v148, v43, v59
	v_cvt_pk_bf16_f32 v149, v91, v75
	v_cvt_pk_bf16_f32 v212, v42, v58
	v_cvt_pk_bf16_f32 v213, v90, v74
	v_add_u32_e32 v77, 0x9c00, v186
	v_max_f32_e32 v61, v61, v255
	v_max_f32_e32 v150, v150, v214
	ds_write2_b64 v77, v[148:149], v[212:213] offset0:100 offset1:134
	s_nop 0
	v_mov_b32_dpp v214, v150 quad_perm:[1,0,3,2] row_mask:0xf bank_mask:0xf
	v_sub_f32_e32 v141, v141, v151
	v_mul_f32_e32 v141, 0x3fb8aa3b, v141
	v_exp_f32_e32 v133, v133
	s_waitcnt lgkmcnt(0)
	v_max3_f32 v150, v142, v150, v214
	v_max_f32_dpp v77, v61, v61 row_ror:8 row_mask:0xf bank_mask:0xf
	v_sub_f32_e32 v45, v92, v150
	s_nop 1
	v_mov_b32_dpp v92, v77 row_shl:4 row_mask:0xf bank_mask:0x5
	s_nop 1
	v_mov_b32_dpp v92, v77 row_shr:4 row_mask:0xf bank_mask:0xa
	v_sub_f32_e32 v60, v60, v150
	v_mul_f32_e32 v60, 0x3fb8aa3b, v60
	v_exp_f32_e32 v61, v60
	v_sub_f32_e32 v60, v76, v150
	v_max_f32_e32 v76, v92, v92
	v_max_f32_e32 v76, v77, v76
	s_nop 1
	v_mov_b32_dpp v92, v76 quad_perm:[2,3,0,1] row_mask:0xf bank_mask:0xf
	v_sub_f32_e32 v44, v44, v150
	v_mul_f32_e32 v44, 0x3fb8aa3b, v44
	v_exp_f32_e32 v77, v44
	v_mul_f32_e32 v60, 0x3fb8aa3b, v60
	v_max_f32_e32 v44, v92, v92
	v_max_f32_e32 v44, v76, v44
	v_exp_f32_e32 v93, v60
	s_nop 1
	v_mov_b32_dpp v60, v44 quad_perm:[1,0,3,2] row_mask:0xf bank_mask:0xf
	v_sub_f32_e32 v142, v142, v150
	v_mul_f32_e32 v76, 0x3fb8aa3b, v142
	v_exp_f32_e32 v142, v76
	v_mul_f32_e32 v45, 0x3fb8aa3b, v45
	v_max3_f32 v149, v143, v44, v60
	v_max3_f32 v60, v94, s59, v62
	v_max3_f32 v60, v60, v78, v46
	v_mov_b32_e32 v76, v60
	v_mov_b32_e32 v255, v60
	s_nop 1
	v_permlane16_swap_b32_e32 v76, v255
	v_sub_f32_e32 v92, v217, v149
	v_max_f32_e32 v76, v76, v255
	v_mov_b32_e32 v217, v95
	v_mul_f32_e32 v60, 0x3fb8aa3b, v92
	v_sub_f32_e32 v92, v218, v149
	v_max_f32_dpp v148, v76, v76 row_ror:8 row_mask:0xf bank_mask:0xf
	v_mov_b32_e32 v218, v63
	s_nop 0
	v_mov_b32_dpp v214, v148 row_shl:4 row_mask:0xf bank_mask:0x5
	s_nop 1
	v_mov_b32_dpp v214, v148 row_shr:4 row_mask:0xf bank_mask:0xa
	v_mov_b32_e32 v219, v79
	v_max3_f32 v63, v217, s59, v218
	v_mov_b32_e32 v96, v47
	v_max3_f32 v47, v63, v219, v96
	v_sub_f32_e32 v44, v216, v149
	v_sub_f32_e32 v76, v215, v149
	v_max_f32_e32 v148, v148, v214
	v_mov_b32_e32 v63, v47
	v_mov_b32_e32 v255, v47
	s_nop 1
	v_permlane16_swap_b32_e32 v63, v255
	v_mul_f32_e32 v44, 0x3fb8aa3b, v44
	v_mul_f32_e32 v92, 0x3fb8aa3b, v92
	v_mul_f32_e32 v76, 0x3fb8aa3b, v76
	v_mov_b32_dpp v216, v148 quad_perm:[2,3,0,1] row_mask:0xf bank_mask:0xf
	v_exp_f32_e32 v45, v45
	v_exp_f32_e32 v44, v44
	v_exp_f32_e32 v60, v60
	v_exp_f32_e32 v92, v92
	v_exp_f32_e32 v76, v76
	v_cvt_pk_bf16_f32 v212, v45, v61
	v_cvt_pk_bf16_f32 v213, v93, v77
	v_cvt_pk_bf16_f32 v214, v44, v60
	v_cvt_pk_bf16_f32 v215, v92, v76
	v_add_u32_e32 v79, 0xa000, v186
	v_max_f32_e32 v63, v63, v255
	v_max_f32_e32 v148, v148, v216
	ds_write2_b64 v79, v[212:213], v[214:215] offset0:176 offset1:210
	s_nop 0
	v_mov_b32_dpp v216, v148 quad_perm:[1,0,3,2] row_mask:0xf bank_mask:0xf
	v_sub_f32_e32 v143, v143, v149
	v_mul_f32_e32 v143, 0x3fb8aa3b, v143
	v_exp_f32_e32 v135, v135
	s_waitcnt lgkmcnt(0)
	v_max3_f32 v148, v144, v148, v216
	v_max_f32_dpp v79, v63, v63 row_ror:8 row_mask:0xf bank_mask:0xf
	v_sub_f32_e32 v47, v94, v148
	s_nop 1
	v_mov_b32_dpp v94, v79 row_shl:4 row_mask:0xf bank_mask:0x5
	s_nop 1
	v_mov_b32_dpp v94, v79 row_shr:4 row_mask:0xf bank_mask:0xa
	v_sub_f32_e32 v62, v62, v148
	v_mul_f32_e32 v62, 0x3fb8aa3b, v62
	v_exp_f32_e32 v63, v62
	v_sub_f32_e32 v62, v78, v148
	v_max_f32_e32 v78, v94, v94
	v_max_f32_e32 v78, v79, v78
	s_nop 1
	v_mov_b32_dpp v94, v78 quad_perm:[2,3,0,1] row_mask:0xf bank_mask:0xf
	v_sub_f32_e32 v46, v46, v148
	v_mul_f32_e32 v46, 0x3fb8aa3b, v46
	v_exp_f32_e32 v79, v46
	v_mul_f32_e32 v62, 0x3fb8aa3b, v62
	v_max_f32_e32 v46, v94, v94
	v_max_f32_e32 v46, v78, v46
	v_exp_f32_e32 v95, v62
	s_nop 1
	v_mov_b32_dpp v62, v46 quad_perm:[1,0,3,2] row_mask:0xf bank_mask:0xf
	v_sub_f32_e32 v144, v144, v148
	v_mul_f32_e32 v78, 0x3fb8aa3b, v144
	v_exp_f32_e32 v144, v78
	v_mul_f32_e32 v47, 0x3fb8aa3b, v47
	v_max3_f32 v147, v145, v46, v62
	v_sub_f32_e32 v78, v219, v147
	v_mul_f32_e32 v78, 0x3fb8aa3b, v78
	v_sub_f32_e32 v46, v217, v147
	v_sub_f32_e32 v62, v218, v147
	v_exp_f32_e32 v94, v78
	v_sub_f32_e32 v78, v96, v147
	v_sub_f32_e32 v145, v145, v147
	v_mul_f32_e32 v46, 0x3fb8aa3b, v46
	v_mul_f32_e32 v62, 0x3fb8aa3b, v62
	v_mul_f32_e32 v78, 0x3fb8aa3b, v78
	v_exp_f32_e32 v47, v47
	v_exp_f32_e32 v46, v46
	v_exp_f32_e32 v62, v62
	v_exp_f32_e32 v78, v78
	v_mul_f32_e32 v96, 0x3fb8aa3b, v145
	v_exp_f32_e32 v137, v137
	v_exp_f32_e32 v139, v139
	v_exp_f32_e32 v141, v141
	v_exp_f32_e32 v143, v143
	v_exp_f32_e32 v145, v96
	v_cvt_pk_bf16_f32 v208, v47, v63
	v_cvt_pk_bf16_f32 v209, v95, v79
	v_cvt_pk_bf16_f32 v210, v46, v62
	v_cvt_pk_bf16_f32 v211, v94, v78
	v_add_u32_e32 v96, 0xa400, v186
	ds_write2_b64 v96, v[208:209], v[210:211] offset0:116 offset1:150
	v_pk_mul_f32 v[14:15], v[14:15], v[144:145]
	v_pk_mul_f32 v[12:13], v[12:13], v[142:143]
	v_pk_mul_f32 v[10:11], v[10:11], v[140:141]
	v_pk_mul_f32 v[8:9], v[8:9], v[138:139]
	v_pk_mul_f32 v[6:7], v[6:7], v[136:137]
	v_pk_mul_f32 v[4:5], v[4:5], v[134:135]
	v_pk_mul_f32 v[2:3], v[2:3], v[132:133]
	v_pk_mul_f32 v[0:1], v[0:1], v[130:131]
	v_pk_mul_f32 v[30:31], v[30:31], v[144:145]
	v_pk_mul_f32 v[28:29], v[28:29], v[142:143]
	v_pk_mul_f32 v[26:27], v[26:27], v[140:141]
	v_pk_mul_f32 v[24:25], v[24:25], v[138:139]
	v_pk_mul_f32 v[22:23], v[22:23], v[136:137]
	v_pk_mul_f32 v[20:21], v[20:21], v[134:135]
	v_pk_mul_f32 v[18:19], v[18:19], v[132:133]
	v_pk_mul_f32 v[16:17], v[16:17], v[130:131]
	s_mov_b32 s2, -16
	v_mov_b32_e32 v96, v185
	v_mov_b32_e32 v208, v184
	s_branch .Latt_join

.LBB0_824:
	v_mov_b32_e32 v51, v162
	s_and_b32 s2, s6, 7
	s_lshl_b32 s13, s2, 6
	v_lshlrev_b32_e32 v68, 3, v51
	v_and_b32_e32 v50, 56, v68
	v_or_b32_e32 v14, s13, v50
	v_readlane_b32 s3, v248, 18
	v_readlane_b32 s16, v251, 4
	v_readlane_b32 s22, v251, 10
	v_or_b32_e32 v0, s3, v14
	v_readlane_b32 s23, v251, 11
	v_mov_b32_e32 v1, v97
	v_or_b32_e32 v96, s34, v14
	v_readlane_b32 s24, v251, 12
	v_readlane_b32 s25, v251, 13
	v_lshl_add_u64 v[8:9], v[0:1], 2, s[22:23]
	s_mov_b64 s[8:9], 0x1000
	v_lshl_add_u64 v[2:3], v[96:97], 2, s[24:25]
	v_lshl_add_u64 v[10:11], v[8:9], 0, s[8:9]
	s_mov_b64 s[8:9], 0x1800
	s_movk_i32 s3, 0x1000
	s_barrier
	v_lshl_add_u64 v[12:13], v[8:9], 0, s[8:9]
	global_load_dwordx4 v[4:7], v[2:3], off offset:16
	s_nop 0
	global_load_dwordx4 v[0:3], v[2:3], off
	s_nop 0
	global_load_dwordx4 v[44:47], v[8:9], off offset:16
	global_load_dwordx4 v[40:43], v[8:9], off
	global_load_dwordx4 v[36:39], v[8:9], off offset:2064
	global_load_dwordx4 v[32:35], v[8:9], off offset:2048
	v_add_co_u32_e32 v8, vcc, s3, v8
	s_add_i32 s3, s4, 0xffffff00
	s_nop 0
	v_addc_co_u32_e32 v9, vcc, 0, v9, vcc
	global_load_dwordx4 v[24:27], v[8:9], off
	global_load_dwordx4 v[16:19], v[8:9], off offset:2048
	global_load_dwordx4 v[28:31], v[10:11], off offset:16
	global_load_dwordx4 v[20:23], v[12:13], off offset:16
	s_and_b64 s[0:1], s[0:1], exec
	s_cselect_b32 s68, s4, s3
	v_ashrrev_i32_e32 v52, 3, v51
	v_readlane_b32 s0, v249, 7
	v_add_u32_e32 v53, s68, v52
	v_lshlrev_b32_e32 v96, 1, v14
	v_readlane_b32 s1, v249, 8
	v_add_u32_e32 v54, -2, v53
	v_cmp_lt_i32_e32 vcc, 1, v53
	v_lshl_add_u64 v[48:49], s[0:1], 0, v[96:97]
	v_cmp_gt_u32_e64 s[0:1], s39, v54
	s_and_b64 s[42:43], vcc, s[0:1]
	v_readlane_b32 s17, v251, 5
	v_readlane_b32 s18, v251, 6
	v_readlane_b32 s19, v251, 7
	v_readlane_b32 s20, v251, 8
	v_readlane_b32 s21, v251, 9
	v_readlane_b32 s26, v251, 14
	v_readlane_b32 s27, v251, 15
	v_readlane_b32 s28, v251, 16
	v_readlane_b32 s29, v251, 17
	v_readlane_b32 s30, v251, 18
	v_readlane_b32 s31, v251, 19
	s_waitcnt vmcnt(8)
	v_mov_b64_e32 v[8:9], v[0:1]
	v_mov_b32_e32 v206, 0
	v_mov_b32_e32 v207, 0
	v_mov_b32_e32 v208, 0
	v_mov_b32_e32 v209, 0
	s_and_saveexec_b64 s[0:1], s[42:43]
	s_cbranch_execz .Lrg17_i
	v_add_u32_e32 v8, s38, v54
	v_mad_u64_u32 v[8:9], s[42:43], v8, s74, v[48:49]
	global_load_dwordx4 v[206:209], v[8:9], off

.Lrg20_i:
	s_or_b64 exec, exec, s[0:1]
	s_waitcnt vmcnt(0)
	s_nop 0
	v_mov_b32_e32 v9, v207
	v_mov_b32_e32 v10, v208
	v_mov_b32_e32 v11, v209
	v_lshlrev_b32_e32 v54, 16, v206
	v_and_b32_e32 v55, 0xffff0000, v206
	v_lshlrev_b32_e32 v8, 16, v9
	v_and_b32_e32 v9, 0xffff0000, v9
	v_lshlrev_b32_e32 v12, 16, v10
	v_and_b32_e32 v13, 0xffff0000, v10
	v_lshlrev_b32_e32 v10, 16, v11
	v_and_b32_e32 v11, 0xffff0000, v11
	v_pk_fma_f32 v[14:15], v[46:47], v[10:11], v[6:7]
	v_pk_fma_f32 v[12:13], v[44:45], v[12:13], v[4:5]
	v_pk_fma_f32 v[10:11], v[42:43], v[8:9], v[2:3]
	v_pk_fma_f32 v[8:9], v[40:41], v[54:55], v[0:1]
	v_mov_b32_e32 v55, v211
	v_mov_b32_e32 v56, v212
	v_mov_b32_e32 v57, v213
	v_lshlrev_b32_e32 v58, 16, v210
	v_and_b32_e32 v59, 0xffff0000, v210
	v_lshlrev_b32_e32 v54, 16, v55
	v_and_b32_e32 v55, 0xffff0000, v55
	v_lshlrev_b32_e32 v60, 16, v56
	v_and_b32_e32 v61, 0xffff0000, v56
	v_lshlrev_b32_e32 v56, 16, v57
	v_and_b32_e32 v57, 0xffff0000, v57
	v_pk_fma_f32 v[14:15], v[38:39], v[56:57], v[14:15]
	v_pk_fma_f32 v[12:13], v[36:37], v[60:61], v[12:13]
	v_pk_fma_f32 v[10:11], v[34:35], v[54:55], v[10:11]
	v_pk_fma_f32 v[8:9], v[32:33], v[58:59], v[8:9]
	v_mov_b32_e32 v55, v215
	v_mov_b32_e32 v56, v216
	v_mov_b32_e32 v57, v217
	v_lshlrev_b32_e32 v58, 16, v214
	v_and_b32_e32 v59, 0xffff0000, v214
	v_lshlrev_b32_e32 v54, 16, v55
	v_and_b32_e32 v55, 0xffff0000, v55
	v_lshlrev_b32_e32 v60, 16, v56
	v_and_b32_e32 v61, 0xffff0000, v56
	v_lshlrev_b32_e32 v56, 16, v57
	v_and_b32_e32 v57, 0xffff0000, v57
	v_pk_fma_f32 v[14:15], v[30:31], v[56:57], v[14:15]
	v_pk_fma_f32 v[12:13], v[28:29], v[60:61], v[12:13]
	v_pk_fma_f32 v[10:11], v[26:27], v[54:55], v[10:11]
	v_pk_fma_f32 v[8:9], v[24:25], v[58:59], v[8:9]
	v_mov_b32_e32 v55, v219
	v_mov_b32_e32 v56, v220
	v_mov_b32_e32 v57, v221
	v_lshlrev_b32_e32 v58, 16, v218
	v_and_b32_e32 v59, 0xffff0000, v218
	v_lshlrev_b32_e32 v54, 16, v55
	v_and_b32_e32 v55, 0xffff0000, v55
	v_lshlrev_b32_e32 v60, 16, v56
	v_and_b32_e32 v61, 0xffff0000, v56
	v_lshlrev_b32_e32 v56, 16, v57
	v_and_b32_e32 v57, 0xffff0000, v57
	v_pk_fma_f32 v[14:15], v[22:23], v[56:57], v[14:15]
	v_pk_fma_f32 v[12:13], v[20:21], v[60:61], v[12:13]
	v_pk_fma_f32 v[10:11], v[18:19], v[54:55], v[10:11]
	v_pk_fma_f32 v[8:9], v[16:17], v[58:59], v[8:9]
	v_lshl_add_u32 v53, v50, 2, 0
	v_lshl_add_u32 v54, v52, 8, v53
	v_lshlrev_b32_e32 v50, 1, v50
	ds_write_b128 v54, v[8:11] offset:36864
	ds_write_b128 v54, v[12:15] offset:36880
	v_add_u32_e32 v54, 32, v52
	v_sub_u32_e32 v50, v53, v50
	v_add_u32_e32 v55, s68, v54
	v_cvt_pk_bf16_f32 v8, v8, v9
	v_cvt_pk_bf16_f32 v9, v10, v11
	v_cvt_pk_bf16_f32 v10, v12, v13
	v_cvt_pk_bf16_f32 v11, v14, v15
	v_mad_u64_u32 v[12:13], s[0:1], v52, s3, v[50:51]
	v_add_u32_e32 v56, -2, v55
	ds_write_b128 v12, v[8:11]
	v_cmp_lt_i32_e32 vcc, 1, v55
	v_cmp_gt_u32_e64 s[0:1], s39, v56
	s_and_b64 s[42:43], vcc, s[0:1]
	v_mov_b64_e32 v[8:9], v[0:1]
	v_mov_b32_e32 v206, 0
	v_mov_b32_e32 v207, 0
	v_mov_b32_e32 v208, 0
	v_mov_b32_e32 v209, 0
	s_and_saveexec_b64 s[0:1], s[42:43]
	s_cbranch_execz .Lrg21_i
	v_add_u32_e32 v8, s38, v56
	v_mad_u64_u32 v[8:9], s[42:43], v8, s74, v[48:49]
	global_load_dwordx4 v[206:209], v[8:9], off

.Lrg24_i:
	s_or_b64 exec, exec, s[0:1]
	s_waitcnt vmcnt(0)
	s_nop 0
	v_mov_b32_e32 v9, v207
	v_mov_b32_e32 v10, v208
	v_mov_b32_e32 v11, v209
	v_lshlrev_b32_e32 v56, 16, v206
	v_and_b32_e32 v57, 0xffff0000, v206
	v_lshlrev_b32_e32 v8, 16, v9
	v_and_b32_e32 v9, 0xffff0000, v9
	v_lshlrev_b32_e32 v12, 16, v10
	v_and_b32_e32 v13, 0xffff0000, v10
	v_lshlrev_b32_e32 v10, 16, v11
	v_and_b32_e32 v11, 0xffff0000, v11
	v_pk_fma_f32 v[14:15], v[46:47], v[10:11], v[6:7]
	v_pk_fma_f32 v[12:13], v[44:45], v[12:13], v[4:5]
	v_pk_fma_f32 v[10:11], v[42:43], v[8:9], v[2:3]
	v_pk_fma_f32 v[8:9], v[40:41], v[56:57], v[0:1]
	v_mov_b32_e32 v57, v211
	v_mov_b32_e32 v58, v212
	v_mov_b32_e32 v59, v213
	v_lshlrev_b32_e32 v60, 16, v210
	v_and_b32_e32 v61, 0xffff0000, v210
	v_lshlrev_b32_e32 v56, 16, v57
	v_and_b32_e32 v57, 0xffff0000, v57
	v_lshlrev_b32_e32 v62, 16, v58
	v_and_b32_e32 v63, 0xffff0000, v58
	v_lshlrev_b32_e32 v58, 16, v59
	v_and_b32_e32 v59, 0xffff0000, v59
	v_pk_fma_f32 v[14:15], v[38:39], v[58:59], v[14:15]
	v_pk_fma_f32 v[12:13], v[36:37], v[62:63], v[12:13]
	v_pk_fma_f32 v[10:11], v[34:35], v[56:57], v[10:11]
	v_pk_fma_f32 v[8:9], v[32:33], v[60:61], v[8:9]
	v_mov_b32_e32 v57, v215
	v_mov_b32_e32 v58, v216
	v_mov_b32_e32 v59, v217
	v_lshlrev_b32_e32 v60, 16, v214
	v_and_b32_e32 v61, 0xffff0000, v214
	v_lshlrev_b32_e32 v56, 16, v57
	v_and_b32_e32 v57, 0xffff0000, v57
	v_lshlrev_b32_e32 v62, 16, v58
	v_and_b32_e32 v63, 0xffff0000, v58
	v_lshlrev_b32_e32 v58, 16, v59
	v_and_b32_e32 v59, 0xffff0000, v59
	v_pk_fma_f32 v[14:15], v[30:31], v[58:59], v[14:15]
	v_pk_fma_f32 v[12:13], v[28:29], v[62:63], v[12:13]
	v_pk_fma_f32 v[10:11], v[26:27], v[56:57], v[10:11]
	v_pk_fma_f32 v[8:9], v[24:25], v[60:61], v[8:9]
	v_mov_b32_e32 v57, v219
	v_mov_b32_e32 v58, v220
	v_mov_b32_e32 v59, v221
	v_lshlrev_b32_e32 v60, 16, v218
	v_and_b32_e32 v61, 0xffff0000, v218
	v_lshlrev_b32_e32 v56, 16, v57
	v_and_b32_e32 v57, 0xffff0000, v57
	v_lshlrev_b32_e32 v62, 16, v58
	v_and_b32_e32 v63, 0xffff0000, v58
	v_lshlrev_b32_e32 v58, 16, v59
	v_and_b32_e32 v59, 0xffff0000, v59
	v_pk_fma_f32 v[14:15], v[22:23], v[58:59], v[14:15]
	v_pk_fma_f32 v[12:13], v[20:21], v[62:63], v[12:13]
	v_pk_fma_f32 v[10:11], v[18:19], v[56:57], v[10:11]
	v_pk_fma_f32 v[8:9], v[16:17], v[60:61], v[8:9]
	v_lshl_add_u32 v55, v54, 8, v53
	ds_write_b128 v55, v[8:11] offset:36864
	ds_write_b128 v55, v[12:15] offset:36880
	v_cvt_pk_bf16_f32 v8, v8, v9
	v_cvt_pk_bf16_f32 v9, v10, v11
	v_cvt_pk_bf16_f32 v10, v12, v13
	v_mad_u64_u32 v[12:13], s[0:1], v54, s3, v[50:51]
	v_add_u32_e32 v54, 64, v52
	v_add_u32_e32 v55, s68, v54
	v_cvt_pk_bf16_f32 v11, v14, v15
	v_add_u32_e32 v56, -2, v55
	ds_write_b128 v12, v[8:11]
	v_cmp_lt_i32_e32 vcc, 1, v55
	v_cmp_gt_u32_e64 s[0:1], s39, v56
	s_and_b64 s[42:43], vcc, s[0:1]
	v_mov_b64_e32 v[8:9], v[0:1]
	v_mov_b32_e32 v206, 0
	v_mov_b32_e32 v207, 0
	v_mov_b32_e32 v208, 0
	v_mov_b32_e32 v209, 0
	s_and_saveexec_b64 s[0:1], s[42:43]
	s_cbranch_execz .Lrg25_i
	v_add_u32_e32 v8, s38, v56
	v_mad_u64_u32 v[8:9], s[42:43], v8, s74, v[48:49]
	global_load_dwordx4 v[206:209], v[8:9], off

.LBB0_857:
	v_add_u32_e32 v2, s4, v0
	s_addk_i32 s4, 0x800
	v_mov_b32_e32 v222, v2
	v_ashrrev_i32_e32 v223, 31, v222
	v_lshlrev_b64 v[222:223], 2, v[222:223]
	v_lshl_add_u64 v[224:225], s[0:1], 0, v[222:223]
	global_load_dword v206, v[224:225], off
	global_load_dword v207, v[224:225], off offset:256
	v_lshl_add_u64 v[224:225], s[2:3], 0, v[222:223]
	global_load_dword v208, v[224:225], off
	global_load_dword v209, v[224:225], off offset:256
	v_add_u32_e32 v222, 0x200, v2
	v_ashrrev_i32_e32 v223, 31, v222
	v_lshlrev_b64 v[222:223], 2, v[222:223]
	v_lshl_add_u64 v[224:225], s[0:1], 0, v[222:223]
	global_load_dword v210, v[224:225], off
	global_load_dword v211, v[224:225], off offset:256
	v_lshl_add_u64 v[224:225], s[2:3], 0, v[222:223]
	global_load_dword v212, v[224:225], off
	global_load_dword v213, v[224:225], off offset:256
	v_add_u32_e32 v222, 0x400, v2
	v_ashrrev_i32_e32 v223, 31, v222
	v_lshlrev_b64 v[222:223], 2, v[222:223]
	v_lshl_add_u64 v[224:225], s[0:1], 0, v[222:223]
	global_load_dword v214, v[224:225], off
	global_load_dword v215, v[224:225], off offset:256
	v_lshl_add_u64 v[224:225], s[2:3], 0, v[222:223]
	global_load_dword v216, v[224:225], off
	global_load_dword v217, v[224:225], off offset:256
	v_add_u32_e32 v222, 0x600, v2
	v_ashrrev_i32_e32 v223, 31, v222
	v_lshlrev_b64 v[222:223], 2, v[222:223]
	v_lshl_add_u64 v[224:225], s[0:1], 0, v[222:223]
	global_load_dword v218, v[224:225], off
	global_load_dword v219, v[224:225], off offset:256
	v_lshl_add_u64 v[224:225], s[2:3], 0, v[222:223]
	global_load_dword v220, v[224:225], off
	global_load_dword v221, v[224:225], off offset:256
	v_add_u32_e32 v2, s4, v0
	s_addk_i32 s4, 0x800
	v_mov_b32_e32 v222, v2
	v_ashrrev_i32_e32 v223, 31, v222
	v_lshlrev_b64 v[222:223], 2, v[222:223]
	v_lshl_add_u64 v[224:225], s[0:1], 0, v[222:223]
	global_load_dword v10, v[224:225], off
	global_load_dword v11, v[224:225], off offset:256
	v_lshl_add_u64 v[224:225], s[2:3], 0, v[222:223]
	global_load_dword v12, v[224:225], off
	global_load_dword v13, v[224:225], off offset:256
	v_add_u32_e32 v222, 0x200, v2
	v_ashrrev_i32_e32 v223, 31, v222
	v_lshlrev_b64 v[222:223], 2, v[222:223]
	v_lshl_add_u64 v[224:225], s[0:1], 0, v[222:223]
	global_load_dword v14, v[224:225], off
	global_load_dword v15, v[224:225], off offset:256
	v_lshl_add_u64 v[224:225], s[2:3], 0, v[222:223]
	global_load_dword v16, v[224:225], off
	global_load_dword v17, v[224:225], off offset:256
	v_add_u32_e32 v222, 0x400, v2
	v_ashrrev_i32_e32 v223, 31, v222
	v_lshlrev_b64 v[222:223], 2, v[222:223]
	v_lshl_add_u64 v[224:225], s[0:1], 0, v[222:223]
	global_load_dword v18, v[224:225], off
	global_load_dword v19, v[224:225], off offset:256
	v_lshl_add_u64 v[224:225], s[2:3], 0, v[222:223]
	global_load_dword v20, v[224:225], off
	global_load_dword v21, v[224:225], off offset:256
	v_add_u32_e32 v222, 0x600, v2
	v_ashrrev_i32_e32 v223, 31, v222
	v_lshlrev_b64 v[222:223], 2, v[222:223]
	v_lshl_add_u64 v[224:225], s[0:1], 0, v[222:223]
	global_load_dword v22, v[224:225], off
	global_load_dword v23, v[224:225], off offset:256
	v_lshl_add_u64 v[224:225], s[2:3], 0, v[222:223]
	global_load_dword v24, v[224:225], off
	global_load_dword v25, v[224:225], off offset:256
	v_add_u32_e32 v9, 0x2400, v1
	s_waitcnt vmcnt(16)
	v_cvt_pk_bf16_f32 v226, v206, v207
	v_cvt_pk_bf16_f32 v230, v208, v209
	v_cvt_pk_bf16_f32 v227, v210, v211
	v_cvt_pk_bf16_f32 v231, v212, v213
	v_cvt_pk_bf16_f32 v228, v214, v215
	v_cvt_pk_bf16_f32 v232, v216, v217
	v_cvt_pk_bf16_f32 v229, v218, v219
	v_cvt_pk_bf16_f32 v233, v220, v221
	ds_write2_b32 v1, v226, v227 offset1:4
	ds_write2_b32 v9, v230, v231 offset1:4
	ds_write2_b32 v1, v228, v229 offset0:8 offset1:12
	ds_write2_b32 v9, v232, v233 offset0:8 offset1:12
	v_add_u32_e32 v1, 64, v1
	v_add_u32_e32 v9, 0x2400, v1
	s_waitcnt vmcnt(0)
	v_cvt_pk_bf16_f32 v226, v10, v11
	v_cvt_pk_bf16_f32 v230, v12, v13
	v_cvt_pk_bf16_f32 v227, v14, v15
	v_cvt_pk_bf16_f32 v231, v16, v17
	v_cvt_pk_bf16_f32 v228, v18, v19
	v_cvt_pk_bf16_f32 v232, v20, v21
	v_cvt_pk_bf16_f32 v229, v22, v23
	v_cvt_pk_bf16_f32 v233, v24, v25
	ds_write2_b32 v1, v226, v227 offset1:4
	ds_write2_b32 v9, v230, v231 offset1:4
	ds_write2_b32 v1, v228, v229 offset0:8 offset1:12
	ds_write2_b32 v9, v232, v233 offset0:8 offset1:12
	s_cmpk_eq_i32 s4, 0x1000
	v_and_b32_e32 v74, 31, v51
	v_mul_u32_u24_e32 v0, 0x48, v74
	v_lshrrev_b32_e32 v1, 1, v51
	v_lshlrev_b32_e32 v0, 1, v0
	v_and_b32_e32 v1, 16, v1
	s_movk_i32 s0, 0x1200
	v_add3_u32 v65, 0, v0, v1
	v_mov_b32_e32 v0, 0
	v_mul_lo_u32 v64, v66, s0
	s_mov_b32 s0, -16
	v_mov_b32_e32 v1, v0
	v_mov_b32_e32 v2, v0
	v_mov_b32_e32 v3, v0
	v_mov_b32_e32 v4, v0
	v_mov_b32_e32 v5, v0
	v_mov_b32_e32 v6, v0
	v_mov_b32_e32 v7, v0
	v_mov_b32_e32 v8, v0
	v_mov_b32_e32 v9, v0
	v_mov_b32_e32 v10, v0
	v_mov_b32_e32 v11, v0
	v_mov_b32_e32 v12, v0
	v_mov_b32_e32 v13, v0
	v_mov_b32_e32 v14, v0
	v_mov_b32_e32 v15, v0
	v_mov_b32_e32 v32, v0
	v_mov_b32_e32 v33, v0
	v_mov_b32_e32 v34, v0
	v_mov_b32_e32 v35, v0
	v_mov_b32_e32 v36, v0
	v_mov_b32_e32 v37, v0
	v_mov_b32_e32 v38, v0
	v_mov_b32_e32 v39, v0
	v_mov_b32_e32 v40, v0
	v_mov_b32_e32 v41, v0
	v_mov_b32_e32 v42, v0
	v_mov_b32_e32 v43, v0
	v_mov_b32_e32 v44, v0
	v_mov_b32_e32 v45, v0
	v_mov_b32_e32 v46, v0
	v_mov_b32_e32 v47, v0
	v_mov_b32_e32 v16, v0
	v_mov_b32_e32 v17, v0
	v_mov_b32_e32 v18, v0
	v_mov_b32_e32 v19, v0
	v_mov_b32_e32 v20, v0
	v_mov_b32_e32 v21, v0
	v_mov_b32_e32 v22, v0
	v_mov_b32_e32 v23, v0
	v_mov_b32_e32 v24, v0
	v_mov_b32_e32 v25, v0
	v_mov_b32_e32 v26, v0
	v_mov_b32_e32 v27, v0
	v_mov_b32_e32 v28, v0
	v_mov_b32_e32 v29, v0
	v_mov_b32_e32 v30, v0
	v_mov_b32_e32 v31, v0
	v_mov_b32_e32 v48, v0
	v_mov_b32_e32 v49, v0
	v_mov_b32_e32 v50, v0
	v_mov_b32_e32 v51, v0
	v_mov_b32_e32 v52, v0
	v_mov_b32_e32 v53, v0
	v_mov_b32_e32 v54, v0
	v_mov_b32_e32 v55, v0
	v_mov_b32_e32 v56, v0
	v_mov_b32_e32 v57, v0
	v_mov_b32_e32 v58, v0
	v_mov_b32_e32 v59, v0
	v_mov_b32_e32 v60, v0
	v_mov_b32_e32 v61, v0
	v_mov_b32_e32 v62, v0
	v_mov_b32_e32 v63, v0
	s_waitcnt lgkmcnt(0)
	s_barrier
.LBB0_859:
	v_add_u32_e32 v67, v65, v64
	ds_read_b128 v[76:79], v65 offset:18432
	ds_read_b128 v[80:83], v67
	s_add_i32 s0, s0, 32
	s_cmp_lt_u32 s0, 48
	s_waitcnt lgkmcnt(0)
	v_mfma_f32_32x32x16_bf16 v[48:63], v[80:83], v[76:79], v[48:63]
	ds_read_b128 v[76:79], v65 offset:23040
	s_waitcnt lgkmcnt(0)
	v_mfma_f32_32x32x16_bf16 v[16:31], v[80:83], v[76:79], v[16:31]
	ds_read_b128 v[76:79], v65 offset:27648
	s_waitcnt lgkmcnt(0)
	v_mfma_f32_32x32x16_bf16 v[32:47], v[80:83], v[76:79], v[32:47]
	ds_read_b128 v[76:79], v65 offset:32256
	ds_read_b128 v[84:87], v65 offset:18464
	s_waitcnt lgkmcnt(1)
	v_mfma_f32_32x32x16_bf16 v[0:15], v[80:83], v[76:79], v[0:15]
	ds_read_b128 v[76:79], v67 offset:32
	ds_read_b128 v[80:83], v65 offset:23072
	s_waitcnt lgkmcnt(0)
	v_mfma_f32_32x32x16_bf16 v[16:31], v[76:79], v[80:83], v[16:31]
	ds_read_b128 v[80:83], v65 offset:27680
	s_waitcnt lgkmcnt(0)
	v_mfma_f32_32x32x16_bf16 v[32:47], v[76:79], v[80:83], v[32:47]
	ds_read_b128 v[80:83], v65 offset:32288
	v_add_u32_e32 v65, 64, v65
	v_mfma_f32_32x32x16_bf16 v[48:63], v[76:79], v[84:87], v[48:63]
	s_waitcnt lgkmcnt(0)
	v_mfma_f32_32x32x16_bf16 v[0:15], v[76:79], v[80:83], v[0:15]
	s_cbranch_scc1 .LBB0_859
	v_and_b32_e32 v141, 63, v72
	v_or_b32_e32 v140, s13, v141
	v_readlane_b32 s0, v249, 15
	v_lshlrev_b32_e32 v96, 3, v140
	v_readlane_b32 s1, v249, 16
	v_readlane_b32 s16, v251, 20
	v_lshlrev_b32_e32 v69, 11, v66
	v_lshl_add_u64 v[64:65], s[0:1], 0, v[96:97]
	v_readlane_b32 s0, v248, 25
	s_or_b32 s3, s13, s0
	v_or_b32_e32 v96, s3, v74
	v_lshlrev_b64 v[66:67], 2, v[96:97]
	v_readlane_b32 s18, v251, 22
	v_readlane_b32 s19, v251, 23
	s_barrier
	s_nop 0
	v_lshl_add_u64 v[70:71], s[18:19], 0, v[66:67]
	v_readlane_b32 s100, v251, 16
	v_readlane_b32 s101, v251, 17
	s_nop 1
	v_lshl_add_u64 v[220:221], s[100:101], 0, v[66:67]
	v_readlane_b32 s100, v251, 20
	v_readlane_b32 s101, v251, 21
	s_nop 1
	v_lshl_add_u64 v[222:223], s[100:101], 0, v[66:67]
	global_load_dword v224, v[220:221], off
	global_load_dword v225, v[222:223], off
	global_load_dword v226, v[70:71], off offset:128
	global_load_dword v227, v[222:223], off offset:128
	global_load_dword v228, v[220:221], off offset:128
	global_load_dword v70, v[70:71], off
	s_mov_b32 s4, 0x3f2aaaab
	s_mov_b32 s8, 0x3f317218
	v_readlane_b32 s40, v251, 4
	v_readlane_b32 s52, v251, 16
	v_readlane_b32 s53, v251, 17
	v_readlane_b32 s17, v251, 21
	s_mov_b32 s9, 0x7f800000
	s_mov_b32 s10, 0x33800000
	s_mov_b32 s20, 0x43000000
	s_mov_b32 s21, 0x42b17217
	s_mov_b32 s22, 0xf800000
	s_mov_b32 s23, 0xc1880000
	s_mov_b32 s2, 0
	s_cmp_eq_u32 s12, 0
	v_readlane_b32 s24, v251, 28
	v_readlane_b32 s25, v251, 29
	v_readlane_b32 s26, v251, 30
	v_readlane_b32 s27, v251, 31
	v_readlane_b32 s28, v251, 32
	v_readlane_b32 s29, v251, 33
	v_readlane_b32 s30, v251, 34
	v_readlane_b32 s31, v251, 35
	v_readlane_b32 s41, v251, 5
	v_readlane_b32 s42, v251, 6
	v_readlane_b32 s43, v251, 7
	v_readlane_b32 s44, v251, 8
	v_readlane_b32 s45, v251, 9
	v_readlane_b32 s46, v251, 10
	v_readlane_b32 s47, v251, 11
	v_readlane_b32 s48, v251, 12
	v_readlane_b32 s49, v251, 13
	v_readlane_b32 s50, v251, 14
	v_readlane_b32 s51, v251, 15
	v_readlane_b32 s54, v251, 18
	v_readlane_b32 s55, v251, 19
	s_waitcnt vmcnt(0)
	v_mul_f32_e32 v70, 0xbfb8aa3b, v70
	v_exp_f32_e32 v73, v70
	s_nop 0
	v_add_f32_e32 v75, 1.0, v73
	v_add_f32_e32 v70, -1.0, v75
	v_sub_f32_e32 v71, v70, v75
	v_add_f32_e32 v71, 1.0, v71
	v_sub_f32_e32 v70, v73, v70
	v_add_f32_e32 v76, v70, v71
	v_frexp_mant_f32_e32 v70, v75
	v_cmp_gt_f32_e32 vcc, s4, v70
	v_cvt_f64_f32_e32 v[70:71], v75
	v_frexp_exp_i32_f64_e32 v70, v[70:71]
	v_subbrev_co_u32_e32 v82, vcc, 0, v70, vcc
	v_sub_u32_e32 v70, 0, v82
	v_ldexp_f32 v71, v75, v70
	v_add_f32_e32 v75, -1.0, v71
	v_add_f32_e32 v77, 1.0, v71
	v_ldexp_f32 v70, v76, v70
	v_add_f32_e32 v76, 1.0, v75
	v_add_f32_e32 v78, -1.0, v77
	v_sub_f32_e32 v76, v71, v76
	v_sub_f32_e32 v71, v71, v78
	v_add_f32_e32 v76, v70, v76
	v_add_f32_e32 v70, v70, v71
	v_add_f32_e32 v83, v77, v70
	v_rcp_f32_e32 v85, v83
	v_sub_f32_e32 v71, v83, v77
	v_sub_f32_e32 v84, v70, v71
	v_add_f32_e32 v71, v75, v76
	v_sub_f32_e32 v70, v71, v75
	v_mul_f32_e32 v86, v71, v85
	v_sub_f32_e32 v75, v76, v70
	v_mul_f32_e32 v76, v83, v86
	v_fma_f32 v78, v86, v83, -v76
	v_fmac_f32_e32 v78, v86, v84
	v_add_f32_e32 v70, v76, v78
	v_sub_f32_e32 v77, v71, v70
	v_pk_add_f32 v[80:81], v[70:71], v[76:77] neg_lo:[0,1] neg_hi:[0,1]
	v_mov_b32_e32 v79, v70
	v_pk_add_f32 v[70:71], v[80:81], v[78:79] neg_lo:[0,1] neg_hi:[0,1]
	v_cmp_neq_f32_e32 vcc, s9, v73
	v_add_f32_e32 v71, v75, v71
	v_add_f32_e32 v70, v70, v71
	v_add_f32_e32 v71, v77, v70
	v_mul_f32_e32 v75, v85, v71
	v_mul_f32_e32 v76, v83, v75
	v_fma_f32 v78, v75, v83, -v76
	v_fmac_f32_e32 v78, v75, v84
	v_sub_f32_e32 v77, v77, v71
	v_add_f32_e32 v83, v70, v77
	v_add_f32_e32 v70, v76, v78
	v_sub_f32_e32 v77, v71, v70
	v_pk_add_f32 v[80:81], v[70:71], v[76:77] neg_lo:[0,1] neg_hi:[0,1]
	v_mov_b32_e32 v79, v70
	v_pk_add_f32 v[70:71], v[80:81], v[78:79] neg_lo:[0,1] neg_hi:[0,1]
	v_add_f32_e32 v71, v83, v71
	v_add_f32_e32 v70, v70, v71
	v_add_f32_e32 v71, v86, v75
	v_add_f32_e32 v70, v77, v70
	v_sub_f32_e32 v76, v71, v86
	v_mul_f32_e32 v70, v85, v70
	v_sub_f32_e32 v75, v75, v76
	v_add_f32_e32 v75, v75, v70
	v_add_f32_e32 v76, v71, v75
	v_mul_f32_e32 v78, v76, v76
	v_fmamk_f32 v70, v78, 0x3e9b6dac, v191
	v_fmaak_f32 v169, v78, v70, 0x3f2aaada
	v_cvt_f32_i32_e32 v70, v82
	v_sub_f32_e32 v71, v76, v71
	v_sub_f32_e32 v71, v75, v71
	v_ldexp_f32 v75, v71, 1
	v_mul_f32_e32 v71, v76, v78
	v_pk_mul_f32 v[78:79], v[70:71], v[168:169]
	v_ldexp_f32 v77, v76, 1
	v_fma_f32 v76, v70, s8, -v78
	v_fmac_f32_e32 v76, 0xb102e308, v70
	v_pk_add_f32 v[70:71], v[78:79], v[76:77]
	v_mov_b32_e32 v80, v78
	v_sub_f32_e32 v77, v71, v77
	v_sub_f32_e32 v77, v79, v77
	v_add_f32_e32 v81, v75, v77
	v_pk_add_f32 v[78:79], v[70:71], v[78:79] neg_lo:[0,1] neg_hi:[0,1]
	v_pk_add_f32 v[82:83], v[70:71], v[80:81]
	v_mov_b32_e32 v77, v70
	v_mov_b32_e32 v79, v83
	v_pk_add_f32 v[84:85], v[76:77], v[78:79] neg_lo:[0,1] neg_hi:[0,1]
	v_pk_add_f32 v[76:77], v[76:77], v[78:79]
	v_mov_b32_e32 v80, v81
	v_pk_add_f32 v[78:79], v[76:77], v[70:71] op_sel:[1,0] op_sel_hi:[0,1] neg_lo:[0,1] neg_hi:[0,1]
	v_pk_add_f32 v[86:87], v[82:83], v[78:79] op_sel_hi:[1,0] neg_lo:[0,1] neg_hi:[0,1]
	v_mov_b32_e32 v82, v83
	v_mov_b32_e32 v83, v77
	v_pk_mov_b32 v[78:79], v[70:71], v[78:79] op_sel:[1,0]
	v_mov_b32_e32 v81, v70
	v_pk_add_f32 v[78:79], v[82:83], v[78:79] neg_lo:[0,1] neg_hi:[0,1]
	v_mov_b32_e32 v86, v84
	v_pk_add_f32 v[70:71], v[80:81], v[78:79] neg_lo:[0,1] neg_hi:[0,1]
	v_mov_b32_e32 v85, v77
	v_pk_add_f32 v[78:79], v[86:87], v[70:71]
	v_pk_add_f32 v[80:81], v[78:79], v[78:79] op_sel:[0,1] op_sel_hi:[1,0]
	v_pk_add_f32 v[76:77], v[76:77], v[80:81] op_sel:[1,0] op_sel_hi:[0,1]
	v_mov_b32_e32 v79, v76
	v_pk_add_f32 v[82:83], v[78:79], v[84:85] neg_lo:[0,1] neg_hi:[0,1]
	v_mov_b32_e32 v71, v80
	v_sub_f32_e32 v75, v78, v82
	v_pk_add_f32 v[70:71], v[70:71], v[82:83] neg_lo:[0,1] neg_hi:[0,1]
	v_sub_f32_e32 v75, v84, v75
	v_add_f32_e32 v70, v70, v75
	v_add_f32_e32 v70, v70, v71
	v_add_f32_e32 v70, v76, v70
	v_mov_b32_e32 v77, v224
	v_mov_b32_e32 v76, v225
	v_cndmask_b32_e32 v70, v199, v70, vcc
	v_cmp_ngt_f32_e32 vcc, -1.0, v73
	s_waitcnt vmcnt(1)
	v_add_f32_e32 v48, v48, v77
	v_mul_f32_e32 v48, 0xbfb8aa3b, v48
	v_exp_f32_e32 v48, v48
	v_cndmask_b32_e32 v70, v200, v70, vcc
	v_cmp_neq_f32_e32 vcc, -1.0, v73
	s_waitcnt vmcnt(0)
	v_add_f32_e32 v32, v32, v76
	v_add_f32_e32 v48, 1.0, v48
	v_rcp_f32_e32 v48, v48
	v_cndmask_b32_e32 v70, v201, v70, vcc
	v_cmp_lt_f32_e64 vcc, |v73|, s10
	v_mul_f32_e32 v32, 0xbfb8aa3b, v32
	v_exp_f32_e32 v32, v32
	v_cndmask_b32_e32 v70, v70, v73, vcc
	v_mul_f32_e32 v75, 0xc1000000, v70
	v_mul_f32_e32 v48, v48, v75
	v_mul_f32_e32 v66, 0x3fb8aa3b, v48
	v_add_f32_e32 v48, v48, v48
	v_exp_f32_e32 v70, v66
	v_mul_f32_e32 v66, 0x3fb8aa3b, v48
	v_rndne_f32_e32 v66, v66
	v_fmamk_f32 v67, v66, 0xbf317218, v48
	v_fmac_f32_e32 v67, 0x3102e308, v66
	v_fmamk_f32 v71, v67, 0x395133b1, v192
	v_cmp_eq_f32_e32 vcc, s20, v66
	v_cvt_i32_f32_e32 v66, v66
	v_fmaak_f32 v71, v67, v71, 0x3c0887f9
	v_fmaak_f32 v71, v67, v71, 0x3d2aaa81
	v_fmaak_f32 v71, v67, v71, 0x3e2aaaab
	v_fma_f32 v71, v67, v71, 0.5
	v_ldexp_f32 v66, 1.0, v66
	v_mul_f32_e32 v71, v67, v71
	v_cndmask_b32_e32 v66, v66, v202, vcc
	v_fmac_f32_e32 v67, v67, v71
	v_add_f32_e32 v71, -1.0, v66
	v_fmac_f32_e32 v71, v66, v67
	v_add_f32_e32 v66, v71, v71
	v_cndmask_b32_e32 v66, v71, v66, vcc
	v_cmp_nlt_f32_e32 vcc, s21, v48
	v_add_f32_e32 v32, 1.0, v32
	v_rcp_f32_e32 v32, v32
	v_cndmask_b32_e64 v66, v201, -v66, vcc
	v_cmp_gt_f32_e32 vcc, s22, v66
	v_mul_f32_e32 v67, 0x4f800000, v66
	v_add_f32_e32 v33, v33, v76
	v_cndmask_b32_e32 v66, v66, v67, vcc
	v_sqrt_f32_e32 v67, v66
	v_mul_f32_e32 v33, 0xbfb8aa3b, v33
	v_exp_f32_e32 v33, v33
	v_add_f32_e32 v34, v34, v76
	v_add_u32_e32 v71, -1, v67
	v_fma_f32 v73, -v71, v67, v66
	v_cmp_ge_f32_e64 s[0:1], 0, v73
	v_add_u32_e32 v73, 1, v67
	v_add_f32_e32 v33, 1.0, v33
	v_cndmask_b32_e64 v71, v67, v71, s[0:1]
	v_fma_f32 v67, -v73, v67, v66
	v_cmp_lt_f32_e64 s[0:1], 0, v67
	v_rcp_f32_e32 v33, v33
	v_mul_f32_e32 v34, 0xbfb8aa3b, v34
	v_cndmask_b32_e64 v67, v71, v73, s[0:1]
	v_mul_f32_e32 v71, 0x37800000, v67
	v_cndmask_b32_e32 v67, v67, v71, vcc
	v_cmp_class_f32_e32 vcc, v66, v193
	v_exp_f32_e32 v34, v34
	s_nop 0
	v_cndmask_b32_e32 v66, v67, v66, vcc
	v_cmp_ngt_f32_e32 vcc, s23, v48
	v_add_f32_e32 v34, 1.0, v34
	v_rcp_f32_e32 v34, v34
	v_cndmask_b32_e32 v48, 1.0, v66, vcc
	v_mul_f32_e32 v48, v32, v48
	v_and_b32_e32 v32, 0x100, v68
	v_or3_b32 v32, v69, v74, v32
	v_lshl_add_u32 v73, v32, 2, 0
	v_add_u32_e32 v32, 0x9000, v73
	ds_read2_b32 v[66:67], v32 offset1:32
	s_waitcnt lgkmcnt(0)
	v_mul_f32_e32 v48, v66, v48
	ds_write_b32 v73, v70
	ds_write_b32 v73, v48 offset:36864
	v_add_f32_e32 v48, v49, v77
	v_mul_f32_e32 v48, 0xbfb8aa3b, v48
	v_exp_f32_e32 v48, v48
	s_nop 0
	v_add_f32_e32 v48, 1.0, v48
	v_rcp_f32_e32 v48, v48
	s_nop 0
	v_mul_f32_e32 v48, v48, v75
	v_mul_f32_e32 v49, 0x3fb8aa3b, v48
	v_add_f32_e32 v48, v48, v48
	v_exp_f32_e32 v66, v49
	v_mul_f32_e32 v49, 0x3fb8aa3b, v48
	v_rndne_f32_e32 v49, v49
	v_fmamk_f32 v68, v49, 0xbf317218, v48
	v_fmac_f32_e32 v68, 0x3102e308, v49
	v_fmamk_f32 v69, v68, 0x395133b1, v192
	v_cmp_eq_f32_e32 vcc, s20, v49
	v_cvt_i32_f32_e32 v49, v49
	v_fmaak_f32 v69, v68, v69, 0x3c0887f9
	v_fmaak_f32 v69, v68, v69, 0x3d2aaa81
	v_fmaak_f32 v69, v68, v69, 0x3e2aaaab
	v_fma_f32 v69, v68, v69, 0.5
	v_ldexp_f32 v49, 1.0, v49
	v_mul_f32_e32 v69, v68, v69
	v_cndmask_b32_e32 v49, v49, v202, vcc
	v_fmac_f32_e32 v68, v68, v69
	v_add_f32_e32 v69, -1.0, v49
	v_fmac_f32_e32 v69, v49, v68
	v_add_f32_e32 v49, v69, v69
	v_cndmask_b32_e32 v49, v69, v49, vcc
	v_cmp_nlt_f32_e32 vcc, s21, v48
	s_nop 1
	v_cndmask_b32_e64 v49, v201, -v49, vcc
	v_cmp_gt_f32_e32 vcc, s22, v49
	v_mul_f32_e32 v68, 0x4f800000, v49
	s_nop 0
	v_cndmask_b32_e32 v49, v49, v68, vcc
	v_sqrt_f32_e32 v68, v49
	s_nop 0
	v_add_u32_e32 v69, -1, v68
	v_fma_f32 v70, -v69, v68, v49
	v_cmp_ge_f32_e64 s[0:1], 0, v70
	v_add_u32_e32 v70, 1, v68
	s_nop 0
	v_cndmask_b32_e64 v69, v68, v69, s[0:1]
	v_fma_f32 v68, -v70, v68, v49
	v_cmp_lt_f32_e64 s[0:1], 0, v68
	s_nop 1
	v_cndmask_b32_e64 v68, v69, v70, s[0:1]
	v_mul_f32_e32 v69, 0x37800000, v68
	v_cndmask_b32_e32 v68, v68, v69, vcc
	v_cmp_class_f32_e32 vcc, v49, v193
	s_nop 1
	v_cndmask_b32_e32 v49, v68, v49, vcc
	v_cmp_ngt_f32_e32 vcc, s23, v48
	s_nop 1
	v_cndmask_b32_e32 v48, 1.0, v49, vcc
	v_mul_f32_e32 v33, v33, v48
	ds_read2_b32 v[48:49], v32 offset0:64 offset1:96
	s_waitcnt lgkmcnt(0)
	v_mul_f32_e32 v33, v48, v33
	ds_write_b32 v73, v66 offset:256
	ds_write_b32 v73, v33 offset:37120
	v_add_f32_e32 v33, v50, v77
	v_mul_f32_e32 v33, 0xbfb8aa3b, v33
	v_exp_f32_e32 v33, v33
	s_nop 0
	v_add_f32_e32 v33, 1.0, v33
	v_rcp_f32_e32 v33, v33
	s_nop 0
	v_mul_f32_e32 v33, v33, v75
	v_mul_f32_e32 v48, 0x3fb8aa3b, v33
	v_add_f32_e32 v33, v33, v33
	v_mul_f32_e32 v50, 0x3fb8aa3b, v33
	v_rndne_f32_e32 v50, v50
	v_fmamk_f32 v66, v50, 0xbf317218, v33
	v_fmac_f32_e32 v66, 0x3102e308, v50
	v_fmamk_f32 v68, v66, 0x395133b1, v192
	v_cmp_eq_f32_e32 vcc, s20, v50
	v_cvt_i32_f32_e32 v50, v50
	v_fmaak_f32 v68, v66, v68, 0x3c0887f9
	v_fmaak_f32 v68, v66, v68, 0x3d2aaa81
	v_fmaak_f32 v68, v66, v68, 0x3e2aaaab
	v_fma_f32 v68, v66, v68, 0.5
	v_ldexp_f32 v50, 1.0, v50
	v_mul_f32_e32 v68, v66, v68
	v_cndmask_b32_e32 v50, v50, v202, vcc
	v_fmac_f32_e32 v66, v66, v68
	v_add_f32_e32 v68, -1.0, v50
	v_fmac_f32_e32 v68, v50, v66
	v_add_f32_e32 v50, v68, v68
	v_cndmask_b32_e32 v50, v68, v50, vcc
	v_cmp_nlt_f32_e32 vcc, s21, v33
	v_exp_f32_e32 v48, v48
	s_nop 0
	v_cndmask_b32_e64 v50, v201, -v50, vcc
	v_cmp_gt_f32_e32 vcc, s22, v50
	v_mul_f32_e32 v66, 0x4f800000, v50
	s_nop 0
	v_cndmask_b32_e32 v50, v50, v66, vcc
	v_sqrt_f32_e32 v66, v50
	s_nop 0
	v_add_u32_e32 v68, -1, v66
	v_fma_f32 v69, -v68, v66, v50
	v_cmp_ge_f32_e64 s[0:1], 0, v69
	v_add_u32_e32 v69, 1, v66
	s_nop 0
	v_cndmask_b32_e64 v68, v66, v68, s[0:1]
	v_fma_f32 v66, -v69, v66, v50
	v_cmp_lt_f32_e64 s[0:1], 0, v66
	s_nop 1
	v_cndmask_b32_e64 v66, v68, v69, s[0:1]
	v_mul_f32_e32 v68, 0x37800000, v66
	v_cndmask_b32_e32 v66, v66, v68, vcc
	ds_read2_b32 v[68:69], v32 offset0:128 offset1:160
	v_cmp_class_f32_e32 vcc, v50, v193
	s_nop 1
	v_cndmask_b32_e32 v50, v66, v50, vcc
	v_cmp_ngt_f32_e32 vcc, s23, v33
	s_nop 1
	v_cndmask_b32_e32 v33, 1.0, v50, vcc
	v_mul_f32_e32 v33, v34, v33
	s_waitcnt lgkmcnt(0)
	v_mul_f32_e32 v33, v68, v33
	ds_write_b32 v73, v48 offset:512
	ds_write_b32 v73, v33 offset:37376
	v_add_f32_e32 v33, v51, v77
	v_mul_f32_e32 v33, 0xbfb8aa3b, v33
	v_exp_f32_e32 v33, v33
	v_add_f32_e32 v34, v35, v76
	v_mul_f32_e32 v34, 0xbfb8aa3b, v34
	v_exp_f32_e32 v34, v34
	v_add_f32_e32 v33, 1.0, v33
	v_rcp_f32_e32 v33, v33
	v_add_f32_e32 v34, 1.0, v34
	v_rcp_f32_e32 v34, v34
	v_mul_f32_e32 v33, v33, v75
	v_mul_f32_e32 v35, 0x3fb8aa3b, v33
	v_add_f32_e32 v33, v33, v33
	v_mul_f32_e32 v48, 0x3fb8aa3b, v33
	v_rndne_f32_e32 v48, v48
	v_fmamk_f32 v50, v48, 0xbf317218, v33
	v_fmac_f32_e32 v50, 0x3102e308, v48
	v_fmamk_f32 v51, v50, 0x395133b1, v192
	v_cmp_eq_f32_e32 vcc, s20, v48
	v_cvt_i32_f32_e32 v48, v48
	v_fmaak_f32 v51, v50, v51, 0x3c0887f9
	v_fmaak_f32 v51, v50, v51, 0x3d2aaa81
	v_fmaak_f32 v51, v50, v51, 0x3e2aaaab
	v_fma_f32 v51, v50, v51, 0.5
	v_ldexp_f32 v48, 1.0, v48
	v_mul_f32_e32 v51, v50, v51
	v_cndmask_b32_e32 v48, v48, v202, vcc
	v_fmac_f32_e32 v50, v50, v51
	v_add_f32_e32 v51, -1.0, v48
	v_fmac_f32_e32 v51, v48, v50
	v_add_f32_e32 v48, v51, v51
	v_cndmask_b32_e32 v48, v51, v48, vcc
	v_cmp_nlt_f32_e32 vcc, s21, v33
	v_exp_f32_e32 v35, v35
	s_nop 0
	v_cndmask_b32_e64 v48, v201, -v48, vcc
	v_cmp_gt_f32_e32 vcc, s22, v48
	v_mul_f32_e32 v50, 0x4f800000, v48
	s_nop 0
	v_cndmask_b32_e32 v48, v48, v50, vcc
	v_sqrt_f32_e32 v50, v48
	s_nop 0
	v_add_u32_e32 v51, -1, v50
	v_fma_f32 v66, -v51, v50, v48
	v_cmp_ge_f32_e64 s[0:1], 0, v66
	v_add_u32_e32 v66, 1, v50
	s_nop 0
	v_cndmask_b32_e64 v51, v50, v51, s[0:1]
	v_fma_f32 v50, -v66, v50, v48
	v_cmp_lt_f32_e64 s[0:1], 0, v50
	s_nop 1
	v_cndmask_b32_e64 v50, v51, v66, s[0:1]
	v_mul_f32_e32 v51, 0x37800000, v50
	v_cndmask_b32_e32 v50, v50, v51, vcc
	v_cmp_class_f32_e32 vcc, v48, v193
	s_nop 1
	v_cndmask_b32_e32 v48, v50, v48, vcc
	ds_read2_b32 v[50:51], v32 offset0:192 offset1:224
	v_cmp_ngt_f32_e32 vcc, s23, v33
	s_nop 1
	v_cndmask_b32_e32 v33, 1.0, v48, vcc
	v_mul_f32_e32 v33, v34, v33
	s_waitcnt lgkmcnt(0)
	v_mul_f32_e32 v32, v50, v33
	ds_write_b32 v73, v35 offset:768
	ds_write_b32 v73, v32 offset:37632
	v_add_f32_e32 v32, v52, v77
	v_mul_f32_e32 v32, 0xbfb8aa3b, v32
	v_exp_f32_e32 v32, v32
	v_add_f32_e32 v33, v36, v76
	v_mul_f32_e32 v33, 0xbfb8aa3b, v33
	v_exp_f32_e32 v33, v33
	v_add_f32_e32 v32, 1.0, v32
	v_rcp_f32_e32 v32, v32
	v_add_f32_e32 v33, 1.0, v33
	v_rcp_f32_e32 v33, v33
	v_mul_f32_e32 v32, v32, v75
	v_mul_f32_e32 v34, 0x3fb8aa3b, v32
	v_add_f32_e32 v32, v32, v32
	v_mul_f32_e32 v35, 0x3fb8aa3b, v32
	v_rndne_f32_e32 v35, v35
	v_fmamk_f32 v36, v35, 0xbf317218, v32
	v_fmac_f32_e32 v36, 0x3102e308, v35
	v_fmamk_f32 v48, v36, 0x395133b1, v192
	v_cmp_eq_f32_e32 vcc, s20, v35
	v_cvt_i32_f32_e32 v35, v35
	v_fmaak_f32 v48, v36, v48, 0x3c0887f9
	v_fmaak_f32 v48, v36, v48, 0x3d2aaa81
	v_fmaak_f32 v48, v36, v48, 0x3e2aaaab
	v_fma_f32 v48, v36, v48, 0.5
	v_ldexp_f32 v35, 1.0, v35
	v_mul_f32_e32 v48, v36, v48
	v_cndmask_b32_e32 v35, v35, v202, vcc
	v_fmac_f32_e32 v36, v36, v48
	v_add_f32_e32 v48, -1.0, v35
	v_fmac_f32_e32 v48, v35, v36
	v_add_f32_e32 v35, v48, v48
	v_cndmask_b32_e32 v35, v48, v35, vcc
	v_cmp_nlt_f32_e32 vcc, s21, v32
	v_exp_f32_e32 v34, v34
	s_nop 0
	v_cndmask_b32_e64 v35, v201, -v35, vcc
	v_cmp_gt_f32_e32 vcc, s22, v35
	v_mul_f32_e32 v36, 0x4f800000, v35
	s_nop 0
	v_cndmask_b32_e32 v35, v35, v36, vcc
	v_sqrt_f32_e32 v36, v35
	s_nop 0
	v_add_u32_e32 v48, -1, v36
	v_fma_f32 v50, -v48, v36, v35
	v_cmp_ge_f32_e64 s[0:1], 0, v50
	v_add_u32_e32 v50, 1, v36
	s_nop 0
	v_cndmask_b32_e64 v48, v36, v48, s[0:1]
	v_fma_f32 v36, -v50, v36, v35
	v_cmp_lt_f32_e64 s[0:1], 0, v36
	s_nop 1
	v_cndmask_b32_e64 v36, v48, v50, s[0:1]
	v_mul_f32_e32 v48, 0x37800000, v36
	v_cndmask_b32_e32 v36, v36, v48, vcc
	v_cmp_class_f32_e32 vcc, v35, v193
	s_nop 1
	v_cndmask_b32_e32 v35, v36, v35, vcc
	v_cmp_ngt_f32_e32 vcc, s23, v32
	s_nop 1
	v_cndmask_b32_e32 v32, 1.0, v35, vcc
	v_mul_f32_e32 v33, v33, v32
	v_add_u32_e32 v32, 0x9800, v73
	ds_read2_b32 v[70:71], v32 offset1:32
	s_waitcnt lgkmcnt(0)
	v_mul_f32_e32 v33, v70, v33
	ds_write_b32 v73, v34 offset:2048
	ds_write_b32 v73, v33 offset:38912
	v_add_f32_e32 v33, v53, v77
	v_mul_f32_e32 v33, 0xbfb8aa3b, v33
	v_exp_f32_e32 v33, v33
	v_add_f32_e32 v34, v37, v76
	v_mul_f32_e32 v34, 0xbfb8aa3b, v34
	v_exp_f32_e32 v34, v34
	v_add_f32_e32 v33, 1.0, v33
	v_rcp_f32_e32 v33, v33
	v_add_f32_e32 v34, 1.0, v34
	v_rcp_f32_e32 v34, v34
	v_mul_f32_e32 v33, v33, v75
	v_mul_f32_e32 v35, 0x3fb8aa3b, v33
	v_add_f32_e32 v33, v33, v33
	v_mul_f32_e32 v36, 0x3fb8aa3b, v33
	v_rndne_f32_e32 v36, v36
	v_fmamk_f32 v37, v36, 0xbf317218, v33
	v_fmac_f32_e32 v37, 0x3102e308, v36
	v_fmamk_f32 v48, v37, 0x395133b1, v192
	v_cmp_eq_f32_e32 vcc, s20, v36
	v_cvt_i32_f32_e32 v36, v36
	v_fmaak_f32 v48, v37, v48, 0x3c0887f9
	v_fmaak_f32 v48, v37, v48, 0x3d2aaa81
	v_fmaak_f32 v48, v37, v48, 0x3e2aaaab
	v_fma_f32 v48, v37, v48, 0.5
	v_ldexp_f32 v36, 1.0, v36
	v_mul_f32_e32 v48, v37, v48
	v_cndmask_b32_e32 v36, v36, v202, vcc
	v_fmac_f32_e32 v37, v37, v48
	v_add_f32_e32 v48, -1.0, v36
	v_fmac_f32_e32 v48, v36, v37
	v_add_f32_e32 v36, v48, v48
	v_cndmask_b32_e32 v36, v48, v36, vcc
	v_cmp_nlt_f32_e32 vcc, s21, v33
	v_exp_f32_e32 v35, v35
	s_nop 0
	v_cndmask_b32_e64 v36, v201, -v36, vcc
	v_cmp_gt_f32_e32 vcc, s22, v36
	v_mul_f32_e32 v37, 0x4f800000, v36
	s_nop 0
	v_cndmask_b32_e32 v36, v36, v37, vcc
	v_sqrt_f32_e32 v37, v36
	s_nop 0
	v_add_u32_e32 v48, -1, v37
	v_fma_f32 v50, -v48, v37, v36
	v_cmp_ge_f32_e64 s[0:1], 0, v50
	v_add_u32_e32 v50, 1, v37
	s_nop 0
	v_cndmask_b32_e64 v48, v37, v48, s[0:1]
	v_fma_f32 v37, -v50, v37, v36
	v_cmp_lt_f32_e64 s[0:1], 0, v37
	s_nop 1
	v_cndmask_b32_e64 v37, v48, v50, s[0:1]
	v_mul_f32_e32 v48, 0x37800000, v37
	v_cndmask_b32_e32 v37, v37, v48, vcc
	v_cmp_class_f32_e32 vcc, v36, v193
	s_nop 1
	v_cndmask_b32_e32 v36, v37, v36, vcc
	v_cmp_ngt_f32_e32 vcc, s23, v33
	s_nop 1
	v_cndmask_b32_e32 v33, 1.0, v36, vcc
	ds_read2_b32 v[36:37], v32 offset0:64 offset1:96
	v_mul_f32_e32 v33, v34, v33
	v_add_f32_e32 v34, v38, v76
	v_mul_f32_e32 v34, 0xbfb8aa3b, v34
	v_exp_f32_e32 v34, v34
	s_waitcnt lgkmcnt(0)
	v_mul_f32_e32 v33, v36, v33
	ds_write_b32 v73, v35 offset:2304
	ds_write_b32 v73, v33 offset:39168
	v_add_f32_e32 v33, v54, v77
	v_mul_f32_e32 v33, 0xbfb8aa3b, v33
	v_exp_f32_e32 v33, v33
	v_add_f32_e32 v34, 1.0, v34
	v_rcp_f32_e32 v34, v34
	ds_read2_b32 v[52:53], v32 offset0:128 offset1:160
	v_add_f32_e32 v33, 1.0, v33
	v_rcp_f32_e32 v33, v33
	s_nop 0
	v_mul_f32_e32 v33, v33, v75
	v_mul_f32_e32 v35, 0x3fb8aa3b, v33
	v_add_f32_e32 v33, v33, v33
	v_mul_f32_e32 v36, 0x3fb8aa3b, v33
	v_rndne_f32_e32 v36, v36
	v_fmamk_f32 v38, v36, 0xbf317218, v33
	v_fmac_f32_e32 v38, 0x3102e308, v36
	v_fmamk_f32 v48, v38, 0x395133b1, v192
	v_cmp_eq_f32_e32 vcc, s20, v36
	v_cvt_i32_f32_e32 v36, v36
	v_fmaak_f32 v48, v38, v48, 0x3c0887f9
	v_fmaak_f32 v48, v38, v48, 0x3d2aaa81
	v_fmaak_f32 v48, v38, v48, 0x3e2aaaab
	v_fma_f32 v48, v38, v48, 0.5
	v_ldexp_f32 v36, 1.0, v36
	v_mul_f32_e32 v48, v38, v48
	v_cndmask_b32_e32 v36, v36, v202, vcc
	v_fmac_f32_e32 v38, v38, v48
	v_add_f32_e32 v48, -1.0, v36
	v_fmac_f32_e32 v48, v36, v38
	v_add_f32_e32 v36, v48, v48
	v_cndmask_b32_e32 v36, v48, v36, vcc
	v_cmp_nlt_f32_e32 vcc, s21, v33
	v_exp_f32_e32 v35, v35
	s_nop 0
	v_cndmask_b32_e64 v36, v201, -v36, vcc
	v_cmp_gt_f32_e32 vcc, s22, v36
	v_mul_f32_e32 v38, 0x4f800000, v36
	s_nop 0
	v_cndmask_b32_e32 v36, v36, v38, vcc
	v_sqrt_f32_e32 v38, v36
	s_nop 0
	v_add_u32_e32 v48, -1, v38
	v_fma_f32 v50, -v48, v38, v36
	v_cmp_ge_f32_e64 s[0:1], 0, v50
	v_add_u32_e32 v50, 1, v38
	s_nop 0
	v_cndmask_b32_e64 v48, v38, v48, s[0:1]
	v_fma_f32 v38, -v50, v38, v36
	v_cmp_lt_f32_e64 s[0:1], 0, v38
	s_nop 1
	v_cndmask_b32_e64 v38, v48, v50, s[0:1]
	v_mul_f32_e32 v48, 0x37800000, v38
	v_cndmask_b32_e32 v38, v38, v48, vcc
	v_cmp_class_f32_e32 vcc, v36, v193
	s_nop 1
	v_cndmask_b32_e32 v36, v38, v36, vcc
	v_cmp_ngt_f32_e32 vcc, s23, v33
	s_nop 1
	v_cndmask_b32_e32 v33, 1.0, v36, vcc
	v_mul_f32_e32 v33, v34, v33
	s_waitcnt lgkmcnt(0)
	v_mul_f32_e32 v33, v52, v33
	ds_write_b32 v73, v35 offset:2560
	ds_write_b32 v73, v33 offset:39424
	v_add_f32_e32 v33, v55, v77
	v_mul_f32_e32 v33, 0xbfb8aa3b, v33
	v_exp_f32_e32 v33, v33
	v_add_f32_e32 v34, v39, v76
	v_mul_f32_e32 v34, 0xbfb8aa3b, v34
	v_exp_f32_e32 v34, v34
	v_add_f32_e32 v33, 1.0, v33
	v_rcp_f32_e32 v33, v33
	v_add_f32_e32 v34, 1.0, v34
	v_rcp_f32_e32 v34, v34
	v_mul_f32_e32 v33, v33, v75
	v_mul_f32_e32 v35, 0x3fb8aa3b, v33
	v_add_f32_e32 v33, v33, v33
	v_mul_f32_e32 v36, 0x3fb8aa3b, v33
	v_rndne_f32_e32 v36, v36
	v_fmamk_f32 v38, v36, 0xbf317218, v33
	v_fmac_f32_e32 v38, 0x3102e308, v36
	v_fmamk_f32 v39, v38, 0x395133b1, v192
	v_cmp_eq_f32_e32 vcc, s20, v36
	v_cvt_i32_f32_e32 v36, v36
	v_fmaak_f32 v39, v38, v39, 0x3c0887f9
	v_fmaak_f32 v39, v38, v39, 0x3d2aaa81
	v_fmaak_f32 v39, v38, v39, 0x3e2aaaab
	v_fma_f32 v39, v38, v39, 0.5
	v_ldexp_f32 v36, 1.0, v36
	v_mul_f32_e32 v39, v38, v39
	v_cndmask_b32_e32 v36, v36, v202, vcc
	v_fmac_f32_e32 v38, v38, v39
	v_add_f32_e32 v39, -1.0, v36
	v_fmac_f32_e32 v39, v36, v38
	v_add_f32_e32 v36, v39, v39
	v_cndmask_b32_e32 v36, v39, v36, vcc
	v_cmp_nlt_f32_e32 vcc, s21, v33
	v_exp_f32_e32 v35, v35
	s_nop 0
	v_cndmask_b32_e64 v36, v201, -v36, vcc
	v_cmp_gt_f32_e32 vcc, s22, v36
	v_mul_f32_e32 v38, 0x4f800000, v36
	s_nop 0
	v_cndmask_b32_e32 v36, v36, v38, vcc
	v_sqrt_f32_e32 v38, v36
	s_nop 0
	v_add_u32_e32 v39, -1, v38
	v_fma_f32 v48, -v39, v38, v36
	v_cmp_ge_f32_e64 s[0:1], 0, v48
	v_add_u32_e32 v48, 1, v38
	s_nop 0
	v_cndmask_b32_e64 v39, v38, v39, s[0:1]
	v_fma_f32 v38, -v48, v38, v36
	v_cmp_lt_f32_e64 s[0:1], 0, v38
	s_nop 1
	v_cndmask_b32_e64 v38, v39, v48, s[0:1]
	v_mul_f32_e32 v39, 0x37800000, v38
	v_cndmask_b32_e32 v38, v38, v39, vcc
	v_cmp_class_f32_e32 vcc, v36, v193
	s_nop 1
	v_cndmask_b32_e32 v36, v38, v36, vcc
	ds_read2_b32 v[38:39], v32 offset0:192 offset1:224
	v_cmp_ngt_f32_e32 vcc, s23, v33
	s_nop 1
	v_cndmask_b32_e32 v33, 1.0, v36, vcc
	v_mul_f32_e32 v33, v34, v33
	s_waitcnt lgkmcnt(0)
	v_mul_f32_e32 v32, v38, v33
	ds_write_b32 v73, v35 offset:2816
	ds_write_b32 v73, v32 offset:39680
	v_add_f32_e32 v32, v56, v77
	v_mul_f32_e32 v32, 0xbfb8aa3b, v32
	v_exp_f32_e32 v32, v32
	v_add_f32_e32 v33, v40, v76
	v_mul_f32_e32 v33, 0xbfb8aa3b, v33
	v_exp_f32_e32 v33, v33
	v_add_f32_e32 v32, 1.0, v32
	v_rcp_f32_e32 v32, v32
	v_add_f32_e32 v33, 1.0, v33
	v_rcp_f32_e32 v33, v33
	v_mul_f32_e32 v32, v32, v75
	v_mul_f32_e32 v34, 0x3fb8aa3b, v32
	v_add_f32_e32 v32, v32, v32
	v_mul_f32_e32 v35, 0x3fb8aa3b, v32
	v_rndne_f32_e32 v35, v35
	v_fmamk_f32 v36, v35, 0xbf317218, v32
	v_fmac_f32_e32 v36, 0x3102e308, v35
	v_fmamk_f32 v38, v36, 0x395133b1, v192
	v_cmp_eq_f32_e32 vcc, s20, v35
	v_cvt_i32_f32_e32 v35, v35
	v_fmaak_f32 v38, v36, v38, 0x3c0887f9
	v_fmaak_f32 v38, v36, v38, 0x3d2aaa81
	v_fmaak_f32 v38, v36, v38, 0x3e2aaaab
	v_fma_f32 v38, v36, v38, 0.5
	v_ldexp_f32 v35, 1.0, v35
	v_mul_f32_e32 v38, v36, v38
	v_cndmask_b32_e32 v35, v35, v202, vcc
	v_fmac_f32_e32 v36, v36, v38
	v_add_f32_e32 v38, -1.0, v35
	v_fmac_f32_e32 v38, v35, v36
	v_add_f32_e32 v35, v38, v38
	v_cndmask_b32_e32 v35, v38, v35, vcc
	v_cmp_nlt_f32_e32 vcc, s21, v32
	v_exp_f32_e32 v34, v34
	s_nop 0
	v_cndmask_b32_e64 v35, v201, -v35, vcc
	v_cmp_gt_f32_e32 vcc, s22, v35
	v_mul_f32_e32 v36, 0x4f800000, v35
	s_nop 0
	v_cndmask_b32_e32 v35, v35, v36, vcc
	v_sqrt_f32_e32 v36, v35
	s_nop 0
	v_add_u32_e32 v38, -1, v36
	v_fma_f32 v40, -v38, v36, v35
	v_cmp_ge_f32_e64 s[0:1], 0, v40
	v_add_u32_e32 v40, 1, v36
	s_nop 0
	v_cndmask_b32_e64 v38, v36, v38, s[0:1]
	v_fma_f32 v36, -v40, v36, v35
	v_cmp_lt_f32_e64 s[0:1], 0, v36
	s_nop 1
	v_cndmask_b32_e64 v36, v38, v40, s[0:1]
	v_mul_f32_e32 v38, 0x37800000, v36
	v_cndmask_b32_e32 v36, v36, v38, vcc
	v_cmp_class_f32_e32 vcc, v35, v193
	s_nop 1
	v_cndmask_b32_e32 v35, v36, v35, vcc
	v_cmp_ngt_f32_e32 vcc, s23, v32
	s_nop 1
	v_cndmask_b32_e32 v32, 1.0, v35, vcc
	v_mul_f32_e32 v33, v33, v32
	v_add_u32_e32 v32, 0xa000, v73
	ds_read2_b32 v[54:55], v32 offset1:32
	s_waitcnt lgkmcnt(0)
	v_mul_f32_e32 v33, v54, v33
	ds_write_b32 v73, v34 offset:4096
	ds_write_b32 v73, v33 offset:40960
	v_add_f32_e32 v33, v57, v77
	v_mul_f32_e32 v33, 0xbfb8aa3b, v33
	v_exp_f32_e32 v33, v33
	v_add_f32_e32 v34, v41, v76
	v_mul_f32_e32 v34, 0xbfb8aa3b, v34
	v_exp_f32_e32 v34, v34
	v_add_f32_e32 v33, 1.0, v33
	v_rcp_f32_e32 v33, v33
	v_add_f32_e32 v34, 1.0, v34
	v_rcp_f32_e32 v34, v34
	v_mul_f32_e32 v33, v33, v75
	v_mul_f32_e32 v35, 0x3fb8aa3b, v33
	v_add_f32_e32 v33, v33, v33
	v_mul_f32_e32 v36, 0x3fb8aa3b, v33
	v_rndne_f32_e32 v36, v36
	v_fmamk_f32 v38, v36, 0xbf317218, v33
	v_fmac_f32_e32 v38, 0x3102e308, v36
	v_fmamk_f32 v40, v38, 0x395133b1, v192
	v_cmp_eq_f32_e32 vcc, s20, v36
	v_cvt_i32_f32_e32 v36, v36
	v_fmaak_f32 v40, v38, v40, 0x3c0887f9
	v_fmaak_f32 v40, v38, v40, 0x3d2aaa81
	v_fmaak_f32 v40, v38, v40, 0x3e2aaaab
	v_fma_f32 v40, v38, v40, 0.5
	v_ldexp_f32 v36, 1.0, v36
	v_mul_f32_e32 v40, v38, v40
	v_cndmask_b32_e32 v36, v36, v202, vcc
	v_fmac_f32_e32 v38, v38, v40
	v_add_f32_e32 v40, -1.0, v36
	v_fmac_f32_e32 v40, v36, v38
	v_add_f32_e32 v36, v40, v40
	v_cndmask_b32_e32 v36, v40, v36, vcc
	v_cmp_nlt_f32_e32 vcc, s21, v33
	v_exp_f32_e32 v35, v35
	s_nop 0
	v_cndmask_b32_e64 v36, v201, -v36, vcc
	v_cmp_gt_f32_e32 vcc, s22, v36
	v_mul_f32_e32 v38, 0x4f800000, v36
	s_nop 0
	v_cndmask_b32_e32 v36, v36, v38, vcc
	v_sqrt_f32_e32 v38, v36
	s_nop 0
	v_add_u32_e32 v40, -1, v38
	v_fma_f32 v41, -v40, v38, v36
	v_cmp_ge_f32_e64 s[0:1], 0, v41
	v_add_u32_e32 v41, 1, v38
	s_nop 0
	v_cndmask_b32_e64 v40, v38, v40, s[0:1]
	v_fma_f32 v38, -v41, v38, v36
	v_cmp_lt_f32_e64 s[0:1], 0, v38
	s_nop 1
	v_cndmask_b32_e64 v38, v40, v41, s[0:1]
	v_mul_f32_e32 v40, 0x37800000, v38
	v_cndmask_b32_e32 v38, v38, v40, vcc
	ds_read2_b32 v[40:41], v32 offset0:64 offset1:96
	v_cmp_class_f32_e32 vcc, v36, v193
	s_nop 1
	v_cndmask_b32_e32 v36, v38, v36, vcc
	v_cmp_ngt_f32_e32 vcc, s23, v33
	s_nop 1
	v_cndmask_b32_e32 v33, 1.0, v36, vcc
	v_mul_f32_e32 v33, v34, v33
	s_waitcnt lgkmcnt(0)
	v_mul_f32_e32 v33, v40, v33
	ds_write_b32 v73, v35 offset:4352
	ds_write_b32 v73, v33 offset:41216
	v_add_f32_e32 v33, v58, v77
	v_mul_f32_e32 v33, 0xbfb8aa3b, v33
	v_exp_f32_e32 v33, v33
	v_add_f32_e32 v34, v42, v76
	v_mul_f32_e32 v34, 0xbfb8aa3b, v34
	v_exp_f32_e32 v34, v34
	v_add_f32_e32 v33, 1.0, v33
	v_rcp_f32_e32 v33, v33
	ds_read2_b32 v[56:57], v32 offset0:128 offset1:160
	v_add_f32_e32 v34, 1.0, v34
	v_rcp_f32_e32 v34, v34
	v_mul_f32_e32 v33, v33, v75
	v_mul_f32_e32 v35, 0x3fb8aa3b, v33
	v_add_f32_e32 v33, v33, v33
	v_mul_f32_e32 v36, 0x3fb8aa3b, v33
	v_rndne_f32_e32 v36, v36
	v_fmamk_f32 v38, v36, 0xbf317218, v33
	v_fmac_f32_e32 v38, 0x3102e308, v36
	v_fmamk_f32 v40, v38, 0x395133b1, v192
	v_cmp_eq_f32_e32 vcc, s20, v36
	v_cvt_i32_f32_e32 v36, v36
	v_fmaak_f32 v40, v38, v40, 0x3c0887f9
	v_fmaak_f32 v40, v38, v40, 0x3d2aaa81
	v_fmaak_f32 v40, v38, v40, 0x3e2aaaab
	v_fma_f32 v40, v38, v40, 0.5
	v_ldexp_f32 v36, 1.0, v36
	v_mul_f32_e32 v40, v38, v40
	v_cndmask_b32_e32 v36, v36, v202, vcc
	v_fmac_f32_e32 v38, v38, v40
	v_add_f32_e32 v40, -1.0, v36
	v_fmac_f32_e32 v40, v36, v38
	v_add_f32_e32 v36, v40, v40
	v_cndmask_b32_e32 v36, v40, v36, vcc
	v_cmp_nlt_f32_e32 vcc, s21, v33
	v_exp_f32_e32 v35, v35
	s_nop 0
	v_cndmask_b32_e64 v36, v201, -v36, vcc
	v_cmp_gt_f32_e32 vcc, s22, v36
	v_mul_f32_e32 v38, 0x4f800000, v36
	s_nop 0
	v_cndmask_b32_e32 v36, v36, v38, vcc
	v_sqrt_f32_e32 v38, v36
	s_nop 0
	v_add_u32_e32 v40, -1, v38
	v_fma_f32 v42, -v40, v38, v36
	v_cmp_ge_f32_e64 s[0:1], 0, v42
	v_add_u32_e32 v42, 1, v38
	s_nop 0
	v_cndmask_b32_e64 v40, v38, v40, s[0:1]
	v_fma_f32 v38, -v42, v38, v36
	v_cmp_lt_f32_e64 s[0:1], 0, v38
	s_nop 1
	v_cndmask_b32_e64 v38, v40, v42, s[0:1]
	v_mul_f32_e32 v40, 0x37800000, v38
	v_cndmask_b32_e32 v38, v38, v40, vcc
	v_cmp_class_f32_e32 vcc, v36, v193
	s_nop 1
	v_cndmask_b32_e32 v36, v38, v36, vcc
	v_cmp_ngt_f32_e32 vcc, s23, v33
	s_nop 1
	v_cndmask_b32_e32 v33, 1.0, v36, vcc
	v_mul_f32_e32 v33, v34, v33
	s_waitcnt lgkmcnt(0)
	v_mul_f32_e32 v33, v56, v33
	ds_write_b32 v73, v35 offset:4608
	ds_write_b32 v73, v33 offset:41472
	v_add_f32_e32 v33, v59, v77
	v_mul_f32_e32 v33, 0xbfb8aa3b, v33
	v_exp_f32_e32 v33, v33
	v_add_f32_e32 v34, v43, v76
	v_mul_f32_e32 v34, 0xbfb8aa3b, v34
	v_exp_f32_e32 v34, v34
	v_add_f32_e32 v33, 1.0, v33
	v_rcp_f32_e32 v33, v33
	v_add_f32_e32 v34, 1.0, v34
	v_rcp_f32_e32 v34, v34
	v_mul_f32_e32 v33, v33, v75
	v_mul_f32_e32 v35, 0x3fb8aa3b, v33
	v_add_f32_e32 v33, v33, v33
	v_mul_f32_e32 v36, 0x3fb8aa3b, v33
	v_rndne_f32_e32 v36, v36
	v_fmamk_f32 v38, v36, 0xbf317218, v33
	v_fmac_f32_e32 v38, 0x3102e308, v36
	v_fmamk_f32 v40, v38, 0x395133b1, v192
	v_cmp_eq_f32_e32 vcc, s20, v36
	v_cvt_i32_f32_e32 v36, v36
	v_fmaak_f32 v40, v38, v40, 0x3c0887f9
	v_fmaak_f32 v40, v38, v40, 0x3d2aaa81
	v_fmaak_f32 v40, v38, v40, 0x3e2aaaab
	v_fma_f32 v40, v38, v40, 0.5
	v_ldexp_f32 v36, 1.0, v36
	v_mul_f32_e32 v40, v38, v40
	v_cndmask_b32_e32 v36, v36, v202, vcc
	v_fmac_f32_e32 v38, v38, v40
	v_add_f32_e32 v40, -1.0, v36
	v_fmac_f32_e32 v40, v36, v38
	v_add_f32_e32 v36, v40, v40
	v_cndmask_b32_e32 v36, v40, v36, vcc
	v_cmp_nlt_f32_e32 vcc, s21, v33
	v_exp_f32_e32 v35, v35
	s_nop 0
	v_cndmask_b32_e64 v36, v201, -v36, vcc
	v_cmp_gt_f32_e32 vcc, s22, v36
	v_mul_f32_e32 v38, 0x4f800000, v36
	s_nop 0
	v_cndmask_b32_e32 v36, v36, v38, vcc
	v_sqrt_f32_e32 v38, v36
	s_nop 0
	v_add_u32_e32 v40, -1, v38
	v_fma_f32 v42, -v40, v38, v36
	v_cmp_ge_f32_e64 s[0:1], 0, v42
	v_add_u32_e32 v42, 1, v38
	s_nop 0
	v_cndmask_b32_e64 v40, v38, v40, s[0:1]
	v_fma_f32 v38, -v42, v38, v36
	v_cmp_lt_f32_e64 s[0:1], 0, v38
	s_nop 1
	v_cndmask_b32_e64 v38, v40, v42, s[0:1]
	v_mul_f32_e32 v40, 0x37800000, v38
	ds_read2_b32 v[42:43], v32 offset0:192 offset1:224
	v_cndmask_b32_e32 v38, v38, v40, vcc
	v_cmp_class_f32_e32 vcc, v36, v193
	s_nop 1
	v_cndmask_b32_e32 v36, v38, v36, vcc
	v_cmp_ngt_f32_e32 vcc, s23, v33
	s_nop 1
	v_cndmask_b32_e32 v33, 1.0, v36, vcc
	v_mul_f32_e32 v33, v34, v33
	s_waitcnt lgkmcnt(0)
	v_mul_f32_e32 v32, v42, v33
	ds_write_b32 v73, v35 offset:4864
	ds_write_b32 v73, v32 offset:41728
	v_add_f32_e32 v32, v60, v77
	v_mul_f32_e32 v32, 0xbfb8aa3b, v32
	v_exp_f32_e32 v32, v32
	v_add_f32_e32 v33, v44, v76
	v_mul_f32_e32 v33, 0xbfb8aa3b, v33
	v_exp_f32_e32 v33, v33
	v_add_f32_e32 v32, 1.0, v32
	v_rcp_f32_e32 v32, v32
	v_add_f32_e32 v33, 1.0, v33
	v_rcp_f32_e32 v33, v33
	v_mul_f32_e32 v32, v32, v75
	v_mul_f32_e32 v34, 0x3fb8aa3b, v32
	v_add_f32_e32 v32, v32, v32
	v_mul_f32_e32 v35, 0x3fb8aa3b, v32
	v_rndne_f32_e32 v35, v35
	v_fmamk_f32 v36, v35, 0xbf317218, v32
	v_fmac_f32_e32 v36, 0x3102e308, v35
	v_fmamk_f32 v38, v36, 0x395133b1, v192
	v_cmp_eq_f32_e32 vcc, s20, v35
	v_cvt_i32_f32_e32 v35, v35
	v_fmaak_f32 v38, v36, v38, 0x3c0887f9
	v_fmaak_f32 v38, v36, v38, 0x3d2aaa81
	v_fmaak_f32 v38, v36, v38, 0x3e2aaaab
	v_fma_f32 v38, v36, v38, 0.5
	v_ldexp_f32 v35, 1.0, v35
	v_mul_f32_e32 v38, v36, v38
	v_cndmask_b32_e32 v35, v35, v202, vcc
	v_fmac_f32_e32 v36, v36, v38
	v_add_f32_e32 v38, -1.0, v35
	v_fmac_f32_e32 v38, v35, v36
	v_add_f32_e32 v35, v38, v38
	v_cndmask_b32_e32 v35, v38, v35, vcc
	v_cmp_nlt_f32_e32 vcc, s21, v32
	v_exp_f32_e32 v34, v34
	s_nop 0
	v_cndmask_b32_e64 v35, v201, -v35, vcc
	v_cmp_gt_f32_e32 vcc, s22, v35
	v_mul_f32_e32 v36, 0x4f800000, v35
	s_nop 0
	v_cndmask_b32_e32 v35, v35, v36, vcc
	v_sqrt_f32_e32 v36, v35
	s_nop 0
	v_add_u32_e32 v38, -1, v36
	v_fma_f32 v40, -v38, v36, v35
	v_cmp_ge_f32_e64 s[0:1], 0, v40
	v_add_u32_e32 v40, 1, v36
	s_nop 0
	v_cndmask_b32_e64 v38, v36, v38, s[0:1]
	v_fma_f32 v36, -v40, v36, v35
	v_cmp_lt_f32_e64 s[0:1], 0, v36
	s_nop 1
	v_cndmask_b32_e64 v36, v38, v40, s[0:1]
	v_mul_f32_e32 v38, 0x37800000, v36
	v_cndmask_b32_e32 v36, v36, v38, vcc
	v_cmp_class_f32_e32 vcc, v35, v193
	s_nop 1
	v_cndmask_b32_e32 v35, v36, v35, vcc
	v_cmp_ngt_f32_e32 vcc, s23, v32
	s_nop 1
	v_cndmask_b32_e32 v32, 1.0, v35, vcc
	v_mul_f32_e32 v32, v33, v32
	v_add_u32_e32 v33, 0xa800, v73
	ds_read2_b32 v[58:59], v33 offset1:32
	s_waitcnt lgkmcnt(0)
	v_mul_f32_e32 v32, v58, v32
	ds_write_b32 v73, v34 offset:6144
	ds_write_b32 v73, v32 offset:43008
	v_add_f32_e32 v32, v61, v77
	v_mul_f32_e32 v32, 0xbfb8aa3b, v32
	v_exp_f32_e32 v32, v32
	v_add_f32_e32 v34, v45, v76
	v_mul_f32_e32 v34, 0xbfb8aa3b, v34
	v_exp_f32_e32 v34, v34
	v_add_f32_e32 v32, 1.0, v32
	v_rcp_f32_e32 v32, v32
	ds_read2_b32 v[44:45], v33 offset0:64 offset1:96
	v_add_f32_e32 v34, 1.0, v34
	v_rcp_f32_e32 v34, v34
	v_mul_f32_e32 v32, v32, v75
	v_mul_f32_e32 v35, 0x3fb8aa3b, v32
	v_add_f32_e32 v32, v32, v32
	v_mul_f32_e32 v36, 0x3fb8aa3b, v32
	v_rndne_f32_e32 v36, v36
	v_fmamk_f32 v38, v36, 0xbf317218, v32
	v_fmac_f32_e32 v38, 0x3102e308, v36
	v_fmamk_f32 v40, v38, 0x395133b1, v192
	v_cmp_eq_f32_e32 vcc, s20, v36
	v_cvt_i32_f32_e32 v36, v36
	v_fmaak_f32 v40, v38, v40, 0x3c0887f9
	v_fmaak_f32 v40, v38, v40, 0x3d2aaa81
	v_fmaak_f32 v40, v38, v40, 0x3e2aaaab
	v_fma_f32 v40, v38, v40, 0.5
	v_ldexp_f32 v36, 1.0, v36
	v_mul_f32_e32 v40, v38, v40
	v_cndmask_b32_e32 v36, v36, v202, vcc
	v_fmac_f32_e32 v38, v38, v40
	v_add_f32_e32 v40, -1.0, v36
	v_fmac_f32_e32 v40, v36, v38
	v_add_f32_e32 v36, v40, v40
	v_cndmask_b32_e32 v36, v40, v36, vcc
	v_cmp_nlt_f32_e32 vcc, s21, v32
	v_exp_f32_e32 v35, v35
	s_nop 0
	v_cndmask_b32_e64 v36, v201, -v36, vcc
	v_cmp_gt_f32_e32 vcc, s22, v36
	v_mul_f32_e32 v38, 0x4f800000, v36
	s_nop 0
	v_cndmask_b32_e32 v36, v36, v38, vcc
	v_sqrt_f32_e32 v38, v36
	s_nop 0
	v_add_u32_e32 v40, -1, v38
	v_fma_f32 v42, -v40, v38, v36
	v_cmp_ge_f32_e64 s[0:1], 0, v42
	v_add_u32_e32 v42, 1, v38
	s_nop 0
	v_cndmask_b32_e64 v40, v38, v40, s[0:1]
	v_fma_f32 v38, -v42, v38, v36
	v_cmp_lt_f32_e64 s[0:1], 0, v38
	s_nop 1
	v_cndmask_b32_e64 v38, v40, v42, s[0:1]
	v_mul_f32_e32 v40, 0x37800000, v38
	v_cndmask_b32_e32 v38, v38, v40, vcc
	v_cmp_class_f32_e32 vcc, v36, v193
	s_nop 1
	v_cndmask_b32_e32 v36, v38, v36, vcc
	v_cmp_ngt_f32_e32 vcc, s23, v32
	s_nop 1
	v_cndmask_b32_e32 v32, 1.0, v36, vcc
	v_mul_f32_e32 v32, v34, v32
	s_waitcnt lgkmcnt(0)
	v_mul_f32_e32 v32, v44, v32
	ds_write_b32 v73, v35 offset:6400
	ds_write_b32 v73, v32 offset:43264
	v_add_f32_e32 v32, v62, v77
	v_mul_f32_e32 v32, 0xbfb8aa3b, v32
	v_exp_f32_e32 v32, v32
	v_add_f32_e32 v34, v46, v76
	v_mul_f32_e32 v34, 0xbfb8aa3b, v34
	v_exp_f32_e32 v34, v34
	v_add_f32_e32 v32, 1.0, v32
	v_rcp_f32_e32 v32, v32
	v_add_f32_e32 v34, 1.0, v34
	v_rcp_f32_e32 v34, v34
	v_mul_f32_e32 v32, v32, v75
	v_mul_f32_e32 v35, 0x3fb8aa3b, v32
	v_add_f32_e32 v32, v32, v32
	v_exp_f32_e32 v36, v35
	v_mul_f32_e32 v35, 0x3fb8aa3b, v32
	v_rndne_f32_e32 v35, v35
	v_fmamk_f32 v38, v35, 0xbf317218, v32
	v_fmac_f32_e32 v38, 0x3102e308, v35
	v_fmamk_f32 v40, v38, 0x395133b1, v192
	v_cmp_eq_f32_e32 vcc, s20, v35
	v_cvt_i32_f32_e32 v35, v35
	v_fmaak_f32 v40, v38, v40, 0x3c0887f9
	v_fmaak_f32 v40, v38, v40, 0x3d2aaa81
	v_fmaak_f32 v40, v38, v40, 0x3e2aaaab
	v_fma_f32 v40, v38, v40, 0.5
	v_ldexp_f32 v35, 1.0, v35
	v_mul_f32_e32 v40, v38, v40
	v_cndmask_b32_e32 v35, v35, v202, vcc
	v_fmac_f32_e32 v38, v38, v40
	v_add_f32_e32 v40, -1.0, v35
	v_fmac_f32_e32 v40, v35, v38
	v_add_f32_e32 v35, v40, v40
	v_cndmask_b32_e32 v35, v40, v35, vcc
	v_cmp_nlt_f32_e32 vcc, s21, v32
	s_nop 1
	v_cndmask_b32_e64 v35, v201, -v35, vcc
	v_cmp_gt_f32_e32 vcc, s22, v35
	v_mul_f32_e32 v38, 0x4f800000, v35
	s_nop 0
	v_cndmask_b32_e32 v35, v35, v38, vcc
	v_sqrt_f32_e32 v38, v35
	s_nop 0
	v_add_u32_e32 v40, -1, v38
	v_fma_f32 v42, -v40, v38, v35
	v_cmp_ge_f32_e64 s[0:1], 0, v42
	v_add_u32_e32 v42, 1, v38
	s_nop 0
	v_cndmask_b32_e64 v40, v38, v40, s[0:1]
	v_fma_f32 v38, -v42, v38, v35
	v_cmp_lt_f32_e64 s[0:1], 0, v38
	s_nop 1
	v_cndmask_b32_e64 v38, v40, v42, s[0:1]
	v_mul_f32_e32 v40, 0x37800000, v38
	v_cndmask_b32_e32 v38, v38, v40, vcc
	v_cmp_class_f32_e32 vcc, v35, v193
	s_nop 1
	v_cndmask_b32_e32 v35, v38, v35, vcc
	v_cmp_ngt_f32_e32 vcc, s23, v32
	s_nop 1
	v_cndmask_b32_e32 v32, 1.0, v35, vcc
	v_mul_f32_e32 v32, v34, v32
	ds_read2_b32 v[34:35], v33 offset0:128 offset1:160
	s_waitcnt lgkmcnt(0)
	v_mul_f32_e32 v32, v34, v32
	ds_write_b32 v73, v36 offset:6656
	ds_write_b32 v73, v32 offset:43520
	v_add_f32_e32 v32, v63, v77
	v_mul_f32_e32 v32, 0xbfb8aa3b, v32
	v_exp_f32_e32 v32, v32
	v_add_f32_e32 v34, v47, v76
	v_mul_f32_e32 v34, 0xbfb8aa3b, v34
	v_exp_f32_e32 v34, v34
	v_add_f32_e32 v32, 1.0, v32
	v_rcp_f32_e32 v32, v32
	v_add_f32_e32 v34, 1.0, v34
	v_rcp_f32_e32 v36, v34
	v_mul_f32_e32 v32, v32, v75
	v_mul_f32_e32 v34, 0x3fb8aa3b, v32
	v_add_f32_e32 v32, v32, v32
	v_mul_f32_e32 v38, 0x3fb8aa3b, v32
	v_rndne_f32_e32 v38, v38
	v_fmamk_f32 v40, v38, 0xbf317218, v32
	v_fmac_f32_e32 v40, 0x3102e308, v38
	v_fmamk_f32 v42, v40, 0x395133b1, v192
	v_cmp_eq_f32_e32 vcc, s20, v38
	v_cvt_i32_f32_e32 v38, v38
	v_fmaak_f32 v42, v40, v42, 0x3c0887f9
	v_fmaak_f32 v42, v40, v42, 0x3d2aaa81
	v_fmaak_f32 v42, v40, v42, 0x3e2aaaab
	v_fma_f32 v42, v40, v42, 0.5
	v_ldexp_f32 v38, 1.0, v38
	v_mul_f32_e32 v42, v40, v42
	v_cndmask_b32_e32 v38, v38, v202, vcc
	v_fmac_f32_e32 v40, v40, v42
	v_add_f32_e32 v42, -1.0, v38
	v_fmac_f32_e32 v42, v38, v40
	v_add_f32_e32 v38, v42, v42
	v_cndmask_b32_e32 v38, v42, v38, vcc
	v_cmp_nlt_f32_e32 vcc, s21, v32
	s_nop 0
	v_exp_f32_e32 v34, v34
	v_cndmask_b32_e64 v38, v201, -v38, vcc
	v_cmp_gt_f32_e32 vcc, s22, v38
	v_mul_f32_e32 v40, 0x4f800000, v38
	s_nop 0
	v_cndmask_b32_e32 v38, v38, v40, vcc
	v_sqrt_f32_e32 v40, v38
	s_nop 0
	v_add_u32_e32 v42, -1, v40
	v_fma_f32 v44, -v42, v40, v38
	v_cmp_ge_f32_e64 s[0:1], 0, v44
	v_add_u32_e32 v44, 1, v40
	s_nop 0
	v_cndmask_b32_e64 v42, v40, v42, s[0:1]
	v_fma_f32 v40, -v44, v40, v38
	v_cmp_lt_f32_e64 s[0:1], 0, v40
	s_nop 1
	v_cndmask_b32_e64 v40, v42, v44, s[0:1]
	v_mul_f32_e32 v42, 0x37800000, v40
	v_cndmask_b32_e32 v40, v40, v42, vcc
	v_cmp_class_f32_e32 vcc, v38, v193
	s_nop 1
	v_cndmask_b32_e32 v38, v40, v38, vcc
	v_cmp_ngt_f32_e32 vcc, s23, v32
	s_nop 1
	v_cndmask_b32_e32 v32, 1.0, v38, vcc
	v_mul_f32_e32 v36, v36, v32
	ds_read2_b32 v[32:33], v33 offset0:192 offset1:224
	s_waitcnt lgkmcnt(0)
	v_mul_f32_e32 v32, v32, v36
	ds_write_b32 v73, v32 offset:43776
	s_waitcnt vmcnt(0)
	v_mul_f32_e32 v32, 0xbfb8aa3b, v226
	v_exp_f32_e32 v32, v32
	s_nop 0
	v_add_f32_e32 v36, 1.0, v32
	v_add_f32_e32 v38, -1.0, v36
	v_sub_f32_e32 v40, v38, v36
	v_add_f32_e32 v40, 1.0, v40
	v_sub_f32_e32 v38, v32, v38
	v_add_f32_e32 v38, v38, v40
	v_frexp_mant_f32_e32 v40, v36
	v_cvt_f64_f32_e32 v[60:61], v36
	v_cmp_gt_f32_e32 vcc, s4, v40
	v_frexp_exp_i32_f64_e32 v40, v[60:61]
	s_mul_i32 s4, s11, 0x24000
	v_subbrev_co_u32_e32 v40, vcc, 0, v40, vcc
	v_sub_u32_e32 v42, 0, v40
	v_ldexp_f32 v36, v36, v42
	v_ldexp_f32 v38, v38, v42
	v_add_f32_e32 v42, -1.0, v36
	v_add_f32_e32 v48, 1.0, v36
	v_add_f32_e32 v44, 1.0, v42
	v_add_f32_e32 v50, -1.0, v48
	v_sub_f32_e32 v44, v36, v44
	v_sub_f32_e32 v36, v36, v50
	v_add_f32_e32 v36, v38, v36
	v_add_f32_e32 v44, v38, v44
	v_add_f32_e32 v38, v48, v36
	v_sub_f32_e32 v48, v38, v48
	v_sub_f32_e32 v36, v36, v48
	v_rcp_f32_e32 v48, v38
	v_add_f32_e32 v61, v42, v44
	v_sub_f32_e32 v42, v61, v42
	v_sub_f32_e32 v42, v44, v42
	v_mul_f32_e32 v44, v61, v48
	v_mul_f32_e32 v62, v38, v44
	v_fma_f32 v74, v44, v38, -v62
	v_fmac_f32_e32 v74, v44, v36
	v_add_f32_e32 v60, v62, v74
	v_sub_f32_e32 v63, v61, v60
	v_pk_add_f32 v[76:77], v[60:61], v[62:63] neg_lo:[0,1] neg_hi:[0,1]
	v_mov_b32_e32 v75, v60
	v_pk_add_f32 v[60:61], v[76:77], v[74:75] neg_lo:[0,1] neg_hi:[0,1]
	v_cmp_neq_f32_e32 vcc, s9, v32
	v_add_f32_e32 v42, v42, v61
	v_add_f32_e32 v42, v60, v42
	v_add_f32_e32 v61, v63, v42
	v_mul_f32_e32 v50, v48, v61
	v_mul_f32_e32 v62, v38, v50
	v_fma_f32 v74, v50, v38, -v62
	v_fmac_f32_e32 v74, v50, v36
	v_add_f32_e32 v60, v62, v74
	v_sub_f32_e32 v36, v63, v61
	v_sub_f32_e32 v63, v61, v60
	v_pk_add_f32 v[76:77], v[60:61], v[62:63] neg_lo:[0,1] neg_hi:[0,1]
	v_mov_b32_e32 v75, v60
	v_add_f32_e32 v36, v42, v36
	v_pk_add_f32 v[60:61], v[76:77], v[74:75] neg_lo:[0,1] neg_hi:[0,1]
	v_add_f32_e32 v38, v44, v50
	v_add_f32_e32 v36, v36, v61
	v_add_f32_e32 v36, v60, v36
	v_add_f32_e32 v36, v63, v36
	v_sub_f32_e32 v42, v38, v44
	v_mul_f32_e32 v36, v48, v36
	v_sub_f32_e32 v42, v50, v42
	v_add_f32_e32 v36, v42, v36
	v_add_f32_e32 v42, v38, v36
	v_cvt_f32_i32_e32 v60, v40
	v_mul_f32_e32 v44, v42, v42
	v_fmamk_f32 v48, v44, 0x3e9b6dac, v191
	v_fmaak_f32 v169, v44, v48, 0x3f2aaada
	v_mul_f32_e32 v61, v42, v44
	v_pk_mul_f32 v[74:75], v[60:61], v[168:169]
	v_ldexp_f32 v63, v42, 1
	v_fma_f32 v62, v60, s8, -v74
	v_fmac_f32_e32 v62, 0xb102e308, v60
	v_sub_f32_e32 v38, v42, v38
	v_pk_add_f32 v[60:61], v[74:75], v[62:63]
	v_sub_f32_e32 v36, v36, v38
	v_sub_f32_e32 v38, v61, v63
	v_ldexp_f32 v36, v36, 1
	v_sub_f32_e32 v38, v75, v38
	v_add_f32_e32 v77, v36, v38
	v_mov_b32_e32 v76, v74
	v_pk_add_f32 v[74:75], v[60:61], v[74:75] neg_lo:[0,1] neg_hi:[0,1]
	v_pk_add_f32 v[78:79], v[60:61], v[76:77]
	v_mov_b32_e32 v63, v60
	v_mov_b32_e32 v75, v79
	v_pk_add_f32 v[80:81], v[62:63], v[74:75] neg_lo:[0,1] neg_hi:[0,1]
	v_pk_add_f32 v[62:63], v[62:63], v[74:75]
	v_mov_b32_e32 v76, v77
	v_pk_add_f32 v[74:75], v[62:63], v[60:61] op_sel:[1,0] op_sel_hi:[0,1] neg_lo:[0,1] neg_hi:[0,1]
	v_pk_add_f32 v[82:83], v[78:79], v[74:75] op_sel_hi:[1,0] neg_lo:[0,1] neg_hi:[0,1]
	v_mov_b32_e32 v78, v79
	v_mov_b32_e32 v79, v63
	v_pk_mov_b32 v[74:75], v[60:61], v[74:75] op_sel:[1,0]
	v_mov_b32_e32 v77, v60
	v_pk_add_f32 v[74:75], v[78:79], v[74:75] neg_lo:[0,1] neg_hi:[0,1]
	v_mov_b32_e32 v82, v80
	v_pk_add_f32 v[60:61], v[76:77], v[74:75] neg_lo:[0,1] neg_hi:[0,1]
	v_mov_b32_e32 v81, v63
	v_pk_add_f32 v[74:75], v[82:83], v[60:61]
	v_pk_add_f32 v[76:77], v[74:75], v[74:75] op_sel:[0,1] op_sel_hi:[1,0]
	v_pk_add_f32 v[62:63], v[62:63], v[76:77] op_sel:[1,0] op_sel_hi:[0,1]
	v_mov_b32_e32 v75, v62
	v_pk_add_f32 v[78:79], v[74:75], v[80:81] neg_lo:[0,1] neg_hi:[0,1]
	v_mov_b32_e32 v61, v76
	v_sub_f32_e32 v36, v74, v78
	v_pk_add_f32 v[60:61], v[60:61], v[78:79] neg_lo:[0,1] neg_hi:[0,1]
	v_sub_f32_e32 v36, v80, v36
	v_add_f32_e32 v36, v60, v36
	v_add_f32_e32 v36, v36, v61
	v_add_f32_e32 v36, v62, v36
	v_cndmask_b32_e32 v36, v199, v36, vcc
	v_cmp_ngt_f32_e32 vcc, -1.0, v32
	s_nop 0
	s_nop 0
	v_cndmask_b32_e32 v36, v200, v36, vcc
	v_cmp_neq_f32_e32 vcc, -1.0, v32
	v_mov_b32_e32 v38, v227
	s_waitcnt vmcnt(0)
	v_add_f32_e32 v0, v0, v38
	v_cndmask_b32_e32 v36, v201, v36, vcc
	v_cmp_lt_f32_e64 vcc, |v32|, s10
	v_mul_f32_e32 v0, 0xbfb8aa3b, v0
	v_exp_f32_e32 v0, v0
	v_cndmask_b32_e32 v32, v36, v32, vcc
	v_mov_b32_e32 v36, v228
	v_mul_f32_e32 v32, 0xc1000000, v32
	v_add_f32_e32 v0, 1.0, v0
	v_rcp_f32_e32 v0, v0
	v_add_f32_e32 v1, v1, v38
	v_mul_f32_e32 v1, 0xbfb8aa3b, v1
	v_exp_f32_e32 v1, v1
	s_waitcnt vmcnt(0)
	v_add_f32_e32 v16, v16, v36
	v_mul_f32_e32 v16, 0xbfb8aa3b, v16
	v_exp_f32_e32 v16, v16
	v_add_f32_e32 v1, 1.0, v1
	v_rcp_f32_e32 v1, v1
	v_add_f32_e32 v16, 1.0, v16
	v_rcp_f32_e32 v16, v16
	s_nop 0
	v_mul_f32_e32 v16, v16, v32
	v_mul_f32_e32 v40, 0x3fb8aa3b, v16
	v_add_f32_e32 v16, v16, v16
	v_mul_f32_e32 v42, 0x3fb8aa3b, v16
	v_rndne_f32_e32 v42, v42
	v_fmamk_f32 v44, v42, 0xbf317218, v16
	v_fmac_f32_e32 v44, 0x3102e308, v42
	v_fmamk_f32 v46, v44, 0x395133b1, v192
	v_cmp_eq_f32_e32 vcc, s20, v42
	v_cvt_i32_f32_e32 v42, v42
	v_fmaak_f32 v46, v44, v46, 0x3c0887f9
	v_fmaak_f32 v46, v44, v46, 0x3d2aaa81
	v_fmaak_f32 v46, v44, v46, 0x3e2aaaab
	v_fma_f32 v46, v44, v46, 0.5
	v_ldexp_f32 v42, 1.0, v42
	v_mul_f32_e32 v46, v44, v46
	v_cndmask_b32_e32 v42, v42, v202, vcc
	v_fmac_f32_e32 v44, v44, v46
	v_add_f32_e32 v46, -1.0, v42
	v_fmac_f32_e32 v46, v42, v44
	v_add_f32_e32 v42, v46, v46
	v_cndmask_b32_e32 v42, v46, v42, vcc
	v_cmp_nlt_f32_e32 vcc, s21, v16
	v_exp_f32_e32 v40, v40
	s_nop 0
	v_cndmask_b32_e64 v42, v201, -v42, vcc
	v_cmp_gt_f32_e32 vcc, s22, v42
	v_mul_f32_e32 v44, 0x4f800000, v42
	s_nop 0
	v_cndmask_b32_e32 v42, v42, v44, vcc
	v_sqrt_f32_e32 v44, v42
	s_nop 0
	v_add_u32_e32 v46, -1, v44
	v_fma_f32 v47, -v46, v44, v42
	v_cmp_ge_f32_e64 s[0:1], 0, v47
	v_add_u32_e32 v47, 1, v44
	s_nop 0
	v_cndmask_b32_e64 v46, v44, v46, s[0:1]
	v_fma_f32 v44, -v47, v44, v42
	v_cmp_lt_f32_e64 s[0:1], 0, v44
	s_nop 1
	v_cndmask_b32_e64 v44, v46, v47, s[0:1]
	v_mul_f32_e32 v46, 0x37800000, v44
	v_cndmask_b32_e32 v44, v44, v46, vcc
	v_cmp_class_f32_e32 vcc, v42, v193
	s_nop 1
	v_cndmask_b32_e32 v42, v44, v42, vcc
	v_cmp_ngt_f32_e32 vcc, s23, v16
	s_nop 1
	v_cndmask_b32_e32 v16, 1.0, v42, vcc
	v_mul_f32_e32 v0, v0, v16
	v_mul_f32_e32 v0, v67, v0
	ds_write_b32 v73, v40 offset:128
	ds_write_b32 v73, v0 offset:36992
	v_add_f32_e32 v0, v17, v36
	v_mul_f32_e32 v0, 0xbfb8aa3b, v0
	v_exp_f32_e32 v0, v0
	s_nop 0
	v_add_f32_e32 v0, 1.0, v0
	v_rcp_f32_e32 v0, v0
	s_nop 0
	v_mul_f32_e32 v0, v0, v32
	v_mul_f32_e32 v16, 0x3fb8aa3b, v0
	v_add_f32_e32 v0, v0, v0
	v_mul_f32_e32 v17, 0x3fb8aa3b, v0
	v_rndne_f32_e32 v17, v17
	v_fmamk_f32 v40, v17, 0xbf317218, v0
	v_fmac_f32_e32 v40, 0x3102e308, v17
	v_fmamk_f32 v42, v40, 0x395133b1, v192
	v_cmp_eq_f32_e32 vcc, s20, v17
	v_cvt_i32_f32_e32 v17, v17
	v_fmaak_f32 v42, v40, v42, 0x3c0887f9
	v_fmaak_f32 v42, v40, v42, 0x3d2aaa81
	v_fmaak_f32 v42, v40, v42, 0x3e2aaaab
	v_fma_f32 v42, v40, v42, 0.5
	v_ldexp_f32 v17, 1.0, v17
	v_mul_f32_e32 v42, v40, v42
	v_cndmask_b32_e32 v17, v17, v202, vcc
	v_fmac_f32_e32 v40, v40, v42
	v_add_f32_e32 v42, -1.0, v17
	v_fmac_f32_e32 v42, v17, v40
	v_add_f32_e32 v17, v42, v42
	v_cndmask_b32_e32 v17, v42, v17, vcc
	v_cmp_nlt_f32_e32 vcc, s21, v0
	v_exp_f32_e32 v16, v16
	s_nop 0
	v_cndmask_b32_e64 v17, v201, -v17, vcc
	v_cmp_gt_f32_e32 vcc, s22, v17
	v_mul_f32_e32 v40, 0x4f800000, v17
	s_nop 0
	v_cndmask_b32_e32 v17, v17, v40, vcc
	v_sqrt_f32_e32 v40, v17
	s_nop 0
	v_add_u32_e32 v42, -1, v40
	v_fma_f32 v44, -v42, v40, v17
	v_cmp_ge_f32_e64 s[0:1], 0, v44
	v_add_u32_e32 v44, 1, v40
	s_nop 0
	v_cndmask_b32_e64 v42, v40, v42, s[0:1]
	v_fma_f32 v40, -v44, v40, v17
	v_cmp_lt_f32_e64 s[0:1], 0, v40
	s_nop 1
	v_cndmask_b32_e64 v40, v42, v44, s[0:1]
	v_mul_f32_e32 v42, 0x37800000, v40
	v_cndmask_b32_e32 v40, v40, v42, vcc
	v_cmp_class_f32_e32 vcc, v17, v193
	s_nop 1
	v_cndmask_b32_e32 v17, v40, v17, vcc
	v_cmp_ngt_f32_e32 vcc, s23, v0
	s_nop 1
	v_cndmask_b32_e32 v0, 1.0, v17, vcc
	v_mul_f32_e32 v0, v1, v0
	v_mul_f32_e32 v0, v49, v0
	ds_write_b32 v73, v16 offset:384
	ds_write_b32 v73, v0 offset:37248
	v_add_f32_e32 v0, v18, v36
	v_mul_f32_e32 v0, 0xbfb8aa3b, v0
	v_exp_f32_e32 v0, v0
	v_add_f32_e32 v1, v2, v38
	v_mul_f32_e32 v1, 0xbfb8aa3b, v1
	v_exp_f32_e32 v1, v1
	v_add_f32_e32 v0, 1.0, v0
	v_rcp_f32_e32 v0, v0
	v_add_f32_e32 v1, 1.0, v1
	v_rcp_f32_e32 v1, v1
	v_mul_f32_e32 v0, v0, v32
	v_mul_f32_e32 v2, 0x3fb8aa3b, v0
	v_add_f32_e32 v0, v0, v0
	v_mul_f32_e32 v16, 0x3fb8aa3b, v0
	v_rndne_f32_e32 v16, v16
	v_fmamk_f32 v17, v16, 0xbf317218, v0
	v_fmac_f32_e32 v17, 0x3102e308, v16
	v_fmamk_f32 v18, v17, 0x395133b1, v192
	v_cmp_eq_f32_e32 vcc, s20, v16
	v_cvt_i32_f32_e32 v16, v16
	v_fmaak_f32 v18, v17, v18, 0x3c0887f9
	v_fmaak_f32 v18, v17, v18, 0x3d2aaa81
	v_fmaak_f32 v18, v17, v18, 0x3e2aaaab
	v_fma_f32 v18, v17, v18, 0.5
	v_ldexp_f32 v16, 1.0, v16
	v_mul_f32_e32 v18, v17, v18
	v_cndmask_b32_e32 v16, v16, v202, vcc
	v_fmac_f32_e32 v17, v17, v18
	v_add_f32_e32 v18, -1.0, v16
	v_fmac_f32_e32 v18, v16, v17
	v_add_f32_e32 v16, v18, v18
	v_cndmask_b32_e32 v16, v18, v16, vcc
	v_cmp_nlt_f32_e32 vcc, s21, v0
	v_exp_f32_e32 v2, v2
	s_nop 0
	v_cndmask_b32_e64 v16, v201, -v16, vcc
	v_cmp_gt_f32_e32 vcc, s22, v16
	v_mul_f32_e32 v17, 0x4f800000, v16
	s_nop 0
	v_cndmask_b32_e32 v16, v16, v17, vcc
	v_sqrt_f32_e32 v17, v16
	s_nop 0
	v_add_u32_e32 v18, -1, v17
	v_fma_f32 v40, -v18, v17, v16
	v_cmp_ge_f32_e64 s[0:1], 0, v40
	v_add_u32_e32 v40, 1, v17
	s_nop 0
	v_cndmask_b32_e64 v18, v17, v18, s[0:1]
	v_fma_f32 v17, -v40, v17, v16
	v_cmp_lt_f32_e64 s[0:1], 0, v17
	s_nop 1
	v_cndmask_b32_e64 v17, v18, v40, s[0:1]
	v_mul_f32_e32 v18, 0x37800000, v17
	v_cndmask_b32_e32 v17, v17, v18, vcc
	v_cmp_class_f32_e32 vcc, v16, v193
	s_nop 1
	v_cndmask_b32_e32 v16, v17, v16, vcc
	v_cmp_ngt_f32_e32 vcc, s23, v0
	s_nop 1
	v_cndmask_b32_e32 v0, 1.0, v16, vcc
	v_mul_f32_e32 v0, v1, v0
	v_mul_f32_e32 v0, v69, v0
	ds_write_b32 v73, v2 offset:640
	ds_write_b32 v73, v0 offset:37504
	v_add_f32_e32 v0, v19, v36
	v_mul_f32_e32 v0, 0xbfb8aa3b, v0
	v_exp_f32_e32 v0, v0
	v_add_f32_e32 v1, v3, v38
	v_mul_f32_e32 v1, 0xbfb8aa3b, v1
	v_exp_f32_e32 v1, v1
	v_add_f32_e32 v0, 1.0, v0
	v_rcp_f32_e32 v0, v0
	v_add_f32_e32 v1, 1.0, v1
	v_rcp_f32_e32 v1, v1
	v_mul_f32_e32 v0, v0, v32
	v_mul_f32_e32 v2, 0x3fb8aa3b, v0
	v_add_f32_e32 v0, v0, v0
	v_mul_f32_e32 v3, 0x3fb8aa3b, v0
	v_rndne_f32_e32 v3, v3
	v_fmamk_f32 v16, v3, 0xbf317218, v0
	v_fmac_f32_e32 v16, 0x3102e308, v3
	v_fmamk_f32 v17, v16, 0x395133b1, v192
	v_cmp_eq_f32_e32 vcc, s20, v3
	v_cvt_i32_f32_e32 v3, v3
	v_fmaak_f32 v17, v16, v17, 0x3c0887f9
	v_fmaak_f32 v17, v16, v17, 0x3d2aaa81
	v_fmaak_f32 v17, v16, v17, 0x3e2aaaab
	v_fma_f32 v17, v16, v17, 0.5
	v_ldexp_f32 v3, 1.0, v3
	v_mul_f32_e32 v17, v16, v17
	v_cndmask_b32_e32 v3, v3, v202, vcc
	v_fmac_f32_e32 v16, v16, v17
	v_add_f32_e32 v17, -1.0, v3
	v_fmac_f32_e32 v17, v3, v16
	v_add_f32_e32 v3, v17, v17
	v_cndmask_b32_e32 v3, v17, v3, vcc
	v_cmp_nlt_f32_e32 vcc, s21, v0
	v_exp_f32_e32 v2, v2
	s_nop 0
	v_cndmask_b32_e64 v3, v201, -v3, vcc
	v_cmp_gt_f32_e32 vcc, s22, v3
	v_mul_f32_e32 v16, 0x4f800000, v3
	s_nop 0
	v_cndmask_b32_e32 v3, v3, v16, vcc
	v_sqrt_f32_e32 v16, v3
	s_nop 0
	v_add_u32_e32 v17, -1, v16
	v_fma_f32 v18, -v17, v16, v3
	v_cmp_ge_f32_e64 s[0:1], 0, v18
	v_add_u32_e32 v18, 1, v16
	s_nop 0
	v_cndmask_b32_e64 v17, v16, v17, s[0:1]
	v_fma_f32 v16, -v18, v16, v3
	v_cmp_lt_f32_e64 s[0:1], 0, v16
	s_nop 1
	v_cndmask_b32_e64 v16, v17, v18, s[0:1]
	v_mul_f32_e32 v17, 0x37800000, v16
	v_cndmask_b32_e32 v16, v16, v17, vcc
	v_cmp_class_f32_e32 vcc, v3, v193
	s_nop 1
	v_cndmask_b32_e32 v3, v16, v3, vcc
	v_cmp_ngt_f32_e32 vcc, s23, v0
	s_nop 1
	v_cndmask_b32_e32 v0, 1.0, v3, vcc
	v_mul_f32_e32 v0, v1, v0
	v_mul_f32_e32 v0, v51, v0
	ds_write_b32 v73, v2 offset:896
	ds_write_b32 v73, v0 offset:37760
	v_add_f32_e32 v0, v20, v36
	v_mul_f32_e32 v0, 0xbfb8aa3b, v0
	v_exp_f32_e32 v0, v0
	v_add_f32_e32 v1, v4, v38
	v_mul_f32_e32 v1, 0xbfb8aa3b, v1
	v_exp_f32_e32 v1, v1
	v_add_f32_e32 v0, 1.0, v0
	v_rcp_f32_e32 v0, v0
	v_add_f32_e32 v1, 1.0, v1
	v_rcp_f32_e32 v1, v1
	v_mul_f32_e32 v0, v0, v32
	v_mul_f32_e32 v2, 0x3fb8aa3b, v0
	v_add_f32_e32 v0, v0, v0
	v_mul_f32_e32 v3, 0x3fb8aa3b, v0
	v_rndne_f32_e32 v3, v3
	v_fmamk_f32 v4, v3, 0xbf317218, v0
	v_fmac_f32_e32 v4, 0x3102e308, v3
	v_fmamk_f32 v16, v4, 0x395133b1, v192
	v_cmp_eq_f32_e32 vcc, s20, v3
	v_cvt_i32_f32_e32 v3, v3
	v_fmaak_f32 v16, v4, v16, 0x3c0887f9
	v_fmaak_f32 v16, v4, v16, 0x3d2aaa81
	v_fmaak_f32 v16, v4, v16, 0x3e2aaaab
	v_fma_f32 v16, v4, v16, 0.5
	v_ldexp_f32 v3, 1.0, v3
	v_mul_f32_e32 v16, v4, v16
	v_cndmask_b32_e32 v3, v3, v202, vcc
	v_fmac_f32_e32 v4, v4, v16
	v_add_f32_e32 v16, -1.0, v3
	v_fmac_f32_e32 v16, v3, v4
	v_add_f32_e32 v3, v16, v16
	v_cndmask_b32_e32 v3, v16, v3, vcc
	v_cmp_nlt_f32_e32 vcc, s21, v0
	v_exp_f32_e32 v2, v2
	s_nop 0
	v_cndmask_b32_e64 v3, v201, -v3, vcc
	v_cmp_gt_f32_e32 vcc, s22, v3
	v_mul_f32_e32 v4, 0x4f800000, v3
	s_nop 0
	v_cndmask_b32_e32 v3, v3, v4, vcc
	v_sqrt_f32_e32 v4, v3
	s_nop 0
	v_add_u32_e32 v16, -1, v4
	v_fma_f32 v17, -v16, v4, v3
	v_cmp_ge_f32_e64 s[0:1], 0, v17
	v_add_u32_e32 v17, 1, v4
	s_nop 0
	v_cndmask_b32_e64 v16, v4, v16, s[0:1]
	v_fma_f32 v4, -v17, v4, v3
	v_cmp_lt_f32_e64 s[0:1], 0, v4
	s_nop 1
	v_cndmask_b32_e64 v4, v16, v17, s[0:1]
	v_mul_f32_e32 v16, 0x37800000, v4
	v_cndmask_b32_e32 v4, v4, v16, vcc
	v_cmp_class_f32_e32 vcc, v3, v193
	s_nop 1
	v_cndmask_b32_e32 v3, v4, v3, vcc
	v_cmp_ngt_f32_e32 vcc, s23, v0
	s_nop 1
	v_cndmask_b32_e32 v0, 1.0, v3, vcc
	v_mul_f32_e32 v0, v1, v0
	v_mul_f32_e32 v0, v71, v0
	ds_write_b32 v73, v2 offset:2176
	ds_write_b32 v73, v0 offset:39040
	v_add_f32_e32 v0, v21, v36
	v_mul_f32_e32 v0, 0xbfb8aa3b, v0
	v_exp_f32_e32 v0, v0
	v_add_f32_e32 v1, v5, v38
	v_mul_f32_e32 v1, 0xbfb8aa3b, v1
	v_exp_f32_e32 v1, v1
	v_add_f32_e32 v0, 1.0, v0
	v_rcp_f32_e32 v0, v0
	v_add_f32_e32 v1, 1.0, v1
	v_rcp_f32_e32 v1, v1
	v_mul_f32_e32 v0, v0, v32
	v_mul_f32_e32 v2, 0x3fb8aa3b, v0
	v_add_f32_e32 v0, v0, v0
	v_mul_f32_e32 v3, 0x3fb8aa3b, v0
	v_rndne_f32_e32 v3, v3
	v_fmamk_f32 v4, v3, 0xbf317218, v0
	v_fmac_f32_e32 v4, 0x3102e308, v3
	v_fmamk_f32 v5, v4, 0x395133b1, v192
	v_cmp_eq_f32_e32 vcc, s20, v3
	v_cvt_i32_f32_e32 v3, v3
	v_fmaak_f32 v5, v4, v5, 0x3c0887f9
	v_fmaak_f32 v5, v4, v5, 0x3d2aaa81
	v_fmaak_f32 v5, v4, v5, 0x3e2aaaab
	v_fma_f32 v5, v4, v5, 0.5
	v_ldexp_f32 v3, 1.0, v3
	v_mul_f32_e32 v5, v4, v5
	v_cndmask_b32_e32 v3, v3, v202, vcc
	v_fmac_f32_e32 v4, v4, v5
	v_add_f32_e32 v5, -1.0, v3
	v_fmac_f32_e32 v5, v3, v4
	v_add_f32_e32 v3, v5, v5
	v_cndmask_b32_e32 v3, v5, v3, vcc
	v_cmp_nlt_f32_e32 vcc, s21, v0
	v_exp_f32_e32 v2, v2
	s_nop 0
	v_cndmask_b32_e64 v3, v201, -v3, vcc
	v_cmp_gt_f32_e32 vcc, s22, v3
	v_mul_f32_e32 v4, 0x4f800000, v3
	s_nop 0
	v_cndmask_b32_e32 v3, v3, v4, vcc
	v_sqrt_f32_e32 v4, v3
	s_nop 0
	v_add_u32_e32 v5, -1, v4
	v_fma_f32 v16, -v5, v4, v3
	v_cmp_ge_f32_e64 s[0:1], 0, v16
	v_add_u32_e32 v16, 1, v4
	s_nop 0
	v_cndmask_b32_e64 v5, v4, v5, s[0:1]
	v_fma_f32 v4, -v16, v4, v3
	v_cmp_lt_f32_e64 s[0:1], 0, v4
	s_nop 1
	v_cndmask_b32_e64 v4, v5, v16, s[0:1]
	v_mul_f32_e32 v5, 0x37800000, v4
	v_cndmask_b32_e32 v4, v4, v5, vcc
	v_cmp_class_f32_e32 vcc, v3, v193
	s_nop 1
	v_cndmask_b32_e32 v3, v4, v3, vcc
	v_cmp_ngt_f32_e32 vcc, s23, v0
	s_nop 1
	v_cndmask_b32_e32 v0, 1.0, v3, vcc
	v_mul_f32_e32 v0, v1, v0
	v_mul_f32_e32 v0, v37, v0
	ds_write_b32 v73, v2 offset:2432
	ds_write_b32 v73, v0 offset:39296
	v_add_f32_e32 v0, v22, v36
	v_mul_f32_e32 v0, 0xbfb8aa3b, v0
	v_exp_f32_e32 v0, v0
	v_add_f32_e32 v1, v6, v38
	v_mul_f32_e32 v1, 0xbfb8aa3b, v1
	v_exp_f32_e32 v1, v1
	v_add_f32_e32 v0, 1.0, v0
	v_rcp_f32_e32 v0, v0
	v_add_f32_e32 v1, 1.0, v1
	v_rcp_f32_e32 v1, v1
	v_mul_f32_e32 v0, v0, v32
	v_mul_f32_e32 v2, 0x3fb8aa3b, v0
	v_add_f32_e32 v0, v0, v0
	v_mul_f32_e32 v3, 0x3fb8aa3b, v0
	v_rndne_f32_e32 v3, v3
	v_fmamk_f32 v4, v3, 0xbf317218, v0
	v_fmac_f32_e32 v4, 0x3102e308, v3
	v_fmamk_f32 v5, v4, 0x395133b1, v192
	v_cmp_eq_f32_e32 vcc, s20, v3
	v_cvt_i32_f32_e32 v3, v3
	v_fmaak_f32 v5, v4, v5, 0x3c0887f9
	v_fmaak_f32 v5, v4, v5, 0x3d2aaa81
	v_fmaak_f32 v5, v4, v5, 0x3e2aaaab
	v_fma_f32 v5, v4, v5, 0.5
	v_ldexp_f32 v3, 1.0, v3
	v_mul_f32_e32 v5, v4, v5
	v_cndmask_b32_e32 v3, v3, v202, vcc
	v_fmac_f32_e32 v4, v4, v5
	v_add_f32_e32 v5, -1.0, v3
	v_fmac_f32_e32 v5, v3, v4
	v_add_f32_e32 v3, v5, v5
	v_cndmask_b32_e32 v3, v5, v3, vcc
	v_cmp_nlt_f32_e32 vcc, s21, v0
	v_exp_f32_e32 v2, v2
	s_nop 0
	v_cndmask_b32_e64 v3, v201, -v3, vcc
	v_cmp_gt_f32_e32 vcc, s22, v3
	v_mul_f32_e32 v4, 0x4f800000, v3
	s_nop 0
	v_cndmask_b32_e32 v3, v3, v4, vcc
	v_sqrt_f32_e32 v4, v3
	s_nop 0
	v_add_u32_e32 v5, -1, v4
	v_fma_f32 v6, -v5, v4, v3
	v_cmp_ge_f32_e64 s[0:1], 0, v6
	v_add_u32_e32 v6, 1, v4
	s_nop 0
	v_cndmask_b32_e64 v5, v4, v5, s[0:1]
	v_fma_f32 v4, -v6, v4, v3
	v_cmp_lt_f32_e64 s[0:1], 0, v4
	s_nop 1
	v_cndmask_b32_e64 v4, v5, v6, s[0:1]
	v_mul_f32_e32 v5, 0x37800000, v4
	v_cndmask_b32_e32 v4, v4, v5, vcc
	v_cmp_class_f32_e32 vcc, v3, v193
	s_nop 1
	v_cndmask_b32_e32 v3, v4, v3, vcc
	v_cmp_ngt_f32_e32 vcc, s23, v0
	s_nop 1
	v_cndmask_b32_e32 v0, 1.0, v3, vcc
	v_mul_f32_e32 v0, v1, v0
	v_mul_f32_e32 v0, v53, v0
	ds_write_b32 v73, v2 offset:2688
	ds_write_b32 v73, v0 offset:39552
	v_add_f32_e32 v0, v23, v36
	v_mul_f32_e32 v0, 0xbfb8aa3b, v0
	v_exp_f32_e32 v0, v0
	v_add_f32_e32 v1, v7, v38
	v_mul_f32_e32 v1, 0xbfb8aa3b, v1
	v_exp_f32_e32 v1, v1
	v_add_f32_e32 v0, 1.0, v0
	v_rcp_f32_e32 v0, v0
	v_add_f32_e32 v1, 1.0, v1
	v_rcp_f32_e32 v1, v1
	v_mul_f32_e32 v0, v0, v32
	v_mul_f32_e32 v2, 0x3fb8aa3b, v0
	v_add_f32_e32 v0, v0, v0
	v_mul_f32_e32 v3, 0x3fb8aa3b, v0
	v_rndne_f32_e32 v3, v3
	v_fmamk_f32 v4, v3, 0xbf317218, v0
	v_fmac_f32_e32 v4, 0x3102e308, v3
	v_fmamk_f32 v5, v4, 0x395133b1, v192
	v_cmp_eq_f32_e32 vcc, s20, v3
	v_cvt_i32_f32_e32 v3, v3
	v_fmaak_f32 v5, v4, v5, 0x3c0887f9
	v_fmaak_f32 v5, v4, v5, 0x3d2aaa81
	v_fmaak_f32 v5, v4, v5, 0x3e2aaaab
	v_fma_f32 v5, v4, v5, 0.5
	v_ldexp_f32 v3, 1.0, v3
	v_mul_f32_e32 v5, v4, v5
	v_cndmask_b32_e32 v3, v3, v202, vcc
	v_fmac_f32_e32 v4, v4, v5
	v_add_f32_e32 v5, -1.0, v3
	v_fmac_f32_e32 v5, v3, v4
	v_add_f32_e32 v3, v5, v5
	v_cndmask_b32_e32 v3, v5, v3, vcc
	v_cmp_nlt_f32_e32 vcc, s21, v0
	v_exp_f32_e32 v2, v2
	s_nop 0
	v_cndmask_b32_e64 v3, v201, -v3, vcc
	v_cmp_gt_f32_e32 vcc, s22, v3
	v_mul_f32_e32 v4, 0x4f800000, v3
	s_nop 0
	v_cndmask_b32_e32 v3, v3, v4, vcc
	v_sqrt_f32_e32 v4, v3
	s_nop 0
	v_add_u32_e32 v5, -1, v4
	v_fma_f32 v6, -v5, v4, v3
	v_cmp_ge_f32_e64 s[0:1], 0, v6
	v_add_u32_e32 v6, 1, v4
	s_nop 0
	v_cndmask_b32_e64 v5, v4, v5, s[0:1]
	v_fma_f32 v4, -v6, v4, v3
	v_cmp_lt_f32_e64 s[0:1], 0, v4
	s_nop 1
	v_cndmask_b32_e64 v4, v5, v6, s[0:1]
	v_mul_f32_e32 v5, 0x37800000, v4
	v_cndmask_b32_e32 v4, v4, v5, vcc
	v_cmp_class_f32_e32 vcc, v3, v193
	s_nop 1
	v_cndmask_b32_e32 v3, v4, v3, vcc
	v_cmp_ngt_f32_e32 vcc, s23, v0
	s_nop 1
	v_cndmask_b32_e32 v0, 1.0, v3, vcc
	v_mul_f32_e32 v0, v1, v0
	v_mul_f32_e32 v0, v39, v0
	ds_write_b32 v73, v2 offset:2944
	ds_write_b32 v73, v0 offset:39808
	v_add_f32_e32 v0, v24, v36
	v_mul_f32_e32 v0, 0xbfb8aa3b, v0
	v_exp_f32_e32 v0, v0
	v_add_f32_e32 v1, v8, v38
	v_mul_f32_e32 v1, 0xbfb8aa3b, v1
	v_exp_f32_e32 v1, v1
	v_add_f32_e32 v0, 1.0, v0
	v_rcp_f32_e32 v0, v0
	v_add_f32_e32 v1, 1.0, v1
	v_rcp_f32_e32 v1, v1
	v_mul_f32_e32 v0, v0, v32
	v_mul_f32_e32 v2, 0x3fb8aa3b, v0
	v_add_f32_e32 v0, v0, v0
	v_mul_f32_e32 v3, 0x3fb8aa3b, v0
	v_rndne_f32_e32 v3, v3
	v_fmamk_f32 v4, v3, 0xbf317218, v0
	v_fmac_f32_e32 v4, 0x3102e308, v3
	v_fmamk_f32 v5, v4, 0x395133b1, v192
	v_cmp_eq_f32_e32 vcc, s20, v3
	v_cvt_i32_f32_e32 v3, v3
	v_fmaak_f32 v5, v4, v5, 0x3c0887f9
	v_fmaak_f32 v5, v4, v5, 0x3d2aaa81
	v_fmaak_f32 v5, v4, v5, 0x3e2aaaab
	v_fma_f32 v5, v4, v5, 0.5
	v_ldexp_f32 v3, 1.0, v3
	v_mul_f32_e32 v5, v4, v5
	v_cndmask_b32_e32 v3, v3, v202, vcc
	v_fmac_f32_e32 v4, v4, v5
	v_add_f32_e32 v5, -1.0, v3
	v_fmac_f32_e32 v5, v3, v4
	v_add_f32_e32 v3, v5, v5
	v_cndmask_b32_e32 v3, v5, v3, vcc
	v_cmp_nlt_f32_e32 vcc, s21, v0
	v_exp_f32_e32 v2, v2
	s_nop 0
	v_cndmask_b32_e64 v3, v201, -v3, vcc
	v_cmp_gt_f32_e32 vcc, s22, v3
	v_mul_f32_e32 v4, 0x4f800000, v3
	s_nop 0
	v_cndmask_b32_e32 v3, v3, v4, vcc
	v_sqrt_f32_e32 v4, v3
	s_nop 0
	v_add_u32_e32 v5, -1, v4
	v_fma_f32 v6, -v5, v4, v3
	v_cmp_ge_f32_e64 s[0:1], 0, v6
	v_add_u32_e32 v6, 1, v4
	s_nop 0
	v_cndmask_b32_e64 v5, v4, v5, s[0:1]
	v_fma_f32 v4, -v6, v4, v3
	v_cmp_lt_f32_e64 s[0:1], 0, v4
	s_nop 1
	v_cndmask_b32_e64 v4, v5, v6, s[0:1]
	v_mul_f32_e32 v5, 0x37800000, v4
	v_cndmask_b32_e32 v4, v4, v5, vcc
	v_cmp_class_f32_e32 vcc, v3, v193
	s_nop 1
	v_cndmask_b32_e32 v3, v4, v3, vcc
	v_cmp_ngt_f32_e32 vcc, s23, v0
	s_nop 1
	v_cndmask_b32_e32 v0, 1.0, v3, vcc
	v_mul_f32_e32 v0, v1, v0
	v_mul_f32_e32 v0, v55, v0
	ds_write_b32 v73, v2 offset:4224
	ds_write_b32 v73, v0 offset:41088
	v_add_f32_e32 v0, v25, v36
	v_mul_f32_e32 v0, 0xbfb8aa3b, v0
	v_exp_f32_e32 v0, v0
	v_add_f32_e32 v1, v9, v38
	v_mul_f32_e32 v1, 0xbfb8aa3b, v1
	v_exp_f32_e32 v1, v1
	v_add_f32_e32 v0, 1.0, v0
	v_rcp_f32_e32 v0, v0
	v_add_f32_e32 v1, 1.0, v1
	v_rcp_f32_e32 v1, v1
	v_mul_f32_e32 v0, v0, v32
	v_mul_f32_e32 v2, 0x3fb8aa3b, v0
	v_add_f32_e32 v0, v0, v0
	v_mul_f32_e32 v3, 0x3fb8aa3b, v0
	v_rndne_f32_e32 v3, v3
	v_fmamk_f32 v4, v3, 0xbf317218, v0
	v_fmac_f32_e32 v4, 0x3102e308, v3
	v_fmamk_f32 v5, v4, 0x395133b1, v192
	v_cmp_eq_f32_e32 vcc, s20, v3
	v_cvt_i32_f32_e32 v3, v3
	v_fmaak_f32 v5, v4, v5, 0x3c0887f9
	v_fmaak_f32 v5, v4, v5, 0x3d2aaa81
	v_fmaak_f32 v5, v4, v5, 0x3e2aaaab
	v_fma_f32 v5, v4, v5, 0.5
	v_ldexp_f32 v3, 1.0, v3
	v_mul_f32_e32 v5, v4, v5
	v_cndmask_b32_e32 v3, v3, v202, vcc
	v_fmac_f32_e32 v4, v4, v5
	v_add_f32_e32 v5, -1.0, v3
	v_fmac_f32_e32 v5, v3, v4
	v_add_f32_e32 v3, v5, v5
	v_cndmask_b32_e32 v3, v5, v3, vcc
	v_cmp_nlt_f32_e32 vcc, s21, v0
	v_exp_f32_e32 v2, v2
	s_nop 0
	v_cndmask_b32_e64 v3, v201, -v3, vcc
	v_cmp_gt_f32_e32 vcc, s22, v3
	v_mul_f32_e32 v4, 0x4f800000, v3
	s_nop 0
	v_cndmask_b32_e32 v3, v3, v4, vcc
	v_sqrt_f32_e32 v4, v3
	s_nop 0
	v_add_u32_e32 v5, -1, v4
	v_fma_f32 v6, -v5, v4, v3
	v_cmp_ge_f32_e64 s[0:1], 0, v6
	v_add_u32_e32 v6, 1, v4
	s_nop 0
	v_cndmask_b32_e64 v5, v4, v5, s[0:1]
	v_fma_f32 v4, -v6, v4, v3
	v_cmp_lt_f32_e64 s[0:1], 0, v4
	s_nop 1
	v_cndmask_b32_e64 v4, v5, v6, s[0:1]
	v_mul_f32_e32 v5, 0x37800000, v4
	v_cndmask_b32_e32 v4, v4, v5, vcc
	v_cmp_class_f32_e32 vcc, v3, v193
	s_nop 1
	v_cndmask_b32_e32 v3, v4, v3, vcc
	v_cmp_ngt_f32_e32 vcc, s23, v0
	s_nop 1
	v_cndmask_b32_e32 v0, 1.0, v3, vcc
	v_mul_f32_e32 v0, v1, v0
	v_mul_f32_e32 v0, v41, v0
	ds_write_b32 v73, v2 offset:4480
	ds_write_b32 v73, v0 offset:41344
	v_add_f32_e32 v0, v26, v36
	v_mul_f32_e32 v0, 0xbfb8aa3b, v0
	v_exp_f32_e32 v0, v0
	v_add_f32_e32 v1, v10, v38
	v_mul_f32_e32 v1, 0xbfb8aa3b, v1
	v_exp_f32_e32 v1, v1
	v_add_f32_e32 v0, 1.0, v0
	v_rcp_f32_e32 v0, v0
	v_add_f32_e32 v1, 1.0, v1
	v_rcp_f32_e32 v1, v1
	v_mul_f32_e32 v0, v0, v32
	v_mul_f32_e32 v2, 0x3fb8aa3b, v0
	v_add_f32_e32 v0, v0, v0
	v_mul_f32_e32 v3, 0x3fb8aa3b, v0
	v_rndne_f32_e32 v3, v3
	v_fmamk_f32 v4, v3, 0xbf317218, v0
	v_fmac_f32_e32 v4, 0x3102e308, v3
	v_fmamk_f32 v5, v4, 0x395133b1, v192
	v_cmp_eq_f32_e32 vcc, s20, v3
	v_cvt_i32_f32_e32 v3, v3
	v_fmaak_f32 v5, v4, v5, 0x3c0887f9
	v_fmaak_f32 v5, v4, v5, 0x3d2aaa81
	v_fmaak_f32 v5, v4, v5, 0x3e2aaaab
	v_fma_f32 v5, v4, v5, 0.5
	v_ldexp_f32 v3, 1.0, v3
	v_mul_f32_e32 v5, v4, v5
	v_cndmask_b32_e32 v3, v3, v202, vcc
	v_fmac_f32_e32 v4, v4, v5
	v_add_f32_e32 v5, -1.0, v3
	v_fmac_f32_e32 v5, v3, v4
	v_add_f32_e32 v3, v5, v5
	v_cndmask_b32_e32 v3, v5, v3, vcc
	v_cmp_nlt_f32_e32 vcc, s21, v0
	v_exp_f32_e32 v2, v2
	s_nop 0
	v_cndmask_b32_e64 v3, v201, -v3, vcc
	v_cmp_gt_f32_e32 vcc, s22, v3
	v_mul_f32_e32 v4, 0x4f800000, v3
	s_nop 0
	v_cndmask_b32_e32 v3, v3, v4, vcc
	v_sqrt_f32_e32 v4, v3
	s_nop 0
	v_add_u32_e32 v5, -1, v4
	v_fma_f32 v6, -v5, v4, v3
	v_cmp_ge_f32_e64 s[0:1], 0, v6
	v_add_u32_e32 v6, 1, v4
	s_nop 0
	v_cndmask_b32_e64 v5, v4, v5, s[0:1]
	v_fma_f32 v4, -v6, v4, v3
	v_cmp_lt_f32_e64 s[0:1], 0, v4
	s_nop 1
	v_cndmask_b32_e64 v4, v5, v6, s[0:1]
	v_mul_f32_e32 v5, 0x37800000, v4
	v_cndmask_b32_e32 v4, v4, v5, vcc
	v_cmp_class_f32_e32 vcc, v3, v193
	s_nop 1
	v_cndmask_b32_e32 v3, v4, v3, vcc
	v_cmp_ngt_f32_e32 vcc, s23, v0
	s_nop 1
	v_cndmask_b32_e32 v0, 1.0, v3, vcc
	v_mul_f32_e32 v0, v1, v0
	v_mul_f32_e32 v0, v57, v0
	ds_write_b32 v73, v2 offset:4736
	ds_write_b32 v73, v0 offset:41600
	v_add_f32_e32 v0, v27, v36
	v_mul_f32_e32 v0, 0xbfb8aa3b, v0
	v_exp_f32_e32 v0, v0
	v_add_f32_e32 v1, v11, v38
	v_mul_f32_e32 v1, 0xbfb8aa3b, v1
	v_exp_f32_e32 v1, v1
	v_add_f32_e32 v0, 1.0, v0
	v_rcp_f32_e32 v0, v0
	v_add_f32_e32 v1, 1.0, v1
	v_rcp_f32_e32 v1, v1
	v_mul_f32_e32 v0, v0, v32
	v_mul_f32_e32 v2, 0x3fb8aa3b, v0
	v_add_f32_e32 v0, v0, v0
	v_mul_f32_e32 v3, 0x3fb8aa3b, v0
	v_rndne_f32_e32 v3, v3
	v_fmamk_f32 v4, v3, 0xbf317218, v0
	v_fmac_f32_e32 v4, 0x3102e308, v3
	v_fmamk_f32 v5, v4, 0x395133b1, v192
	v_cmp_eq_f32_e32 vcc, s20, v3
	v_cvt_i32_f32_e32 v3, v3
	v_fmaak_f32 v5, v4, v5, 0x3c0887f9
	v_fmaak_f32 v5, v4, v5, 0x3d2aaa81
	v_fmaak_f32 v5, v4, v5, 0x3e2aaaab
	v_fma_f32 v5, v4, v5, 0.5
	v_ldexp_f32 v3, 1.0, v3
	v_mul_f32_e32 v5, v4, v5
	v_cndmask_b32_e32 v3, v3, v202, vcc
	v_fmac_f32_e32 v4, v4, v5
	v_add_f32_e32 v5, -1.0, v3
	v_fmac_f32_e32 v5, v3, v4
	v_add_f32_e32 v3, v5, v5
	v_cndmask_b32_e32 v3, v5, v3, vcc
	v_cmp_nlt_f32_e32 vcc, s21, v0
	v_exp_f32_e32 v2, v2
	s_nop 0
	v_cndmask_b32_e64 v3, v201, -v3, vcc
	v_cmp_gt_f32_e32 vcc, s22, v3
	v_mul_f32_e32 v4, 0x4f800000, v3
	s_nop 0
	v_cndmask_b32_e32 v3, v3, v4, vcc
	v_sqrt_f32_e32 v4, v3
	s_nop 0
	v_add_u32_e32 v5, -1, v4
	v_fma_f32 v6, -v5, v4, v3
	v_cmp_ge_f32_e64 s[0:1], 0, v6
	v_add_u32_e32 v6, 1, v4
	s_nop 0
	v_cndmask_b32_e64 v5, v4, v5, s[0:1]
	v_fma_f32 v4, -v6, v4, v3
	v_cmp_lt_f32_e64 s[0:1], 0, v4
	s_nop 1
	v_cndmask_b32_e64 v4, v5, v6, s[0:1]
	v_mul_f32_e32 v5, 0x37800000, v4
	v_cndmask_b32_e32 v4, v4, v5, vcc
	v_cmp_class_f32_e32 vcc, v3, v193
	s_nop 1
	v_cndmask_b32_e32 v3, v4, v3, vcc
	v_cmp_ngt_f32_e32 vcc, s23, v0
	s_nop 1
	v_cndmask_b32_e32 v0, 1.0, v3, vcc
	v_mul_f32_e32 v0, v1, v0
	v_mul_f32_e32 v0, v43, v0
	ds_write_b32 v73, v2 offset:4992
	ds_write_b32 v73, v0 offset:41856
	v_add_f32_e32 v0, v28, v36
	v_mul_f32_e32 v0, 0xbfb8aa3b, v0
	v_exp_f32_e32 v0, v0
	v_add_f32_e32 v1, v12, v38
	v_mul_f32_e32 v1, 0xbfb8aa3b, v1
	v_exp_f32_e32 v1, v1
	v_add_f32_e32 v0, 1.0, v0
	v_rcp_f32_e32 v0, v0
	v_add_f32_e32 v1, 1.0, v1
	v_rcp_f32_e32 v1, v1
	v_mul_f32_e32 v0, v0, v32
	v_mul_f32_e32 v2, 0x3fb8aa3b, v0
	v_add_f32_e32 v0, v0, v0
	v_mul_f32_e32 v3, 0x3fb8aa3b, v0
	v_rndne_f32_e32 v3, v3
	v_fmamk_f32 v4, v3, 0xbf317218, v0
	v_fmac_f32_e32 v4, 0x3102e308, v3
	v_fmamk_f32 v5, v4, 0x395133b1, v192
	v_cmp_eq_f32_e32 vcc, s20, v3
	v_cvt_i32_f32_e32 v3, v3
	v_fmaak_f32 v5, v4, v5, 0x3c0887f9
	v_fmaak_f32 v5, v4, v5, 0x3d2aaa81
	v_fmaak_f32 v5, v4, v5, 0x3e2aaaab
	v_fma_f32 v5, v4, v5, 0.5
	v_ldexp_f32 v3, 1.0, v3
	v_mul_f32_e32 v5, v4, v5
	v_cndmask_b32_e32 v3, v3, v202, vcc
	v_fmac_f32_e32 v4, v4, v5
	v_add_f32_e32 v5, -1.0, v3
	v_fmac_f32_e32 v5, v3, v4
	v_add_f32_e32 v3, v5, v5
	v_cndmask_b32_e32 v3, v5, v3, vcc
	v_cmp_nlt_f32_e32 vcc, s21, v0
	v_exp_f32_e32 v2, v2
	s_nop 0
	v_cndmask_b32_e64 v3, v201, -v3, vcc
	v_cmp_gt_f32_e32 vcc, s22, v3
	v_mul_f32_e32 v4, 0x4f800000, v3
	s_nop 0
	v_cndmask_b32_e32 v3, v3, v4, vcc
	v_sqrt_f32_e32 v4, v3
	s_nop 0
	v_add_u32_e32 v5, -1, v4
	v_fma_f32 v6, -v5, v4, v3
	v_cmp_ge_f32_e64 s[0:1], 0, v6
	v_add_u32_e32 v6, 1, v4
	s_nop 0
	v_cndmask_b32_e64 v5, v4, v5, s[0:1]
	v_fma_f32 v4, -v6, v4, v3
	v_cmp_lt_f32_e64 s[0:1], 0, v4
	s_nop 1
	v_cndmask_b32_e64 v4, v5, v6, s[0:1]
	v_mul_f32_e32 v5, 0x37800000, v4
	v_cndmask_b32_e32 v4, v4, v5, vcc
	v_cmp_class_f32_e32 vcc, v3, v193
	s_nop 1
	v_cndmask_b32_e32 v3, v4, v3, vcc
	v_cmp_ngt_f32_e32 vcc, s23, v0
	s_nop 1
	v_cndmask_b32_e32 v0, 1.0, v3, vcc
	v_mul_f32_e32 v0, v1, v0
	v_mul_f32_e32 v0, v59, v0
	ds_write_b32 v73, v2 offset:6272
	ds_write_b32 v73, v0 offset:43136
	v_add_f32_e32 v0, v29, v36
	v_mul_f32_e32 v0, 0xbfb8aa3b, v0
	v_exp_f32_e32 v0, v0
	v_add_f32_e32 v1, v13, v38
	v_mul_f32_e32 v1, 0xbfb8aa3b, v1
	v_exp_f32_e32 v1, v1
	v_add_f32_e32 v0, 1.0, v0
	v_rcp_f32_e32 v0, v0
	v_add_f32_e32 v1, 1.0, v1
	v_rcp_f32_e32 v1, v1
	v_mul_f32_e32 v0, v0, v32
	v_mul_f32_e32 v2, 0x3fb8aa3b, v0
	v_add_f32_e32 v0, v0, v0
	v_mul_f32_e32 v3, 0x3fb8aa3b, v0
	v_rndne_f32_e32 v3, v3
	v_fmamk_f32 v4, v3, 0xbf317218, v0
	v_fmac_f32_e32 v4, 0x3102e308, v3
	v_fmamk_f32 v5, v4, 0x395133b1, v192
	v_cmp_eq_f32_e32 vcc, s20, v3
	v_cvt_i32_f32_e32 v3, v3
	v_fmaak_f32 v5, v4, v5, 0x3c0887f9
	v_fmaak_f32 v5, v4, v5, 0x3d2aaa81
	v_fmaak_f32 v5, v4, v5, 0x3e2aaaab
	v_fma_f32 v5, v4, v5, 0.5
	v_ldexp_f32 v3, 1.0, v3
	v_mul_f32_e32 v5, v4, v5
	v_cndmask_b32_e32 v3, v3, v202, vcc
	v_fmac_f32_e32 v4, v4, v5
	v_add_f32_e32 v5, -1.0, v3
	v_fmac_f32_e32 v5, v3, v4
	v_add_f32_e32 v3, v5, v5
	v_cndmask_b32_e32 v3, v5, v3, vcc
	v_cmp_nlt_f32_e32 vcc, s21, v0
	v_exp_f32_e32 v2, v2
	s_nop 0
	v_cndmask_b32_e64 v3, v201, -v3, vcc
	v_cmp_gt_f32_e32 vcc, s22, v3
	v_mul_f32_e32 v4, 0x4f800000, v3
	s_nop 0
	v_cndmask_b32_e32 v3, v3, v4, vcc
	v_sqrt_f32_e32 v4, v3
	s_nop 0
	v_add_u32_e32 v5, -1, v4
	v_fma_f32 v6, -v5, v4, v3
	v_cmp_ge_f32_e64 s[0:1], 0, v6
	v_add_u32_e32 v6, 1, v4
	s_nop 0
	v_cndmask_b32_e64 v5, v4, v5, s[0:1]
	v_fma_f32 v4, -v6, v4, v3
	v_cmp_lt_f32_e64 s[0:1], 0, v4
	s_nop 1
	v_cndmask_b32_e64 v4, v5, v6, s[0:1]
	v_mul_f32_e32 v5, 0x37800000, v4
	v_cndmask_b32_e32 v4, v4, v5, vcc
	v_cmp_class_f32_e32 vcc, v3, v193
	s_nop 1
	v_cndmask_b32_e32 v3, v4, v3, vcc
	v_cmp_ngt_f32_e32 vcc, s23, v0
	s_nop 1
	v_cndmask_b32_e32 v0, 1.0, v3, vcc
	v_mul_f32_e32 v0, v1, v0
	v_mul_f32_e32 v0, v45, v0
	ds_write_b32 v73, v2 offset:6528
	ds_write_b32 v73, v0 offset:43392
	v_add_f32_e32 v0, v30, v36
	v_mul_f32_e32 v0, 0xbfb8aa3b, v0
	v_exp_f32_e32 v0, v0
	v_add_f32_e32 v1, v14, v38
	v_mul_f32_e32 v1, 0xbfb8aa3b, v1
	v_exp_f32_e32 v1, v1
	v_add_f32_e32 v0, 1.0, v0
	v_rcp_f32_e32 v0, v0
	v_add_f32_e32 v1, 1.0, v1
	v_rcp_f32_e32 v1, v1
	v_mul_f32_e32 v0, v0, v32
	v_mul_f32_e32 v2, 0x3fb8aa3b, v0
	v_add_f32_e32 v0, v0, v0
	v_mul_f32_e32 v3, 0x3fb8aa3b, v0
	v_rndne_f32_e32 v3, v3
	v_fmamk_f32 v4, v3, 0xbf317218, v0
	v_fmac_f32_e32 v4, 0x3102e308, v3
	v_fmamk_f32 v5, v4, 0x395133b1, v192
	v_cmp_eq_f32_e32 vcc, s20, v3
	v_cvt_i32_f32_e32 v3, v3
	v_fmaak_f32 v5, v4, v5, 0x3c0887f9
	v_fmaak_f32 v5, v4, v5, 0x3d2aaa81
	v_fmaak_f32 v5, v4, v5, 0x3e2aaaab
	v_fma_f32 v5, v4, v5, 0.5
	v_ldexp_f32 v3, 1.0, v3
	v_mul_f32_e32 v5, v4, v5
	v_cndmask_b32_e32 v3, v3, v202, vcc
	v_fmac_f32_e32 v4, v4, v5
	v_add_f32_e32 v5, -1.0, v3
	v_fmac_f32_e32 v5, v3, v4
	v_add_f32_e32 v3, v5, v5
	v_cndmask_b32_e32 v3, v5, v3, vcc
	v_cmp_nlt_f32_e32 vcc, s21, v0
	v_exp_f32_e32 v2, v2
	s_nop 0
	v_cndmask_b32_e64 v3, v201, -v3, vcc
	v_cmp_gt_f32_e32 vcc, s22, v3
	v_mul_f32_e32 v4, 0x4f800000, v3
	s_nop 0
	v_cndmask_b32_e32 v3, v3, v4, vcc
	v_sqrt_f32_e32 v4, v3
	s_nop 0
	v_add_u32_e32 v5, -1, v4
	v_fma_f32 v6, -v5, v4, v3
	v_cmp_ge_f32_e64 s[0:1], 0, v6
	v_add_u32_e32 v6, 1, v4
	s_nop 0
	v_cndmask_b32_e64 v5, v4, v5, s[0:1]
	v_fma_f32 v4, -v6, v4, v3
	v_cmp_lt_f32_e64 s[0:1], 0, v4
	s_nop 1
	v_cndmask_b32_e64 v4, v5, v6, s[0:1]
	v_mul_f32_e32 v5, 0x37800000, v4
	v_cndmask_b32_e32 v4, v4, v5, vcc
	v_cmp_class_f32_e32 vcc, v3, v193
	s_nop 1
	v_cndmask_b32_e32 v3, v4, v3, vcc
	v_cmp_ngt_f32_e32 vcc, s23, v0
	s_nop 1
	v_cndmask_b32_e32 v0, 1.0, v3, vcc
	v_mul_f32_e32 v0, v1, v0
	v_mul_f32_e32 v0, v35, v0
	v_add_u32_e32 v1, 0x1800, v73
	ds_write2_b32 v1, v2, v34 offset0:160 offset1:192
	ds_write_b32 v73, v0 offset:43648
	v_add_f32_e32 v0, v31, v36
	v_mul_f32_e32 v0, 0xbfb8aa3b, v0
	v_exp_f32_e32 v0, v0
	v_add_f32_e32 v1, v15, v38
	v_mul_f32_e32 v1, 0xbfb8aa3b, v1
	v_exp_f32_e32 v1, v1
	v_add_f32_e32 v0, 1.0, v0
	v_rcp_f32_e32 v0, v0
	v_add_f32_e32 v1, 1.0, v1
	v_rcp_f32_e32 v1, v1
	v_mul_f32_e32 v0, v0, v32
	v_mul_f32_e32 v2, 0x3fb8aa3b, v0
	v_add_f32_e32 v0, v0, v0
	v_mul_f32_e32 v3, 0x3fb8aa3b, v0
	v_rndne_f32_e32 v3, v3
	v_fmamk_f32 v4, v3, 0xbf317218, v0
	v_fmac_f32_e32 v4, 0x3102e308, v3
	v_fmamk_f32 v5, v4, 0x395133b1, v192
	v_cmp_eq_f32_e32 vcc, s20, v3
	v_cvt_i32_f32_e32 v3, v3
	v_fmaak_f32 v5, v4, v5, 0x3c0887f9
	v_fmaak_f32 v5, v4, v5, 0x3d2aaa81
	v_fmaak_f32 v5, v4, v5, 0x3e2aaaab
	v_fma_f32 v5, v4, v5, 0.5
	v_ldexp_f32 v3, 1.0, v3
	v_mul_f32_e32 v5, v4, v5
	v_cndmask_b32_e32 v3, v3, v202, vcc
	v_fmac_f32_e32 v4, v4, v5
	v_add_f32_e32 v5, -1.0, v3
	v_fmac_f32_e32 v5, v3, v4
	v_add_f32_e32 v3, v5, v5
	v_cndmask_b32_e32 v3, v5, v3, vcc
	v_cmp_nlt_f32_e32 vcc, s21, v0
	v_exp_f32_e32 v2, v2
	s_nop 0
	v_cndmask_b32_e64 v3, v201, -v3, vcc
	v_cmp_gt_f32_e32 vcc, s22, v3
	v_mul_f32_e32 v4, 0x4f800000, v3
	s_nop 0
	v_cndmask_b32_e32 v3, v3, v4, vcc
	v_sqrt_f32_e32 v4, v3
	s_nop 0
	v_add_u32_e32 v5, -1, v4
	v_fma_f32 v6, -v5, v4, v3
	v_cmp_ge_f32_e64 s[0:1], 0, v6
	v_add_u32_e32 v6, 1, v4
	s_nop 0
	v_cndmask_b32_e64 v5, v4, v5, s[0:1]
	v_fma_f32 v4, -v6, v4, v3
	v_cmp_lt_f32_e64 s[0:1], 0, v4
	s_nop 1
	v_cndmask_b32_e64 v4, v5, v6, s[0:1]
	v_mul_f32_e32 v5, 0x37800000, v4
	v_cndmask_b32_e32 v4, v4, v5, vcc
	v_cmp_class_f32_e32 vcc, v3, v193
	s_nop 1
	v_cndmask_b32_e32 v3, v4, v3, vcc
	v_cmp_ngt_f32_e32 vcc, s23, v0
	s_nop 1
	v_cndmask_b32_e32 v0, 1.0, v3, vcc
	v_mul_f32_e32 v0, v1, v0
	v_mul_f32_e32 v0, v33, v0
	ds_write_b32 v73, v2 offset:7040
	ds_write_b32 v73, v0 offset:43904
	s_waitcnt lgkmcnt(0)
	s_barrier
	s_cbranch_scc1 .LBB0_866
	v_lshl_add_u64 v[0:1], v[64:65], 0, s[4:5]
	global_load_dwordx2 v[98:99], v[0:1], off
	s_cmp_eq_u32 s12, 1
	s_waitcnt vmcnt(0)
	v_fmac_f32_e32 v99, 0, v98
	s_cbranch_scc1 .LBB0_867
	v_add_co_u32_e32 v0, vcc, 0x1000, v0
	s_cmp_eq_u32 s12, 2
	s_nop 0
	v_addc_co_u32_e32 v1, vcc, 0, v1, vcc
	global_load_dwordx2 v[0:1], v[0:1], off
	s_waitcnt vmcnt(0)
	v_fmac_f32_e32 v1, v99, v0
	s_cbranch_scc1 .LBB0_865
	v_readlane_b32 s0, v248, 32
	s_mul_i32 s46, s11, 36
	s_add_i32 s0, s0, s75
	s_mov_b32 s47, s5
	s_sub_i32 s0, s0, s70
	s_lshl_b64 s[44:45], s[46:47], 12
	v_readlane_b32 s1, v249, 45
	s_add_u32 s44, s1, s44
	v_readlane_b32 s1, v249, 46
	v_add_lshl_u32 v96, s13, v141, 3
	s_addc_u32 s45, s1, s45
	v_lshl_add_u64 v[2:3], s[44:45], 0, v[96:97]
	s_mov_b64 s[8:9], 0x1000

.LBB0_873:
	s_or_b64 exec, exec, s[0:1]
	v_mov_b32_e32 v51, v162
	ds_read2st64_b32 v[102:103], v98 offset1:1
	ds_read2st64_b32 v[104:105], v98 offset0:2 offset1:3
	ds_read2st64_b32 v[106:107], v98 offset0:4 offset1:5
	ds_read2st64_b32 v[108:109], v98 offset0:6 offset1:7
	ds_read2st64_b32 v[66:67], v98 offset0:144 offset1:145
	ds_read2st64_b32 v[68:69], v98 offset0:146 offset1:147
	ds_read2st64_b32 v[70:71], v98 offset0:148 offset1:149
	ds_read2st64_b32 v[72:73], v98 offset0:150 offset1:151
	ds_read2st64_b32 v[110:111], v98 offset0:8 offset1:9
	ds_read2st64_b32 v[112:113], v98 offset0:10 offset1:11
	ds_read2st64_b32 v[114:115], v98 offset0:12 offset1:13
	ds_read2st64_b32 v[116:117], v98 offset0:14 offset1:15
	ds_read2st64_b32 v[74:75], v98 offset0:152 offset1:153
	ds_read2st64_b32 v[76:77], v98 offset0:154 offset1:155
	ds_read2st64_b32 v[78:79], v98 offset0:156 offset1:157
	ds_read2st64_b32 v[80:81], v98 offset0:158 offset1:159
	ds_read2st64_b32 v[118:119], v98 offset0:16 offset1:17
	ds_read2st64_b32 v[120:121], v98 offset0:18 offset1:19
	ds_read2st64_b32 v[122:123], v98 offset0:20 offset1:21
	ds_read2st64_b32 v[124:125], v98 offset0:22 offset1:23
	ds_read2st64_b32 v[82:83], v98 offset0:160 offset1:161
	ds_read2st64_b32 v[84:85], v98 offset0:162 offset1:163
	ds_read2st64_b32 v[86:87], v98 offset0:164 offset1:165
	ds_read2st64_b32 v[88:89], v98 offset0:166 offset1:167
	ds_read2st64_b32 v[126:127], v98 offset0:24 offset1:25
	ds_read2st64_b32 v[128:129], v98 offset0:26 offset1:27
	ds_read2st64_b32 v[130:131], v98 offset0:28 offset1:29
	ds_read2st64_b32 v[132:133], v98 offset0:30 offset1:31
	ds_read2st64_b32 v[90:91], v98 offset0:168 offset1:169
	ds_read2st64_b32 v[92:93], v98 offset0:170 offset1:171
	ds_read2st64_b32 v[94:95], v98 offset0:172 offset1:173
	ds_read2st64_b32 v[100:101], v98 offset0:174 offset1:175
	v_readlane_b32 s0, v248, 18
	v_lshlrev_b32_e32 v136, 3, v51
	v_and_b32_e32 v50, 56, v136
	v_or_b32_e32 v14, s13, v50
	v_readlane_b32 s16, v251, 4
	v_or_b32_e32 v0, s0, v14
	v_readlane_b32 s22, v251, 10
	v_readlane_b32 s23, v251, 11
	v_mov_b32_e32 v1, v97
	s_mov_b64 s[0:1], 0x1000
	v_lshl_add_u64 v[8:9], v[0:1], 2, s[22:23]
	v_or_b32_e32 v96, s34, v14
	v_readlane_b32 s24, v251, 12
	v_readlane_b32 s25, v251, 13
	v_lshl_add_u64 v[10:11], v[8:9], 0, s[0:1]
	s_mov_b64 s[0:1], 0x1800
	v_lshl_add_u64 v[2:3], v[96:97], 2, s[24:25]
	v_lshl_add_u64 v[12:13], v[8:9], 0, s[0:1]
	s_movk_i32 s0, 0x1000
	s_waitcnt lgkmcnt(0)
	s_barrier
	global_load_dwordx4 v[4:7], v[2:3], off offset:16
	s_nop 0
	global_load_dwordx4 v[0:3], v[2:3], off
	s_nop 0
	global_load_dwordx4 v[44:47], v[8:9], off offset:16
	global_load_dwordx4 v[40:43], v[8:9], off
	global_load_dwordx4 v[36:39], v[8:9], off offset:2064
	global_load_dwordx4 v[32:35], v[8:9], off offset:2048
	v_add_co_u32_e32 v8, vcc, s0, v8
	v_ashrrev_i32_e32 v52, 3, v51
	s_nop 0
	v_addc_co_u32_e32 v9, vcc, 0, v9, vcc
	global_load_dwordx4 v[24:27], v[8:9], off
	global_load_dwordx4 v[16:19], v[8:9], off offset:2048
	global_load_dwordx4 v[28:31], v[10:11], off offset:16
	global_load_dwordx4 v[20:23], v[12:13], off offset:16
	v_readlane_b32 s0, v249, 7
	v_add_u32_e32 v53, s68, v52
	v_lshlrev_b32_e32 v96, 1, v14
	v_readlane_b32 s1, v249, 8
	v_add_u32_e32 v54, -2, v53
	v_cmp_lt_i32_e32 vcc, 1, v53
	v_lshl_add_u64 v[48:49], s[0:1], 0, v[96:97]
	v_cmp_gt_u32_e64 s[0:1], s39, v54
	s_and_b64 s[2:3], vcc, s[0:1]
	v_readlane_b32 s17, v251, 5
	v_readlane_b32 s18, v251, 6
	v_readlane_b32 s19, v251, 7
	v_readlane_b32 s20, v251, 8
	v_readlane_b32 s21, v251, 9
	v_readlane_b32 s26, v251, 14
	v_readlane_b32 s27, v251, 15
	v_readlane_b32 s28, v251, 16
	v_readlane_b32 s29, v251, 17
	v_readlane_b32 s30, v251, 18
	v_readlane_b32 s31, v251, 19
	s_waitcnt vmcnt(8)
	v_mov_b64_e32 v[8:9], v[0:1]
	v_mov_b32_e32 v206, 0
	v_mov_b32_e32 v207, 0
	v_mov_b32_e32 v208, 0
	v_mov_b32_e32 v209, 0
	s_and_saveexec_b64 s[0:1], s[2:3]
	s_cbranch_execz .Lrg33_i
	v_add_u32_e32 v8, s38, v54
	v_mad_u64_u32 v[8:9], s[2:3], v8, s74, v[48:49]
	global_load_dwordx4 v[206:209], v[8:9], off

.Lrg36_i:
	s_or_b64 exec, exec, s[0:1]
	s_waitcnt vmcnt(0)
	s_nop 0
	v_mov_b32_e32 v9, v207
	v_mov_b32_e32 v10, v208
	v_mov_b32_e32 v11, v209
	v_lshlrev_b32_e32 v54, 16, v206
	v_and_b32_e32 v55, 0xffff0000, v206
	v_lshlrev_b32_e32 v8, 16, v9
	v_and_b32_e32 v9, 0xffff0000, v9
	v_lshlrev_b32_e32 v12, 16, v10
	v_and_b32_e32 v13, 0xffff0000, v10
	v_lshlrev_b32_e32 v10, 16, v11
	v_and_b32_e32 v11, 0xffff0000, v11
	v_pk_fma_f32 v[14:15], v[46:47], v[10:11], v[6:7]
	v_pk_fma_f32 v[12:13], v[44:45], v[12:13], v[4:5]
	v_pk_fma_f32 v[10:11], v[42:43], v[8:9], v[2:3]
	v_pk_fma_f32 v[8:9], v[40:41], v[54:55], v[0:1]
	v_mov_b32_e32 v55, v211
	v_mov_b32_e32 v56, v212
	v_mov_b32_e32 v57, v213
	v_lshlrev_b32_e32 v58, 16, v210
	v_and_b32_e32 v59, 0xffff0000, v210
	v_lshlrev_b32_e32 v54, 16, v55
	v_and_b32_e32 v55, 0xffff0000, v55
	v_lshlrev_b32_e32 v60, 16, v56
	v_and_b32_e32 v61, 0xffff0000, v56
	v_lshlrev_b32_e32 v56, 16, v57
	v_and_b32_e32 v57, 0xffff0000, v57
	v_pk_fma_f32 v[14:15], v[38:39], v[56:57], v[14:15]
	v_pk_fma_f32 v[12:13], v[36:37], v[60:61], v[12:13]
	v_pk_fma_f32 v[10:11], v[34:35], v[54:55], v[10:11]
	v_pk_fma_f32 v[8:9], v[32:33], v[58:59], v[8:9]
	v_mov_b32_e32 v55, v215
	v_mov_b32_e32 v56, v216
	v_mov_b32_e32 v57, v217
	v_lshlrev_b32_e32 v58, 16, v214
	v_and_b32_e32 v59, 0xffff0000, v214
	v_lshlrev_b32_e32 v54, 16, v55
	v_and_b32_e32 v55, 0xffff0000, v55
	v_lshlrev_b32_e32 v60, 16, v56
	v_and_b32_e32 v61, 0xffff0000, v56
	v_lshlrev_b32_e32 v56, 16, v57
	v_and_b32_e32 v57, 0xffff0000, v57
	v_pk_fma_f32 v[14:15], v[30:31], v[56:57], v[14:15]
	v_pk_fma_f32 v[12:13], v[28:29], v[60:61], v[12:13]
	v_pk_fma_f32 v[10:11], v[26:27], v[54:55], v[10:11]
	v_pk_fma_f32 v[8:9], v[24:25], v[58:59], v[8:9]
	v_mov_b32_e32 v55, v219
	v_mov_b32_e32 v56, v220
	v_mov_b32_e32 v57, v221
	v_lshlrev_b32_e32 v58, 16, v218
	v_and_b32_e32 v59, 0xffff0000, v218
	v_lshlrev_b32_e32 v54, 16, v55
	v_and_b32_e32 v55, 0xffff0000, v55
	v_lshlrev_b32_e32 v60, 16, v56
	v_and_b32_e32 v61, 0xffff0000, v56
	v_lshlrev_b32_e32 v56, 16, v57
	v_and_b32_e32 v57, 0xffff0000, v57
	v_pk_fma_f32 v[14:15], v[22:23], v[56:57], v[14:15]
	v_pk_fma_f32 v[12:13], v[20:21], v[60:61], v[12:13]
	v_pk_fma_f32 v[10:11], v[18:19], v[54:55], v[10:11]
	v_pk_fma_f32 v[8:9], v[16:17], v[58:59], v[8:9]
	v_lshl_add_u32 v53, v50, 2, 0
	v_lshl_add_u32 v54, v52, 8, v53
	v_lshlrev_b32_e32 v50, 1, v50
	ds_write_b128 v54, v[8:11] offset:36864
	ds_write_b128 v54, v[12:15] offset:36880
	v_add_u32_e32 v54, 32, v52
	v_sub_u32_e32 v50, v53, v50
	v_add_u32_e32 v55, s68, v54
	v_cvt_pk_bf16_f32 v8, v8, v9
	v_cvt_pk_bf16_f32 v9, v10, v11
	v_cvt_pk_bf16_f32 v10, v12, v13
	v_cvt_pk_bf16_f32 v11, v14, v15
	v_mad_u64_u32 v[12:13], s[0:1], v52, s8, v[50:51]
	v_add_u32_e32 v56, -2, v55
	ds_write_b128 v12, v[8:11]
	v_cmp_lt_i32_e32 vcc, 1, v55
	v_cmp_gt_u32_e64 s[0:1], s39, v56
	s_and_b64 s[2:3], vcc, s[0:1]
	v_mov_b64_e32 v[8:9], v[0:1]
	v_mov_b32_e32 v206, 0
	v_mov_b32_e32 v207, 0
	v_mov_b32_e32 v208, 0
	v_mov_b32_e32 v209, 0
	s_and_saveexec_b64 s[0:1], s[2:3]
	s_cbranch_execz .Lrg37_i
	v_add_u32_e32 v8, s38, v56
	v_mad_u64_u32 v[8:9], s[2:3], v8, s74, v[48:49]
	global_load_dwordx4 v[206:209], v[8:9], off

.Lrg40_i:
	s_or_b64 exec, exec, s[0:1]
	s_waitcnt vmcnt(0)
	s_nop 0
	v_mov_b32_e32 v9, v207
	v_mov_b32_e32 v10, v208
	v_mov_b32_e32 v11, v209
	v_lshlrev_b32_e32 v56, 16, v206
	v_and_b32_e32 v57, 0xffff0000, v206
	v_lshlrev_b32_e32 v8, 16, v9
	v_and_b32_e32 v9, 0xffff0000, v9
	v_lshlrev_b32_e32 v12, 16, v10
	v_and_b32_e32 v13, 0xffff0000, v10
	v_lshlrev_b32_e32 v10, 16, v11
	v_and_b32_e32 v11, 0xffff0000, v11
	v_pk_fma_f32 v[14:15], v[46:47], v[10:11], v[6:7]
	v_pk_fma_f32 v[12:13], v[44:45], v[12:13], v[4:5]
	v_pk_fma_f32 v[10:11], v[42:43], v[8:9], v[2:3]
	v_pk_fma_f32 v[8:9], v[40:41], v[56:57], v[0:1]
	v_mov_b32_e32 v57, v211
	v_mov_b32_e32 v58, v212
	v_mov_b32_e32 v59, v213
	v_lshlrev_b32_e32 v60, 16, v210
	v_and_b32_e32 v61, 0xffff0000, v210
	v_lshlrev_b32_e32 v56, 16, v57
	v_and_b32_e32 v57, 0xffff0000, v57
	v_lshlrev_b32_e32 v62, 16, v58
	v_and_b32_e32 v63, 0xffff0000, v58
	v_lshlrev_b32_e32 v58, 16, v59
	v_and_b32_e32 v59, 0xffff0000, v59
	v_pk_fma_f32 v[14:15], v[38:39], v[58:59], v[14:15]
	v_pk_fma_f32 v[12:13], v[36:37], v[62:63], v[12:13]
	v_pk_fma_f32 v[10:11], v[34:35], v[56:57], v[10:11]
	v_pk_fma_f32 v[8:9], v[32:33], v[60:61], v[8:9]
	v_mov_b32_e32 v57, v215
	v_mov_b32_e32 v58, v216
	v_mov_b32_e32 v59, v217
	v_lshlrev_b32_e32 v60, 16, v214
	v_and_b32_e32 v61, 0xffff0000, v214
	v_lshlrev_b32_e32 v56, 16, v57
	v_and_b32_e32 v57, 0xffff0000, v57
	v_lshlrev_b32_e32 v62, 16, v58
	v_and_b32_e32 v63, 0xffff0000, v58
	v_lshlrev_b32_e32 v58, 16, v59
	v_and_b32_e32 v59, 0xffff0000, v59
	v_pk_fma_f32 v[14:15], v[30:31], v[58:59], v[14:15]
	v_pk_fma_f32 v[12:13], v[28:29], v[62:63], v[12:13]
	v_pk_fma_f32 v[10:11], v[26:27], v[56:57], v[10:11]
	v_pk_fma_f32 v[8:9], v[24:25], v[60:61], v[8:9]
	v_mov_b32_e32 v57, v219
	v_mov_b32_e32 v58, v220
	v_mov_b32_e32 v59, v221
	v_lshlrev_b32_e32 v60, 16, v218
	v_and_b32_e32 v61, 0xffff0000, v218
	v_lshlrev_b32_e32 v56, 16, v57
	v_and_b32_e32 v57, 0xffff0000, v57
	v_lshlrev_b32_e32 v62, 16, v58
	v_and_b32_e32 v63, 0xffff0000, v58
	v_lshlrev_b32_e32 v58, 16, v59
	v_and_b32_e32 v59, 0xffff0000, v59
	v_pk_fma_f32 v[14:15], v[22:23], v[58:59], v[14:15]
	v_pk_fma_f32 v[12:13], v[20:21], v[62:63], v[12:13]
	v_pk_fma_f32 v[10:11], v[18:19], v[56:57], v[10:11]
	v_pk_fma_f32 v[8:9], v[16:17], v[60:61], v[8:9]
	v_lshl_add_u32 v55, v54, 8, v53
	ds_write_b128 v55, v[8:11] offset:36864
	ds_write_b128 v55, v[12:15] offset:36880
	v_cvt_pk_bf16_f32 v8, v8, v9
	v_cvt_pk_bf16_f32 v9, v10, v11
	v_cvt_pk_bf16_f32 v10, v12, v13
	v_mad_u64_u32 v[12:13], s[0:1], v54, s8, v[50:51]
	v_add_u32_e32 v54, 64, v52
	v_add_u32_e32 v55, s68, v54
	v_cvt_pk_bf16_f32 v11, v14, v15
	v_add_u32_e32 v56, -2, v55
	ds_write_b128 v12, v[8:11]
	v_cmp_lt_i32_e32 vcc, 1, v55
	v_cmp_gt_u32_e64 s[0:1], s39, v56
	s_and_b64 s[2:3], vcc, s[0:1]
	v_mov_b64_e32 v[8:9], v[0:1]
	v_mov_b32_e32 v206, 0
	v_mov_b32_e32 v207, 0
	v_mov_b32_e32 v208, 0
	v_mov_b32_e32 v209, 0
	s_and_saveexec_b64 s[0:1], s[2:3]
	s_cbranch_execz .Lrg41_i
	v_add_u32_e32 v8, s38, v56
	v_mad_u64_u32 v[8:9], s[2:3], v8, s74, v[48:49]
	global_load_dwordx4 v[206:209], v[8:9], off

.LBB0_906:
	v_add_u32_e32 v2, s38, v0
	s_addk_i32 s38, 0x800
	v_mov_b32_e32 v222, v2
	v_ashrrev_i32_e32 v223, 31, v222
	v_lshlrev_b64 v[222:223], 2, v[222:223]
	v_lshl_add_u64 v[224:225], s[0:1], 0, v[222:223]
	global_load_dword v206, v[224:225], off
	global_load_dword v207, v[224:225], off offset:256
	v_lshl_add_u64 v[224:225], s[2:3], 0, v[222:223]
	global_load_dword v208, v[224:225], off
	global_load_dword v209, v[224:225], off offset:256
	v_add_u32_e32 v222, 0x200, v2
	v_ashrrev_i32_e32 v223, 31, v222
	v_lshlrev_b64 v[222:223], 2, v[222:223]
	v_lshl_add_u64 v[224:225], s[0:1], 0, v[222:223]
	global_load_dword v210, v[224:225], off
	global_load_dword v211, v[224:225], off offset:256
	v_lshl_add_u64 v[224:225], s[2:3], 0, v[222:223]
	global_load_dword v212, v[224:225], off
	global_load_dword v213, v[224:225], off offset:256
	v_add_u32_e32 v222, 0x400, v2
	v_ashrrev_i32_e32 v223, 31, v222
	v_lshlrev_b64 v[222:223], 2, v[222:223]
	v_lshl_add_u64 v[224:225], s[0:1], 0, v[222:223]
	global_load_dword v214, v[224:225], off
	global_load_dword v215, v[224:225], off offset:256
	v_lshl_add_u64 v[224:225], s[2:3], 0, v[222:223]
	global_load_dword v216, v[224:225], off
	global_load_dword v217, v[224:225], off offset:256
	v_add_u32_e32 v222, 0x600, v2
	v_ashrrev_i32_e32 v223, 31, v222
	v_lshlrev_b64 v[222:223], 2, v[222:223]
	v_lshl_add_u64 v[224:225], s[0:1], 0, v[222:223]
	global_load_dword v218, v[224:225], off
	global_load_dword v219, v[224:225], off offset:256
	v_lshl_add_u64 v[224:225], s[2:3], 0, v[222:223]
	global_load_dword v220, v[224:225], off
	global_load_dword v221, v[224:225], off offset:256
	v_add_u32_e32 v2, s38, v0
	s_addk_i32 s38, 0x800
	v_mov_b32_e32 v222, v2
	v_ashrrev_i32_e32 v223, 31, v222
	v_lshlrev_b64 v[222:223], 2, v[222:223]
	v_lshl_add_u64 v[224:225], s[0:1], 0, v[222:223]
	global_load_dword v10, v[224:225], off
	global_load_dword v11, v[224:225], off offset:256
	v_lshl_add_u64 v[224:225], s[2:3], 0, v[222:223]
	global_load_dword v12, v[224:225], off
	global_load_dword v13, v[224:225], off offset:256
	v_add_u32_e32 v222, 0x200, v2
	v_ashrrev_i32_e32 v223, 31, v222
	v_lshlrev_b64 v[222:223], 2, v[222:223]
	v_lshl_add_u64 v[224:225], s[0:1], 0, v[222:223]
	global_load_dword v14, v[224:225], off
	global_load_dword v15, v[224:225], off offset:256
	v_lshl_add_u64 v[224:225], s[2:3], 0, v[222:223]
	global_load_dword v16, v[224:225], off
	global_load_dword v17, v[224:225], off offset:256
	v_add_u32_e32 v222, 0x400, v2
	v_ashrrev_i32_e32 v223, 31, v222
	v_lshlrev_b64 v[222:223], 2, v[222:223]
	v_lshl_add_u64 v[224:225], s[0:1], 0, v[222:223]
	global_load_dword v18, v[224:225], off
	global_load_dword v19, v[224:225], off offset:256
	v_lshl_add_u64 v[224:225], s[2:3], 0, v[222:223]
	global_load_dword v20, v[224:225], off
	global_load_dword v21, v[224:225], off offset:256
	v_add_u32_e32 v222, 0x600, v2
	v_ashrrev_i32_e32 v223, 31, v222
	v_lshlrev_b64 v[222:223], 2, v[222:223]
	v_lshl_add_u64 v[224:225], s[0:1], 0, v[222:223]
	global_load_dword v22, v[224:225], off
	global_load_dword v23, v[224:225], off offset:256
	v_lshl_add_u64 v[224:225], s[2:3], 0, v[222:223]
	global_load_dword v24, v[224:225], off
	global_load_dword v25, v[224:225], off offset:256
	v_add_u32_e32 v9, 0x2400, v1
	s_waitcnt vmcnt(16)
	v_cvt_pk_bf16_f32 v226, v206, v207
	v_cvt_pk_bf16_f32 v230, v208, v209
	v_cvt_pk_bf16_f32 v227, v210, v211
	v_cvt_pk_bf16_f32 v231, v212, v213
	v_cvt_pk_bf16_f32 v228, v214, v215
	v_cvt_pk_bf16_f32 v232, v216, v217
	v_cvt_pk_bf16_f32 v229, v218, v219
	v_cvt_pk_bf16_f32 v233, v220, v221
	ds_write2_b32 v1, v226, v227 offset1:4
	ds_write2_b32 v9, v230, v231 offset1:4
	ds_write2_b32 v1, v228, v229 offset0:8 offset1:12
	ds_write2_b32 v9, v232, v233 offset0:8 offset1:12
	v_add_u32_e32 v1, 64, v1
	v_add_u32_e32 v9, 0x2400, v1
	s_waitcnt vmcnt(0)
	v_cvt_pk_bf16_f32 v226, v10, v11
	v_cvt_pk_bf16_f32 v230, v12, v13
	v_cvt_pk_bf16_f32 v227, v14, v15
	v_cvt_pk_bf16_f32 v231, v16, v17
	v_cvt_pk_bf16_f32 v228, v18, v19
	v_cvt_pk_bf16_f32 v232, v20, v21
	v_cvt_pk_bf16_f32 v229, v22, v23
	v_cvt_pk_bf16_f32 v233, v24, v25
	ds_write2_b32 v1, v226, v227 offset1:4
	ds_write2_b32 v9, v230, v231 offset1:4
	ds_write2_b32 v1, v228, v229 offset0:8 offset1:12
	ds_write2_b32 v9, v232, v233 offset0:8 offset1:12
	s_cmpk_lg_i32 s38, 0x1000
	v_and_b32_e32 v145, 31, v51
	v_mul_u32_u24_e32 v0, 0x48, v145
	v_lshrrev_b32_e32 v1, 1, v51
	v_lshlrev_b32_e32 v0, 1, v0
	v_and_b32_e32 v1, 16, v1
	s_movk_i32 s0, 0x1200
	v_add3_u32 v135, 0, v0, v1
	v_mov_b32_e32 v0, 0
	v_mul_lo_u32 v134, v96, s0
	s_mov_b32 s0, -16
	v_mov_b32_e32 v1, v0
	v_mov_b32_e32 v2, v0
	v_mov_b32_e32 v3, v0
	v_mov_b32_e32 v4, v0
	v_mov_b32_e32 v5, v0
	v_mov_b32_e32 v6, v0
	v_mov_b32_e32 v7, v0
	v_mov_b32_e32 v8, v0
	v_mov_b32_e32 v9, v0
	v_mov_b32_e32 v10, v0
	v_mov_b32_e32 v11, v0
	v_mov_b32_e32 v12, v0
	v_mov_b32_e32 v13, v0
	v_mov_b32_e32 v14, v0
	v_mov_b32_e32 v15, v0
	v_mov_b32_e32 v32, v0
	v_mov_b32_e32 v33, v0
	v_mov_b32_e32 v34, v0
	v_mov_b32_e32 v35, v0
	v_mov_b32_e32 v36, v0
	v_mov_b32_e32 v37, v0
	v_mov_b32_e32 v38, v0
	v_mov_b32_e32 v39, v0
	v_mov_b32_e32 v40, v0
	v_mov_b32_e32 v41, v0
	v_mov_b32_e32 v42, v0
	v_mov_b32_e32 v43, v0
	v_mov_b32_e32 v44, v0
	v_mov_b32_e32 v45, v0
	v_mov_b32_e32 v46, v0
	v_mov_b32_e32 v47, v0
	v_mov_b32_e32 v16, v0
	v_mov_b32_e32 v17, v0
	v_mov_b32_e32 v18, v0
	v_mov_b32_e32 v19, v0
	v_mov_b32_e32 v20, v0
	v_mov_b32_e32 v21, v0
	v_mov_b32_e32 v22, v0
	v_mov_b32_e32 v23, v0
	v_mov_b32_e32 v24, v0
	v_mov_b32_e32 v25, v0
	v_mov_b32_e32 v26, v0
	v_mov_b32_e32 v27, v0
	v_mov_b32_e32 v28, v0
	v_mov_b32_e32 v29, v0
	v_mov_b32_e32 v30, v0
	v_mov_b32_e32 v31, v0
	v_mov_b32_e32 v48, v0
	v_mov_b32_e32 v49, v0
	v_mov_b32_e32 v50, v0
	v_mov_b32_e32 v51, v0
	v_mov_b32_e32 v52, v0
	v_mov_b32_e32 v53, v0
	v_mov_b32_e32 v54, v0
	v_mov_b32_e32 v55, v0
	v_mov_b32_e32 v56, v0
	v_mov_b32_e32 v57, v0
	v_mov_b32_e32 v58, v0
	v_mov_b32_e32 v59, v0
	v_mov_b32_e32 v60, v0
	v_mov_b32_e32 v61, v0
	v_mov_b32_e32 v62, v0
	v_mov_b32_e32 v63, v0
	s_waitcnt lgkmcnt(0)
	s_barrier
.LBB0_908:
	v_add_u32_e32 v137, v135, v134
	ds_read_b128 v[146:149], v135 offset:18432
	ds_read_b128 v[150:153], v137
	s_add_i32 s0, s0, 32
	s_cmp_lt_u32 s0, 48
	s_waitcnt lgkmcnt(0)
	v_mfma_f32_32x32x16_bf16 v[48:63], v[150:153], v[146:149], v[48:63]
	ds_read_b128 v[146:149], v135 offset:23040
	s_waitcnt lgkmcnt(0)
	v_mfma_f32_32x32x16_bf16 v[16:31], v[150:153], v[146:149], v[16:31]
	ds_read_b128 v[146:149], v135 offset:27648
	s_waitcnt lgkmcnt(0)
	v_mfma_f32_32x32x16_bf16 v[32:47], v[150:153], v[146:149], v[32:47]
	ds_read_b128 v[146:149], v135 offset:32256
	ds_read_b128 v[154:157], v135 offset:18464
	s_waitcnt lgkmcnt(1)
	v_mfma_f32_32x32x16_bf16 v[0:15], v[150:153], v[146:149], v[0:15]
	ds_read_b128 v[146:149], v137 offset:32
	ds_read_b128 v[150:153], v135 offset:23072
	s_waitcnt lgkmcnt(0)
	v_mfma_f32_32x32x16_bf16 v[16:31], v[146:149], v[150:153], v[16:31]
	ds_read_b128 v[150:153], v135 offset:27680
	s_waitcnt lgkmcnt(0)
	v_mfma_f32_32x32x16_bf16 v[32:47], v[146:149], v[150:153], v[32:47]
	ds_read_b128 v[150:153], v135 offset:32288
	v_add_u32_e32 v135, 64, v135
	v_mfma_f32_32x32x16_bf16 v[48:63], v[146:149], v[154:157], v[48:63]
	s_waitcnt lgkmcnt(0)
	v_mfma_f32_32x32x16_bf16 v[0:15], v[146:149], v[150:153], v[0:15]
	s_cbranch_scc1 .LBB0_908
	s_cmp_gt_u32 s12, 1
	v_readlane_b32 s0, v248, 27
	s_cselect_b32 s2, 19, 1
	s_or_b32 s3, s13, s0
	v_lshlrev_b32_e32 v137, 11, v96
	v_or_b32_e32 v96, s3, v145
	s_nop 0
	v_lshlrev_b64 v[134:135], 2, v[96:97]
	v_readlane_b32 s18, v251, 22
	v_readlane_b32 s19, v251, 23
	s_barrier
	s_nop 0
	v_lshl_add_u64 v[138:139], s[18:19], 0, v[134:135]
	v_readlane_b32 s100, v251, 16
	v_readlane_b32 s101, v251, 17
	s_nop 1
	v_lshl_add_u64 v[220:221], s[100:101], 0, v[134:135]
	v_readlane_b32 s100, v251, 20
	v_readlane_b32 s101, v251, 21
	s_nop 1
	v_lshl_add_u64 v[222:223], s[100:101], 0, v[134:135]
	global_load_dword v224, v[220:221], off
	global_load_dword v225, v[222:223], off
	global_load_dword v226, v[138:139], off offset:128
	global_load_dword v227, v[222:223], off offset:128
	global_load_dword v228, v[220:221], off offset:128
	global_load_dword v96, v[138:139], off
	s_mov_b32 s8, 0x3f2aaaab
	s_mov_b32 s9, 0x3f317218
	s_mov_b32 s10, 0x7f800000
	s_mov_b32 s20, 0x33800000
	v_readlane_b32 s40, v251, 4
	v_readlane_b32 s52, v251, 16
	v_readlane_b32 s53, v251, 17
	s_mov_b32 s21, 0x43000000
	s_mov_b32 s22, 0x42b17217
	s_mov_b32 s23, 0xf800000
	s_mov_b32 s24, 0xc1880000
	v_readlane_b32 s30, v248, 2
	s_cmp_eq_u32 s2, s12
	v_readlane_b32 s31, v248, 3
	s_mov_b32 s28, 0x4800000
	s_movk_i32 s29, 0x47ff
	s_mov_b32 s25, 0x85000
	v_readlane_b32 s27, v248, 10
	v_readlane_b32 s26, v251, 30
	v_readlane_b32 s41, v251, 5
	v_readlane_b32 s42, v251, 6
	v_readlane_b32 s43, v251, 7
	v_readlane_b32 s44, v251, 8
	v_readlane_b32 s45, v251, 9
	v_readlane_b32 s46, v251, 10
	v_readlane_b32 s47, v251, 11
	v_readlane_b32 s48, v251, 12
	v_readlane_b32 s49, v251, 13
	v_readlane_b32 s50, v251, 14
	v_readlane_b32 s51, v251, 15
	v_readlane_b32 s54, v251, 18
	v_readlane_b32 s55, v251, 19
	s_waitcnt vmcnt(0)
	v_mul_f32_e32 v96, 0xbfb8aa3b, v96
	v_exp_f32_e32 v96, v96
	s_nop 0
	v_add_f32_e32 v144, 1.0, v96
	v_add_f32_e32 v138, -1.0, v144
	v_sub_f32_e32 v139, v138, v144
	v_add_f32_e32 v139, 1.0, v139
	v_sub_f32_e32 v138, v96, v138
	v_add_f32_e32 v146, v138, v139
	v_frexp_mant_f32_e32 v138, v144
	v_cmp_gt_f32_e32 vcc, s8, v138
	v_cvt_f64_f32_e32 v[138:139], v144
	v_frexp_exp_i32_f64_e32 v138, v[138:139]
	v_subbrev_co_u32_e32 v152, vcc, 0, v138, vcc
	v_sub_u32_e32 v138, 0, v152
	v_ldexp_f32 v139, v144, v138
	v_add_f32_e32 v144, -1.0, v139
	v_add_f32_e32 v147, 1.0, v139
	v_ldexp_f32 v138, v146, v138
	v_add_f32_e32 v146, 1.0, v144
	v_add_f32_e32 v148, -1.0, v147
	v_sub_f32_e32 v146, v139, v146
	v_sub_f32_e32 v139, v139, v148
	v_add_f32_e32 v146, v138, v146
	v_add_f32_e32 v138, v138, v139
	v_add_f32_e32 v153, v147, v138
	v_rcp_f32_e32 v155, v153
	v_sub_f32_e32 v139, v153, v147
	v_sub_f32_e32 v154, v138, v139
	v_add_f32_e32 v139, v144, v146
	v_sub_f32_e32 v138, v139, v144
	v_mul_f32_e32 v156, v139, v155
	v_sub_f32_e32 v144, v146, v138
	v_mul_f32_e32 v146, v153, v156
	v_fma_f32 v148, v156, v153, -v146
	v_fmac_f32_e32 v148, v156, v154
	v_add_f32_e32 v138, v146, v148
	v_sub_f32_e32 v147, v139, v138
	v_pk_add_f32 v[150:151], v[138:139], v[146:147] neg_lo:[0,1] neg_hi:[0,1]
	v_mov_b32_e32 v149, v138
	v_pk_add_f32 v[138:139], v[150:151], v[148:149] neg_lo:[0,1] neg_hi:[0,1]
	v_cmp_neq_f32_e32 vcc, s10, v96
	v_add_f32_e32 v139, v144, v139
	v_add_f32_e32 v138, v138, v139
	v_add_f32_e32 v139, v147, v138
	v_mul_f32_e32 v144, v155, v139
	v_mul_f32_e32 v146, v153, v144
	v_fma_f32 v148, v144, v153, -v146
	v_fmac_f32_e32 v148, v144, v154
	v_sub_f32_e32 v147, v147, v139
	v_add_f32_e32 v153, v138, v147
	v_add_f32_e32 v138, v146, v148
	v_sub_f32_e32 v147, v139, v138
	v_pk_add_f32 v[150:151], v[138:139], v[146:147] neg_lo:[0,1] neg_hi:[0,1]
	v_mov_b32_e32 v149, v138
	v_pk_add_f32 v[138:139], v[150:151], v[148:149] neg_lo:[0,1] neg_hi:[0,1]
	v_add_f32_e32 v139, v153, v139
	v_add_f32_e32 v138, v138, v139
	v_add_f32_e32 v139, v156, v144
	v_add_f32_e32 v138, v147, v138
	v_sub_f32_e32 v146, v139, v156
	v_mul_f32_e32 v138, v155, v138
	v_sub_f32_e32 v144, v144, v146
	v_add_f32_e32 v144, v144, v138
	v_add_f32_e32 v146, v139, v144
	v_mul_f32_e32 v148, v146, v146
	v_fmamk_f32 v138, v148, 0x3e9b6dac, v191
	v_fmaak_f32 v169, v148, v138, 0x3f2aaada
	v_cvt_f32_i32_e32 v138, v152
	v_sub_f32_e32 v139, v146, v139
	v_sub_f32_e32 v139, v144, v139
	v_ldexp_f32 v144, v139, 1
	v_mul_f32_e32 v139, v146, v148
	v_pk_mul_f32 v[148:149], v[138:139], v[168:169]
	v_ldexp_f32 v147, v146, 1
	v_fma_f32 v146, v138, s9, -v148
	v_fmac_f32_e32 v146, 0xb102e308, v138
	v_pk_add_f32 v[138:139], v[148:149], v[146:147]
	v_mov_b32_e32 v150, v148
	v_sub_f32_e32 v147, v139, v147
	v_sub_f32_e32 v147, v149, v147
	v_add_f32_e32 v151, v144, v147
	v_pk_add_f32 v[148:149], v[138:139], v[148:149] neg_lo:[0,1] neg_hi:[0,1]
	v_pk_add_f32 v[152:153], v[138:139], v[150:151]
	v_mov_b32_e32 v147, v138
	v_mov_b32_e32 v149, v153
	v_pk_add_f32 v[154:155], v[146:147], v[148:149] neg_lo:[0,1] neg_hi:[0,1]
	v_pk_add_f32 v[146:147], v[146:147], v[148:149]
	v_mov_b32_e32 v150, v151
	v_pk_add_f32 v[148:149], v[146:147], v[138:139] op_sel:[1,0] op_sel_hi:[0,1] neg_lo:[0,1] neg_hi:[0,1]
	v_pk_add_f32 v[156:157], v[152:153], v[148:149] op_sel_hi:[1,0] neg_lo:[0,1] neg_hi:[0,1]
	v_mov_b32_e32 v152, v153
	v_mov_b32_e32 v153, v147
	v_pk_mov_b32 v[148:149], v[138:139], v[148:149] op_sel:[1,0]
	v_mov_b32_e32 v151, v138
	v_pk_add_f32 v[148:149], v[152:153], v[148:149] neg_lo:[0,1] neg_hi:[0,1]
	v_mov_b32_e32 v156, v154
	v_pk_add_f32 v[138:139], v[150:151], v[148:149] neg_lo:[0,1] neg_hi:[0,1]
	v_mov_b32_e32 v155, v147
	v_pk_add_f32 v[148:149], v[156:157], v[138:139]
	v_pk_add_f32 v[150:151], v[148:149], v[148:149] op_sel:[0,1] op_sel_hi:[1,0]
	v_pk_add_f32 v[146:147], v[146:147], v[150:151] op_sel:[1,0] op_sel_hi:[0,1]
	v_mov_b32_e32 v149, v146
	v_pk_add_f32 v[152:153], v[148:149], v[154:155] neg_lo:[0,1] neg_hi:[0,1]
	v_mov_b32_e32 v139, v150
	v_sub_f32_e32 v144, v148, v152
	v_pk_add_f32 v[138:139], v[138:139], v[152:153] neg_lo:[0,1] neg_hi:[0,1]
	v_sub_f32_e32 v144, v154, v144
	v_add_f32_e32 v138, v138, v144
	v_add_f32_e32 v138, v138, v139
	v_add_f32_e32 v138, v146, v138
	v_cndmask_b32_e32 v138, v199, v138, vcc
	v_cmp_ngt_f32_e32 vcc, -1.0, v96
	s_nop 1
	v_cndmask_b32_e32 v138, v200, v138, vcc
	v_cmp_neq_f32_e32 vcc, -1.0, v96
	s_nop 1
	v_cndmask_b32_e32 v138, v201, v138, vcc
	v_cmp_lt_f32_e64 vcc, |v96|, s20
	s_nop 1
	v_cndmask_b32_e32 v96, v138, v96, vcc
	v_mov_b32_e32 v147, v224
	v_mov_b32_e32 v146, v225
	v_mul_f32_e32 v96, 0xc1000000, v96
	s_waitcnt vmcnt(1)
	v_add_f32_e32 v48, v48, v147
	v_mul_f32_e32 v48, 0xbfb8aa3b, v48
	v_exp_f32_e32 v48, v48
	s_waitcnt vmcnt(0)
	v_add_f32_e32 v32, v32, v146
	v_mul_f32_e32 v32, 0xbfb8aa3b, v32
	v_exp_f32_e32 v32, v32
	v_add_f32_e32 v48, 1.0, v48
	v_rcp_f32_e32 v48, v48
	v_add_f32_e32 v33, v33, v146
	v_add_f32_e32 v32, 1.0, v32
	v_rcp_f32_e32 v32, v32
	v_mul_f32_e32 v48, v48, v96
	v_mul_f32_e32 v134, 0x3fb8aa3b, v48
	v_add_f32_e32 v48, v48, v48
	v_exp_f32_e32 v138, v134
	v_mul_f32_e32 v134, 0x3fb8aa3b, v48
	v_rndne_f32_e32 v134, v134
	v_fmamk_f32 v135, v134, 0xbf317218, v48
	v_fmac_f32_e32 v135, 0x3102e308, v134
	v_fmamk_f32 v139, v135, 0x395133b1, v192
	v_cmp_eq_f32_e32 vcc, s21, v134
	v_cvt_i32_f32_e32 v134, v134
	v_fmaak_f32 v139, v135, v139, 0x3c0887f9
	v_fmaak_f32 v139, v135, v139, 0x3d2aaa81
	v_fmaak_f32 v139, v135, v139, 0x3e2aaaab
	v_fma_f32 v139, v135, v139, 0.5
	v_ldexp_f32 v134, 1.0, v134
	v_mul_f32_e32 v139, v135, v139
	v_cndmask_b32_e32 v134, v134, v202, vcc
	v_fmac_f32_e32 v135, v135, v139
	v_add_f32_e32 v139, -1.0, v134
	v_fmac_f32_e32 v139, v134, v135
	v_add_f32_e32 v134, v139, v139
	v_cndmask_b32_e32 v134, v139, v134, vcc
	v_cmp_nlt_f32_e32 vcc, s22, v48
	v_mul_f32_e32 v33, 0xbfb8aa3b, v33
	v_exp_f32_e32 v33, v33
	v_cndmask_b32_e64 v134, v201, -v134, vcc
	v_cmp_gt_f32_e32 vcc, s23, v134
	v_mul_f32_e32 v135, 0x4f800000, v134
	v_add_f32_e32 v33, 1.0, v33
	v_cndmask_b32_e32 v134, v134, v135, vcc
	v_sqrt_f32_e32 v135, v134
	v_rcp_f32_e32 v33, v33
	v_add_f32_e32 v34, v34, v146
	v_mul_f32_e32 v34, 0xbfb8aa3b, v34
	v_add_u32_e32 v139, -1, v135
	v_fma_f32 v144, -v139, v135, v134
	v_cmp_ge_f32_e64 s[0:1], 0, v144
	v_add_u32_e32 v144, 1, v135
	v_exp_f32_e32 v34, v34
	v_cndmask_b32_e64 v139, v135, v139, s[0:1]
	v_fma_f32 v135, -v144, v135, v134
	v_cmp_lt_f32_e64 s[0:1], 0, v135
	v_add_f32_e32 v34, 1.0, v34
	v_rcp_f32_e32 v34, v34
	v_cndmask_b32_e64 v135, v139, v144, s[0:1]
	v_mul_f32_e32 v139, 0x37800000, v135
	v_cndmask_b32_e32 v135, v135, v139, vcc
	v_cmp_class_f32_e32 vcc, v134, v193
	s_nop 1
	v_cndmask_b32_e32 v134, v135, v134, vcc
	v_cmp_ngt_f32_e32 vcc, s24, v48
	s_nop 1
	v_cndmask_b32_e32 v48, 1.0, v134, vcc
	v_mul_f32_e32 v48, v32, v48
	v_and_b32_e32 v32, 0x100, v136
	v_or3_b32 v32, v137, v145, v32
	v_lshl_add_u32 v144, v32, 2, 0
	v_add_u32_e32 v32, 0x9000, v144
	ds_read2_b32 v[134:135], v32 offset1:32
	s_waitcnt lgkmcnt(0)
	v_mul_f32_e32 v48, v134, v48
	ds_write_b32 v144, v138
	ds_write_b32 v144, v48 offset:36864
	v_add_f32_e32 v48, v49, v147
	v_mul_f32_e32 v48, 0xbfb8aa3b, v48
	v_exp_f32_e32 v48, v48
	s_nop 0
	v_add_f32_e32 v48, 1.0, v48
	v_rcp_f32_e32 v48, v48
	s_nop 0
	v_mul_f32_e32 v48, v48, v96
	v_mul_f32_e32 v49, 0x3fb8aa3b, v48
	v_add_f32_e32 v48, v48, v48
	v_exp_f32_e32 v134, v49
	v_mul_f32_e32 v49, 0x3fb8aa3b, v48
	v_rndne_f32_e32 v49, v49
	v_fmamk_f32 v136, v49, 0xbf317218, v48
	v_fmac_f32_e32 v136, 0x3102e308, v49
	v_fmamk_f32 v137, v136, 0x395133b1, v192
	v_cmp_eq_f32_e32 vcc, s21, v49
	v_cvt_i32_f32_e32 v49, v49
	v_fmaak_f32 v137, v136, v137, 0x3c0887f9
	v_fmaak_f32 v137, v136, v137, 0x3d2aaa81
	v_fmaak_f32 v137, v136, v137, 0x3e2aaaab
	v_fma_f32 v137, v136, v137, 0.5
	v_ldexp_f32 v49, 1.0, v49
	v_mul_f32_e32 v137, v136, v137
	v_cndmask_b32_e32 v49, v49, v202, vcc
	v_fmac_f32_e32 v136, v136, v137
	v_add_f32_e32 v137, -1.0, v49
	v_fmac_f32_e32 v137, v49, v136
	v_add_f32_e32 v49, v137, v137
	v_cndmask_b32_e32 v49, v137, v49, vcc
	v_cmp_nlt_f32_e32 vcc, s22, v48
	s_nop 1
	v_cndmask_b32_e64 v49, v201, -v49, vcc
	v_cmp_gt_f32_e32 vcc, s23, v49
	v_mul_f32_e32 v136, 0x4f800000, v49
	s_nop 0
	v_cndmask_b32_e32 v49, v49, v136, vcc
	v_sqrt_f32_e32 v136, v49
	s_nop 0
	v_add_u32_e32 v137, -1, v136
	v_fma_f32 v138, -v137, v136, v49
	v_cmp_ge_f32_e64 s[0:1], 0, v138
	v_add_u32_e32 v138, 1, v136
	s_nop 0
	v_cndmask_b32_e64 v137, v136, v137, s[0:1]
	v_fma_f32 v136, -v138, v136, v49
	v_cmp_lt_f32_e64 s[0:1], 0, v136
	s_nop 1
	v_cndmask_b32_e64 v136, v137, v138, s[0:1]
	v_mul_f32_e32 v137, 0x37800000, v136
	v_cndmask_b32_e32 v136, v136, v137, vcc
	v_cmp_class_f32_e32 vcc, v49, v193
	s_nop 1
	v_cndmask_b32_e32 v49, v136, v49, vcc
	v_cmp_ngt_f32_e32 vcc, s24, v48
	s_nop 1
	v_cndmask_b32_e32 v48, 1.0, v49, vcc
	v_mul_f32_e32 v33, v33, v48
	ds_read2_b32 v[48:49], v32 offset0:64 offset1:96
	s_waitcnt lgkmcnt(0)
	v_mul_f32_e32 v33, v48, v33
	ds_write_b32 v144, v134 offset:256
	ds_write_b32 v144, v33 offset:37120
	v_add_f32_e32 v33, v50, v147
	v_mul_f32_e32 v33, 0xbfb8aa3b, v33
	v_exp_f32_e32 v33, v33
	s_nop 0
	v_add_f32_e32 v33, 1.0, v33
	v_rcp_f32_e32 v33, v33
	s_nop 0
	v_mul_f32_e32 v33, v33, v96
	v_mul_f32_e32 v48, 0x3fb8aa3b, v33
	v_add_f32_e32 v33, v33, v33
	v_mul_f32_e32 v50, 0x3fb8aa3b, v33
	v_rndne_f32_e32 v50, v50
	v_fmamk_f32 v134, v50, 0xbf317218, v33
	v_fmac_f32_e32 v134, 0x3102e308, v50
	v_fmamk_f32 v136, v134, 0x395133b1, v192
	v_cmp_eq_f32_e32 vcc, s21, v50
	v_cvt_i32_f32_e32 v50, v50
	v_fmaak_f32 v136, v134, v136, 0x3c0887f9
	v_fmaak_f32 v136, v134, v136, 0x3d2aaa81
	v_fmaak_f32 v136, v134, v136, 0x3e2aaaab
	v_fma_f32 v136, v134, v136, 0.5
	v_ldexp_f32 v50, 1.0, v50
	v_mul_f32_e32 v136, v134, v136
	v_cndmask_b32_e32 v50, v50, v202, vcc
	v_fmac_f32_e32 v134, v134, v136
	v_add_f32_e32 v136, -1.0, v50
	v_fmac_f32_e32 v136, v50, v134
	v_add_f32_e32 v50, v136, v136
	v_cndmask_b32_e32 v50, v136, v50, vcc
	v_cmp_nlt_f32_e32 vcc, s22, v33
	v_exp_f32_e32 v48, v48
	s_nop 0
	v_cndmask_b32_e64 v50, v201, -v50, vcc
	v_cmp_gt_f32_e32 vcc, s23, v50
	v_mul_f32_e32 v134, 0x4f800000, v50
	s_nop 0
	v_cndmask_b32_e32 v50, v50, v134, vcc
	v_sqrt_f32_e32 v134, v50
	s_nop 0
	v_add_u32_e32 v136, -1, v134
	v_fma_f32 v137, -v136, v134, v50
	v_cmp_ge_f32_e64 s[0:1], 0, v137
	v_add_u32_e32 v137, 1, v134
	s_nop 0
	v_cndmask_b32_e64 v136, v134, v136, s[0:1]
	v_fma_f32 v134, -v137, v134, v50
	v_cmp_lt_f32_e64 s[0:1], 0, v134
	s_nop 1
	v_cndmask_b32_e64 v134, v136, v137, s[0:1]
	v_mul_f32_e32 v136, 0x37800000, v134
	v_cndmask_b32_e32 v134, v134, v136, vcc
	ds_read2_b32 v[136:137], v32 offset0:128 offset1:160
	v_cmp_class_f32_e32 vcc, v50, v193
	s_nop 1
	v_cndmask_b32_e32 v50, v134, v50, vcc
	v_cmp_ngt_f32_e32 vcc, s24, v33
	s_nop 1
	v_cndmask_b32_e32 v33, 1.0, v50, vcc
	v_mul_f32_e32 v33, v34, v33
	s_waitcnt lgkmcnt(0)
	v_mul_f32_e32 v33, v136, v33
	ds_write_b32 v144, v48 offset:512
	ds_write_b32 v144, v33 offset:37376
	v_add_f32_e32 v33, v51, v147
	v_mul_f32_e32 v33, 0xbfb8aa3b, v33
	v_exp_f32_e32 v33, v33
	v_add_f32_e32 v34, v35, v146
	v_mul_f32_e32 v34, 0xbfb8aa3b, v34
	v_exp_f32_e32 v34, v34
	v_add_f32_e32 v33, 1.0, v33
	v_rcp_f32_e32 v33, v33
	v_add_f32_e32 v34, 1.0, v34
	v_rcp_f32_e32 v34, v34
	v_mul_f32_e32 v33, v33, v96
	v_mul_f32_e32 v35, 0x3fb8aa3b, v33
	v_add_f32_e32 v33, v33, v33
	v_mul_f32_e32 v48, 0x3fb8aa3b, v33
	v_rndne_f32_e32 v48, v48
	v_fmamk_f32 v50, v48, 0xbf317218, v33
	v_fmac_f32_e32 v50, 0x3102e308, v48
	v_fmamk_f32 v51, v50, 0x395133b1, v192
	v_cmp_eq_f32_e32 vcc, s21, v48
	v_cvt_i32_f32_e32 v48, v48
	v_fmaak_f32 v51, v50, v51, 0x3c0887f9
	v_fmaak_f32 v51, v50, v51, 0x3d2aaa81
	v_fmaak_f32 v51, v50, v51, 0x3e2aaaab
	v_fma_f32 v51, v50, v51, 0.5
	v_ldexp_f32 v48, 1.0, v48
	v_mul_f32_e32 v51, v50, v51
	v_cndmask_b32_e32 v48, v48, v202, vcc
	v_fmac_f32_e32 v50, v50, v51
	v_add_f32_e32 v51, -1.0, v48
	v_fmac_f32_e32 v51, v48, v50
	v_add_f32_e32 v48, v51, v51
	v_cndmask_b32_e32 v48, v51, v48, vcc
	v_cmp_nlt_f32_e32 vcc, s22, v33
	v_exp_f32_e32 v35, v35
	s_nop 0
	v_cndmask_b32_e64 v48, v201, -v48, vcc
	v_cmp_gt_f32_e32 vcc, s23, v48
	v_mul_f32_e32 v50, 0x4f800000, v48
	s_nop 0
	v_cndmask_b32_e32 v48, v48, v50, vcc
	v_sqrt_f32_e32 v50, v48
	s_nop 0
	v_add_u32_e32 v51, -1, v50
	v_fma_f32 v134, -v51, v50, v48
	v_cmp_ge_f32_e64 s[0:1], 0, v134
	v_add_u32_e32 v134, 1, v50
	s_nop 0
	v_cndmask_b32_e64 v51, v50, v51, s[0:1]
	v_fma_f32 v50, -v134, v50, v48
	v_cmp_lt_f32_e64 s[0:1], 0, v50
	s_nop 1
	v_cndmask_b32_e64 v50, v51, v134, s[0:1]
	v_mul_f32_e32 v51, 0x37800000, v50
	v_cndmask_b32_e32 v50, v50, v51, vcc
	v_cmp_class_f32_e32 vcc, v48, v193
	s_nop 1
	v_cndmask_b32_e32 v48, v50, v48, vcc
	ds_read2_b32 v[50:51], v32 offset0:192 offset1:224
	v_cmp_ngt_f32_e32 vcc, s24, v33
	s_nop 1
	v_cndmask_b32_e32 v33, 1.0, v48, vcc
	v_mul_f32_e32 v33, v34, v33
	s_waitcnt lgkmcnt(0)
	v_mul_f32_e32 v32, v50, v33
	ds_write_b32 v144, v35 offset:768
	ds_write_b32 v144, v32 offset:37632
	v_add_f32_e32 v32, v52, v147
	v_mul_f32_e32 v32, 0xbfb8aa3b, v32
	v_exp_f32_e32 v32, v32
	v_add_f32_e32 v33, v36, v146
	v_mul_f32_e32 v33, 0xbfb8aa3b, v33
	v_exp_f32_e32 v33, v33
	v_add_f32_e32 v32, 1.0, v32
	v_rcp_f32_e32 v32, v32
	v_add_f32_e32 v33, 1.0, v33
	v_rcp_f32_e32 v33, v33
	v_mul_f32_e32 v32, v32, v96
	v_mul_f32_e32 v34, 0x3fb8aa3b, v32
	v_add_f32_e32 v32, v32, v32
	v_mul_f32_e32 v35, 0x3fb8aa3b, v32
	v_rndne_f32_e32 v35, v35
	v_fmamk_f32 v36, v35, 0xbf317218, v32
	v_fmac_f32_e32 v36, 0x3102e308, v35
	v_fmamk_f32 v48, v36, 0x395133b1, v192
	v_cmp_eq_f32_e32 vcc, s21, v35
	v_cvt_i32_f32_e32 v35, v35
	v_fmaak_f32 v48, v36, v48, 0x3c0887f9
	v_fmaak_f32 v48, v36, v48, 0x3d2aaa81
	v_fmaak_f32 v48, v36, v48, 0x3e2aaaab
	v_fma_f32 v48, v36, v48, 0.5
	v_ldexp_f32 v35, 1.0, v35
	v_mul_f32_e32 v48, v36, v48
	v_cndmask_b32_e32 v35, v35, v202, vcc
	v_fmac_f32_e32 v36, v36, v48
	v_add_f32_e32 v48, -1.0, v35
	v_fmac_f32_e32 v48, v35, v36
	v_add_f32_e32 v35, v48, v48
	v_cndmask_b32_e32 v35, v48, v35, vcc
	v_cmp_nlt_f32_e32 vcc, s22, v32
	v_exp_f32_e32 v34, v34
	s_nop 0
	v_cndmask_b32_e64 v35, v201, -v35, vcc
	v_cmp_gt_f32_e32 vcc, s23, v35
	v_mul_f32_e32 v36, 0x4f800000, v35
	s_nop 0
	v_cndmask_b32_e32 v35, v35, v36, vcc
	v_sqrt_f32_e32 v36, v35
	s_nop 0
	v_add_u32_e32 v48, -1, v36
	v_fma_f32 v50, -v48, v36, v35
	v_cmp_ge_f32_e64 s[0:1], 0, v50
	v_add_u32_e32 v50, 1, v36
	s_nop 0
	v_cndmask_b32_e64 v48, v36, v48, s[0:1]
	v_fma_f32 v36, -v50, v36, v35
	v_cmp_lt_f32_e64 s[0:1], 0, v36
	s_nop 1
	v_cndmask_b32_e64 v36, v48, v50, s[0:1]
	v_mul_f32_e32 v48, 0x37800000, v36
	v_cndmask_b32_e32 v36, v36, v48, vcc
	v_cmp_class_f32_e32 vcc, v35, v193
	s_nop 1
	v_cndmask_b32_e32 v35, v36, v35, vcc
	v_cmp_ngt_f32_e32 vcc, s24, v32
	s_nop 1
	v_cndmask_b32_e32 v32, 1.0, v35, vcc
	v_mul_f32_e32 v33, v33, v32
	v_add_u32_e32 v32, 0x9800, v144
	ds_read2_b32 v[138:139], v32 offset1:32
	s_waitcnt lgkmcnt(0)
	v_mul_f32_e32 v33, v138, v33
	ds_write_b32 v144, v34 offset:2048
	ds_write_b32 v144, v33 offset:38912
	v_add_f32_e32 v33, v53, v147
	v_mul_f32_e32 v33, 0xbfb8aa3b, v33
	v_exp_f32_e32 v33, v33
	v_add_f32_e32 v34, v37, v146
	v_mul_f32_e32 v34, 0xbfb8aa3b, v34
	v_exp_f32_e32 v34, v34
	v_add_f32_e32 v33, 1.0, v33
	v_rcp_f32_e32 v33, v33
	v_add_f32_e32 v34, 1.0, v34
	v_rcp_f32_e32 v34, v34
	v_mul_f32_e32 v33, v33, v96
	v_mul_f32_e32 v35, 0x3fb8aa3b, v33
	v_add_f32_e32 v33, v33, v33
	v_mul_f32_e32 v36, 0x3fb8aa3b, v33
	v_rndne_f32_e32 v36, v36
	v_fmamk_f32 v37, v36, 0xbf317218, v33
	v_fmac_f32_e32 v37, 0x3102e308, v36
	v_fmamk_f32 v48, v37, 0x395133b1, v192
	v_cmp_eq_f32_e32 vcc, s21, v36
	v_cvt_i32_f32_e32 v36, v36
	v_fmaak_f32 v48, v37, v48, 0x3c0887f9
	v_fmaak_f32 v48, v37, v48, 0x3d2aaa81
	v_fmaak_f32 v48, v37, v48, 0x3e2aaaab
	v_fma_f32 v48, v37, v48, 0.5
	v_ldexp_f32 v36, 1.0, v36
	v_mul_f32_e32 v48, v37, v48
	v_cndmask_b32_e32 v36, v36, v202, vcc
	v_fmac_f32_e32 v37, v37, v48
	v_add_f32_e32 v48, -1.0, v36
	v_fmac_f32_e32 v48, v36, v37
	v_add_f32_e32 v36, v48, v48
	v_cndmask_b32_e32 v36, v48, v36, vcc
	v_cmp_nlt_f32_e32 vcc, s22, v33
	v_exp_f32_e32 v35, v35
	s_nop 0
	v_cndmask_b32_e64 v36, v201, -v36, vcc
	v_cmp_gt_f32_e32 vcc, s23, v36
	v_mul_f32_e32 v37, 0x4f800000, v36
	s_nop 0
	v_cndmask_b32_e32 v36, v36, v37, vcc
	v_sqrt_f32_e32 v37, v36
	s_nop 0
	v_add_u32_e32 v48, -1, v37
	v_fma_f32 v50, -v48, v37, v36
	v_cmp_ge_f32_e64 s[0:1], 0, v50
	v_add_u32_e32 v50, 1, v37
	s_nop 0
	v_cndmask_b32_e64 v48, v37, v48, s[0:1]
	v_fma_f32 v37, -v50, v37, v36
	v_cmp_lt_f32_e64 s[0:1], 0, v37
	s_nop 1
	v_cndmask_b32_e64 v37, v48, v50, s[0:1]
	v_mul_f32_e32 v48, 0x37800000, v37
	v_cndmask_b32_e32 v37, v37, v48, vcc
	v_cmp_class_f32_e32 vcc, v36, v193
	s_nop 1
	v_cndmask_b32_e32 v36, v37, v36, vcc
	v_cmp_ngt_f32_e32 vcc, s24, v33
	s_nop 1
	v_cndmask_b32_e32 v33, 1.0, v36, vcc
	ds_read2_b32 v[36:37], v32 offset0:64 offset1:96
	v_mul_f32_e32 v33, v34, v33
	v_add_f32_e32 v34, v38, v146
	v_mul_f32_e32 v34, 0xbfb8aa3b, v34
	v_exp_f32_e32 v34, v34
	s_waitcnt lgkmcnt(0)
	v_mul_f32_e32 v33, v36, v33
	ds_write_b32 v144, v35 offset:2304
	ds_write_b32 v144, v33 offset:39168
	v_add_f32_e32 v33, v54, v147
	v_mul_f32_e32 v33, 0xbfb8aa3b, v33
	v_exp_f32_e32 v33, v33
	v_add_f32_e32 v34, 1.0, v34
	v_rcp_f32_e32 v34, v34
	ds_read2_b32 v[52:53], v32 offset0:128 offset1:160
	v_add_f32_e32 v33, 1.0, v33
	v_rcp_f32_e32 v33, v33
	s_nop 0
	v_mul_f32_e32 v33, v33, v96
	v_mul_f32_e32 v35, 0x3fb8aa3b, v33
	v_add_f32_e32 v33, v33, v33
	v_mul_f32_e32 v36, 0x3fb8aa3b, v33
	v_rndne_f32_e32 v36, v36
	v_fmamk_f32 v38, v36, 0xbf317218, v33
	v_fmac_f32_e32 v38, 0x3102e308, v36
	v_fmamk_f32 v48, v38, 0x395133b1, v192
	v_cmp_eq_f32_e32 vcc, s21, v36
	v_cvt_i32_f32_e32 v36, v36
	v_fmaak_f32 v48, v38, v48, 0x3c0887f9
	v_fmaak_f32 v48, v38, v48, 0x3d2aaa81
	v_fmaak_f32 v48, v38, v48, 0x3e2aaaab
	v_fma_f32 v48, v38, v48, 0.5
	v_ldexp_f32 v36, 1.0, v36
	v_mul_f32_e32 v48, v38, v48
	v_cndmask_b32_e32 v36, v36, v202, vcc
	v_fmac_f32_e32 v38, v38, v48
	v_add_f32_e32 v48, -1.0, v36
	v_fmac_f32_e32 v48, v36, v38
	v_add_f32_e32 v36, v48, v48
	v_cndmask_b32_e32 v36, v48, v36, vcc
	v_cmp_nlt_f32_e32 vcc, s22, v33
	v_exp_f32_e32 v35, v35
	s_nop 0
	v_cndmask_b32_e64 v36, v201, -v36, vcc
	v_cmp_gt_f32_e32 vcc, s23, v36
	v_mul_f32_e32 v38, 0x4f800000, v36
	s_nop 0
	v_cndmask_b32_e32 v36, v36, v38, vcc
	v_sqrt_f32_e32 v38, v36
	s_nop 0
	v_add_u32_e32 v48, -1, v38
	v_fma_f32 v50, -v48, v38, v36
	v_cmp_ge_f32_e64 s[0:1], 0, v50
	v_add_u32_e32 v50, 1, v38
	s_nop 0
	v_cndmask_b32_e64 v48, v38, v48, s[0:1]
	v_fma_f32 v38, -v50, v38, v36
	v_cmp_lt_f32_e64 s[0:1], 0, v38
	s_nop 1
	v_cndmask_b32_e64 v38, v48, v50, s[0:1]
	v_mul_f32_e32 v48, 0x37800000, v38
	v_cndmask_b32_e32 v38, v38, v48, vcc
	v_cmp_class_f32_e32 vcc, v36, v193
	s_nop 1
	v_cndmask_b32_e32 v36, v38, v36, vcc
	v_cmp_ngt_f32_e32 vcc, s24, v33
	s_nop 1
	v_cndmask_b32_e32 v33, 1.0, v36, vcc
	v_mul_f32_e32 v33, v34, v33
	s_waitcnt lgkmcnt(0)
	v_mul_f32_e32 v33, v52, v33
	ds_write_b32 v144, v35 offset:2560
	ds_write_b32 v144, v33 offset:39424
	v_add_f32_e32 v33, v55, v147
	v_mul_f32_e32 v33, 0xbfb8aa3b, v33
	v_exp_f32_e32 v33, v33
	v_add_f32_e32 v34, v39, v146
	v_mul_f32_e32 v34, 0xbfb8aa3b, v34
	v_exp_f32_e32 v34, v34
	v_add_f32_e32 v33, 1.0, v33
	v_rcp_f32_e32 v33, v33
	v_add_f32_e32 v34, 1.0, v34
	v_rcp_f32_e32 v34, v34
	v_mul_f32_e32 v33, v33, v96
	v_mul_f32_e32 v35, 0x3fb8aa3b, v33
	v_add_f32_e32 v33, v33, v33
	v_mul_f32_e32 v36, 0x3fb8aa3b, v33
	v_rndne_f32_e32 v36, v36
	v_fmamk_f32 v38, v36, 0xbf317218, v33
	v_fmac_f32_e32 v38, 0x3102e308, v36
	v_fmamk_f32 v39, v38, 0x395133b1, v192
	v_cmp_eq_f32_e32 vcc, s21, v36
	v_cvt_i32_f32_e32 v36, v36
	v_fmaak_f32 v39, v38, v39, 0x3c0887f9
	v_fmaak_f32 v39, v38, v39, 0x3d2aaa81
	v_fmaak_f32 v39, v38, v39, 0x3e2aaaab
	v_fma_f32 v39, v38, v39, 0.5
	v_ldexp_f32 v36, 1.0, v36
	v_mul_f32_e32 v39, v38, v39
	v_cndmask_b32_e32 v36, v36, v202, vcc
	v_fmac_f32_e32 v38, v38, v39
	v_add_f32_e32 v39, -1.0, v36
	v_fmac_f32_e32 v39, v36, v38
	v_add_f32_e32 v36, v39, v39
	v_cndmask_b32_e32 v36, v39, v36, vcc
	v_cmp_nlt_f32_e32 vcc, s22, v33
	v_exp_f32_e32 v35, v35
	s_nop 0
	v_cndmask_b32_e64 v36, v201, -v36, vcc
	v_cmp_gt_f32_e32 vcc, s23, v36
	v_mul_f32_e32 v38, 0x4f800000, v36
	s_nop 0
	v_cndmask_b32_e32 v36, v36, v38, vcc
	v_sqrt_f32_e32 v38, v36
	s_nop 0
	v_add_u32_e32 v39, -1, v38
	v_fma_f32 v48, -v39, v38, v36
	v_cmp_ge_f32_e64 s[0:1], 0, v48
	v_add_u32_e32 v48, 1, v38
	s_nop 0
	v_cndmask_b32_e64 v39, v38, v39, s[0:1]
	v_fma_f32 v38, -v48, v38, v36
	v_cmp_lt_f32_e64 s[0:1], 0, v38
	s_nop 1
	v_cndmask_b32_e64 v38, v39, v48, s[0:1]
	v_mul_f32_e32 v39, 0x37800000, v38
	v_cndmask_b32_e32 v38, v38, v39, vcc
	v_cmp_class_f32_e32 vcc, v36, v193
	s_nop 1
	v_cndmask_b32_e32 v36, v38, v36, vcc
	ds_read2_b32 v[38:39], v32 offset0:192 offset1:224
	v_cmp_ngt_f32_e32 vcc, s24, v33
	s_nop 1
	v_cndmask_b32_e32 v33, 1.0, v36, vcc
	v_mul_f32_e32 v33, v34, v33
	s_waitcnt lgkmcnt(0)
	v_mul_f32_e32 v32, v38, v33
	ds_write_b32 v144, v35 offset:2816
	ds_write_b32 v144, v32 offset:39680
	v_add_f32_e32 v32, v56, v147
	v_mul_f32_e32 v32, 0xbfb8aa3b, v32
	v_exp_f32_e32 v32, v32
	v_add_f32_e32 v33, v40, v146
	v_mul_f32_e32 v33, 0xbfb8aa3b, v33
	v_exp_f32_e32 v33, v33
	v_add_f32_e32 v32, 1.0, v32
	v_rcp_f32_e32 v32, v32
	v_add_f32_e32 v33, 1.0, v33
	v_rcp_f32_e32 v33, v33
	v_mul_f32_e32 v32, v32, v96
	v_mul_f32_e32 v34, 0x3fb8aa3b, v32
	v_add_f32_e32 v32, v32, v32
	v_mul_f32_e32 v35, 0x3fb8aa3b, v32
	v_rndne_f32_e32 v35, v35
	v_fmamk_f32 v36, v35, 0xbf317218, v32
	v_fmac_f32_e32 v36, 0x3102e308, v35
	v_fmamk_f32 v38, v36, 0x395133b1, v192
	v_cmp_eq_f32_e32 vcc, s21, v35
	v_cvt_i32_f32_e32 v35, v35
	v_fmaak_f32 v38, v36, v38, 0x3c0887f9
	v_fmaak_f32 v38, v36, v38, 0x3d2aaa81
	v_fmaak_f32 v38, v36, v38, 0x3e2aaaab
	v_fma_f32 v38, v36, v38, 0.5
	v_ldexp_f32 v35, 1.0, v35
	v_mul_f32_e32 v38, v36, v38
	v_cndmask_b32_e32 v35, v35, v202, vcc
	v_fmac_f32_e32 v36, v36, v38
	v_add_f32_e32 v38, -1.0, v35
	v_fmac_f32_e32 v38, v35, v36
	v_add_f32_e32 v35, v38, v38
	v_cndmask_b32_e32 v35, v38, v35, vcc
	v_cmp_nlt_f32_e32 vcc, s22, v32
	v_exp_f32_e32 v34, v34
	s_nop 0
	v_cndmask_b32_e64 v35, v201, -v35, vcc
	v_cmp_gt_f32_e32 vcc, s23, v35
	v_mul_f32_e32 v36, 0x4f800000, v35
	s_nop 0
	v_cndmask_b32_e32 v35, v35, v36, vcc
	v_sqrt_f32_e32 v36, v35
	s_nop 0
	v_add_u32_e32 v38, -1, v36
	v_fma_f32 v40, -v38, v36, v35
	v_cmp_ge_f32_e64 s[0:1], 0, v40
	v_add_u32_e32 v40, 1, v36
	s_nop 0
	v_cndmask_b32_e64 v38, v36, v38, s[0:1]
	v_fma_f32 v36, -v40, v36, v35
	v_cmp_lt_f32_e64 s[0:1], 0, v36
	s_nop 1
	v_cndmask_b32_e64 v36, v38, v40, s[0:1]
	v_mul_f32_e32 v38, 0x37800000, v36
	v_cndmask_b32_e32 v36, v36, v38, vcc
	v_cmp_class_f32_e32 vcc, v35, v193
	s_nop 1
	v_cndmask_b32_e32 v35, v36, v35, vcc
	v_cmp_ngt_f32_e32 vcc, s24, v32
	s_nop 1
	v_cndmask_b32_e32 v32, 1.0, v35, vcc
	v_mul_f32_e32 v33, v33, v32
	v_add_u32_e32 v32, 0xa000, v144
	ds_read2_b32 v[54:55], v32 offset1:32
	s_waitcnt lgkmcnt(0)
	v_mul_f32_e32 v33, v54, v33
	ds_write_b32 v144, v34 offset:4096
	ds_write_b32 v144, v33 offset:40960
	v_add_f32_e32 v33, v57, v147
	v_mul_f32_e32 v33, 0xbfb8aa3b, v33
	v_exp_f32_e32 v33, v33
	v_add_f32_e32 v34, v41, v146
	v_mul_f32_e32 v34, 0xbfb8aa3b, v34
	v_exp_f32_e32 v34, v34
	v_add_f32_e32 v33, 1.0, v33
	v_rcp_f32_e32 v33, v33
	v_add_f32_e32 v34, 1.0, v34
	v_rcp_f32_e32 v34, v34
	v_mul_f32_e32 v33, v33, v96
	v_mul_f32_e32 v35, 0x3fb8aa3b, v33
	v_add_f32_e32 v33, v33, v33
	v_mul_f32_e32 v36, 0x3fb8aa3b, v33
	v_rndne_f32_e32 v36, v36
	v_fmamk_f32 v38, v36, 0xbf317218, v33
	v_fmac_f32_e32 v38, 0x3102e308, v36
	v_fmamk_f32 v40, v38, 0x395133b1, v192
	v_cmp_eq_f32_e32 vcc, s21, v36
	v_cvt_i32_f32_e32 v36, v36
	v_fmaak_f32 v40, v38, v40, 0x3c0887f9
	v_fmaak_f32 v40, v38, v40, 0x3d2aaa81
	v_fmaak_f32 v40, v38, v40, 0x3e2aaaab
	v_fma_f32 v40, v38, v40, 0.5
	v_ldexp_f32 v36, 1.0, v36
	v_mul_f32_e32 v40, v38, v40
	v_cndmask_b32_e32 v36, v36, v202, vcc
	v_fmac_f32_e32 v38, v38, v40
	v_add_f32_e32 v40, -1.0, v36
	v_fmac_f32_e32 v40, v36, v38
	v_add_f32_e32 v36, v40, v40
	v_cndmask_b32_e32 v36, v40, v36, vcc
	v_cmp_nlt_f32_e32 vcc, s22, v33
	v_exp_f32_e32 v35, v35
	s_nop 0
	v_cndmask_b32_e64 v36, v201, -v36, vcc
	v_cmp_gt_f32_e32 vcc, s23, v36
	v_mul_f32_e32 v38, 0x4f800000, v36
	s_nop 0
	v_cndmask_b32_e32 v36, v36, v38, vcc
	v_sqrt_f32_e32 v38, v36
	s_nop 0
	v_add_u32_e32 v40, -1, v38
	v_fma_f32 v41, -v40, v38, v36
	v_cmp_ge_f32_e64 s[0:1], 0, v41
	v_add_u32_e32 v41, 1, v38
	s_nop 0
	v_cndmask_b32_e64 v40, v38, v40, s[0:1]
	v_fma_f32 v38, -v41, v38, v36
	v_cmp_lt_f32_e64 s[0:1], 0, v38
	s_nop 1
	v_cndmask_b32_e64 v38, v40, v41, s[0:1]
	v_mul_f32_e32 v40, 0x37800000, v38
	v_cndmask_b32_e32 v38, v38, v40, vcc
	ds_read2_b32 v[40:41], v32 offset0:64 offset1:96
	v_cmp_class_f32_e32 vcc, v36, v193
	s_nop 1
	v_cndmask_b32_e32 v36, v38, v36, vcc
	v_cmp_ngt_f32_e32 vcc, s24, v33
	s_nop 1
	v_cndmask_b32_e32 v33, 1.0, v36, vcc
	v_mul_f32_e32 v33, v34, v33
	s_waitcnt lgkmcnt(0)
	v_mul_f32_e32 v33, v40, v33
	ds_write_b32 v144, v35 offset:4352
	ds_write_b32 v144, v33 offset:41216
	v_add_f32_e32 v33, v58, v147
	v_mul_f32_e32 v33, 0xbfb8aa3b, v33
	v_exp_f32_e32 v33, v33
	v_add_f32_e32 v34, v42, v146
	v_mul_f32_e32 v34, 0xbfb8aa3b, v34
	v_exp_f32_e32 v34, v34
	v_add_f32_e32 v33, 1.0, v33
	v_rcp_f32_e32 v33, v33
	ds_read2_b32 v[56:57], v32 offset0:128 offset1:160
	v_add_f32_e32 v34, 1.0, v34
	v_rcp_f32_e32 v34, v34
	v_mul_f32_e32 v33, v33, v96
	v_mul_f32_e32 v35, 0x3fb8aa3b, v33
	v_add_f32_e32 v33, v33, v33
	v_mul_f32_e32 v36, 0x3fb8aa3b, v33
	v_rndne_f32_e32 v36, v36
	v_fmamk_f32 v38, v36, 0xbf317218, v33
	v_fmac_f32_e32 v38, 0x3102e308, v36
	v_fmamk_f32 v40, v38, 0x395133b1, v192
	v_cmp_eq_f32_e32 vcc, s21, v36
	v_cvt_i32_f32_e32 v36, v36
	v_fmaak_f32 v40, v38, v40, 0x3c0887f9
	v_fmaak_f32 v40, v38, v40, 0x3d2aaa81
	v_fmaak_f32 v40, v38, v40, 0x3e2aaaab
	v_fma_f32 v40, v38, v40, 0.5
	v_ldexp_f32 v36, 1.0, v36
	v_mul_f32_e32 v40, v38, v40
	v_cndmask_b32_e32 v36, v36, v202, vcc
	v_fmac_f32_e32 v38, v38, v40
	v_add_f32_e32 v40, -1.0, v36
	v_fmac_f32_e32 v40, v36, v38
	v_add_f32_e32 v36, v40, v40
	v_cndmask_b32_e32 v36, v40, v36, vcc
	v_cmp_nlt_f32_e32 vcc, s22, v33
	v_exp_f32_e32 v35, v35
	s_nop 0
	v_cndmask_b32_e64 v36, v201, -v36, vcc
	v_cmp_gt_f32_e32 vcc, s23, v36
	v_mul_f32_e32 v38, 0x4f800000, v36
	s_nop 0
	v_cndmask_b32_e32 v36, v36, v38, vcc
	v_sqrt_f32_e32 v38, v36
	s_nop 0
	v_add_u32_e32 v40, -1, v38
	v_fma_f32 v42, -v40, v38, v36
	v_cmp_ge_f32_e64 s[0:1], 0, v42
	v_add_u32_e32 v42, 1, v38
	s_nop 0
	v_cndmask_b32_e64 v40, v38, v40, s[0:1]
	v_fma_f32 v38, -v42, v38, v36
	v_cmp_lt_f32_e64 s[0:1], 0, v38
	s_nop 1
	v_cndmask_b32_e64 v38, v40, v42, s[0:1]
	v_mul_f32_e32 v40, 0x37800000, v38
	v_cndmask_b32_e32 v38, v38, v40, vcc
	v_cmp_class_f32_e32 vcc, v36, v193
	s_nop 1
	v_cndmask_b32_e32 v36, v38, v36, vcc
	v_cmp_ngt_f32_e32 vcc, s24, v33
	s_nop 1
	v_cndmask_b32_e32 v33, 1.0, v36, vcc
	v_mul_f32_e32 v33, v34, v33
	s_waitcnt lgkmcnt(0)
	v_mul_f32_e32 v33, v56, v33
	ds_write_b32 v144, v35 offset:4608
	ds_write_b32 v144, v33 offset:41472
	v_add_f32_e32 v33, v59, v147
	v_mul_f32_e32 v33, 0xbfb8aa3b, v33
	v_exp_f32_e32 v33, v33
	v_add_f32_e32 v34, v43, v146
	v_mul_f32_e32 v34, 0xbfb8aa3b, v34
	v_exp_f32_e32 v34, v34
	v_add_f32_e32 v33, 1.0, v33
	v_rcp_f32_e32 v33, v33
	v_add_f32_e32 v34, 1.0, v34
	v_rcp_f32_e32 v34, v34
	v_mul_f32_e32 v33, v33, v96
	v_mul_f32_e32 v35, 0x3fb8aa3b, v33
	v_add_f32_e32 v33, v33, v33
	v_mul_f32_e32 v36, 0x3fb8aa3b, v33
	v_rndne_f32_e32 v36, v36
	v_fmamk_f32 v38, v36, 0xbf317218, v33
	v_fmac_f32_e32 v38, 0x3102e308, v36
	v_fmamk_f32 v40, v38, 0x395133b1, v192
	v_cmp_eq_f32_e32 vcc, s21, v36
	v_cvt_i32_f32_e32 v36, v36
	v_fmaak_f32 v40, v38, v40, 0x3c0887f9
	v_fmaak_f32 v40, v38, v40, 0x3d2aaa81
	v_fmaak_f32 v40, v38, v40, 0x3e2aaaab
	v_fma_f32 v40, v38, v40, 0.5
	v_ldexp_f32 v36, 1.0, v36
	v_mul_f32_e32 v40, v38, v40
	v_cndmask_b32_e32 v36, v36, v202, vcc
	v_fmac_f32_e32 v38, v38, v40
	v_add_f32_e32 v40, -1.0, v36
	v_fmac_f32_e32 v40, v36, v38
	v_add_f32_e32 v36, v40, v40
	v_cndmask_b32_e32 v36, v40, v36, vcc
	v_cmp_nlt_f32_e32 vcc, s22, v33
	v_exp_f32_e32 v35, v35
	s_nop 0
	v_cndmask_b32_e64 v36, v201, -v36, vcc
	v_cmp_gt_f32_e32 vcc, s23, v36
	v_mul_f32_e32 v38, 0x4f800000, v36
	s_nop 0
	v_cndmask_b32_e32 v36, v36, v38, vcc
	v_sqrt_f32_e32 v38, v36
	s_nop 0
	v_add_u32_e32 v40, -1, v38
	v_fma_f32 v42, -v40, v38, v36
	v_cmp_ge_f32_e64 s[0:1], 0, v42
	v_add_u32_e32 v42, 1, v38
	s_nop 0
	v_cndmask_b32_e64 v40, v38, v40, s[0:1]
	v_fma_f32 v38, -v42, v38, v36
	v_cmp_lt_f32_e64 s[0:1], 0, v38
	s_nop 1
	v_cndmask_b32_e64 v38, v40, v42, s[0:1]
	v_mul_f32_e32 v40, 0x37800000, v38
	ds_read2_b32 v[42:43], v32 offset0:192 offset1:224
	v_cndmask_b32_e32 v38, v38, v40, vcc
	v_cmp_class_f32_e32 vcc, v36, v193
	s_nop 1
	v_cndmask_b32_e32 v36, v38, v36, vcc
	v_cmp_ngt_f32_e32 vcc, s24, v33
	s_nop 1
	v_cndmask_b32_e32 v33, 1.0, v36, vcc
	v_mul_f32_e32 v33, v34, v33
	s_waitcnt lgkmcnt(0)
	v_mul_f32_e32 v32, v42, v33
	ds_write_b32 v144, v35 offset:4864
	ds_write_b32 v144, v32 offset:41728
	v_add_f32_e32 v32, v60, v147
	v_mul_f32_e32 v32, 0xbfb8aa3b, v32
	v_exp_f32_e32 v32, v32
	v_add_f32_e32 v33, v44, v146
	v_mul_f32_e32 v33, 0xbfb8aa3b, v33
	v_exp_f32_e32 v33, v33
	v_add_f32_e32 v32, 1.0, v32
	v_rcp_f32_e32 v32, v32
	v_add_f32_e32 v33, 1.0, v33
	v_rcp_f32_e32 v33, v33
	v_mul_f32_e32 v32, v32, v96
	v_mul_f32_e32 v34, 0x3fb8aa3b, v32
	v_add_f32_e32 v32, v32, v32
	v_mul_f32_e32 v35, 0x3fb8aa3b, v32
	v_rndne_f32_e32 v35, v35
	v_fmamk_f32 v36, v35, 0xbf317218, v32
	v_fmac_f32_e32 v36, 0x3102e308, v35
	v_fmamk_f32 v38, v36, 0x395133b1, v192
	v_cmp_eq_f32_e32 vcc, s21, v35
	v_cvt_i32_f32_e32 v35, v35
	v_fmaak_f32 v38, v36, v38, 0x3c0887f9
	v_fmaak_f32 v38, v36, v38, 0x3d2aaa81
	v_fmaak_f32 v38, v36, v38, 0x3e2aaaab
	v_fma_f32 v38, v36, v38, 0.5
	v_ldexp_f32 v35, 1.0, v35
	v_mul_f32_e32 v38, v36, v38
	v_cndmask_b32_e32 v35, v35, v202, vcc
	v_fmac_f32_e32 v36, v36, v38
	v_add_f32_e32 v38, -1.0, v35
	v_fmac_f32_e32 v38, v35, v36
	v_add_f32_e32 v35, v38, v38
	v_cndmask_b32_e32 v35, v38, v35, vcc
	v_cmp_nlt_f32_e32 vcc, s22, v32
	v_exp_f32_e32 v34, v34
	s_nop 0
	v_cndmask_b32_e64 v35, v201, -v35, vcc
	v_cmp_gt_f32_e32 vcc, s23, v35
	v_mul_f32_e32 v36, 0x4f800000, v35
	s_nop 0
	v_cndmask_b32_e32 v35, v35, v36, vcc
	v_sqrt_f32_e32 v36, v35
	s_nop 0
	v_add_u32_e32 v38, -1, v36
	v_fma_f32 v40, -v38, v36, v35
	v_cmp_ge_f32_e64 s[0:1], 0, v40
	v_add_u32_e32 v40, 1, v36
	s_nop 0
	v_cndmask_b32_e64 v38, v36, v38, s[0:1]
	v_fma_f32 v36, -v40, v36, v35
	v_cmp_lt_f32_e64 s[0:1], 0, v36
	s_nop 1
	v_cndmask_b32_e64 v36, v38, v40, s[0:1]
	v_mul_f32_e32 v38, 0x37800000, v36
	v_cndmask_b32_e32 v36, v36, v38, vcc
	v_cmp_class_f32_e32 vcc, v35, v193
	s_nop 1
	v_cndmask_b32_e32 v35, v36, v35, vcc
	v_cmp_ngt_f32_e32 vcc, s24, v32
	s_nop 1
	v_cndmask_b32_e32 v32, 1.0, v35, vcc
	v_mul_f32_e32 v32, v33, v32
	v_add_u32_e32 v33, 0xa800, v144
	ds_read2_b32 v[58:59], v33 offset1:32
	s_waitcnt lgkmcnt(0)
	v_mul_f32_e32 v32, v58, v32
	ds_write_b32 v144, v34 offset:6144
	ds_write_b32 v144, v32 offset:43008
	v_add_f32_e32 v32, v61, v147
	v_mul_f32_e32 v32, 0xbfb8aa3b, v32
	v_exp_f32_e32 v32, v32
	v_add_f32_e32 v34, v45, v146
	v_mul_f32_e32 v34, 0xbfb8aa3b, v34
	v_exp_f32_e32 v34, v34
	v_add_f32_e32 v32, 1.0, v32
	v_rcp_f32_e32 v32, v32
	ds_read2_b32 v[44:45], v33 offset0:64 offset1:96
	v_add_f32_e32 v34, 1.0, v34
	v_rcp_f32_e32 v34, v34
	v_mul_f32_e32 v32, v32, v96
	v_mul_f32_e32 v35, 0x3fb8aa3b, v32
	v_add_f32_e32 v32, v32, v32
	v_mul_f32_e32 v36, 0x3fb8aa3b, v32
	v_rndne_f32_e32 v36, v36
	v_fmamk_f32 v38, v36, 0xbf317218, v32
	v_fmac_f32_e32 v38, 0x3102e308, v36
	v_fmamk_f32 v40, v38, 0x395133b1, v192
	v_cmp_eq_f32_e32 vcc, s21, v36
	v_cvt_i32_f32_e32 v36, v36
	v_fmaak_f32 v40, v38, v40, 0x3c0887f9
	v_fmaak_f32 v40, v38, v40, 0x3d2aaa81
	v_fmaak_f32 v40, v38, v40, 0x3e2aaaab
	v_fma_f32 v40, v38, v40, 0.5
	v_ldexp_f32 v36, 1.0, v36
	v_mul_f32_e32 v40, v38, v40
	v_cndmask_b32_e32 v36, v36, v202, vcc
	v_fmac_f32_e32 v38, v38, v40
	v_add_f32_e32 v40, -1.0, v36
	v_fmac_f32_e32 v40, v36, v38
	v_add_f32_e32 v36, v40, v40
	v_cndmask_b32_e32 v36, v40, v36, vcc
	v_cmp_nlt_f32_e32 vcc, s22, v32
	v_exp_f32_e32 v35, v35
	s_nop 0
	v_cndmask_b32_e64 v36, v201, -v36, vcc
	v_cmp_gt_f32_e32 vcc, s23, v36
	v_mul_f32_e32 v38, 0x4f800000, v36
	s_nop 0
	v_cndmask_b32_e32 v36, v36, v38, vcc
	v_sqrt_f32_e32 v38, v36
	s_nop 0
	v_add_u32_e32 v40, -1, v38
	v_fma_f32 v42, -v40, v38, v36
	v_cmp_ge_f32_e64 s[0:1], 0, v42
	v_add_u32_e32 v42, 1, v38
	s_nop 0
	v_cndmask_b32_e64 v40, v38, v40, s[0:1]
	v_fma_f32 v38, -v42, v38, v36
	v_cmp_lt_f32_e64 s[0:1], 0, v38
	s_nop 1
	v_cndmask_b32_e64 v38, v40, v42, s[0:1]
	v_mul_f32_e32 v40, 0x37800000, v38
	v_cndmask_b32_e32 v38, v38, v40, vcc
	v_cmp_class_f32_e32 vcc, v36, v193
	s_nop 1
	v_cndmask_b32_e32 v36, v38, v36, vcc
	v_cmp_ngt_f32_e32 vcc, s24, v32
	s_nop 1
	v_cndmask_b32_e32 v32, 1.0, v36, vcc
	v_mul_f32_e32 v32, v34, v32
	s_waitcnt lgkmcnt(0)
	v_mul_f32_e32 v32, v44, v32
	ds_write_b32 v144, v35 offset:6400
	ds_write_b32 v144, v32 offset:43264
	v_add_f32_e32 v32, v62, v147
	v_mul_f32_e32 v32, 0xbfb8aa3b, v32
	v_exp_f32_e32 v32, v32
	v_add_f32_e32 v34, v46, v146
	v_mul_f32_e32 v34, 0xbfb8aa3b, v34
	v_exp_f32_e32 v34, v34
	v_add_f32_e32 v32, 1.0, v32
	v_rcp_f32_e32 v32, v32
	v_add_f32_e32 v34, 1.0, v34
	v_rcp_f32_e32 v34, v34
	v_mul_f32_e32 v32, v32, v96
	v_mul_f32_e32 v35, 0x3fb8aa3b, v32
	v_add_f32_e32 v32, v32, v32
	v_exp_f32_e32 v36, v35
	v_mul_f32_e32 v35, 0x3fb8aa3b, v32
	v_rndne_f32_e32 v35, v35
	v_fmamk_f32 v38, v35, 0xbf317218, v32
	v_fmac_f32_e32 v38, 0x3102e308, v35
	v_fmamk_f32 v40, v38, 0x395133b1, v192
	v_cmp_eq_f32_e32 vcc, s21, v35
	v_cvt_i32_f32_e32 v35, v35
	v_fmaak_f32 v40, v38, v40, 0x3c0887f9
	v_fmaak_f32 v40, v38, v40, 0x3d2aaa81
	v_fmaak_f32 v40, v38, v40, 0x3e2aaaab
	v_fma_f32 v40, v38, v40, 0.5
	v_ldexp_f32 v35, 1.0, v35
	v_mul_f32_e32 v40, v38, v40
	v_cndmask_b32_e32 v35, v35, v202, vcc
	v_fmac_f32_e32 v38, v38, v40
	v_add_f32_e32 v40, -1.0, v35
	v_fmac_f32_e32 v40, v35, v38
	v_add_f32_e32 v35, v40, v40
	v_cndmask_b32_e32 v35, v40, v35, vcc
	v_cmp_nlt_f32_e32 vcc, s22, v32
	s_nop 1
	v_cndmask_b32_e64 v35, v201, -v35, vcc
	v_cmp_gt_f32_e32 vcc, s23, v35
	v_mul_f32_e32 v38, 0x4f800000, v35
	s_nop 0
	v_cndmask_b32_e32 v35, v35, v38, vcc
	v_sqrt_f32_e32 v38, v35
	s_nop 0
	v_add_u32_e32 v40, -1, v38
	v_fma_f32 v42, -v40, v38, v35
	v_cmp_ge_f32_e64 s[0:1], 0, v42
	v_add_u32_e32 v42, 1, v38
	s_nop 0
	v_cndmask_b32_e64 v40, v38, v40, s[0:1]
	v_fma_f32 v38, -v42, v38, v35
	v_cmp_lt_f32_e64 s[0:1], 0, v38
	s_nop 1
	v_cndmask_b32_e64 v38, v40, v42, s[0:1]
	v_mul_f32_e32 v40, 0x37800000, v38
	v_cndmask_b32_e32 v38, v38, v40, vcc
	v_cmp_class_f32_e32 vcc, v35, v193
	s_nop 1
	v_cndmask_b32_e32 v35, v38, v35, vcc
	v_cmp_ngt_f32_e32 vcc, s24, v32
	s_nop 1
	v_cndmask_b32_e32 v32, 1.0, v35, vcc
	v_mul_f32_e32 v32, v34, v32
	ds_read2_b32 v[34:35], v33 offset0:128 offset1:160
	s_waitcnt lgkmcnt(0)
	v_mul_f32_e32 v32, v34, v32
	ds_write_b32 v144, v36 offset:6656
	ds_write_b32 v144, v32 offset:43520
	v_add_f32_e32 v32, v63, v147
	v_mul_f32_e32 v32, 0xbfb8aa3b, v32
	v_exp_f32_e32 v32, v32
	v_add_f32_e32 v34, v47, v146
	v_mul_f32_e32 v34, 0xbfb8aa3b, v34
	v_exp_f32_e32 v34, v34
	v_add_f32_e32 v32, 1.0, v32
	v_rcp_f32_e32 v32, v32
	v_add_f32_e32 v34, 1.0, v34
	v_rcp_f32_e32 v36, v34
	v_mul_f32_e32 v32, v32, v96
	v_mul_f32_e32 v34, 0x3fb8aa3b, v32
	v_add_f32_e32 v32, v32, v32
	v_mul_f32_e32 v38, 0x3fb8aa3b, v32
	v_rndne_f32_e32 v38, v38
	v_fmamk_f32 v40, v38, 0xbf317218, v32
	v_fmac_f32_e32 v40, 0x3102e308, v38
	v_fmamk_f32 v42, v40, 0x395133b1, v192
	v_cmp_eq_f32_e32 vcc, s21, v38
	v_cvt_i32_f32_e32 v38, v38
	v_fmaak_f32 v42, v40, v42, 0x3c0887f9
	v_fmaak_f32 v42, v40, v42, 0x3d2aaa81
	v_fmaak_f32 v42, v40, v42, 0x3e2aaaab
	v_fma_f32 v42, v40, v42, 0.5
	v_ldexp_f32 v38, 1.0, v38
	v_mul_f32_e32 v42, v40, v42
	v_cndmask_b32_e32 v38, v38, v202, vcc
	v_fmac_f32_e32 v40, v40, v42
	v_add_f32_e32 v42, -1.0, v38
	v_fmac_f32_e32 v42, v38, v40
	v_add_f32_e32 v38, v42, v42
	v_cndmask_b32_e32 v38, v42, v38, vcc
	v_cmp_nlt_f32_e32 vcc, s22, v32
	v_add_u32_e32 v96, s3, v145
	v_lshlrev_b64 v[46:47], 2, v[96:97]
	v_cndmask_b32_e64 v38, v201, -v38, vcc
	v_cmp_gt_f32_e32 vcc, s23, v38
	v_mul_f32_e32 v40, 0x4f800000, v38
	s_nop 0
	v_cndmask_b32_e32 v38, v38, v40, vcc
	v_sqrt_f32_e32 v40, v38
	v_exp_f32_e32 v34, v34
	s_movk_i32 s18, 0x1600
	s_mov_b32 s19, 0x2c000
	v_add_u32_e32 v42, -1, v40
	v_fma_f32 v44, -v42, v40, v38
	v_cmp_ge_f32_e64 s[0:1], 0, v44
	v_add_u32_e32 v44, 1, v40
	s_nop 0
	v_cndmask_b32_e64 v42, v40, v42, s[0:1]
	v_fma_f32 v40, -v44, v40, v38
	v_cmp_lt_f32_e64 s[0:1], 0, v40
	s_nop 1
	v_cndmask_b32_e64 v40, v42, v44, s[0:1]
	v_mul_f32_e32 v42, 0x37800000, v40
	v_cndmask_b32_e32 v40, v40, v42, vcc
	v_cmp_class_f32_e32 vcc, v38, v193
	s_nop 1
	v_cndmask_b32_e32 v38, v40, v38, vcc
	v_cmp_ngt_f32_e32 vcc, s24, v32
	s_nop 1
	v_cndmask_b32_e32 v32, 1.0, v38, vcc
	v_mul_f32_e32 v36, v36, v32
	ds_read2_b32 v[32:33], v33 offset0:192 offset1:224
	s_waitcnt lgkmcnt(0)
	v_mul_f32_e32 v32, v32, v36
	ds_write_b32 v144, v32 offset:43776
	s_waitcnt vmcnt(0)
	v_mul_f32_e32 v32, 0xbfb8aa3b, v226
	v_exp_f32_e32 v32, v32
	s_nop 0
	v_add_f32_e32 v36, 1.0, v32
	v_add_f32_e32 v38, -1.0, v36
	v_sub_f32_e32 v40, v38, v36
	v_add_f32_e32 v40, 1.0, v40
	v_sub_f32_e32 v38, v32, v38
	v_add_f32_e32 v38, v38, v40
	v_frexp_mant_f32_e32 v40, v36
	v_cvt_f64_f32_e32 v[60:61], v36
	v_cmp_gt_f32_e32 vcc, s8, v40
	v_frexp_exp_i32_f64_e32 v40, v[60:61]
	s_nop 0
	v_subbrev_co_u32_e32 v40, vcc, 0, v40, vcc
	v_sub_u32_e32 v42, 0, v40
	v_ldexp_f32 v36, v36, v42
	v_ldexp_f32 v38, v38, v42
	v_add_f32_e32 v42, -1.0, v36
	v_add_f32_e32 v48, 1.0, v36
	v_add_f32_e32 v44, 1.0, v42
	v_add_f32_e32 v50, -1.0, v48
	v_sub_f32_e32 v44, v36, v44
	v_sub_f32_e32 v36, v36, v50
	v_add_f32_e32 v36, v38, v36
	v_add_f32_e32 v44, v38, v44
	v_add_f32_e32 v38, v48, v36
	v_sub_f32_e32 v48, v38, v48
	v_sub_f32_e32 v36, v36, v48
	v_rcp_f32_e32 v48, v38
	v_add_f32_e32 v61, v42, v44
	v_sub_f32_e32 v42, v61, v42
	v_sub_f32_e32 v42, v44, v42
	v_mul_f32_e32 v44, v61, v48
	v_mul_f32_e32 v62, v38, v44
	v_fma_f32 v146, v44, v38, -v62
	v_fmac_f32_e32 v146, v44, v36
	v_add_f32_e32 v60, v62, v146
	v_sub_f32_e32 v63, v61, v60
	v_pk_add_f32 v[148:149], v[60:61], v[62:63] neg_lo:[0,1] neg_hi:[0,1]
	v_mov_b32_e32 v147, v60
	v_pk_add_f32 v[60:61], v[148:149], v[146:147] neg_lo:[0,1] neg_hi:[0,1]
	v_cmp_neq_f32_e32 vcc, s10, v32
	v_add_f32_e32 v42, v42, v61
	v_add_f32_e32 v42, v60, v42
	v_add_f32_e32 v61, v63, v42
	v_mul_f32_e32 v50, v48, v61
	v_mul_f32_e32 v62, v38, v50
	v_fma_f32 v146, v50, v38, -v62
	v_fmac_f32_e32 v146, v50, v36
	v_add_f32_e32 v60, v62, v146
	v_sub_f32_e32 v36, v63, v61
	v_sub_f32_e32 v63, v61, v60
	v_pk_add_f32 v[148:149], v[60:61], v[62:63] neg_lo:[0,1] neg_hi:[0,1]
	v_mov_b32_e32 v147, v60
	v_add_f32_e32 v36, v42, v36
	v_pk_add_f32 v[60:61], v[148:149], v[146:147] neg_lo:[0,1] neg_hi:[0,1]
	v_add_f32_e32 v38, v44, v50
	v_add_f32_e32 v36, v36, v61
	v_add_f32_e32 v36, v60, v36
	v_add_f32_e32 v36, v63, v36
	v_sub_f32_e32 v42, v38, v44
	v_mul_f32_e32 v36, v48, v36
	v_sub_f32_e32 v42, v50, v42
	v_add_f32_e32 v36, v42, v36
	v_add_f32_e32 v42, v38, v36
	v_cvt_f32_i32_e32 v60, v40
	v_mul_f32_e32 v44, v42, v42
	v_fmamk_f32 v48, v44, 0x3e9b6dac, v191
	v_fmaak_f32 v169, v44, v48, 0x3f2aaada
	v_mul_f32_e32 v61, v42, v44
	v_pk_mul_f32 v[146:147], v[60:61], v[168:169]
	v_ldexp_f32 v63, v42, 1
	v_fma_f32 v62, v60, s9, -v146
	v_fmac_f32_e32 v62, 0xb102e308, v60
	v_sub_f32_e32 v38, v42, v38
	v_pk_add_f32 v[60:61], v[146:147], v[62:63]
	v_sub_f32_e32 v36, v36, v38
	v_sub_f32_e32 v38, v61, v63
	v_ldexp_f32 v36, v36, 1
	v_sub_f32_e32 v38, v147, v38
	v_add_f32_e32 v149, v36, v38
	v_mov_b32_e32 v148, v146
	v_pk_add_f32 v[146:147], v[60:61], v[146:147] neg_lo:[0,1] neg_hi:[0,1]
	v_pk_add_f32 v[150:151], v[60:61], v[148:149]
	v_mov_b32_e32 v63, v60
	v_mov_b32_e32 v147, v151
	v_pk_add_f32 v[152:153], v[62:63], v[146:147] neg_lo:[0,1] neg_hi:[0,1]
	v_pk_add_f32 v[62:63], v[62:63], v[146:147]
	v_mov_b32_e32 v148, v149
	v_pk_add_f32 v[146:147], v[62:63], v[60:61] op_sel:[1,0] op_sel_hi:[0,1] neg_lo:[0,1] neg_hi:[0,1]
	v_pk_add_f32 v[154:155], v[150:151], v[146:147] op_sel_hi:[1,0] neg_lo:[0,1] neg_hi:[0,1]
	v_mov_b32_e32 v150, v151
	v_mov_b32_e32 v151, v63
	v_pk_mov_b32 v[146:147], v[60:61], v[146:147] op_sel:[1,0]
	v_mov_b32_e32 v149, v60
	v_pk_add_f32 v[146:147], v[150:151], v[146:147] neg_lo:[0,1] neg_hi:[0,1]
	v_mov_b32_e32 v154, v152
	v_pk_add_f32 v[60:61], v[148:149], v[146:147] neg_lo:[0,1] neg_hi:[0,1]
	v_mov_b32_e32 v153, v63
	v_pk_add_f32 v[146:147], v[154:155], v[60:61]
	v_readlane_b32 s10, v248, 33
	v_pk_add_f32 v[148:149], v[146:147], v[146:147] op_sel:[0,1] op_sel_hi:[1,0]
	v_pk_add_f32 v[62:63], v[62:63], v[148:149] op_sel:[1,0] op_sel_hi:[0,1]
	v_mov_b32_e32 v147, v62
	v_pk_add_f32 v[150:151], v[146:147], v[152:153] neg_lo:[0,1] neg_hi:[0,1]
	v_mov_b32_e32 v61, v148
	v_sub_f32_e32 v36, v146, v150
	v_pk_add_f32 v[60:61], v[60:61], v[150:151] neg_lo:[0,1] neg_hi:[0,1]
	v_sub_f32_e32 v36, v152, v36
	v_add_f32_e32 v36, v60, v36
	v_add_f32_e32 v36, v36, v61
	v_add_f32_e32 v36, v62, v36
	v_cndmask_b32_e32 v36, v199, v36, vcc
	v_cmp_ngt_f32_e32 vcc, -1.0, v32
	v_lshl_add_u64 v[60:61], s[52:53], 0, v[46:47]
	s_nop 0
	v_cndmask_b32_e32 v36, v200, v36, vcc
	v_cmp_neq_f32_e32 vcc, -1.0, v32
	v_mov_b32_e32 v38, v227
	s_mov_b64 s[16:17], s[82:83]
	v_cndmask_b32_e32 v36, v201, v36, vcc
	v_cmp_lt_f32_e64 vcc, |v32|, s20
	s_mov_b32 s20, 0x58000
	s_waitcnt vmcnt(0)
	v_add_f32_e32 v0, v0, v38
	v_cndmask_b32_e32 v32, v36, v32, vcc
	v_mov_b32_e32 v36, v228
	v_mul_f32_e32 v32, 0xc1000000, v32
	v_mul_f32_e32 v0, 0xbfb8aa3b, v0
	v_exp_f32_e32 v0, v0
	v_add_f32_e32 v1, v1, v38
	v_mul_f32_e32 v1, 0xbfb8aa3b, v1
	v_exp_f32_e32 v1, v1
	v_add_f32_e32 v0, 1.0, v0
	v_rcp_f32_e32 v0, v0
	v_add_f32_e32 v1, 1.0, v1
	v_rcp_f32_e32 v1, v1
	s_waitcnt vmcnt(0)
	v_add_f32_e32 v16, v16, v36
	v_mul_f32_e32 v16, 0xbfb8aa3b, v16
	v_exp_f32_e32 v16, v16
	s_nop 0
	v_add_f32_e32 v16, 1.0, v16
	v_rcp_f32_e32 v16, v16
	s_nop 0
	v_mul_f32_e32 v16, v16, v32
	v_mul_f32_e32 v40, 0x3fb8aa3b, v16
	v_add_f32_e32 v16, v16, v16
	v_mul_f32_e32 v42, 0x3fb8aa3b, v16
	v_rndne_f32_e32 v42, v42
	v_fmamk_f32 v44, v42, 0xbf317218, v16
	v_fmac_f32_e32 v44, 0x3102e308, v42
	v_fmamk_f32 v46, v44, 0x395133b1, v192
	v_cmp_eq_f32_e32 vcc, s21, v42
	v_cvt_i32_f32_e32 v42, v42
	v_fmaak_f32 v46, v44, v46, 0x3c0887f9
	v_fmaak_f32 v46, v44, v46, 0x3d2aaa81
	v_fmaak_f32 v46, v44, v46, 0x3e2aaaab
	v_fma_f32 v46, v44, v46, 0.5
	v_ldexp_f32 v42, 1.0, v42
	v_mul_f32_e32 v46, v44, v46
	v_cndmask_b32_e32 v42, v42, v202, vcc
	v_fmac_f32_e32 v44, v44, v46
	v_add_f32_e32 v46, -1.0, v42
	v_fmac_f32_e32 v46, v42, v44
	v_add_f32_e32 v42, v46, v46
	v_cndmask_b32_e32 v42, v46, v42, vcc
	v_cmp_nlt_f32_e32 vcc, s22, v16
	v_exp_f32_e32 v40, v40
	s_nop 0
	v_cndmask_b32_e64 v42, v201, -v42, vcc
	v_cmp_gt_f32_e32 vcc, s23, v42
	v_mul_f32_e32 v44, 0x4f800000, v42
	s_nop 0
	v_cndmask_b32_e32 v42, v42, v44, vcc
	v_sqrt_f32_e32 v44, v42
	s_nop 0
	v_add_u32_e32 v46, -1, v44
	v_fma_f32 v47, -v46, v44, v42
	v_cmp_ge_f32_e64 s[0:1], 0, v47
	v_add_u32_e32 v47, 1, v44
	s_nop 0
	v_cndmask_b32_e64 v46, v44, v46, s[0:1]
	v_fma_f32 v44, -v47, v44, v42
	v_cmp_lt_f32_e64 s[0:1], 0, v44
	s_nop 1
	v_cndmask_b32_e64 v44, v46, v47, s[0:1]
	v_mul_f32_e32 v46, 0x37800000, v44
	v_cndmask_b32_e32 v44, v44, v46, vcc
	v_cmp_class_f32_e32 vcc, v42, v193
	s_nop 1
	v_cndmask_b32_e32 v42, v44, v42, vcc
	v_cmp_ngt_f32_e32 vcc, s24, v16
	s_nop 1
	v_cndmask_b32_e32 v16, 1.0, v42, vcc
	v_mul_f32_e32 v0, v0, v16
	v_mul_f32_e32 v0, v135, v0
	ds_write_b32 v144, v40 offset:128
	ds_write_b32 v144, v0 offset:36992
	v_add_f32_e32 v0, v17, v36
	v_mul_f32_e32 v0, 0xbfb8aa3b, v0
	v_exp_f32_e32 v0, v0
	s_nop 0
	v_add_f32_e32 v0, 1.0, v0
	v_rcp_f32_e32 v0, v0
	s_nop 0
	v_mul_f32_e32 v0, v0, v32
	v_mul_f32_e32 v16, 0x3fb8aa3b, v0
	v_add_f32_e32 v0, v0, v0
	v_mul_f32_e32 v17, 0x3fb8aa3b, v0
	v_rndne_f32_e32 v17, v17
	v_fmamk_f32 v40, v17, 0xbf317218, v0
	v_fmac_f32_e32 v40, 0x3102e308, v17
	v_fmamk_f32 v42, v40, 0x395133b1, v192
	v_cmp_eq_f32_e32 vcc, s21, v17
	v_cvt_i32_f32_e32 v17, v17
	v_fmaak_f32 v42, v40, v42, 0x3c0887f9
	v_fmaak_f32 v42, v40, v42, 0x3d2aaa81
	v_fmaak_f32 v42, v40, v42, 0x3e2aaaab
	v_fma_f32 v42, v40, v42, 0.5
	v_ldexp_f32 v17, 1.0, v17
	v_mul_f32_e32 v42, v40, v42
	v_cndmask_b32_e32 v17, v17, v202, vcc
	v_fmac_f32_e32 v40, v40, v42
	v_add_f32_e32 v42, -1.0, v17
	v_fmac_f32_e32 v42, v17, v40
	v_add_f32_e32 v17, v42, v42
	v_cndmask_b32_e32 v17, v42, v17, vcc
	v_cmp_nlt_f32_e32 vcc, s22, v0
	v_exp_f32_e32 v16, v16
	s_nop 0
	v_cndmask_b32_e64 v17, v201, -v17, vcc
	v_cmp_gt_f32_e32 vcc, s23, v17
	v_mul_f32_e32 v40, 0x4f800000, v17
	s_nop 0
	v_cndmask_b32_e32 v17, v17, v40, vcc
	v_sqrt_f32_e32 v40, v17
	s_nop 0
	v_add_u32_e32 v42, -1, v40
	v_fma_f32 v44, -v42, v40, v17
	v_cmp_ge_f32_e64 s[0:1], 0, v44
	v_add_u32_e32 v44, 1, v40
	s_nop 0
	v_cndmask_b32_e64 v42, v40, v42, s[0:1]
	v_fma_f32 v40, -v44, v40, v17
	v_cmp_lt_f32_e64 s[0:1], 0, v40
	s_nop 1
	v_cndmask_b32_e64 v40, v42, v44, s[0:1]
	v_mul_f32_e32 v42, 0x37800000, v40
	v_cndmask_b32_e32 v40, v40, v42, vcc
	v_cmp_class_f32_e32 vcc, v17, v193
	s_nop 1
	v_cndmask_b32_e32 v17, v40, v17, vcc
	v_cmp_ngt_f32_e32 vcc, s24, v0
	s_nop 1
	v_cndmask_b32_e32 v0, 1.0, v17, vcc
	v_mul_f32_e32 v0, v1, v0
	v_mul_f32_e32 v0, v49, v0
	ds_write_b32 v144, v16 offset:384
	ds_write_b32 v144, v0 offset:37248
	v_add_f32_e32 v0, v18, v36
	v_mul_f32_e32 v0, 0xbfb8aa3b, v0
	v_exp_f32_e32 v0, v0
	v_add_f32_e32 v1, v2, v38
	v_mul_f32_e32 v1, 0xbfb8aa3b, v1
	v_exp_f32_e32 v1, v1
	v_add_f32_e32 v0, 1.0, v0
	v_rcp_f32_e32 v0, v0
	v_add_f32_e32 v1, 1.0, v1
	v_rcp_f32_e32 v1, v1
	v_mul_f32_e32 v0, v0, v32
	v_mul_f32_e32 v2, 0x3fb8aa3b, v0
	v_add_f32_e32 v0, v0, v0
	v_mul_f32_e32 v16, 0x3fb8aa3b, v0
	v_rndne_f32_e32 v16, v16
	v_fmamk_f32 v17, v16, 0xbf317218, v0
	v_fmac_f32_e32 v17, 0x3102e308, v16
	v_fmamk_f32 v18, v17, 0x395133b1, v192
	v_cmp_eq_f32_e32 vcc, s21, v16
	v_cvt_i32_f32_e32 v16, v16
	v_fmaak_f32 v18, v17, v18, 0x3c0887f9
	v_fmaak_f32 v18, v17, v18, 0x3d2aaa81
	v_fmaak_f32 v18, v17, v18, 0x3e2aaaab
	v_fma_f32 v18, v17, v18, 0.5
	v_ldexp_f32 v16, 1.0, v16
	v_mul_f32_e32 v18, v17, v18
	v_cndmask_b32_e32 v16, v16, v202, vcc
	v_fmac_f32_e32 v17, v17, v18
	v_add_f32_e32 v18, -1.0, v16
	v_fmac_f32_e32 v18, v16, v17
	v_add_f32_e32 v16, v18, v18
	v_cndmask_b32_e32 v16, v18, v16, vcc
	v_cmp_nlt_f32_e32 vcc, s22, v0
	v_exp_f32_e32 v2, v2
	s_nop 0
	v_cndmask_b32_e64 v16, v201, -v16, vcc
	v_cmp_gt_f32_e32 vcc, s23, v16
	v_mul_f32_e32 v17, 0x4f800000, v16
	s_nop 0
	v_cndmask_b32_e32 v16, v16, v17, vcc
	v_sqrt_f32_e32 v17, v16
	s_nop 0
	v_add_u32_e32 v18, -1, v17
	v_fma_f32 v40, -v18, v17, v16
	v_cmp_ge_f32_e64 s[0:1], 0, v40
	v_add_u32_e32 v40, 1, v17
	s_nop 0
	v_cndmask_b32_e64 v18, v17, v18, s[0:1]
	v_fma_f32 v17, -v40, v17, v16
	v_cmp_lt_f32_e64 s[0:1], 0, v17
	s_nop 1
	v_cndmask_b32_e64 v17, v18, v40, s[0:1]
	v_mul_f32_e32 v18, 0x37800000, v17
	v_cndmask_b32_e32 v17, v17, v18, vcc
	v_cmp_class_f32_e32 vcc, v16, v193
	s_nop 1
	v_cndmask_b32_e32 v16, v17, v16, vcc
	v_cmp_ngt_f32_e32 vcc, s24, v0
	s_nop 1
	v_cndmask_b32_e32 v0, 1.0, v16, vcc
	v_mul_f32_e32 v0, v1, v0
	v_mul_f32_e32 v0, v137, v0
	ds_write_b32 v144, v2 offset:640
	ds_write_b32 v144, v0 offset:37504
	v_add_f32_e32 v0, v19, v36
	v_mul_f32_e32 v0, 0xbfb8aa3b, v0
	v_exp_f32_e32 v0, v0
	v_add_f32_e32 v1, v3, v38
	v_mul_f32_e32 v1, 0xbfb8aa3b, v1
	v_exp_f32_e32 v1, v1
	v_add_f32_e32 v0, 1.0, v0
	v_rcp_f32_e32 v0, v0
	v_add_f32_e32 v1, 1.0, v1
	v_rcp_f32_e32 v1, v1
	v_mul_f32_e32 v0, v0, v32
	v_mul_f32_e32 v2, 0x3fb8aa3b, v0
	v_add_f32_e32 v0, v0, v0
	v_mul_f32_e32 v3, 0x3fb8aa3b, v0
	v_rndne_f32_e32 v3, v3
	v_fmamk_f32 v16, v3, 0xbf317218, v0
	v_fmac_f32_e32 v16, 0x3102e308, v3
	v_fmamk_f32 v17, v16, 0x395133b1, v192
	v_cmp_eq_f32_e32 vcc, s21, v3
	v_cvt_i32_f32_e32 v3, v3
	v_fmaak_f32 v17, v16, v17, 0x3c0887f9
	v_fmaak_f32 v17, v16, v17, 0x3d2aaa81
	v_fmaak_f32 v17, v16, v17, 0x3e2aaaab
	v_fma_f32 v17, v16, v17, 0.5
	v_ldexp_f32 v3, 1.0, v3
	v_mul_f32_e32 v17, v16, v17
	v_cndmask_b32_e32 v3, v3, v202, vcc
	v_fmac_f32_e32 v16, v16, v17
	v_add_f32_e32 v17, -1.0, v3
	v_fmac_f32_e32 v17, v3, v16
	v_add_f32_e32 v3, v17, v17
	v_cndmask_b32_e32 v3, v17, v3, vcc
	v_cmp_nlt_f32_e32 vcc, s22, v0
	v_exp_f32_e32 v2, v2
	s_nop 0
	v_cndmask_b32_e64 v3, v201, -v3, vcc
	v_cmp_gt_f32_e32 vcc, s23, v3
	v_mul_f32_e32 v16, 0x4f800000, v3
	s_nop 0
	v_cndmask_b32_e32 v3, v3, v16, vcc
	v_sqrt_f32_e32 v16, v3
	s_nop 0
	v_add_u32_e32 v17, -1, v16
	v_fma_f32 v18, -v17, v16, v3
	v_cmp_ge_f32_e64 s[0:1], 0, v18
	v_add_u32_e32 v18, 1, v16
	s_nop 0
	v_cndmask_b32_e64 v17, v16, v17, s[0:1]
	v_fma_f32 v16, -v18, v16, v3
	v_cmp_lt_f32_e64 s[0:1], 0, v16
	s_nop 1
	v_cndmask_b32_e64 v16, v17, v18, s[0:1]
	v_mul_f32_e32 v17, 0x37800000, v16
	v_cndmask_b32_e32 v16, v16, v17, vcc
	v_cmp_class_f32_e32 vcc, v3, v193
	s_nop 1
	v_cndmask_b32_e32 v3, v16, v3, vcc
	v_cmp_ngt_f32_e32 vcc, s24, v0
	s_nop 1
	v_cndmask_b32_e32 v0, 1.0, v3, vcc
	v_mul_f32_e32 v0, v1, v0
	v_mul_f32_e32 v0, v51, v0
	ds_write_b32 v144, v2 offset:896
	ds_write_b32 v144, v0 offset:37760
	v_add_f32_e32 v0, v20, v36
	v_mul_f32_e32 v0, 0xbfb8aa3b, v0
	v_exp_f32_e32 v0, v0
	v_add_f32_e32 v1, v4, v38
	v_mul_f32_e32 v1, 0xbfb8aa3b, v1
	v_exp_f32_e32 v1, v1
	v_add_f32_e32 v0, 1.0, v0
	v_rcp_f32_e32 v0, v0
	v_add_f32_e32 v1, 1.0, v1
	v_rcp_f32_e32 v1, v1
	v_mul_f32_e32 v0, v0, v32
	v_mul_f32_e32 v2, 0x3fb8aa3b, v0
	v_add_f32_e32 v0, v0, v0
	v_mul_f32_e32 v3, 0x3fb8aa3b, v0
	v_rndne_f32_e32 v3, v3
	v_fmamk_f32 v4, v3, 0xbf317218, v0
	v_fmac_f32_e32 v4, 0x3102e308, v3
	v_fmamk_f32 v16, v4, 0x395133b1, v192
	v_cmp_eq_f32_e32 vcc, s21, v3
	v_cvt_i32_f32_e32 v3, v3
	v_fmaak_f32 v16, v4, v16, 0x3c0887f9
	v_fmaak_f32 v16, v4, v16, 0x3d2aaa81
	v_fmaak_f32 v16, v4, v16, 0x3e2aaaab
	v_fma_f32 v16, v4, v16, 0.5
	v_ldexp_f32 v3, 1.0, v3
	v_mul_f32_e32 v16, v4, v16
	v_cndmask_b32_e32 v3, v3, v202, vcc
	v_fmac_f32_e32 v4, v4, v16
	v_add_f32_e32 v16, -1.0, v3
	v_fmac_f32_e32 v16, v3, v4
	v_add_f32_e32 v3, v16, v16
	v_cndmask_b32_e32 v3, v16, v3, vcc
	v_cmp_nlt_f32_e32 vcc, s22, v0
	v_exp_f32_e32 v2, v2
	s_nop 0
	v_cndmask_b32_e64 v3, v201, -v3, vcc
	v_cmp_gt_f32_e32 vcc, s23, v3
	v_mul_f32_e32 v4, 0x4f800000, v3
	s_nop 0
	v_cndmask_b32_e32 v3, v3, v4, vcc
	v_sqrt_f32_e32 v4, v3
	s_nop 0
	v_add_u32_e32 v16, -1, v4
	v_fma_f32 v17, -v16, v4, v3
	v_cmp_ge_f32_e64 s[0:1], 0, v17
	v_add_u32_e32 v17, 1, v4
	s_nop 0
	v_cndmask_b32_e64 v16, v4, v16, s[0:1]
	v_fma_f32 v4, -v17, v4, v3
	v_cmp_lt_f32_e64 s[0:1], 0, v4
	s_nop 1
	v_cndmask_b32_e64 v4, v16, v17, s[0:1]
	v_mul_f32_e32 v16, 0x37800000, v4
	v_cndmask_b32_e32 v4, v4, v16, vcc
	v_cmp_class_f32_e32 vcc, v3, v193
	s_nop 1
	v_cndmask_b32_e32 v3, v4, v3, vcc
	v_cmp_ngt_f32_e32 vcc, s24, v0
	s_nop 1
	v_cndmask_b32_e32 v0, 1.0, v3, vcc
	v_mul_f32_e32 v0, v1, v0
	v_mul_f32_e32 v0, v139, v0
	ds_write_b32 v144, v2 offset:2176
	ds_write_b32 v144, v0 offset:39040
	v_add_f32_e32 v0, v21, v36
	v_mul_f32_e32 v0, 0xbfb8aa3b, v0
	v_exp_f32_e32 v0, v0
	v_add_f32_e32 v1, v5, v38
	v_mul_f32_e32 v1, 0xbfb8aa3b, v1
	v_exp_f32_e32 v1, v1
	v_add_f32_e32 v0, 1.0, v0
	v_rcp_f32_e32 v0, v0
	v_add_f32_e32 v1, 1.0, v1
	v_rcp_f32_e32 v1, v1
	v_mul_f32_e32 v0, v0, v32
	v_mul_f32_e32 v2, 0x3fb8aa3b, v0
	v_add_f32_e32 v0, v0, v0
	v_mul_f32_e32 v3, 0x3fb8aa3b, v0
	v_rndne_f32_e32 v3, v3
	v_fmamk_f32 v4, v3, 0xbf317218, v0
	v_fmac_f32_e32 v4, 0x3102e308, v3
	v_fmamk_f32 v5, v4, 0x395133b1, v192
	v_cmp_eq_f32_e32 vcc, s21, v3
	v_cvt_i32_f32_e32 v3, v3
	v_fmaak_f32 v5, v4, v5, 0x3c0887f9
	v_fmaak_f32 v5, v4, v5, 0x3d2aaa81
	v_fmaak_f32 v5, v4, v5, 0x3e2aaaab
	v_fma_f32 v5, v4, v5, 0.5
	v_ldexp_f32 v3, 1.0, v3
	v_mul_f32_e32 v5, v4, v5
	v_cndmask_b32_e32 v3, v3, v202, vcc
	v_fmac_f32_e32 v4, v4, v5
	v_add_f32_e32 v5, -1.0, v3
	v_fmac_f32_e32 v5, v3, v4
	v_add_f32_e32 v3, v5, v5
	v_cndmask_b32_e32 v3, v5, v3, vcc
	v_cmp_nlt_f32_e32 vcc, s22, v0
	v_exp_f32_e32 v2, v2
	s_nop 0
	v_cndmask_b32_e64 v3, v201, -v3, vcc
	v_cmp_gt_f32_e32 vcc, s23, v3
	v_mul_f32_e32 v4, 0x4f800000, v3
	s_nop 0
	v_cndmask_b32_e32 v3, v3, v4, vcc
	v_sqrt_f32_e32 v4, v3
	s_nop 0
	v_add_u32_e32 v5, -1, v4
	v_fma_f32 v16, -v5, v4, v3
	v_cmp_ge_f32_e64 s[0:1], 0, v16
	v_add_u32_e32 v16, 1, v4
	s_nop 0
	v_cndmask_b32_e64 v5, v4, v5, s[0:1]
	v_fma_f32 v4, -v16, v4, v3
	v_cmp_lt_f32_e64 s[0:1], 0, v4
	s_nop 1
	v_cndmask_b32_e64 v4, v5, v16, s[0:1]
	v_mul_f32_e32 v5, 0x37800000, v4
	v_cndmask_b32_e32 v4, v4, v5, vcc
	v_cmp_class_f32_e32 vcc, v3, v193
	s_nop 1
	v_cndmask_b32_e32 v3, v4, v3, vcc
	v_cmp_ngt_f32_e32 vcc, s24, v0
	s_nop 1
	v_cndmask_b32_e32 v0, 1.0, v3, vcc
	v_mul_f32_e32 v0, v1, v0
	v_mul_f32_e32 v0, v37, v0
	ds_write_b32 v144, v2 offset:2432
	ds_write_b32 v144, v0 offset:39296
	v_add_f32_e32 v0, v22, v36
	v_mul_f32_e32 v0, 0xbfb8aa3b, v0
	v_exp_f32_e32 v0, v0
	v_add_f32_e32 v1, v6, v38
	v_mul_f32_e32 v1, 0xbfb8aa3b, v1
	v_exp_f32_e32 v1, v1
	v_add_f32_e32 v0, 1.0, v0
	v_rcp_f32_e32 v0, v0
	v_add_f32_e32 v1, 1.0, v1
	v_rcp_f32_e32 v1, v1
	v_mul_f32_e32 v0, v0, v32
	v_mul_f32_e32 v2, 0x3fb8aa3b, v0
	v_add_f32_e32 v0, v0, v0
	v_mul_f32_e32 v3, 0x3fb8aa3b, v0
	v_rndne_f32_e32 v3, v3
	v_fmamk_f32 v4, v3, 0xbf317218, v0
	v_fmac_f32_e32 v4, 0x3102e308, v3
	v_fmamk_f32 v5, v4, 0x395133b1, v192
	v_cmp_eq_f32_e32 vcc, s21, v3
	v_cvt_i32_f32_e32 v3, v3
	v_fmaak_f32 v5, v4, v5, 0x3c0887f9
	v_fmaak_f32 v5, v4, v5, 0x3d2aaa81
	v_fmaak_f32 v5, v4, v5, 0x3e2aaaab
	v_fma_f32 v5, v4, v5, 0.5
	v_ldexp_f32 v3, 1.0, v3
	v_mul_f32_e32 v5, v4, v5
	v_cndmask_b32_e32 v3, v3, v202, vcc
	v_fmac_f32_e32 v4, v4, v5
	v_add_f32_e32 v5, -1.0, v3
	v_fmac_f32_e32 v5, v3, v4
	v_add_f32_e32 v3, v5, v5
	v_cndmask_b32_e32 v3, v5, v3, vcc
	v_cmp_nlt_f32_e32 vcc, s22, v0
	v_exp_f32_e32 v2, v2
	s_nop 0
	v_cndmask_b32_e64 v3, v201, -v3, vcc
	v_cmp_gt_f32_e32 vcc, s23, v3
	v_mul_f32_e32 v4, 0x4f800000, v3
	s_nop 0
	v_cndmask_b32_e32 v3, v3, v4, vcc
	v_sqrt_f32_e32 v4, v3
	s_nop 0
	v_add_u32_e32 v5, -1, v4
	v_fma_f32 v6, -v5, v4, v3
	v_cmp_ge_f32_e64 s[0:1], 0, v6
	v_add_u32_e32 v6, 1, v4
	s_nop 0
	v_cndmask_b32_e64 v5, v4, v5, s[0:1]
	v_fma_f32 v4, -v6, v4, v3
	v_cmp_lt_f32_e64 s[0:1], 0, v4
	s_nop 1
	v_cndmask_b32_e64 v4, v5, v6, s[0:1]
	v_mul_f32_e32 v5, 0x37800000, v4
	v_cndmask_b32_e32 v4, v4, v5, vcc
	v_cmp_class_f32_e32 vcc, v3, v193
	s_nop 1
	v_cndmask_b32_e32 v3, v4, v3, vcc
	v_cmp_ngt_f32_e32 vcc, s24, v0
	s_nop 1
	v_cndmask_b32_e32 v0, 1.0, v3, vcc
	v_mul_f32_e32 v0, v1, v0
	v_mul_f32_e32 v0, v53, v0
	ds_write_b32 v144, v2 offset:2688
	ds_write_b32 v144, v0 offset:39552
	v_add_f32_e32 v0, v23, v36
	v_mul_f32_e32 v0, 0xbfb8aa3b, v0
	v_exp_f32_e32 v0, v0
	v_add_f32_e32 v1, v7, v38
	v_mul_f32_e32 v1, 0xbfb8aa3b, v1
	v_exp_f32_e32 v1, v1
	v_add_f32_e32 v0, 1.0, v0
	v_rcp_f32_e32 v0, v0
	v_add_f32_e32 v1, 1.0, v1
	v_rcp_f32_e32 v1, v1
	v_mul_f32_e32 v0, v0, v32
	v_mul_f32_e32 v2, 0x3fb8aa3b, v0
	v_add_f32_e32 v0, v0, v0
	v_mul_f32_e32 v3, 0x3fb8aa3b, v0
	v_rndne_f32_e32 v3, v3
	v_fmamk_f32 v4, v3, 0xbf317218, v0
	v_fmac_f32_e32 v4, 0x3102e308, v3
	v_fmamk_f32 v5, v4, 0x395133b1, v192
	v_cmp_eq_f32_e32 vcc, s21, v3
	v_cvt_i32_f32_e32 v3, v3
	v_fmaak_f32 v5, v4, v5, 0x3c0887f9
	v_fmaak_f32 v5, v4, v5, 0x3d2aaa81
	v_fmaak_f32 v5, v4, v5, 0x3e2aaaab
	v_fma_f32 v5, v4, v5, 0.5
	v_ldexp_f32 v3, 1.0, v3
	v_mul_f32_e32 v5, v4, v5
	v_cndmask_b32_e32 v3, v3, v202, vcc
	v_fmac_f32_e32 v4, v4, v5
	v_add_f32_e32 v5, -1.0, v3
	v_fmac_f32_e32 v5, v3, v4
	v_add_f32_e32 v3, v5, v5
	v_cndmask_b32_e32 v3, v5, v3, vcc
	v_cmp_nlt_f32_e32 vcc, s22, v0
	v_exp_f32_e32 v2, v2
	s_nop 0
	v_cndmask_b32_e64 v3, v201, -v3, vcc
	v_cmp_gt_f32_e32 vcc, s23, v3
	v_mul_f32_e32 v4, 0x4f800000, v3
	s_nop 0
	v_cndmask_b32_e32 v3, v3, v4, vcc
	v_sqrt_f32_e32 v4, v3
	s_nop 0
	v_add_u32_e32 v5, -1, v4
	v_fma_f32 v6, -v5, v4, v3
	v_cmp_ge_f32_e64 s[0:1], 0, v6
	v_add_u32_e32 v6, 1, v4
	s_nop 0
	v_cndmask_b32_e64 v5, v4, v5, s[0:1]
	v_fma_f32 v4, -v6, v4, v3
	v_cmp_lt_f32_e64 s[0:1], 0, v4
	s_nop 1
	v_cndmask_b32_e64 v4, v5, v6, s[0:1]
	v_mul_f32_e32 v5, 0x37800000, v4
	v_cndmask_b32_e32 v4, v4, v5, vcc
	v_cmp_class_f32_e32 vcc, v3, v193
	s_nop 1
	v_cndmask_b32_e32 v3, v4, v3, vcc
	v_cmp_ngt_f32_e32 vcc, s24, v0
	s_nop 1
	v_cndmask_b32_e32 v0, 1.0, v3, vcc
	v_mul_f32_e32 v0, v1, v0
	v_mul_f32_e32 v0, v39, v0
	ds_write_b32 v144, v2 offset:2944
	ds_write_b32 v144, v0 offset:39808
	v_add_f32_e32 v0, v24, v36
	v_mul_f32_e32 v0, 0xbfb8aa3b, v0
	v_exp_f32_e32 v0, v0
	v_add_f32_e32 v1, v8, v38
	v_mul_f32_e32 v1, 0xbfb8aa3b, v1
	v_exp_f32_e32 v1, v1
	v_add_f32_e32 v0, 1.0, v0
	v_rcp_f32_e32 v0, v0
	v_add_f32_e32 v1, 1.0, v1
	v_rcp_f32_e32 v1, v1
	v_mul_f32_e32 v0, v0, v32
	v_mul_f32_e32 v2, 0x3fb8aa3b, v0
	v_add_f32_e32 v0, v0, v0
	v_mul_f32_e32 v3, 0x3fb8aa3b, v0
	v_rndne_f32_e32 v3, v3
	v_fmamk_f32 v4, v3, 0xbf317218, v0
	v_fmac_f32_e32 v4, 0x3102e308, v3
	v_fmamk_f32 v5, v4, 0x395133b1, v192
	v_cmp_eq_f32_e32 vcc, s21, v3
	v_cvt_i32_f32_e32 v3, v3
	v_fmaak_f32 v5, v4, v5, 0x3c0887f9
	v_fmaak_f32 v5, v4, v5, 0x3d2aaa81
	v_fmaak_f32 v5, v4, v5, 0x3e2aaaab
	v_fma_f32 v5, v4, v5, 0.5
	v_ldexp_f32 v3, 1.0, v3
	v_mul_f32_e32 v5, v4, v5
	v_cndmask_b32_e32 v3, v3, v202, vcc
	v_fmac_f32_e32 v4, v4, v5
	v_add_f32_e32 v5, -1.0, v3
	v_fmac_f32_e32 v5, v3, v4
	v_add_f32_e32 v3, v5, v5
	v_cndmask_b32_e32 v3, v5, v3, vcc
	v_cmp_nlt_f32_e32 vcc, s22, v0
	v_exp_f32_e32 v2, v2
	s_nop 0
	v_cndmask_b32_e64 v3, v201, -v3, vcc
	v_cmp_gt_f32_e32 vcc, s23, v3
	v_mul_f32_e32 v4, 0x4f800000, v3
	s_nop 0
	v_cndmask_b32_e32 v3, v3, v4, vcc
	v_sqrt_f32_e32 v4, v3
	s_nop 0
	v_add_u32_e32 v5, -1, v4
	v_fma_f32 v6, -v5, v4, v3
	v_cmp_ge_f32_e64 s[0:1], 0, v6
	v_add_u32_e32 v6, 1, v4
	s_nop 0
	v_cndmask_b32_e64 v5, v4, v5, s[0:1]
	v_fma_f32 v4, -v6, v4, v3
	v_cmp_lt_f32_e64 s[0:1], 0, v4
	s_nop 1
	v_cndmask_b32_e64 v4, v5, v6, s[0:1]
	v_mul_f32_e32 v5, 0x37800000, v4
	v_cndmask_b32_e32 v4, v4, v5, vcc
	v_cmp_class_f32_e32 vcc, v3, v193
	s_nop 1
	v_cndmask_b32_e32 v3, v4, v3, vcc
	v_cmp_ngt_f32_e32 vcc, s24, v0
	s_nop 1
	v_cndmask_b32_e32 v0, 1.0, v3, vcc
	v_mul_f32_e32 v0, v1, v0
	v_mul_f32_e32 v0, v55, v0
	ds_write_b32 v144, v2 offset:4224
	ds_write_b32 v144, v0 offset:41088
	v_add_f32_e32 v0, v25, v36
	v_mul_f32_e32 v0, 0xbfb8aa3b, v0
	v_exp_f32_e32 v0, v0
	v_add_f32_e32 v1, v9, v38
	v_mul_f32_e32 v1, 0xbfb8aa3b, v1
	v_exp_f32_e32 v1, v1
	v_add_f32_e32 v0, 1.0, v0
	v_rcp_f32_e32 v0, v0
	v_add_f32_e32 v1, 1.0, v1
	v_rcp_f32_e32 v1, v1
	v_mul_f32_e32 v0, v0, v32
	v_mul_f32_e32 v2, 0x3fb8aa3b, v0
	v_add_f32_e32 v0, v0, v0
	v_mul_f32_e32 v3, 0x3fb8aa3b, v0
	v_rndne_f32_e32 v3, v3
	v_fmamk_f32 v4, v3, 0xbf317218, v0
	v_fmac_f32_e32 v4, 0x3102e308, v3
	v_fmamk_f32 v5, v4, 0x395133b1, v192
	v_cmp_eq_f32_e32 vcc, s21, v3
	v_cvt_i32_f32_e32 v3, v3
	v_fmaak_f32 v5, v4, v5, 0x3c0887f9
	v_fmaak_f32 v5, v4, v5, 0x3d2aaa81
	v_fmaak_f32 v5, v4, v5, 0x3e2aaaab
	v_fma_f32 v5, v4, v5, 0.5
	v_ldexp_f32 v3, 1.0, v3
	v_mul_f32_e32 v5, v4, v5
	v_cndmask_b32_e32 v3, v3, v202, vcc
	v_fmac_f32_e32 v4, v4, v5
	v_add_f32_e32 v5, -1.0, v3
	v_fmac_f32_e32 v5, v3, v4
	v_add_f32_e32 v3, v5, v5
	v_cndmask_b32_e32 v3, v5, v3, vcc
	v_cmp_nlt_f32_e32 vcc, s22, v0
	v_exp_f32_e32 v2, v2
	s_nop 0
	v_cndmask_b32_e64 v3, v201, -v3, vcc
	v_cmp_gt_f32_e32 vcc, s23, v3
	v_mul_f32_e32 v4, 0x4f800000, v3
	s_nop 0
	v_cndmask_b32_e32 v3, v3, v4, vcc
	v_sqrt_f32_e32 v4, v3
	s_nop 0
	v_add_u32_e32 v5, -1, v4
	v_fma_f32 v6, -v5, v4, v3
	v_cmp_ge_f32_e64 s[0:1], 0, v6
	v_add_u32_e32 v6, 1, v4
	s_nop 0
	v_cndmask_b32_e64 v5, v4, v5, s[0:1]
	v_fma_f32 v4, -v6, v4, v3
	v_cmp_lt_f32_e64 s[0:1], 0, v4
	s_nop 1
	v_cndmask_b32_e64 v4, v5, v6, s[0:1]
	v_mul_f32_e32 v5, 0x37800000, v4
	v_cndmask_b32_e32 v4, v4, v5, vcc
	v_cmp_class_f32_e32 vcc, v3, v193
	s_nop 1
	v_cndmask_b32_e32 v3, v4, v3, vcc
	v_cmp_ngt_f32_e32 vcc, s24, v0
	s_nop 1
	v_cndmask_b32_e32 v0, 1.0, v3, vcc
	v_mul_f32_e32 v0, v1, v0
	v_mul_f32_e32 v0, v41, v0
	ds_write_b32 v144, v2 offset:4480
	ds_write_b32 v144, v0 offset:41344
	v_add_f32_e32 v0, v26, v36
	v_mul_f32_e32 v0, 0xbfb8aa3b, v0
	v_exp_f32_e32 v0, v0
	v_add_f32_e32 v1, v10, v38
	v_mul_f32_e32 v1, 0xbfb8aa3b, v1
	v_exp_f32_e32 v1, v1
	v_add_f32_e32 v0, 1.0, v0
	v_rcp_f32_e32 v0, v0
	v_add_f32_e32 v1, 1.0, v1
	v_rcp_f32_e32 v1, v1
	v_mul_f32_e32 v0, v0, v32
	v_mul_f32_e32 v2, 0x3fb8aa3b, v0
	v_add_f32_e32 v0, v0, v0
	v_mul_f32_e32 v3, 0x3fb8aa3b, v0
	v_rndne_f32_e32 v3, v3
	v_fmamk_f32 v4, v3, 0xbf317218, v0
	v_fmac_f32_e32 v4, 0x3102e308, v3
	v_fmamk_f32 v5, v4, 0x395133b1, v192
	v_cmp_eq_f32_e32 vcc, s21, v3
	v_cvt_i32_f32_e32 v3, v3
	v_fmaak_f32 v5, v4, v5, 0x3c0887f9
	v_fmaak_f32 v5, v4, v5, 0x3d2aaa81
	v_fmaak_f32 v5, v4, v5, 0x3e2aaaab
	v_fma_f32 v5, v4, v5, 0.5
	v_ldexp_f32 v3, 1.0, v3
	v_mul_f32_e32 v5, v4, v5
	v_cndmask_b32_e32 v3, v3, v202, vcc
	v_fmac_f32_e32 v4, v4, v5
	v_add_f32_e32 v5, -1.0, v3
	v_fmac_f32_e32 v5, v3, v4
	v_add_f32_e32 v3, v5, v5
	v_cndmask_b32_e32 v3, v5, v3, vcc
	v_cmp_nlt_f32_e32 vcc, s22, v0
	v_exp_f32_e32 v2, v2
	s_nop 0
	v_cndmask_b32_e64 v3, v201, -v3, vcc
	v_cmp_gt_f32_e32 vcc, s23, v3
	v_mul_f32_e32 v4, 0x4f800000, v3
	s_nop 0
	v_cndmask_b32_e32 v3, v3, v4, vcc
	v_sqrt_f32_e32 v4, v3
	s_nop 0
	v_add_u32_e32 v5, -1, v4
	v_fma_f32 v6, -v5, v4, v3
	v_cmp_ge_f32_e64 s[0:1], 0, v6
	v_add_u32_e32 v6, 1, v4
	s_nop 0
	v_cndmask_b32_e64 v5, v4, v5, s[0:1]
	v_fma_f32 v4, -v6, v4, v3
	v_cmp_lt_f32_e64 s[0:1], 0, v4
	s_nop 1
	v_cndmask_b32_e64 v4, v5, v6, s[0:1]
	v_mul_f32_e32 v5, 0x37800000, v4
	v_cndmask_b32_e32 v4, v4, v5, vcc
	v_cmp_class_f32_e32 vcc, v3, v193
	s_nop 1
	v_cndmask_b32_e32 v3, v4, v3, vcc
	v_cmp_ngt_f32_e32 vcc, s24, v0
	s_nop 1
	v_cndmask_b32_e32 v0, 1.0, v3, vcc
	v_mul_f32_e32 v0, v1, v0
	v_mul_f32_e32 v0, v57, v0
	ds_write_b32 v144, v2 offset:4736
	ds_write_b32 v144, v0 offset:41600
	v_add_f32_e32 v0, v27, v36
	v_mul_f32_e32 v0, 0xbfb8aa3b, v0
	v_exp_f32_e32 v0, v0
	v_add_f32_e32 v1, v11, v38
	v_mul_f32_e32 v1, 0xbfb8aa3b, v1
	v_exp_f32_e32 v1, v1
	v_add_f32_e32 v0, 1.0, v0
	v_rcp_f32_e32 v0, v0
	v_add_f32_e32 v1, 1.0, v1
	v_rcp_f32_e32 v1, v1
	v_mul_f32_e32 v0, v0, v32
	v_mul_f32_e32 v2, 0x3fb8aa3b, v0
	v_add_f32_e32 v0, v0, v0
	v_mul_f32_e32 v3, 0x3fb8aa3b, v0
	v_rndne_f32_e32 v3, v3
	v_fmamk_f32 v4, v3, 0xbf317218, v0
	v_fmac_f32_e32 v4, 0x3102e308, v3
	v_fmamk_f32 v5, v4, 0x395133b1, v192
	v_cmp_eq_f32_e32 vcc, s21, v3
	v_cvt_i32_f32_e32 v3, v3
	v_fmaak_f32 v5, v4, v5, 0x3c0887f9
	v_fmaak_f32 v5, v4, v5, 0x3d2aaa81
	v_fmaak_f32 v5, v4, v5, 0x3e2aaaab
	v_fma_f32 v5, v4, v5, 0.5
	v_ldexp_f32 v3, 1.0, v3
	v_mul_f32_e32 v5, v4, v5
	v_cndmask_b32_e32 v3, v3, v202, vcc
	v_fmac_f32_e32 v4, v4, v5
	v_add_f32_e32 v5, -1.0, v3
	v_fmac_f32_e32 v5, v3, v4
	v_add_f32_e32 v3, v5, v5
	v_cndmask_b32_e32 v3, v5, v3, vcc
	v_cmp_nlt_f32_e32 vcc, s22, v0
	v_exp_f32_e32 v2, v2
	s_nop 0
	v_cndmask_b32_e64 v3, v201, -v3, vcc
	v_cmp_gt_f32_e32 vcc, s23, v3
	v_mul_f32_e32 v4, 0x4f800000, v3
	s_nop 0
	v_cndmask_b32_e32 v3, v3, v4, vcc
	v_sqrt_f32_e32 v4, v3
	s_nop 0
	v_add_u32_e32 v5, -1, v4
	v_fma_f32 v6, -v5, v4, v3
	v_cmp_ge_f32_e64 s[0:1], 0, v6
	v_add_u32_e32 v6, 1, v4
	s_nop 0
	v_cndmask_b32_e64 v5, v4, v5, s[0:1]
	v_fma_f32 v4, -v6, v4, v3
	v_cmp_lt_f32_e64 s[0:1], 0, v4
	s_nop 1
	v_cndmask_b32_e64 v4, v5, v6, s[0:1]
	v_mul_f32_e32 v5, 0x37800000, v4
	v_cndmask_b32_e32 v4, v4, v5, vcc
	v_cmp_class_f32_e32 vcc, v3, v193
	s_nop 1
	v_cndmask_b32_e32 v3, v4, v3, vcc
	v_cmp_ngt_f32_e32 vcc, s24, v0
	s_nop 1
	v_cndmask_b32_e32 v0, 1.0, v3, vcc
	v_mul_f32_e32 v0, v1, v0
	v_mul_f32_e32 v0, v43, v0
	ds_write_b32 v144, v2 offset:4992
	ds_write_b32 v144, v0 offset:41856
	v_add_f32_e32 v0, v28, v36
	v_mul_f32_e32 v0, 0xbfb8aa3b, v0
	v_exp_f32_e32 v0, v0
	v_add_f32_e32 v1, v12, v38
	v_mul_f32_e32 v1, 0xbfb8aa3b, v1
	v_exp_f32_e32 v1, v1
	v_add_f32_e32 v0, 1.0, v0
	v_rcp_f32_e32 v0, v0
	v_add_f32_e32 v1, 1.0, v1
	v_rcp_f32_e32 v1, v1
	v_mul_f32_e32 v0, v0, v32
	v_mul_f32_e32 v2, 0x3fb8aa3b, v0
	v_add_f32_e32 v0, v0, v0
	v_mul_f32_e32 v3, 0x3fb8aa3b, v0
	v_rndne_f32_e32 v3, v3
	v_fmamk_f32 v4, v3, 0xbf317218, v0
	v_fmac_f32_e32 v4, 0x3102e308, v3
	v_fmamk_f32 v5, v4, 0x395133b1, v192
	v_cmp_eq_f32_e32 vcc, s21, v3
	v_cvt_i32_f32_e32 v3, v3
	v_fmaak_f32 v5, v4, v5, 0x3c0887f9
	v_fmaak_f32 v5, v4, v5, 0x3d2aaa81
	v_fmaak_f32 v5, v4, v5, 0x3e2aaaab
	v_fma_f32 v5, v4, v5, 0.5
	v_ldexp_f32 v3, 1.0, v3
	v_mul_f32_e32 v5, v4, v5
	v_cndmask_b32_e32 v3, v3, v202, vcc
	v_fmac_f32_e32 v4, v4, v5
	v_add_f32_e32 v5, -1.0, v3
	v_fmac_f32_e32 v5, v3, v4
	v_add_f32_e32 v3, v5, v5
	v_cndmask_b32_e32 v3, v5, v3, vcc
	v_cmp_nlt_f32_e32 vcc, s22, v0
	v_exp_f32_e32 v2, v2
	s_nop 0
	v_cndmask_b32_e64 v3, v201, -v3, vcc
	v_cmp_gt_f32_e32 vcc, s23, v3
	v_mul_f32_e32 v4, 0x4f800000, v3
	s_nop 0
	v_cndmask_b32_e32 v3, v3, v4, vcc
	v_sqrt_f32_e32 v4, v3
	s_nop 0
	v_add_u32_e32 v5, -1, v4
	v_fma_f32 v6, -v5, v4, v3
	v_cmp_ge_f32_e64 s[0:1], 0, v6
	v_add_u32_e32 v6, 1, v4
	s_nop 0
	v_cndmask_b32_e64 v5, v4, v5, s[0:1]
	v_fma_f32 v4, -v6, v4, v3
	v_cmp_lt_f32_e64 s[0:1], 0, v4
	s_nop 1
	v_cndmask_b32_e64 v4, v5, v6, s[0:1]
	v_mul_f32_e32 v5, 0x37800000, v4
	v_cndmask_b32_e32 v4, v4, v5, vcc
	v_cmp_class_f32_e32 vcc, v3, v193
	s_nop 1
	v_cndmask_b32_e32 v3, v4, v3, vcc
	v_cmp_ngt_f32_e32 vcc, s24, v0
	s_nop 1
	v_cndmask_b32_e32 v0, 1.0, v3, vcc
	v_mul_f32_e32 v0, v1, v0
	v_mul_f32_e32 v0, v59, v0
	ds_write_b32 v144, v2 offset:6272
	ds_write_b32 v144, v0 offset:43136
	v_add_f32_e32 v0, v29, v36
	v_mul_f32_e32 v0, 0xbfb8aa3b, v0
	v_exp_f32_e32 v0, v0
	v_add_f32_e32 v1, v13, v38
	v_mul_f32_e32 v1, 0xbfb8aa3b, v1
	v_exp_f32_e32 v1, v1
	v_add_f32_e32 v0, 1.0, v0
	v_rcp_f32_e32 v0, v0
	v_add_f32_e32 v1, 1.0, v1
	v_rcp_f32_e32 v1, v1
	v_mul_f32_e32 v0, v0, v32
	v_mul_f32_e32 v2, 0x3fb8aa3b, v0
	v_add_f32_e32 v0, v0, v0
	v_mul_f32_e32 v3, 0x3fb8aa3b, v0
	v_rndne_f32_e32 v3, v3
	v_fmamk_f32 v4, v3, 0xbf317218, v0
	v_fmac_f32_e32 v4, 0x3102e308, v3
	v_fmamk_f32 v5, v4, 0x395133b1, v192
	v_cmp_eq_f32_e32 vcc, s21, v3
	v_cvt_i32_f32_e32 v3, v3
	v_fmaak_f32 v5, v4, v5, 0x3c0887f9
	v_fmaak_f32 v5, v4, v5, 0x3d2aaa81
	v_fmaak_f32 v5, v4, v5, 0x3e2aaaab
	v_fma_f32 v5, v4, v5, 0.5
	v_ldexp_f32 v3, 1.0, v3
	v_mul_f32_e32 v5, v4, v5
	v_cndmask_b32_e32 v3, v3, v202, vcc
	v_fmac_f32_e32 v4, v4, v5
	v_add_f32_e32 v5, -1.0, v3
	v_fmac_f32_e32 v5, v3, v4
	v_add_f32_e32 v3, v5, v5
	v_cndmask_b32_e32 v3, v5, v3, vcc
	v_cmp_nlt_f32_e32 vcc, s22, v0
	v_exp_f32_e32 v2, v2
	s_nop 0
	v_cndmask_b32_e64 v3, v201, -v3, vcc
	v_cmp_gt_f32_e32 vcc, s23, v3
	v_mul_f32_e32 v4, 0x4f800000, v3
	s_nop 0
	v_cndmask_b32_e32 v3, v3, v4, vcc
	v_sqrt_f32_e32 v4, v3
	s_nop 0
	v_add_u32_e32 v5, -1, v4
	v_fma_f32 v6, -v5, v4, v3
	v_cmp_ge_f32_e64 s[0:1], 0, v6
	v_add_u32_e32 v6, 1, v4
	s_nop 0
	v_cndmask_b32_e64 v5, v4, v5, s[0:1]
	v_fma_f32 v4, -v6, v4, v3
	v_cmp_lt_f32_e64 s[0:1], 0, v4
	s_nop 1
	v_cndmask_b32_e64 v4, v5, v6, s[0:1]
	v_mul_f32_e32 v5, 0x37800000, v4
	v_cndmask_b32_e32 v4, v4, v5, vcc
	v_cmp_class_f32_e32 vcc, v3, v193
	s_nop 1
	v_cndmask_b32_e32 v3, v4, v3, vcc
	v_cmp_ngt_f32_e32 vcc, s24, v0
	s_nop 1
	v_cndmask_b32_e32 v0, 1.0, v3, vcc
	v_mul_f32_e32 v0, v1, v0
	v_mul_f32_e32 v0, v45, v0
	ds_write_b32 v144, v2 offset:6528
	ds_write_b32 v144, v0 offset:43392
	v_add_f32_e32 v0, v30, v36
	v_mul_f32_e32 v0, 0xbfb8aa3b, v0
	v_exp_f32_e32 v0, v0
	v_add_f32_e32 v1, v14, v38
	v_mul_f32_e32 v1, 0xbfb8aa3b, v1
	v_exp_f32_e32 v1, v1
	v_add_f32_e32 v0, 1.0, v0
	v_rcp_f32_e32 v0, v0
	v_add_f32_e32 v1, 1.0, v1
	v_rcp_f32_e32 v1, v1
	v_mul_f32_e32 v0, v0, v32
	v_mul_f32_e32 v2, 0x3fb8aa3b, v0
	v_add_f32_e32 v0, v0, v0
	v_mul_f32_e32 v3, 0x3fb8aa3b, v0
	v_rndne_f32_e32 v3, v3
	v_fmamk_f32 v4, v3, 0xbf317218, v0
	v_fmac_f32_e32 v4, 0x3102e308, v3
	v_fmamk_f32 v5, v4, 0x395133b1, v192
	v_cmp_eq_f32_e32 vcc, s21, v3
	v_cvt_i32_f32_e32 v3, v3
	v_fmaak_f32 v5, v4, v5, 0x3c0887f9
	v_fmaak_f32 v5, v4, v5, 0x3d2aaa81
	v_fmaak_f32 v5, v4, v5, 0x3e2aaaab
	v_fma_f32 v5, v4, v5, 0.5
	v_ldexp_f32 v3, 1.0, v3
	v_mul_f32_e32 v5, v4, v5
	v_cndmask_b32_e32 v3, v3, v202, vcc
	v_fmac_f32_e32 v4, v4, v5
	v_add_f32_e32 v5, -1.0, v3
	v_fmac_f32_e32 v5, v3, v4
	v_add_f32_e32 v3, v5, v5
	v_cndmask_b32_e32 v3, v5, v3, vcc
	v_cmp_nlt_f32_e32 vcc, s22, v0
	v_exp_f32_e32 v2, v2
	s_nop 0
	v_cndmask_b32_e64 v3, v201, -v3, vcc
	v_cmp_gt_f32_e32 vcc, s23, v3
	v_mul_f32_e32 v4, 0x4f800000, v3
	s_nop 0
	v_cndmask_b32_e32 v3, v3, v4, vcc
	v_sqrt_f32_e32 v4, v3
	s_nop 0
	v_add_u32_e32 v5, -1, v4
	v_fma_f32 v6, -v5, v4, v3
	v_cmp_ge_f32_e64 s[0:1], 0, v6
	v_add_u32_e32 v6, 1, v4
	s_nop 0
	v_cndmask_b32_e64 v5, v4, v5, s[0:1]
	v_fma_f32 v4, -v6, v4, v3
	v_cmp_lt_f32_e64 s[0:1], 0, v4
	s_nop 1
	v_cndmask_b32_e64 v4, v5, v6, s[0:1]
	v_mul_f32_e32 v5, 0x37800000, v4
	v_cndmask_b32_e32 v4, v4, v5, vcc
	v_cmp_class_f32_e32 vcc, v3, v193
	s_nop 1
	v_cndmask_b32_e32 v3, v4, v3, vcc
	v_cmp_ngt_f32_e32 vcc, s24, v0
	s_nop 1
	v_cndmask_b32_e32 v0, 1.0, v3, vcc
	v_mul_f32_e32 v0, v1, v0
	v_mul_f32_e32 v0, v35, v0
	v_add_u32_e32 v1, 0x1800, v144
	ds_write2_b32 v1, v2, v34 offset0:160 offset1:192
	ds_write_b32 v144, v0 offset:43648
	v_add_f32_e32 v0, v31, v36
	v_mul_f32_e32 v0, 0xbfb8aa3b, v0
	v_exp_f32_e32 v0, v0
	v_add_f32_e32 v1, v15, v38
	v_mul_f32_e32 v1, 0xbfb8aa3b, v1
	v_exp_f32_e32 v1, v1
	v_add_f32_e32 v0, 1.0, v0
	v_rcp_f32_e32 v0, v0
	v_add_f32_e32 v1, 1.0, v1
	v_rcp_f32_e32 v1, v1
	v_mul_f32_e32 v0, v0, v32
	v_mul_f32_e32 v2, 0x3fb8aa3b, v0
	v_add_f32_e32 v0, v0, v0
	v_mul_f32_e32 v3, 0x3fb8aa3b, v0
	v_rndne_f32_e32 v3, v3
	v_fmamk_f32 v4, v3, 0xbf317218, v0
	v_fmac_f32_e32 v4, 0x3102e308, v3
	v_fmamk_f32 v5, v4, 0x395133b1, v192
	v_cmp_eq_f32_e32 vcc, s21, v3
	v_cvt_i32_f32_e32 v3, v3
	v_fmaak_f32 v5, v4, v5, 0x3c0887f9
	v_fmaak_f32 v5, v4, v5, 0x3d2aaa81
	v_fmaak_f32 v5, v4, v5, 0x3e2aaaab
	v_fma_f32 v5, v4, v5, 0.5
	v_ldexp_f32 v3, 1.0, v3
	v_mul_f32_e32 v5, v4, v5
	v_cndmask_b32_e32 v3, v3, v202, vcc
	v_fmac_f32_e32 v4, v4, v5
	v_add_f32_e32 v5, -1.0, v3
	v_fmac_f32_e32 v5, v3, v4
	v_add_f32_e32 v3, v5, v5
	v_cndmask_b32_e32 v3, v5, v3, vcc
	v_cmp_nlt_f32_e32 vcc, s22, v0
	v_exp_f32_e32 v2, v2
	s_mov_b32 s21, 0x84000
	v_cndmask_b32_e64 v3, v201, -v3, vcc
	v_cmp_gt_f32_e32 vcc, s23, v3
	v_mul_f32_e32 v4, 0x4f800000, v3
	s_mov_b32 s22, 0x2d000
	v_cndmask_b32_e32 v3, v3, v4, vcc
	v_sqrt_f32_e32 v4, v3
	s_mov_b32 s23, 0x59000
	v_add_u32_e32 v5, -1, v4
	v_fma_f32 v6, -v5, v4, v3
	v_cmp_ge_f32_e64 s[0:1], 0, v6
	v_add_u32_e32 v6, 1, v4
	s_nop 0
	v_cndmask_b32_e64 v5, v4, v5, s[0:1]
	v_fma_f32 v4, -v6, v4, v3
	v_cmp_lt_f32_e64 s[0:1], 0, v4
	s_nop 1
	v_cndmask_b32_e64 v4, v5, v6, s[0:1]
	v_mul_f32_e32 v5, 0x37800000, v4
	v_cndmask_b32_e32 v4, v4, v5, vcc
	v_cmp_class_f32_e32 vcc, v3, v193
	v_mov_b32_e32 v5, 0
	s_nop 0
	v_cndmask_b32_e32 v3, v4, v3, vcc
	v_cmp_ngt_f32_e32 vcc, s24, v0
	v_readlane_b32 s24, v248, 7
	s_nop 0
	v_cndmask_b32_e32 v0, 1.0, v3, vcc
	v_mul_f32_e32 v0, v1, v0
	v_mul_f32_e32 v0, v33, v0
	ds_write_b32 v144, v2 offset:7040
	ds_write_b32 v144, v0 offset:43904
	v_mov_b32_e32 v0, 0
	s_waitcnt lgkmcnt(0)
	s_barrier
	s_cbranch_scc1 .LBB0_915
	v_lshl_add_u64 v[2:3], v[64:65], 0, s[4:5]
	v_add_co_u32_e32 v4, vcc, 0x13000, v2
	s_sub_i32 s0, s2, s12
	s_nop 0
	v_addc_co_u32_e32 v5, vcc, 0, v3, vcc
	global_load_dwordx2 v[4:5], v[4:5], off
	s_cmp_eq_u32 s0, 1
	s_waitcnt vmcnt(0)
	v_fmac_f32_e32 v5, 0, v4
	s_cbranch_scc1 .LBB0_915
	v_add_co_u32_e32 v2, vcc, 0x12000, v2
	s_cmp_eq_u32 s0, 2
	s_nop 0
	v_addc_co_u32_e32 v3, vcc, 0, v3, vcc
	global_load_dwordx2 v[2:3], v[2:3], off
	s_waitcnt vmcnt(0)
	v_fmac_f32_e32 v3, v5, v2
	s_cbranch_scc1 .LBB0_914
	s_mul_i32 s1, s11, 36
	s_add_i32 s2, s1, 36
	s_ashr_i32 s3, s2, 31
	s_lshl_b64 s[2:3], s[2:3], 12
	v_readlane_b32 s1, v249, 47
	s_add_u32 s2, s1, s2
	v_readlane_b32 s1, v249, 48
	v_add_lshl_u32 v96, s13, v141, 3
	s_addc_u32 s3, s1, s3
	v_lshl_add_u64 v[4:5], s[2:3], 0, v[96:97]
	s_add_i32 s0, s0, -2

.Lm3acq_done:
	s_mov_b64 exec, s[100:101]
	s_barrier
	s_nop 0
	s_ashr_i32 s0, s6, 31
	v_readlane_b32 s1, v248, 29
	s_xor_b32 s0, s0, s1
	s_abs_i32 s1, s6
	v_readlane_b32 s2, v248, 31
	s_mul_hi_u32 s2, s1, s2
	v_readlane_b32 s7, v248, 30
	s_mul_i32 s3, s2, s7
	s_sub_i32 s1, s1, s3
	s_add_i32 s3, s2, 1
	s_sub_i32 s4, s1, s7
	s_cmp_ge_u32 s1, s7
	s_cselect_b32 s2, s3, s2
	s_cselect_b32 s1, s4, s1
	s_add_i32 s3, s2, 1
	s_cmp_ge_u32 s1, s7
	s_cselect_b32 s1, s3, s2
	s_xor_b32 s1, s1, s0
	s_sub_i32 s0, s1, s0
	s_mul_i32 s1, s0, s60
	s_sub_i32 s60, s6, s1
	s_add_i32 s60, s60, s61
	s_ashr_i32 s4, s0, 2
	s_and_b32 s11, s0, 3
	s_lshl_b32 s0, s60, 7
	s_cmp_lt_i32 s60, 2
	s_movk_i32 s2, 0xff00
	s_cselect_b32 s1, 8, 11
	s_cselect_b32 s2, 0x4000, s2
	s_mov_b32 s9, s61
	s_lshl_b32 s1, s4, s1
	s_add_i32 s61, s0, s2
	s_add_i32 s61, s61, s1
	s_mul_i32 s1, s61, 0x3600
	v_readlane_b32 s2, v249, 7
	s_mul_hi_i32 s0, s61, 0x3600
	v_readlane_b32 s3, v249, 8
	s_add_u32 s6, s2, s1
	s_addc_u32 s7, s3, s0
	s_lshl_b32 s0, s11, 8
	v_mov_b32_e32 v0, v162
	s_add_u32 s70, s6, s0
	v_mov_b32_e32 v1, v162
	s_movk_i32 s0, 0x800
	s_barrier
	s_addc_u32 s71, s7, 0
	s_nop 0
	v_cmp_gt_i32_e32 vcc, s0, v1
	s_and_saveexec_b64 s[0:1], vcc
	s_cbranch_execz .LBB0_926
	v_readlane_b32 s2, v249, 53
	v_lshlrev_b32_e32 v3, 3, v1
	s_nop 0
	v_lshl_add_u32 v2, v1, 4, s2
	s_mov_b64 s[2:3], 0
.LBB0_925:
	v_ashrrev_i32_e32 v6, 31, v1
	v_lshrrev_b32_e32 v6, 28, v6
	v_add_u32_e32 v8, v1, v6
	v_mov_b64_e32 v[4:5], s[70:71]
	v_ashrrev_i32_e32 v6, 4, v8
	v_mad_i64_i32 v[4:5], s[12:13], v6, s74, v[4:5]
	v_lshlrev_b32_e32 v6, 7, v6
	v_sub_u32_e32 v6, v3, v6
	v_ashrrev_i32_e32 v7, 31, v6
	v_lshl_add_u64 v[4:5], v[6:7], 1, v[4:5]
	global_load_dwordx4 v[16:19], v[4:5], off offset:2048
	v_add_u32_e32 v9, 0x100, v1
	v_cmp_lt_i32_e32 vcc, s77, v1
	v_and_b32_e32 v8, -16, v8
	s_or_b64 s[2:3], vcc, s[2:3]
	v_mov_b32_e32 v1, v9
	v_add_u32_e32 v8, v2, v8
	v_add_u32_e32 v2, 0x1000, v2
	v_add_u32_e32 v3, 0x800, v3
	v_mov_b32_e32 v44, v8
	v_ashrrev_i32_e32 v6, 31, v1
	v_lshrrev_b32_e32 v6, 28, v6
	v_add_u32_e32 v8, v1, v6
	v_mov_b64_e32 v[4:5], s[70:71]
	v_ashrrev_i32_e32 v6, 4, v8
	v_mad_i64_i32 v[4:5], s[12:13], v6, s74, v[4:5]
	v_lshlrev_b32_e32 v6, 7, v6
	v_sub_u32_e32 v6, v3, v6
	v_ashrrev_i32_e32 v7, 31, v6
	v_lshl_add_u64 v[4:5], v[6:7], 1, v[4:5]
	global_load_dwordx4 v[20:23], v[4:5], off offset:2048
	v_add_u32_e32 v9, 0x100, v1
	v_cmp_lt_i32_e32 vcc, s77, v1
	v_and_b32_e32 v8, -16, v8
	s_or_b64 s[2:3], vcc, s[2:3]
	v_mov_b32_e32 v1, v9
	v_add_u32_e32 v8, v2, v8
	v_add_u32_e32 v2, 0x1000, v2
	v_add_u32_e32 v3, 0x800, v3
	v_mov_b32_e32 v45, v8
	v_ashrrev_i32_e32 v6, 31, v1
	v_lshrrev_b32_e32 v6, 28, v6
	v_add_u32_e32 v8, v1, v6
	v_mov_b64_e32 v[4:5], s[70:71]
	v_ashrrev_i32_e32 v6, 4, v8
	v_mad_i64_i32 v[4:5], s[12:13], v6, s74, v[4:5]
	v_lshlrev_b32_e32 v6, 7, v6
	v_sub_u32_e32 v6, v3, v6
	v_ashrrev_i32_e32 v7, 31, v6
	v_lshl_add_u64 v[4:5], v[6:7], 1, v[4:5]
	global_load_dwordx4 v[24:27], v[4:5], off offset:2048
	v_add_u32_e32 v9, 0x100, v1
	v_cmp_lt_i32_e32 vcc, s77, v1
	v_and_b32_e32 v8, -16, v8
	s_or_b64 s[2:3], vcc, s[2:3]
	v_mov_b32_e32 v1, v9
	v_add_u32_e32 v8, v2, v8
	v_add_u32_e32 v2, 0x1000, v2
	v_add_u32_e32 v3, 0x800, v3
	v_mov_b32_e32 v46, v8
	v_ashrrev_i32_e32 v6, 31, v1
	v_lshrrev_b32_e32 v6, 28, v6
	v_add_u32_e32 v8, v1, v6
	v_mov_b64_e32 v[4:5], s[70:71]
	v_ashrrev_i32_e32 v6, 4, v8
	v_mad_i64_i32 v[4:5], s[12:13], v6, s74, v[4:5]
	v_lshlrev_b32_e32 v6, 7, v6
	v_sub_u32_e32 v6, v3, v6
	v_ashrrev_i32_e32 v7, 31, v6
	v_lshl_add_u64 v[4:5], v[6:7], 1, v[4:5]
	global_load_dwordx4 v[28:31], v[4:5], off offset:2048
	v_add_u32_e32 v9, 0x100, v1
	v_cmp_lt_i32_e32 vcc, s77, v1
	v_and_b32_e32 v8, -16, v8
	s_or_b64 s[2:3], vcc, s[2:3]
	v_mov_b32_e32 v1, v9
	v_add_u32_e32 v8, v2, v8
	v_add_u32_e32 v2, 0x1000, v2
	v_add_u32_e32 v3, 0x800, v3
	v_mov_b32_e32 v47, v8
	v_ashrrev_i32_e32 v6, 31, v1
	v_lshrrev_b32_e32 v6, 28, v6
	v_add_u32_e32 v8, v1, v6
	v_mov_b64_e32 v[4:5], s[70:71]
	v_ashrrev_i32_e32 v6, 4, v8
	v_mad_i64_i32 v[4:5], s[12:13], v6, s74, v[4:5]
	v_lshlrev_b32_e32 v6, 7, v6
	v_sub_u32_e32 v6, v3, v6
	v_ashrrev_i32_e32 v7, 31, v6
	v_lshl_add_u64 v[4:5], v[6:7], 1, v[4:5]
	global_load_dwordx4 v[32:35], v[4:5], off offset:2048
	v_add_u32_e32 v9, 0x100, v1
	v_cmp_lt_i32_e32 vcc, s77, v1
	v_and_b32_e32 v8, -16, v8
	s_or_b64 s[2:3], vcc, s[2:3]
	v_mov_b32_e32 v1, v9
	v_add_u32_e32 v8, v2, v8
	v_add_u32_e32 v2, 0x1000, v2
	v_add_u32_e32 v3, 0x800, v3
	v_mov_b32_e32 v48, v8
	v_ashrrev_i32_e32 v6, 31, v1
	v_lshrrev_b32_e32 v6, 28, v6
	v_add_u32_e32 v8, v1, v6
	v_mov_b64_e32 v[4:5], s[70:71]
	v_ashrrev_i32_e32 v6, 4, v8
	v_mad_i64_i32 v[4:5], s[12:13], v6, s74, v[4:5]
	v_lshlrev_b32_e32 v6, 7, v6
	v_sub_u32_e32 v6, v3, v6
	v_ashrrev_i32_e32 v7, 31, v6
	v_lshl_add_u64 v[4:5], v[6:7], 1, v[4:5]
	global_load_dwordx4 v[36:39], v[4:5], off offset:2048
	v_add_u32_e32 v9, 0x100, v1
	v_cmp_lt_i32_e32 vcc, s77, v1
	v_and_b32_e32 v8, -16, v8
	s_or_b64 s[2:3], vcc, s[2:3]
	v_mov_b32_e32 v1, v9
	v_add_u32_e32 v8, v2, v8
	v_add_u32_e32 v2, 0x1000, v2
	v_add_u32_e32 v3, 0x800, v3
	v_mov_b32_e32 v49, v8
	v_ashrrev_i32_e32 v6, 31, v1
	v_lshrrev_b32_e32 v6, 28, v6
	v_add_u32_e32 v8, v1, v6
	v_mov_b64_e32 v[4:5], s[70:71]
	v_ashrrev_i32_e32 v6, 4, v8
	v_mad_i64_i32 v[4:5], s[12:13], v6, s74, v[4:5]
	v_lshlrev_b32_e32 v6, 7, v6
	v_sub_u32_e32 v6, v3, v6
	v_ashrrev_i32_e32 v7, 31, v6
	v_lshl_add_u64 v[4:5], v[6:7], 1, v[4:5]
	global_load_dwordx4 v[40:43], v[4:5], off offset:2048
	v_add_u32_e32 v9, 0x100, v1
	v_cmp_lt_i32_e32 vcc, s77, v1
	v_and_b32_e32 v8, -16, v8
	s_or_b64 s[2:3], vcc, s[2:3]
	v_mov_b32_e32 v1, v9
	v_add_u32_e32 v8, v2, v8
	v_add_u32_e32 v2, 0x1000, v2
	v_add_u32_e32 v3, 0x800, v3
	v_mov_b32_e32 v50, v8
	v_ashrrev_i32_e32 v6, 31, v1
	v_lshrrev_b32_e32 v6, 28, v6
	v_add_u32_e32 v8, v1, v6
	v_mov_b64_e32 v[4:5], s[70:71]
	v_ashrrev_i32_e32 v6, 4, v8
	v_mad_i64_i32 v[4:5], s[12:13], v6, s74, v[4:5]
	v_lshlrev_b32_e32 v6, 7, v6
	v_sub_u32_e32 v6, v3, v6
	v_ashrrev_i32_e32 v7, 31, v6
	v_lshl_add_u64 v[4:5], v[6:7], 1, v[4:5]
	global_load_dwordx4 v[4:7], v[4:5], off offset:2048
	v_add_u32_e32 v9, 0x100, v1
	v_cmp_lt_i32_e32 vcc, s77, v1
	v_and_b32_e32 v8, -16, v8
	s_or_b64 s[2:3], vcc, s[2:3]
	v_add_u32_e32 v8, v2, v8
	s_waitcnt vmcnt(7)
	ds_write_b128 v44, v[16:19]
	s_waitcnt vmcnt(6)
	ds_write_b128 v45, v[20:23]
	s_waitcnt vmcnt(5)
	ds_write_b128 v46, v[24:27]
	s_waitcnt vmcnt(4)
	ds_write_b128 v47, v[28:31]
	s_waitcnt vmcnt(3)
	ds_write_b128 v48, v[32:35]
	s_waitcnt vmcnt(2)
	ds_write_b128 v49, v[36:39]
	s_waitcnt vmcnt(1)
	ds_write_b128 v50, v[40:43]
	s_waitcnt vmcnt(0)
	ds_write_b128 v8, v[4:7]

.LBB0_928:
	s_or_b32 s0, s4, s62
	s_mul_i32 s0, s0, 18
	s_add_i32 s12, s0, s60
	s_ashr_i32 s13, s12, 31
	s_lshl_b64 s[0:1], s[12:13], 2
	s_add_u32 s0, s78, s0
	s_addc_u32 s1, s72, s1
	global_load_dword v96, v97, s[0:1]
	s_barrier
	s_and_saveexec_b64 s[0:1], s[38:39]
	s_cbranch_execz .LBB0_930
	s_lshl_b32 s4, s4, 3
	s_or_b32 s54, s4, s63
	s_mov_b32 s55, s5
	s_nop 0
	s_lshl_b64 s[54:55], s[54:55], 2
	v_readlane_b32 s20, v251, 24
	v_readlane_b32 s21, v251, 25
	s_add_u32 s54, s20, s54
	v_lshl_add_u64 v[0:1], s[4:5], 2, v[114:115]
	s_addc_u32 s55, s21, s55
	s_add_i32 s4, s4, s63
	global_load_dword v3, v97, s[54:55]
	s_lshl_b64 s[54:55], s[4:5], 2
	s_add_u32 s54, s20, s54
	s_addc_u32 s55, s21, s55
	global_load_dword v2, v[0:1], off
	s_mov_b32 s4, 0xbfb8aa3b
	global_load_dword v0, v[0:1], off offset:16
	global_load_dword v1, v97, s[54:55] offset:16
	s_lshl_b64 s[54:55], s[12:13], 9
	v_readlane_b32 s30, v248, 2
	s_mov_b64 s[16:17], s[82:83]
	s_mov_b32 s25, 0x85000
	s_mov_b32 s23, 0x59000
	s_mov_b32 s22, 0x2d000
	s_mov_b32 s19, 0x2c000
	s_movk_i32 s18, 0x1600
	s_movk_i32 s29, 0x47ff
	s_mov_b32 s28, 0x4800000
	v_readlane_b32 s31, v248, 3
	s_mov_b32 s20, 0x58000
	s_mov_b32 s21, 0x84000
	v_readlane_b32 s24, v251, 28
	v_readlane_b32 s26, v251, 30
	v_readlane_b32 s27, v251, 31
	s_waitcnt vmcnt(2)
	v_add_f32_e32 v2, v2, v3
	ds_write_b32 v130, v2
	s_waitcnt vmcnt(0)
	v_add_f32_e32 v0, v0, v1
	v_min_f32_e32 v2, 0, v0
	v_mul_f32_e64 v0, |v0|, s4
	v_exp_f32_e32 v3, v0
	s_mov_b32 s4, 0x3f2aaaab
	v_add_f32_e32 v4, 1.0, v3
	v_add_f32_e32 v0, -1.0, v4
	v_sub_f32_e32 v1, v0, v4
	v_add_f32_e32 v1, 1.0, v1
	v_sub_f32_e32 v0, v3, v0
	v_add_f32_e32 v5, v0, v1
	v_frexp_mant_f32_e32 v0, v4
	v_cmp_gt_f32_e32 vcc, s4, v0
	v_cvt_f64_f32_e32 v[0:1], v4
	v_frexp_exp_i32_f64_e32 v0, v[0:1]
	v_subbrev_co_u32_e32 v0, vcc, 0, v0, vcc
	v_sub_u32_e32 v1, 0, v0
	v_ldexp_f32 v4, v4, v1
	v_ldexp_f32 v1, v5, v1
	v_add_f32_e32 v5, -1.0, v4
	v_add_f32_e32 v6, 1.0, v5
	v_sub_f32_e32 v6, v4, v6
	v_add_f32_e32 v6, v1, v6
	v_add_f32_e32 v7, v5, v6
	v_sub_f32_e32 v5, v7, v5
	v_sub_f32_e32 v5, v6, v5
	v_add_f32_e32 v6, 1.0, v4
	v_add_f32_e32 v8, -1.0, v6
	v_sub_f32_e32 v4, v4, v8
	v_add_f32_e32 v1, v1, v4
	v_add_f32_e32 v4, v6, v1
	v_sub_f32_e32 v6, v4, v6
	v_sub_f32_e32 v1, v1, v6
	v_rcp_f32_e32 v6, v4
	v_cvt_f32_i32_e32 v0, v0
	s_mov_b32 s4, 0x3f317218
	v_mul_f32_e32 v8, v7, v6
	v_mul_f32_e32 v9, v4, v8
	v_fma_f32 v10, v8, v4, -v9
	v_fmac_f32_e32 v10, v8, v1
	v_add_f32_e32 v11, v9, v10
	v_sub_f32_e32 v12, v7, v11
	v_sub_f32_e32 v7, v7, v12
	v_sub_f32_e32 v9, v11, v9
	v_sub_f32_e32 v7, v7, v11
	v_add_f32_e32 v5, v5, v7
	v_sub_f32_e32 v7, v9, v10
	v_add_f32_e32 v5, v7, v5
	v_add_f32_e32 v7, v12, v5
	v_mul_f32_e32 v9, v6, v7
	v_mul_f32_e32 v10, v4, v9
	v_fma_f32 v4, v9, v4, -v10
	v_fmac_f32_e32 v4, v9, v1
	v_sub_f32_e32 v1, v12, v7
	v_add_f32_e32 v1, v5, v1
	v_add_f32_e32 v5, v10, v4
	v_sub_f32_e32 v11, v7, v5
	v_sub_f32_e32 v7, v7, v11
	v_sub_f32_e32 v10, v5, v10
	v_sub_f32_e32 v5, v7, v5
	v_add_f32_e32 v1, v1, v5
	v_sub_f32_e32 v4, v10, v4
	v_add_f32_e32 v1, v4, v1
	v_add_f32_e32 v4, v8, v9
	v_add_f32_e32 v1, v11, v1
	v_sub_f32_e32 v5, v4, v8
	v_mul_f32_e32 v1, v6, v1
	v_sub_f32_e32 v5, v9, v5
	v_add_f32_e32 v1, v5, v1
	v_mul_f32_e32 v8, 0x3f317218, v0
	v_add_f32_e32 v5, v4, v1
	v_fma_f32 v9, v0, s4, -v8
	v_mul_f32_e32 v6, v5, v5
	v_fmac_f32_e32 v9, 0xb102e308, v0
	v_sub_f32_e32 v0, v5, v4
	v_fmamk_f32 v7, v6, 0x3e9b6dac, v191
	v_sub_f32_e32 v0, v1, v0
	v_add_f32_e32 v1, v8, v9
	v_fmaak_f32 v7, v6, v7, 0x3f2aaada
	v_sub_f32_e32 v4, v1, v8
	v_ldexp_f32 v8, v5, 1
	v_mul_f32_e32 v5, v5, v6
	v_mul_f32_e32 v5, v5, v7
	v_add_f32_e32 v6, v8, v5
	v_sub_f32_e32 v7, v6, v8
	v_ldexp_f32 v0, v0, 1
	v_sub_f32_e32 v5, v5, v7
	v_add_f32_e32 v0, v0, v5
	v_add_f32_e32 v5, v6, v0
	v_sub_f32_e32 v6, v5, v6
	v_sub_f32_e32 v0, v0, v6
	v_add_f32_e32 v6, v1, v5
	v_sub_f32_e32 v7, v6, v1
	v_sub_f32_e32 v8, v6, v7
	v_sub_f32_e32 v4, v9, v4
	v_sub_f32_e32 v1, v1, v8
	v_sub_f32_e32 v5, v5, v7
	v_add_f32_e32 v1, v5, v1
	v_add_f32_e32 v5, v4, v0
	v_sub_f32_e32 v7, v5, v4
	v_sub_f32_e32 v8, v5, v7
	v_sub_f32_e32 v4, v4, v8
	v_sub_f32_e32 v0, v0, v7
	v_add_f32_e32 v1, v5, v1
	v_add_f32_e32 v0, v0, v4
	v_add_f32_e32 v4, v6, v1
	v_sub_f32_e32 v5, v4, v6
	v_sub_f32_e32 v1, v1, v5
	v_add_f32_e32 v0, v0, v1
	s_mov_b32 s4, 0x7f800000
	v_add_f32_e32 v0, v4, v0
	v_cmp_neq_f32_e32 vcc, s4, v3
	s_mov_b32 s4, 0x33800000
	s_nop 0
	v_cndmask_b32_e32 v0, v199, v0, vcc
	v_cmp_ngt_f32_e32 vcc, -1.0, v3
	s_nop 1
	v_cndmask_b32_e32 v0, v200, v0, vcc
	v_cmp_neq_f32_e32 vcc, -1.0, v3
	s_nop 1
	v_cndmask_b32_e32 v0, v201, v0, vcc
	v_cmp_lt_f32_e64 vcc, |v3|, s4
	s_nop 1
	v_cndmask_b32_e32 v0, v0, v3, vcc
	v_sub_f32_e32 v0, v2, v0
	ds_write_b32 v131, v0
	v_lshl_add_u64 v[0:1], v[116:117], 0, s[54:55]
	global_load_dword v0, v[0:1], off
	s_waitcnt vmcnt(0)
	ds_write_b32 v132, v0

.LBB0_947:
	s_or_b64 exec, exec, s[0:1]
	v_add_f32_e32 v0, 0, v110
	v_add_f32_e32 v0, v0, v111
	v_add_f32_e32 v0, v0, v109
	v_cvt_pk_bf16_f32 v110, v110, v111
	v_cvt_pk_bf16_f32 v111, v109, v112
	v_xor_b32_e32 v109, 16, v105
	v_cmp_lt_i32_e64 s[0:1], v109, v106
	v_add_f32_e32 v118, v0, v112
	v_lshl_add_u32 v113, v99, 3, 0
	v_cndmask_b32_e64 v109, v105, v109, s[0:1]
	v_lshlrev_b32_e32 v229, 2, v109
	v_mul_lo_u32 v0, v100, s87
	v_mov_b32_e32 v109, v118
	v_mov_b32_e32 v255, v118
	s_nop 1
	v_permlane16_swap_b32_e32 v109, v255
	v_add_u32_e32 v0, v113, v0
	ds_write_b64 v0, v[110:111] offset:34816
	v_xor_b32_e32 v110, 8, v105
	v_cmp_lt_i32_e64 s[0:1], v110, v106
	s_waitcnt lgkmcnt(1)
	v_add_f32_e32 v109, v109, v255
	v_cmp_eq_u32_e32 vcc, 0, v99
	v_cndmask_b32_e64 v110, v105, v110, s[0:1]
	v_lshlrev_b32_e32 v230, 2, v110
	s_waitcnt lgkmcnt(0)
	v_add_f32_dpp v109, v109, v109 row_ror:8 row_mask:0xf bank_mask:0xf
	v_xor_b32_e32 v110, 4, v105
	v_cmp_lt_i32_e64 s[0:1], v110, v106
	s_nop 1
	v_cndmask_b32_e64 v110, v105, v110, s[0:1]
	s_nop 0
	v_mov_b32_dpp v110, v109 row_shl:4 row_mask:0xf bank_mask:0x5
	v_mov_b32_dpp v110, v109 row_shr:4 row_mask:0xf bank_mask:0xa
	v_add_f32_e32 v109, v109, v110
	v_xor_b32_e32 v110, 2, v105
	v_cmp_lt_i32_e64 s[0:1], v110, v106
	s_nop 1
	v_cndmask_b32_e64 v110, v105, v110, s[0:1]
	v_lshlrev_b32_e32 v232, 2, v110
	v_add_f32_dpp v109, v109, v109 quad_perm:[2,3,0,1] row_mask:0xf bank_mask:0xf
	v_xor_b32_e32 v110, 1, v105
	v_cmp_lt_i32_e64 s[0:1], v110, v106
	s_nop 1
	v_cndmask_b32_e64 v105, v105, v110, s[0:1]
	v_lshlrev_b32_e32 v233, 2, v105
	v_mov_b32_dpp v105, v109 quad_perm:[1,0,3,2] row_mask:0xf bank_mask:0xf
	s_and_saveexec_b64 s[0:1], vcc
	s_cbranch_execz .LBB0_949
	s_waitcnt lgkmcnt(0)
	v_add_f32_e32 v105, v109, v105
	s_waitcnt vmcnt(0)
	v_sub_f32_e32 v106, v96, v108
	v_add_u32_e32 v109, 0x11c00, v107
	v_mul_f32_e32 v106, 0x3fb8aa3b, v106
	ds_read_b32 v109, v109
	v_exp_f32_e32 v106, v106
	s_waitcnt lgkmcnt(0)
	v_fmac_f32_e32 v105, v106, v109
	v_add_u32_e32 v109, 0x11e00, v107
	ds_write_b32 v109, v105
	v_add_u32_e32 v105, 0x12000, v107
	ds_write_b32 v105, v106
	v_add_u32_e32 v105, 0x11800, v107
	ds_read_b32 v105, v105
	v_add_u32_e32 v106, 0x12200, v107
	s_waitcnt lgkmcnt(0)
	v_add_f32_e32 v105, v108, v105
	v_mul_f32_e32 v105, 0xbfb8aa3b, v105
	v_exp_f32_e32 v105, v105
	ds_write_b32 v106, v105

.LBB0_1101:
	s_waitcnt lgkmcnt(0)
	v_ashrrev_i32_e32 v3, 31, v0
	v_lshrrev_b32_e32 v3, 28, v3
	v_add_u32_e32 v3, v0, v3
	v_ashrrev_i32_e32 v4, 4, v3
	v_ashrrev_i32_e32 v5, 31, v4
	v_lshlrev_b32_e32 v6, 7, v4
	v_lshlrev_b64 v[4:5], 8, v[4:5]
	v_sub_u32_e32 v6, v2, v6
	v_lshl_add_u64 v[4:5], s[6:7], 0, v[4:5]
	v_ashrrev_i32_e32 v7, 31, v6
	v_lshl_add_u64 v[4:5], v[6:7], 1, v[4:5]
	global_load_dwordx4 v[16:19], v[4:5], off
	v_add_u32_e32 v8, 0x100, v0
	v_cmp_lt_i32_e32 vcc, s77, v0
	v_and_b32_e32 v3, -16, v3
	s_or_b64 s[12:13], vcc, s[12:13]
	v_mov_b32_e32 v0, v8
	v_add_u32_e32 v3, v1, v3
	v_add_u32_e32 v1, 0x1000, v1
	v_add_u32_e32 v2, 0x800, v2
	v_mov_b32_e32 v44, v3
	s_waitcnt lgkmcnt(0)
	v_ashrrev_i32_e32 v3, 31, v0
	v_lshrrev_b32_e32 v3, 28, v3
	v_add_u32_e32 v3, v0, v3
	v_ashrrev_i32_e32 v4, 4, v3
	v_ashrrev_i32_e32 v5, 31, v4
	v_lshlrev_b32_e32 v6, 7, v4
	v_lshlrev_b64 v[4:5], 8, v[4:5]
	v_sub_u32_e32 v6, v2, v6
	v_lshl_add_u64 v[4:5], s[6:7], 0, v[4:5]
	v_ashrrev_i32_e32 v7, 31, v6
	v_lshl_add_u64 v[4:5], v[6:7], 1, v[4:5]
	global_load_dwordx4 v[20:23], v[4:5], off
	v_add_u32_e32 v8, 0x100, v0
	v_cmp_lt_i32_e32 vcc, s77, v0
	v_and_b32_e32 v3, -16, v3
	s_or_b64 s[12:13], vcc, s[12:13]
	v_mov_b32_e32 v0, v8
	v_add_u32_e32 v3, v1, v3
	v_add_u32_e32 v1, 0x1000, v1
	v_add_u32_e32 v2, 0x800, v2
	v_mov_b32_e32 v45, v3
	s_waitcnt lgkmcnt(0)
	v_ashrrev_i32_e32 v3, 31, v0
	v_lshrrev_b32_e32 v3, 28, v3
	v_add_u32_e32 v3, v0, v3
	v_ashrrev_i32_e32 v4, 4, v3
	v_ashrrev_i32_e32 v5, 31, v4
	v_lshlrev_b32_e32 v6, 7, v4
	v_lshlrev_b64 v[4:5], 8, v[4:5]
	v_sub_u32_e32 v6, v2, v6
	v_lshl_add_u64 v[4:5], s[6:7], 0, v[4:5]
	v_ashrrev_i32_e32 v7, 31, v6
	v_lshl_add_u64 v[4:5], v[6:7], 1, v[4:5]
	global_load_dwordx4 v[24:27], v[4:5], off
	v_add_u32_e32 v8, 0x100, v0
	v_cmp_lt_i32_e32 vcc, s77, v0
	v_and_b32_e32 v3, -16, v3
	s_or_b64 s[12:13], vcc, s[12:13]
	v_mov_b32_e32 v0, v8
	v_add_u32_e32 v3, v1, v3
	v_add_u32_e32 v1, 0x1000, v1
	v_add_u32_e32 v2, 0x800, v2
	v_mov_b32_e32 v46, v3
	s_waitcnt lgkmcnt(0)
	v_ashrrev_i32_e32 v3, 31, v0
	v_lshrrev_b32_e32 v3, 28, v3
	v_add_u32_e32 v3, v0, v3
	v_ashrrev_i32_e32 v4, 4, v3
	v_ashrrev_i32_e32 v5, 31, v4
	v_lshlrev_b32_e32 v6, 7, v4
	v_lshlrev_b64 v[4:5], 8, v[4:5]
	v_sub_u32_e32 v6, v2, v6
	v_lshl_add_u64 v[4:5], s[6:7], 0, v[4:5]
	v_ashrrev_i32_e32 v7, 31, v6
	v_lshl_add_u64 v[4:5], v[6:7], 1, v[4:5]
	global_load_dwordx4 v[28:31], v[4:5], off
	v_add_u32_e32 v8, 0x100, v0
	v_cmp_lt_i32_e32 vcc, s77, v0
	v_and_b32_e32 v3, -16, v3
	s_or_b64 s[12:13], vcc, s[12:13]
	v_mov_b32_e32 v0, v8
	v_add_u32_e32 v3, v1, v3
	v_add_u32_e32 v1, 0x1000, v1
	v_add_u32_e32 v2, 0x800, v2
	v_mov_b32_e32 v47, v3
	s_waitcnt lgkmcnt(0)
	v_ashrrev_i32_e32 v3, 31, v0
	v_lshrrev_b32_e32 v3, 28, v3
	v_add_u32_e32 v3, v0, v3
	v_ashrrev_i32_e32 v4, 4, v3
	v_ashrrev_i32_e32 v5, 31, v4
	v_lshlrev_b32_e32 v6, 7, v4
	v_lshlrev_b64 v[4:5], 8, v[4:5]
	v_sub_u32_e32 v6, v2, v6
	v_lshl_add_u64 v[4:5], s[6:7], 0, v[4:5]
	v_ashrrev_i32_e32 v7, 31, v6
	v_lshl_add_u64 v[4:5], v[6:7], 1, v[4:5]
	global_load_dwordx4 v[32:35], v[4:5], off
	v_add_u32_e32 v8, 0x100, v0
	v_cmp_lt_i32_e32 vcc, s77, v0
	v_and_b32_e32 v3, -16, v3
	s_or_b64 s[12:13], vcc, s[12:13]
	v_mov_b32_e32 v0, v8
	v_add_u32_e32 v3, v1, v3
	v_add_u32_e32 v1, 0x1000, v1
	v_add_u32_e32 v2, 0x800, v2
	v_mov_b32_e32 v48, v3
	s_waitcnt lgkmcnt(0)
	v_ashrrev_i32_e32 v3, 31, v0
	v_lshrrev_b32_e32 v3, 28, v3
	v_add_u32_e32 v3, v0, v3
	v_ashrrev_i32_e32 v4, 4, v3
	v_ashrrev_i32_e32 v5, 31, v4
	v_lshlrev_b32_e32 v6, 7, v4
	v_lshlrev_b64 v[4:5], 8, v[4:5]
	v_sub_u32_e32 v6, v2, v6
	v_lshl_add_u64 v[4:5], s[6:7], 0, v[4:5]
	v_ashrrev_i32_e32 v7, 31, v6
	v_lshl_add_u64 v[4:5], v[6:7], 1, v[4:5]
	global_load_dwordx4 v[36:39], v[4:5], off
	v_add_u32_e32 v8, 0x100, v0
	v_cmp_lt_i32_e32 vcc, s77, v0
	v_and_b32_e32 v3, -16, v3
	s_or_b64 s[12:13], vcc, s[12:13]
	v_mov_b32_e32 v0, v8
	v_add_u32_e32 v3, v1, v3
	v_add_u32_e32 v1, 0x1000, v1
	v_add_u32_e32 v2, 0x800, v2
	v_mov_b32_e32 v49, v3
	s_waitcnt lgkmcnt(0)
	v_ashrrev_i32_e32 v3, 31, v0
	v_lshrrev_b32_e32 v3, 28, v3
	v_add_u32_e32 v3, v0, v3
	v_ashrrev_i32_e32 v4, 4, v3
	v_ashrrev_i32_e32 v5, 31, v4
	v_lshlrev_b32_e32 v6, 7, v4
	v_lshlrev_b64 v[4:5], 8, v[4:5]
	v_sub_u32_e32 v6, v2, v6
	v_lshl_add_u64 v[4:5], s[6:7], 0, v[4:5]
	v_ashrrev_i32_e32 v7, 31, v6
	v_lshl_add_u64 v[4:5], v[6:7], 1, v[4:5]
	global_load_dwordx4 v[40:43], v[4:5], off
	v_add_u32_e32 v8, 0x100, v0
	v_cmp_lt_i32_e32 vcc, s77, v0
	v_and_b32_e32 v3, -16, v3
	s_or_b64 s[12:13], vcc, s[12:13]
	v_mov_b32_e32 v0, v8
	v_add_u32_e32 v3, v1, v3
	v_add_u32_e32 v1, 0x1000, v1
	v_add_u32_e32 v2, 0x800, v2
	v_mov_b32_e32 v50, v3
	s_waitcnt lgkmcnt(0)
	v_ashrrev_i32_e32 v3, 31, v0
	v_lshrrev_b32_e32 v3, 28, v3
	v_add_u32_e32 v3, v0, v3
	v_ashrrev_i32_e32 v4, 4, v3
	v_ashrrev_i32_e32 v5, 31, v4
	v_lshlrev_b32_e32 v6, 7, v4
	v_lshlrev_b64 v[4:5], 8, v[4:5]
	v_sub_u32_e32 v6, v2, v6
	v_lshl_add_u64 v[4:5], s[6:7], 0, v[4:5]
	v_ashrrev_i32_e32 v7, 31, v6
	v_lshl_add_u64 v[4:5], v[6:7], 1, v[4:5]
	global_load_dwordx4 v[4:7], v[4:5], off
	v_cmp_lt_i32_e32 vcc, s77, v0
	v_and_b32_e32 v3, -16, v3
	s_or_b64 s[12:13], vcc, s[12:13]
	v_add_u32_e32 v3, v1, v3
	s_waitcnt vmcnt(7)
	ds_write_b128 v44, v[16:19]
	s_waitcnt vmcnt(6)
	ds_write_b128 v45, v[20:23]
	s_waitcnt vmcnt(5)
	ds_write_b128 v46, v[24:27]
	s_waitcnt vmcnt(4)
	ds_write_b128 v47, v[28:31]
	s_waitcnt vmcnt(3)
	ds_write_b128 v48, v[32:35]
	s_waitcnt vmcnt(2)
	ds_write_b128 v49, v[36:39]
	s_waitcnt vmcnt(1)
	ds_write_b128 v50, v[40:43]
	s_waitcnt vmcnt(0)
	ds_write_b128 v3, v[4:7]
	s_or_b64 exec, exec, s[12:13]

.LBB0_1105:
	v_mov_b32_e32 v233, 0
	v_bfe_u32 v121, v119, 5, 1
	v_lshl_or_b32 v96, v121, 6, v118
	v_mul_u32_u24_e32 v96, 0x1b00, v96
	v_ashrrev_i32_e32 v238, 3, v119
	v_lshlrev_b32_e32 v96, 1, v96
	v_and_b32_e32 v126, -8, v238
	v_lshl_add_u64 v[122:123], s[2:3], 0, v[96:97]
	v_ashrrev_i32_e32 v127, 31, v126
	v_lshl_add_u64 v[234:235], v[126:127], 1, v[122:123]
	global_load_dwordx4 v[122:125], v[234:235], off
	v_add_co_u32_e32 v234, vcc, s85, v234
	v_lshl_add_u32 v96, v121, 2, v120
	s_nop 0
	v_addc_co_u32_e32 v235, vcc, 0, v235, vcc
	global_load_dwordx4 v[234:237], v[234:235], off
	v_mad_u64_u32 v[126:127], s[12:13], v126, s87, v[96:97]
	v_add_u32_e32 v229, 0x100, v119
	v_bfe_u32 v230, v229, 5, 1
	v_lshl_or_b32 v232, v230, 6, v118
	v_mul_u32_u24_e32 v232, 0x1b00, v232
	v_ashrrev_i32_e32 v239, 3, v229
	v_lshlrev_b32_e32 v232, 1, v232
	v_and_b32_e32 v246, -8, v239
	v_lshl_add_u64 v[242:243], s[2:3], 0, v[232:233]
	v_ashrrev_i32_e32 v247, 31, v246
	v_lshl_add_u64 v[252:253], v[246:247], 1, v[242:243]
	global_load_dwordx4 v[242:245], v[252:253], off
	v_add_co_u32_e32 v252, vcc, s85, v252
	v_lshl_add_u32 v232, v230, 2, v120
	s_nop 0
	v_addc_co_u32_e32 v253, vcc, 0, v253, vcc
	global_load_dwordx4 v[252:255], v[252:253], off
	v_mad_u64_u32 v[246:247], s[12:13], v246, s87, v[232:233]
	s_waitcnt vmcnt(3)
	v_and_b32_e32 v121, 0xffff, v122
	v_lshrrev_b32_e32 v122, 16, v122
	s_waitcnt vmcnt(2)
	v_lshl_or_b32 v121, v234, 16, v121
	v_and_or_b32 v122, v234, s79, v122
	ds_write2_b32 v126, v121, v122 offset1:68
	v_and_b32_e32 v121, 0xffff, v123
	v_lshrrev_b32_e32 v122, 16, v123
	v_lshl_or_b32 v121, v235, 16, v121
	v_and_or_b32 v122, v235, s79, v122
	ds_write2_b32 v126, v121, v122 offset0:136 offset1:204
	v_and_b32_e32 v121, 0xffff, v124
	v_lshrrev_b32_e32 v122, 16, v124
	v_lshl_or_b32 v121, v236, 16, v121
	v_and_or_b32 v122, v236, s79, v122
	v_add_u32_e32 v123, 0x400, v126
	ds_write2_b32 v123, v121, v122 offset0:16 offset1:84
	v_and_b32_e32 v121, 0xffff, v125
	v_lshl_or_b32 v121, v237, 16, v121
	v_or_b32_e32 v122, 7, v238
	ds_write_b32 v126, v121 offset:1632
	v_lshrrev_b32_e32 v121, 16, v125
	v_mad_u64_u32 v[122:123], s[12:13], v122, s87, v[96:97]
	v_and_or_b32 v121, v237, s79, v121
	ds_write_b32 v122, v121
	s_waitcnt vmcnt(1)
	v_and_b32_e32 v230, 0xffff, v242
	v_lshrrev_b32_e32 v242, 16, v242
	s_waitcnt vmcnt(0)
	v_lshl_or_b32 v230, v252, 16, v230
	v_and_or_b32 v242, v252, s79, v242
	ds_write2_b32 v246, v230, v242 offset1:68
	v_and_b32_e32 v230, 0xffff, v243
	v_lshrrev_b32_e32 v242, 16, v243
	v_lshl_or_b32 v230, v253, 16, v230
	v_and_or_b32 v242, v253, s79, v242
	ds_write2_b32 v246, v230, v242 offset0:136 offset1:204
	v_and_b32_e32 v230, 0xffff, v244
	v_lshrrev_b32_e32 v242, 16, v244
	v_lshl_or_b32 v230, v254, 16, v230
	v_and_or_b32 v242, v254, s79, v242
	v_add_u32_e32 v243, 0x400, v246
	ds_write2_b32 v243, v230, v242 offset0:16 offset1:84
	v_and_b32_e32 v230, 0xffff, v245
	v_lshl_or_b32 v230, v255, 16, v230
	v_or_b32_e32 v242, 7, v239
	ds_write_b32 v246, v230 offset:1632
	v_lshrrev_b32_e32 v230, 16, v245
	v_mad_u64_u32 v[242:243], s[12:13], v242, s87, v[232:233]
	v_and_or_b32 v230, v255, s79, v230
	ds_write_b32 v242, v230
	v_add_u32_e32 v119, 0x200, v119
	v_bfe_u32 v121, v119, 5, 1
	v_lshl_or_b32 v96, v121, 6, v118
	v_mul_u32_u24_e32 v96, 0x1b00, v96
	v_ashrrev_i32_e32 v238, 3, v119
	v_lshlrev_b32_e32 v96, 1, v96
	v_and_b32_e32 v126, -8, v238
	v_lshl_add_u64 v[122:123], s[2:3], 0, v[96:97]
	v_ashrrev_i32_e32 v127, 31, v126
	v_lshl_add_u64 v[234:235], v[126:127], 1, v[122:123]
	global_load_dwordx4 v[122:125], v[234:235], off
	v_add_co_u32_e32 v234, vcc, s85, v234
	v_lshl_add_u32 v96, v121, 2, v120
	s_nop 0
	v_addc_co_u32_e32 v235, vcc, 0, v235, vcc
	global_load_dwordx4 v[234:237], v[234:235], off
	v_mad_u64_u32 v[126:127], s[12:13], v126, s87, v[96:97]
	v_add_u32_e32 v229, 0x100, v119
	v_bfe_u32 v230, v229, 5, 1
	v_lshl_or_b32 v232, v230, 6, v118
	v_mul_u32_u24_e32 v232, 0x1b00, v232
	v_ashrrev_i32_e32 v239, 3, v229
	v_lshlrev_b32_e32 v232, 1, v232
	v_and_b32_e32 v246, -8, v239
	v_lshl_add_u64 v[242:243], s[2:3], 0, v[232:233]
	v_ashrrev_i32_e32 v247, 31, v246
	v_lshl_add_u64 v[252:253], v[246:247], 1, v[242:243]
	global_load_dwordx4 v[242:245], v[252:253], off
	v_add_co_u32_e32 v252, vcc, s85, v252
	v_lshl_add_u32 v232, v230, 2, v120
	s_nop 0
	v_addc_co_u32_e32 v253, vcc, 0, v253, vcc
	global_load_dwordx4 v[252:255], v[252:253], off
	v_mad_u64_u32 v[246:247], s[12:13], v246, s87, v[232:233]
	s_waitcnt vmcnt(3)
	v_and_b32_e32 v121, 0xffff, v122
	v_lshrrev_b32_e32 v122, 16, v122
	s_waitcnt vmcnt(2)
	v_lshl_or_b32 v121, v234, 16, v121
	v_and_or_b32 v122, v234, s79, v122
	ds_write2_b32 v126, v121, v122 offset1:68
	v_and_b32_e32 v121, 0xffff, v123
	v_lshrrev_b32_e32 v122, 16, v123
	v_lshl_or_b32 v121, v235, 16, v121
	v_and_or_b32 v122, v235, s79, v122
	ds_write2_b32 v126, v121, v122 offset0:136 offset1:204
	v_and_b32_e32 v121, 0xffff, v124
	v_lshrrev_b32_e32 v122, 16, v124
	v_lshl_or_b32 v121, v236, 16, v121
	v_and_or_b32 v122, v236, s79, v122
	v_add_u32_e32 v123, 0x400, v126
	ds_write2_b32 v123, v121, v122 offset0:16 offset1:84
	v_and_b32_e32 v121, 0xffff, v125
	v_lshl_or_b32 v121, v237, 16, v121
	v_or_b32_e32 v122, 7, v238
	ds_write_b32 v126, v121 offset:1632
	v_lshrrev_b32_e32 v121, 16, v125
	v_mad_u64_u32 v[122:123], s[12:13], v122, s87, v[96:97]
	v_and_or_b32 v121, v237, s79, v121
	ds_write_b32 v122, v121
	s_waitcnt vmcnt(1)
	v_and_b32_e32 v230, 0xffff, v242
	v_lshrrev_b32_e32 v242, 16, v242
	s_waitcnt vmcnt(0)
	v_lshl_or_b32 v230, v252, 16, v230
	v_and_or_b32 v242, v252, s79, v242
	ds_write2_b32 v246, v230, v242 offset1:68
	v_and_b32_e32 v230, 0xffff, v243
	v_lshrrev_b32_e32 v242, 16, v243
	v_lshl_or_b32 v230, v253, 16, v230
	v_and_or_b32 v242, v253, s79, v242
	ds_write2_b32 v246, v230, v242 offset0:136 offset1:204
	v_and_b32_e32 v230, 0xffff, v244
	v_lshrrev_b32_e32 v242, 16, v244
	v_lshl_or_b32 v230, v254, 16, v230
	v_and_or_b32 v242, v254, s79, v242
	v_add_u32_e32 v243, 0x400, v246
	ds_write2_b32 v243, v230, v242 offset0:16 offset1:84
	v_and_b32_e32 v230, 0xffff, v245
	v_lshl_or_b32 v230, v255, 16, v230
	v_or_b32_e32 v242, 7, v239
	ds_write_b32 v246, v230 offset:1632
	v_lshrrev_b32_e32 v230, 16, v245
	v_mad_u64_u32 v[242:243], s[12:13], v242, s87, v[232:233]
	v_and_or_b32 v230, v255, s79, v230
	ds_write_b32 v242, v230
	s_mov_b64 s[6:7], exec

.LBB0_1107:
	ds_read_b128 v[100:103], v98
	ds_read_b128 v[104:107], v96
	s_add_i32 s0, s0, 32
	s_cmpk_lt_u32 s0, 0x70
	s_waitcnt lgkmcnt(0)
	v_mfma_f32_32x32x16_bf16 v[0:15], v[100:103], v[104:107], v[0:15]
	ds_read_b128 v[104:107], v96 offset:8704
	s_waitcnt lgkmcnt(0)
	v_mfma_f32_32x32x16_bf16 v[16:31], v[100:103], v[104:107], v[16:31]
	ds_read_b128 v[104:107], v96 offset:17408
	s_waitcnt lgkmcnt(0)
	v_mfma_f32_32x32x16_bf16 v[32:47], v[100:103], v[104:107], v[32:47]
	ds_read_b128 v[104:107], v96 offset:26112
	s_waitcnt lgkmcnt(0)
	v_mfma_f32_32x32x16_bf16 v[48:63], v[100:103], v[104:107], v[48:63]
	ds_read_b128 v[100:103], v98 offset:32
	ds_read_b128 v[104:107], v96 offset:32
	v_add_u32_e32 v98, 64, v98
	s_waitcnt lgkmcnt(0)
	v_mfma_f32_32x32x16_bf16 v[0:15], v[100:103], v[104:107], v[0:15]
	ds_read_b128 v[104:107], v96 offset:8736
	s_waitcnt lgkmcnt(0)
	v_mfma_f32_32x32x16_bf16 v[16:31], v[100:103], v[104:107], v[16:31]
	ds_read_b128 v[104:107], v96 offset:17440
	s_waitcnt lgkmcnt(0)
	v_mfma_f32_32x32x16_bf16 v[32:47], v[100:103], v[104:107], v[32:47]
	ds_read_b128 v[104:107], v96 offset:26144
	v_add_u32_e32 v96, 64, v96
	s_waitcnt lgkmcnt(0)
	v_mfma_f32_32x32x16_bf16 v[48:63], v[100:103], v[104:107], v[48:63]
	s_cbranch_scc1 .LBB0_1107
	s_nop 0
	s_mov_b64 s[0:1], -1
	v_ashrrev_i32_e32 v98, 3, v128
	v_and_b32_e32 v98, -4, v98
	v_and_b32_e32 v103, 31, v128
	v_add_u32_e32 v105, v98, v129
	v_lshlrev_b32_e32 v96, 2, v103
	v_lshl_add_u64 v[98:99], s[56:57], 0, v[96:97]
	v_add_u32_e32 v100, s61, v105
	v_or_b32_e32 v96, 1, v105
	v_or_b32_e32 v102, 2, v105
	s_andn2_b64 vcc, exec, s[54:55]
	v_lshlrev_b32_e32 v237, 2, v105
	v_ashrrev_i32_e32 v101, 31, v100
	v_lshlrev_b32_e32 v236, 2, v96
	v_add_u32_e32 v104, s61, v96
	v_lshlrev_b32_e32 v235, 2, v102
	v_add_u32_e32 v102, s61, v102
	v_or_b32_e32 v234, 3, v105
	s_cbranch_vccnz .LBB0_1110
	s_add_i32 s0, 0, 0x11e00
	s_add_i32 s1, 0, 0x12200
	v_add_u32_e32 v238, s0, v237
	v_add_u32_e32 v239, s1, v237
	ds_read_b32 v96, v238
	ds_read_b32 v105, v239
	v_mov_b32_e32 v110, v0
	v_mov_b32_e32 v111, v16
	v_or_b32_e32 v103, s75, v103
	s_waitcnt lgkmcnt(1)
	v_max_f32_e64 v96, |v96|, |v96|
	s_waitcnt lgkmcnt(0)
	v_max_f32_e32 v96, v96, v105
	v_div_scale_f32 v105, s[6:7], v96, v96, 1.0
	v_rcp_f32_e32 v106, v105
	v_readlane_b32 s6, v249, 7
	v_readlane_b32 s7, v249, 8
	v_readlane_b32 s12, v251, 20
	v_fma_f32 v107, -v105, v106, 1.0
	v_fmac_f32_e32 v106, v107, v106
	v_div_scale_f32 v107, vcc, 1.0, v96, 1.0
	v_mul_f32_e32 v108, v107, v106
	v_fma_f32 v109, -v105, v108, v107
	v_fmac_f32_e32 v108, v109, v106
	v_fma_f32 v105, -v105, v108, v107
	v_div_fmas_f32 v105, v105, v106, v108
	v_lshlrev_b64 v[106:107], 11, v[100:101]
	v_lshl_add_u64 v[106:107], v[98:99], 0, v[106:107]
	global_load_dword v108, v[106:107], off
	global_load_dword v109, v[106:107], off offset:128
	global_load_dword v112, v[106:107], off offset:256
	global_load_dword v113, v[106:107], off offset:384
	v_div_fixup_f32 v96, v105, v96, 1.0
	v_mov_b32_e32 v106, v32
	v_mov_b32_e32 v107, v48
	v_readlane_b32 s18, v251, 26
	v_readlane_b32 s19, v251, 27
	v_readlane_b32 s14, v248, 4
	s_mov_b64 s[16:17], s[82:83]
	s_mov_b32 s25, 0x85000
	s_mov_b32 s23, 0x59000
	s_mov_b32 s22, 0x2d000
	s_mov_b32 s21, 0x84000
	s_mov_b32 s20, 0x58000
	s_movk_i32 s29, 0x47ff
	s_mov_b32 s28, 0x4800000
	v_readlane_b32 s15, v248, 5
	v_readlane_b32 s13, v251, 21
	v_readlane_b32 s24, v251, 32
	v_readlane_b32 s26, v251, 34
	v_readlane_b32 s27, v251, 35
	s_waitcnt vmcnt(2)
	v_pk_fma_f32 v[110:111], v[110:111], v[96:97], v[108:109] op_sel_hi:[1,0,1]
	v_pk_mul_f32 v[108:109], v[110:111], v[110:111]
	s_waitcnt vmcnt(0)
	v_pk_fma_f32 v[124:125], v[106:107], v[96:97], v[112:113] op_sel_hi:[1,0,1]
	v_add_f32_e32 v96, v108, v109
	v_pk_mul_f32 v[106:107], v[124:125], v[124:125]
	v_add_f32_e32 v96, v96, v106
	v_add_f32_e32 v96, v96, v107
	v_mov_b32_e32 v105, v96
	v_mov_b32_e32 v255, v96
	s_nop 1
	v_permlane16_swap_b32_e32 v105, v255
	s_nop 1
	v_mov_b32_dpp v105, v255 quad_perm:[0,1,2,3] row_mask:0x5 bank_mask:0xf
	v_mov_b64_e32 v[106:107], s[6:7]
	v_mad_i64_i32 v[108:109], s[6:7], v100, s74, v[106:107]
	v_lshl_add_u64 v[126:127], v[108:109], 0, s[96:97]
	v_add_f32_e32 v96, v96, v105
	s_nop 1
	v_mov_b32_dpp v105, v96 row_ror:8 row_mask:0xf bank_mask:0xf
	v_lshlrev_b64 v[108:109], 10, v[100:101]
	v_lshl_add_u64 v[112:113], s[66:67], 0, v[108:109]
	v_add_f32_e32 v96, v96, v105
	s_nop 1
	v_mov_b32_dpp v105, v96 row_shl:4 row_mask:0xf bank_mask:0x5
	v_mov_b32_dpp v105, v96 row_shr:4 row_mask:0xf bank_mask:0xa
	s_nop 0
	v_add_f32_e32 v96, v96, v105
	s_nop 1
	v_mov_b32_dpp v105, v96 quad_perm:[2,3,0,1] row_mask:0xf bank_mask:0xf
	v_add_f32_e32 v96, v96, v105
	s_nop 1
	v_add_f32_dpp v96, v96, v96 quad_perm:[1,0,3,2] row_mask:0xf bank_mask:0xf
	v_fmamk_f32 v96, v96, 0x3c000000, v163
	v_cmp_gt_f32_e32 vcc, s86, v96
	v_mul_f32_e32 v105, 0x4b800000, v96
	s_nop 0
	v_cndmask_b32_e32 v96, v96, v105, vcc
	v_rsq_f32_e32 v96, v96
	s_nop 0
	v_mul_f32_e32 v105, 0x45800000, v96
	v_cndmask_b32_e32 v105, v96, v105, vcc
	v_lshlrev_b32_e32 v96, 1, v103
	v_lshl_add_u64 v[108:109], v[126:127], 0, v[96:97]
	global_load_ushort v108, v[108:109], off
	v_mov_b32_e32 v109, v97
	v_mul_f32_e32 v110, v110, v105
	v_lshl_add_u64 v[122:123], v[112:113], 0, v[96:97]
	v_or_b32_e32 v112, 64, v96
	v_mov_b32_e32 v113, v97
	s_waitcnt vmcnt(0)
	v_lshlrev_b32_e32 v108, 16, v108
	v_mul_f32_e32 v108, 0xbfb8aa3b, v108
	v_exp_f32_e32 v108, v108
	s_nop 0
	v_add_f32_e32 v108, 1.0, v108
	v_rcp_f32_e32 v118, v108
	v_or_b32_e32 v108, s34, v103
	v_lshl_add_u64 v[108:109], v[108:109], 2, s[18:19]
	global_load_dword v119, v[108:109], off
	s_waitcnt vmcnt(0)
	v_mul_f32_e32 v110, v119, v110
	v_mul_f32_e32 v110, v118, v110
	v_cvt_pk_bf16_f32 v110, v110, s0
	v_lshl_add_u64 v[118:119], v[126:127], 0, v[112:113]
	global_store_short v[122:123], v110, off
	global_load_ushort v110, v[118:119], off
	v_mul_f32_e32 v119, v111, v105
	v_mov_b32_e32 v111, v97
	s_waitcnt vmcnt(0)
	v_lshlrev_b32_e32 v110, 16, v110
	v_mul_f32_e32 v110, 0xbfb8aa3b, v110
	v_exp_f32_e32 v110, v110
	s_nop 0
	v_add_f32_e32 v110, 1.0, v110
	v_rcp_f32_e32 v118, v110
	v_add_u32_e32 v110, s34, v103
	v_lshl_add_u64 v[110:111], v[110:111], 2, s[18:19]
	global_load_dword v103, v[110:111], off offset:128
	s_mov_b32 s19, 0x2c000
	s_movk_i32 s18, 0x1600
	s_waitcnt vmcnt(0)
	v_mul_f32_e32 v103, v103, v119
	v_mul_f32_e32 v103, v118, v103
	v_or_b32_e32 v118, 0x80, v96
	v_mov_b32_e32 v119, v97
	v_cvt_pk_bf16_f32 v103, v103, s0
	v_lshl_add_u64 v[120:121], v[126:127], 0, v[118:119]
	global_store_short v[122:123], v103, off offset:64
	global_load_ushort v103, v[120:121], off
	v_mul_f32_e32 v120, v124, v105
	global_load_dword v121, v[110:111], off offset:256
	global_load_dword v124, v[110:111], off offset:384
	v_mul_f32_e32 v105, v125, v105
	s_waitcnt vmcnt(2)
	v_lshlrev_b32_e32 v103, 16, v103
	v_mul_f32_e32 v103, 0xbfb8aa3b, v103
	v_exp_f32_e32 v103, v103
	s_waitcnt vmcnt(1)
	v_mul_f32_e32 v120, v121, v120
	v_mov_b32_e32 v121, v97
	s_waitcnt vmcnt(0)
	v_mul_f32_e32 v105, v124, v105
	v_add_f32_e32 v103, 1.0, v103
	v_rcp_f32_e32 v103, v103
	s_nop 0
	v_mul_f32_e32 v103, v120, v103
	v_or_b32_e32 v120, 0xc0, v96
	v_cvt_pk_bf16_f32 v103, v103, s0
	v_lshl_add_u64 v[126:127], v[126:127], 0, v[120:121]
	global_store_short v[122:123], v103, off offset:128
	global_load_ushort v103, v[126:127], off
	s_waitcnt vmcnt(0)
	v_lshlrev_b32_e32 v103, 16, v103
	v_mul_f32_e32 v103, 0xbfb8aa3b, v103
	v_exp_f32_e32 v103, v103
	s_nop 0
	v_add_f32_e32 v103, 1.0, v103
	v_rcp_f32_e32 v103, v103
	s_nop 0
	v_mul_f32_e32 v103, v105, v103
	v_cvt_pk_bf16_f32 v103, v103, s0
	global_store_short v[122:123], v103, off offset:192
	v_add_u32_e32 v103, s0, v236
	v_add_u32_e32 v105, s1, v236
	ds_read_b32 v103, v103
	ds_read_b32 v105, v105
	v_mov_b32_e32 v242, v1
	v_mov_b32_e32 v243, v17
	s_waitcnt lgkmcnt(1)
	v_max_f32_e64 v103, |v103|, |v103|
	s_waitcnt lgkmcnt(0)
	v_max_f32_e32 v103, v103, v105
	v_div_scale_f32 v105, s[6:7], v103, v103, 1.0
	v_rcp_f32_e32 v122, v105
	s_nop 0
	v_fma_f32 v123, -v105, v122, 1.0
	v_fmac_f32_e32 v122, v123, v122
	v_div_scale_f32 v123, vcc, 1.0, v103, 1.0
	v_mul_f32_e32 v124, v123, v122
	v_fma_f32 v125, -v105, v124, v123
	v_fmac_f32_e32 v124, v125, v122
	v_fma_f32 v105, -v105, v124, v123
	v_div_fmas_f32 v105, v105, v122, v124
	v_div_fixup_f32 v122, v105, v103, 1.0
	v_ashrrev_i32_e32 v105, 31, v104
	v_lshlrev_b64 v[124:125], 11, v[104:105]
	v_lshl_add_u64 v[124:125], v[98:99], 0, v[124:125]
	global_load_dword v126, v[124:125], off
	global_load_dword v127, v[124:125], off offset:128
	global_load_dword v244, v[124:125], off offset:256
	global_load_dword v245, v[124:125], off offset:384
	v_mov_b32_e32 v124, v33
	v_mov_b32_e32 v125, v49
	s_waitcnt vmcnt(2)
	v_pk_fma_f32 v[126:127], v[242:243], v[122:123], v[126:127] op_sel_hi:[1,0,1]
	v_pk_mul_f32 v[242:243], v[126:127], v[126:127]
	s_waitcnt vmcnt(0)
	v_pk_fma_f32 v[124:125], v[124:125], v[122:123], v[244:245] op_sel_hi:[1,0,1]
	v_add_f32_e32 v103, v242, v243
	v_pk_mul_f32 v[122:123], v[124:125], v[124:125]
	v_add_f32_e32 v103, v103, v122
	v_add_f32_e32 v103, v103, v123
	v_mov_b32_e32 v122, v103
	v_mov_b32_e32 v255, v103
	s_nop 1
	v_permlane16_swap_b32_e32 v122, v255
	s_nop 1
	v_mov_b32_dpp v122, v255 quad_perm:[0,1,2,3] row_mask:0x5 bank_mask:0xf
	s_nop 0
	v_add_f32_e32 v103, v103, v122
	s_nop 1
	v_mov_b32_dpp v122, v103 row_ror:8 row_mask:0xf bank_mask:0xf
	s_nop 0
	v_add_f32_e32 v103, v103, v122
	s_nop 1
	v_mov_b32_dpp v122, v103 row_shl:4 row_mask:0xf bank_mask:0x5
	v_mov_b32_dpp v122, v103 row_shr:4 row_mask:0xf bank_mask:0xa
	s_nop 0
	v_add_f32_e32 v103, v103, v122
	s_nop 1
	v_mov_b32_dpp v122, v103 quad_perm:[2,3,0,1] row_mask:0xf bank_mask:0xf
	v_add_f32_e32 v103, v103, v122
	s_nop 1
	v_add_f32_dpp v103, v103, v103 quad_perm:[1,0,3,2] row_mask:0xf bank_mask:0xf
	v_fmamk_f32 v103, v103, 0x3c000000, v163
	v_cmp_gt_f32_e32 vcc, s86, v103
	v_mul_f32_e32 v122, 0x4b800000, v103
	s_nop 0
	v_cndmask_b32_e32 v103, v103, v122, vcc
	v_rsq_f32_e32 v103, v103
	s_nop 0
	v_mul_f32_e32 v122, 0x45800000, v103
	v_cndmask_b32_e32 v103, v103, v122, vcc
	v_mad_i64_i32 v[122:123], s[6:7], v104, s74, v[106:107]
	v_lshl_add_u64 v[242:243], v[122:123], 0, s[96:97]
	v_lshl_add_u64 v[244:245], v[242:243], 0, v[96:97]
	v_lshlrev_b64 v[122:123], 10, v[104:105]
	global_load_ushort v105, v[244:245], off
	v_mul_f32_e32 v126, v126, v103
	global_load_dword v244, v[108:109], off
	v_lshl_add_u64 v[122:123], s[66:67], 0, v[122:123]
	v_lshl_add_u64 v[122:123], v[122:123], 0, v[96:97]
	v_mul_f32_e32 v124, v124, v103
	s_waitcnt vmcnt(1)
	v_lshlrev_b32_e32 v105, 16, v105
	v_mul_f32_e32 v105, 0xbfb8aa3b, v105
	v_exp_f32_e32 v105, v105
	s_waitcnt vmcnt(0)
	v_mul_f32_e32 v126, v244, v126
	v_lshl_add_u64 v[244:245], v[242:243], 0, v[112:113]
	v_add_f32_e32 v105, 1.0, v105
	v_rcp_f32_e32 v105, v105
	s_nop 0
	v_mul_f32_e32 v105, v105, v126
	v_cvt_pk_bf16_f32 v105, v105, s0
	global_store_short v[122:123], v105, off
	global_load_ushort v105, v[244:245], off
	v_mul_f32_e32 v126, v127, v103
	global_load_dword v127, v[110:111], off offset:128
	v_mul_f32_e32 v103, v125, v103
	s_waitcnt vmcnt(1)
	v_lshlrev_b32_e32 v105, 16, v105
	v_mul_f32_e32 v105, 0xbfb8aa3b, v105
	v_exp_f32_e32 v105, v105
	s_waitcnt vmcnt(0)
	v_mul_f32_e32 v126, v127, v126
	v_add_f32_e32 v105, 1.0, v105
	v_rcp_f32_e32 v105, v105
	s_nop 0
	v_mul_f32_e32 v105, v105, v126
	v_cvt_pk_bf16_f32 v105, v105, s0
	v_lshl_add_u64 v[126:127], v[242:243], 0, v[118:119]
	global_store_short v[122:123], v105, off offset:64
	global_load_ushort v105, v[126:127], off
	s_waitcnt vmcnt(0)
	v_lshlrev_b32_e32 v105, 16, v105
	global_load_dword v126, v[110:111], off offset:256
	v_mul_f32_e32 v105, 0xbfb8aa3b, v105
	v_exp_f32_e32 v105, v105
	s_waitcnt vmcnt(0)
	v_mul_f32_e32 v124, v126, v124
	v_add_f32_e32 v105, 1.0, v105
	v_rcp_f32_e32 v105, v105
	v_lshl_add_u64 v[126:127], v[242:243], 0, v[120:121]
	v_mul_f32_e32 v105, v124, v105
	v_cvt_pk_bf16_f32 v105, v105, s0
	global_store_short v[122:123], v105, off offset:128
	global_load_ushort v105, v[126:127], off
	s_waitcnt vmcnt(0)
	v_lshlrev_b32_e32 v105, 16, v105
	global_load_dword v124, v[110:111], off offset:384
	v_mul_f32_e32 v105, 0xbfb8aa3b, v105
	v_exp_f32_e32 v105, v105
	s_waitcnt vmcnt(0)
	v_mul_f32_e32 v103, v124, v103
	v_add_f32_e32 v105, 1.0, v105
	v_rcp_f32_e32 v105, v105
	s_nop 0
	v_mul_f32_e32 v103, v103, v105
	v_cvt_pk_bf16_f32 v103, v103, s0
	global_store_short v[122:123], v103, off offset:192
	v_add_u32_e32 v103, s0, v235
	v_add_u32_e32 v105, s1, v235
	ds_read_b32 v103, v103
	ds_read_b32 v105, v105
	v_mov_b32_e32 v242, v2
	v_mov_b32_e32 v243, v18
	s_waitcnt lgkmcnt(1)
	v_max_f32_e64 v103, |v103|, |v103|
	s_waitcnt lgkmcnt(0)
	v_max_f32_e32 v103, v103, v105
	v_div_scale_f32 v105, s[6:7], v103, v103, 1.0
	v_rcp_f32_e32 v122, v105
	s_nop 0
	v_fma_f32 v123, -v105, v122, 1.0
	v_fmac_f32_e32 v122, v123, v122
	v_div_scale_f32 v123, vcc, 1.0, v103, 1.0
	v_mul_f32_e32 v124, v123, v122
	v_fma_f32 v125, -v105, v124, v123
	v_fmac_f32_e32 v124, v125, v122
	v_fma_f32 v105, -v105, v124, v123
	v_div_fmas_f32 v105, v105, v122, v124
	v_div_fixup_f32 v122, v105, v103, 1.0
	v_ashrrev_i32_e32 v103, 31, v102
	v_lshlrev_b64 v[124:125], 11, v[102:103]
	v_lshl_add_u64 v[124:125], v[98:99], 0, v[124:125]
	global_load_dword v126, v[124:125], off
	global_load_dword v127, v[124:125], off offset:128
	global_load_dword v244, v[124:125], off offset:256
	global_load_dword v245, v[124:125], off offset:384
	v_mov_b32_e32 v124, v34
	v_mov_b32_e32 v125, v50
	s_waitcnt vmcnt(2)
	v_pk_fma_f32 v[126:127], v[242:243], v[122:123], v[126:127] op_sel_hi:[1,0,1]
	v_pk_mul_f32 v[242:243], v[126:127], v[126:127]
	s_waitcnt vmcnt(0)
	v_pk_fma_f32 v[124:125], v[124:125], v[122:123], v[244:245] op_sel_hi:[1,0,1]
	v_add_f32_e32 v105, v242, v243
	v_pk_mul_f32 v[122:123], v[124:125], v[124:125]
	v_add_f32_e32 v105, v105, v122
	v_add_f32_e32 v105, v105, v123
	v_mov_b32_e32 v122, v105
	v_mov_b32_e32 v255, v105
	s_nop 1
	v_permlane16_swap_b32_e32 v122, v255
	s_nop 1
	v_mov_b32_dpp v122, v255 quad_perm:[0,1,2,3] row_mask:0x5 bank_mask:0xf
	s_nop 0
	v_add_f32_e32 v105, v105, v122
	s_nop 1
	v_mov_b32_dpp v122, v105 row_ror:8 row_mask:0xf bank_mask:0xf
	s_nop 0
	v_add_f32_e32 v105, v105, v122
	s_nop 1
	v_mov_b32_dpp v122, v105 row_shl:4 row_mask:0xf bank_mask:0x5
	v_mov_b32_dpp v122, v105 row_shr:4 row_mask:0xf bank_mask:0xa
	s_nop 0
	v_add_f32_e32 v105, v105, v122
	s_nop 1
	v_mov_b32_dpp v122, v105 quad_perm:[2,3,0,1] row_mask:0xf bank_mask:0xf
	v_add_f32_e32 v105, v105, v122
	s_nop 1
	v_add_f32_dpp v105, v105, v105 quad_perm:[1,0,3,2] row_mask:0xf bank_mask:0xf
	v_fmamk_f32 v105, v105, 0x3c000000, v163
	v_cmp_gt_f32_e32 vcc, s86, v105
	v_mul_f32_e32 v122, 0x4b800000, v105
	s_nop 0
	v_cndmask_b32_e32 v105, v105, v122, vcc
	v_rsq_f32_e32 v105, v105
	s_nop 0
	v_mul_f32_e32 v122, 0x45800000, v105
	v_cndmask_b32_e32 v105, v105, v122, vcc
	v_mad_i64_i32 v[122:123], s[6:7], v102, s74, v[106:107]
	v_lshl_add_u64 v[242:243], v[122:123], 0, s[96:97]
	v_lshl_add_u64 v[244:245], v[242:243], 0, v[96:97]
	v_lshlrev_b64 v[122:123], 10, v[102:103]
	global_load_ushort v103, v[244:245], off
	v_mul_f32_e32 v126, v126, v105
	global_load_dword v244, v[108:109], off
	v_lshl_add_u64 v[122:123], s[66:67], 0, v[122:123]
	v_lshl_add_u64 v[122:123], v[122:123], 0, v[96:97]
	v_mul_f32_e32 v124, v124, v105
	s_waitcnt vmcnt(1)
	v_lshlrev_b32_e32 v103, 16, v103
	v_mul_f32_e32 v103, 0xbfb8aa3b, v103
	v_exp_f32_e32 v103, v103
	s_waitcnt vmcnt(0)
	v_mul_f32_e32 v126, v244, v126
	v_lshl_add_u64 v[244:245], v[242:243], 0, v[112:113]
	v_add_f32_e32 v103, 1.0, v103
	v_rcp_f32_e32 v103, v103
	s_nop 0
	v_mul_f32_e32 v103, v103, v126
	v_cvt_pk_bf16_f32 v103, v103, s0
	global_store_short v[122:123], v103, off
	global_load_ushort v103, v[244:245], off
	v_mul_f32_e32 v126, v127, v105
	global_load_dword v127, v[110:111], off offset:128
	v_mul_f32_e32 v105, v125, v105
	s_waitcnt vmcnt(1)
	v_lshlrev_b32_e32 v103, 16, v103
	v_mul_f32_e32 v103, 0xbfb8aa3b, v103
	v_exp_f32_e32 v103, v103
	s_waitcnt vmcnt(0)
	v_mul_f32_e32 v126, v127, v126
	v_add_f32_e32 v103, 1.0, v103
	v_rcp_f32_e32 v103, v103
	s_nop 0
	v_mul_f32_e32 v103, v103, v126
	v_cvt_pk_bf16_f32 v103, v103, s0
	v_lshl_add_u64 v[126:127], v[242:243], 0, v[118:119]
	global_store_short v[122:123], v103, off offset:64
	global_load_ushort v103, v[126:127], off
	s_waitcnt vmcnt(0)
	v_lshlrev_b32_e32 v103, 16, v103
	global_load_dword v126, v[110:111], off offset:256
	v_mul_f32_e32 v103, 0xbfb8aa3b, v103
	v_exp_f32_e32 v103, v103
	s_waitcnt vmcnt(0)
	v_mul_f32_e32 v124, v126, v124
	v_add_f32_e32 v103, 1.0, v103
	v_rcp_f32_e32 v103, v103
	v_lshl_add_u64 v[126:127], v[242:243], 0, v[120:121]
	v_mul_f32_e32 v103, v124, v103
	v_cvt_pk_bf16_f32 v103, v103, s0
	global_store_short v[122:123], v103, off offset:128
	global_load_ushort v103, v[126:127], off
	s_waitcnt vmcnt(0)
	v_lshlrev_b32_e32 v103, 16, v103
	global_load_dword v124, v[110:111], off offset:384
	v_mul_f32_e32 v103, 0xbfb8aa3b, v103
	v_exp_f32_e32 v103, v103
	s_waitcnt vmcnt(0)
	v_mul_f32_e32 v105, v124, v105
	v_add_f32_e32 v103, 1.0, v103
	v_rcp_f32_e32 v103, v103
	s_nop 0
	v_mul_f32_e32 v103, v105, v103
	v_cvt_pk_bf16_f32 v103, v103, s0
	global_store_short v[122:123], v103, off offset:192
	v_lshlrev_b32_e32 v103, 2, v234
	v_add_u32_e32 v105, s0, v103
	v_add_u32_e32 v103, s1, v103
	ds_read_b32 v105, v105
	ds_read_b32 v103, v103
	v_add_u32_e32 v126, s61, v234
	v_ashrrev_i32_e32 v127, 31, v126
	v_mov_b32_e32 v244, v3
	s_waitcnt lgkmcnt(1)
	v_max_f32_e64 v105, |v105|, |v105|
	s_waitcnt lgkmcnt(0)
	v_max_f32_e32 v103, v105, v103
	v_div_scale_f32 v105, s[0:1], v103, v103, 1.0
	v_rcp_f32_e32 v122, v105
	v_mov_b32_e32 v245, v19
	v_fma_f32 v123, -v105, v122, 1.0
	v_fmac_f32_e32 v122, v123, v122
	v_div_scale_f32 v123, vcc, 1.0, v103, 1.0
	v_mul_f32_e32 v124, v123, v122
	v_fma_f32 v125, -v105, v124, v123
	v_fmac_f32_e32 v124, v125, v122
	v_fma_f32 v105, -v105, v124, v123
	v_div_fmas_f32 v105, v105, v122, v124
	v_lshlrev_b64 v[124:125], 11, v[126:127]
	v_lshl_add_u64 v[124:125], v[98:99], 0, v[124:125]
	global_load_dword v242, v[124:125], off
	global_load_dword v243, v[124:125], off offset:128
	global_load_dword v246, v[124:125], off offset:256
	global_load_dword v247, v[124:125], off offset:384
	v_div_fixup_f32 v122, v105, v103, 1.0
	v_mov_b32_e32 v124, v35
	v_mov_b32_e32 v125, v51
	s_waitcnt vmcnt(2)
	v_pk_fma_f32 v[242:243], v[244:245], v[122:123], v[242:243] op_sel_hi:[1,0,1]
	v_pk_mul_f32 v[244:245], v[242:243], v[242:243]
	s_waitcnt vmcnt(0)
	v_pk_fma_f32 v[124:125], v[124:125], v[122:123], v[246:247] op_sel_hi:[1,0,1]
	v_add_f32_e32 v103, v244, v245
	v_pk_mul_f32 v[122:123], v[124:125], v[124:125]
	v_add_f32_e32 v103, v103, v122
	v_add_f32_e32 v103, v103, v123
	v_mov_b32_e32 v105, v103
	v_mov_b32_e32 v255, v103
	s_nop 1
	v_permlane16_swap_b32_e32 v105, v255
	s_nop 1
	v_mov_b32_dpp v105, v255 quad_perm:[0,1,2,3] row_mask:0x5 bank_mask:0xf
	v_mad_i64_i32 v[122:123], s[0:1], v126, s74, v[106:107]
	v_lshl_add_u64 v[244:245], v[122:123], 0, s[96:97]
	v_lshlrev_b64 v[122:123], 10, v[126:127]
	v_add_f32_e32 v103, v103, v105
	s_nop 1
	v_mov_b32_dpp v105, v103 row_ror:8 row_mask:0xf bank_mask:0xf
	v_lshl_add_u64 v[126:127], v[244:245], 0, v[96:97]
	v_lshl_add_u64 v[122:123], s[66:67], 0, v[122:123]
	v_lshl_add_u64 v[122:123], v[122:123], 0, v[96:97]
	v_add_f32_e32 v103, v103, v105
	s_nop 1
	v_mov_b32_dpp v105, v103 row_shl:4 row_mask:0xf bank_mask:0x5
	v_mov_b32_dpp v105, v103 row_shr:4 row_mask:0xf bank_mask:0xa
	s_nop 0
	v_add_f32_e32 v103, v103, v105
	s_nop 1
	v_mov_b32_dpp v105, v103 quad_perm:[2,3,0,1] row_mask:0xf bank_mask:0xf
	v_add_f32_e32 v103, v103, v105
	s_nop 1
	v_add_f32_dpp v103, v103, v103 quad_perm:[1,0,3,2] row_mask:0xf bank_mask:0xf
	v_fmamk_f32 v103, v103, 0x3c000000, v163
	v_cmp_gt_f32_e32 vcc, s86, v103
	v_mul_f32_e32 v105, 0x4b800000, v103
	s_nop 0
	v_cndmask_b32_e32 v103, v103, v105, vcc
	v_rsq_f32_e32 v103, v103
	s_nop 0
	v_mul_f32_e32 v105, 0x45800000, v103
	v_cndmask_b32_e32 v103, v103, v105, vcc
	global_load_ushort v105, v[126:127], off
	v_mul_f32_e32 v126, v242, v103
	global_load_dword v127, v[108:109], off
	v_mul_f32_e32 v124, v124, v103
	s_waitcnt vmcnt(1)
	v_lshlrev_b32_e32 v105, 16, v105
	v_mul_f32_e32 v105, 0xbfb8aa3b, v105
	v_exp_f32_e32 v105, v105
	s_waitcnt vmcnt(0)
	v_mul_f32_e32 v126, v127, v126
	v_add_f32_e32 v105, 1.0, v105
	v_rcp_f32_e32 v105, v105
	s_nop 0
	v_mul_f32_e32 v105, v105, v126
	v_cvt_pk_bf16_f32 v105, v105, s0
	v_lshl_add_u64 v[126:127], v[244:245], 0, v[112:113]
	global_store_short v[122:123], v105, off
	global_load_ushort v105, v[126:127], off
	v_mul_f32_e32 v126, v243, v103
	global_load_dword v127, v[110:111], off offset:128
	v_mul_f32_e32 v103, v125, v103
	s_waitcnt vmcnt(1)
	v_lshlrev_b32_e32 v105, 16, v105
	v_mul_f32_e32 v105, 0xbfb8aa3b, v105
	v_exp_f32_e32 v105, v105
	s_waitcnt vmcnt(0)
	v_mul_f32_e32 v126, v127, v126
	v_add_f32_e32 v105, 1.0, v105
	v_rcp_f32_e32 v105, v105
	s_nop 0
	v_mul_f32_e32 v105, v105, v126
	v_cvt_pk_bf16_f32 v105, v105, s0
	v_lshl_add_u64 v[126:127], v[244:245], 0, v[118:119]
	global_store_short v[122:123], v105, off offset:64
	global_load_ushort v105, v[126:127], off
	s_waitcnt vmcnt(0)
	v_lshlrev_b32_e32 v105, 16, v105
	global_load_dword v126, v[110:111], off offset:256
	v_mul_f32_e32 v105, 0xbfb8aa3b, v105
	v_exp_f32_e32 v105, v105
	s_waitcnt vmcnt(0)
	v_mul_f32_e32 v124, v126, v124
	v_add_f32_e32 v105, 1.0, v105
	v_rcp_f32_e32 v105, v105
	v_lshl_add_u64 v[126:127], v[244:245], 0, v[120:121]
	v_mul_f32_e32 v105, v124, v105
	v_cvt_pk_bf16_f32 v105, v105, s0
	global_store_short v[122:123], v105, off offset:128
	global_load_ushort v105, v[126:127], off
	s_waitcnt vmcnt(0)
	v_lshlrev_b32_e32 v105, 16, v105
	global_load_dword v124, v[110:111], off offset:384
	v_mul_f32_e32 v105, 0xbfb8aa3b, v105
	v_exp_f32_e32 v105, v105
	s_waitcnt vmcnt(0)
	v_mul_f32_e32 v103, v124, v103
	v_add_f32_e32 v105, 1.0, v105
	v_rcp_f32_e32 v105, v105
	s_nop 0
	v_mul_f32_e32 v103, v103, v105
	v_cvt_pk_bf16_f32 v103, v103, s0
	global_store_short v[122:123], v103, off offset:192
	ds_read_b32 v103, v238 offset:32
	ds_read_b32 v105, v239 offset:32
	v_add_u32_e32 v126, 8, v100
	v_ashrrev_i32_e32 v127, 31, v126
	v_mov_b32_e32 v244, v4
	s_waitcnt lgkmcnt(1)
	v_max_f32_e64 v103, |v103|, |v103|
	s_waitcnt lgkmcnt(0)
	v_max_f32_e32 v103, v103, v105
	v_div_scale_f32 v105, s[0:1], v103, v103, 1.0
	v_rcp_f32_e32 v122, v105
	v_mov_b32_e32 v245, v20
	v_fma_f32 v123, -v105, v122, 1.0
	v_fmac_f32_e32 v122, v123, v122
	v_div_scale_f32 v123, vcc, 1.0, v103, 1.0
	v_mul_f32_e32 v124, v123, v122
	v_fma_f32 v125, -v105, v124, v123
	v_fmac_f32_e32 v124, v125, v122
	v_fma_f32 v105, -v105, v124, v123
	v_div_fmas_f32 v105, v105, v122, v124
	v_lshlrev_b64 v[124:125], 11, v[126:127]
	v_lshl_add_u64 v[124:125], v[98:99], 0, v[124:125]
	global_load_dword v242, v[124:125], off
	global_load_dword v243, v[124:125], off offset:128
	global_load_dword v246, v[124:125], off offset:256
	global_load_dword v247, v[124:125], off offset:384
	v_div_fixup_f32 v122, v105, v103, 1.0
	v_mov_b32_e32 v124, v36
	v_mov_b32_e32 v125, v52
	s_waitcnt vmcnt(2)
	v_pk_fma_f32 v[242:243], v[244:245], v[122:123], v[242:243] op_sel_hi:[1,0,1]
	v_pk_mul_f32 v[244:245], v[242:243], v[242:243]
	s_waitcnt vmcnt(0)
	v_pk_fma_f32 v[124:125], v[124:125], v[122:123], v[246:247] op_sel_hi:[1,0,1]
	v_add_f32_e32 v103, v244, v245
	v_pk_mul_f32 v[122:123], v[124:125], v[124:125]
	v_add_f32_e32 v103, v103, v122
	v_add_f32_e32 v103, v103, v123
	v_mov_b32_e32 v105, v103
	v_mov_b32_e32 v255, v103
	s_nop 1
	v_permlane16_swap_b32_e32 v105, v255
	s_nop 1
	v_mov_b32_dpp v105, v255 quad_perm:[0,1,2,3] row_mask:0x5 bank_mask:0xf
	v_mad_i64_i32 v[122:123], s[0:1], v126, s74, v[106:107]
	v_lshl_add_u64 v[244:245], v[122:123], 0, s[96:97]
	v_lshlrev_b64 v[122:123], 10, v[126:127]
	v_add_f32_e32 v103, v103, v105
	s_nop 1
	v_mov_b32_dpp v105, v103 row_ror:8 row_mask:0xf bank_mask:0xf
	v_lshl_add_u64 v[126:127], v[244:245], 0, v[96:97]
	v_lshl_add_u64 v[122:123], s[66:67], 0, v[122:123]
	v_lshl_add_u64 v[122:123], v[122:123], 0, v[96:97]
	v_add_f32_e32 v103, v103, v105
	s_nop 1
	v_mov_b32_dpp v105, v103 row_shl:4 row_mask:0xf bank_mask:0x5
	v_mov_b32_dpp v105, v103 row_shr:4 row_mask:0xf bank_mask:0xa
	s_nop 0
	v_add_f32_e32 v103, v103, v105
	s_nop 1
	v_mov_b32_dpp v105, v103 quad_perm:[2,3,0,1] row_mask:0xf bank_mask:0xf
	v_add_f32_e32 v103, v103, v105
	s_nop 1
	v_add_f32_dpp v103, v103, v103 quad_perm:[1,0,3,2] row_mask:0xf bank_mask:0xf
	v_fmamk_f32 v103, v103, 0x3c000000, v163
	v_cmp_gt_f32_e32 vcc, s86, v103
	v_mul_f32_e32 v105, 0x4b800000, v103
	s_nop 0
	v_cndmask_b32_e32 v103, v103, v105, vcc
	v_rsq_f32_e32 v103, v103
	s_nop 0
	v_mul_f32_e32 v105, 0x45800000, v103
	v_cndmask_b32_e32 v103, v103, v105, vcc
	global_load_ushort v105, v[126:127], off
	v_mul_f32_e32 v126, v242, v103
	global_load_dword v127, v[108:109], off
	v_mul_f32_e32 v124, v124, v103
	s_waitcnt vmcnt(1)
	v_lshlrev_b32_e32 v105, 16, v105
	v_mul_f32_e32 v105, 0xbfb8aa3b, v105
	v_exp_f32_e32 v105, v105
	s_waitcnt vmcnt(0)
	v_mul_f32_e32 v126, v127, v126
	v_add_f32_e32 v105, 1.0, v105
	v_rcp_f32_e32 v105, v105
	s_nop 0
	v_mul_f32_e32 v105, v105, v126
	v_cvt_pk_bf16_f32 v105, v105, s0
	v_lshl_add_u64 v[126:127], v[244:245], 0, v[112:113]
	global_store_short v[122:123], v105, off
	global_load_ushort v105, v[126:127], off
	v_mul_f32_e32 v126, v243, v103
	global_load_dword v127, v[110:111], off offset:128
	v_mul_f32_e32 v103, v125, v103
	s_waitcnt vmcnt(1)
	v_lshlrev_b32_e32 v105, 16, v105
	v_mul_f32_e32 v105, 0xbfb8aa3b, v105
	v_exp_f32_e32 v105, v105
	s_waitcnt vmcnt(0)
	v_mul_f32_e32 v126, v127, v126
	v_add_f32_e32 v105, 1.0, v105
	v_rcp_f32_e32 v105, v105
	s_nop 0
	v_mul_f32_e32 v105, v105, v126
	v_cvt_pk_bf16_f32 v105, v105, s0
	v_lshl_add_u64 v[126:127], v[244:245], 0, v[118:119]
	global_store_short v[122:123], v105, off offset:64
	global_load_ushort v105, v[126:127], off
	s_waitcnt vmcnt(0)
	v_lshlrev_b32_e32 v105, 16, v105
	global_load_dword v126, v[110:111], off offset:256
	v_mul_f32_e32 v105, 0xbfb8aa3b, v105
	v_exp_f32_e32 v105, v105
	s_waitcnt vmcnt(0)
	v_mul_f32_e32 v124, v126, v124
	v_add_f32_e32 v105, 1.0, v105
	v_rcp_f32_e32 v105, v105
	v_lshl_add_u64 v[126:127], v[244:245], 0, v[120:121]
	v_mul_f32_e32 v105, v124, v105
	v_cvt_pk_bf16_f32 v105, v105, s0
	global_store_short v[122:123], v105, off offset:128
	global_load_ushort v105, v[126:127], off
	s_waitcnt vmcnt(0)
	v_lshlrev_b32_e32 v105, 16, v105
	global_load_dword v124, v[110:111], off offset:384
	v_mul_f32_e32 v105, 0xbfb8aa3b, v105
	v_exp_f32_e32 v105, v105
	s_waitcnt vmcnt(0)
	v_mul_f32_e32 v103, v124, v103
	v_add_f32_e32 v105, 1.0, v105
	v_rcp_f32_e32 v105, v105
	s_nop 0
	v_mul_f32_e32 v103, v103, v105
	v_cvt_pk_bf16_f32 v103, v103, s0
	global_store_short v[122:123], v103, off offset:192
	ds_read_b32 v103, v238 offset:36
	ds_read_b32 v105, v239 offset:36
	v_add_u32_e32 v126, 9, v100
	v_ashrrev_i32_e32 v127, 31, v126
	v_mov_b32_e32 v244, v5
	s_waitcnt lgkmcnt(1)
	v_max_f32_e64 v103, |v103|, |v103|
	s_waitcnt lgkmcnt(0)
	v_max_f32_e32 v103, v103, v105
	v_div_scale_f32 v105, s[0:1], v103, v103, 1.0
	v_rcp_f32_e32 v122, v105
	v_mov_b32_e32 v245, v21
	v_fma_f32 v123, -v105, v122, 1.0
	v_fmac_f32_e32 v122, v123, v122
	v_div_scale_f32 v123, vcc, 1.0, v103, 1.0
	v_mul_f32_e32 v124, v123, v122
	v_fma_f32 v125, -v105, v124, v123
	v_fmac_f32_e32 v124, v125, v122
	v_fma_f32 v105, -v105, v124, v123
	v_div_fmas_f32 v105, v105, v122, v124
	v_lshlrev_b64 v[124:125], 11, v[126:127]
	v_lshl_add_u64 v[124:125], v[98:99], 0, v[124:125]
	global_load_dword v242, v[124:125], off
	global_load_dword v243, v[124:125], off offset:128
	global_load_dword v246, v[124:125], off offset:256
	global_load_dword v247, v[124:125], off offset:384
	v_div_fixup_f32 v122, v105, v103, 1.0
	v_mov_b32_e32 v124, v37
	v_mov_b32_e32 v125, v53
	s_waitcnt vmcnt(2)
	v_pk_fma_f32 v[242:243], v[244:245], v[122:123], v[242:243] op_sel_hi:[1,0,1]
	v_pk_mul_f32 v[244:245], v[242:243], v[242:243]
	s_waitcnt vmcnt(0)
	v_pk_fma_f32 v[124:125], v[124:125], v[122:123], v[246:247] op_sel_hi:[1,0,1]
	v_add_f32_e32 v103, v244, v245
	v_pk_mul_f32 v[122:123], v[124:125], v[124:125]
	v_add_f32_e32 v103, v103, v122
	v_add_f32_e32 v103, v103, v123
	v_mov_b32_e32 v105, v103
	v_mov_b32_e32 v255, v103
	s_nop 1
	v_permlane16_swap_b32_e32 v105, v255
	s_nop 1
	v_mov_b32_dpp v105, v255 quad_perm:[0,1,2,3] row_mask:0x5 bank_mask:0xf
	v_mad_i64_i32 v[122:123], s[0:1], v126, s74, v[106:107]
	v_lshl_add_u64 v[244:245], v[122:123], 0, s[96:97]
	v_lshlrev_b64 v[122:123], 10, v[126:127]
	v_add_f32_e32 v103, v103, v105
	s_nop 1
	v_mov_b32_dpp v105, v103 row_ror:8 row_mask:0xf bank_mask:0xf
	v_lshl_add_u64 v[126:127], v[244:245], 0, v[96:97]
	v_lshl_add_u64 v[122:123], s[66:67], 0, v[122:123]
	v_lshl_add_u64 v[122:123], v[122:123], 0, v[96:97]
	v_add_f32_e32 v103, v103, v105
	s_nop 1
	v_mov_b32_dpp v105, v103 row_shl:4 row_mask:0xf bank_mask:0x5
	v_mov_b32_dpp v105, v103 row_shr:4 row_mask:0xf bank_mask:0xa
	s_nop 0
	v_add_f32_e32 v103, v103, v105
	s_nop 1
	v_mov_b32_dpp v105, v103 quad_perm:[2,3,0,1] row_mask:0xf bank_mask:0xf
	v_add_f32_e32 v103, v103, v105
	s_nop 1
	v_add_f32_dpp v103, v103, v103 quad_perm:[1,0,3,2] row_mask:0xf bank_mask:0xf
	v_fmamk_f32 v103, v103, 0x3c000000, v163
	v_cmp_gt_f32_e32 vcc, s86, v103
	v_mul_f32_e32 v105, 0x4b800000, v103
	s_nop 0
	v_cndmask_b32_e32 v103, v103, v105, vcc
	v_rsq_f32_e32 v103, v103
	s_nop 0
	v_mul_f32_e32 v105, 0x45800000, v103
	v_cndmask_b32_e32 v103, v103, v105, vcc
	global_load_ushort v105, v[126:127], off
	v_mul_f32_e32 v126, v242, v103
	global_load_dword v127, v[108:109], off
	v_mul_f32_e32 v124, v124, v103
	s_waitcnt vmcnt(1)
	v_lshlrev_b32_e32 v105, 16, v105
	v_mul_f32_e32 v105, 0xbfb8aa3b, v105
	v_exp_f32_e32 v105, v105
	s_waitcnt vmcnt(0)
	v_mul_f32_e32 v126, v127, v126
	v_add_f32_e32 v105, 1.0, v105
	v_rcp_f32_e32 v105, v105
	s_nop 0
	v_mul_f32_e32 v105, v105, v126
	v_cvt_pk_bf16_f32 v105, v105, s0
	v_lshl_add_u64 v[126:127], v[244:245], 0, v[112:113]
	global_store_short v[122:123], v105, off
	global_load_ushort v105, v[126:127], off
	v_mul_f32_e32 v126, v243, v103
	global_load_dword v127, v[110:111], off offset:128
	v_mul_f32_e32 v103, v125, v103
	s_waitcnt vmcnt(1)
	v_lshlrev_b32_e32 v105, 16, v105
	v_mul_f32_e32 v105, 0xbfb8aa3b, v105
	v_exp_f32_e32 v105, v105
	s_waitcnt vmcnt(0)
	v_mul_f32_e32 v126, v127, v126
	v_add_f32_e32 v105, 1.0, v105
	v_rcp_f32_e32 v105, v105
	s_nop 0
	v_mul_f32_e32 v105, v105, v126
	v_cvt_pk_bf16_f32 v105, v105, s0
	v_lshl_add_u64 v[126:127], v[244:245], 0, v[118:119]
	global_store_short v[122:123], v105, off offset:64
	global_load_ushort v105, v[126:127], off
	s_waitcnt vmcnt(0)
	v_lshlrev_b32_e32 v105, 16, v105
	global_load_dword v126, v[110:111], off offset:256
	v_mul_f32_e32 v105, 0xbfb8aa3b, v105
	v_exp_f32_e32 v105, v105
	s_waitcnt vmcnt(0)
	v_mul_f32_e32 v124, v126, v124
	v_add_f32_e32 v105, 1.0, v105
	v_rcp_f32_e32 v105, v105
	v_lshl_add_u64 v[126:127], v[244:245], 0, v[120:121]
	v_mul_f32_e32 v105, v124, v105
	v_cvt_pk_bf16_f32 v105, v105, s0
	global_store_short v[122:123], v105, off offset:128
	global_load_ushort v105, v[126:127], off
	s_waitcnt vmcnt(0)
	v_lshlrev_b32_e32 v105, 16, v105
	global_load_dword v124, v[110:111], off offset:384
	v_mul_f32_e32 v105, 0xbfb8aa3b, v105
	v_exp_f32_e32 v105, v105
	s_waitcnt vmcnt(0)
	v_mul_f32_e32 v103, v124, v103
	v_add_f32_e32 v105, 1.0, v105
	v_rcp_f32_e32 v105, v105
	s_nop 0
	v_mul_f32_e32 v103, v103, v105
	v_cvt_pk_bf16_f32 v103, v103, s0
	global_store_short v[122:123], v103, off offset:192
	ds_read_b32 v103, v238 offset:40
	ds_read_b32 v105, v239 offset:40
	v_add_u32_e32 v126, 10, v100
	v_ashrrev_i32_e32 v127, 31, v126
	v_mov_b32_e32 v244, v6
	s_waitcnt lgkmcnt(1)
	v_max_f32_e64 v103, |v103|, |v103|
	s_waitcnt lgkmcnt(0)
	v_max_f32_e32 v103, v103, v105
	v_div_scale_f32 v105, s[0:1], v103, v103, 1.0
	v_rcp_f32_e32 v122, v105
	v_mov_b32_e32 v245, v22
	v_fma_f32 v123, -v105, v122, 1.0
	v_fmac_f32_e32 v122, v123, v122
	v_div_scale_f32 v123, vcc, 1.0, v103, 1.0
	v_mul_f32_e32 v124, v123, v122
	v_fma_f32 v125, -v105, v124, v123
	v_fmac_f32_e32 v124, v125, v122
	v_fma_f32 v105, -v105, v124, v123
	v_div_fmas_f32 v105, v105, v122, v124
	v_lshlrev_b64 v[124:125], 11, v[126:127]
	v_lshl_add_u64 v[124:125], v[98:99], 0, v[124:125]
	global_load_dword v242, v[124:125], off
	global_load_dword v243, v[124:125], off offset:128
	global_load_dword v246, v[124:125], off offset:256
	global_load_dword v247, v[124:125], off offset:384
	v_div_fixup_f32 v122, v105, v103, 1.0
	v_mov_b32_e32 v124, v38
	v_mov_b32_e32 v125, v54
	s_waitcnt vmcnt(2)
	v_pk_fma_f32 v[242:243], v[244:245], v[122:123], v[242:243] op_sel_hi:[1,0,1]
	v_pk_mul_f32 v[244:245], v[242:243], v[242:243]
	s_waitcnt vmcnt(0)
	v_pk_fma_f32 v[124:125], v[124:125], v[122:123], v[246:247] op_sel_hi:[1,0,1]
	v_add_f32_e32 v103, v244, v245
	v_pk_mul_f32 v[122:123], v[124:125], v[124:125]
	v_add_f32_e32 v103, v103, v122
	v_add_f32_e32 v103, v103, v123
	v_mov_b32_e32 v105, v103
	v_mov_b32_e32 v255, v103
	s_nop 1
	v_permlane16_swap_b32_e32 v105, v255
	s_nop 1
	v_mov_b32_dpp v105, v255 quad_perm:[0,1,2,3] row_mask:0x5 bank_mask:0xf
	v_mad_i64_i32 v[122:123], s[0:1], v126, s74, v[106:107]
	v_lshl_add_u64 v[244:245], v[122:123], 0, s[96:97]
	v_lshlrev_b64 v[122:123], 10, v[126:127]
	v_add_f32_e32 v103, v103, v105
	s_nop 1
	v_mov_b32_dpp v105, v103 row_ror:8 row_mask:0xf bank_mask:0xf
	v_lshl_add_u64 v[126:127], v[244:245], 0, v[96:97]
	v_lshl_add_u64 v[122:123], s[66:67], 0, v[122:123]
	v_lshl_add_u64 v[122:123], v[122:123], 0, v[96:97]
	v_add_f32_e32 v103, v103, v105
	s_nop 1
	v_mov_b32_dpp v105, v103 row_shl:4 row_mask:0xf bank_mask:0x5
	v_mov_b32_dpp v105, v103 row_shr:4 row_mask:0xf bank_mask:0xa
	s_nop 0
	v_add_f32_e32 v103, v103, v105
	s_nop 1
	v_mov_b32_dpp v105, v103 quad_perm:[2,3,0,1] row_mask:0xf bank_mask:0xf
	v_add_f32_e32 v103, v103, v105
	s_nop 1
	v_add_f32_dpp v103, v103, v103 quad_perm:[1,0,3,2] row_mask:0xf bank_mask:0xf
	v_fmamk_f32 v103, v103, 0x3c000000, v163
	v_cmp_gt_f32_e32 vcc, s86, v103
	v_mul_f32_e32 v105, 0x4b800000, v103
	s_nop 0
	v_cndmask_b32_e32 v103, v103, v105, vcc
	v_rsq_f32_e32 v103, v103
	s_nop 0
	v_mul_f32_e32 v105, 0x45800000, v103
	v_cndmask_b32_e32 v103, v103, v105, vcc
	global_load_ushort v105, v[126:127], off
	v_mul_f32_e32 v126, v242, v103
	global_load_dword v127, v[108:109], off
	v_mul_f32_e32 v124, v124, v103
	s_waitcnt vmcnt(1)
	v_lshlrev_b32_e32 v105, 16, v105
	v_mul_f32_e32 v105, 0xbfb8aa3b, v105
	v_exp_f32_e32 v105, v105
	s_waitcnt vmcnt(0)
	v_mul_f32_e32 v126, v127, v126
	v_add_f32_e32 v105, 1.0, v105
	v_rcp_f32_e32 v105, v105
	s_nop 0
	v_mul_f32_e32 v105, v105, v126
	v_cvt_pk_bf16_f32 v105, v105, s0
	v_lshl_add_u64 v[126:127], v[244:245], 0, v[112:113]
	global_store_short v[122:123], v105, off
	global_load_ushort v105, v[126:127], off
	v_mul_f32_e32 v126, v243, v103
	global_load_dword v127, v[110:111], off offset:128
	v_mul_f32_e32 v103, v125, v103
	s_waitcnt vmcnt(1)
	v_lshlrev_b32_e32 v105, 16, v105
	v_mul_f32_e32 v105, 0xbfb8aa3b, v105
	v_exp_f32_e32 v105, v105
	s_waitcnt vmcnt(0)
	v_mul_f32_e32 v126, v127, v126
	v_add_f32_e32 v105, 1.0, v105
	v_rcp_f32_e32 v105, v105
	s_nop 0
	v_mul_f32_e32 v105, v105, v126
	v_cvt_pk_bf16_f32 v105, v105, s0
	v_lshl_add_u64 v[126:127], v[244:245], 0, v[118:119]
	global_store_short v[122:123], v105, off offset:64
	global_load_ushort v105, v[126:127], off
	s_waitcnt vmcnt(0)
	v_lshlrev_b32_e32 v105, 16, v105
	global_load_dword v126, v[110:111], off offset:256
	v_mul_f32_e32 v105, 0xbfb8aa3b, v105
	v_exp_f32_e32 v105, v105
	s_waitcnt vmcnt(0)
	v_mul_f32_e32 v124, v126, v124
	v_add_f32_e32 v105, 1.0, v105
	v_rcp_f32_e32 v105, v105
	v_lshl_add_u64 v[126:127], v[244:245], 0, v[120:121]
	v_mul_f32_e32 v105, v124, v105
	v_cvt_pk_bf16_f32 v105, v105, s0
	global_store_short v[122:123], v105, off offset:128
	global_load_ushort v105, v[126:127], off
	s_waitcnt vmcnt(0)
	v_lshlrev_b32_e32 v105, 16, v105
	global_load_dword v124, v[110:111], off offset:384
	v_mul_f32_e32 v105, 0xbfb8aa3b, v105
	v_exp_f32_e32 v105, v105
	s_waitcnt vmcnt(0)
	v_mul_f32_e32 v103, v124, v103
	v_add_f32_e32 v105, 1.0, v105
	v_rcp_f32_e32 v105, v105
	s_nop 0
	v_mul_f32_e32 v103, v103, v105
	v_cvt_pk_bf16_f32 v103, v103, s0
	global_store_short v[122:123], v103, off offset:192
	ds_read_b32 v103, v238 offset:44
	ds_read_b32 v105, v239 offset:44
	v_add_u32_e32 v126, 11, v100
	v_ashrrev_i32_e32 v127, 31, v126
	v_mov_b32_e32 v244, v7
	s_waitcnt lgkmcnt(1)
	v_max_f32_e64 v103, |v103|, |v103|
	s_waitcnt lgkmcnt(0)
	v_max_f32_e32 v103, v103, v105
	v_div_scale_f32 v105, s[0:1], v103, v103, 1.0
	v_rcp_f32_e32 v122, v105
	v_mov_b32_e32 v245, v23
	v_fma_f32 v123, -v105, v122, 1.0
	v_fmac_f32_e32 v122, v123, v122
	v_div_scale_f32 v123, vcc, 1.0, v103, 1.0
	v_mul_f32_e32 v124, v123, v122
	v_fma_f32 v125, -v105, v124, v123
	v_fmac_f32_e32 v124, v125, v122
	v_fma_f32 v105, -v105, v124, v123
	v_div_fmas_f32 v105, v105, v122, v124
	v_lshlrev_b64 v[124:125], 11, v[126:127]
	v_lshl_add_u64 v[124:125], v[98:99], 0, v[124:125]
	global_load_dword v242, v[124:125], off
	global_load_dword v243, v[124:125], off offset:128
	global_load_dword v246, v[124:125], off offset:256
	global_load_dword v247, v[124:125], off offset:384
	v_div_fixup_f32 v122, v105, v103, 1.0
	v_mov_b32_e32 v124, v39
	v_mov_b32_e32 v125, v55
	s_waitcnt vmcnt(2)
	v_pk_fma_f32 v[242:243], v[244:245], v[122:123], v[242:243] op_sel_hi:[1,0,1]
	v_pk_mul_f32 v[244:245], v[242:243], v[242:243]
	s_waitcnt vmcnt(0)
	v_pk_fma_f32 v[124:125], v[124:125], v[122:123], v[246:247] op_sel_hi:[1,0,1]
	v_add_f32_e32 v103, v244, v245
	v_pk_mul_f32 v[122:123], v[124:125], v[124:125]
	v_add_f32_e32 v103, v103, v122
	v_add_f32_e32 v103, v103, v123
	v_mov_b32_e32 v105, v103
	v_mov_b32_e32 v255, v103
	s_nop 1
	v_permlane16_swap_b32_e32 v105, v255
	s_nop 1
	v_mov_b32_dpp v105, v255 quad_perm:[0,1,2,3] row_mask:0x5 bank_mask:0xf
	v_mad_i64_i32 v[122:123], s[0:1], v126, s74, v[106:107]
	v_lshl_add_u64 v[244:245], v[122:123], 0, s[96:97]
	v_lshlrev_b64 v[122:123], 10, v[126:127]
	v_add_f32_e32 v103, v103, v105
	s_nop 1
	v_mov_b32_dpp v105, v103 row_ror:8 row_mask:0xf bank_mask:0xf
	v_lshl_add_u64 v[126:127], v[244:245], 0, v[96:97]
	v_lshl_add_u64 v[122:123], s[66:67], 0, v[122:123]
	v_lshl_add_u64 v[122:123], v[122:123], 0, v[96:97]
	v_add_f32_e32 v103, v103, v105
	s_nop 1
	v_mov_b32_dpp v105, v103 row_shl:4 row_mask:0xf bank_mask:0x5
	v_mov_b32_dpp v105, v103 row_shr:4 row_mask:0xf bank_mask:0xa
	s_nop 0
	v_add_f32_e32 v103, v103, v105
	s_nop 1
	v_mov_b32_dpp v105, v103 quad_perm:[2,3,0,1] row_mask:0xf bank_mask:0xf
	v_add_f32_e32 v103, v103, v105
	s_nop 1
	v_add_f32_dpp v103, v103, v103 quad_perm:[1,0,3,2] row_mask:0xf bank_mask:0xf
	v_fmamk_f32 v103, v103, 0x3c000000, v163
	v_cmp_gt_f32_e32 vcc, s86, v103
	v_mul_f32_e32 v105, 0x4b800000, v103
	s_nop 0
	v_cndmask_b32_e32 v103, v103, v105, vcc
	v_rsq_f32_e32 v103, v103
	s_nop 0
	v_mul_f32_e32 v105, 0x45800000, v103
	v_cndmask_b32_e32 v103, v103, v105, vcc
	global_load_ushort v105, v[126:127], off
	v_mul_f32_e32 v126, v242, v103
	global_load_dword v127, v[108:109], off
	v_mul_f32_e32 v124, v124, v103
	s_waitcnt vmcnt(1)
	v_lshlrev_b32_e32 v105, 16, v105
	v_mul_f32_e32 v105, 0xbfb8aa3b, v105
	v_exp_f32_e32 v105, v105
	s_waitcnt vmcnt(0)
	v_mul_f32_e32 v126, v127, v126
	v_add_f32_e32 v105, 1.0, v105
	v_rcp_f32_e32 v105, v105
	s_nop 0
	v_mul_f32_e32 v105, v105, v126
	v_cvt_pk_bf16_f32 v105, v105, s0
	v_lshl_add_u64 v[126:127], v[244:245], 0, v[112:113]
	global_store_short v[122:123], v105, off
	global_load_ushort v105, v[126:127], off
	v_mul_f32_e32 v126, v243, v103
	global_load_dword v127, v[110:111], off offset:128
	v_mul_f32_e32 v103, v125, v103
	s_waitcnt vmcnt(1)
	v_lshlrev_b32_e32 v105, 16, v105
	v_mul_f32_e32 v105, 0xbfb8aa3b, v105
	v_exp_f32_e32 v105, v105
	s_waitcnt vmcnt(0)
	v_mul_f32_e32 v126, v127, v126
	v_add_f32_e32 v105, 1.0, v105
	v_rcp_f32_e32 v105, v105
	s_nop 0
	v_mul_f32_e32 v105, v105, v126
	v_cvt_pk_bf16_f32 v105, v105, s0
	v_lshl_add_u64 v[126:127], v[244:245], 0, v[118:119]
	global_store_short v[122:123], v105, off offset:64
	global_load_ushort v105, v[126:127], off
	s_waitcnt vmcnt(0)
	v_lshlrev_b32_e32 v105, 16, v105
	global_load_dword v126, v[110:111], off offset:256
	v_mul_f32_e32 v105, 0xbfb8aa3b, v105
	v_exp_f32_e32 v105, v105
	s_waitcnt vmcnt(0)
	v_mul_f32_e32 v124, v126, v124
	v_add_f32_e32 v105, 1.0, v105
	v_rcp_f32_e32 v105, v105
	v_lshl_add_u64 v[126:127], v[244:245], 0, v[120:121]
	v_mul_f32_e32 v105, v124, v105
	v_cvt_pk_bf16_f32 v105, v105, s0
	global_store_short v[122:123], v105, off offset:128
	global_load_ushort v105, v[126:127], off
	s_waitcnt vmcnt(0)
	v_lshlrev_b32_e32 v105, 16, v105
	global_load_dword v124, v[110:111], off offset:384
	v_mul_f32_e32 v105, 0xbfb8aa3b, v105
	v_exp_f32_e32 v105, v105
	s_waitcnt vmcnt(0)
	v_mul_f32_e32 v103, v124, v103
	v_add_f32_e32 v105, 1.0, v105
	v_rcp_f32_e32 v105, v105
	s_nop 0
	v_mul_f32_e32 v103, v103, v105
	v_cvt_pk_bf16_f32 v103, v103, s0
	global_store_short v[122:123], v103, off offset:192
	ds_read_b32 v103, v238 offset:64
	ds_read_b32 v105, v239 offset:64
	v_add_u32_e32 v126, 16, v100
	v_ashrrev_i32_e32 v127, 31, v126
	v_mov_b32_e32 v244, v8
	s_waitcnt lgkmcnt(1)
	v_max_f32_e64 v103, |v103|, |v103|
	s_waitcnt lgkmcnt(0)
	v_max_f32_e32 v103, v103, v105
	v_div_scale_f32 v105, s[0:1], v103, v103, 1.0
	v_rcp_f32_e32 v122, v105
	v_mov_b32_e32 v245, v24
	v_fma_f32 v123, -v105, v122, 1.0
	v_fmac_f32_e32 v122, v123, v122
	v_div_scale_f32 v123, vcc, 1.0, v103, 1.0
	v_mul_f32_e32 v124, v123, v122
	v_fma_f32 v125, -v105, v124, v123
	v_fmac_f32_e32 v124, v125, v122
	v_fma_f32 v105, -v105, v124, v123
	v_div_fmas_f32 v105, v105, v122, v124
	v_lshlrev_b64 v[124:125], 11, v[126:127]
	v_lshl_add_u64 v[124:125], v[98:99], 0, v[124:125]
	global_load_dword v242, v[124:125], off
	global_load_dword v243, v[124:125], off offset:128
	global_load_dword v246, v[124:125], off offset:256
	global_load_dword v247, v[124:125], off offset:384
	v_div_fixup_f32 v122, v105, v103, 1.0
	v_mov_b32_e32 v124, v40
	v_mov_b32_e32 v125, v56
	s_waitcnt vmcnt(2)
	v_pk_fma_f32 v[242:243], v[244:245], v[122:123], v[242:243] op_sel_hi:[1,0,1]
	v_pk_mul_f32 v[244:245], v[242:243], v[242:243]
	s_waitcnt vmcnt(0)
	v_pk_fma_f32 v[124:125], v[124:125], v[122:123], v[246:247] op_sel_hi:[1,0,1]
	v_add_f32_e32 v103, v244, v245
	v_pk_mul_f32 v[122:123], v[124:125], v[124:125]
	v_add_f32_e32 v103, v103, v122
	v_add_f32_e32 v103, v103, v123
	v_mov_b32_e32 v105, v103
	v_mov_b32_e32 v255, v103
	s_nop 1
	v_permlane16_swap_b32_e32 v105, v255
	s_nop 1
	v_mov_b32_dpp v105, v255 quad_perm:[0,1,2,3] row_mask:0x5 bank_mask:0xf
	v_mad_i64_i32 v[122:123], s[0:1], v126, s74, v[106:107]
	v_lshl_add_u64 v[244:245], v[122:123], 0, s[96:97]
	v_lshlrev_b64 v[122:123], 10, v[126:127]
	v_add_f32_e32 v103, v103, v105
	s_nop 1
	v_mov_b32_dpp v105, v103 row_ror:8 row_mask:0xf bank_mask:0xf
	v_lshl_add_u64 v[126:127], v[244:245], 0, v[96:97]
	v_lshl_add_u64 v[122:123], s[66:67], 0, v[122:123]
	v_lshl_add_u64 v[122:123], v[122:123], 0, v[96:97]
	v_add_f32_e32 v103, v103, v105
	s_nop 1
	v_mov_b32_dpp v105, v103 row_shl:4 row_mask:0xf bank_mask:0x5
	v_mov_b32_dpp v105, v103 row_shr:4 row_mask:0xf bank_mask:0xa
	s_nop 0
	v_add_f32_e32 v103, v103, v105
	s_nop 1
	v_mov_b32_dpp v105, v103 quad_perm:[2,3,0,1] row_mask:0xf bank_mask:0xf
	v_add_f32_e32 v103, v103, v105
	s_nop 1
	v_add_f32_dpp v103, v103, v103 quad_perm:[1,0,3,2] row_mask:0xf bank_mask:0xf
	v_fmamk_f32 v103, v103, 0x3c000000, v163
	v_cmp_gt_f32_e32 vcc, s86, v103
	v_mul_f32_e32 v105, 0x4b800000, v103
	s_nop 0
	v_cndmask_b32_e32 v103, v103, v105, vcc
	v_rsq_f32_e32 v103, v103
	s_nop 0
	v_mul_f32_e32 v105, 0x45800000, v103
	v_cndmask_b32_e32 v103, v103, v105, vcc
	global_load_ushort v105, v[126:127], off
	v_mul_f32_e32 v126, v242, v103
	global_load_dword v127, v[108:109], off
	v_mul_f32_e32 v124, v124, v103
	s_waitcnt vmcnt(1)
	v_lshlrev_b32_e32 v105, 16, v105
	v_mul_f32_e32 v105, 0xbfb8aa3b, v105
	v_exp_f32_e32 v105, v105
	s_waitcnt vmcnt(0)
	v_mul_f32_e32 v126, v127, v126
	v_add_f32_e32 v105, 1.0, v105
	v_rcp_f32_e32 v105, v105
	s_nop 0
	v_mul_f32_e32 v105, v105, v126
	v_cvt_pk_bf16_f32 v105, v105, s0
	v_lshl_add_u64 v[126:127], v[244:245], 0, v[112:113]
	global_store_short v[122:123], v105, off
	global_load_ushort v105, v[126:127], off
	v_mul_f32_e32 v126, v243, v103
	global_load_dword v127, v[110:111], off offset:128
	v_mul_f32_e32 v103, v125, v103
	s_waitcnt vmcnt(1)
	v_lshlrev_b32_e32 v105, 16, v105
	v_mul_f32_e32 v105, 0xbfb8aa3b, v105
	v_exp_f32_e32 v105, v105
	s_waitcnt vmcnt(0)
	v_mul_f32_e32 v126, v127, v126
	v_add_f32_e32 v105, 1.0, v105
	v_rcp_f32_e32 v105, v105
	s_nop 0
	v_mul_f32_e32 v105, v105, v126
	v_cvt_pk_bf16_f32 v105, v105, s0
	v_lshl_add_u64 v[126:127], v[244:245], 0, v[118:119]
	global_store_short v[122:123], v105, off offset:64
	global_load_ushort v105, v[126:127], off
	s_waitcnt vmcnt(0)
	v_lshlrev_b32_e32 v105, 16, v105
	global_load_dword v126, v[110:111], off offset:256
	v_mul_f32_e32 v105, 0xbfb8aa3b, v105
	v_exp_f32_e32 v105, v105
	s_waitcnt vmcnt(0)
	v_mul_f32_e32 v124, v126, v124
	v_add_f32_e32 v105, 1.0, v105
	v_rcp_f32_e32 v105, v105
	v_lshl_add_u64 v[126:127], v[244:245], 0, v[120:121]
	v_mul_f32_e32 v105, v124, v105
	v_cvt_pk_bf16_f32 v105, v105, s0
	global_store_short v[122:123], v105, off offset:128
	global_load_ushort v105, v[126:127], off
	s_waitcnt vmcnt(0)
	v_lshlrev_b32_e32 v105, 16, v105
	global_load_dword v124, v[110:111], off offset:384
	v_mul_f32_e32 v105, 0xbfb8aa3b, v105
	v_exp_f32_e32 v105, v105
	s_waitcnt vmcnt(0)
	v_mul_f32_e32 v103, v124, v103
	v_add_f32_e32 v105, 1.0, v105
	v_rcp_f32_e32 v105, v105
	s_nop 0
	v_mul_f32_e32 v103, v103, v105
	v_cvt_pk_bf16_f32 v103, v103, s0
	global_store_short v[122:123], v103, off offset:192
	ds_read_b32 v103, v238 offset:68
	ds_read_b32 v105, v239 offset:68
	v_add_u32_e32 v126, 17, v100
	v_ashrrev_i32_e32 v127, 31, v126
	v_mov_b32_e32 v244, v9
	s_waitcnt lgkmcnt(1)
	v_max_f32_e64 v103, |v103|, |v103|
	s_waitcnt lgkmcnt(0)
	v_max_f32_e32 v103, v103, v105
	v_div_scale_f32 v105, s[0:1], v103, v103, 1.0
	v_rcp_f32_e32 v122, v105
	v_mov_b32_e32 v245, v25
	v_fma_f32 v123, -v105, v122, 1.0
	v_fmac_f32_e32 v122, v123, v122
	v_div_scale_f32 v123, vcc, 1.0, v103, 1.0
	v_mul_f32_e32 v124, v123, v122
	v_fma_f32 v125, -v105, v124, v123
	v_fmac_f32_e32 v124, v125, v122
	v_fma_f32 v105, -v105, v124, v123
	v_div_fmas_f32 v105, v105, v122, v124
	v_lshlrev_b64 v[124:125], 11, v[126:127]
	v_lshl_add_u64 v[124:125], v[98:99], 0, v[124:125]
	global_load_dword v242, v[124:125], off
	global_load_dword v243, v[124:125], off offset:128
	global_load_dword v246, v[124:125], off offset:256
	global_load_dword v247, v[124:125], off offset:384
	v_div_fixup_f32 v122, v105, v103, 1.0
	v_mov_b32_e32 v124, v41
	v_mov_b32_e32 v125, v57
	s_waitcnt vmcnt(2)
	v_pk_fma_f32 v[242:243], v[244:245], v[122:123], v[242:243] op_sel_hi:[1,0,1]
	v_pk_mul_f32 v[244:245], v[242:243], v[242:243]
	s_waitcnt vmcnt(0)
	v_pk_fma_f32 v[124:125], v[124:125], v[122:123], v[246:247] op_sel_hi:[1,0,1]
	v_add_f32_e32 v103, v244, v245
	v_pk_mul_f32 v[122:123], v[124:125], v[124:125]
	v_add_f32_e32 v103, v103, v122
	v_add_f32_e32 v103, v103, v123
	v_mov_b32_e32 v105, v103
	v_mov_b32_e32 v255, v103
	s_nop 1
	v_permlane16_swap_b32_e32 v105, v255
	s_nop 1
	v_mov_b32_dpp v105, v255 quad_perm:[0,1,2,3] row_mask:0x5 bank_mask:0xf
	v_mad_i64_i32 v[122:123], s[0:1], v126, s74, v[106:107]
	v_lshl_add_u64 v[244:245], v[122:123], 0, s[96:97]
	v_lshlrev_b64 v[122:123], 10, v[126:127]
	v_add_f32_e32 v103, v103, v105
	s_nop 1
	v_mov_b32_dpp v105, v103 row_ror:8 row_mask:0xf bank_mask:0xf
	v_lshl_add_u64 v[126:127], v[244:245], 0, v[96:97]
	v_lshl_add_u64 v[122:123], s[66:67], 0, v[122:123]
	v_lshl_add_u64 v[122:123], v[122:123], 0, v[96:97]
	v_add_f32_e32 v103, v103, v105
	s_nop 1
	v_mov_b32_dpp v105, v103 row_shl:4 row_mask:0xf bank_mask:0x5
	v_mov_b32_dpp v105, v103 row_shr:4 row_mask:0xf bank_mask:0xa
	s_nop 0
	v_add_f32_e32 v103, v103, v105
	s_nop 1
	v_mov_b32_dpp v105, v103 quad_perm:[2,3,0,1] row_mask:0xf bank_mask:0xf
	v_add_f32_e32 v103, v103, v105
	s_nop 1
	v_add_f32_dpp v103, v103, v103 quad_perm:[1,0,3,2] row_mask:0xf bank_mask:0xf
	v_fmamk_f32 v103, v103, 0x3c000000, v163
	v_cmp_gt_f32_e32 vcc, s86, v103
	v_mul_f32_e32 v105, 0x4b800000, v103
	s_nop 0
	v_cndmask_b32_e32 v103, v103, v105, vcc
	v_rsq_f32_e32 v103, v103
	s_nop 0
	v_mul_f32_e32 v105, 0x45800000, v103
	v_cndmask_b32_e32 v103, v103, v105, vcc
	global_load_ushort v105, v[126:127], off
	v_mul_f32_e32 v126, v242, v103
	global_load_dword v127, v[108:109], off
	v_mul_f32_e32 v124, v124, v103
	s_waitcnt vmcnt(1)
	v_lshlrev_b32_e32 v105, 16, v105
	v_mul_f32_e32 v105, 0xbfb8aa3b, v105
	v_exp_f32_e32 v105, v105
	s_waitcnt vmcnt(0)
	v_mul_f32_e32 v126, v127, v126
	v_add_f32_e32 v105, 1.0, v105
	v_rcp_f32_e32 v105, v105
	s_nop 0
	v_mul_f32_e32 v105, v105, v126
	v_cvt_pk_bf16_f32 v105, v105, s0
	v_lshl_add_u64 v[126:127], v[244:245], 0, v[112:113]
	global_store_short v[122:123], v105, off
	global_load_ushort v105, v[126:127], off
	v_mul_f32_e32 v126, v243, v103
	global_load_dword v127, v[110:111], off offset:128
	v_mul_f32_e32 v103, v125, v103
	s_waitcnt vmcnt(1)
	v_lshlrev_b32_e32 v105, 16, v105
	v_mul_f32_e32 v105, 0xbfb8aa3b, v105
	v_exp_f32_e32 v105, v105
	s_waitcnt vmcnt(0)
	v_mul_f32_e32 v126, v127, v126
	v_add_f32_e32 v105, 1.0, v105
	v_rcp_f32_e32 v105, v105
	s_nop 0
	v_mul_f32_e32 v105, v105, v126
	v_cvt_pk_bf16_f32 v105, v105, s0
	v_lshl_add_u64 v[126:127], v[244:245], 0, v[118:119]
	global_store_short v[122:123], v105, off offset:64
	global_load_ushort v105, v[126:127], off
	s_waitcnt vmcnt(0)
	v_lshlrev_b32_e32 v105, 16, v105
	global_load_dword v126, v[110:111], off offset:256
	v_mul_f32_e32 v105, 0xbfb8aa3b, v105
	v_exp_f32_e32 v105, v105
	s_waitcnt vmcnt(0)
	v_mul_f32_e32 v124, v126, v124
	v_add_f32_e32 v105, 1.0, v105
	v_rcp_f32_e32 v105, v105
	v_lshl_add_u64 v[126:127], v[244:245], 0, v[120:121]
	v_mul_f32_e32 v105, v124, v105
	v_cvt_pk_bf16_f32 v105, v105, s0
	global_store_short v[122:123], v105, off offset:128
	global_load_ushort v105, v[126:127], off
	s_waitcnt vmcnt(0)
	v_lshlrev_b32_e32 v105, 16, v105
	global_load_dword v124, v[110:111], off offset:384
	v_mul_f32_e32 v105, 0xbfb8aa3b, v105
	v_exp_f32_e32 v105, v105
	s_waitcnt vmcnt(0)
	v_mul_f32_e32 v103, v124, v103
	v_add_f32_e32 v105, 1.0, v105
	v_rcp_f32_e32 v105, v105
	s_nop 0
	v_mul_f32_e32 v103, v103, v105
	v_cvt_pk_bf16_f32 v103, v103, s0
	global_store_short v[122:123], v103, off offset:192
	ds_read_b32 v103, v238 offset:72
	ds_read_b32 v105, v239 offset:72
	v_add_u32_e32 v126, 18, v100
	v_ashrrev_i32_e32 v127, 31, v126
	v_mov_b32_e32 v244, v10
	s_waitcnt lgkmcnt(1)
	v_max_f32_e64 v103, |v103|, |v103|
	s_waitcnt lgkmcnt(0)
	v_max_f32_e32 v103, v103, v105
	v_div_scale_f32 v105, s[0:1], v103, v103, 1.0
	v_rcp_f32_e32 v122, v105
	v_mov_b32_e32 v245, v26
	v_fma_f32 v123, -v105, v122, 1.0
	v_fmac_f32_e32 v122, v123, v122
	v_div_scale_f32 v123, vcc, 1.0, v103, 1.0
	v_mul_f32_e32 v124, v123, v122
	v_fma_f32 v125, -v105, v124, v123
	v_fmac_f32_e32 v124, v125, v122
	v_fma_f32 v105, -v105, v124, v123
	v_div_fmas_f32 v105, v105, v122, v124
	v_lshlrev_b64 v[124:125], 11, v[126:127]
	v_lshl_add_u64 v[124:125], v[98:99], 0, v[124:125]
	global_load_dword v242, v[124:125], off
	global_load_dword v243, v[124:125], off offset:128
	global_load_dword v246, v[124:125], off offset:256
	global_load_dword v247, v[124:125], off offset:384
	v_div_fixup_f32 v122, v105, v103, 1.0
	v_mov_b32_e32 v124, v42
	v_mov_b32_e32 v125, v58
	s_waitcnt vmcnt(2)
	v_pk_fma_f32 v[242:243], v[244:245], v[122:123], v[242:243] op_sel_hi:[1,0,1]
	v_pk_mul_f32 v[244:245], v[242:243], v[242:243]
	s_waitcnt vmcnt(0)
	v_pk_fma_f32 v[124:125], v[124:125], v[122:123], v[246:247] op_sel_hi:[1,0,1]
	v_add_f32_e32 v103, v244, v245
	v_pk_mul_f32 v[122:123], v[124:125], v[124:125]
	v_add_f32_e32 v103, v103, v122
	v_add_f32_e32 v103, v103, v123
	v_mov_b32_e32 v105, v103
	v_mov_b32_e32 v255, v103
	s_nop 1
	v_permlane16_swap_b32_e32 v105, v255
	s_nop 1
	v_mov_b32_dpp v105, v255 quad_perm:[0,1,2,3] row_mask:0x5 bank_mask:0xf
	v_mad_i64_i32 v[122:123], s[0:1], v126, s74, v[106:107]
	v_lshl_add_u64 v[244:245], v[122:123], 0, s[96:97]
	v_lshlrev_b64 v[122:123], 10, v[126:127]
	v_add_f32_e32 v103, v103, v105
	s_nop 1
	v_mov_b32_dpp v105, v103 row_ror:8 row_mask:0xf bank_mask:0xf
	v_lshl_add_u64 v[126:127], v[244:245], 0, v[96:97]
	v_lshl_add_u64 v[122:123], s[66:67], 0, v[122:123]
	v_lshl_add_u64 v[122:123], v[122:123], 0, v[96:97]
	v_add_f32_e32 v103, v103, v105
	s_nop 1
	v_mov_b32_dpp v105, v103 row_shl:4 row_mask:0xf bank_mask:0x5
	v_mov_b32_dpp v105, v103 row_shr:4 row_mask:0xf bank_mask:0xa
	s_nop 0
	v_add_f32_e32 v103, v103, v105
	s_nop 1
	v_mov_b32_dpp v105, v103 quad_perm:[2,3,0,1] row_mask:0xf bank_mask:0xf
	v_add_f32_e32 v103, v103, v105
	s_nop 1
	v_add_f32_dpp v103, v103, v103 quad_perm:[1,0,3,2] row_mask:0xf bank_mask:0xf
	v_fmamk_f32 v103, v103, 0x3c000000, v163
	v_cmp_gt_f32_e32 vcc, s86, v103
	v_mul_f32_e32 v105, 0x4b800000, v103
	s_nop 0
	v_cndmask_b32_e32 v103, v103, v105, vcc
	v_rsq_f32_e32 v103, v103
	s_nop 0
	v_mul_f32_e32 v105, 0x45800000, v103
	v_cndmask_b32_e32 v103, v103, v105, vcc
	global_load_ushort v105, v[126:127], off
	v_mul_f32_e32 v126, v242, v103
	global_load_dword v127, v[108:109], off
	v_mul_f32_e32 v124, v124, v103
	s_waitcnt vmcnt(1)
	v_lshlrev_b32_e32 v105, 16, v105
	v_mul_f32_e32 v105, 0xbfb8aa3b, v105
	v_exp_f32_e32 v105, v105
	s_waitcnt vmcnt(0)
	v_mul_f32_e32 v126, v127, v126
	v_add_f32_e32 v105, 1.0, v105
	v_rcp_f32_e32 v105, v105
	s_nop 0
	v_mul_f32_e32 v105, v105, v126
	v_cvt_pk_bf16_f32 v105, v105, s0
	v_lshl_add_u64 v[126:127], v[244:245], 0, v[112:113]
	global_store_short v[122:123], v105, off
	global_load_ushort v105, v[126:127], off
	v_mul_f32_e32 v126, v243, v103
	global_load_dword v127, v[110:111], off offset:128
	v_mul_f32_e32 v103, v125, v103
	s_waitcnt vmcnt(1)
	v_lshlrev_b32_e32 v105, 16, v105
	v_mul_f32_e32 v105, 0xbfb8aa3b, v105
	v_exp_f32_e32 v105, v105
	s_waitcnt vmcnt(0)
	v_mul_f32_e32 v126, v127, v126
	v_add_f32_e32 v105, 1.0, v105
	v_rcp_f32_e32 v105, v105
	s_nop 0
	v_mul_f32_e32 v105, v105, v126
	v_cvt_pk_bf16_f32 v105, v105, s0
	v_lshl_add_u64 v[126:127], v[244:245], 0, v[118:119]
	global_store_short v[122:123], v105, off offset:64
	global_load_ushort v105, v[126:127], off
	s_waitcnt vmcnt(0)
	v_lshlrev_b32_e32 v105, 16, v105
	global_load_dword v126, v[110:111], off offset:256
	v_mul_f32_e32 v105, 0xbfb8aa3b, v105
	v_exp_f32_e32 v105, v105
	s_waitcnt vmcnt(0)
	v_mul_f32_e32 v124, v126, v124
	v_add_f32_e32 v105, 1.0, v105
	v_rcp_f32_e32 v105, v105
	v_lshl_add_u64 v[126:127], v[244:245], 0, v[120:121]
	v_mul_f32_e32 v105, v124, v105
	v_cvt_pk_bf16_f32 v105, v105, s0
	global_store_short v[122:123], v105, off offset:128
	global_load_ushort v105, v[126:127], off
	s_waitcnt vmcnt(0)
	v_lshlrev_b32_e32 v105, 16, v105
	global_load_dword v124, v[110:111], off offset:384
	v_mul_f32_e32 v105, 0xbfb8aa3b, v105
	v_exp_f32_e32 v105, v105
	s_waitcnt vmcnt(0)
	v_mul_f32_e32 v103, v124, v103
	v_add_f32_e32 v105, 1.0, v105
	v_rcp_f32_e32 v105, v105
	s_nop 0
	v_mul_f32_e32 v103, v103, v105
	v_cvt_pk_bf16_f32 v103, v103, s0
	global_store_short v[122:123], v103, off offset:192
	ds_read_b32 v103, v238 offset:76
	ds_read_b32 v105, v239 offset:76
	v_add_u32_e32 v126, 19, v100
	v_ashrrev_i32_e32 v127, 31, v126
	v_mov_b32_e32 v244, v11
	s_waitcnt lgkmcnt(1)
	v_max_f32_e64 v103, |v103|, |v103|
	s_waitcnt lgkmcnt(0)
	v_max_f32_e32 v103, v103, v105
	v_div_scale_f32 v105, s[0:1], v103, v103, 1.0
	v_rcp_f32_e32 v122, v105
	v_mov_b32_e32 v245, v27
	v_fma_f32 v123, -v105, v122, 1.0
	v_fmac_f32_e32 v122, v123, v122
	v_div_scale_f32 v123, vcc, 1.0, v103, 1.0
	v_mul_f32_e32 v124, v123, v122
	v_fma_f32 v125, -v105, v124, v123
	v_fmac_f32_e32 v124, v125, v122
	v_fma_f32 v105, -v105, v124, v123
	v_div_fmas_f32 v105, v105, v122, v124
	v_lshlrev_b64 v[124:125], 11, v[126:127]
	v_lshl_add_u64 v[124:125], v[98:99], 0, v[124:125]
	global_load_dword v242, v[124:125], off
	global_load_dword v243, v[124:125], off offset:128
	global_load_dword v246, v[124:125], off offset:256
	global_load_dword v247, v[124:125], off offset:384
	v_div_fixup_f32 v122, v105, v103, 1.0
	v_mov_b32_e32 v124, v43
	v_mov_b32_e32 v125, v59
	s_waitcnt vmcnt(2)
	v_pk_fma_f32 v[242:243], v[244:245], v[122:123], v[242:243] op_sel_hi:[1,0,1]
	v_pk_mul_f32 v[244:245], v[242:243], v[242:243]
	s_waitcnt vmcnt(0)
	v_pk_fma_f32 v[124:125], v[124:125], v[122:123], v[246:247] op_sel_hi:[1,0,1]
	v_add_f32_e32 v103, v244, v245
	v_pk_mul_f32 v[122:123], v[124:125], v[124:125]
	v_add_f32_e32 v103, v103, v122
	v_add_f32_e32 v103, v103, v123
	v_mov_b32_e32 v105, v103
	v_mov_b32_e32 v255, v103
	s_nop 1
	v_permlane16_swap_b32_e32 v105, v255
	s_nop 1
	v_mov_b32_dpp v105, v255 quad_perm:[0,1,2,3] row_mask:0x5 bank_mask:0xf
	v_mad_i64_i32 v[122:123], s[0:1], v126, s74, v[106:107]
	v_lshl_add_u64 v[244:245], v[122:123], 0, s[96:97]
	v_lshlrev_b64 v[122:123], 10, v[126:127]
	v_add_f32_e32 v103, v103, v105
	s_nop 1
	v_mov_b32_dpp v105, v103 row_ror:8 row_mask:0xf bank_mask:0xf
	v_lshl_add_u64 v[126:127], v[244:245], 0, v[96:97]
	v_lshl_add_u64 v[122:123], s[66:67], 0, v[122:123]
	v_lshl_add_u64 v[122:123], v[122:123], 0, v[96:97]
	v_add_f32_e32 v103, v103, v105
	s_nop 1
	v_mov_b32_dpp v105, v103 row_shl:4 row_mask:0xf bank_mask:0x5
	v_mov_b32_dpp v105, v103 row_shr:4 row_mask:0xf bank_mask:0xa
	s_nop 0
	v_add_f32_e32 v103, v103, v105
	s_nop 1
	v_mov_b32_dpp v105, v103 quad_perm:[2,3,0,1] row_mask:0xf bank_mask:0xf
	v_add_f32_e32 v103, v103, v105
	s_nop 1
	v_add_f32_dpp v103, v103, v103 quad_perm:[1,0,3,2] row_mask:0xf bank_mask:0xf
	v_fmamk_f32 v103, v103, 0x3c000000, v163
	v_cmp_gt_f32_e32 vcc, s86, v103
	v_mul_f32_e32 v105, 0x4b800000, v103
	s_nop 0
	v_cndmask_b32_e32 v103, v103, v105, vcc
	v_rsq_f32_e32 v103, v103
	s_nop 0
	v_mul_f32_e32 v105, 0x45800000, v103
	v_cndmask_b32_e32 v103, v103, v105, vcc
	global_load_ushort v105, v[126:127], off
	v_mul_f32_e32 v126, v242, v103
	global_load_dword v127, v[108:109], off
	v_mul_f32_e32 v124, v124, v103
	s_waitcnt vmcnt(1)
	v_lshlrev_b32_e32 v105, 16, v105
	v_mul_f32_e32 v105, 0xbfb8aa3b, v105
	v_exp_f32_e32 v105, v105
	s_waitcnt vmcnt(0)
	v_mul_f32_e32 v126, v127, v126
	v_add_f32_e32 v105, 1.0, v105
	v_rcp_f32_e32 v105, v105
	s_nop 0
	v_mul_f32_e32 v105, v105, v126
	v_cvt_pk_bf16_f32 v105, v105, s0
	v_lshl_add_u64 v[126:127], v[244:245], 0, v[112:113]
	global_store_short v[122:123], v105, off
	global_load_ushort v105, v[126:127], off
	v_mul_f32_e32 v126, v243, v103
	global_load_dword v127, v[110:111], off offset:128
	v_mul_f32_e32 v103, v125, v103
	s_waitcnt vmcnt(1)
	v_lshlrev_b32_e32 v105, 16, v105
	v_mul_f32_e32 v105, 0xbfb8aa3b, v105
	v_exp_f32_e32 v105, v105
	s_waitcnt vmcnt(0)
	v_mul_f32_e32 v126, v127, v126
	v_add_f32_e32 v105, 1.0, v105
	v_rcp_f32_e32 v105, v105
	s_nop 0
	v_mul_f32_e32 v105, v105, v126
	v_cvt_pk_bf16_f32 v105, v105, s0
	v_lshl_add_u64 v[126:127], v[244:245], 0, v[118:119]
	global_store_short v[122:123], v105, off offset:64
	global_load_ushort v105, v[126:127], off
	s_waitcnt vmcnt(0)
	v_lshlrev_b32_e32 v105, 16, v105
	global_load_dword v126, v[110:111], off offset:256
	v_mul_f32_e32 v105, 0xbfb8aa3b, v105
	v_exp_f32_e32 v105, v105
	s_waitcnt vmcnt(0)
	v_mul_f32_e32 v124, v126, v124
	v_add_f32_e32 v105, 1.0, v105
	v_rcp_f32_e32 v105, v105
	v_lshl_add_u64 v[126:127], v[244:245], 0, v[120:121]
	v_mul_f32_e32 v105, v124, v105
	v_cvt_pk_bf16_f32 v105, v105, s0
	global_store_short v[122:123], v105, off offset:128
	global_load_ushort v105, v[126:127], off
	s_waitcnt vmcnt(0)
	v_lshlrev_b32_e32 v105, 16, v105
	global_load_dword v124, v[110:111], off offset:384
	v_mul_f32_e32 v105, 0xbfb8aa3b, v105
	v_exp_f32_e32 v105, v105
	s_waitcnt vmcnt(0)
	v_mul_f32_e32 v103, v124, v103
	v_add_f32_e32 v105, 1.0, v105
	v_rcp_f32_e32 v105, v105
	s_nop 0
	v_mul_f32_e32 v103, v103, v105
	v_cvt_pk_bf16_f32 v103, v103, s0
	global_store_short v[122:123], v103, off offset:192
	ds_read_b32 v103, v238 offset:96
	ds_read_b32 v105, v239 offset:96
	v_add_u32_e32 v126, 24, v100
	v_ashrrev_i32_e32 v127, 31, v126
	v_mov_b32_e32 v244, v12
	s_waitcnt lgkmcnt(1)
	v_max_f32_e64 v103, |v103|, |v103|
	s_waitcnt lgkmcnt(0)
	v_max_f32_e32 v103, v103, v105
	v_div_scale_f32 v105, s[0:1], v103, v103, 1.0
	v_rcp_f32_e32 v122, v105
	v_mov_b32_e32 v245, v28
	v_fma_f32 v123, -v105, v122, 1.0
	v_fmac_f32_e32 v122, v123, v122
	v_div_scale_f32 v123, vcc, 1.0, v103, 1.0
	v_mul_f32_e32 v124, v123, v122
	v_fma_f32 v125, -v105, v124, v123
	v_fmac_f32_e32 v124, v125, v122
	v_fma_f32 v105, -v105, v124, v123
	v_div_fmas_f32 v105, v105, v122, v124
	v_lshlrev_b64 v[124:125], 11, v[126:127]
	v_lshl_add_u64 v[124:125], v[98:99], 0, v[124:125]
	global_load_dword v242, v[124:125], off
	global_load_dword v243, v[124:125], off offset:128
	global_load_dword v246, v[124:125], off offset:256
	global_load_dword v247, v[124:125], off offset:384
	v_div_fixup_f32 v122, v105, v103, 1.0
	v_mov_b32_e32 v124, v44
	v_mov_b32_e32 v125, v60
	s_waitcnt vmcnt(2)
	v_pk_fma_f32 v[242:243], v[244:245], v[122:123], v[242:243] op_sel_hi:[1,0,1]
	v_pk_mul_f32 v[244:245], v[242:243], v[242:243]
	s_waitcnt vmcnt(0)
	v_pk_fma_f32 v[124:125], v[124:125], v[122:123], v[246:247] op_sel_hi:[1,0,1]
	v_add_f32_e32 v103, v244, v245
	v_pk_mul_f32 v[122:123], v[124:125], v[124:125]
	v_add_f32_e32 v103, v103, v122
	v_add_f32_e32 v103, v103, v123
	v_mov_b32_e32 v105, v103
	v_mov_b32_e32 v255, v103
	s_nop 1
	v_permlane16_swap_b32_e32 v105, v255
	s_nop 1
	v_mov_b32_dpp v105, v255 quad_perm:[0,1,2,3] row_mask:0x5 bank_mask:0xf
	v_mad_i64_i32 v[122:123], s[0:1], v126, s74, v[106:107]
	v_lshl_add_u64 v[244:245], v[122:123], 0, s[96:97]
	v_lshlrev_b64 v[122:123], 10, v[126:127]
	v_add_f32_e32 v103, v103, v105
	s_nop 1
	v_mov_b32_dpp v105, v103 row_ror:8 row_mask:0xf bank_mask:0xf
	v_lshl_add_u64 v[126:127], v[244:245], 0, v[96:97]
	v_lshl_add_u64 v[122:123], s[66:67], 0, v[122:123]
	v_lshl_add_u64 v[122:123], v[122:123], 0, v[96:97]
	v_add_f32_e32 v103, v103, v105
	s_nop 1
	v_mov_b32_dpp v105, v103 row_shl:4 row_mask:0xf bank_mask:0x5
	v_mov_b32_dpp v105, v103 row_shr:4 row_mask:0xf bank_mask:0xa
	s_nop 0
	v_add_f32_e32 v103, v103, v105
	s_nop 1
	v_mov_b32_dpp v105, v103 quad_perm:[2,3,0,1] row_mask:0xf bank_mask:0xf
	v_add_f32_e32 v103, v103, v105
	s_nop 1
	v_add_f32_dpp v103, v103, v103 quad_perm:[1,0,3,2] row_mask:0xf bank_mask:0xf
	v_fmamk_f32 v103, v103, 0x3c000000, v163
	v_cmp_gt_f32_e32 vcc, s86, v103
	v_mul_f32_e32 v105, 0x4b800000, v103
	s_nop 0
	v_cndmask_b32_e32 v103, v103, v105, vcc
	v_rsq_f32_e32 v103, v103
	s_nop 0
	v_mul_f32_e32 v105, 0x45800000, v103
	v_cndmask_b32_e32 v103, v103, v105, vcc
	global_load_ushort v105, v[126:127], off
	v_mul_f32_e32 v126, v242, v103
	global_load_dword v127, v[108:109], off
	v_mul_f32_e32 v124, v124, v103
	s_waitcnt vmcnt(1)
	v_lshlrev_b32_e32 v105, 16, v105
	v_mul_f32_e32 v105, 0xbfb8aa3b, v105
	v_exp_f32_e32 v105, v105
	s_waitcnt vmcnt(0)
	v_mul_f32_e32 v126, v127, v126
	v_add_f32_e32 v105, 1.0, v105
	v_rcp_f32_e32 v105, v105
	s_nop 0
	v_mul_f32_e32 v105, v105, v126
	v_cvt_pk_bf16_f32 v105, v105, s0
	v_lshl_add_u64 v[126:127], v[244:245], 0, v[112:113]
	global_store_short v[122:123], v105, off
	global_load_ushort v105, v[126:127], off
	v_mul_f32_e32 v126, v243, v103
	global_load_dword v127, v[110:111], off offset:128
	v_mul_f32_e32 v103, v125, v103
	s_waitcnt vmcnt(1)
	v_lshlrev_b32_e32 v105, 16, v105
	v_mul_f32_e32 v105, 0xbfb8aa3b, v105
	v_exp_f32_e32 v105, v105
	s_waitcnt vmcnt(0)
	v_mul_f32_e32 v126, v127, v126
	v_add_f32_e32 v105, 1.0, v105
	v_rcp_f32_e32 v105, v105
	s_nop 0
	v_mul_f32_e32 v105, v105, v126
	v_cvt_pk_bf16_f32 v105, v105, s0
	v_lshl_add_u64 v[126:127], v[244:245], 0, v[118:119]
	global_store_short v[122:123], v105, off offset:64
	global_load_ushort v105, v[126:127], off
	s_waitcnt vmcnt(0)
	v_lshlrev_b32_e32 v105, 16, v105
	global_load_dword v126, v[110:111], off offset:256
	v_mul_f32_e32 v105, 0xbfb8aa3b, v105
	v_exp_f32_e32 v105, v105
	s_waitcnt vmcnt(0)
	v_mul_f32_e32 v124, v126, v124
	v_add_f32_e32 v105, 1.0, v105
	v_rcp_f32_e32 v105, v105
	v_lshl_add_u64 v[126:127], v[244:245], 0, v[120:121]
	v_mul_f32_e32 v105, v124, v105
	v_cvt_pk_bf16_f32 v105, v105, s0
	global_store_short v[122:123], v105, off offset:128
	global_load_ushort v105, v[126:127], off
	s_waitcnt vmcnt(0)
	v_lshlrev_b32_e32 v105, 16, v105
	global_load_dword v124, v[110:111], off offset:384
	v_mul_f32_e32 v105, 0xbfb8aa3b, v105
	v_exp_f32_e32 v105, v105
	s_waitcnt vmcnt(0)
	v_mul_f32_e32 v103, v124, v103
	v_add_f32_e32 v105, 1.0, v105
	v_rcp_f32_e32 v105, v105
	s_nop 0
	v_mul_f32_e32 v103, v103, v105
	v_cvt_pk_bf16_f32 v103, v103, s0
	global_store_short v[122:123], v103, off offset:192
	ds_read_b32 v103, v238 offset:100
	ds_read_b32 v105, v239 offset:100
	v_add_u32_e32 v126, 25, v100
	v_ashrrev_i32_e32 v127, 31, v126
	v_mov_b32_e32 v244, v13
	s_waitcnt lgkmcnt(1)
	v_max_f32_e64 v103, |v103|, |v103|
	s_waitcnt lgkmcnt(0)
	v_max_f32_e32 v103, v103, v105
	v_div_scale_f32 v105, s[0:1], v103, v103, 1.0
	v_rcp_f32_e32 v122, v105
	v_mov_b32_e32 v245, v29
	v_fma_f32 v123, -v105, v122, 1.0
	v_fmac_f32_e32 v122, v123, v122
	v_div_scale_f32 v123, vcc, 1.0, v103, 1.0
	v_mul_f32_e32 v124, v123, v122
	v_fma_f32 v125, -v105, v124, v123
	v_fmac_f32_e32 v124, v125, v122
	v_fma_f32 v105, -v105, v124, v123
	v_div_fmas_f32 v105, v105, v122, v124
	v_lshlrev_b64 v[124:125], 11, v[126:127]
	v_lshl_add_u64 v[124:125], v[98:99], 0, v[124:125]
	global_load_dword v242, v[124:125], off
	global_load_dword v243, v[124:125], off offset:128
	global_load_dword v246, v[124:125], off offset:256
	global_load_dword v247, v[124:125], off offset:384
	v_div_fixup_f32 v122, v105, v103, 1.0
	v_mov_b32_e32 v124, v45
	v_mov_b32_e32 v125, v61
	s_waitcnt vmcnt(2)
	v_pk_fma_f32 v[242:243], v[244:245], v[122:123], v[242:243] op_sel_hi:[1,0,1]
	v_pk_mul_f32 v[244:245], v[242:243], v[242:243]
	s_waitcnt vmcnt(0)
	v_pk_fma_f32 v[124:125], v[124:125], v[122:123], v[246:247] op_sel_hi:[1,0,1]
	v_add_f32_e32 v103, v244, v245
	v_pk_mul_f32 v[122:123], v[124:125], v[124:125]
	v_add_f32_e32 v103, v103, v122
	v_add_f32_e32 v103, v103, v123
	v_mov_b32_e32 v105, v103
	v_mov_b32_e32 v255, v103
	s_nop 1
	v_permlane16_swap_b32_e32 v105, v255
	s_nop 1
	v_mov_b32_dpp v105, v255 quad_perm:[0,1,2,3] row_mask:0x5 bank_mask:0xf
	v_mad_i64_i32 v[122:123], s[0:1], v126, s74, v[106:107]
	v_lshl_add_u64 v[244:245], v[122:123], 0, s[96:97]
	v_lshlrev_b64 v[122:123], 10, v[126:127]
	v_add_f32_e32 v103, v103, v105
	s_nop 1
	v_mov_b32_dpp v105, v103 row_ror:8 row_mask:0xf bank_mask:0xf
	v_lshl_add_u64 v[126:127], v[244:245], 0, v[96:97]
	v_lshl_add_u64 v[122:123], s[66:67], 0, v[122:123]
	v_lshl_add_u64 v[122:123], v[122:123], 0, v[96:97]
	v_add_f32_e32 v103, v103, v105
	s_nop 1
	v_mov_b32_dpp v105, v103 row_shl:4 row_mask:0xf bank_mask:0x5
	v_mov_b32_dpp v105, v103 row_shr:4 row_mask:0xf bank_mask:0xa
	s_nop 0
	v_add_f32_e32 v103, v103, v105
	s_nop 1
	v_mov_b32_dpp v105, v103 quad_perm:[2,3,0,1] row_mask:0xf bank_mask:0xf
	v_add_f32_e32 v103, v103, v105
	s_nop 1
	v_add_f32_dpp v103, v103, v103 quad_perm:[1,0,3,2] row_mask:0xf bank_mask:0xf
	v_fmamk_f32 v103, v103, 0x3c000000, v163
	v_cmp_gt_f32_e32 vcc, s86, v103
	v_mul_f32_e32 v105, 0x4b800000, v103
	s_nop 0
	v_cndmask_b32_e32 v103, v103, v105, vcc
	v_rsq_f32_e32 v103, v103
	s_nop 0
	v_mul_f32_e32 v105, 0x45800000, v103
	v_cndmask_b32_e32 v103, v103, v105, vcc
	global_load_ushort v105, v[126:127], off
	v_mul_f32_e32 v126, v242, v103
	global_load_dword v127, v[108:109], off
	v_mul_f32_e32 v124, v124, v103
	s_waitcnt vmcnt(1)
	v_lshlrev_b32_e32 v105, 16, v105
	v_mul_f32_e32 v105, 0xbfb8aa3b, v105
	v_exp_f32_e32 v105, v105
	s_waitcnt vmcnt(0)
	v_mul_f32_e32 v126, v127, v126
	v_add_f32_e32 v105, 1.0, v105
	v_rcp_f32_e32 v105, v105
	s_nop 0
	v_mul_f32_e32 v105, v105, v126
	v_cvt_pk_bf16_f32 v105, v105, s0
	v_lshl_add_u64 v[126:127], v[244:245], 0, v[112:113]
	global_store_short v[122:123], v105, off
	global_load_ushort v105, v[126:127], off
	v_mul_f32_e32 v126, v243, v103
	global_load_dword v127, v[110:111], off offset:128
	v_mul_f32_e32 v103, v125, v103
	s_waitcnt vmcnt(1)
	v_lshlrev_b32_e32 v105, 16, v105
	v_mul_f32_e32 v105, 0xbfb8aa3b, v105
	v_exp_f32_e32 v105, v105
	s_waitcnt vmcnt(0)
	v_mul_f32_e32 v126, v127, v126
	v_add_f32_e32 v105, 1.0, v105
	v_rcp_f32_e32 v105, v105
	s_nop 0
	v_mul_f32_e32 v105, v105, v126
	v_cvt_pk_bf16_f32 v105, v105, s0
	v_lshl_add_u64 v[126:127], v[244:245], 0, v[118:119]
	global_store_short v[122:123], v105, off offset:64
	global_load_ushort v105, v[126:127], off
	s_waitcnt vmcnt(0)
	v_lshlrev_b32_e32 v105, 16, v105
	global_load_dword v126, v[110:111], off offset:256
	v_mul_f32_e32 v105, 0xbfb8aa3b, v105
	v_exp_f32_e32 v105, v105
	s_waitcnt vmcnt(0)
	v_mul_f32_e32 v124, v126, v124
	v_add_f32_e32 v105, 1.0, v105
	v_rcp_f32_e32 v105, v105
	v_lshl_add_u64 v[126:127], v[244:245], 0, v[120:121]
	v_mul_f32_e32 v105, v124, v105
	v_cvt_pk_bf16_f32 v105, v105, s0
	global_store_short v[122:123], v105, off offset:128
	global_load_ushort v105, v[126:127], off
	s_waitcnt vmcnt(0)
	v_lshlrev_b32_e32 v105, 16, v105
	global_load_dword v124, v[110:111], off offset:384
	v_mul_f32_e32 v105, 0xbfb8aa3b, v105
	v_exp_f32_e32 v105, v105
	s_waitcnt vmcnt(0)
	v_mul_f32_e32 v103, v124, v103
	v_add_f32_e32 v105, 1.0, v105
	v_rcp_f32_e32 v105, v105
	s_nop 0
	v_mul_f32_e32 v103, v103, v105
	v_cvt_pk_bf16_f32 v103, v103, s0
	global_store_short v[122:123], v103, off offset:192
	ds_read_b32 v103, v238 offset:104
	ds_read_b32 v105, v239 offset:104
	v_add_u32_e32 v126, 26, v100
	v_ashrrev_i32_e32 v127, 31, v126
	v_mov_b32_e32 v244, v14
	s_waitcnt lgkmcnt(1)
	v_max_f32_e64 v103, |v103|, |v103|
	s_waitcnt lgkmcnt(0)
	v_max_f32_e32 v103, v103, v105
	v_div_scale_f32 v105, s[0:1], v103, v103, 1.0
	v_rcp_f32_e32 v122, v105
	v_mov_b32_e32 v245, v30
	v_fma_f32 v123, -v105, v122, 1.0
	v_fmac_f32_e32 v122, v123, v122
	v_div_scale_f32 v123, vcc, 1.0, v103, 1.0
	v_mul_f32_e32 v124, v123, v122
	v_fma_f32 v125, -v105, v124, v123
	v_fmac_f32_e32 v124, v125, v122
	v_fma_f32 v105, -v105, v124, v123
	v_div_fmas_f32 v105, v105, v122, v124
	v_lshlrev_b64 v[124:125], 11, v[126:127]
	v_lshl_add_u64 v[124:125], v[98:99], 0, v[124:125]
	global_load_dword v242, v[124:125], off
	global_load_dword v243, v[124:125], off offset:128
	global_load_dword v246, v[124:125], off offset:256
	global_load_dword v247, v[124:125], off offset:384
	v_div_fixup_f32 v122, v105, v103, 1.0
	v_mov_b32_e32 v124, v46
	v_mov_b32_e32 v125, v62
	s_waitcnt vmcnt(2)
	v_pk_fma_f32 v[242:243], v[244:245], v[122:123], v[242:243] op_sel_hi:[1,0,1]
	v_pk_mul_f32 v[244:245], v[242:243], v[242:243]
	s_waitcnt vmcnt(0)
	v_pk_fma_f32 v[124:125], v[124:125], v[122:123], v[246:247] op_sel_hi:[1,0,1]
	v_add_f32_e32 v103, v244, v245
	v_pk_mul_f32 v[122:123], v[124:125], v[124:125]
	v_add_f32_e32 v103, v103, v122
	v_add_f32_e32 v103, v103, v123
	v_mov_b32_e32 v105, v103
	v_mov_b32_e32 v255, v103
	s_nop 1
	v_permlane16_swap_b32_e32 v105, v255
	s_nop 1
	v_mov_b32_dpp v105, v255 quad_perm:[0,1,2,3] row_mask:0x5 bank_mask:0xf
	v_mad_i64_i32 v[122:123], s[0:1], v126, s74, v[106:107]
	v_lshl_add_u64 v[244:245], v[122:123], 0, s[96:97]
	v_lshlrev_b64 v[122:123], 10, v[126:127]
	v_add_f32_e32 v103, v103, v105
	s_nop 1
	v_mov_b32_dpp v105, v103 row_ror:8 row_mask:0xf bank_mask:0xf
	v_lshl_add_u64 v[126:127], v[244:245], 0, v[96:97]
	v_lshl_add_u64 v[122:123], s[66:67], 0, v[122:123]
	v_lshl_add_u64 v[122:123], v[122:123], 0, v[96:97]
	v_add_f32_e32 v103, v103, v105
	s_nop 1
	v_mov_b32_dpp v105, v103 row_shl:4 row_mask:0xf bank_mask:0x5
	v_mov_b32_dpp v105, v103 row_shr:4 row_mask:0xf bank_mask:0xa
	s_nop 0
	v_add_f32_e32 v103, v103, v105
	s_nop 1
	v_mov_b32_dpp v105, v103 quad_perm:[2,3,0,1] row_mask:0xf bank_mask:0xf
	v_add_f32_e32 v103, v103, v105
	s_nop 1
	v_add_f32_dpp v103, v103, v103 quad_perm:[1,0,3,2] row_mask:0xf bank_mask:0xf
	v_fmamk_f32 v103, v103, 0x3c000000, v163
	v_cmp_gt_f32_e32 vcc, s86, v103
	v_mul_f32_e32 v105, 0x4b800000, v103
	s_nop 0
	v_cndmask_b32_e32 v103, v103, v105, vcc
	v_rsq_f32_e32 v103, v103
	s_nop 0
	v_mul_f32_e32 v105, 0x45800000, v103
	v_cndmask_b32_e32 v103, v103, v105, vcc
	global_load_ushort v105, v[126:127], off
	v_mul_f32_e32 v126, v242, v103
	global_load_dword v127, v[108:109], off
	v_mul_f32_e32 v124, v124, v103
	s_waitcnt vmcnt(1)
	v_lshlrev_b32_e32 v105, 16, v105
	v_mul_f32_e32 v105, 0xbfb8aa3b, v105
	v_exp_f32_e32 v105, v105
	s_waitcnt vmcnt(0)
	v_mul_f32_e32 v126, v127, v126
	v_add_f32_e32 v105, 1.0, v105
	v_rcp_f32_e32 v105, v105
	s_nop 0
	v_mul_f32_e32 v105, v105, v126
	v_cvt_pk_bf16_f32 v105, v105, s0
	v_lshl_add_u64 v[126:127], v[244:245], 0, v[112:113]
	global_store_short v[122:123], v105, off
	global_load_ushort v105, v[126:127], off
	v_mul_f32_e32 v126, v243, v103
	global_load_dword v127, v[110:111], off offset:128
	v_mul_f32_e32 v103, v125, v103
	s_waitcnt vmcnt(1)
	v_lshlrev_b32_e32 v105, 16, v105
	v_mul_f32_e32 v105, 0xbfb8aa3b, v105
	v_exp_f32_e32 v105, v105
	s_waitcnt vmcnt(0)
	v_mul_f32_e32 v126, v127, v126
	v_add_f32_e32 v105, 1.0, v105
	v_rcp_f32_e32 v105, v105
	s_nop 0
	v_mul_f32_e32 v105, v105, v126
	v_cvt_pk_bf16_f32 v105, v105, s0
	v_lshl_add_u64 v[126:127], v[244:245], 0, v[118:119]
	global_store_short v[122:123], v105, off offset:64
	global_load_ushort v105, v[126:127], off
	s_waitcnt vmcnt(0)
	v_lshlrev_b32_e32 v105, 16, v105
	global_load_dword v126, v[110:111], off offset:256
	v_mul_f32_e32 v105, 0xbfb8aa3b, v105
	v_exp_f32_e32 v105, v105
	s_waitcnt vmcnt(0)
	v_mul_f32_e32 v124, v126, v124
	v_add_f32_e32 v105, 1.0, v105
	v_rcp_f32_e32 v105, v105
	v_lshl_add_u64 v[126:127], v[244:245], 0, v[120:121]
	v_mul_f32_e32 v105, v124, v105
	v_cvt_pk_bf16_f32 v105, v105, s0
	global_store_short v[122:123], v105, off offset:128
	global_load_ushort v105, v[126:127], off
	s_waitcnt vmcnt(0)
	v_lshlrev_b32_e32 v105, 16, v105
	global_load_dword v124, v[110:111], off offset:384
	v_mul_f32_e32 v105, 0xbfb8aa3b, v105
	v_exp_f32_e32 v105, v105
	s_waitcnt vmcnt(0)
	v_mul_f32_e32 v103, v124, v103
	v_add_f32_e32 v105, 1.0, v105
	v_rcp_f32_e32 v105, v105
	s_nop 0
	v_mul_f32_e32 v103, v103, v105
	v_cvt_pk_bf16_f32 v103, v103, s0
	global_store_short v[122:123], v103, off offset:192
	v_add_u32_e32 v122, 27, v100
	v_ashrrev_i32_e32 v123, 31, v122
	v_lshlrev_b64 v[124:125], 11, v[122:123]
	v_lshl_add_u64 v[124:125], v[98:99], 0, v[124:125]
	global_load_dword v126, v[124:125], off
	global_load_dword v127, v[124:125], off offset:128
	global_load_dword v242, v[124:125], off offset:256
	global_load_dword v243, v[124:125], off offset:384
	v_mad_i64_i32 v[106:107], s[0:1], v122, s74, v[106:107]
	v_lshl_add_u64 v[106:107], v[106:107], 0, s[96:97]
	v_lshl_add_u64 v[124:125], v[106:107], 0, v[96:97]
	global_load_ushort v103, v[124:125], off
	v_lshl_add_u64 v[112:113], v[106:107], 0, v[112:113]
	v_lshl_add_u64 v[118:119], v[106:107], 0, v[118:119]
	v_lshl_add_u64 v[106:107], v[106:107], 0, v[120:121]
	global_load_ushort v105, v[112:113], off
	global_load_ushort v118, v[118:119], off
	global_load_ushort v119, v[106:107], off
	global_load_dword v120, v[108:109], off
	global_load_dword v121, v[110:111], off offset:128
	global_load_dword v124, v[110:111], off offset:256
	global_load_dword v125, v[110:111], off offset:384
	ds_read_b32 v109, v239 offset:108
	ds_read_b32 v110, v238 offset:108
	v_mov_b32_e32 v106, v15
	v_mov_b32_e32 v107, v31
	v_mov_b32_e32 v108, v47
	s_waitcnt lgkmcnt(1)
	s_waitcnt lgkmcnt(0)
	v_max_f32_e64 v110, |v110|, |v110|
	v_max_f32_e32 v110, v110, v109
	v_div_scale_f32 v111, s[0:1], v110, v110, 1.0
	v_rcp_f32_e32 v112, v111
	v_div_scale_f32 v113, vcc, 1.0, v110, 1.0
	v_mov_b32_e32 v109, v63
	v_fma_f32 v238, -v111, v112, 1.0
	v_fmac_f32_e32 v112, v238, v112
	v_mul_f32_e32 v238, v113, v112
	v_fma_f32 v239, -v111, v238, v113
	v_fmac_f32_e32 v238, v239, v112
	v_fma_f32 v111, -v111, v238, v113
	v_div_fmas_f32 v111, v111, v112, v238
	v_div_fixup_f32 v110, v111, v110, 1.0
	s_waitcnt vmcnt(10)
	v_pk_fma_f32 v[106:107], v[106:107], v[110:111], v[126:127] op_sel_hi:[1,0,1]
	s_waitcnt vmcnt(8)
	v_pk_fma_f32 v[108:109], v[108:109], v[110:111], v[242:243] op_sel_hi:[1,0,1]
	v_pk_mul_f32 v[110:111], v[106:107], v[106:107]
	v_pk_mul_f32 v[112:113], v[108:109], v[108:109]
	v_add_f32_e32 v110, v110, v111
	v_add_f32_e32 v110, v110, v112
	v_add_f32_e32 v112, v110, v113
	v_mov_b32_e32 v113, v112
	v_mov_b32_e32 v255, v112
	s_nop 1
	v_permlane16_swap_b32_e32 v113, v255
	v_lshlrev_b64 v[110:111], 10, v[122:123]
	v_lshl_add_u64 v[110:111], s[66:67], 0, v[110:111]
	v_lshl_add_u64 v[110:111], v[110:111], 0, v[96:97]
	s_waitcnt vmcnt(7)
	v_lshlrev_b32_e32 v96, 16, v103
	v_add_f32_e32 v103, v113, v255
	s_nop 1
	v_mov_b32_dpp v112, v103 row_ror:8 row_mask:0xf bank_mask:0xf
	s_waitcnt vmcnt(5)
	v_lshlrev_b32_e32 v113, 16, v118
	s_waitcnt vmcnt(4)
	v_lshlrev_b32_e32 v118, 16, v119
	v_lshlrev_b32_e32 v105, 16, v105
	v_mul_f32_e32 v96, 0xbfb8aa3b, v96
	v_add_f32_e32 v103, v103, v112
	s_nop 1
	v_mov_b32_dpp v112, v103 row_shl:4 row_mask:0xf bank_mask:0x5
	v_mov_b32_dpp v112, v103 row_shr:4 row_mask:0xf bank_mask:0xa
	v_mul_f32_e32 v113, 0xbfb8aa3b, v113
	v_mul_f32_e32 v118, 0xbfb8aa3b, v118
	v_mul_f32_e32 v105, 0xbfb8aa3b, v105
	v_exp_f32_e32 v96, v96
	v_add_f32_e32 v103, v103, v112
	s_nop 1
	v_mov_b32_dpp v112, v103 quad_perm:[2,3,0,1] row_mask:0xf bank_mask:0xf
	v_exp_f32_e32 v113, v113
	v_exp_f32_e32 v118, v118
	v_exp_f32_e32 v105, v105
	v_add_f32_e32 v96, 1.0, v96
	v_add_f32_e32 v103, v103, v112
	v_add_f32_e32 v113, 1.0, v113
	v_add_f32_e32 v118, 1.0, v118
	v_add_f32_e32 v105, 1.0, v105
	v_rcp_f32_e32 v96, v96
	v_add_f32_dpp v103, v103, v103 quad_perm:[1,0,3,2] row_mask:0xf bank_mask:0xf
	v_fmamk_f32 v103, v103, 0x3c000000, v163
	v_mul_f32_e32 v112, 0x4b800000, v103
	v_cmp_gt_f32_e32 vcc, s86, v103
	v_rcp_f32_e32 v105, v105
	s_nop 0
	v_cndmask_b32_e32 v103, v103, v112, vcc
	v_rsq_f32_e32 v103, v103
	v_rcp_f32_e32 v112, v113
	v_rcp_f32_e32 v113, v118
	v_mul_f32_e32 v118, 0x45800000, v103
	v_cndmask_b32_e32 v103, v103, v118, vcc
	v_mul_f32_e32 v106, v106, v103
	v_mul_f32_e32 v107, v107, v103
	v_mul_f32_e32 v108, v108, v103
	v_mul_f32_e32 v103, v109, v103
	s_waitcnt vmcnt(3)
	v_mul_f32_e32 v106, v120, v106
	s_waitcnt vmcnt(2)
	v_mul_f32_e32 v107, v121, v107
	s_waitcnt vmcnt(1)
	v_mul_f32_e32 v108, v124, v108
	s_waitcnt vmcnt(0)
	v_mul_f32_e32 v103, v125, v103
	v_mul_f32_e32 v96, v96, v106
	v_mul_f32_e32 v105, v105, v107
	v_mul_f32_e32 v106, v108, v112
	v_mul_f32_e32 v103, v103, v113
	v_cvt_pk_bf16_f32 v96, v96, s0
	v_cvt_pk_bf16_f32 v105, v105, s0
	v_cvt_pk_bf16_f32 v106, v106, s0
	v_cvt_pk_bf16_f32 v103, v103, s0
	global_store_short v[110:111], v96, off
	global_store_short v[110:111], v105, off offset:64
	global_store_short v[110:111], v106, off offset:128
	global_store_short v[110:111], v103, off offset:192
	s_cbranch_execnz .LBB0_927
	s_branch .LBB0_1111

.LBB0_1243:
	s_lshl_b32 s11, s11, 1
	v_readlane_b32 s0, v251, 36
	s_nop 0
	s_mov_b32 s2, s0
	s_cmp_lt_i32 s0, s11
	s_cselect_b64 s[0:1], -1, 0
	s_cmp_ge_i32 s2, s11
	s_cbranch_scc1 .LBB0_1246
	v_readlane_b32 s2, v251, 36
	v_readlane_b32 s44, v248, 8
	v_lshl_or_b32 v102, v174, 5, v175
	s_mov_b32 s12, s2
	s_mov_b32 s8, 0x10000
	s_mov_b32 s9, 0x20000
	s_mov_b64 s[42:43], s[16:17]
	s_mov_b32 s16, 0x30000
	v_readlane_b32 s45, v248, 9
	v_readlane_b32 s3, v251, 37
